# flat_* -> global_* (all pointers are global); no other change
# baseline (speedup 1.0000x reference)
.LBB0_8:
	s_mov_b32 s15, s2
	s_mov_b64 s[6:7], -1
	s_mov_b64 s[0:1], 0
	s_cmp_lt_i32 s2, 19
	s_mov_b64 s[4:5], 0
	s_cbranch_scc1 .LBB0_17
	s_cmp_eq_u32 s15, 19
	s_mov_b64 s[4:5], -1
	s_cbranch_scc0 .LBB0_16
	v_mov_b32_e32 v0, 0xe0
	v_mov_b32_e32 v2, 0xd8
	v_add_u32_e32 v0, s91, v0
	ds_read_b64 v[0:1], v0
	v_mov_b32_e32 v4, 0xe0
	v_add_u32_e32 v2, s91, v2
	ds_read_b64 v[2:3], v2
	s_waitcnt lgkmcnt(0)
	v_readfirstlane_b32 s9, v1
	v_add_u32_e32 v4, s91, v4
	ds_read_b64 v[4:5], v4
	v_readfirstlane_b32 s8, v0
	v_mbcnt_lo_u32_b32 v0, -1, 0
	v_mbcnt_hi_u32_b32 v0, -1, v0
	v_readlane_b32 s2, v253, 11
	v_add_u32_e32 v1, s57, v0
	v_ashrrev_i32_e32 v1, 6, v1
	v_add_u32_e32 v52, s2, v1
	s_waitcnt lgkmcnt(1)
	v_readfirstlane_b32 s11, v3
	v_readfirstlane_b32 s10, v2
	s_waitcnt lgkmcnt(0)
	v_readfirstlane_b32 s7, v5
	v_readfirstlane_b32 s6, v4
	v_cmp_gt_i32_e32 vcc, s3, v52
	s_and_saveexec_b64 s[4:5], vcc
	s_cbranch_execz .LBB0_15
	v_and_b32_e32 v0, 63, v0
	v_lshlrev_b32_e32 v160, 4, v0
	v_lshl_add_u64 v[12:13], s[10:11], 0, v[160:161]
	global_load_dwordx4 v[0:3], v[12:13], off
	global_load_dwordx4 v[4:7], v[12:13], off offset:1024
	global_load_dwordx4 v[8:11], v[12:13], off offset:2048
	s_nop 0
	global_load_dwordx4 v[12:15], v[12:13], off offset:3072
	v_cmp_lt_i32_e32 vcc, v214, v213
	v_lshl_add_u64 v[48:49], s[8:9], 0, v[160:161]
	v_lshl_add_u64 v[50:51], s[6:7], 0, v[160:161]
	v_cndmask_b32_e32 v16, v211, v214, vcc
	v_cmp_lt_i32_e32 vcc, v215, v213
	v_lshlrev_b32_e32 v60, 2, v16
	s_mov_b64 s[6:7], 0
	v_cndmask_b32_e32 v16, v211, v215, vcc
	v_cmp_lt_i32_e32 vcc, v216, v213
	v_lshlrev_b32_e32 v61, 2, v16
	s_nop 0
	v_cndmask_b32_e32 v16, v211, v216, vcc
	v_cmp_lt_i32_e32 vcc, v217, v213
	v_lshlrev_b32_e32 v62, 2, v16
	s_nop 0
	v_cndmask_b32_e32 v16, v211, v217, vcc
	v_cmp_lt_i32_e32 vcc, v218, v213
	v_lshlrev_b32_e32 v63, 2, v16
	s_nop 0
	v_cndmask_b32_e32 v16, v211, v218, vcc
	v_cmp_lt_i32_e32 vcc, v219, v213
	v_lshlrev_b32_e32 v64, 2, v16
	s_nop 0
	v_cndmask_b32_e32 v16, v211, v219, vcc
	v_lshlrev_b32_e32 v65, 2, v16
	s_branch .LBB0_13

.LBB0_13:
	v_ashrrev_i32_e32 v53, 31, v52
	v_lshlrev_b64 v[58:59], 12, v[52:53]
	v_lshl_add_u64 v[16:17], v[48:49], 0, v[58:59]
	global_load_dwordx4 v[44:47], v[16:17], off
	global_load_dwordx4 v[40:43], v[16:17], off offset:1024
	global_load_dwordx4 v[36:39], v[16:17], off offset:2048
	global_load_dwordx4 v[32:35], v[16:17], off offset:3072
	v_add_u32_e32 v53, s18, v52
	v_cmp_gt_i32_e32 vcc, s3, v53
	v_lshl_add_u64 v[58:59], v[50:51], 0, v[58:59]
	s_waitcnt vmcnt(0) lgkmcnt(0)
	v_pk_mul_f32 v[66:67], v[46:47], v[46:47]
	v_cndmask_b32_e32 v56, v52, v53, vcc
	v_ashrrev_i32_e32 v57, 31, v56
	v_lshlrev_b64 v[54:55], 12, v[56:57]
	v_lshl_add_u64 v[16:17], v[48:49], 0, v[54:55]
	global_load_dwordx4 v[28:31], v[16:17], off
	global_load_dwordx4 v[24:27], v[16:17], off offset:1024
	global_load_dwordx4 v[20:23], v[16:17], off offset:2048
	s_nop 0
	global_load_dwordx4 v[16:19], v[16:17], off offset:3072
	v_pk_mul_f32 v[68:69], v[44:45], v[44:45]
	v_mul_f32_e32 v57, v32, v32
	v_pk_mov_b32 v[70:71], v[68:69], v[66:67] op_sel:[1,0]
	v_mov_b32_e32 v69, v67
	v_pk_add_f32 v[66:67], v[70:71], v[68:69]
	v_pk_mul_f32 v[68:69], v[42:43], v[42:43]
	v_pk_mul_f32 v[70:71], v[40:41], v[40:41]
	v_pk_add_f32 v[66:67], v[66:67], v[66:67] op_sel:[0,1] op_sel_hi:[1,0]
	v_pk_mov_b32 v[72:73], v[70:71], v[68:69] op_sel:[1,0]
	v_mov_b32_e32 v71, v69
	v_pk_add_f32 v[68:69], v[72:73], v[70:71]
	v_mul_f32_e32 v70, v33, v33
	v_pk_add_f32 v[68:69], v[68:69], v[68:69] op_sel:[0,1] op_sel_hi:[1,0]
	v_mov_b32_e32 v67, v57
	v_mov_b32_e32 v69, v70
	v_pk_add_f32 v[66:67], v[66:67], v[68:69]
	v_mul_f32_e32 v68, v37, v37
	v_mul_f32_e32 v71, v34, v34
	v_pk_fma_f32 v[68:69], v[36:37], v[36:37], v[68:69] op_sel_hi:[1,1,0]
	v_mul_f32_e32 v70, v39, v39
	v_mul_f32_e32 v72, v35, v35
	v_mov_b32_e32 v69, v71
	v_pk_fma_f32 v[70:71], v[38:39], v[38:39], v[70:71] op_sel_hi:[1,1,0]
	s_nop 0
	v_mov_b32_e32 v71, v72
	v_pk_add_f32 v[68:69], v[68:69], v[70:71]
	s_nop 0
	v_pk_add_f32 v[66:67], v[66:67], v[68:69]
	s_waitcnt vmcnt(0) lgkmcnt(0)
	v_mul_f32_e32 v68, v27, v27
	v_add_f32_e32 v57, v66, v67
	v_mul_f32_e32 v66, v29, v29
	v_mul_f32_e32 v67, v31, v31
	v_fmac_f32_e32 v66, v28, v28
	v_fmac_f32_e32 v67, v30, v30
	v_add_f32_e32 v66, v66, v67
	v_mul_f32_e32 v67, v25, v25
	v_fmac_f32_e32 v67, v24, v24
	v_fmac_f32_e32 v68, v26, v26
	v_add_f32_e32 v67, v67, v68
	v_add_f32_e32 v66, v66, v67
	v_mul_f32_e32 v67, v21, v21
	v_mul_f32_e32 v68, v23, v23
	v_fmac_f32_e32 v67, v20, v20
	v_fmac_f32_e32 v68, v22, v22
	v_add_f32_e32 v67, v67, v68
	v_add_f32_e32 v66, v66, v67
	v_mul_f32_e32 v67, v17, v17
	v_mul_f32_e32 v68, v19, v19
	v_fmac_f32_e32 v67, v16, v16
	v_fmac_f32_e32 v68, v18, v18
	v_add_f32_e32 v67, v67, v68
	v_add_f32_e32 v66, v66, v67
	ds_bpermute_b32 v67, v60, v57
	s_waitcnt lgkmcnt(0)
	v_add_f32_e32 v57, v57, v67
	ds_bpermute_b32 v67, v60, v66
	s_waitcnt lgkmcnt(0)
	v_add_f32_e32 v66, v66, v67
	ds_bpermute_b32 v67, v61, v57
	s_waitcnt lgkmcnt(0)
	v_add_f32_e32 v57, v57, v67
	ds_bpermute_b32 v67, v61, v66
	s_waitcnt lgkmcnt(0)
	v_add_f32_e32 v66, v66, v67
	ds_bpermute_b32 v67, v62, v57
	s_waitcnt lgkmcnt(0)
	v_add_f32_e32 v57, v57, v67
	ds_bpermute_b32 v67, v62, v66
	s_waitcnt lgkmcnt(0)
	v_add_f32_e32 v66, v66, v67
	ds_bpermute_b32 v67, v63, v57
	s_waitcnt lgkmcnt(0)
	v_add_f32_e32 v57, v57, v67
	ds_bpermute_b32 v67, v63, v66
	s_waitcnt lgkmcnt(0)
	v_add_f32_e32 v66, v66, v67
	ds_bpermute_b32 v67, v64, v57
	s_waitcnt lgkmcnt(0)
	v_add_f32_e32 v67, v57, v67
	ds_bpermute_b32 v57, v64, v66
	s_waitcnt lgkmcnt(0)
	v_add_f32_e32 v57, v66, v57
	ds_bpermute_b32 v66, v65, v67
	s_waitcnt lgkmcnt(0)
	v_add_f32_e32 v67, v67, v66
	v_fmamk_f32 v67, v67, 0x3a800000, v208
	v_cmp_gt_f32_e32 vcc, s14, v67
	v_mul_f32_e32 v68, 0x4b800000, v67
	ds_bpermute_b32 v66, v65, v57
	v_cndmask_b32_e32 v67, v67, v68, vcc
	v_rsq_f32_e32 v67, v67
	s_nop 0
	v_mul_f32_e32 v68, 0x45800000, v67
	v_cndmask_b32_e32 v68, v67, v68, vcc
	v_pk_mul_f32 v[44:45], v[44:45], v[68:69] op_sel_hi:[1,0]
	v_pk_mul_f32 v[46:47], v[46:47], v[68:69] op_sel_hi:[1,0]
	v_pk_mul_f32 v[40:41], v[40:41], v[68:69] op_sel_hi:[1,0]
	v_pk_mul_f32 v[42:43], v[42:43], v[68:69] op_sel_hi:[1,0]
	v_pk_mul_f32 v[36:37], v[36:37], v[68:69] op_sel_hi:[1,0]
	v_pk_mul_f32 v[38:39], v[38:39], v[68:69] op_sel_hi:[1,0]
	v_pk_mul_f32 v[32:33], v[32:33], v[68:69] op_sel_hi:[1,0]
	v_pk_mul_f32 v[34:35], v[34:35], v[68:69] op_sel_hi:[1,0]
	v_pk_mul_f32 v[46:47], v[2:3], v[46:47]
	v_pk_mul_f32 v[44:45], v[0:1], v[44:45]
	v_pk_mul_f32 v[42:43], v[6:7], v[42:43]
	v_pk_mul_f32 v[40:41], v[4:5], v[40:41]
	v_pk_mul_f32 v[38:39], v[10:11], v[38:39]
	v_pk_mul_f32 v[36:37], v[8:9], v[36:37]
	v_pk_mul_f32 v[34:35], v[14:15], v[34:35]
	v_pk_mul_f32 v[32:33], v[12:13], v[32:33]
	v_cmp_ne_u32_e32 vcc, v52, v56
	global_store_dwordx4 v[58:59], v[44:47], off
	global_store_dwordx4 v[58:59], v[40:43], off offset:1024
	global_store_dwordx4 v[58:59], v[36:39], off offset:2048
	global_store_dwordx4 v[58:59], v[32:35], off offset:3072
	s_and_saveexec_b64 s[8:9], vcc
	s_cbranch_execz .LBB0_12
	s_waitcnt lgkmcnt(0)
	v_add_f32_e32 v32, v57, v66
	v_fmamk_f32 v32, v32, 0x3a800000, v208
	v_mul_f32_e32 v33, 0x4b800000, v32
	v_cmp_gt_f32_e32 vcc, s14, v32
	s_nop 1
	v_cndmask_b32_e32 v32, v32, v33, vcc
	v_rsq_f32_e32 v34, v32
	v_lshl_add_u64 v[32:33], v[50:51], 0, v[54:55]
	v_mul_f32_e32 v35, 0x45800000, v34
	v_cndmask_b32_e32 v34, v34, v35, vcc
	v_pk_mul_f32 v[28:29], v[28:29], v[34:35] op_sel_hi:[1,0]
	v_pk_mul_f32 v[30:31], v[30:31], v[34:35] op_sel_hi:[1,0]
	v_pk_mul_f32 v[24:25], v[24:25], v[34:35] op_sel_hi:[1,0]
	v_pk_mul_f32 v[26:27], v[26:27], v[34:35] op_sel_hi:[1,0]
	v_pk_mul_f32 v[20:21], v[20:21], v[34:35] op_sel_hi:[1,0]
	v_pk_mul_f32 v[22:23], v[22:23], v[34:35] op_sel_hi:[1,0]
	v_pk_mul_f32 v[16:17], v[16:17], v[34:35] op_sel_hi:[1,0]
	v_pk_mul_f32 v[18:19], v[18:19], v[34:35] op_sel_hi:[1,0]
	v_pk_mul_f32 v[30:31], v[2:3], v[30:31]
	v_pk_mul_f32 v[28:29], v[0:1], v[28:29]
	v_pk_mul_f32 v[26:27], v[6:7], v[26:27]
	v_pk_mul_f32 v[24:25], v[4:5], v[24:25]
	v_pk_mul_f32 v[22:23], v[10:11], v[22:23]
	v_pk_mul_f32 v[20:21], v[8:9], v[20:21]
	v_pk_mul_f32 v[18:19], v[14:15], v[18:19]
	v_pk_mul_f32 v[16:17], v[12:13], v[16:17]
	global_store_dwordx4 v[32:33], v[28:31], off
	global_store_dwordx4 v[32:33], v[24:27], off offset:1024
	global_store_dwordx4 v[32:33], v[20:23], off offset:2048
	global_store_dwordx4 v[32:33], v[16:19], off offset:3072
	s_branch .LBB0_12

.LBB0_23:
	v_readlane_b32 s4, v252, 24
	v_readlane_b32 s0, v253, 0
	s_add_i32 s2, s4, 1
	v_readlane_b32 s1, v253, 1
	s_cmp_ge_i32 s2, s1
	s_mov_b64 s[0:1], -1
	v_readlane_b32 s18, v252, 23
	s_mov_b32 s14, 0x800000
	s_cbranch_scc1 .LBB0_7
	v_readlane_b32 s0, v253, 0
	v_readlane_b32 s1, v253, 1
	s_cmp_lg_u32 s4, s0
	s_mov_b64 s[0:1], -1
	s_cbranch_scc0 .LBB0_41
	v_readlane_b32 s4, v253, 27
	v_readlane_b32 s0, v252, 1
	v_readlane_b32 s5, v253, 28
	s_add_i32 s8, s0, 1
	s_mov_b64 s[0:1], -1
	s_and_b64 vcc, exec, s[4:5]
	s_cbranch_vccz .LBB0_32
	v_mov_b32_e32 v0, 0xe8
	s_nop 0
	v_add_u32_e32 v0, 0, v0
	v_add_u32_e32 v0, 0x20400, v0
	ds_read_b64 v[0:1], v0
	s_waitcnt lgkmcnt(0)
	s_barrier
	v_readfirstlane_b32 s5, v1
	v_readfirstlane_b32 s4, v0
	s_mov_b64 s[0:1], exec
	v_readlane_b32 s6, v253, 2
	v_readlane_b32 s7, v253, 3
	s_and_b64 s[6:7], s[0:1], s[6:7]
	s_mov_b64 exec, s[6:7]
	s_cbranch_execz .LBB0_31
	v_mov_b64_e32 v[0:1], s[4:5]
	buffer_wbl2 sc1
	s_waitcnt vmcnt(0)
	buffer_inv sc1
	global_atomic_add v[0:1], v210, off offset:512
	global_load_dword v0, v[0:1], off offset:512 sc1
	s_mul_i32 s9, s78, s8
	s_waitcnt vmcnt(0) lgkmcnt(0)
	v_cmp_gt_u32_e32 vcc, s9, v0
	s_and_b64 exec, exec, vcc
	s_cbranch_execz .LBB0_30
	s_mov_b64 s[6:7], 0
.LBB0_29:
	v_mov_b64_e32 v[0:1], s[4:5]
	s_sleep 1
	global_load_dword v0, v[0:1], off offset:512 sc1
	s_waitcnt vmcnt(0) lgkmcnt(0)
	v_readfirstlane_b32 s10, v0
	s_cmp_ge_u32 s10, s9
	s_cselect_b64 s[10:11], -1, 0
	s_and_b64 s[10:11], exec, s[10:11]
	s_or_b64 s[6:7], s[10:11], s[6:7]
	s_andn2_b64 exec, exec, s[6:7]
	s_cbranch_execnz .LBB0_29

.LBB0_32:
	s_and_b64 vcc, exec, s[0:1]
	s_cbranch_vccz .LBB0_78
	v_mov_b32_e32 v0, 0xe8
	s_nop 0
	v_add_u32_e32 v0, 0, v0
	v_add_u32_e32 v0, 0x20400, v0
	ds_read_b64 v[0:1], v0
	s_waitcnt lgkmcnt(0)
	s_barrier
	v_readfirstlane_b32 s5, v1
	v_readfirstlane_b32 s4, v0
	s_mov_b64 s[0:1], exec
	v_readlane_b32 s6, v253, 2
	v_readlane_b32 s7, v253, 3
	s_and_b64 s[6:7], s[0:1], s[6:7]
	s_mov_b64 exec, s[6:7]
	s_cbranch_execz .LBB0_40
	s_add_u32 s4, s4, 0x1000
	s_addc_u32 s5, s5, 0
	v_readlane_b32 s6, v254, 40
	s_add_u32 s6, s4, s6
	s_addc_u32 s7, s5, 0
	v_mov_b64_e32 v[0:1], s[6:7]
	buffer_wbl2 sc1
	s_waitcnt vmcnt(0)
	buffer_inv sc1
	global_atomic_add v0, v[0:1], v210, off offset:256 sc0
	v_readlane_b32 s6, v253, 29
	s_mul_i32 s6, s6, s8
	s_waitcnt vmcnt(0) lgkmcnt(0)
	v_add_u32_e32 v0, 1, v0
	v_cmp_eq_u32_e32 vcc, s6, v0
	s_and_saveexec_b64 s[6:7], vcc
	s_cbranch_execz .LBB0_36
	v_mov_b64_e32 v[0:1], s[4:5]
	global_atomic_add v[0:1], v210, off
.LBB0_36:
	s_or_b64 exec, exec, s[6:7]
	v_mov_b64_e32 v[0:1], s[4:5]
	global_load_dword v0, v[0:1], off sc1
	s_lshl_b32 s9, s8, 3
	s_waitcnt vmcnt(0) lgkmcnt(0)
	v_cmp_gt_u32_e32 vcc, s9, v0
	s_and_b64 exec, exec, vcc
	s_cbranch_execz .LBB0_39
	s_mov_b64 s[6:7], 0
.LBB0_38:
	v_mov_b64_e32 v[0:1], s[4:5]
	s_sleep 1
	global_load_dword v0, v[0:1], off sc1
	s_waitcnt vmcnt(0) lgkmcnt(0)
	v_readfirstlane_b32 s10, v0
	s_cmp_ge_u32 s10, s9
	s_cselect_b64 s[10:11], -1, 0
	s_and_b64 s[10:11], exec, s[10:11]
	s_or_b64 s[6:7], s[10:11], s[6:7]
	s_andn2_b64 exec, exec, s[6:7]
	s_cbranch_execnz .LBB0_38

.LBB0_75:
	v_lshl_add_u32 v144, s39, 8, v140
	v_lshl_add_u32 v138, s38, 8, v142
	v_ashrrev_i32_e32 v145, 31, v144
	v_ashrrev_i32_e32 v139, 31, v138
	v_lshlrev_b64 v[146:147], 13, v[144:145]
	v_max_f32_e32 v125, v125, v125
	v_max_f32_e32 v124, v124, v124
	v_max_f32_e32 v127, v127, v127
	v_max_f32_e32 v126, v126, v126
	v_max_f32_e32 v121, v121, v121
	v_max_f32_e32 v120, v120, v120
	v_max_f32_e32 v123, v123, v123
	v_max_f32_e32 v122, v122, v122
	v_lshl_add_u64 v[146:147], s[10:11], 0, v[146:147]
	v_lshlrev_b64 v[148:149], 1, v[138:139]
	v_max_f32_e32 v125, 0, v125
	v_max_f32_e32 v124, 0, v124
	v_max_f32_e32 v127, 0, v127
	v_max_f32_e32 v126, 0, v126
	v_max_f32_e32 v121, 0, v121
	v_max_f32_e32 v120, 0, v120
	v_max_f32_e32 v123, 0, v123
	v_max_f32_e32 v122, 0, v122
	v_lshl_add_u64 v[138:139], v[146:147], 0, v[148:149]
	v_pk_mul_f32 v[126:127], v[126:127], v[126:127]
	v_pk_mul_f32 v[124:125], v[124:125], v[124:125]
	v_pk_mul_f32 v[146:147], v[122:123], v[122:123]
	v_pk_mul_f32 v[122:123], v[120:121], v[120:121]
	v_max_f32_e32 v117, v117, v117
	v_max_f32_e32 v116, v116, v116
	v_max_f32_e32 v119, v119, v119
	v_max_f32_e32 v118, v118, v118
	v_max_f32_e32 v113, v113, v113
	v_max_f32_e32 v112, v112, v112
	v_max_f32_e32 v115, v115, v115
	v_max_f32_e32 v114, v114, v114
	v_cvt_pk_bf16_f32 v120, v124, v125
	v_cvt_pk_bf16_f32 v121, v126, v127
	v_cvt_pk_bf16_f32 v122, v122, v123
	v_cvt_pk_bf16_f32 v123, v146, v147
	v_max_f32_e32 v117, 0, v117
	v_max_f32_e32 v116, 0, v116
	v_max_f32_e32 v119, 0, v119
	v_max_f32_e32 v118, 0, v118
	v_max_f32_e32 v113, 0, v113
	v_max_f32_e32 v112, 0, v112
	v_max_f32_e32 v115, 0, v115
	v_max_f32_e32 v114, 0, v114
	global_store_dwordx4 v[138:139], v[120:123], off
	v_pk_mul_f32 v[118:119], v[118:119], v[118:119]
	v_pk_mul_f32 v[116:117], v[116:117], v[116:117]
	v_pk_mul_f32 v[120:121], v[114:115], v[114:115]
	v_pk_mul_f32 v[114:115], v[112:113], v[112:113]
	v_cvt_pk_bf16_f32 v112, v116, v117
	v_cvt_pk_bf16_f32 v113, v118, v119
	v_cvt_pk_bf16_f32 v114, v114, v115
	v_cvt_pk_bf16_f32 v115, v120, v121
	global_store_dwordx4 v[138:139], v[112:115], off offset:256
	v_max_f32_e32 v109, v109, v109
	v_max_f32_e32 v108, v108, v108
	v_or_b32_e32 v112, 16, v144
	v_ashrrev_i32_e32 v113, 31, v112
	v_max_f32_e32 v111, v111, v111
	v_max_f32_e32 v110, v110, v110
	v_max_f32_e32 v105, v105, v105
	v_max_f32_e32 v104, v104, v104
	v_max_f32_e32 v107, v107, v107
	v_max_f32_e32 v106, v106, v106
	v_lshlrev_b64 v[112:113], 13, v[112:113]
	v_max_f32_e32 v109, 0, v109
	v_max_f32_e32 v108, 0, v108
	v_max_f32_e32 v111, 0, v111
	v_max_f32_e32 v110, 0, v110
	v_max_f32_e32 v105, 0, v105
	v_max_f32_e32 v104, 0, v104
	v_max_f32_e32 v107, 0, v107
	v_max_f32_e32 v106, 0, v106
	v_lshl_add_u64 v[112:113], s[10:11], 0, v[112:113]
	v_pk_mul_f32 v[110:111], v[110:111], v[110:111]
	v_pk_mul_f32 v[108:109], v[108:109], v[108:109]
	v_pk_mul_f32 v[114:115], v[106:107], v[106:107]
	v_pk_mul_f32 v[106:107], v[104:105], v[104:105]
	v_max_f32_e32 v101, v101, v101
	v_max_f32_e32 v100, v100, v100
	v_max_f32_e32 v103, v103, v103
	v_max_f32_e32 v102, v102, v102
	v_max_f32_e32 v97, v97, v97
	v_max_f32_e32 v96, v96, v96
	v_max_f32_e32 v99, v99, v99
	v_max_f32_e32 v98, v98, v98
	v_lshl_add_u64 v[112:113], v[112:113], 0, v[148:149]
	v_cvt_pk_bf16_f32 v104, v108, v109
	v_cvt_pk_bf16_f32 v105, v110, v111
	v_cvt_pk_bf16_f32 v106, v106, v107
	v_cvt_pk_bf16_f32 v107, v114, v115
	v_max_f32_e32 v101, 0, v101
	v_max_f32_e32 v100, 0, v100
	v_max_f32_e32 v103, 0, v103
	v_max_f32_e32 v102, 0, v102
	v_max_f32_e32 v97, 0, v97
	v_max_f32_e32 v96, 0, v96
	v_max_f32_e32 v99, 0, v99
	v_max_f32_e32 v98, 0, v98
	global_store_dwordx4 v[112:113], v[104:107], off
	v_pk_mul_f32 v[102:103], v[102:103], v[102:103]
	v_pk_mul_f32 v[100:101], v[100:101], v[100:101]
	v_pk_mul_f32 v[104:105], v[98:99], v[98:99]
	v_pk_mul_f32 v[98:99], v[96:97], v[96:97]
	v_cvt_pk_bf16_f32 v96, v100, v101
	v_cvt_pk_bf16_f32 v97, v102, v103
	v_cvt_pk_bf16_f32 v98, v98, v99
	v_cvt_pk_bf16_f32 v99, v104, v105
	global_store_dwordx4 v[112:113], v[96:99], off offset:256
	v_max_f32_e32 v93, v93, v93
	v_max_f32_e32 v92, v92, v92
	v_or_b32_e32 v96, 32, v144
	v_ashrrev_i32_e32 v97, 31, v96
	v_max_f32_e32 v95, v95, v95
	v_max_f32_e32 v94, v94, v94
	v_max_f32_e32 v89, v89, v89
	v_max_f32_e32 v88, v88, v88
	v_max_f32_e32 v91, v91, v91
	v_max_f32_e32 v90, v90, v90
	v_lshlrev_b64 v[96:97], 13, v[96:97]
	v_max_f32_e32 v93, 0, v93
	v_max_f32_e32 v92, 0, v92
	v_max_f32_e32 v95, 0, v95
	v_max_f32_e32 v94, 0, v94
	v_max_f32_e32 v89, 0, v89
	v_max_f32_e32 v88, 0, v88
	v_max_f32_e32 v91, 0, v91
	v_max_f32_e32 v90, 0, v90
	v_lshl_add_u64 v[96:97], s[10:11], 0, v[96:97]
	v_pk_mul_f32 v[94:95], v[94:95], v[94:95]
	v_pk_mul_f32 v[92:93], v[92:93], v[92:93]
	v_pk_mul_f32 v[98:99], v[90:91], v[90:91]
	v_pk_mul_f32 v[90:91], v[88:89], v[88:89]
	v_max_f32_e32 v85, v85, v85
	v_max_f32_e32 v84, v84, v84
	v_max_f32_e32 v87, v87, v87
	v_max_f32_e32 v86, v86, v86
	v_max_f32_e32 v81, v81, v81
	v_max_f32_e32 v80, v80, v80
	v_max_f32_e32 v83, v83, v83
	v_max_f32_e32 v82, v82, v82
	v_lshl_add_u64 v[96:97], v[96:97], 0, v[148:149]
	v_cvt_pk_bf16_f32 v88, v92, v93
	v_cvt_pk_bf16_f32 v89, v94, v95
	v_cvt_pk_bf16_f32 v90, v90, v91
	v_cvt_pk_bf16_f32 v91, v98, v99
	v_max_f32_e32 v85, 0, v85
	v_max_f32_e32 v84, 0, v84
	v_max_f32_e32 v87, 0, v87
	v_max_f32_e32 v86, 0, v86
	v_max_f32_e32 v81, 0, v81
	v_max_f32_e32 v80, 0, v80
	v_max_f32_e32 v83, 0, v83
	v_max_f32_e32 v82, 0, v82
	global_store_dwordx4 v[96:97], v[88:91], off
	v_pk_mul_f32 v[86:87], v[86:87], v[86:87]
	v_pk_mul_f32 v[84:85], v[84:85], v[84:85]
	v_pk_mul_f32 v[88:89], v[82:83], v[82:83]
	v_pk_mul_f32 v[82:83], v[80:81], v[80:81]
	v_cvt_pk_bf16_f32 v80, v84, v85
	v_cvt_pk_bf16_f32 v81, v86, v87
	v_cvt_pk_bf16_f32 v82, v82, v83
	v_cvt_pk_bf16_f32 v83, v88, v89
	global_store_dwordx4 v[96:97], v[80:83], off offset:256
	v_max_f32_e32 v77, v77, v77
	v_max_f32_e32 v76, v76, v76
	v_or_b32_e32 v80, 48, v144
	v_ashrrev_i32_e32 v81, 31, v80
	v_max_f32_e32 v79, v79, v79
	v_max_f32_e32 v78, v78, v78
	v_max_f32_e32 v73, v73, v73
	v_max_f32_e32 v72, v72, v72
	v_max_f32_e32 v75, v75, v75
	v_max_f32_e32 v74, v74, v74
	v_lshlrev_b64 v[80:81], 13, v[80:81]
	v_max_f32_e32 v77, 0, v77
	v_max_f32_e32 v76, 0, v76
	v_max_f32_e32 v79, 0, v79
	v_max_f32_e32 v78, 0, v78
	v_max_f32_e32 v73, 0, v73
	v_max_f32_e32 v72, 0, v72
	v_max_f32_e32 v75, 0, v75
	v_max_f32_e32 v74, 0, v74
	v_lshl_add_u64 v[80:81], s[10:11], 0, v[80:81]
	v_pk_mul_f32 v[78:79], v[78:79], v[78:79]
	v_pk_mul_f32 v[76:77], v[76:77], v[76:77]
	v_pk_mul_f32 v[82:83], v[74:75], v[74:75]
	v_pk_mul_f32 v[74:75], v[72:73], v[72:73]
	v_max_f32_e32 v69, v69, v69
	v_max_f32_e32 v68, v68, v68
	v_max_f32_e32 v71, v71, v71
	v_max_f32_e32 v70, v70, v70
	v_max_f32_e32 v65, v65, v65
	v_max_f32_e32 v64, v64, v64
	v_max_f32_e32 v67, v67, v67
	v_max_f32_e32 v66, v66, v66
	v_lshl_add_u64 v[80:81], v[80:81], 0, v[148:149]
	v_cvt_pk_bf16_f32 v72, v76, v77
	v_cvt_pk_bf16_f32 v73, v78, v79
	v_cvt_pk_bf16_f32 v74, v74, v75
	v_cvt_pk_bf16_f32 v75, v82, v83
	v_max_f32_e32 v69, 0, v69
	v_max_f32_e32 v68, 0, v68
	v_max_f32_e32 v71, 0, v71
	v_max_f32_e32 v70, 0, v70
	v_max_f32_e32 v65, 0, v65
	v_max_f32_e32 v64, 0, v64
	v_max_f32_e32 v67, 0, v67
	v_max_f32_e32 v66, 0, v66
	v_max_f32_e32 v61, v61, v61
	v_max_f32_e32 v60, v60, v60
	global_store_dwordx4 v[80:81], v[72:75], off
	v_pk_mul_f32 v[70:71], v[70:71], v[70:71]
	v_pk_mul_f32 v[68:69], v[68:69], v[68:69]
	v_pk_mul_f32 v[72:73], v[66:67], v[66:67]
	v_pk_mul_f32 v[66:67], v[64:65], v[64:65]
	v_max_f32_e32 v61, 0, v61
	v_max_f32_e32 v60, 0, v60
	v_max_f32_e32 v63, v63, v63
	v_max_f32_e32 v62, v62, v62
	v_max_f32_e32 v57, v57, v57
	v_max_f32_e32 v56, v56, v56
	v_max_f32_e32 v59, v59, v59
	v_max_f32_e32 v58, v58, v58
	v_cvt_pk_bf16_f32 v64, v68, v69
	v_cvt_pk_bf16_f32 v65, v70, v71
	v_cvt_pk_bf16_f32 v66, v66, v67
	v_cvt_pk_bf16_f32 v67, v72, v73
	v_max_f32_e32 v63, 0, v63
	v_max_f32_e32 v62, 0, v62
	v_max_f32_e32 v57, 0, v57
	v_max_f32_e32 v56, 0, v56
	v_max_f32_e32 v59, 0, v59
	v_max_f32_e32 v58, 0, v58
	v_pk_mul_f32 v[60:61], v[60:61], v[60:61]
	s_mov_b32 s13, 0x100000
	global_store_dwordx4 v[80:81], v[64:67], off offset:256
	v_pk_mul_f32 v[62:63], v[62:63], v[62:63]
	v_max_f32_e32 v53, v53, v53
	v_pk_mul_f32 v[66:67], v[58:59], v[58:59]
	v_pk_mul_f32 v[58:59], v[56:57], v[56:57]
	v_cvt_pk_bf16_f32 v56, v60, v61
	v_add_co_u32_e32 v60, vcc, s13, v138
	v_max_f32_e32 v52, v52, v52
	v_max_f32_e32 v55, v55, v55
	v_max_f32_e32 v54, v54, v54
	v_max_f32_e32 v49, v49, v49
	v_max_f32_e32 v48, v48, v48
	v_max_f32_e32 v51, v51, v51
	v_max_f32_e32 v50, v50, v50
	v_cvt_pk_bf16_f32 v57, v62, v63
	v_cvt_pk_bf16_f32 v58, v58, v59
	v_cvt_pk_bf16_f32 v59, v66, v67
	v_addc_co_u32_e32 v61, vcc, 0, v139, vcc
	v_max_f32_e32 v53, 0, v53
	v_max_f32_e32 v52, 0, v52
	v_max_f32_e32 v55, 0, v55
	v_max_f32_e32 v54, 0, v54
	v_max_f32_e32 v49, 0, v49
	v_max_f32_e32 v48, 0, v48
	v_max_f32_e32 v51, 0, v51
	v_max_f32_e32 v50, 0, v50
	v_max_f32_e32 v45, v45, v45
	v_max_f32_e32 v44, v44, v44
	s_mov_b64 s[20:21], 0x100000
	global_store_dwordx4 v[60:61], v[56:59], off
	v_pk_mul_f32 v[54:55], v[54:55], v[54:55]
	v_pk_mul_f32 v[52:53], v[52:53], v[52:53]
	v_pk_mul_f32 v[56:57], v[50:51], v[50:51]
	v_pk_mul_f32 v[50:51], v[48:49], v[48:49]
	v_max_f32_e32 v45, 0, v45
	v_max_f32_e32 v44, 0, v44
	v_max_f32_e32 v47, v47, v47
	v_max_f32_e32 v46, v46, v46
	v_max_f32_e32 v41, v41, v41
	v_max_f32_e32 v40, v40, v40
	v_max_f32_e32 v43, v43, v43
	v_max_f32_e32 v42, v42, v42
	v_lshl_add_u64 v[64:65], v[138:139], 0, s[20:21]
	v_cvt_pk_bf16_f32 v48, v52, v53
	v_cvt_pk_bf16_f32 v49, v54, v55
	v_cvt_pk_bf16_f32 v50, v50, v51
	v_cvt_pk_bf16_f32 v51, v56, v57
	v_max_f32_e32 v47, 0, v47
	v_max_f32_e32 v46, 0, v46
	v_max_f32_e32 v41, 0, v41
	v_max_f32_e32 v40, 0, v40
	v_max_f32_e32 v43, 0, v43
	v_max_f32_e32 v42, 0, v42
	v_pk_mul_f32 v[44:45], v[44:45], v[44:45]
	s_mov_b32 s13, 0x120000
	global_store_dwordx4 v[64:65], v[48:51], off offset:256
	v_pk_mul_f32 v[46:47], v[46:47], v[46:47]
	v_max_f32_e32 v37, v37, v37
	v_pk_mul_f32 v[50:51], v[42:43], v[42:43]
	v_pk_mul_f32 v[42:43], v[40:41], v[40:41]
	v_cvt_pk_bf16_f32 v40, v44, v45
	v_add_co_u32_e32 v44, vcc, s13, v138
	v_max_f32_e32 v36, v36, v36
	v_max_f32_e32 v39, v39, v39
	v_max_f32_e32 v38, v38, v38
	v_max_f32_e32 v33, v33, v33
	v_max_f32_e32 v32, v32, v32
	v_max_f32_e32 v35, v35, v35
	v_max_f32_e32 v34, v34, v34
	v_cvt_pk_bf16_f32 v41, v46, v47
	v_cvt_pk_bf16_f32 v42, v42, v43
	v_cvt_pk_bf16_f32 v43, v50, v51
	v_addc_co_u32_e32 v45, vcc, 0, v139, vcc
	v_max_f32_e32 v37, 0, v37
	v_max_f32_e32 v36, 0, v36
	v_max_f32_e32 v39, 0, v39
	v_max_f32_e32 v38, 0, v38
	v_max_f32_e32 v33, 0, v33
	v_max_f32_e32 v32, 0, v32
	v_max_f32_e32 v35, 0, v35
	v_max_f32_e32 v34, 0, v34
	v_max_f32_e32 v29, v29, v29
	v_max_f32_e32 v28, v28, v28
	s_mov_b64 s[20:21], 0x120000
	global_store_dwordx4 v[44:45], v[40:43], off
	v_pk_mul_f32 v[38:39], v[38:39], v[38:39]
	v_pk_mul_f32 v[36:37], v[36:37], v[36:37]
	v_pk_mul_f32 v[40:41], v[34:35], v[34:35]
	v_pk_mul_f32 v[34:35], v[32:33], v[32:33]
	v_max_f32_e32 v29, 0, v29
	v_max_f32_e32 v28, 0, v28
	v_max_f32_e32 v31, v31, v31
	v_max_f32_e32 v30, v30, v30
	v_max_f32_e32 v25, v25, v25
	v_max_f32_e32 v24, v24, v24
	v_max_f32_e32 v27, v27, v27
	v_max_f32_e32 v26, v26, v26
	v_lshl_add_u64 v[48:49], v[138:139], 0, s[20:21]
	v_cvt_pk_bf16_f32 v32, v36, v37
	v_cvt_pk_bf16_f32 v33, v38, v39
	v_cvt_pk_bf16_f32 v34, v34, v35
	v_cvt_pk_bf16_f32 v35, v40, v41
	v_max_f32_e32 v31, 0, v31
	v_max_f32_e32 v30, 0, v30
	v_max_f32_e32 v25, 0, v25
	v_max_f32_e32 v24, 0, v24
	v_max_f32_e32 v27, 0, v27
	v_max_f32_e32 v26, 0, v26
	v_pk_mul_f32 v[28:29], v[28:29], v[28:29]
	s_mov_b32 s13, 0x140000
	global_store_dwordx4 v[48:49], v[32:35], off offset:256
	v_pk_mul_f32 v[30:31], v[30:31], v[30:31]
	v_max_f32_e32 v21, v21, v21
	v_pk_mul_f32 v[34:35], v[26:27], v[26:27]
	v_pk_mul_f32 v[26:27], v[24:25], v[24:25]
	v_cvt_pk_bf16_f32 v24, v28, v29
	v_add_co_u32_e32 v28, vcc, s13, v138
	v_max_f32_e32 v20, v20, v20
	v_max_f32_e32 v23, v23, v23
	v_max_f32_e32 v22, v22, v22
	v_max_f32_e32 v17, v17, v17
	v_max_f32_e32 v16, v16, v16
	v_max_f32_e32 v19, v19, v19
	v_max_f32_e32 v18, v18, v18
	v_cvt_pk_bf16_f32 v25, v30, v31
	v_cvt_pk_bf16_f32 v26, v26, v27
	v_cvt_pk_bf16_f32 v27, v34, v35
	v_addc_co_u32_e32 v29, vcc, 0, v139, vcc
	v_max_f32_e32 v21, 0, v21
	v_max_f32_e32 v20, 0, v20
	v_max_f32_e32 v23, 0, v23
	v_max_f32_e32 v22, 0, v22
	v_max_f32_e32 v17, 0, v17
	v_max_f32_e32 v16, 0, v16
	v_max_f32_e32 v19, 0, v19
	v_max_f32_e32 v18, 0, v18
	v_max_f32_e32 v13, v13, v13
	v_max_f32_e32 v12, v12, v12
	s_mov_b64 s[20:21], 0x140000
	global_store_dwordx4 v[28:29], v[24:27], off
	v_pk_mul_f32 v[22:23], v[22:23], v[22:23]
	v_pk_mul_f32 v[20:21], v[20:21], v[20:21]
	v_pk_mul_f32 v[24:25], v[18:19], v[18:19]
	v_pk_mul_f32 v[18:19], v[16:17], v[16:17]
	v_max_f32_e32 v13, 0, v13
	v_max_f32_e32 v12, 0, v12
	v_max_f32_e32 v15, v15, v15
	v_max_f32_e32 v14, v14, v14
	v_max_f32_e32 v9, v9, v9
	v_max_f32_e32 v8, v8, v8
	v_max_f32_e32 v11, v11, v11
	v_max_f32_e32 v10, v10, v10
	v_lshl_add_u64 v[32:33], v[138:139], 0, s[20:21]
	v_cvt_pk_bf16_f32 v16, v20, v21
	v_cvt_pk_bf16_f32 v17, v22, v23
	v_cvt_pk_bf16_f32 v18, v18, v19
	v_cvt_pk_bf16_f32 v19, v24, v25
	v_max_f32_e32 v15, 0, v15
	v_max_f32_e32 v14, 0, v14
	v_max_f32_e32 v9, 0, v9
	v_max_f32_e32 v8, 0, v8
	v_max_f32_e32 v11, 0, v11
	v_max_f32_e32 v10, 0, v10
	v_pk_mul_f32 v[12:13], v[12:13], v[12:13]
	s_mov_b32 s13, 0x160000
	global_store_dwordx4 v[32:33], v[16:19], off offset:256
	v_pk_mul_f32 v[14:15], v[14:15], v[14:15]
	v_max_f32_e32 v5, v5, v5
	v_pk_mul_f32 v[18:19], v[10:11], v[10:11]
	v_pk_mul_f32 v[10:11], v[8:9], v[8:9]
	v_cvt_pk_bf16_f32 v8, v12, v13
	v_add_co_u32_e32 v12, vcc, s13, v138
	v_max_f32_e32 v4, v4, v4
	v_max_f32_e32 v7, v7, v7
	v_max_f32_e32 v6, v6, v6
	v_max_f32_e32 v1, v1, v1
	v_max_f32_e32 v0, v0, v0
	v_max_f32_e32 v3, v3, v3
	v_max_f32_e32 v2, v2, v2
	v_cvt_pk_bf16_f32 v9, v14, v15
	v_cvt_pk_bf16_f32 v10, v10, v11
	v_cvt_pk_bf16_f32 v11, v18, v19
	v_addc_co_u32_e32 v13, vcc, 0, v139, vcc
	v_max_f32_e32 v5, 0, v5
	v_max_f32_e32 v4, 0, v4
	v_max_f32_e32 v7, 0, v7
	v_max_f32_e32 v6, 0, v6
	v_max_f32_e32 v1, 0, v1
	v_max_f32_e32 v0, 0, v0
	v_max_f32_e32 v3, 0, v3
	v_max_f32_e32 v2, 0, v2
	s_mov_b64 s[20:21], 0x160000
	global_store_dwordx4 v[12:13], v[8:11], off
	v_pk_mul_f32 v[6:7], v[6:7], v[6:7]
	v_pk_mul_f32 v[4:5], v[4:5], v[4:5]
	v_pk_mul_f32 v[8:9], v[2:3], v[2:3]
	v_pk_mul_f32 v[2:3], v[0:1], v[0:1]
	v_lshl_add_u64 v[16:17], v[138:139], 0, s[20:21]
	v_cvt_pk_bf16_f32 v0, v4, v5
	v_cvt_pk_bf16_f32 v1, v6, v7
	v_cvt_pk_bf16_f32 v2, v2, v3
	v_cvt_pk_bf16_f32 v3, v8, v9
	s_andn2_b64 vcc, exec, s[6:7]
	s_mov_b64 s[6:7], -1
	global_store_dwordx4 v[16:17], v[0:3], off offset:256
	s_cbranch_vccnz .LBB0_64
	s_and_b64 vcc, exec, s[4:5]
	s_cbranch_vccnz .LBB0_63
	s_barrier
	s_branch .LBB0_63

.LBB0_83:
	v_writelane_b32 v252, s4, 35
	s_and_b64 vcc, exec, s[8:9]
	s_nop 0
	v_writelane_b32 v252, s5, 36
	s_cbranch_vccz .LBB0_90
	v_mov_b32_e32 v0, 0xe0
	v_readlane_b32 s4, v253, 11
	v_add_u32_e32 v0, s91, v0
	ds_read_b64 v[0:1], v0
	s_waitcnt lgkmcnt(0)
	v_readfirstlane_b32 s6, v0
	v_mov_b32_e32 v0, 24
	v_readfirstlane_b32 s7, v1
	v_add_u32_e32 v0, s91, v0
	ds_read_b64 v[0:1], v0
	s_waitcnt lgkmcnt(0)
	v_readfirstlane_b32 s10, v0
	v_mov_b32_e32 v0, 0xe8
	v_readfirstlane_b32 s2, v1
	v_add_u32_e32 v0, s91, v0
	ds_read_b64 v[0:1], v0
	s_waitcnt lgkmcnt(0)
	v_readfirstlane_b32 s9, v1
	v_readfirstlane_b32 s8, v0
	v_mbcnt_lo_u32_b32 v0, -1, 0
	v_mbcnt_hi_u32_b32 v0, -1, v0
	s_nop 0
	v_add_u32_e32 v1, s57, v0
	v_ashrrev_i32_e32 v1, 6, v1
	v_add_u32_e32 v56, s4, v1
	v_cmp_gt_i32_e32 vcc, s3, v56
	s_and_saveexec_b64 s[4:5], vcc
	v_readlane_b32 s14, v252, 23
	s_cbranch_execz .LBB0_89
	v_readlane_b32 s11, v252, 31
	s_lshl_b32 s12, s11, 10
	s_ashr_i32 s13, s12, 31
	s_lshl_b64 s[12:13], s[12:13], 2
	s_add_u32 s10, s10, s12
	v_and_b32_e32 v18, 63, v0
	s_addc_u32 s11, s2, s13
	v_lshlrev_b32_e32 v160, 4, v18
	v_lshl_add_u64 v[12:13], s[10:11], 0, v[160:161]
	global_load_dwordx4 v[0:3], v[12:13], off
	global_load_dwordx4 v[4:7], v[12:13], off offset:1024
	global_load_dwordx4 v[8:11], v[12:13], off offset:2048
	s_nop 0
	global_load_dwordx4 v[12:15], v[12:13], off offset:3072
	v_cmp_lt_i32_e32 vcc, v214, v213
	v_lshl_add_u64 v[48:49], s[6:7], 0, v[160:161]
	v_readlane_b32 s6, v252, 32
	v_cndmask_b32_e32 v16, v211, v214, vcc
	v_cmp_lt_i32_e32 vcc, v215, v213
	v_lshlrev_b32_e32 v61, 2, v16
	v_readlane_b32 s7, v252, 33
	v_cndmask_b32_e32 v16, v211, v215, vcc
	v_cmp_lt_i32_e32 vcc, v216, v213
	v_lshlrev_b32_e32 v66, 2, v16
	s_nop 0
	v_cndmask_b32_e32 v16, v211, v216, vcc
	v_cmp_lt_i32_e32 vcc, v217, v213
	v_lshlrev_b32_e32 v67, 2, v16
	s_nop 0
	v_cndmask_b32_e32 v16, v211, v217, vcc
	v_cmp_lt_i32_e32 vcc, v218, v213
	v_lshlrev_b32_e32 v68, 2, v16
	s_nop 0
	v_cndmask_b32_e32 v16, v211, v218, vcc
	v_lshlrev_b32_e32 v69, 2, v16
	v_xor_b32_e32 v16, 32, v211
	v_cmp_lt_i32_e32 vcc, v16, v213
	s_nop 1
	v_cndmask_b32_e32 v16, v211, v16, vcc
	v_lshlrev_b32_e32 v70, 2, v16
	v_lshl_add_u64 v[16:17], s[6:7], 0, v[160:161]
	s_mov_b64 s[6:7], 0x4000
	v_lshl_add_u64 v[50:51], v[16:17], 0, s[6:7]
	s_mov_b64 s[6:7], 0x3000
	v_lshlrev_b32_e32 v160, 3, v18
	v_lshl_add_u64 v[52:53], v[16:17], 0, s[6:7]
	v_lshl_add_u64 v[16:17], s[8:9], 0, v[160:161]
	s_mov_b64 s[6:7], 0x5200000
	v_lshl_add_u64 v[54:55], v[16:17], 0, s[6:7]
	s_mov_b64 s[6:7], 0
	s_branch .LBB0_87

.LBB0_87:
	v_ashrrev_i32_e32 v57, 31, v56
	v_lshlrev_b64 v[16:17], 12, v[56:57]
	v_lshl_add_u64 v[16:17], v[48:49], 0, v[16:17]
	global_load_dwordx4 v[44:47], v[16:17], off
	global_load_dwordx4 v[40:43], v[16:17], off offset:1024
	global_load_dwordx4 v[36:39], v[16:17], off offset:2048
	global_load_dwordx4 v[32:35], v[16:17], off offset:3072
	v_add_u32_e32 v71, s14, v56
	v_cmp_gt_i32_e32 vcc, s3, v71
	s_mov_b32 s2, 0x800000
	s_waitcnt vmcnt(0) lgkmcnt(0)
	v_pk_mul_f32 v[62:63], v[46:47], v[46:47]
	v_cndmask_b32_e32 v58, v56, v71, vcc
	v_ashrrev_i32_e32 v59, 31, v58
	v_lshlrev_b64 v[16:17], 12, v[58:59]
	v_lshl_add_u64 v[16:17], v[48:49], 0, v[16:17]
	global_load_dwordx4 v[28:31], v[16:17], off
	global_load_dwordx4 v[24:27], v[16:17], off offset:1024
	global_load_dwordx4 v[20:23], v[16:17], off offset:2048
	s_nop 0
	global_load_dwordx4 v[16:19], v[16:17], off offset:3072
	v_pk_mul_f32 v[64:65], v[44:45], v[44:45]
	v_mul_f32_e32 v60, v32, v32
	v_pk_mov_b32 v[72:73], v[64:65], v[62:63] op_sel:[1,0]
	v_mov_b32_e32 v65, v63
	v_pk_add_f32 v[62:63], v[72:73], v[64:65]
	v_pk_mul_f32 v[64:65], v[42:43], v[42:43]
	v_pk_mul_f32 v[72:73], v[40:41], v[40:41]
	v_pk_add_f32 v[62:63], v[62:63], v[62:63] op_sel:[0,1] op_sel_hi:[1,0]
	v_pk_mov_b32 v[74:75], v[72:73], v[64:65] op_sel:[1,0]
	v_mov_b32_e32 v73, v65
	v_pk_add_f32 v[64:65], v[74:75], v[72:73]
	v_mul_f32_e32 v72, v33, v33
	v_pk_add_f32 v[64:65], v[64:65], v[64:65] op_sel:[0,1] op_sel_hi:[1,0]
	v_mov_b32_e32 v63, v60
	v_mov_b32_e32 v65, v72
	v_mul_f32_e32 v60, v37, v37
	v_mul_f32_e32 v73, v34, v34
	v_pk_add_f32 v[62:63], v[62:63], v[64:65]
	v_pk_fma_f32 v[64:65], v[36:37], v[36:37], v[60:61] op_sel_hi:[1,1,0]
	v_mul_f32_e32 v60, v39, v39
	v_mul_f32_e32 v74, v35, v35
	v_mov_b32_e32 v65, v73
	v_pk_fma_f32 v[72:73], v[38:39], v[38:39], v[60:61] op_sel_hi:[1,1,0]
	s_nop 0
	v_mov_b32_e32 v73, v74
	v_pk_add_f32 v[64:65], v[64:65], v[72:73]
	v_lshlrev_b64 v[74:75], 11, v[56:57]
	v_pk_add_f32 v[62:63], v[62:63], v[64:65]
	s_waitcnt vmcnt(0) lgkmcnt(0)
	v_mul_f32_e32 v64, v27, v27
	v_add_f32_e32 v60, v62, v63
	v_mul_f32_e32 v62, v29, v29
	v_mul_f32_e32 v63, v31, v31
	v_fmac_f32_e32 v62, v28, v28
	v_fmac_f32_e32 v63, v30, v30
	v_add_f32_e32 v62, v62, v63
	v_mul_f32_e32 v63, v25, v25
	v_fmac_f32_e32 v63, v24, v24
	v_fmac_f32_e32 v64, v26, v26
	v_add_f32_e32 v63, v63, v64
	v_add_f32_e32 v62, v62, v63
	v_mul_f32_e32 v63, v21, v21
	v_mul_f32_e32 v64, v23, v23
	v_fmac_f32_e32 v63, v20, v20
	v_fmac_f32_e32 v64, v22, v22
	v_add_f32_e32 v63, v63, v64
	v_add_f32_e32 v62, v62, v63
	v_mul_f32_e32 v63, v17, v17
	v_mul_f32_e32 v64, v19, v19
	v_fmac_f32_e32 v63, v16, v16
	v_fmac_f32_e32 v64, v18, v18
	v_add_f32_e32 v63, v63, v64
	v_add_f32_e32 v62, v62, v63
	ds_bpermute_b32 v63, v61, v60
	s_waitcnt lgkmcnt(0)
	v_add_f32_e32 v60, v60, v63
	ds_bpermute_b32 v63, v61, v62
	s_waitcnt lgkmcnt(0)
	v_add_f32_e32 v62, v62, v63
	ds_bpermute_b32 v63, v66, v60
	s_waitcnt lgkmcnt(0)
	v_add_f32_e32 v60, v60, v63
	ds_bpermute_b32 v63, v66, v62
	s_waitcnt lgkmcnt(0)
	v_add_f32_e32 v62, v62, v63
	ds_bpermute_b32 v63, v67, v60
	s_waitcnt lgkmcnt(0)
	v_add_f32_e32 v60, v60, v63
	ds_bpermute_b32 v63, v67, v62
	s_waitcnt lgkmcnt(0)
	v_add_f32_e32 v62, v62, v63
	ds_bpermute_b32 v63, v68, v60
	s_waitcnt lgkmcnt(0)
	v_add_f32_e32 v60, v60, v63
	ds_bpermute_b32 v63, v68, v62
	s_waitcnt lgkmcnt(0)
	v_add_f32_e32 v62, v62, v63
	ds_bpermute_b32 v63, v69, v60
	s_waitcnt lgkmcnt(0)
	v_add_f32_e32 v60, v60, v63
	ds_bpermute_b32 v63, v69, v62
	s_waitcnt lgkmcnt(0)
	v_add_f32_e32 v72, v62, v63
	ds_bpermute_b32 v62, v70, v60
	ds_bpermute_b32 v73, v70, v72
	s_waitcnt lgkmcnt(1)
	v_add_f32_e32 v60, v60, v62
	v_fmamk_f32 v60, v60, 0x3a800000, v208
	v_cmp_gt_f32_e32 vcc, s2, v60
	v_mul_f32_e32 v62, 0x4b800000, v60
	s_nop 0
	v_cndmask_b32_e32 v60, v60, v62, vcc
	v_rsq_f32_e32 v60, v60
	s_nop 0
	v_mul_f32_e32 v62, 0x45800000, v60
	v_cndmask_b32_e32 v60, v60, v62, vcc
	v_ashrrev_i32_e32 v62, 11, v56
	v_mul_hi_i32_i24_e32 v63, 0x1800, v62
	v_mul_i32_i24_e32 v62, 0x1800, v62
	v_pk_mul_f32 v[46:47], v[46:47], v[60:61] op_sel_hi:[1,0]
	v_pk_mul_f32 v[44:45], v[44:45], v[60:61] op_sel_hi:[1,0]
	v_pk_mul_f32 v[78:79], v[2:3], v[46:47]
	v_lshlrev_b64 v[46:47], 2, v[62:63]
	v_pk_mul_f32 v[76:77], v[0:1], v[44:45]
	v_lshl_add_u64 v[44:45], v[50:51], 0, v[46:47]
	global_load_dwordx4 v[62:65], v[44:45], off
	v_lshl_add_u64 v[46:47], v[52:53], 0, v[46:47]
	v_pk_mul_f32 v[42:43], v[42:43], v[60:61] op_sel_hi:[1,0]
	v_pk_mul_f32 v[40:41], v[40:41], v[60:61] op_sel_hi:[1,0]
	v_pk_mul_f32 v[38:39], v[38:39], v[60:61] op_sel_hi:[1,0]
	v_pk_mul_f32 v[36:37], v[36:37], v[60:61] op_sel_hi:[1,0]
	v_pk_mul_f32 v[34:35], v[34:35], v[60:61] op_sel_hi:[1,0]
	v_pk_mul_f32 v[32:33], v[32:33], v[60:61] op_sel_hi:[1,0]
	v_cmp_ne_u32_e32 vcc, v56, v58
	s_waitcnt vmcnt(0) lgkmcnt(0)
	v_pk_add_f32 v[80:81], v[64:65], 1.0 op_sel_hi:[1,0]
	v_pk_add_f32 v[82:83], v[62:63], 1.0 op_sel_hi:[1,0]
	global_load_dwordx4 v[62:65], v[46:47], off
	s_waitcnt vmcnt(0) lgkmcnt(0)
	v_pk_fma_f32 v[78:79], v[80:81], v[78:79], v[64:65]
	v_pk_fma_f32 v[62:63], v[82:83], v[76:77], v[62:63]
	v_cvt_pk_bf16_f32 v65, v78, v79
	v_cvt_pk_bf16_f32 v64, v62, v63
	v_lshl_add_u64 v[62:63], v[54:55], 0, v[74:75]
	global_store_dwordx2 v[62:63], v[64:65], off
	v_pk_mul_f32 v[64:65], v[4:5], v[40:41]
	v_pk_mul_f32 v[74:75], v[6:7], v[42:43]
	global_load_dwordx4 v[40:43], v[44:45], off offset:1024
	s_waitcnt vmcnt(0) lgkmcnt(0)
	v_pk_add_f32 v[76:77], v[42:43], 1.0 op_sel_hi:[1,0]
	v_pk_add_f32 v[78:79], v[40:41], 1.0 op_sel_hi:[1,0]
	global_load_dwordx4 v[40:43], v[46:47], off offset:1024
	s_waitcnt vmcnt(0) lgkmcnt(0)
	v_pk_fma_f32 v[42:43], v[76:77], v[74:75], v[42:43]
	v_pk_fma_f32 v[40:41], v[78:79], v[64:65], v[40:41]
	s_nop 0
	v_cvt_pk_bf16_f32 v40, v40, v41
	v_cvt_pk_bf16_f32 v41, v42, v43
	global_store_dwordx2 v[62:63], v[40:41], off offset:512
	v_pk_mul_f32 v[40:41], v[8:9], v[36:37]
	v_pk_mul_f32 v[42:43], v[10:11], v[38:39]
	global_load_dwordx4 v[36:39], v[44:45], off offset:2048
	s_waitcnt vmcnt(0) lgkmcnt(0)
	v_pk_add_f32 v[64:65], v[38:39], 1.0 op_sel_hi:[1,0]
	v_pk_add_f32 v[74:75], v[36:37], 1.0 op_sel_hi:[1,0]
	global_load_dwordx4 v[36:39], v[46:47], off offset:2048
	s_waitcnt vmcnt(0) lgkmcnt(0)
	v_pk_fma_f32 v[38:39], v[64:65], v[42:43], v[38:39]
	v_pk_fma_f32 v[36:37], v[74:75], v[40:41], v[36:37]
	s_nop 0
	v_cvt_pk_bf16_f32 v36, v36, v37
	v_cvt_pk_bf16_f32 v37, v38, v39
	global_store_dwordx2 v[62:63], v[36:37], off offset:1024
	v_pk_mul_f32 v[36:37], v[12:13], v[32:33]
	v_pk_mul_f32 v[38:39], v[14:15], v[34:35]
	global_load_dwordx4 v[32:35], v[44:45], off offset:3072
	s_waitcnt vmcnt(0) lgkmcnt(0)
	v_pk_add_f32 v[40:41], v[34:35], 1.0 op_sel_hi:[1,0]
	v_pk_add_f32 v[42:43], v[32:33], 1.0 op_sel_hi:[1,0]
	global_load_dwordx4 v[32:35], v[46:47], off offset:3072
	s_waitcnt vmcnt(0) lgkmcnt(0)
	v_pk_fma_f32 v[34:35], v[40:41], v[38:39], v[34:35]
	v_pk_fma_f32 v[32:33], v[42:43], v[36:37], v[32:33]
	s_nop 0
	v_cvt_pk_bf16_f32 v32, v32, v33
	v_cvt_pk_bf16_f32 v33, v34, v35
	global_store_dwordx2 v[62:63], v[32:33], off offset:1536
	s_and_saveexec_b64 s[8:9], vcc
	s_cbranch_execz .LBB0_86
	v_ashrrev_i32_e32 v32, 11, v58
	v_mul_hi_i32_i24_e32 v33, 0x1800, v32
	v_mul_i32_i24_e32 v32, 0x1800, v32
	v_lshlrev_b64 v[36:37], 2, v[32:33]
	v_lshl_add_u64 v[40:41], v[50:51], 0, v[36:37]
	global_load_dwordx4 v[32:35], v[40:41], off
	v_lshl_add_u64 v[42:43], v[52:53], 0, v[36:37]
	global_load_dwordx4 v[36:39], v[42:43], off
	v_add_f32_e32 v44, v72, v73
	v_fmamk_f32 v44, v44, 0x3a800000, v208
	v_mul_f32_e32 v45, 0x4b800000, v44
	v_cmp_gt_f32_e32 vcc, s2, v44
	s_waitcnt vmcnt(0) lgkmcnt(0)
	v_pk_add_f32 v[34:35], v[34:35], 1.0 op_sel_hi:[1,0]
	v_cndmask_b32_e32 v44, v44, v45, vcc
	v_rsq_f32_e32 v46, v44
	v_pk_add_f32 v[32:33], v[32:33], 1.0 op_sel_hi:[1,0]
	v_lshlrev_b64 v[44:45], 11, v[58:59]
	v_lshl_add_u64 v[44:45], v[54:55], 0, v[44:45]
	v_mul_f32_e32 v47, 0x45800000, v46
	v_cndmask_b32_e32 v46, v46, v47, vcc
	v_pk_mul_f32 v[30:31], v[30:31], v[46:47] op_sel_hi:[1,0]
	v_pk_mul_f32 v[28:29], v[28:29], v[46:47] op_sel_hi:[1,0]
	v_pk_mul_f32 v[30:31], v[2:3], v[30:31]
	v_pk_mul_f32 v[28:29], v[0:1], v[28:29]
	v_pk_fma_f32 v[30:31], v[30:31], v[34:35], v[38:39]
	v_pk_fma_f32 v[28:29], v[28:29], v[32:33], v[36:37]
	v_pk_mul_f32 v[26:27], v[26:27], v[46:47] op_sel_hi:[1,0]
	v_cvt_pk_bf16_f32 v28, v28, v29
	v_cvt_pk_bf16_f32 v29, v30, v31
	global_store_dwordx2 v[44:45], v[28:29], off
	global_load_dwordx4 v[28:31], v[40:41], off offset:1024
	s_nop 0
	global_load_dwordx4 v[32:35], v[42:43], off offset:1024
	v_pk_mul_f32 v[24:25], v[24:25], v[46:47] op_sel_hi:[1,0]
	v_pk_mul_f32 v[26:27], v[6:7], v[26:27]
	v_pk_mul_f32 v[24:25], v[4:5], v[24:25]
	v_pk_mul_f32 v[22:23], v[22:23], v[46:47] op_sel_hi:[1,0]
	v_pk_mul_f32 v[20:21], v[20:21], v[46:47] op_sel_hi:[1,0]
	v_pk_mul_f32 v[22:23], v[10:11], v[22:23]
	v_pk_mul_f32 v[20:21], v[8:9], v[20:21]
	v_pk_mul_f32 v[18:19], v[18:19], v[46:47] op_sel_hi:[1,0]
	v_pk_mul_f32 v[16:17], v[16:17], v[46:47] op_sel_hi:[1,0]
	v_pk_mul_f32 v[18:19], v[14:15], v[18:19]
	v_pk_mul_f32 v[16:17], v[12:13], v[16:17]
	s_waitcnt vmcnt(0) lgkmcnt(0)
	v_pk_add_f32 v[30:31], v[30:31], 1.0 op_sel_hi:[1,0]
	v_pk_add_f32 v[28:29], v[28:29], 1.0 op_sel_hi:[1,0]
	v_pk_fma_f32 v[26:27], v[26:27], v[30:31], v[34:35]
	v_pk_fma_f32 v[24:25], v[24:25], v[28:29], v[32:33]
	s_nop 0
	v_cvt_pk_bf16_f32 v24, v24, v25
	v_cvt_pk_bf16_f32 v25, v26, v27
	global_store_dwordx2 v[44:45], v[24:25], off offset:512
	global_load_dwordx4 v[24:27], v[40:41], off offset:2048
	s_nop 0
	global_load_dwordx4 v[28:31], v[42:43], off offset:2048
	s_waitcnt vmcnt(0) lgkmcnt(0)
	v_pk_add_f32 v[26:27], v[26:27], 1.0 op_sel_hi:[1,0]
	v_pk_add_f32 v[24:25], v[24:25], 1.0 op_sel_hi:[1,0]
	v_pk_fma_f32 v[22:23], v[22:23], v[26:27], v[30:31]
	v_pk_fma_f32 v[20:21], v[20:21], v[24:25], v[28:29]
	s_nop 0
	v_cvt_pk_bf16_f32 v20, v20, v21
	v_cvt_pk_bf16_f32 v21, v22, v23
	global_store_dwordx2 v[44:45], v[20:21], off offset:1024
	global_load_dwordx4 v[20:23], v[40:41], off offset:3072
	s_nop 0
	global_load_dwordx4 v[24:27], v[42:43], off offset:3072
	s_waitcnt vmcnt(0) lgkmcnt(0)
	v_pk_add_f32 v[22:23], v[22:23], 1.0 op_sel_hi:[1,0]
	v_pk_add_f32 v[20:21], v[20:21], 1.0 op_sel_hi:[1,0]
	v_pk_fma_f32 v[18:19], v[18:19], v[22:23], v[26:27]
	v_pk_fma_f32 v[16:17], v[16:17], v[20:21], v[24:25]
	s_nop 0
	v_cvt_pk_bf16_f32 v16, v16, v17
	v_cvt_pk_bf16_f32 v17, v18, v19
	global_store_dwordx2 v[44:45], v[16:17], off offset:1536
	s_branch .LBB0_86

.LBB0_108:
	v_lshl_add_u32 v154, s39, 8, v156
	v_lshl_add_u32 v152, s38, 8, v158
	s_ashr_i32 s11, s39, 3
	v_ashrrev_i32_e32 v155, 31, v154
	s_mul_hi_i32 s13, s11, 0x6000
	s_mulk_i32 s11, 0x6000
	v_ashrrev_i32_e32 v153, 31, v152
	v_lshlrev_b64 v[148:149], 10, v[154:155]
	s_add_u32 s18, s31, s11
	v_lshl_add_u64 v[148:149], v[148:149], 0, v[152:153]
	v_readlane_b32 s20, v252, 25
	s_addc_u32 s19, s34, s13
	v_lshlrev_b64 v[150:151], 2, v[148:149]
	v_readlane_b32 s21, v252, 26
	v_lshl_add_u64 v[146:147], v[152:153], 2, s[18:19]
	global_load_dwordx4 v[132:135], v[146:147], off
	global_load_dwordx4 v[128:131], v[146:147], off offset:16
	v_lshl_add_u64 v[148:149], s[20:21], 0, v[150:151]
	global_load_dwordx4 v[170:173], v[148:149], off
	global_load_dwordx4 v[174:177], v[148:149], off offset:16
	s_mov_b64 s[18:19], 0x80000
	s_andn2_b64 vcc, exec, s[6:7]
	s_waitcnt vmcnt(0) lgkmcnt(0)
	v_pk_fma_f32 v[170:171], v[124:125], v[132:133], v[170:171]
	v_lshl_add_u64 v[124:125], s[8:9], 0, v[150:151]
	v_pk_fma_f32 v[122:123], v[122:123], v[130:131], v[176:177]
	v_pk_fma_f32 v[120:121], v[120:121], v[128:129], v[174:175]
	global_store_dwordx4 v[124:125], v[120:123], off offset:16
	v_pk_fma_f32 v[172:173], v[126:127], v[134:135], v[172:173]
	global_store_dwordx4 v[124:125], v[170:173], off
	v_or_b32_e32 v120, 16, v154
	v_ashrrev_i32_e32 v121, 31, v120
	v_lshlrev_b64 v[120:121], 10, v[120:121]
	v_lshl_add_u64 v[120:121], v[120:121], 0, v[152:153]
	v_lshlrev_b64 v[122:123], 2, v[120:121]
	v_lshl_add_u64 v[120:121], s[20:21], 0, v[122:123]
	global_load_dwordx4 v[170:173], v[120:121], off
	global_load_dwordx4 v[174:177], v[120:121], off offset:16
	s_waitcnt vmcnt(0) lgkmcnt(0)
	v_pk_fma_f32 v[170:171], v[116:117], v[132:133], v[170:171]
	v_lshl_add_u64 v[116:117], s[8:9], 0, v[122:123]
	v_pk_fma_f32 v[114:115], v[114:115], v[130:131], v[176:177]
	v_pk_fma_f32 v[112:113], v[112:113], v[128:129], v[174:175]
	global_store_dwordx4 v[116:117], v[112:115], off offset:16
	v_pk_fma_f32 v[172:173], v[118:119], v[134:135], v[172:173]
	global_store_dwordx4 v[116:117], v[170:173], off
	v_or_b32_e32 v112, 32, v154
	v_ashrrev_i32_e32 v113, 31, v112
	v_lshlrev_b64 v[112:113], 10, v[112:113]
	v_lshl_add_u64 v[112:113], v[112:113], 0, v[152:153]
	v_lshlrev_b64 v[114:115], 2, v[112:113]
	v_lshl_add_u64 v[112:113], s[20:21], 0, v[114:115]
	global_load_dwordx4 v[170:173], v[112:113], off
	global_load_dwordx4 v[174:177], v[112:113], off offset:16
	s_waitcnt vmcnt(0) lgkmcnt(0)
	v_pk_fma_f32 v[170:171], v[108:109], v[132:133], v[170:171]
	v_lshl_add_u64 v[108:109], s[8:9], 0, v[114:115]
	v_pk_fma_f32 v[106:107], v[106:107], v[130:131], v[176:177]
	v_pk_fma_f32 v[104:105], v[104:105], v[128:129], v[174:175]
	global_store_dwordx4 v[108:109], v[104:107], off offset:16
	v_pk_fma_f32 v[172:173], v[110:111], v[134:135], v[172:173]
	global_store_dwordx4 v[108:109], v[170:173], off
	v_or_b32_e32 v104, 48, v154
	v_ashrrev_i32_e32 v105, 31, v104
	v_lshlrev_b64 v[104:105], 10, v[104:105]
	v_lshl_add_u64 v[104:105], v[104:105], 0, v[152:153]
	v_lshlrev_b64 v[106:107], 2, v[104:105]
	v_lshl_add_u64 v[104:105], s[20:21], 0, v[106:107]
	global_load_dwordx4 v[152:155], v[104:105], off
	global_load_dwordx4 v[170:173], v[104:105], off offset:16
	s_waitcnt vmcnt(0) lgkmcnt(0)
	v_pk_fma_f32 v[152:153], v[100:101], v[132:133], v[152:153]
	v_lshl_add_u64 v[100:101], s[8:9], 0, v[106:107]
	v_pk_fma_f32 v[98:99], v[98:99], v[130:131], v[172:173]
	v_pk_fma_f32 v[96:97], v[96:97], v[128:129], v[170:171]
	v_pk_fma_f32 v[154:155], v[102:103], v[134:135], v[154:155]
	global_store_dwordx4 v[100:101], v[96:99], off offset:16
	global_store_dwordx4 v[100:101], v[152:155], off
	s_nop 0
	v_lshl_add_u64 v[98:99], v[150:151], 0, s[18:19]
	v_lshl_add_u64 v[96:97], s[20:21], 0, v[98:99]
	global_load_dwordx4 v[152:155], v[96:97], off
	global_load_dwordx4 v[170:173], v[96:97], off offset:16
	s_mov_b64 s[18:19], 0x90000
	s_waitcnt vmcnt(0) lgkmcnt(0)
	v_pk_fma_f32 v[152:153], v[92:93], v[132:133], v[152:153]
	v_lshl_add_u64 v[92:93], s[8:9], 0, v[98:99]
	v_pk_fma_f32 v[90:91], v[90:91], v[130:131], v[172:173]
	v_pk_fma_f32 v[88:89], v[88:89], v[128:129], v[170:171]
	v_pk_fma_f32 v[154:155], v[94:95], v[134:135], v[154:155]
	global_store_dwordx4 v[92:93], v[88:91], off offset:16
	global_store_dwordx4 v[92:93], v[152:155], off
	s_nop 0
	v_lshl_add_u64 v[90:91], v[150:151], 0, s[18:19]
	v_lshl_add_u64 v[88:89], s[20:21], 0, v[90:91]
	global_load_dwordx4 v[152:155], v[88:89], off
	global_load_dwordx4 v[170:173], v[88:89], off offset:16
	s_mov_b64 s[18:19], 0xa0000
	s_waitcnt vmcnt(0) lgkmcnt(0)
	v_pk_fma_f32 v[152:153], v[84:85], v[132:133], v[152:153]
	v_lshl_add_u64 v[84:85], s[8:9], 0, v[90:91]
	v_pk_fma_f32 v[82:83], v[82:83], v[130:131], v[172:173]
	v_pk_fma_f32 v[80:81], v[80:81], v[128:129], v[170:171]
	v_pk_fma_f32 v[154:155], v[86:87], v[134:135], v[154:155]
	global_store_dwordx4 v[84:85], v[80:83], off offset:16
	global_store_dwordx4 v[84:85], v[152:155], off
	s_nop 0
	v_lshl_add_u64 v[82:83], v[150:151], 0, s[18:19]
	v_lshl_add_u64 v[80:81], s[20:21], 0, v[82:83]
	global_load_dwordx4 v[152:155], v[80:81], off
	global_load_dwordx4 v[170:173], v[80:81], off offset:16
	s_mov_b64 s[18:19], 0xb0000
	s_waitcnt vmcnt(0) lgkmcnt(0)
	v_pk_fma_f32 v[152:153], v[76:77], v[132:133], v[152:153]
	v_lshl_add_u64 v[76:77], s[8:9], 0, v[82:83]
	v_pk_fma_f32 v[74:75], v[74:75], v[130:131], v[172:173]
	v_pk_fma_f32 v[72:73], v[72:73], v[128:129], v[170:171]
	v_pk_fma_f32 v[154:155], v[78:79], v[134:135], v[154:155]
	global_store_dwordx4 v[76:77], v[72:75], off offset:16
	global_store_dwordx4 v[76:77], v[152:155], off
	s_nop 0
	v_lshl_add_u64 v[74:75], v[150:151], 0, s[18:19]
	v_lshl_add_u64 v[72:73], s[20:21], 0, v[74:75]
	global_load_dwordx4 v[150:153], v[72:73], off
	global_load_dwordx4 v[170:173], v[72:73], off offset:16
	s_mov_b64 s[18:19], -1
	s_waitcnt vmcnt(0) lgkmcnt(0)
	v_pk_fma_f32 v[134:135], v[70:71], v[134:135], v[152:153]
	v_pk_fma_f32 v[132:133], v[68:69], v[132:133], v[150:151]
	v_lshl_add_u64 v[68:69], s[8:9], 0, v[74:75]
	v_pk_fma_f32 v[58:59], v[58:59], v[130:131], v[172:173]
	v_pk_fma_f32 v[56:57], v[56:57], v[128:129], v[170:171]
	global_store_dwordx4 v[68:69], v[132:135], off
	global_store_dwordx4 v[68:69], v[56:59], off offset:16
	global_load_dwordx4 v[56:59], v[146:147], off offset:512
	s_nop 0
	global_load_dwordx4 v[126:129], v[146:147], off offset:528
	global_load_dwordx4 v[130:133], v[148:149], off offset:512
	s_nop 0
	global_load_dwordx4 v[146:149], v[148:149], off offset:528
	s_waitcnt vmcnt(0) lgkmcnt(0)
	v_pk_fma_f32 v[66:67], v[66:67], v[58:59], v[132:133]
	v_pk_fma_f32 v[64:65], v[64:65], v[56:57], v[130:131]
	v_pk_fma_f32 v[62:63], v[62:63], v[128:129], v[148:149]
	v_pk_fma_f32 v[60:61], v[60:61], v[126:127], v[146:147]
	global_store_dwordx4 v[124:125], v[64:67], off offset:512
	global_store_dwordx4 v[124:125], v[60:63], off offset:528
	global_load_dwordx4 v[60:63], v[120:121], off offset:512
	s_nop 0
	global_load_dwordx4 v[64:67], v[120:121], off offset:528
	s_waitcnt vmcnt(0) lgkmcnt(0)
	v_pk_fma_f32 v[54:55], v[54:55], v[58:59], v[62:63]
	v_pk_fma_f32 v[52:53], v[52:53], v[56:57], v[60:61]
	v_pk_fma_f32 v[50:51], v[50:51], v[128:129], v[66:67]
	v_pk_fma_f32 v[48:49], v[48:49], v[126:127], v[64:65]
	global_store_dwordx4 v[116:117], v[52:55], off offset:512
	global_store_dwordx4 v[116:117], v[48:51], off offset:528
	global_load_dwordx4 v[48:51], v[112:113], off offset:512
	s_nop 0
	global_load_dwordx4 v[52:55], v[112:113], off offset:528
	s_waitcnt vmcnt(0) lgkmcnt(0)
	v_pk_fma_f32 v[46:47], v[46:47], v[58:59], v[50:51]
	v_pk_fma_f32 v[44:45], v[44:45], v[56:57], v[48:49]
	v_pk_fma_f32 v[42:43], v[42:43], v[128:129], v[54:55]
	v_pk_fma_f32 v[40:41], v[40:41], v[126:127], v[52:53]
	global_store_dwordx4 v[108:109], v[44:47], off offset:512
	global_store_dwordx4 v[108:109], v[40:43], off offset:528
	global_load_dwordx4 v[40:43], v[104:105], off offset:512
	s_nop 0
	global_load_dwordx4 v[44:47], v[104:105], off offset:528
	s_waitcnt vmcnt(0) lgkmcnt(0)
	v_pk_fma_f32 v[38:39], v[38:39], v[58:59], v[42:43]
	v_pk_fma_f32 v[36:37], v[36:37], v[56:57], v[40:41]
	v_pk_fma_f32 v[34:35], v[34:35], v[128:129], v[46:47]
	v_pk_fma_f32 v[32:33], v[32:33], v[126:127], v[44:45]
	global_store_dwordx4 v[100:101], v[36:39], off offset:512
	global_store_dwordx4 v[100:101], v[32:35], off offset:528
	global_load_dwordx4 v[32:35], v[96:97], off offset:512
	s_nop 0
	global_load_dwordx4 v[36:39], v[96:97], off offset:528
	s_waitcnt vmcnt(0) lgkmcnt(0)
	v_pk_fma_f32 v[30:31], v[30:31], v[58:59], v[34:35]
	v_pk_fma_f32 v[28:29], v[28:29], v[56:57], v[32:33]
	v_pk_fma_f32 v[26:27], v[26:27], v[128:129], v[38:39]
	v_pk_fma_f32 v[24:25], v[24:25], v[126:127], v[36:37]
	global_store_dwordx4 v[92:93], v[28:31], off offset:512
	global_store_dwordx4 v[92:93], v[24:27], off offset:528
	global_load_dwordx4 v[24:27], v[88:89], off offset:512
	s_nop 0
	global_load_dwordx4 v[28:31], v[88:89], off offset:528
	s_waitcnt vmcnt(0) lgkmcnt(0)
	v_pk_fma_f32 v[22:23], v[22:23], v[58:59], v[26:27]
	v_pk_fma_f32 v[20:21], v[20:21], v[56:57], v[24:25]
	v_pk_fma_f32 v[18:19], v[18:19], v[128:129], v[30:31]
	v_pk_fma_f32 v[16:17], v[16:17], v[126:127], v[28:29]
	global_store_dwordx4 v[84:85], v[20:23], off offset:512
	global_store_dwordx4 v[84:85], v[16:19], off offset:528
	global_load_dwordx4 v[16:19], v[80:81], off offset:512
	s_nop 0
	global_load_dwordx4 v[20:23], v[80:81], off offset:528
	s_waitcnt vmcnt(0) lgkmcnt(0)
	v_pk_fma_f32 v[14:15], v[14:15], v[58:59], v[18:19]
	v_pk_fma_f32 v[12:13], v[12:13], v[56:57], v[16:17]
	v_pk_fma_f32 v[10:11], v[10:11], v[128:129], v[22:23]
	v_pk_fma_f32 v[8:9], v[8:9], v[126:127], v[20:21]
	global_store_dwordx4 v[76:77], v[12:15], off offset:512
	global_store_dwordx4 v[76:77], v[8:11], off offset:528
	global_load_dwordx4 v[8:11], v[72:73], off offset:512
	s_nop 0
	global_load_dwordx4 v[12:15], v[72:73], off offset:528
	s_waitcnt vmcnt(0) lgkmcnt(0)
	v_pk_fma_f32 v[6:7], v[6:7], v[58:59], v[10:11]
	v_pk_fma_f32 v[4:5], v[4:5], v[56:57], v[8:9]
	v_pk_fma_f32 v[2:3], v[2:3], v[128:129], v[14:15]
	v_pk_fma_f32 v[0:1], v[0:1], v[126:127], v[12:13]
	global_store_dwordx4 v[68:69], v[4:7], off offset:512
	global_store_dwordx4 v[68:69], v[0:3], off offset:528
	s_cbranch_vccnz .LBB0_97
	s_and_b64 vcc, exec, s[4:5]
	s_cbranch_vccnz .LBB0_96
	s_barrier
	s_branch .LBB0_96

.LBB0_130:
	v_lshl_add_u32 v142, s41, 8, v144
	v_lshl_add_u32 v140, s40, 8, v146
	v_ashrrev_i32_e32 v143, 31, v142
	v_ashrrev_i32_e32 v141, 31, v140
	v_lshlrev_b64 v[138:139], 10, v[142:143]
	v_lshl_add_u64 v[138:139], v[138:139], 0, v[140:141]
	v_lshlrev_b64 v[138:139], 1, v[138:139]
	v_lshl_add_u64 v[152:153], s[12:13], 0, v[138:139]
	global_load_dwordx4 v[148:151], v[152:153], off
	s_mov_b64 s[22:23], 0x40000
	s_andn2_b64 vcc, exec, s[8:9]
	s_waitcnt vmcnt(0) lgkmcnt(0)
	v_lshlrev_b32_e32 v154, 16, v148
	v_and_b32_e32 v155, 0xffff0000, v148
	v_lshlrev_b32_e32 v148, 16, v149
	v_and_b32_e32 v149, 0xffff0000, v149
	v_pk_mul_f32 v[126:127], v[126:127], v[148:149]
	v_lshlrev_b32_e32 v148, 16, v150
	v_and_b32_e32 v149, 0xffff0000, v150
	v_pk_mul_f32 v[148:149], v[120:121], v[148:149]
	v_lshlrev_b32_e32 v120, 16, v151
	v_and_b32_e32 v121, 0xffff0000, v151
	v_pk_mul_f32 v[124:125], v[124:125], v[154:155]
	v_pk_mul_f32 v[150:151], v[122:123], v[120:121]
	v_cvt_pk_bf16_f32 v120, v124, v125
	v_cvt_pk_bf16_f32 v121, v126, v127
	v_cvt_pk_bf16_f32 v122, v148, v149
	v_cvt_pk_bf16_f32 v123, v150, v151
	v_lshl_add_u64 v[124:125], s[10:11], 0, v[138:139]
	global_store_dwordx4 v[124:125], v[120:123], off
	global_load_dwordx4 v[120:123], v[152:153], off offset:256
	s_waitcnt vmcnt(0) lgkmcnt(0)
	v_lshlrev_b32_e32 v126, 16, v120
	v_and_b32_e32 v127, 0xffff0000, v120
	v_lshlrev_b32_e32 v120, 16, v121
	v_and_b32_e32 v121, 0xffff0000, v121
	v_pk_mul_f32 v[118:119], v[118:119], v[120:121]
	v_lshlrev_b32_e32 v120, 16, v122
	v_and_b32_e32 v121, 0xffff0000, v122
	v_pk_mul_f32 v[120:121], v[112:113], v[120:121]
	v_lshlrev_b32_e32 v112, 16, v123
	v_and_b32_e32 v113, 0xffff0000, v123
	v_pk_mul_f32 v[116:117], v[116:117], v[126:127]
	v_pk_mul_f32 v[122:123], v[114:115], v[112:113]
	v_cvt_pk_bf16_f32 v112, v116, v117
	v_cvt_pk_bf16_f32 v113, v118, v119
	v_cvt_pk_bf16_f32 v114, v120, v121
	v_cvt_pk_bf16_f32 v115, v122, v123
	global_store_dwordx4 v[124:125], v[112:115], off offset:256
	s_nop 1
	v_or_b32_e32 v112, 16, v142
	v_ashrrev_i32_e32 v113, 31, v112
	v_lshlrev_b64 v[112:113], 10, v[112:113]
	v_lshl_add_u64 v[112:113], v[112:113], 0, v[140:141]
	v_lshlrev_b64 v[116:117], 1, v[112:113]
	v_lshl_add_u64 v[118:119], s[12:13], 0, v[116:117]
	global_load_dwordx4 v[112:115], v[118:119], off
	s_waitcnt vmcnt(0) lgkmcnt(0)
	v_lshlrev_b32_e32 v120, 16, v112
	v_and_b32_e32 v121, 0xffff0000, v112
	v_lshlrev_b32_e32 v112, 16, v113
	v_and_b32_e32 v113, 0xffff0000, v113
	v_pk_mul_f32 v[110:111], v[110:111], v[112:113]
	v_lshlrev_b32_e32 v112, 16, v114
	v_and_b32_e32 v113, 0xffff0000, v114
	v_pk_mul_f32 v[112:113], v[104:105], v[112:113]
	v_lshlrev_b32_e32 v104, 16, v115
	v_and_b32_e32 v105, 0xffff0000, v115
	v_pk_mul_f32 v[108:109], v[108:109], v[120:121]
	v_pk_mul_f32 v[114:115], v[106:107], v[104:105]
	v_cvt_pk_bf16_f32 v104, v108, v109
	v_cvt_pk_bf16_f32 v105, v110, v111
	v_cvt_pk_bf16_f32 v106, v112, v113
	v_cvt_pk_bf16_f32 v107, v114, v115
	v_lshl_add_u64 v[108:109], s[10:11], 0, v[116:117]
	global_store_dwordx4 v[108:109], v[104:107], off
	global_load_dwordx4 v[104:107], v[118:119], off offset:256
	s_waitcnt vmcnt(0) lgkmcnt(0)
	v_lshlrev_b32_e32 v110, 16, v104
	v_and_b32_e32 v111, 0xffff0000, v104
	v_lshlrev_b32_e32 v104, 16, v105
	v_and_b32_e32 v105, 0xffff0000, v105
	v_pk_mul_f32 v[102:103], v[102:103], v[104:105]
	v_lshlrev_b32_e32 v104, 16, v106
	v_and_b32_e32 v105, 0xffff0000, v106
	v_pk_mul_f32 v[104:105], v[96:97], v[104:105]
	v_lshlrev_b32_e32 v96, 16, v107
	v_and_b32_e32 v97, 0xffff0000, v107
	v_pk_mul_f32 v[100:101], v[100:101], v[110:111]
	v_pk_mul_f32 v[106:107], v[98:99], v[96:97]
	v_cvt_pk_bf16_f32 v96, v100, v101
	v_cvt_pk_bf16_f32 v97, v102, v103
	v_cvt_pk_bf16_f32 v98, v104, v105
	v_cvt_pk_bf16_f32 v99, v106, v107
	global_store_dwordx4 v[108:109], v[96:99], off offset:256
	s_nop 1
	v_or_b32_e32 v96, 32, v142
	v_ashrrev_i32_e32 v97, 31, v96
	v_lshlrev_b64 v[96:97], 10, v[96:97]
	v_lshl_add_u64 v[96:97], v[96:97], 0, v[140:141]
	v_lshlrev_b64 v[100:101], 1, v[96:97]
	v_lshl_add_u64 v[102:103], s[12:13], 0, v[100:101]
	global_load_dwordx4 v[96:99], v[102:103], off
	s_waitcnt vmcnt(0) lgkmcnt(0)
	v_lshlrev_b32_e32 v104, 16, v96
	v_and_b32_e32 v105, 0xffff0000, v96
	v_lshlrev_b32_e32 v96, 16, v97
	v_and_b32_e32 v97, 0xffff0000, v97
	v_pk_mul_f32 v[94:95], v[94:95], v[96:97]
	v_lshlrev_b32_e32 v96, 16, v98
	v_and_b32_e32 v97, 0xffff0000, v98
	v_pk_mul_f32 v[96:97], v[88:89], v[96:97]
	v_lshlrev_b32_e32 v88, 16, v99
	v_and_b32_e32 v89, 0xffff0000, v99
	v_pk_mul_f32 v[92:93], v[92:93], v[104:105]
	v_pk_mul_f32 v[98:99], v[90:91], v[88:89]
	v_cvt_pk_bf16_f32 v88, v92, v93
	v_cvt_pk_bf16_f32 v89, v94, v95
	v_cvt_pk_bf16_f32 v90, v96, v97
	v_cvt_pk_bf16_f32 v91, v98, v99
	v_lshl_add_u64 v[92:93], s[10:11], 0, v[100:101]
	global_store_dwordx4 v[92:93], v[88:91], off
	global_load_dwordx4 v[88:91], v[102:103], off offset:256
	s_waitcnt vmcnt(0) lgkmcnt(0)
	v_lshlrev_b32_e32 v94, 16, v88
	v_and_b32_e32 v95, 0xffff0000, v88
	v_lshlrev_b32_e32 v88, 16, v89
	v_and_b32_e32 v89, 0xffff0000, v89
	v_pk_mul_f32 v[86:87], v[86:87], v[88:89]
	v_lshlrev_b32_e32 v88, 16, v90
	v_and_b32_e32 v89, 0xffff0000, v90
	v_pk_mul_f32 v[88:89], v[80:81], v[88:89]
	v_lshlrev_b32_e32 v80, 16, v91
	v_and_b32_e32 v81, 0xffff0000, v91
	v_pk_mul_f32 v[84:85], v[84:85], v[94:95]
	v_pk_mul_f32 v[90:91], v[82:83], v[80:81]
	v_cvt_pk_bf16_f32 v80, v84, v85
	v_cvt_pk_bf16_f32 v81, v86, v87
	v_cvt_pk_bf16_f32 v82, v88, v89
	v_cvt_pk_bf16_f32 v83, v90, v91
	global_store_dwordx4 v[92:93], v[80:83], off offset:256
	s_nop 1
	v_or_b32_e32 v80, 48, v142
	v_ashrrev_i32_e32 v81, 31, v80
	v_lshlrev_b64 v[80:81], 10, v[80:81]
	v_lshl_add_u64 v[80:81], v[80:81], 0, v[140:141]
	v_lshlrev_b64 v[84:85], 1, v[80:81]
	v_lshl_add_u64 v[86:87], s[12:13], 0, v[84:85]
	global_load_dwordx4 v[80:83], v[86:87], off
	s_waitcnt vmcnt(0) lgkmcnt(0)
	v_lshlrev_b32_e32 v88, 16, v80
	v_and_b32_e32 v89, 0xffff0000, v80
	v_lshlrev_b32_e32 v80, 16, v81
	v_and_b32_e32 v81, 0xffff0000, v81
	v_pk_mul_f32 v[78:79], v[78:79], v[80:81]
	v_lshlrev_b32_e32 v80, 16, v82
	v_and_b32_e32 v81, 0xffff0000, v82
	v_pk_mul_f32 v[80:81], v[72:73], v[80:81]
	v_lshlrev_b32_e32 v72, 16, v83
	v_and_b32_e32 v73, 0xffff0000, v83
	v_pk_mul_f32 v[76:77], v[76:77], v[88:89]
	v_pk_mul_f32 v[82:83], v[74:75], v[72:73]
	v_cvt_pk_bf16_f32 v72, v76, v77
	v_cvt_pk_bf16_f32 v73, v78, v79
	v_cvt_pk_bf16_f32 v74, v80, v81
	v_cvt_pk_bf16_f32 v75, v82, v83
	v_lshl_add_u64 v[76:77], s[10:11], 0, v[84:85]
	global_store_dwordx4 v[76:77], v[72:75], off
	global_load_dwordx4 v[72:75], v[86:87], off offset:256
	s_waitcnt vmcnt(0) lgkmcnt(0)
	v_lshlrev_b32_e32 v78, 16, v72
	v_and_b32_e32 v79, 0xffff0000, v72
	v_lshlrev_b32_e32 v72, 16, v73
	v_and_b32_e32 v73, 0xffff0000, v73
	v_pk_mul_f32 v[70:71], v[70:71], v[72:73]
	v_lshlrev_b32_e32 v72, 16, v74
	v_and_b32_e32 v73, 0xffff0000, v74
	v_pk_mul_f32 v[72:73], v[64:65], v[72:73]
	v_lshlrev_b32_e32 v64, 16, v75
	v_and_b32_e32 v65, 0xffff0000, v75
	v_pk_mul_f32 v[68:69], v[68:69], v[78:79]
	v_pk_mul_f32 v[74:75], v[66:67], v[64:65]
	v_cvt_pk_bf16_f32 v64, v68, v69
	v_cvt_pk_bf16_f32 v65, v70, v71
	v_cvt_pk_bf16_f32 v66, v72, v73
	v_cvt_pk_bf16_f32 v67, v74, v75
	v_lshl_add_u64 v[68:69], v[138:139], 0, s[22:23]
	global_store_dwordx4 v[76:77], v[64:67], off offset:256
	v_lshl_add_u64 v[70:71], s[12:13], 0, v[68:69]
	global_load_dwordx4 v[64:67], v[70:71], off
	s_mov_b64 s[22:23], 0x48000
	s_waitcnt vmcnt(0) lgkmcnt(0)
	v_lshlrev_b32_e32 v72, 16, v64
	v_and_b32_e32 v73, 0xffff0000, v64
	v_lshlrev_b32_e32 v64, 16, v65
	v_and_b32_e32 v65, 0xffff0000, v65
	v_pk_mul_f32 v[62:63], v[62:63], v[64:65]
	v_lshlrev_b32_e32 v64, 16, v66
	v_and_b32_e32 v65, 0xffff0000, v66
	v_pk_mul_f32 v[64:65], v[56:57], v[64:65]
	v_lshlrev_b32_e32 v56, 16, v67
	v_and_b32_e32 v57, 0xffff0000, v67
	v_pk_mul_f32 v[60:61], v[60:61], v[72:73]
	v_pk_mul_f32 v[66:67], v[58:59], v[56:57]
	v_cvt_pk_bf16_f32 v56, v60, v61
	v_cvt_pk_bf16_f32 v57, v62, v63
	v_cvt_pk_bf16_f32 v58, v64, v65
	v_cvt_pk_bf16_f32 v59, v66, v67
	v_lshl_add_u64 v[60:61], s[10:11], 0, v[68:69]
	global_store_dwordx4 v[60:61], v[56:59], off
	global_load_dwordx4 v[56:59], v[70:71], off offset:256
	s_waitcnt vmcnt(0) lgkmcnt(0)
	v_lshlrev_b32_e32 v62, 16, v56
	v_and_b32_e32 v63, 0xffff0000, v56
	v_lshlrev_b32_e32 v56, 16, v57
	v_and_b32_e32 v57, 0xffff0000, v57
	v_pk_mul_f32 v[54:55], v[54:55], v[56:57]
	v_lshlrev_b32_e32 v56, 16, v58
	v_and_b32_e32 v57, 0xffff0000, v58
	v_pk_mul_f32 v[56:57], v[48:49], v[56:57]
	v_lshlrev_b32_e32 v48, 16, v59
	v_and_b32_e32 v49, 0xffff0000, v59
	v_pk_mul_f32 v[52:53], v[52:53], v[62:63]
	v_pk_mul_f32 v[58:59], v[50:51], v[48:49]
	v_cvt_pk_bf16_f32 v48, v52, v53
	v_cvt_pk_bf16_f32 v49, v54, v55
	v_cvt_pk_bf16_f32 v50, v56, v57
	v_cvt_pk_bf16_f32 v51, v58, v59
	v_lshl_add_u64 v[52:53], v[138:139], 0, s[22:23]
	global_store_dwordx4 v[60:61], v[48:51], off offset:256
	v_lshl_add_u64 v[54:55], s[12:13], 0, v[52:53]
	global_load_dwordx4 v[48:51], v[54:55], off
	s_mov_b64 s[22:23], 0x50000
	s_waitcnt vmcnt(0) lgkmcnt(0)
	v_lshlrev_b32_e32 v56, 16, v48
	v_and_b32_e32 v57, 0xffff0000, v48
	v_lshlrev_b32_e32 v48, 16, v49
	v_and_b32_e32 v49, 0xffff0000, v49
	v_pk_mul_f32 v[46:47], v[46:47], v[48:49]
	v_lshlrev_b32_e32 v48, 16, v50
	v_and_b32_e32 v49, 0xffff0000, v50
	v_pk_mul_f32 v[48:49], v[40:41], v[48:49]
	v_lshlrev_b32_e32 v40, 16, v51
	v_and_b32_e32 v41, 0xffff0000, v51
	v_pk_mul_f32 v[44:45], v[44:45], v[56:57]
	v_pk_mul_f32 v[50:51], v[42:43], v[40:41]
	v_cvt_pk_bf16_f32 v40, v44, v45
	v_cvt_pk_bf16_f32 v41, v46, v47
	v_cvt_pk_bf16_f32 v42, v48, v49
	v_cvt_pk_bf16_f32 v43, v50, v51
	v_lshl_add_u64 v[44:45], s[10:11], 0, v[52:53]
	global_store_dwordx4 v[44:45], v[40:43], off
	global_load_dwordx4 v[40:43], v[54:55], off offset:256
	s_waitcnt vmcnt(0) lgkmcnt(0)
	v_lshlrev_b32_e32 v46, 16, v40
	v_and_b32_e32 v47, 0xffff0000, v40
	v_lshlrev_b32_e32 v40, 16, v41
	v_and_b32_e32 v41, 0xffff0000, v41
	v_pk_mul_f32 v[38:39], v[38:39], v[40:41]
	v_lshlrev_b32_e32 v40, 16, v42
	v_and_b32_e32 v41, 0xffff0000, v42
	v_pk_mul_f32 v[40:41], v[32:33], v[40:41]
	v_lshlrev_b32_e32 v32, 16, v43
	v_and_b32_e32 v33, 0xffff0000, v43
	v_pk_mul_f32 v[36:37], v[36:37], v[46:47]
	v_pk_mul_f32 v[42:43], v[34:35], v[32:33]
	v_cvt_pk_bf16_f32 v32, v36, v37
	v_cvt_pk_bf16_f32 v33, v38, v39
	v_cvt_pk_bf16_f32 v34, v40, v41
	v_cvt_pk_bf16_f32 v35, v42, v43
	v_lshl_add_u64 v[36:37], v[138:139], 0, s[22:23]
	global_store_dwordx4 v[44:45], v[32:35], off offset:256
	v_lshl_add_u64 v[38:39], s[12:13], 0, v[36:37]
	global_load_dwordx4 v[32:35], v[38:39], off
	s_mov_b64 s[22:23], 0x58000
	s_waitcnt vmcnt(0) lgkmcnt(0)
	v_lshlrev_b32_e32 v40, 16, v32
	v_and_b32_e32 v41, 0xffff0000, v32
	v_lshlrev_b32_e32 v32, 16, v33
	v_and_b32_e32 v33, 0xffff0000, v33
	v_pk_mul_f32 v[30:31], v[30:31], v[32:33]
	v_lshlrev_b32_e32 v32, 16, v34
	v_and_b32_e32 v33, 0xffff0000, v34
	v_pk_mul_f32 v[32:33], v[24:25], v[32:33]
	v_lshlrev_b32_e32 v24, 16, v35
	v_and_b32_e32 v25, 0xffff0000, v35
	v_pk_mul_f32 v[28:29], v[28:29], v[40:41]
	v_pk_mul_f32 v[34:35], v[26:27], v[24:25]
	v_cvt_pk_bf16_f32 v24, v28, v29
	v_cvt_pk_bf16_f32 v25, v30, v31
	v_cvt_pk_bf16_f32 v26, v32, v33
	v_cvt_pk_bf16_f32 v27, v34, v35
	v_lshl_add_u64 v[28:29], s[10:11], 0, v[36:37]
	global_store_dwordx4 v[28:29], v[24:27], off
	global_load_dwordx4 v[24:27], v[38:39], off offset:256
	s_waitcnt vmcnt(0) lgkmcnt(0)
	v_lshlrev_b32_e32 v30, 16, v24
	v_and_b32_e32 v31, 0xffff0000, v24
	v_lshlrev_b32_e32 v24, 16, v25
	v_and_b32_e32 v25, 0xffff0000, v25
	v_pk_mul_f32 v[22:23], v[22:23], v[24:25]
	v_lshlrev_b32_e32 v24, 16, v26
	v_and_b32_e32 v25, 0xffff0000, v26
	v_pk_mul_f32 v[24:25], v[16:17], v[24:25]
	v_lshlrev_b32_e32 v16, 16, v27
	v_and_b32_e32 v17, 0xffff0000, v27
	v_pk_mul_f32 v[20:21], v[20:21], v[30:31]
	v_pk_mul_f32 v[26:27], v[18:19], v[16:17]
	v_cvt_pk_bf16_f32 v16, v20, v21
	v_cvt_pk_bf16_f32 v17, v22, v23
	v_cvt_pk_bf16_f32 v18, v24, v25
	v_cvt_pk_bf16_f32 v19, v26, v27
	v_lshl_add_u64 v[20:21], v[138:139], 0, s[22:23]
	global_store_dwordx4 v[28:29], v[16:19], off offset:256
	v_lshl_add_u64 v[22:23], s[12:13], 0, v[20:21]
	global_load_dwordx4 v[16:19], v[22:23], off
	s_mov_b64 s[22:23], -1
	s_waitcnt vmcnt(0) lgkmcnt(0)
	v_lshlrev_b32_e32 v24, 16, v16
	v_and_b32_e32 v25, 0xffff0000, v16
	v_lshlrev_b32_e32 v16, 16, v17
	v_and_b32_e32 v17, 0xffff0000, v17
	v_pk_mul_f32 v[14:15], v[14:15], v[16:17]
	v_lshlrev_b32_e32 v16, 16, v18
	v_and_b32_e32 v17, 0xffff0000, v18
	v_pk_mul_f32 v[16:17], v[8:9], v[16:17]
	v_lshlrev_b32_e32 v8, 16, v19
	v_and_b32_e32 v9, 0xffff0000, v19
	v_pk_mul_f32 v[12:13], v[12:13], v[24:25]
	v_pk_mul_f32 v[18:19], v[10:11], v[8:9]
	v_cvt_pk_bf16_f32 v8, v12, v13
	v_cvt_pk_bf16_f32 v9, v14, v15
	v_cvt_pk_bf16_f32 v10, v16, v17
	v_cvt_pk_bf16_f32 v11, v18, v19
	v_lshl_add_u64 v[12:13], s[10:11], 0, v[20:21]
	global_store_dwordx4 v[12:13], v[8:11], off
	global_load_dwordx4 v[8:11], v[22:23], off offset:256
	s_waitcnt vmcnt(0) lgkmcnt(0)
	v_lshlrev_b32_e32 v14, 16, v8
	v_and_b32_e32 v15, 0xffff0000, v8
	v_lshlrev_b32_e32 v8, 16, v9
	v_and_b32_e32 v9, 0xffff0000, v9
	v_pk_mul_f32 v[6:7], v[6:7], v[8:9]
	v_lshlrev_b32_e32 v8, 16, v10
	v_and_b32_e32 v9, 0xffff0000, v10
	v_pk_mul_f32 v[8:9], v[0:1], v[8:9]
	v_lshlrev_b32_e32 v0, 16, v11
	v_and_b32_e32 v1, 0xffff0000, v11
	v_pk_mul_f32 v[4:5], v[4:5], v[14:15]
	v_pk_mul_f32 v[10:11], v[2:3], v[0:1]
	v_cvt_pk_bf16_f32 v0, v4, v5
	v_cvt_pk_bf16_f32 v1, v6, v7
	v_cvt_pk_bf16_f32 v2, v8, v9
	v_cvt_pk_bf16_f32 v3, v10, v11
	global_store_dwordx4 v[12:13], v[0:3], off offset:256
	s_cbranch_vccnz .LBB0_119
	s_and_b64 vcc, exec, s[6:7]
	s_cbranch_vccnz .LBB0_118
	s_barrier
	s_branch .LBB0_118

.LBB0_150:
	v_lshl_add_u32 v142, s41, 8, v144
	v_lshl_add_u32 v140, s2, 8, v146
	v_ashrrev_i32_e32 v143, 31, v142
	v_ashrrev_i32_e32 v141, 31, v140
	v_lshlrev_b64 v[138:139], 10, v[142:143]
	v_lshl_add_u64 v[138:139], v[138:139], 0, v[140:141]
	v_lshlrev_b64 v[138:139], 1, v[138:139]
	v_lshl_add_u64 v[156:157], s[12:13], 0, v[138:139]
	v_lshl_add_u64 v[158:159], s[10:11], 0, v[138:139]
	global_load_dwordx4 v[148:151], v[156:157], off
	global_load_dwordx4 v[152:155], v[158:159], off
	s_mov_b64 s[22:23], 0x40000
	s_andn2_b64 vcc, exec, s[8:9]
	s_waitcnt vmcnt(0) lgkmcnt(0)
	v_lshlrev_b32_e32 v166, 16, v148
	v_and_b32_e32 v167, 0xffff0000, v148
	v_lshlrev_b32_e32 v168, 16, v152
	v_and_b32_e32 v169, 0xffff0000, v152
	v_lshlrev_b32_e32 v148, 16, v149
	v_and_b32_e32 v149, 0xffff0000, v149
	v_lshlrev_b32_e32 v152, 16, v153
	v_and_b32_e32 v153, 0xffff0000, v153
	v_pk_fma_f32 v[126:127], v[126:127], v[148:149], v[152:153]
	v_lshlrev_b32_e32 v148, 16, v150
	v_and_b32_e32 v149, 0xffff0000, v150
	v_lshlrev_b32_e32 v152, 16, v154
	v_and_b32_e32 v153, 0xffff0000, v154
	v_pk_fma_f32 v[148:149], v[120:121], v[148:149], v[152:153]
	v_lshlrev_b32_e32 v120, 16, v151
	v_and_b32_e32 v121, 0xffff0000, v151
	v_lshlrev_b32_e32 v150, 16, v155
	v_and_b32_e32 v151, 0xffff0000, v155
	v_pk_fma_f32 v[124:125], v[124:125], v[166:167], v[168:169]
	v_pk_fma_f32 v[150:151], v[122:123], v[120:121], v[150:151]
	v_cvt_pk_bf16_f32 v120, v124, v125
	v_cvt_pk_bf16_f32 v121, v126, v127
	v_cvt_pk_bf16_f32 v122, v148, v149
	v_cvt_pk_bf16_f32 v123, v150, v151
	global_store_dwordx4 v[158:159], v[120:123], off
	global_load_dwordx4 v[120:123], v[156:157], off offset:256
	s_nop 0
	global_load_dwordx4 v[124:127], v[158:159], off offset:256
	s_waitcnt vmcnt(0) lgkmcnt(0)
	v_lshlrev_b32_e32 v148, 16, v120
	v_and_b32_e32 v149, 0xffff0000, v120
	v_lshlrev_b32_e32 v150, 16, v124
	v_and_b32_e32 v151, 0xffff0000, v124
	v_lshlrev_b32_e32 v120, 16, v121
	v_and_b32_e32 v121, 0xffff0000, v121
	v_lshlrev_b32_e32 v124, 16, v125
	v_and_b32_e32 v125, 0xffff0000, v125
	v_pk_fma_f32 v[118:119], v[118:119], v[120:121], v[124:125]
	v_lshlrev_b32_e32 v120, 16, v122
	v_and_b32_e32 v121, 0xffff0000, v122
	v_lshlrev_b32_e32 v124, 16, v126
	v_and_b32_e32 v125, 0xffff0000, v126
	v_pk_fma_f32 v[120:121], v[112:113], v[120:121], v[124:125]
	v_lshlrev_b32_e32 v112, 16, v123
	v_and_b32_e32 v113, 0xffff0000, v123
	v_lshlrev_b32_e32 v122, 16, v127
	v_and_b32_e32 v123, 0xffff0000, v127
	v_pk_fma_f32 v[116:117], v[116:117], v[148:149], v[150:151]
	v_pk_fma_f32 v[122:123], v[114:115], v[112:113], v[122:123]
	v_cvt_pk_bf16_f32 v112, v116, v117
	v_cvt_pk_bf16_f32 v113, v118, v119
	v_cvt_pk_bf16_f32 v114, v120, v121
	v_cvt_pk_bf16_f32 v115, v122, v123
	global_store_dwordx4 v[158:159], v[112:115], off offset:256
	s_nop 1
	v_or_b32_e32 v112, 16, v142
	v_ashrrev_i32_e32 v113, 31, v112
	v_lshlrev_b64 v[112:113], 10, v[112:113]
	v_lshl_add_u64 v[112:113], v[112:113], 0, v[140:141]
	v_lshlrev_b64 v[116:117], 1, v[112:113]
	v_lshl_add_u64 v[120:121], s[12:13], 0, v[116:117]
	v_lshl_add_u64 v[122:123], s[10:11], 0, v[116:117]
	global_load_dwordx4 v[112:115], v[120:121], off
	global_load_dwordx4 v[116:119], v[122:123], off
	s_waitcnt vmcnt(0) lgkmcnt(0)
	v_lshlrev_b32_e32 v124, 16, v112
	v_and_b32_e32 v125, 0xffff0000, v112
	v_lshlrev_b32_e32 v126, 16, v116
	v_and_b32_e32 v127, 0xffff0000, v116
	v_lshlrev_b32_e32 v112, 16, v113
	v_and_b32_e32 v113, 0xffff0000, v113
	v_lshlrev_b32_e32 v116, 16, v117
	v_and_b32_e32 v117, 0xffff0000, v117
	v_pk_fma_f32 v[110:111], v[110:111], v[112:113], v[116:117]
	v_lshlrev_b32_e32 v112, 16, v114
	v_and_b32_e32 v113, 0xffff0000, v114
	v_lshlrev_b32_e32 v116, 16, v118
	v_and_b32_e32 v117, 0xffff0000, v118
	v_pk_fma_f32 v[112:113], v[104:105], v[112:113], v[116:117]
	v_lshlrev_b32_e32 v104, 16, v115
	v_and_b32_e32 v105, 0xffff0000, v115
	v_lshlrev_b32_e32 v114, 16, v119
	v_and_b32_e32 v115, 0xffff0000, v119
	v_pk_fma_f32 v[108:109], v[108:109], v[124:125], v[126:127]
	v_pk_fma_f32 v[114:115], v[106:107], v[104:105], v[114:115]
	v_cvt_pk_bf16_f32 v104, v108, v109
	v_cvt_pk_bf16_f32 v105, v110, v111
	v_cvt_pk_bf16_f32 v106, v112, v113
	v_cvt_pk_bf16_f32 v107, v114, v115
	global_store_dwordx4 v[122:123], v[104:107], off
	global_load_dwordx4 v[104:107], v[120:121], off offset:256
	s_nop 0
	global_load_dwordx4 v[108:111], v[122:123], off offset:256
	s_waitcnt vmcnt(0) lgkmcnt(0)
	v_lshlrev_b32_e32 v112, 16, v104
	v_and_b32_e32 v113, 0xffff0000, v104
	v_lshlrev_b32_e32 v114, 16, v108
	v_and_b32_e32 v115, 0xffff0000, v108
	v_lshlrev_b32_e32 v104, 16, v105
	v_and_b32_e32 v105, 0xffff0000, v105
	v_lshlrev_b32_e32 v108, 16, v109
	v_and_b32_e32 v109, 0xffff0000, v109
	v_pk_fma_f32 v[102:103], v[102:103], v[104:105], v[108:109]
	v_lshlrev_b32_e32 v104, 16, v106
	v_and_b32_e32 v105, 0xffff0000, v106
	v_lshlrev_b32_e32 v108, 16, v110
	v_and_b32_e32 v109, 0xffff0000, v110
	v_pk_fma_f32 v[104:105], v[96:97], v[104:105], v[108:109]
	v_lshlrev_b32_e32 v96, 16, v107
	v_and_b32_e32 v97, 0xffff0000, v107
	v_lshlrev_b32_e32 v106, 16, v111
	v_and_b32_e32 v107, 0xffff0000, v111
	v_pk_fma_f32 v[100:101], v[100:101], v[112:113], v[114:115]
	v_pk_fma_f32 v[106:107], v[98:99], v[96:97], v[106:107]
	v_cvt_pk_bf16_f32 v96, v100, v101
	v_cvt_pk_bf16_f32 v97, v102, v103
	v_cvt_pk_bf16_f32 v98, v104, v105
	v_cvt_pk_bf16_f32 v99, v106, v107
	global_store_dwordx4 v[122:123], v[96:99], off offset:256
	s_nop 1
	v_or_b32_e32 v96, 32, v142
	v_ashrrev_i32_e32 v97, 31, v96
	v_lshlrev_b64 v[96:97], 10, v[96:97]
	v_lshl_add_u64 v[96:97], v[96:97], 0, v[140:141]
	v_lshlrev_b64 v[100:101], 1, v[96:97]
	v_lshl_add_u64 v[104:105], s[12:13], 0, v[100:101]
	v_lshl_add_u64 v[106:107], s[10:11], 0, v[100:101]
	global_load_dwordx4 v[96:99], v[104:105], off
	global_load_dwordx4 v[100:103], v[106:107], off
	s_waitcnt vmcnt(0) lgkmcnt(0)
	v_lshlrev_b32_e32 v108, 16, v96
	v_and_b32_e32 v109, 0xffff0000, v96
	v_lshlrev_b32_e32 v110, 16, v100
	v_and_b32_e32 v111, 0xffff0000, v100
	v_lshlrev_b32_e32 v96, 16, v97
	v_and_b32_e32 v97, 0xffff0000, v97
	v_lshlrev_b32_e32 v100, 16, v101
	v_and_b32_e32 v101, 0xffff0000, v101
	v_pk_fma_f32 v[94:95], v[94:95], v[96:97], v[100:101]
	v_lshlrev_b32_e32 v96, 16, v98
	v_and_b32_e32 v97, 0xffff0000, v98
	v_lshlrev_b32_e32 v100, 16, v102
	v_and_b32_e32 v101, 0xffff0000, v102
	v_pk_fma_f32 v[96:97], v[88:89], v[96:97], v[100:101]
	v_lshlrev_b32_e32 v88, 16, v99
	v_and_b32_e32 v89, 0xffff0000, v99
	v_lshlrev_b32_e32 v98, 16, v103
	v_and_b32_e32 v99, 0xffff0000, v103
	v_pk_fma_f32 v[92:93], v[92:93], v[108:109], v[110:111]
	v_pk_fma_f32 v[98:99], v[90:91], v[88:89], v[98:99]
	v_cvt_pk_bf16_f32 v88, v92, v93
	v_cvt_pk_bf16_f32 v89, v94, v95
	v_cvt_pk_bf16_f32 v90, v96, v97
	v_cvt_pk_bf16_f32 v91, v98, v99
	global_store_dwordx4 v[106:107], v[88:91], off
	global_load_dwordx4 v[88:91], v[104:105], off offset:256
	s_nop 0
	global_load_dwordx4 v[92:95], v[106:107], off offset:256
	s_waitcnt vmcnt(0) lgkmcnt(0)
	v_lshlrev_b32_e32 v96, 16, v88
	v_and_b32_e32 v97, 0xffff0000, v88
	v_lshlrev_b32_e32 v98, 16, v92
	v_and_b32_e32 v99, 0xffff0000, v92
	v_lshlrev_b32_e32 v88, 16, v89
	v_and_b32_e32 v89, 0xffff0000, v89
	v_lshlrev_b32_e32 v92, 16, v93
	v_and_b32_e32 v93, 0xffff0000, v93
	v_pk_fma_f32 v[86:87], v[86:87], v[88:89], v[92:93]
	v_lshlrev_b32_e32 v88, 16, v90
	v_and_b32_e32 v89, 0xffff0000, v90
	v_lshlrev_b32_e32 v92, 16, v94
	v_and_b32_e32 v93, 0xffff0000, v94
	v_pk_fma_f32 v[88:89], v[80:81], v[88:89], v[92:93]
	v_lshlrev_b32_e32 v80, 16, v91
	v_and_b32_e32 v81, 0xffff0000, v91
	v_lshlrev_b32_e32 v90, 16, v95
	v_and_b32_e32 v91, 0xffff0000, v95
	v_pk_fma_f32 v[84:85], v[84:85], v[96:97], v[98:99]
	v_pk_fma_f32 v[90:91], v[82:83], v[80:81], v[90:91]
	v_cvt_pk_bf16_f32 v80, v84, v85
	v_cvt_pk_bf16_f32 v81, v86, v87
	v_cvt_pk_bf16_f32 v82, v88, v89
	v_cvt_pk_bf16_f32 v83, v90, v91
	global_store_dwordx4 v[106:107], v[80:83], off offset:256
	s_nop 1
	v_or_b32_e32 v80, 48, v142
	v_ashrrev_i32_e32 v81, 31, v80
	v_lshlrev_b64 v[80:81], 10, v[80:81]
	v_lshl_add_u64 v[80:81], v[80:81], 0, v[140:141]
	v_lshlrev_b64 v[84:85], 1, v[80:81]
	v_lshl_add_u64 v[88:89], s[12:13], 0, v[84:85]
	v_lshl_add_u64 v[90:91], s[10:11], 0, v[84:85]
	global_load_dwordx4 v[80:83], v[88:89], off
	global_load_dwordx4 v[84:87], v[90:91], off
	s_waitcnt vmcnt(0) lgkmcnt(0)
	v_lshlrev_b32_e32 v92, 16, v80
	v_and_b32_e32 v93, 0xffff0000, v80
	v_lshlrev_b32_e32 v94, 16, v84
	v_and_b32_e32 v95, 0xffff0000, v84
	v_lshlrev_b32_e32 v80, 16, v81
	v_and_b32_e32 v81, 0xffff0000, v81
	v_lshlrev_b32_e32 v84, 16, v85
	v_and_b32_e32 v85, 0xffff0000, v85
	v_pk_fma_f32 v[78:79], v[78:79], v[80:81], v[84:85]
	v_lshlrev_b32_e32 v80, 16, v82
	v_and_b32_e32 v81, 0xffff0000, v82
	v_lshlrev_b32_e32 v84, 16, v86
	v_and_b32_e32 v85, 0xffff0000, v86
	v_pk_fma_f32 v[80:81], v[72:73], v[80:81], v[84:85]
	v_lshlrev_b32_e32 v72, 16, v83
	v_and_b32_e32 v73, 0xffff0000, v83
	v_lshlrev_b32_e32 v82, 16, v87
	v_and_b32_e32 v83, 0xffff0000, v87
	v_pk_fma_f32 v[76:77], v[76:77], v[92:93], v[94:95]
	v_pk_fma_f32 v[82:83], v[74:75], v[72:73], v[82:83]
	v_cvt_pk_bf16_f32 v72, v76, v77
	v_cvt_pk_bf16_f32 v73, v78, v79
	v_cvt_pk_bf16_f32 v74, v80, v81
	v_cvt_pk_bf16_f32 v75, v82, v83
	global_store_dwordx4 v[90:91], v[72:75], off
	global_load_dwordx4 v[72:75], v[88:89], off offset:256
	s_nop 0
	global_load_dwordx4 v[76:79], v[90:91], off offset:256
	s_waitcnt vmcnt(0) lgkmcnt(0)
	v_lshlrev_b32_e32 v80, 16, v72
	v_and_b32_e32 v81, 0xffff0000, v72
	v_lshlrev_b32_e32 v82, 16, v76
	v_and_b32_e32 v83, 0xffff0000, v76
	v_lshlrev_b32_e32 v72, 16, v73
	v_and_b32_e32 v73, 0xffff0000, v73
	v_lshlrev_b32_e32 v76, 16, v77
	v_and_b32_e32 v77, 0xffff0000, v77
	v_pk_fma_f32 v[70:71], v[70:71], v[72:73], v[76:77]
	v_lshlrev_b32_e32 v72, 16, v74
	v_and_b32_e32 v73, 0xffff0000, v74
	v_lshlrev_b32_e32 v76, 16, v78
	v_and_b32_e32 v77, 0xffff0000, v78
	v_pk_fma_f32 v[72:73], v[64:65], v[72:73], v[76:77]
	v_lshlrev_b32_e32 v64, 16, v75
	v_and_b32_e32 v65, 0xffff0000, v75
	v_lshlrev_b32_e32 v74, 16, v79
	v_and_b32_e32 v75, 0xffff0000, v79
	v_pk_fma_f32 v[68:69], v[68:69], v[80:81], v[82:83]
	v_pk_fma_f32 v[74:75], v[66:67], v[64:65], v[74:75]
	v_cvt_pk_bf16_f32 v64, v68, v69
	v_cvt_pk_bf16_f32 v65, v70, v71
	v_cvt_pk_bf16_f32 v66, v72, v73
	v_cvt_pk_bf16_f32 v67, v74, v75
	v_lshl_add_u64 v[68:69], v[138:139], 0, s[22:23]
	global_store_dwordx4 v[90:91], v[64:67], off offset:256
	v_lshl_add_u64 v[72:73], s[12:13], 0, v[68:69]
	v_lshl_add_u64 v[74:75], s[10:11], 0, v[68:69]
	global_load_dwordx4 v[64:67], v[72:73], off
	global_load_dwordx4 v[68:71], v[74:75], off
	s_mov_b64 s[22:23], 0x48000
	s_waitcnt vmcnt(0) lgkmcnt(0)
	v_lshlrev_b32_e32 v76, 16, v64
	v_and_b32_e32 v77, 0xffff0000, v64
	v_lshlrev_b32_e32 v78, 16, v68
	v_and_b32_e32 v79, 0xffff0000, v68
	v_lshlrev_b32_e32 v64, 16, v65
	v_and_b32_e32 v65, 0xffff0000, v65
	v_lshlrev_b32_e32 v68, 16, v69
	v_and_b32_e32 v69, 0xffff0000, v69
	v_pk_fma_f32 v[62:63], v[62:63], v[64:65], v[68:69]
	v_lshlrev_b32_e32 v64, 16, v66
	v_and_b32_e32 v65, 0xffff0000, v66
	v_lshlrev_b32_e32 v68, 16, v70
	v_and_b32_e32 v69, 0xffff0000, v70
	v_pk_fma_f32 v[64:65], v[56:57], v[64:65], v[68:69]
	v_lshlrev_b32_e32 v56, 16, v67
	v_and_b32_e32 v57, 0xffff0000, v67
	v_lshlrev_b32_e32 v66, 16, v71
	v_and_b32_e32 v67, 0xffff0000, v71
	v_pk_fma_f32 v[60:61], v[60:61], v[76:77], v[78:79]
	v_pk_fma_f32 v[66:67], v[58:59], v[56:57], v[66:67]
	v_cvt_pk_bf16_f32 v56, v60, v61
	v_cvt_pk_bf16_f32 v57, v62, v63
	v_cvt_pk_bf16_f32 v58, v64, v65
	v_cvt_pk_bf16_f32 v59, v66, v67
	global_store_dwordx4 v[74:75], v[56:59], off
	global_load_dwordx4 v[56:59], v[72:73], off offset:256
	s_nop 0
	global_load_dwordx4 v[60:63], v[74:75], off offset:256
	s_waitcnt vmcnt(0) lgkmcnt(0)
	v_lshlrev_b32_e32 v64, 16, v56
	v_and_b32_e32 v65, 0xffff0000, v56
	v_lshlrev_b32_e32 v66, 16, v60
	v_and_b32_e32 v67, 0xffff0000, v60
	v_lshlrev_b32_e32 v56, 16, v57
	v_and_b32_e32 v57, 0xffff0000, v57
	v_lshlrev_b32_e32 v60, 16, v61
	v_and_b32_e32 v61, 0xffff0000, v61
	v_pk_fma_f32 v[54:55], v[54:55], v[56:57], v[60:61]
	v_lshlrev_b32_e32 v56, 16, v58
	v_and_b32_e32 v57, 0xffff0000, v58
	v_lshlrev_b32_e32 v60, 16, v62
	v_and_b32_e32 v61, 0xffff0000, v62
	v_pk_fma_f32 v[56:57], v[48:49], v[56:57], v[60:61]
	v_lshlrev_b32_e32 v48, 16, v59
	v_and_b32_e32 v49, 0xffff0000, v59
	v_lshlrev_b32_e32 v58, 16, v63
	v_and_b32_e32 v59, 0xffff0000, v63
	v_pk_fma_f32 v[52:53], v[52:53], v[64:65], v[66:67]
	v_pk_fma_f32 v[58:59], v[50:51], v[48:49], v[58:59]
	v_cvt_pk_bf16_f32 v48, v52, v53
	v_cvt_pk_bf16_f32 v49, v54, v55
	v_cvt_pk_bf16_f32 v50, v56, v57
	v_cvt_pk_bf16_f32 v51, v58, v59
	v_lshl_add_u64 v[52:53], v[138:139], 0, s[22:23]
	global_store_dwordx4 v[74:75], v[48:51], off offset:256
	v_lshl_add_u64 v[56:57], s[12:13], 0, v[52:53]
	v_lshl_add_u64 v[58:59], s[10:11], 0, v[52:53]
	global_load_dwordx4 v[48:51], v[56:57], off
	global_load_dwordx4 v[52:55], v[58:59], off
	s_mov_b64 s[22:23], 0x50000
	s_waitcnt vmcnt(0) lgkmcnt(0)
	v_lshlrev_b32_e32 v60, 16, v48
	v_and_b32_e32 v61, 0xffff0000, v48
	v_lshlrev_b32_e32 v62, 16, v52
	v_and_b32_e32 v63, 0xffff0000, v52
	v_lshlrev_b32_e32 v48, 16, v49
	v_and_b32_e32 v49, 0xffff0000, v49
	v_lshlrev_b32_e32 v52, 16, v53
	v_and_b32_e32 v53, 0xffff0000, v53
	v_pk_fma_f32 v[46:47], v[46:47], v[48:49], v[52:53]
	v_lshlrev_b32_e32 v48, 16, v50
	v_and_b32_e32 v49, 0xffff0000, v50
	v_lshlrev_b32_e32 v52, 16, v54
	v_and_b32_e32 v53, 0xffff0000, v54
	v_pk_fma_f32 v[48:49], v[40:41], v[48:49], v[52:53]
	v_lshlrev_b32_e32 v40, 16, v51
	v_and_b32_e32 v41, 0xffff0000, v51
	v_lshlrev_b32_e32 v50, 16, v55
	v_and_b32_e32 v51, 0xffff0000, v55
	v_pk_fma_f32 v[44:45], v[44:45], v[60:61], v[62:63]
	v_pk_fma_f32 v[50:51], v[42:43], v[40:41], v[50:51]
	v_cvt_pk_bf16_f32 v40, v44, v45
	v_cvt_pk_bf16_f32 v41, v46, v47
	v_cvt_pk_bf16_f32 v42, v48, v49
	v_cvt_pk_bf16_f32 v43, v50, v51
	global_store_dwordx4 v[58:59], v[40:43], off
	global_load_dwordx4 v[40:43], v[56:57], off offset:256
	s_nop 0
	global_load_dwordx4 v[44:47], v[58:59], off offset:256
	s_waitcnt vmcnt(0) lgkmcnt(0)
	v_lshlrev_b32_e32 v48, 16, v40
	v_and_b32_e32 v49, 0xffff0000, v40
	v_lshlrev_b32_e32 v50, 16, v44
	v_and_b32_e32 v51, 0xffff0000, v44
	v_lshlrev_b32_e32 v40, 16, v41
	v_and_b32_e32 v41, 0xffff0000, v41
	v_lshlrev_b32_e32 v44, 16, v45
	v_and_b32_e32 v45, 0xffff0000, v45
	v_pk_fma_f32 v[38:39], v[38:39], v[40:41], v[44:45]
	v_lshlrev_b32_e32 v40, 16, v42
	v_and_b32_e32 v41, 0xffff0000, v42
	v_lshlrev_b32_e32 v44, 16, v46
	v_and_b32_e32 v45, 0xffff0000, v46
	v_pk_fma_f32 v[40:41], v[32:33], v[40:41], v[44:45]
	v_lshlrev_b32_e32 v32, 16, v43
	v_and_b32_e32 v33, 0xffff0000, v43
	v_lshlrev_b32_e32 v42, 16, v47
	v_and_b32_e32 v43, 0xffff0000, v47
	v_pk_fma_f32 v[36:37], v[36:37], v[48:49], v[50:51]
	v_pk_fma_f32 v[42:43], v[34:35], v[32:33], v[42:43]
	v_cvt_pk_bf16_f32 v32, v36, v37
	v_cvt_pk_bf16_f32 v33, v38, v39
	v_cvt_pk_bf16_f32 v34, v40, v41
	v_cvt_pk_bf16_f32 v35, v42, v43
	v_lshl_add_u64 v[36:37], v[138:139], 0, s[22:23]
	global_store_dwordx4 v[58:59], v[32:35], off offset:256
	v_lshl_add_u64 v[40:41], s[12:13], 0, v[36:37]
	v_lshl_add_u64 v[42:43], s[10:11], 0, v[36:37]
	global_load_dwordx4 v[32:35], v[40:41], off
	global_load_dwordx4 v[36:39], v[42:43], off
	s_mov_b64 s[22:23], 0x58000
	s_waitcnt vmcnt(0) lgkmcnt(0)
	v_lshlrev_b32_e32 v44, 16, v32
	v_and_b32_e32 v45, 0xffff0000, v32
	v_lshlrev_b32_e32 v46, 16, v36
	v_and_b32_e32 v47, 0xffff0000, v36
	v_lshlrev_b32_e32 v32, 16, v33
	v_and_b32_e32 v33, 0xffff0000, v33
	v_lshlrev_b32_e32 v36, 16, v37
	v_and_b32_e32 v37, 0xffff0000, v37
	v_pk_fma_f32 v[30:31], v[30:31], v[32:33], v[36:37]
	v_lshlrev_b32_e32 v32, 16, v34
	v_and_b32_e32 v33, 0xffff0000, v34
	v_lshlrev_b32_e32 v36, 16, v38
	v_and_b32_e32 v37, 0xffff0000, v38
	v_pk_fma_f32 v[32:33], v[24:25], v[32:33], v[36:37]
	v_lshlrev_b32_e32 v24, 16, v35
	v_and_b32_e32 v25, 0xffff0000, v35
	v_lshlrev_b32_e32 v34, 16, v39
	v_and_b32_e32 v35, 0xffff0000, v39
	v_pk_fma_f32 v[28:29], v[28:29], v[44:45], v[46:47]
	v_pk_fma_f32 v[34:35], v[26:27], v[24:25], v[34:35]
	v_cvt_pk_bf16_f32 v24, v28, v29
	v_cvt_pk_bf16_f32 v25, v30, v31
	v_cvt_pk_bf16_f32 v26, v32, v33
	v_cvt_pk_bf16_f32 v27, v34, v35
	global_store_dwordx4 v[42:43], v[24:27], off
	global_load_dwordx4 v[24:27], v[40:41], off offset:256
	s_nop 0
	global_load_dwordx4 v[28:31], v[42:43], off offset:256
	s_waitcnt vmcnt(0) lgkmcnt(0)
	v_lshlrev_b32_e32 v32, 16, v24
	v_and_b32_e32 v33, 0xffff0000, v24
	v_lshlrev_b32_e32 v34, 16, v28
	v_and_b32_e32 v35, 0xffff0000, v28
	v_lshlrev_b32_e32 v24, 16, v25
	v_and_b32_e32 v25, 0xffff0000, v25
	v_lshlrev_b32_e32 v28, 16, v29
	v_and_b32_e32 v29, 0xffff0000, v29
	v_pk_fma_f32 v[22:23], v[22:23], v[24:25], v[28:29]
	v_lshlrev_b32_e32 v24, 16, v26
	v_and_b32_e32 v25, 0xffff0000, v26
	v_lshlrev_b32_e32 v28, 16, v30
	v_and_b32_e32 v29, 0xffff0000, v30
	v_pk_fma_f32 v[24:25], v[16:17], v[24:25], v[28:29]
	v_lshlrev_b32_e32 v16, 16, v27
	v_and_b32_e32 v17, 0xffff0000, v27
	v_lshlrev_b32_e32 v26, 16, v31
	v_and_b32_e32 v27, 0xffff0000, v31
	v_pk_fma_f32 v[20:21], v[20:21], v[32:33], v[34:35]
	v_pk_fma_f32 v[26:27], v[18:19], v[16:17], v[26:27]
	v_cvt_pk_bf16_f32 v16, v20, v21
	v_cvt_pk_bf16_f32 v17, v22, v23
	v_cvt_pk_bf16_f32 v18, v24, v25
	v_cvt_pk_bf16_f32 v19, v26, v27
	v_lshl_add_u64 v[20:21], v[138:139], 0, s[22:23]
	global_store_dwordx4 v[42:43], v[16:19], off offset:256
	v_lshl_add_u64 v[24:25], s[12:13], 0, v[20:21]
	v_lshl_add_u64 v[26:27], s[10:11], 0, v[20:21]
	global_load_dwordx4 v[16:19], v[24:25], off
	global_load_dwordx4 v[20:23], v[26:27], off
	s_mov_b64 s[22:23], -1
	s_waitcnt vmcnt(0) lgkmcnt(0)
	v_lshlrev_b32_e32 v28, 16, v16
	v_and_b32_e32 v29, 0xffff0000, v16
	v_lshlrev_b32_e32 v30, 16, v20
	v_and_b32_e32 v31, 0xffff0000, v20
	v_lshlrev_b32_e32 v16, 16, v17
	v_and_b32_e32 v17, 0xffff0000, v17
	v_lshlrev_b32_e32 v20, 16, v21
	v_and_b32_e32 v21, 0xffff0000, v21
	v_pk_fma_f32 v[14:15], v[14:15], v[16:17], v[20:21]
	v_lshlrev_b32_e32 v16, 16, v18
	v_and_b32_e32 v17, 0xffff0000, v18
	v_lshlrev_b32_e32 v20, 16, v22
	v_and_b32_e32 v21, 0xffff0000, v22
	v_pk_fma_f32 v[16:17], v[8:9], v[16:17], v[20:21]
	v_lshlrev_b32_e32 v8, 16, v19
	v_and_b32_e32 v9, 0xffff0000, v19
	v_lshlrev_b32_e32 v18, 16, v23
	v_and_b32_e32 v19, 0xffff0000, v23
	v_pk_fma_f32 v[12:13], v[12:13], v[28:29], v[30:31]
	v_pk_fma_f32 v[18:19], v[10:11], v[8:9], v[18:19]
	v_cvt_pk_bf16_f32 v8, v12, v13
	v_cvt_pk_bf16_f32 v9, v14, v15
	v_cvt_pk_bf16_f32 v10, v16, v17
	v_cvt_pk_bf16_f32 v11, v18, v19
	global_store_dwordx4 v[26:27], v[8:11], off
	global_load_dwordx4 v[8:11], v[24:25], off offset:256
	s_nop 0
	global_load_dwordx4 v[12:15], v[26:27], off offset:256
	s_waitcnt vmcnt(0) lgkmcnt(0)
	v_lshlrev_b32_e32 v16, 16, v8
	v_and_b32_e32 v17, 0xffff0000, v8
	v_lshlrev_b32_e32 v18, 16, v12
	v_and_b32_e32 v19, 0xffff0000, v12
	v_lshlrev_b32_e32 v8, 16, v9
	v_and_b32_e32 v9, 0xffff0000, v9
	v_lshlrev_b32_e32 v12, 16, v13
	v_and_b32_e32 v13, 0xffff0000, v13
	v_pk_fma_f32 v[6:7], v[6:7], v[8:9], v[12:13]
	v_lshlrev_b32_e32 v8, 16, v10
	v_and_b32_e32 v9, 0xffff0000, v10
	v_lshlrev_b32_e32 v12, 16, v14
	v_and_b32_e32 v13, 0xffff0000, v14
	v_pk_fma_f32 v[8:9], v[0:1], v[8:9], v[12:13]
	v_lshlrev_b32_e32 v0, 16, v11
	v_and_b32_e32 v1, 0xffff0000, v11
	v_lshlrev_b32_e32 v10, 16, v15
	v_and_b32_e32 v11, 0xffff0000, v15
	v_pk_fma_f32 v[4:5], v[4:5], v[16:17], v[18:19]
	v_pk_fma_f32 v[10:11], v[2:3], v[0:1], v[10:11]
	v_cvt_pk_bf16_f32 v0, v4, v5
	v_cvt_pk_bf16_f32 v1, v6, v7
	v_cvt_pk_bf16_f32 v2, v8, v9
	v_cvt_pk_bf16_f32 v3, v10, v11
	global_store_dwordx4 v[26:27], v[0:3], off offset:256
	s_cbranch_vccnz .LBB0_139
	s_and_b64 vcc, exec, s[6:7]
	s_cbranch_vccnz .LBB0_138
	s_barrier
	s_branch .LBB0_138

.LBB0_170:
	v_lshl_add_u32 v142, s39, 8, v144
	v_lshl_add_u32 v140, s2, 8, v146
	v_ashrrev_i32_e32 v143, 31, v142
	v_ashrrev_i32_e32 v141, 31, v140
	v_lshlrev_b64 v[138:139], 10, v[142:143]
	v_lshl_add_u64 v[138:139], v[138:139], 0, v[140:141]
	v_lshlrev_b64 v[138:139], 1, v[138:139]
	v_lshl_add_u64 v[156:157], s[10:11], 0, v[138:139]
	v_lshl_add_u64 v[158:159], s[8:9], 0, v[138:139]
	global_load_dwordx4 v[148:151], v[156:157], off
	global_load_dwordx4 v[152:155], v[158:159], off
	s_mov_b64 s[20:21], 0x40000
	s_andn2_b64 vcc, exec, s[6:7]
	s_waitcnt vmcnt(0) lgkmcnt(0)
	v_lshlrev_b32_e32 v166, 16, v148
	v_and_b32_e32 v167, 0xffff0000, v148
	v_lshlrev_b32_e32 v168, 16, v152
	v_and_b32_e32 v169, 0xffff0000, v152
	v_lshlrev_b32_e32 v148, 16, v149
	v_and_b32_e32 v149, 0xffff0000, v149
	v_lshlrev_b32_e32 v152, 16, v153
	v_and_b32_e32 v153, 0xffff0000, v153
	v_pk_fma_f32 v[126:127], v[126:127], v[148:149], v[152:153]
	v_lshlrev_b32_e32 v148, 16, v150
	v_and_b32_e32 v149, 0xffff0000, v150
	v_lshlrev_b32_e32 v152, 16, v154
	v_and_b32_e32 v153, 0xffff0000, v154
	v_pk_fma_f32 v[148:149], v[120:121], v[148:149], v[152:153]
	v_lshlrev_b32_e32 v120, 16, v151
	v_and_b32_e32 v121, 0xffff0000, v151
	v_lshlrev_b32_e32 v150, 16, v155
	v_and_b32_e32 v151, 0xffff0000, v155
	v_pk_fma_f32 v[124:125], v[124:125], v[166:167], v[168:169]
	v_pk_fma_f32 v[150:151], v[122:123], v[120:121], v[150:151]
	v_cvt_pk_bf16_f32 v120, v124, v125
	v_cvt_pk_bf16_f32 v121, v126, v127
	v_cvt_pk_bf16_f32 v122, v148, v149
	v_cvt_pk_bf16_f32 v123, v150, v151
	global_store_dwordx4 v[158:159], v[120:123], off
	global_load_dwordx4 v[120:123], v[156:157], off offset:256
	s_nop 0
	global_load_dwordx4 v[124:127], v[158:159], off offset:256
	s_waitcnt vmcnt(0) lgkmcnt(0)
	v_lshlrev_b32_e32 v148, 16, v120
	v_and_b32_e32 v149, 0xffff0000, v120
	v_lshlrev_b32_e32 v150, 16, v124
	v_and_b32_e32 v151, 0xffff0000, v124
	v_lshlrev_b32_e32 v120, 16, v121
	v_and_b32_e32 v121, 0xffff0000, v121
	v_lshlrev_b32_e32 v124, 16, v125
	v_and_b32_e32 v125, 0xffff0000, v125
	v_pk_fma_f32 v[118:119], v[118:119], v[120:121], v[124:125]
	v_lshlrev_b32_e32 v120, 16, v122
	v_and_b32_e32 v121, 0xffff0000, v122
	v_lshlrev_b32_e32 v124, 16, v126
	v_and_b32_e32 v125, 0xffff0000, v126
	v_pk_fma_f32 v[120:121], v[112:113], v[120:121], v[124:125]
	v_lshlrev_b32_e32 v112, 16, v123
	v_and_b32_e32 v113, 0xffff0000, v123
	v_lshlrev_b32_e32 v122, 16, v127
	v_and_b32_e32 v123, 0xffff0000, v127
	v_pk_fma_f32 v[116:117], v[116:117], v[148:149], v[150:151]
	v_pk_fma_f32 v[122:123], v[114:115], v[112:113], v[122:123]
	v_cvt_pk_bf16_f32 v112, v116, v117
	v_cvt_pk_bf16_f32 v113, v118, v119
	v_cvt_pk_bf16_f32 v114, v120, v121
	v_cvt_pk_bf16_f32 v115, v122, v123
	global_store_dwordx4 v[158:159], v[112:115], off offset:256
	s_nop 1
	v_or_b32_e32 v112, 16, v142
	v_ashrrev_i32_e32 v113, 31, v112
	v_lshlrev_b64 v[112:113], 10, v[112:113]
	v_lshl_add_u64 v[112:113], v[112:113], 0, v[140:141]
	v_lshlrev_b64 v[116:117], 1, v[112:113]
	v_lshl_add_u64 v[120:121], s[10:11], 0, v[116:117]
	v_lshl_add_u64 v[122:123], s[8:9], 0, v[116:117]
	global_load_dwordx4 v[112:115], v[120:121], off
	global_load_dwordx4 v[116:119], v[122:123], off
	s_waitcnt vmcnt(0) lgkmcnt(0)
	v_lshlrev_b32_e32 v124, 16, v112
	v_and_b32_e32 v125, 0xffff0000, v112
	v_lshlrev_b32_e32 v126, 16, v116
	v_and_b32_e32 v127, 0xffff0000, v116
	v_lshlrev_b32_e32 v112, 16, v113
	v_and_b32_e32 v113, 0xffff0000, v113
	v_lshlrev_b32_e32 v116, 16, v117
	v_and_b32_e32 v117, 0xffff0000, v117
	v_pk_fma_f32 v[110:111], v[110:111], v[112:113], v[116:117]
	v_lshlrev_b32_e32 v112, 16, v114
	v_and_b32_e32 v113, 0xffff0000, v114
	v_lshlrev_b32_e32 v116, 16, v118
	v_and_b32_e32 v117, 0xffff0000, v118
	v_pk_fma_f32 v[112:113], v[104:105], v[112:113], v[116:117]
	v_lshlrev_b32_e32 v104, 16, v115
	v_and_b32_e32 v105, 0xffff0000, v115
	v_lshlrev_b32_e32 v114, 16, v119
	v_and_b32_e32 v115, 0xffff0000, v119
	v_pk_fma_f32 v[108:109], v[108:109], v[124:125], v[126:127]
	v_pk_fma_f32 v[114:115], v[106:107], v[104:105], v[114:115]
	v_cvt_pk_bf16_f32 v104, v108, v109
	v_cvt_pk_bf16_f32 v105, v110, v111
	v_cvt_pk_bf16_f32 v106, v112, v113
	v_cvt_pk_bf16_f32 v107, v114, v115
	global_store_dwordx4 v[122:123], v[104:107], off
	global_load_dwordx4 v[104:107], v[120:121], off offset:256
	s_nop 0
	global_load_dwordx4 v[108:111], v[122:123], off offset:256
	s_waitcnt vmcnt(0) lgkmcnt(0)
	v_lshlrev_b32_e32 v112, 16, v104
	v_and_b32_e32 v113, 0xffff0000, v104
	v_lshlrev_b32_e32 v114, 16, v108
	v_and_b32_e32 v115, 0xffff0000, v108
	v_lshlrev_b32_e32 v104, 16, v105
	v_and_b32_e32 v105, 0xffff0000, v105
	v_lshlrev_b32_e32 v108, 16, v109
	v_and_b32_e32 v109, 0xffff0000, v109
	v_pk_fma_f32 v[102:103], v[102:103], v[104:105], v[108:109]
	v_lshlrev_b32_e32 v104, 16, v106
	v_and_b32_e32 v105, 0xffff0000, v106
	v_lshlrev_b32_e32 v108, 16, v110
	v_and_b32_e32 v109, 0xffff0000, v110
	v_pk_fma_f32 v[104:105], v[96:97], v[104:105], v[108:109]
	v_lshlrev_b32_e32 v96, 16, v107
	v_and_b32_e32 v97, 0xffff0000, v107
	v_lshlrev_b32_e32 v106, 16, v111
	v_and_b32_e32 v107, 0xffff0000, v111
	v_pk_fma_f32 v[100:101], v[100:101], v[112:113], v[114:115]
	v_pk_fma_f32 v[106:107], v[98:99], v[96:97], v[106:107]
	v_cvt_pk_bf16_f32 v96, v100, v101
	v_cvt_pk_bf16_f32 v97, v102, v103
	v_cvt_pk_bf16_f32 v98, v104, v105
	v_cvt_pk_bf16_f32 v99, v106, v107
	global_store_dwordx4 v[122:123], v[96:99], off offset:256
	s_nop 1
	v_or_b32_e32 v96, 32, v142
	v_ashrrev_i32_e32 v97, 31, v96
	v_lshlrev_b64 v[96:97], 10, v[96:97]
	v_lshl_add_u64 v[96:97], v[96:97], 0, v[140:141]
	v_lshlrev_b64 v[100:101], 1, v[96:97]
	v_lshl_add_u64 v[104:105], s[10:11], 0, v[100:101]
	v_lshl_add_u64 v[106:107], s[8:9], 0, v[100:101]
	global_load_dwordx4 v[96:99], v[104:105], off
	global_load_dwordx4 v[100:103], v[106:107], off
	s_waitcnt vmcnt(0) lgkmcnt(0)
	v_lshlrev_b32_e32 v108, 16, v96
	v_and_b32_e32 v109, 0xffff0000, v96
	v_lshlrev_b32_e32 v110, 16, v100
	v_and_b32_e32 v111, 0xffff0000, v100
	v_lshlrev_b32_e32 v96, 16, v97
	v_and_b32_e32 v97, 0xffff0000, v97
	v_lshlrev_b32_e32 v100, 16, v101
	v_and_b32_e32 v101, 0xffff0000, v101
	v_pk_fma_f32 v[94:95], v[94:95], v[96:97], v[100:101]
	v_lshlrev_b32_e32 v96, 16, v98
	v_and_b32_e32 v97, 0xffff0000, v98
	v_lshlrev_b32_e32 v100, 16, v102
	v_and_b32_e32 v101, 0xffff0000, v102
	v_pk_fma_f32 v[96:97], v[88:89], v[96:97], v[100:101]
	v_lshlrev_b32_e32 v88, 16, v99
	v_and_b32_e32 v89, 0xffff0000, v99
	v_lshlrev_b32_e32 v98, 16, v103
	v_and_b32_e32 v99, 0xffff0000, v103
	v_pk_fma_f32 v[92:93], v[92:93], v[108:109], v[110:111]
	v_pk_fma_f32 v[98:99], v[90:91], v[88:89], v[98:99]
	v_cvt_pk_bf16_f32 v88, v92, v93
	v_cvt_pk_bf16_f32 v89, v94, v95
	v_cvt_pk_bf16_f32 v90, v96, v97
	v_cvt_pk_bf16_f32 v91, v98, v99
	global_store_dwordx4 v[106:107], v[88:91], off
	global_load_dwordx4 v[88:91], v[104:105], off offset:256
	s_nop 0
	global_load_dwordx4 v[92:95], v[106:107], off offset:256
	s_waitcnt vmcnt(0) lgkmcnt(0)
	v_lshlrev_b32_e32 v96, 16, v88
	v_and_b32_e32 v97, 0xffff0000, v88
	v_lshlrev_b32_e32 v98, 16, v92
	v_and_b32_e32 v99, 0xffff0000, v92
	v_lshlrev_b32_e32 v88, 16, v89
	v_and_b32_e32 v89, 0xffff0000, v89
	v_lshlrev_b32_e32 v92, 16, v93
	v_and_b32_e32 v93, 0xffff0000, v93
	v_pk_fma_f32 v[86:87], v[86:87], v[88:89], v[92:93]
	v_lshlrev_b32_e32 v88, 16, v90
	v_and_b32_e32 v89, 0xffff0000, v90
	v_lshlrev_b32_e32 v92, 16, v94
	v_and_b32_e32 v93, 0xffff0000, v94
	v_pk_fma_f32 v[88:89], v[80:81], v[88:89], v[92:93]
	v_lshlrev_b32_e32 v80, 16, v91
	v_and_b32_e32 v81, 0xffff0000, v91
	v_lshlrev_b32_e32 v90, 16, v95
	v_and_b32_e32 v91, 0xffff0000, v95
	v_pk_fma_f32 v[84:85], v[84:85], v[96:97], v[98:99]
	v_pk_fma_f32 v[90:91], v[82:83], v[80:81], v[90:91]
	v_cvt_pk_bf16_f32 v80, v84, v85
	v_cvt_pk_bf16_f32 v81, v86, v87
	v_cvt_pk_bf16_f32 v82, v88, v89
	v_cvt_pk_bf16_f32 v83, v90, v91
	global_store_dwordx4 v[106:107], v[80:83], off offset:256
	s_nop 1
	v_or_b32_e32 v80, 48, v142
	v_ashrrev_i32_e32 v81, 31, v80
	v_lshlrev_b64 v[80:81], 10, v[80:81]
	v_lshl_add_u64 v[80:81], v[80:81], 0, v[140:141]
	v_lshlrev_b64 v[84:85], 1, v[80:81]
	v_lshl_add_u64 v[88:89], s[10:11], 0, v[84:85]
	v_lshl_add_u64 v[90:91], s[8:9], 0, v[84:85]
	global_load_dwordx4 v[80:83], v[88:89], off
	global_load_dwordx4 v[84:87], v[90:91], off
	s_waitcnt vmcnt(0) lgkmcnt(0)
	v_lshlrev_b32_e32 v92, 16, v80
	v_and_b32_e32 v93, 0xffff0000, v80
	v_lshlrev_b32_e32 v94, 16, v84
	v_and_b32_e32 v95, 0xffff0000, v84
	v_lshlrev_b32_e32 v80, 16, v81
	v_and_b32_e32 v81, 0xffff0000, v81
	v_lshlrev_b32_e32 v84, 16, v85
	v_and_b32_e32 v85, 0xffff0000, v85
	v_pk_fma_f32 v[78:79], v[78:79], v[80:81], v[84:85]
	v_lshlrev_b32_e32 v80, 16, v82
	v_and_b32_e32 v81, 0xffff0000, v82
	v_lshlrev_b32_e32 v84, 16, v86
	v_and_b32_e32 v85, 0xffff0000, v86
	v_pk_fma_f32 v[80:81], v[72:73], v[80:81], v[84:85]
	v_lshlrev_b32_e32 v72, 16, v83
	v_and_b32_e32 v73, 0xffff0000, v83
	v_lshlrev_b32_e32 v82, 16, v87
	v_and_b32_e32 v83, 0xffff0000, v87
	v_pk_fma_f32 v[76:77], v[76:77], v[92:93], v[94:95]
	v_pk_fma_f32 v[82:83], v[74:75], v[72:73], v[82:83]
	v_cvt_pk_bf16_f32 v72, v76, v77
	v_cvt_pk_bf16_f32 v73, v78, v79
	v_cvt_pk_bf16_f32 v74, v80, v81
	v_cvt_pk_bf16_f32 v75, v82, v83
	global_store_dwordx4 v[90:91], v[72:75], off
	global_load_dwordx4 v[72:75], v[88:89], off offset:256
	s_nop 0
	global_load_dwordx4 v[76:79], v[90:91], off offset:256
	s_waitcnt vmcnt(0) lgkmcnt(0)
	v_lshlrev_b32_e32 v80, 16, v72
	v_and_b32_e32 v81, 0xffff0000, v72
	v_lshlrev_b32_e32 v82, 16, v76
	v_and_b32_e32 v83, 0xffff0000, v76
	v_lshlrev_b32_e32 v72, 16, v73
	v_and_b32_e32 v73, 0xffff0000, v73
	v_lshlrev_b32_e32 v76, 16, v77
	v_and_b32_e32 v77, 0xffff0000, v77
	v_pk_fma_f32 v[70:71], v[70:71], v[72:73], v[76:77]
	v_lshlrev_b32_e32 v72, 16, v74
	v_and_b32_e32 v73, 0xffff0000, v74
	v_lshlrev_b32_e32 v76, 16, v78
	v_and_b32_e32 v77, 0xffff0000, v78
	v_pk_fma_f32 v[72:73], v[64:65], v[72:73], v[76:77]
	v_lshlrev_b32_e32 v64, 16, v75
	v_and_b32_e32 v65, 0xffff0000, v75
	v_lshlrev_b32_e32 v74, 16, v79
	v_and_b32_e32 v75, 0xffff0000, v79
	v_pk_fma_f32 v[68:69], v[68:69], v[80:81], v[82:83]
	v_pk_fma_f32 v[74:75], v[66:67], v[64:65], v[74:75]
	v_cvt_pk_bf16_f32 v64, v68, v69
	v_cvt_pk_bf16_f32 v65, v70, v71
	v_cvt_pk_bf16_f32 v66, v72, v73
	v_cvt_pk_bf16_f32 v67, v74, v75
	v_lshl_add_u64 v[68:69], v[138:139], 0, s[20:21]
	global_store_dwordx4 v[90:91], v[64:67], off offset:256
	v_lshl_add_u64 v[72:73], s[10:11], 0, v[68:69]
	v_lshl_add_u64 v[74:75], s[8:9], 0, v[68:69]
	global_load_dwordx4 v[64:67], v[72:73], off
	global_load_dwordx4 v[68:71], v[74:75], off
	s_mov_b64 s[20:21], 0x48000
	s_waitcnt vmcnt(0) lgkmcnt(0)
	v_lshlrev_b32_e32 v76, 16, v64
	v_and_b32_e32 v77, 0xffff0000, v64
	v_lshlrev_b32_e32 v78, 16, v68
	v_and_b32_e32 v79, 0xffff0000, v68
	v_lshlrev_b32_e32 v64, 16, v65
	v_and_b32_e32 v65, 0xffff0000, v65
	v_lshlrev_b32_e32 v68, 16, v69
	v_and_b32_e32 v69, 0xffff0000, v69
	v_pk_fma_f32 v[62:63], v[62:63], v[64:65], v[68:69]
	v_lshlrev_b32_e32 v64, 16, v66
	v_and_b32_e32 v65, 0xffff0000, v66
	v_lshlrev_b32_e32 v68, 16, v70
	v_and_b32_e32 v69, 0xffff0000, v70
	v_pk_fma_f32 v[64:65], v[56:57], v[64:65], v[68:69]
	v_lshlrev_b32_e32 v56, 16, v67
	v_and_b32_e32 v57, 0xffff0000, v67
	v_lshlrev_b32_e32 v66, 16, v71
	v_and_b32_e32 v67, 0xffff0000, v71
	v_pk_fma_f32 v[60:61], v[60:61], v[76:77], v[78:79]
	v_pk_fma_f32 v[66:67], v[58:59], v[56:57], v[66:67]
	v_cvt_pk_bf16_f32 v56, v60, v61
	v_cvt_pk_bf16_f32 v57, v62, v63
	v_cvt_pk_bf16_f32 v58, v64, v65
	v_cvt_pk_bf16_f32 v59, v66, v67
	global_store_dwordx4 v[74:75], v[56:59], off
	global_load_dwordx4 v[56:59], v[72:73], off offset:256
	s_nop 0
	global_load_dwordx4 v[60:63], v[74:75], off offset:256
	s_waitcnt vmcnt(0) lgkmcnt(0)
	v_lshlrev_b32_e32 v64, 16, v56
	v_and_b32_e32 v65, 0xffff0000, v56
	v_lshlrev_b32_e32 v66, 16, v60
	v_and_b32_e32 v67, 0xffff0000, v60
	v_lshlrev_b32_e32 v56, 16, v57
	v_and_b32_e32 v57, 0xffff0000, v57
	v_lshlrev_b32_e32 v60, 16, v61
	v_and_b32_e32 v61, 0xffff0000, v61
	v_pk_fma_f32 v[54:55], v[54:55], v[56:57], v[60:61]
	v_lshlrev_b32_e32 v56, 16, v58
	v_and_b32_e32 v57, 0xffff0000, v58
	v_lshlrev_b32_e32 v60, 16, v62
	v_and_b32_e32 v61, 0xffff0000, v62
	v_pk_fma_f32 v[56:57], v[48:49], v[56:57], v[60:61]
	v_lshlrev_b32_e32 v48, 16, v59
	v_and_b32_e32 v49, 0xffff0000, v59
	v_lshlrev_b32_e32 v58, 16, v63
	v_and_b32_e32 v59, 0xffff0000, v63
	v_pk_fma_f32 v[52:53], v[52:53], v[64:65], v[66:67]
	v_pk_fma_f32 v[58:59], v[50:51], v[48:49], v[58:59]
	v_cvt_pk_bf16_f32 v48, v52, v53
	v_cvt_pk_bf16_f32 v49, v54, v55
	v_cvt_pk_bf16_f32 v50, v56, v57
	v_cvt_pk_bf16_f32 v51, v58, v59
	v_lshl_add_u64 v[52:53], v[138:139], 0, s[20:21]
	global_store_dwordx4 v[74:75], v[48:51], off offset:256
	v_lshl_add_u64 v[56:57], s[10:11], 0, v[52:53]
	v_lshl_add_u64 v[58:59], s[8:9], 0, v[52:53]
	global_load_dwordx4 v[48:51], v[56:57], off
	global_load_dwordx4 v[52:55], v[58:59], off
	s_mov_b64 s[20:21], 0x50000
	s_waitcnt vmcnt(0) lgkmcnt(0)
	v_lshlrev_b32_e32 v60, 16, v48
	v_and_b32_e32 v61, 0xffff0000, v48
	v_lshlrev_b32_e32 v62, 16, v52
	v_and_b32_e32 v63, 0xffff0000, v52
	v_lshlrev_b32_e32 v48, 16, v49
	v_and_b32_e32 v49, 0xffff0000, v49
	v_lshlrev_b32_e32 v52, 16, v53
	v_and_b32_e32 v53, 0xffff0000, v53
	v_pk_fma_f32 v[46:47], v[46:47], v[48:49], v[52:53]
	v_lshlrev_b32_e32 v48, 16, v50
	v_and_b32_e32 v49, 0xffff0000, v50
	v_lshlrev_b32_e32 v52, 16, v54
	v_and_b32_e32 v53, 0xffff0000, v54
	v_pk_fma_f32 v[48:49], v[40:41], v[48:49], v[52:53]
	v_lshlrev_b32_e32 v40, 16, v51
	v_and_b32_e32 v41, 0xffff0000, v51
	v_lshlrev_b32_e32 v50, 16, v55
	v_and_b32_e32 v51, 0xffff0000, v55
	v_pk_fma_f32 v[44:45], v[44:45], v[60:61], v[62:63]
	v_pk_fma_f32 v[50:51], v[42:43], v[40:41], v[50:51]
	v_cvt_pk_bf16_f32 v40, v44, v45
	v_cvt_pk_bf16_f32 v41, v46, v47
	v_cvt_pk_bf16_f32 v42, v48, v49
	v_cvt_pk_bf16_f32 v43, v50, v51
	global_store_dwordx4 v[58:59], v[40:43], off
	global_load_dwordx4 v[40:43], v[56:57], off offset:256
	s_nop 0
	global_load_dwordx4 v[44:47], v[58:59], off offset:256
	s_waitcnt vmcnt(0) lgkmcnt(0)
	v_lshlrev_b32_e32 v48, 16, v40
	v_and_b32_e32 v49, 0xffff0000, v40
	v_lshlrev_b32_e32 v50, 16, v44
	v_and_b32_e32 v51, 0xffff0000, v44
	v_lshlrev_b32_e32 v40, 16, v41
	v_and_b32_e32 v41, 0xffff0000, v41
	v_lshlrev_b32_e32 v44, 16, v45
	v_and_b32_e32 v45, 0xffff0000, v45
	v_pk_fma_f32 v[38:39], v[38:39], v[40:41], v[44:45]
	v_lshlrev_b32_e32 v40, 16, v42
	v_and_b32_e32 v41, 0xffff0000, v42
	v_lshlrev_b32_e32 v44, 16, v46
	v_and_b32_e32 v45, 0xffff0000, v46
	v_pk_fma_f32 v[40:41], v[32:33], v[40:41], v[44:45]
	v_lshlrev_b32_e32 v32, 16, v43
	v_and_b32_e32 v33, 0xffff0000, v43
	v_lshlrev_b32_e32 v42, 16, v47
	v_and_b32_e32 v43, 0xffff0000, v47
	v_pk_fma_f32 v[36:37], v[36:37], v[48:49], v[50:51]
	v_pk_fma_f32 v[42:43], v[34:35], v[32:33], v[42:43]
	v_cvt_pk_bf16_f32 v32, v36, v37
	v_cvt_pk_bf16_f32 v33, v38, v39
	v_cvt_pk_bf16_f32 v34, v40, v41
	v_cvt_pk_bf16_f32 v35, v42, v43
	v_lshl_add_u64 v[36:37], v[138:139], 0, s[20:21]
	global_store_dwordx4 v[58:59], v[32:35], off offset:256
	v_lshl_add_u64 v[40:41], s[10:11], 0, v[36:37]
	v_lshl_add_u64 v[42:43], s[8:9], 0, v[36:37]
	global_load_dwordx4 v[32:35], v[40:41], off
	global_load_dwordx4 v[36:39], v[42:43], off
	s_mov_b64 s[20:21], 0x58000
	s_waitcnt vmcnt(0) lgkmcnt(0)
	v_lshlrev_b32_e32 v44, 16, v32
	v_and_b32_e32 v45, 0xffff0000, v32
	v_lshlrev_b32_e32 v46, 16, v36
	v_and_b32_e32 v47, 0xffff0000, v36
	v_lshlrev_b32_e32 v32, 16, v33
	v_and_b32_e32 v33, 0xffff0000, v33
	v_lshlrev_b32_e32 v36, 16, v37
	v_and_b32_e32 v37, 0xffff0000, v37
	v_pk_fma_f32 v[30:31], v[30:31], v[32:33], v[36:37]
	v_lshlrev_b32_e32 v32, 16, v34
	v_and_b32_e32 v33, 0xffff0000, v34
	v_lshlrev_b32_e32 v36, 16, v38
	v_and_b32_e32 v37, 0xffff0000, v38
	v_pk_fma_f32 v[32:33], v[24:25], v[32:33], v[36:37]
	v_lshlrev_b32_e32 v24, 16, v35
	v_and_b32_e32 v25, 0xffff0000, v35
	v_lshlrev_b32_e32 v34, 16, v39
	v_and_b32_e32 v35, 0xffff0000, v39
	v_pk_fma_f32 v[28:29], v[28:29], v[44:45], v[46:47]
	v_pk_fma_f32 v[34:35], v[26:27], v[24:25], v[34:35]
	v_cvt_pk_bf16_f32 v24, v28, v29
	v_cvt_pk_bf16_f32 v25, v30, v31
	v_cvt_pk_bf16_f32 v26, v32, v33
	v_cvt_pk_bf16_f32 v27, v34, v35
	global_store_dwordx4 v[42:43], v[24:27], off
	global_load_dwordx4 v[24:27], v[40:41], off offset:256
	s_nop 0
	global_load_dwordx4 v[28:31], v[42:43], off offset:256
	s_waitcnt vmcnt(0) lgkmcnt(0)
	v_lshlrev_b32_e32 v32, 16, v24
	v_and_b32_e32 v33, 0xffff0000, v24
	v_lshlrev_b32_e32 v34, 16, v28
	v_and_b32_e32 v35, 0xffff0000, v28
	v_lshlrev_b32_e32 v24, 16, v25
	v_and_b32_e32 v25, 0xffff0000, v25
	v_lshlrev_b32_e32 v28, 16, v29
	v_and_b32_e32 v29, 0xffff0000, v29
	v_pk_fma_f32 v[22:23], v[22:23], v[24:25], v[28:29]
	v_lshlrev_b32_e32 v24, 16, v26
	v_and_b32_e32 v25, 0xffff0000, v26
	v_lshlrev_b32_e32 v28, 16, v30
	v_and_b32_e32 v29, 0xffff0000, v30
	v_pk_fma_f32 v[24:25], v[16:17], v[24:25], v[28:29]
	v_lshlrev_b32_e32 v16, 16, v27
	v_and_b32_e32 v17, 0xffff0000, v27
	v_lshlrev_b32_e32 v26, 16, v31
	v_and_b32_e32 v27, 0xffff0000, v31
	v_pk_fma_f32 v[20:21], v[20:21], v[32:33], v[34:35]
	v_pk_fma_f32 v[26:27], v[18:19], v[16:17], v[26:27]
	v_cvt_pk_bf16_f32 v16, v20, v21
	v_cvt_pk_bf16_f32 v17, v22, v23
	v_cvt_pk_bf16_f32 v18, v24, v25
	v_cvt_pk_bf16_f32 v19, v26, v27
	v_lshl_add_u64 v[20:21], v[138:139], 0, s[20:21]
	global_store_dwordx4 v[42:43], v[16:19], off offset:256
	v_lshl_add_u64 v[24:25], s[10:11], 0, v[20:21]
	v_lshl_add_u64 v[26:27], s[8:9], 0, v[20:21]
	global_load_dwordx4 v[16:19], v[24:25], off
	global_load_dwordx4 v[20:23], v[26:27], off
	s_mov_b64 s[20:21], -1
	s_waitcnt vmcnt(0) lgkmcnt(0)
	v_lshlrev_b32_e32 v28, 16, v16
	v_and_b32_e32 v29, 0xffff0000, v16
	v_lshlrev_b32_e32 v30, 16, v20
	v_and_b32_e32 v31, 0xffff0000, v20
	v_lshlrev_b32_e32 v16, 16, v17
	v_and_b32_e32 v17, 0xffff0000, v17
	v_lshlrev_b32_e32 v20, 16, v21
	v_and_b32_e32 v21, 0xffff0000, v21
	v_pk_fma_f32 v[14:15], v[14:15], v[16:17], v[20:21]
	v_lshlrev_b32_e32 v16, 16, v18
	v_and_b32_e32 v17, 0xffff0000, v18
	v_lshlrev_b32_e32 v20, 16, v22
	v_and_b32_e32 v21, 0xffff0000, v22
	v_pk_fma_f32 v[16:17], v[8:9], v[16:17], v[20:21]
	v_lshlrev_b32_e32 v8, 16, v19
	v_and_b32_e32 v9, 0xffff0000, v19
	v_lshlrev_b32_e32 v18, 16, v23
	v_and_b32_e32 v19, 0xffff0000, v23
	v_pk_fma_f32 v[12:13], v[12:13], v[28:29], v[30:31]
	v_pk_fma_f32 v[18:19], v[10:11], v[8:9], v[18:19]
	v_cvt_pk_bf16_f32 v8, v12, v13
	v_cvt_pk_bf16_f32 v9, v14, v15
	v_cvt_pk_bf16_f32 v10, v16, v17
	v_cvt_pk_bf16_f32 v11, v18, v19
	global_store_dwordx4 v[26:27], v[8:11], off
	global_load_dwordx4 v[8:11], v[24:25], off offset:256
	s_nop 0
	global_load_dwordx4 v[12:15], v[26:27], off offset:256
	s_waitcnt vmcnt(0) lgkmcnt(0)
	v_lshlrev_b32_e32 v16, 16, v8
	v_and_b32_e32 v17, 0xffff0000, v8
	v_lshlrev_b32_e32 v18, 16, v12
	v_and_b32_e32 v19, 0xffff0000, v12
	v_lshlrev_b32_e32 v8, 16, v9
	v_and_b32_e32 v9, 0xffff0000, v9
	v_lshlrev_b32_e32 v12, 16, v13
	v_and_b32_e32 v13, 0xffff0000, v13
	v_pk_fma_f32 v[6:7], v[6:7], v[8:9], v[12:13]
	v_lshlrev_b32_e32 v8, 16, v10
	v_and_b32_e32 v9, 0xffff0000, v10
	v_lshlrev_b32_e32 v12, 16, v14
	v_and_b32_e32 v13, 0xffff0000, v14
	v_pk_fma_f32 v[8:9], v[0:1], v[8:9], v[12:13]
	v_lshlrev_b32_e32 v0, 16, v11
	v_and_b32_e32 v1, 0xffff0000, v11
	v_lshlrev_b32_e32 v10, 16, v15
	v_and_b32_e32 v11, 0xffff0000, v15
	v_pk_fma_f32 v[4:5], v[4:5], v[16:17], v[18:19]
	v_pk_fma_f32 v[10:11], v[2:3], v[0:1], v[10:11]
	v_cvt_pk_bf16_f32 v0, v4, v5
	v_cvt_pk_bf16_f32 v1, v6, v7
	v_cvt_pk_bf16_f32 v2, v8, v9
	v_cvt_pk_bf16_f32 v3, v10, v11
	global_store_dwordx4 v[26:27], v[0:3], off offset:256
	s_cbranch_vccnz .LBB0_159
	s_and_b64 vcc, exec, s[4:5]
	s_cbranch_vccnz .LBB0_158
	s_barrier
	s_branch .LBB0_158

.LBB0_188:
	v_lshl_add_u64 v[0:1], s[86:87], 0, v[104:105]
	s_mov_b32 s1, 0x15200000
	v_add_co_u32_e32 v0, vcc, s1, v0
	v_cvt_f32_u32_e32 v107, s82
	s_nop 0
	v_addc_co_u32_e32 v1, vcc, 0, v1, vcc
	global_load_dwordx4 v[4:7], v[0:1], off
	s_nop 0
	global_load_dwordx4 v[0:3], v[0:1], off offset:64
	v_cmp_lt_f32_e32 vcc, s72, v107
	s_nop 1
	v_cndmask_b32_e32 v108, 0, v220, vcc
	v_sub_f32_e32 v107, v108, v107
	v_exp_f32_e32 v107, v107
	s_and_b64 vcc, vcc, exec
	s_cselect_b32 s1, 0xffffffc0, 0
	v_ldexp_f32 v152, v107, s1
	global_load_dwordx4 v[108:111], v[16:17], off
	global_load_dwordx4 v[112:115], v[16:17], off offset:64
	s_waitcnt vmcnt(0) lgkmcnt(0)
	v_mfma_f32_16x16x32_bf16 v[108:111], v[108:111], v[4:7], 0
	global_load_dwordx4 v[116:119], v[16:17], off offset:2112
	v_mfma_f32_16x16x32_bf16 v[108:111], v[112:115], v[0:3], v[108:111]
	global_load_dwordx4 v[112:115], v[16:17], off offset:2048
	s_waitcnt vmcnt(0) lgkmcnt(0)
	v_mfma_f32_16x16x32_bf16 v[112:115], v[112:115], v[4:7], 0
	v_mfma_f32_16x16x32_bf16 v[112:115], v[116:119], v[0:3], v[112:115]
	global_load_dwordx4 v[116:119], v[26:27], off
	global_load_dwordx4 v[120:123], v[28:29], off
	s_waitcnt vmcnt(0) lgkmcnt(0)
	v_mfma_f32_16x16x32_bf16 v[116:119], v[116:119], v[4:7], 0
	global_load_dwordx4 v[124:127], v[38:39], off
	v_mfma_f32_16x16x32_bf16 v[116:119], v[120:123], v[0:3], v[116:119]
	global_load_dwordx4 v[120:123], v[36:37], off
	s_waitcnt vmcnt(0) lgkmcnt(0)
	v_mfma_f32_16x16x32_bf16 v[120:123], v[120:123], v[4:7], 0
	v_mfma_f32_16x16x32_bf16 v[120:123], v[124:127], v[0:3], v[120:123]
	global_load_dwordx4 v[124:127], v[44:45], off
	global_load_dwordx4 v[128:131], v[46:47], off
	s_waitcnt vmcnt(0) lgkmcnt(0)
	v_mfma_f32_16x16x32_bf16 v[124:127], v[124:127], v[4:7], 0
	global_load_dwordx4 v[132:135], v[54:55], off
	v_mfma_f32_16x16x32_bf16 v[124:127], v[128:131], v[0:3], v[124:127]
	global_load_dwordx4 v[128:131], v[52:53], off
	s_waitcnt vmcnt(0) lgkmcnt(0)
	v_mfma_f32_16x16x32_bf16 v[128:131], v[128:131], v[4:7], 0
	v_mfma_f32_16x16x32_bf16 v[128:131], v[132:135], v[0:3], v[128:131]
	global_load_dwordx4 v[132:135], v[60:61], off
	global_load_dwordx4 v[136:139], v[68:69], off
	global_load_dwordx4 v[140:143], v[62:63], off
	global_load_dwordx4 v[148:151], v[70:71], off
	v_pk_mul_f32 v[154:155], v[22:23], v[152:153] op_sel_hi:[1,0]
	v_pk_mul_f32 v[156:157], v[24:25], v[152:153] op_sel_hi:[1,0]
	v_pk_mul_f32 v[180:181], v[40:41], v[152:153] op_sel_hi:[1,0]
	v_pk_mul_f32 v[182:183], v[42:43], v[152:153] op_sel_hi:[1,0]
	v_pk_mul_f32 v[188:189], v[18:19], v[152:153] op_sel_hi:[1,0]
	v_pk_mul_f32 v[158:159], v[72:73], v[152:153] op_sel_hi:[1,0]
	v_pk_mul_f32 v[166:167], v[74:75], v[152:153] op_sel_hi:[1,0]
	v_pk_mul_f32 v[168:169], v[64:65], v[152:153] op_sel_hi:[1,0]
	v_pk_mul_f32 v[170:171], v[66:67], v[152:153] op_sel_hi:[1,0]
	v_pk_mul_f32 v[172:173], v[56:57], v[152:153] op_sel_hi:[1,0]
	v_pk_mul_f32 v[174:175], v[58:59], v[152:153] op_sel_hi:[1,0]
	v_pk_mul_f32 v[176:177], v[48:49], v[152:153] op_sel_hi:[1,0]
	v_pk_mul_f32 v[178:179], v[50:51], v[152:153] op_sel_hi:[1,0]
	v_pk_mul_f32 v[184:185], v[30:31], v[152:153] op_sel_hi:[1,0]
	v_pk_mul_f32 v[186:187], v[34:35], v[152:153] op_sel_hi:[1,0]
	v_pk_mul_f32 v[152:153], v[20:21], v[152:153] op_sel_hi:[1,0]
	v_pk_fma_f32 v[112:113], v[112:113], s[90:91], v[154:155] op_sel_hi:[1,0,1] neg_lo:[0,0,1] neg_hi:[0,0,1]
	v_pk_fma_f32 v[114:115], v[114:115], s[90:91], v[156:157] op_sel_hi:[1,0,1] neg_lo:[0,0,1] neg_hi:[0,0,1]
	v_pk_fma_f32 v[120:121], v[120:121], s[90:91], v[180:181] op_sel_hi:[1,0,1] neg_lo:[0,0,1] neg_hi:[0,0,1]
	v_pk_fma_f32 v[122:123], v[122:123], s[90:91], v[182:183] op_sel_hi:[1,0,1] neg_lo:[0,0,1] neg_hi:[0,0,1]
	v_pk_fma_f32 v[108:109], v[108:109], s[90:91], v[188:189] op_sel_hi:[1,0,1] neg_lo:[0,0,1] neg_hi:[0,0,1]
	v_pk_fma_f32 v[110:111], v[110:111], s[90:91], v[152:153] op_sel_hi:[1,0,1] neg_lo:[0,0,1] neg_hi:[0,0,1]
	v_cndmask_b32_e64 v107, v221, v113, s[14:15]
	v_cndmask_b32_e64 v113, v221, v115, s[16:17]
	v_cndmask_b32_e64 v115, v221, v121, s[34:35]
	v_cndmask_b32_e64 v121, v221, v123, s[36:37]
	v_cndmask_b32_e64 v123, v221, v109, s[6:7]
	v_cndmask_b32_e64 v152, v221, v108, s[4:5]
	v_cndmask_b32_e64 v153, v221, v111, s[8:9]
	v_cndmask_b32_e64 v154, v221, v110, s[10:11]
	v_max3_f32 v108, v152, s73, v123
	v_cndmask_b32_e64 v112, v221, v112, s[12:13]
	v_max3_f32 v108, v108, v154, v153
	v_pk_fma_f32 v[116:117], v[116:117], s[90:91], v[184:185] op_sel_hi:[1,0,1] neg_lo:[0,0,1] neg_hi:[0,0,1]
	v_cndmask_b32_e64 v114, v221, v114, s[20:21]
	v_max3_f32 v155, v108, v112, v107
	v_pk_fma_f32 v[118:119], v[118:119], s[90:91], v[186:187] op_sel_hi:[1,0,1] neg_lo:[0,0,1] neg_hi:[0,0,1]
	v_cndmask_b32_e64 v117, v221, v117, s[24:25]
	v_cndmask_b32_e64 v116, v221, v116, s[22:23]
	v_cndmask_b32_e64 v119, v221, v119, s[26:27]
	v_cndmask_b32_e64 v118, v221, v118, s[28:29]
	v_cndmask_b32_e64 v120, v221, v120, s[30:31]
	v_pk_fma_f32 v[124:125], v[124:125], s[90:91], v[176:177] op_sel_hi:[1,0,1] neg_lo:[0,0,1] neg_hi:[0,0,1]
	v_cndmask_b32_e64 v122, v221, v122, s[38:39]
	v_pk_fma_f32 v[126:127], v[126:127], s[90:91], v[178:179] op_sel_hi:[1,0,1] neg_lo:[0,0,1] neg_hi:[0,0,1]
	v_cndmask_b32_e64 v125, v221, v125, s[44:45]
	v_cndmask_b32_e64 v124, v221, v124, s[42:43]
	v_pk_fma_f32 v[128:129], v[128:129], s[90:91], v[172:173] op_sel_hi:[1,0,1] neg_lo:[0,0,1] neg_hi:[0,0,1]
	v_cndmask_b32_e64 v127, v221, v127, s[40:41]
	v_cndmask_b32_e64 v126, v221, v126, s[46:47]
	v_pk_fma_f32 v[130:131], v[130:131], s[90:91], v[174:175] op_sel_hi:[1,0,1] neg_lo:[0,0,1] neg_hi:[0,0,1]
	v_cndmask_b32_e64 v129, v221, v129, s[52:53]
	v_cndmask_b32_e64 v128, v221, v128, s[50:51]
	v_cndmask_b32_e64 v131, v221, v131, s[48:49]
	v_cndmask_b32_e64 v130, v221, v130, s[54:55]
	v_cmp_lt_f32_e32 vcc, s92, v123
	s_waitcnt vmcnt(0) lgkmcnt(0)
	v_mfma_f32_16x16x32_bf16 v[108:111], v[132:135], v[4:7], 0
	v_max3_f32 v132, v155, v114, v113
	v_max3_f32 v132, v132, v116, v117
	v_max3_f32 v132, v132, v118, v119
	v_mfma_f32_16x16x32_bf16 v[4:7], v[136:139], v[4:7], 0
	v_max3_f32 v132, v132, v120, v115
	v_max3_f32 v132, v132, v122, v121
	v_max3_f32 v132, v132, v124, v125
	v_mfma_f32_16x16x32_bf16 v[108:111], v[140:143], v[0:3], v[108:111]
	v_max3_f32 v132, v132, v126, v127
	v_max3_f32 v132, v132, v128, v129
	v_max3_f32 v132, v132, v130, v131
	v_mfma_f32_16x16x32_bf16 v[0:3], v[148:151], v[0:3], v[4:7]
	s_nop 3
	v_fma_f32 v4, v108, s90, -v168
	v_fma_f32 v5, v109, s90, -v169
	s_nop 1
	v_pk_fma_f32 v[0:1], v[0:1], s[90:91], v[158:159] op_sel_hi:[1,0,1] neg_lo:[0,0,1] neg_hi:[0,0,1]
	v_pk_fma_f32 v[6:7], v[110:111], s[90:91], v[170:171] op_sel_hi:[1,0,1] neg_lo:[0,0,1] neg_hi:[0,0,1]
	v_cndmask_b32_e64 v137, v221, v5, s[60:61]
	v_cndmask_b32_e64 v138, v221, v4, s[58:59]
	v_cndmask_b32_e64 v134, v221, v0, s[66:67]
	v_cndmask_b32_e64 v139, v221, v7, s[56:57]
	v_cndmask_b32_e64 v140, v221, v6, s[62:63]
	v_max3_f32 v0, v132, v138, v137
	v_pk_fma_f32 v[2:3], v[2:3], s[90:91], v[166:167] op_sel_hi:[1,0,1] neg_lo:[0,0,1] neg_hi:[0,0,1]
	v_cndmask_b32_e64 v133, v221, v1, s[68:69]
	v_max3_f32 v0, v0, v140, v139
	v_cndmask_b32_e64 v135, v221, v3, s[64:65]
	v_cndmask_b32_e64 v136, v221, v2, s[70:71]
	v_max3_f32 v0, v0, v134, v133
	v_max3_f32 v0, v0, v136, v135
	ds_bpermute_b32 v1, v193, v0
	s_waitcnt lgkmcnt(0)
	v_max_f32_e32 v1, v1, v1
	v_max_f32_e32 v0, v0, v1
	ds_bpermute_b32 v1, v194, v0
	s_waitcnt lgkmcnt(0)
	v_max_f32_e32 v1, v1, v1
	v_max_f32_e32 v132, v0, v1
	v_sub_f32_e32 v1, v123, v132
	v_sub_f32_e32 v0, v152, v132
	v_mul_f32_e32 v1, 0x3fb8aa3b, v1
	v_sub_f32_e32 v3, v153, v132
	v_mul_f32_e32 v0, 0x3fb8aa3b, v0
	v_exp_f32_e32 v1, v1
	v_sub_f32_e32 v2, v154, v132
	v_mul_f32_e32 v3, 0x3fb8aa3b, v3
	v_exp_f32_e32 v0, v0
	v_sub_f32_e32 v5, v107, v132
	v_mul_f32_e32 v2, 0x3fb8aa3b, v2
	v_exp_f32_e32 v3, v3
	v_sub_f32_e32 v4, v112, v132
	v_mul_f32_e32 v5, 0x3fb8aa3b, v5
	v_exp_f32_e32 v2, v2
	v_mul_f32_e32 v4, 0x3fb8aa3b, v4
	v_exp_f32_e32 v5, v5
	v_cndmask_b32_e32 v1, 0, v1, vcc
	v_cmp_lt_f32_e32 vcc, s92, v152
	v_exp_f32_e32 v4, v4
	v_sub_f32_e32 v7, v113, v132
	v_cndmask_b32_e32 v0, 0, v0, vcc
	v_cmp_lt_f32_e32 vcc, s92, v153
	v_add_f32_e32 v6, 0, v0
	v_add_f32_e32 v6, v1, v6
	v_cndmask_b32_e32 v3, 0, v3, vcc
	v_cmp_lt_f32_e32 vcc, s92, v154
	v_mul_f32_e32 v7, 0x3fb8aa3b, v7
	v_exp_f32_e32 v7, v7
	v_cndmask_b32_e32 v2, 0, v2, vcc
	v_cmp_lt_f32_e32 vcc, s92, v107
	v_add_f32_e32 v6, v2, v6
	v_add_f32_e32 v6, v3, v6
	v_cndmask_b32_e32 v5, 0, v5, vcc
	v_cmp_lt_f32_e32 vcc, s92, v112
	v_sub_f32_e32 v109, v117, v132
	v_sub_f32_e32 v108, v116, v132
	v_cndmask_b32_e32 v4, 0, v4, vcc
	v_add_f32_e32 v6, v4, v6
	v_add_f32_e32 v107, v5, v6
	v_sub_f32_e32 v6, v114, v132
	v_mul_f32_e32 v6, 0x3fb8aa3b, v6
	v_exp_f32_e32 v6, v6
	v_mul_f32_e32 v109, 0x3fb8aa3b, v109
	v_exp_f32_e32 v109, v109
	v_mul_f32_e32 v108, 0x3fb8aa3b, v108
	v_sub_f32_e32 v111, v119, v132
	v_cmp_lt_f32_e32 vcc, s92, v113
	v_exp_f32_e32 v108, v108
	v_sub_f32_e32 v110, v118, v132
	v_mul_f32_e32 v111, 0x3fb8aa3b, v111
	v_cndmask_b32_e32 v7, 0, v7, vcc
	v_cmp_lt_f32_e32 vcc, s92, v114
	v_exp_f32_e32 v111, v111
	v_mul_f32_e32 v110, 0x3fb8aa3b, v110
	v_cndmask_b32_e32 v6, 0, v6, vcc
	v_cmp_lt_f32_e32 vcc, s92, v117
	v_exp_f32_e32 v110, v110
	v_sub_f32_e32 v113, v115, v132
	v_cndmask_b32_e32 v109, 0, v109, vcc
	v_cmp_lt_f32_e32 vcc, s92, v116
	v_sub_f32_e32 v112, v120, v132
	v_mul_f32_e32 v113, 0x3fb8aa3b, v113
	v_cndmask_b32_e32 v108, 0, v108, vcc
	v_cmp_lt_f32_e32 vcc, s92, v119
	v_add_f32_e32 v107, v6, v107
	v_exp_f32_e32 v113, v113
	v_cndmask_b32_e32 v111, 0, v111, vcc
	v_cmp_lt_f32_e32 vcc, s92, v118
	v_mul_f32_e32 v112, 0x3fb8aa3b, v112
	v_add_f32_e32 v107, v7, v107
	v_cndmask_b32_e32 v110, 0, v110, vcc
	v_cmp_lt_f32_e32 vcc, s92, v115
	v_sub_f32_e32 v115, v121, v132
	v_exp_f32_e32 v112, v112
	v_sub_f32_e32 v114, v122, v132
	v_mul_f32_e32 v115, 0x3fb8aa3b, v115
	v_add_f32_e32 v107, v108, v107
	v_exp_f32_e32 v115, v115
	v_mul_f32_e32 v114, 0x3fb8aa3b, v114
	v_sub_f32_e32 v117, v125, v132
	v_add_f32_e32 v107, v109, v107
	v_exp_f32_e32 v114, v114
	v_sub_f32_e32 v116, v124, v132
	v_mul_f32_e32 v117, 0x3fb8aa3b, v117
	v_add_f32_e32 v107, v110, v107
	v_cndmask_b32_e32 v113, 0, v113, vcc
	v_cmp_lt_f32_e32 vcc, s92, v120
	v_exp_f32_e32 v117, v117
	v_mul_f32_e32 v116, 0x3fb8aa3b, v116
	v_sub_f32_e32 v119, v127, v132
	v_add_f32_e32 v107, v111, v107
	v_cndmask_b32_e32 v112, 0, v112, vcc
	v_cmp_lt_f32_e32 vcc, s92, v121
	v_exp_f32_e32 v116, v116
	v_sub_f32_e32 v118, v126, v132
	v_mul_f32_e32 v119, 0x3fb8aa3b, v119
	v_add_f32_e32 v107, v112, v107
	v_cndmask_b32_e32 v115, 0, v115, vcc
	v_cmp_lt_f32_e32 vcc, s92, v122
	v_exp_f32_e32 v119, v119
	v_mul_f32_e32 v118, 0x3fb8aa3b, v118
	v_sub_f32_e32 v121, v129, v132
	v_add_f32_e32 v107, v113, v107
	v_cndmask_b32_e32 v114, 0, v114, vcc
	v_cmp_lt_f32_e32 vcc, s92, v125
	v_exp_f32_e32 v118, v118
	v_sub_f32_e32 v120, v128, v132
	v_mul_f32_e32 v121, 0x3fb8aa3b, v121
	v_add_f32_e32 v107, v114, v107
	v_cndmask_b32_e32 v117, 0, v117, vcc
	v_cmp_lt_f32_e32 vcc, s92, v124
	v_exp_f32_e32 v121, v121
	v_mul_f32_e32 v120, 0x3fb8aa3b, v120
	v_sub_f32_e32 v123, v131, v132
	v_add_f32_e32 v107, v115, v107
	v_cndmask_b32_e32 v116, 0, v116, vcc
	v_cmp_lt_f32_e32 vcc, s92, v127
	v_exp_f32_e32 v120, v120
	v_sub_f32_e32 v122, v130, v132
	v_mul_f32_e32 v123, 0x3fb8aa3b, v123
	v_add_f32_e32 v107, v116, v107
	v_cndmask_b32_e32 v119, 0, v119, vcc
	v_cmp_lt_f32_e32 vcc, s92, v126
	v_exp_f32_e32 v123, v123
	v_mul_f32_e32 v122, 0x3fb8aa3b, v122
	v_sub_f32_e32 v125, v137, v132
	v_add_f32_e32 v107, v117, v107
	v_cndmask_b32_e32 v118, 0, v118, vcc
	v_cmp_lt_f32_e32 vcc, s92, v129
	v_exp_f32_e32 v122, v122
	v_sub_f32_e32 v124, v138, v132
	v_mul_f32_e32 v125, 0x3fb8aa3b, v125
	v_add_f32_e32 v107, v118, v107
	v_cndmask_b32_e32 v121, 0, v121, vcc
	v_cmp_lt_f32_e32 vcc, s92, v128
	v_exp_f32_e32 v125, v125
	v_mul_f32_e32 v124, 0x3fb8aa3b, v124
	v_sub_f32_e32 v127, v139, v132
	v_add_f32_e32 v107, v119, v107
	v_cndmask_b32_e32 v120, 0, v120, vcc
	v_cmp_lt_f32_e32 vcc, s92, v131
	v_exp_f32_e32 v124, v124
	v_sub_f32_e32 v126, v140, v132
	v_mul_f32_e32 v127, 0x3fb8aa3b, v127
	v_add_f32_e32 v107, v120, v107
	v_cndmask_b32_e32 v123, 0, v123, vcc
	v_cmp_lt_f32_e32 vcc, s92, v130
	v_exp_f32_e32 v127, v127
	v_mul_f32_e32 v126, 0x3fb8aa3b, v126
	v_sub_f32_e32 v129, v133, v132
	v_add_f32_e32 v107, v121, v107
	v_cndmask_b32_e32 v122, 0, v122, vcc
	v_cmp_lt_f32_e32 vcc, s92, v137
	v_exp_f32_e32 v126, v126
	v_sub_f32_e32 v128, v134, v132
	v_mul_f32_e32 v129, 0x3fb8aa3b, v129
	v_add_f32_e32 v107, v122, v107
	v_cndmask_b32_e32 v125, 0, v125, vcc
	v_cmp_lt_f32_e32 vcc, s92, v138
	v_exp_f32_e32 v129, v129
	v_mul_f32_e32 v128, 0x3fb8aa3b, v128
	v_sub_f32_e32 v131, v135, v132
	v_add_f32_e32 v107, v123, v107
	v_cndmask_b32_e32 v124, 0, v124, vcc
	v_cmp_lt_f32_e32 vcc, s92, v139
	v_exp_f32_e32 v128, v128
	v_sub_f32_e32 v130, v136, v132
	v_mul_f32_e32 v131, 0x3fb8aa3b, v131
	v_add_f32_e32 v107, v124, v107
	v_cndmask_b32_e32 v127, 0, v127, vcc
	v_cmp_lt_f32_e32 vcc, s92, v140
	v_exp_f32_e32 v131, v131
	v_mul_f32_e32 v130, 0x3fb8aa3b, v130
	v_add_f32_e32 v107, v125, v107
	v_cndmask_b32_e32 v126, 0, v126, vcc
	v_cmp_lt_f32_e32 vcc, s92, v133
	v_exp_f32_e32 v130, v130
	v_add_f32_e32 v107, v126, v107
	v_cndmask_b32_e32 v129, 0, v129, vcc
	v_cmp_lt_f32_e32 vcc, s92, v134
	v_add_f32_e32 v107, v127, v107
	s_nop 0
	v_cndmask_b32_e32 v128, 0, v128, vcc
	v_cmp_lt_f32_e32 vcc, s92, v135
	v_add_f32_e32 v107, v128, v107
	v_add_f32_e32 v107, v129, v107
	v_cndmask_b32_e32 v131, 0, v131, vcc
	v_cmp_lt_f32_e32 vcc, s92, v136
	s_nop 1
	v_cndmask_b32_e32 v130, 0, v130, vcc
	v_add_f32_e32 v107, v130, v107
	v_add_f32_e32 v107, v131, v107
	ds_bpermute_b32 v132, v193, v107
	s_waitcnt lgkmcnt(0)
	v_add_f32_e32 v107, v107, v132
	ds_bpermute_b32 v132, v194, v107
	s_waitcnt lgkmcnt(0)
	v_add_f32_e32 v107, v107, v132
	v_div_scale_f32 v132, vcc, v107, v107, 1.0
	v_rcp_f32_e32 v133, v132
	s_nop 0
	v_fma_f32 v134, -v132, v133, 1.0
	v_fmac_f32_e32 v133, v134, v133
	v_div_scale_f32 v134, vcc, 1.0, v107, 1.0
	v_mul_f32_e32 v135, v134, v133
	v_fma_f32 v136, -v132, v135, v134
	v_fmac_f32_e32 v135, v136, v133
	v_fma_f32 v132, -v132, v135, v134
	v_div_fmas_f32 v132, v132, v133, v135
	v_div_fixup_f32 v132, v132, v107, 1.0
	v_cmp_lt_f32_e32 vcc, 0, v107
	s_nop 1
	v_cndmask_b32_e32 v132, 0, v132, vcc
	v_pk_mul_f32 v[134:135], v[2:3], v[132:133] op_sel_hi:[1,0]
	v_pk_mul_f32 v[136:137], v[6:7], v[132:133] op_sel_hi:[1,0]
	ds_bpermute_b32 v2, v33, v135
	ds_bpermute_b32 v107, v33, v137
	v_pk_mul_f32 v[138:139], v[0:1], v[132:133] op_sel_hi:[1,0]
	v_pk_mul_f32 v[140:141], v[4:5], v[132:133] op_sel_hi:[1,0]
	v_mov_b32_e32 v4, v139
	s_waitcnt lgkmcnt(1)
	v_cndmask_b32_e64 v0, 0, v2, s[18:19]
	s_waitcnt lgkmcnt(0)
	v_cndmask_b32_e64 v1, v2, v107, s[18:19]
	v_mov_b32_e32 v2, v138
	v_mov_b32_e32 v3, v140
	v_mov_b32_e32 v5, v141
	v_pk_add_f32 v[2:3], v[2:3], v[4:5]
	v_mov_b32_e32 v4, v134
	v_mov_b32_e32 v5, v136
	v_mov_b32_e32 v6, v135
	v_mov_b32_e32 v7, v137
	v_pk_add_f32 v[4:5], v[4:5], v[6:7]
	v_pk_mul_f32 v[148:149], v[110:111], v[132:133] op_sel_hi:[1,0]
	v_pk_mul_f32 v[152:153], v[114:115], v[132:133] op_sel_hi:[1,0]
	v_pk_add_f32 v[2:3], v[2:3], v[4:5]
	ds_bpermute_b32 v6, v33, v149
	ds_bpermute_b32 v7, v33, v153
	v_pk_add_f32 v[0:1], v[0:1], v[2:3]
	v_pk_mul_f32 v[142:143], v[108:109], v[132:133] op_sel_hi:[1,0]
	v_pk_mul_f32 v[150:151], v[112:113], v[132:133] op_sel_hi:[1,0]
	v_pk_add_f32 v[14:15], v[14:15], v[0:1]
	v_mov_b32_e32 v0, v142
	v_mov_b32_e32 v1, v150
	v_mov_b32_e32 v2, v143
	v_mov_b32_e32 v3, v151
	v_pk_add_f32 v[0:1], v[0:1], v[2:3]
	v_mov_b32_e32 v2, v148
	v_mov_b32_e32 v3, v152
	v_mov_b32_e32 v4, v149
	v_mov_b32_e32 v5, v153
	v_pk_add_f32 v[2:3], v[2:3], v[4:5]
	v_pk_mul_f32 v[156:157], v[118:119], v[132:133] op_sel_hi:[1,0]
	v_pk_mul_f32 v[166:167], v[122:123], v[132:133] op_sel_hi:[1,0]
	v_pk_add_f32 v[0:1], v[0:1], v[2:3]
	s_waitcnt lgkmcnt(0)
	v_cndmask_b32_e64 v3, v6, v7, s[18:19]
	v_cndmask_b32_e64 v2, v107, v6, s[18:19]
	ds_bpermute_b32 v6, v33, v157
	ds_bpermute_b32 v107, v33, v167
	v_pk_add_f32 v[0:1], v[0:1], v[2:3]
	v_pk_mul_f32 v[154:155], v[116:117], v[132:133] op_sel_hi:[1,0]
	v_pk_mul_f32 v[158:159], v[120:121], v[132:133] op_sel_hi:[1,0]
	v_pk_add_f32 v[12:13], v[12:13], v[0:1]
	v_mov_b32_e32 v0, v154
	v_mov_b32_e32 v1, v158
	v_mov_b32_e32 v2, v155
	v_mov_b32_e32 v3, v159
	v_pk_add_f32 v[0:1], v[0:1], v[2:3]
	v_mov_b32_e32 v2, v156
	v_mov_b32_e32 v3, v166
	v_mov_b32_e32 v4, v157
	v_mov_b32_e32 v5, v167
	v_pk_add_f32 v[2:3], v[2:3], v[4:5]
	v_pk_mul_f32 v[4:5], v[128:129], v[132:133] op_sel_hi:[1,0]
	v_pk_add_f32 v[0:1], v[0:1], v[2:3]
	s_waitcnt lgkmcnt(0)
	v_cndmask_b32_e64 v3, v6, v107, s[18:19]
	v_cndmask_b32_e64 v2, v7, v6, s[18:19]
	v_pk_add_f32 v[0:1], v[0:1], v[2:3]
	v_pk_mul_f32 v[2:3], v[126:127], v[132:133] op_sel_hi:[1,0]
	v_pk_mul_f32 v[6:7], v[130:131], v[132:133] op_sel_hi:[1,0]
	ds_bpermute_b32 v114, v33, v3
	ds_bpermute_b32 v115, v33, v7
	v_pk_add_f32 v[10:11], v[10:11], v[0:1]
	v_pk_mul_f32 v[0:1], v[124:125], v[132:133] op_sel_hi:[1,0]
	v_mov_b32_e32 v109, v4
	v_mov_b32_e32 v108, v0
	v_mov_b32_e32 v110, v1
	v_mov_b32_e32 v111, v5
	v_pk_add_f32 v[108:109], v[108:109], v[110:111]
	v_mov_b32_e32 v110, v2
	v_mov_b32_e32 v111, v6
	v_mov_b32_e32 v112, v3
	v_mov_b32_e32 v113, v7
	v_pk_add_f32 v[110:111], v[110:111], v[112:113]
	s_nop 0
	v_pk_add_f32 v[108:109], v[108:109], v[110:111]
	s_waitcnt lgkmcnt(0)
	v_cndmask_b32_e64 v111, v114, v115, s[18:19]
	v_cndmask_b32_e64 v110, v107, v114, s[18:19]
	v_pk_add_f32 v[108:109], v[108:109], v[110:111]
	s_nop 0
	v_pk_add_f32 v[8:9], v[8:9], v[108:109]
	global_load_dwordx2 v[108:109], v[76:77], off
	global_load_dwordx2 v[110:111], v[76:77], off offset:32
	global_load_dwordx2 v[112:113], v[78:79], off
	global_load_dwordx2 v[114:115], v[78:79], off offset:32
	global_load_dwordx2 v[120:121], v[80:81], off
	global_load_dwordx2 v[122:123], v[80:81], off offset:32
	global_load_dwordx2 v[124:125], v[82:83], off
	global_load_dwordx2 v[126:127], v[82:83], off offset:32
	v_cvt_pk_bf16_f32 v116, v138, v139
	v_cvt_pk_bf16_f32 v117, v134, v135
	v_cvt_pk_bf16_f32 v118, v140, v141
	v_cvt_pk_bf16_f32 v119, v136, v137
	s_waitcnt vmcnt(0) lgkmcnt(0)
	s_nop 0
	v_mfma_f32_16x16x32_bf16 v[108:111], v[108:111], v[116:119], 0
	v_mfma_f32_16x16x32_bf16 v[112:115], v[112:115], v[116:119], 0
	v_mfma_f32_16x16x32_bf16 v[120:123], v[120:123], v[116:119], 0
	v_mfma_f32_16x16x32_bf16 v[116:119], v[124:127], v[116:119], 0
	global_load_dwordx2 v[128:129], v[76:77], off offset:64
	global_load_dwordx2 v[130:131], v[76:77], off offset:96
	v_cvt_pk_bf16_f32 v124, v142, v143
	v_cvt_pk_bf16_f32 v125, v148, v149
	v_cvt_pk_bf16_f32 v126, v150, v151
	v_cvt_pk_bf16_f32 v127, v152, v153
	s_waitcnt vmcnt(0) lgkmcnt(0)
	s_nop 0
	v_mfma_f32_16x16x32_bf16 v[108:111], v[128:131], v[124:127], v[108:111]
	global_load_dwordx2 v[128:129], v[84:85], off
	global_load_dwordx2 v[130:131], v[84:85], off offset:32
	s_waitcnt vmcnt(0) lgkmcnt(0)
	v_mfma_f32_16x16x32_bf16 v[112:115], v[128:131], v[124:127], v[112:115]
	global_load_dwordx2 v[128:129], v[86:87], off
	global_load_dwordx2 v[130:131], v[86:87], off offset:32
	s_waitcnt vmcnt(0) lgkmcnt(0)
	v_mfma_f32_16x16x32_bf16 v[120:123], v[128:131], v[124:127], v[120:123]
	global_load_dwordx2 v[128:129], v[88:89], off
	global_load_dwordx2 v[130:131], v[88:89], off offset:32
	s_waitcnt vmcnt(0) lgkmcnt(0)
	v_mfma_f32_16x16x32_bf16 v[116:119], v[128:131], v[124:127], v[116:119]
	global_load_dwordx2 v[128:129], v[76:77], off offset:128
	global_load_dwordx2 v[130:131], v[76:77], off offset:160
	v_cvt_pk_bf16_f32 v124, v154, v155
	v_cvt_pk_bf16_f32 v125, v156, v157
	v_cvt_pk_bf16_f32 v126, v158, v159
	v_cvt_pk_bf16_f32 v127, v166, v167
	s_waitcnt vmcnt(0) lgkmcnt(0)
	s_nop 0
	v_mfma_f32_16x16x32_bf16 v[108:111], v[128:131], v[124:127], v[108:111]
	global_load_dwordx2 v[128:129], v[90:91], off
	global_load_dwordx2 v[130:131], v[90:91], off offset:32
	s_waitcnt vmcnt(0) lgkmcnt(0)
	v_mfma_f32_16x16x32_bf16 v[112:115], v[128:131], v[124:127], v[112:115]
	global_load_dwordx2 v[128:129], v[92:93], off
	global_load_dwordx2 v[130:131], v[92:93], off offset:32
	s_waitcnt vmcnt(0) lgkmcnt(0)
	v_mfma_f32_16x16x32_bf16 v[120:123], v[128:131], v[124:127], v[120:123]
	global_load_dwordx2 v[128:129], v[94:95], off
	global_load_dwordx2 v[130:131], v[94:95], off offset:32
	s_waitcnt vmcnt(0) lgkmcnt(0)
	v_mfma_f32_16x16x32_bf16 v[116:119], v[128:131], v[124:127], v[116:119]
	v_cvt_pk_bf16_f32 v0, v0, v1
	v_cvt_pk_bf16_f32 v1, v2, v3
	v_cvt_pk_bf16_f32 v2, v4, v5
	v_cvt_pk_bf16_f32 v3, v6, v7
	global_load_dwordx2 v[4:5], v[76:77], off offset:192
	global_load_dwordx2 v[6:7], v[76:77], off offset:224
	s_waitcnt vmcnt(0) lgkmcnt(0)
	v_mfma_f32_16x16x32_bf16 v[4:7], v[4:7], v[0:3], v[108:111]
	s_nop 2
	global_load_dwordx2 v[108:109], v[96:97], off
	global_load_dwordx2 v[110:111], v[96:97], off offset:32
	s_waitcnt vmcnt(0) lgkmcnt(0)
	v_mfma_f32_16x16x32_bf16 v[108:111], v[108:111], v[0:3], v[112:115]
	s_nop 2
	global_load_dwordx2 v[112:113], v[98:99], off
	global_load_dwordx2 v[114:115], v[98:99], off offset:32
	s_waitcnt vmcnt(0) lgkmcnt(0)
	v_mfma_f32_16x16x32_bf16 v[112:115], v[112:115], v[0:3], v[120:123]
	s_nop 2
	global_load_dwordx2 v[120:121], v[100:101], off
	global_load_dwordx2 v[122:123], v[100:101], off offset:32
	s_waitcnt vmcnt(0) lgkmcnt(0)
	v_mfma_f32_16x16x32_bf16 v[0:3], v[120:123], v[0:3], v[116:119]
	s_nop 2
	v_lshl_add_u64 v[116:117], s[86:87], 0, v[102:103]
	global_load_dword v107, v[116:117], off
	v_add_u32_e32 v116, s0, v192
	s_waitcnt vmcnt(0) lgkmcnt(0)
	v_mul_f32_e32 v107, 0xbfb8aa3b, v107
	v_exp_f32_e32 v107, v107
	s_nop 0
	v_add_f32_e32 v107, 1.0, v107
	v_rcp_f32_e32 v107, v107
	s_nop 0
	v_mul_f32_e32 v4, v4, v107
	v_mul_f32_e32 v5, v5, v107
	ds_write2st64_b32 v116, v4, v5 offset1:1
	v_mul_f32_e32 v4, v6, v107
	v_mul_f32_e32 v5, v7, v107
	ds_write2st64_b32 v116, v4, v5 offset0:2 offset1:3
	v_mul_f32_e32 v4, v108, v107
	v_mul_f32_e32 v5, v109, v107
	ds_write2st64_b32 v116, v4, v5 offset0:4 offset1:5
	v_mul_f32_e32 v4, v110, v107
	v_mul_f32_e32 v5, v111, v107
	ds_write2st64_b32 v116, v4, v5 offset0:6 offset1:7
	v_mul_f32_e32 v4, v112, v107
	v_mul_f32_e32 v5, v113, v107
	v_mul_f32_e32 v0, v0, v107
	v_mul_f32_e32 v1, v1, v107
	ds_write2st64_b32 v116, v4, v5 offset0:8 offset1:9
	v_mul_f32_e32 v4, v114, v107
	v_mul_f32_e32 v5, v115, v107
	ds_write2st64_b32 v116, v0, v1 offset0:12 offset1:13
	v_mul_f32_e32 v0, v2, v107
	v_mul_f32_e32 v1, v3, v107
	ds_write2st64_b32 v116, v4, v5 offset0:10 offset1:11
	ds_write2st64_b32 v116, v0, v1 offset0:14 offset1:15
	s_addk_i32 s0, 0x1000
	s_add_i32 s82, s82, 1
	v_lshl_add_u64 v[102:103], v[102:103], 0, 12
	s_cmpk_eq_i32 s0, 0x4000
	v_lshl_add_u64 v[104:105], v[104:105], 0, s[96:97]
	s_cbranch_scc0 .LBB0_188
	s_or_b32 s0, s95, s81
	v_or_b32_e32 v0, s0, v190
	v_ashrrev_i32_e32 v1, 31, v0
	v_lshlrev_b64 v[2:3], 7, v[0:1]
	v_lshl_add_u64 v[2:3], s[86:87], 0, v[2:3]
	s_mul_i32 s82, s2, 48
	v_lshl_add_u64 v[2:3], v[2:3], 0, s[82:83]
	s_mov_b64 s[0:1], 0x2f200020
	v_lshl_add_u64 v[148:149], v[2:3], 0, s[0:1]
	s_lshl_b32 s0, s2, 2
	s_or_b32 s1, s0, 1
	v_cvt_f32_ubyte0_e32 v2, s1
	v_cmp_lt_f32_e32 vcc, s72, v2
	s_or_b32 s1, s0, 2
	v_cvt_f32_ubyte0_e32 v3, s1
	v_cndmask_b32_e32 v6, 0, v220, vcc
	v_sub_f32_e32 v2, v6, v2
	v_exp_f32_e32 v2, v2
	s_or_b32 s1, s0, 3
	s_add_i32 s0, s0, 4
	v_cvt_f32_ubyte0_e32 v4, s1
	v_cvt_f32_ubyte0_e32 v5, s0
	s_and_b64 s[0:1], vcc, exec
	s_cselect_b32 s0, 0xffffffc0, 0
	v_cmp_lt_f32_e32 vcc, s72, v3
	v_ldexp_f32 v34, v2, s0
	s_and_b64 s[0:1], vcc, exec
	v_cndmask_b32_e32 v2, 0, v220, vcc
	v_sub_f32_e32 v2, v2, v3
	v_exp_f32_e32 v2, v2
	s_cselect_b32 s0, 0xffffffc0, 0
	v_cmp_lt_f32_e32 vcc, s72, v4
	v_and_or_b32 v17, v211, 64, v190
	v_ldexp_f32 v35, v2, s0
	v_cndmask_b32_e32 v2, 0, v220, vcc
	v_sub_f32_e32 v2, v2, v4
	v_exp_f32_e32 v2, v2
	s_and_b64 s[0:1], vcc, exec
	s_cselect_b32 s0, 0xffffffc0, 0
	v_cmp_lt_f32_e32 vcc, s72, v5
	v_ldexp_f32 v36, v2, s0
	s_and_b64 s[0:1], vcc, exec
	v_cndmask_b32_e32 v2, 0, v220, vcc
	v_sub_f32_e32 v2, v2, v5
	v_exp_f32_e32 v2, v2
	s_cselect_b32 s0, 0xffffffc0, 0
	s_lshr_b32 s20, s81, 6
	s_add_i32 s22, s20, -1
	v_cmp_eq_u32_e64 s[4:5], s20, v32
	v_cmp_eq_u32_e64 s[6:7], s22, v32
	v_ldexp_f32 v37, v2, s0
	v_cmp_gt_u32_e64 s[0:1], 16, v106
	s_or_b64 s[4:5], s[4:5], s[6:7]
	s_or_b64 s[0:1], s[4:5], s[0:1]
	v_cmp_lt_i32_e32 vcc, s20, v32
	v_cndmask_b32_e64 v2, v14, v222, s[0:1]
	v_lshlrev_b32_e32 v17, 2, v17
	v_cndmask_b32_e32 v14, v2, v221, vcc
	v_add_u32_e32 v2, 4, v32
	v_cmp_eq_u32_e64 s[0:1], 0, v2
	v_cmp_eq_u32_e64 s[6:7], s20, v2
	s_or_b64 s[6:7], s[0:1], s[6:7]
	v_cmp_eq_u32_e64 s[0:1], s22, v2
	s_or_b64 s[0:1], s[6:7], s[0:1]
	v_cmp_lt_i32_e64 s[4:5], s20, v2
	v_cndmask_b32_e64 v3, v15, v222, s[0:1]
	ds_bpermute_b32 v18, v17, v14
	v_cndmask_b32_e64 v15, v3, v221, s[4:5]
	v_add_u32_e32 v3, 8, v32
	v_cmp_eq_u32_e64 s[0:1], 0, v3
	v_cmp_eq_u32_e64 s[8:9], s20, v3
	s_or_b64 s[8:9], s[0:1], s[8:9]
	v_cmp_eq_u32_e64 s[0:1], s22, v3
	s_or_b64 s[0:1], s[8:9], s[0:1]
	v_cmp_lt_i32_e64 s[6:7], s20, v3
	v_cndmask_b32_e64 v4, v12, v222, s[0:1]
	v_cmp_lt_i32_e64 s[24:25], -8, v32
	v_cndmask_b32_e64 v12, v4, v221, s[6:7]
	v_add_u32_e32 v4, 12, v32
	v_cmp_eq_u32_e64 s[0:1], 0, v4
	v_cmp_eq_u32_e64 s[10:11], s20, v4
	s_or_b64 s[10:11], s[0:1], s[10:11]
	v_cmp_eq_u32_e64 s[0:1], s22, v4
	s_or_b64 s[0:1], s[10:11], s[0:1]
	v_cmp_lt_i32_e64 s[8:9], s20, v4
	v_cndmask_b32_e64 v5, v13, v222, s[0:1]
	v_cmp_lt_i32_e64 s[28:29], -12, v32
	v_cndmask_b32_e64 v13, v5, v221, s[8:9]
	v_add_u32_e32 v5, 16, v32
	v_cmp_eq_u32_e64 s[0:1], 0, v5
	v_cmp_eq_u32_e64 s[12:13], s20, v5
	s_or_b64 s[12:13], s[0:1], s[12:13]
	v_cmp_eq_u32_e64 s[0:1], s22, v5
	s_or_b64 s[0:1], s[12:13], s[0:1]
	v_cmp_lt_i32_e64 s[10:11], s20, v5
	v_cndmask_b32_e64 v6, v10, v222, s[0:1]
	v_cmp_lt_i32_e64 s[34:35], -16, v32
	v_cndmask_b32_e64 v10, v6, v221, s[10:11]
	v_add_u32_e32 v6, 20, v32
	v_cmp_eq_u32_e64 s[0:1], 0, v6
	v_cmp_eq_u32_e64 s[14:15], s20, v6
	s_or_b64 s[14:15], s[0:1], s[14:15]
	v_cmp_eq_u32_e64 s[0:1], s22, v6
	s_or_b64 s[0:1], s[14:15], s[0:1]
	v_cmp_lt_i32_e64 s[12:13], s20, v6
	v_cndmask_b32_e64 v7, v11, v222, s[0:1]
	s_movk_i32 s30, 0xffe8
	v_cndmask_b32_e64 v11, v7, v221, s[12:13]
	v_add_u32_e32 v7, 24, v32
	v_cmp_eq_u32_e64 s[0:1], 0, v7
	v_cmp_eq_u32_e64 s[16:17], s20, v7
	s_or_b64 s[16:17], s[0:1], s[16:17]
	v_cmp_eq_u32_e64 s[0:1], s22, v7
	s_or_b64 s[0:1], s[16:17], s[0:1]
	v_cmp_lt_i32_e64 s[14:15], s20, v7
	v_cndmask_b32_e64 v8, v8, v222, s[0:1]
	s_waitcnt lgkmcnt(0)
	v_cmp_eq_f32_e64 s[26:27], v11, v18
	v_cndmask_b32_e64 v16, v8, v221, s[14:15]
	v_add_u32_e32 v8, 28, v32
	v_cmp_lt_i32_e64 s[16:17], s20, v8
	v_cmp_eq_u32_e64 s[0:1], 0, v8
	v_cmp_eq_u32_e64 s[20:21], s20, v8
	s_or_b64 s[20:21], s[0:1], s[20:21]
	v_cmp_eq_u32_e64 s[0:1], s22, v8
	s_or_b64 s[0:1], s[20:21], s[0:1]
	v_cmp_eq_f32_e64 s[20:21], v14, v18
	v_cndmask_b32_e64 v9, v9, v222, s[0:1]
	v_cmp_lt_f32_e64 s[0:1], v14, v18
	s_and_b64 s[20:21], s[18:19], s[20:21]
	s_or_b64 s[0:1], s[0:1], s[20:21]
	v_cmp_eq_f32_e64 s[22:23], v15, v18
	v_cmp_lt_i32_e64 s[20:21], -4, v32
	v_cndmask_b32_e64 v19, 0, 1, s[0:1]
	v_cmp_lt_f32_e64 s[0:1], v15, v18
	s_and_b64 s[22:23], s[20:21], s[22:23]
	s_or_b64 s[0:1], s[0:1], s[22:23]
	v_cmp_eq_f32_e64 s[22:23], v12, v18
	v_cndmask_b32_e64 v20, 0, 1, s[0:1]
	v_cmp_lt_f32_e64 s[0:1], v12, v18
	s_and_b64 s[22:23], s[24:25], s[22:23]
	s_or_b64 s[0:1], s[0:1], s[22:23]
	v_cmp_eq_f32_e64 s[22:23], v13, v18
	v_cndmask_b32_e64 v21, 0, 1, s[0:1]
	v_cmp_lt_f32_e64 s[0:1], v13, v18
	s_and_b64 s[22:23], s[28:29], s[22:23]
	s_or_b64 s[0:1], s[0:1], s[22:23]
	v_cmp_eq_f32_e64 s[22:23], v10, v18
	v_cndmask_b32_e64 v22, 0, 1, s[0:1]
	v_cmp_lt_f32_e64 s[0:1], v10, v18
	s_and_b64 s[22:23], s[34:35], s[22:23]
	s_or_b64 s[0:1], s[0:1], s[22:23]
	v_cndmask_b32_e64 v23, 0, 1, s[0:1]
	s_movk_i32 s0, 0xffec
	v_cmp_lt_i32_e64 s[0:1], s0, v32
	v_cmp_lt_f32_e64 s[22:23], v11, v18
	s_and_b64 s[26:27], s[0:1], s[26:27]
	s_or_b64 s[22:23], s[22:23], s[26:27]
	v_cmp_eq_f32_e64 s[26:27], v16, v18
	v_cmp_lt_i32_e64 s[30:31], s30, v32
	ds_bpermute_b32 v26, v17, v15
	v_cndmask_b32_e64 v9, v9, v221, s[16:17]
	v_cndmask_b32_e64 v24, 0, 1, s[22:23]
	v_cmp_lt_f32_e64 s[22:23], v16, v18
	s_and_b64 s[26:27], s[30:31], s[26:27]
	s_movk_i32 s36, 0xffe4
	s_or_b64 s[22:23], s[22:23], s[26:27]
	v_cmp_eq_f32_e64 s[26:27], v9, v18
	v_cmp_lt_i32_e64 s[36:37], s36, v32
	v_cndmask_b32_e64 v25, 0, 1, s[22:23]
	v_cmp_lt_f32_e64 s[22:23], v9, v18
	s_and_b64 s[26:27], s[36:37], s[26:27]
	s_or_b64 s[22:23], s[22:23], s[26:27]
	v_cndmask_b32_e64 v18, 0, 1, s[22:23]
	s_waitcnt lgkmcnt(0)
	v_cmp_eq_f32_e64 s[36:37], v14, v26
	v_cmp_lt_i32_e64 s[22:23], 4, v32
	v_cmp_lt_f32_e64 s[26:27], v14, v26
	s_and_b64 s[36:37], s[22:23], s[36:37]
	s_or_b64 s[26:27], s[26:27], s[36:37]
	v_addc_co_u32_e64 v19, s[26:27], 0, v19, s[26:27]
	v_cmp_eq_f32_e64 s[36:37], v15, v26
	v_cmp_lt_f32_e64 s[26:27], v15, v26
	s_and_b64 s[36:37], s[18:19], s[36:37]
	s_or_b64 s[26:27], s[26:27], s[36:37]
	v_cmp_eq_f32_e64 s[36:37], v12, v26
	v_cndmask_b32_e64 v27, 0, 1, s[26:27]
	v_cmp_lt_f32_e64 s[26:27], v12, v26
	s_and_b64 s[36:37], s[20:21], s[36:37]
	s_or_b64 s[26:27], s[26:27], s[36:37]
	v_addc_co_u32_e64 v21, s[26:27], 0, v21, s[26:27]
	v_cmp_eq_f32_e64 s[36:37], v13, v26
	v_cmp_lt_f32_e64 s[26:27], v13, v26
	s_and_b64 s[36:37], s[24:25], s[36:37]
	s_or_b64 s[26:27], s[26:27], s[36:37]
	v_cmp_eq_f32_e64 s[36:37], v10, v26
	v_add_u32_e32 v20, v27, v20
	v_cndmask_b32_e64 v27, 0, 1, s[26:27]
	v_cmp_lt_f32_e64 s[26:27], v10, v26
	s_and_b64 s[36:37], s[28:29], s[36:37]
	s_or_b64 s[26:27], s[26:27], s[36:37]
	v_addc_co_u32_e64 v23, s[26:27], 0, v23, s[26:27]
	v_cmp_eq_f32_e64 s[36:37], v11, v26
	v_cmp_lt_f32_e64 s[26:27], v11, v26
	s_and_b64 s[36:37], s[34:35], s[36:37]
	s_or_b64 s[26:27], s[26:27], s[36:37]
	v_cmp_eq_f32_e64 s[36:37], v16, v26
	v_cndmask_b32_e64 v28, 0, 1, s[26:27]
	v_cmp_lt_f32_e64 s[26:27], v16, v26
	s_and_b64 s[36:37], s[0:1], s[36:37]
	ds_bpermute_b32 v29, v17, v12
	s_or_b64 s[26:27], s[26:27], s[36:37]
	v_addc_co_u32_e64 v25, s[26:27], 0, v25, s[26:27]
	v_cmp_eq_f32_e64 s[36:37], v9, v26
	v_cmp_lt_f32_e64 s[26:27], v9, v26
	s_and_b64 s[30:31], s[30:31], s[36:37]
	s_or_b64 s[26:27], s[26:27], s[30:31]
	v_cndmask_b32_e64 v26, 0, 1, s[26:27]
	s_waitcnt lgkmcnt(0)
	v_cmp_eq_f32_e64 s[36:37], v14, v29
	v_cmp_lt_i32_e64 s[26:27], 8, v32
	v_cmp_lt_f32_e64 s[30:31], v14, v29
	s_and_b64 s[36:37], s[26:27], s[36:37]
	s_or_b64 s[30:31], s[30:31], s[36:37]
	v_cmp_eq_f32_e64 s[36:37], v15, v29
	v_cndmask_b32_e64 v30, 0, 1, s[30:31]
	v_cmp_lt_f32_e64 s[30:31], v15, v29
	s_and_b64 s[36:37], s[22:23], s[36:37]
	s_or_b64 s[30:31], s[30:31], s[36:37]
	v_cmp_eq_f32_e64 s[36:37], v12, v29
	v_cndmask_b32_e64 v31, 0, 1, s[30:31]
	v_cmp_lt_f32_e64 s[30:31], v12, v29
	s_and_b64 s[36:37], s[18:19], s[36:37]
	s_or_b64 s[30:31], s[30:31], s[36:37]
	v_cmp_eq_f32_e64 s[36:37], v13, v29
	v_cndmask_b32_e64 v38, 0, 1, s[30:31]
	v_cmp_lt_f32_e64 s[30:31], v13, v29
	s_and_b64 s[36:37], s[20:21], s[36:37]
	s_or_b64 s[30:31], s[30:31], s[36:37]
	v_addc_co_u32_e64 v22, s[30:31], v27, v22, s[30:31]
	v_cmp_eq_f32_e64 s[36:37], v10, v29
	v_cmp_lt_f32_e64 s[30:31], v10, v29
	s_and_b64 s[36:37], s[24:25], s[36:37]
	s_or_b64 s[30:31], s[30:31], s[36:37]
	v_cmp_eq_f32_e64 s[36:37], v11, v29
	v_cndmask_b32_e64 v27, 0, 1, s[30:31]
	v_cmp_lt_f32_e64 s[30:31], v11, v29
	s_and_b64 s[36:37], s[28:29], s[36:37]
	s_or_b64 s[30:31], s[30:31], s[36:37]
	v_addc_co_u32_e64 v24, s[30:31], v28, v24, s[30:31]
	v_cmp_eq_f32_e64 s[36:37], v16, v29
	v_cmp_lt_f32_e64 s[30:31], v16, v29
	s_and_b64 s[36:37], s[34:35], s[36:37]
	s_or_b64 s[30:31], s[30:31], s[36:37]
	v_cmp_eq_f32_e64 s[36:37], v9, v29
	v_cndmask_b32_e64 v28, 0, 1, s[30:31]
	v_cmp_lt_f32_e64 s[30:31], v9, v29
	s_and_b64 s[0:1], s[0:1], s[36:37]
	s_or_b64 s[0:1], s[30:31], s[0:1]
	v_addc_co_u32_e64 v18, s[0:1], v26, v18, s[0:1]
	ds_bpermute_b32 v26, v17, v13
	v_cmp_lt_i32_e64 s[30:31], 12, v32
	v_lshlrev_b32_e64 v2, v2, 1
	v_lshlrev_b32_e64 v3, v3, 1
	v_lshlrev_b32_e64 v4, v4, 1
	s_waitcnt lgkmcnt(0)
	v_cmp_eq_f32_e64 s[36:37], v14, v26
	v_cmp_lt_f32_e64 s[0:1], v14, v26
	s_and_b64 s[36:37], s[30:31], s[36:37]
	s_or_b64 s[0:1], s[0:1], s[36:37]
	v_addc_co_u32_e64 v19, s[0:1], v19, v30, s[0:1]
	v_cmp_eq_f32_e64 s[36:37], v15, v26
	v_cmp_lt_f32_e64 s[0:1], v15, v26
	s_and_b64 s[36:37], s[26:27], s[36:37]
	s_or_b64 s[0:1], s[0:1], s[36:37]
	v_addc_co_u32_e64 v20, s[0:1], v20, v31, s[0:1]
	v_cmp_eq_f32_e64 s[36:37], v12, v26
	v_cmp_lt_f32_e64 s[0:1], v12, v26
	s_and_b64 s[36:37], s[22:23], s[36:37]
	s_or_b64 s[0:1], s[0:1], s[36:37]
	v_addc_co_u32_e64 v21, s[0:1], v21, v38, s[0:1]
	v_cmp_eq_f32_e64 s[36:37], v13, v26
	v_cmp_lt_f32_e64 s[0:1], v13, v26
	s_and_b64 s[36:37], s[18:19], s[36:37]
	s_or_b64 s[0:1], s[0:1], s[36:37]
	v_cmp_eq_f32_e64 s[36:37], v10, v26
	v_cndmask_b32_e64 v29, 0, 1, s[0:1]
	v_cmp_lt_f32_e64 s[0:1], v10, v26
	s_and_b64 s[36:37], s[20:21], s[36:37]
	s_or_b64 s[0:1], s[0:1], s[36:37]
	v_addc_co_u32_e64 v23, s[0:1], v23, v27, s[0:1]
	v_cmp_eq_f32_e64 s[36:37], v11, v26
	v_cmp_lt_f32_e64 s[0:1], v11, v26
	s_and_b64 s[36:37], s[24:25], s[36:37]
	s_or_b64 s[0:1], s[0:1], s[36:37]
	v_cmp_eq_f32_e64 s[36:37], v16, v26
	v_cndmask_b32_e64 v27, 0, 1, s[0:1]
	v_cmp_lt_f32_e64 s[0:1], v16, v26
	s_and_b64 s[36:37], s[28:29], s[36:37]
	s_or_b64 s[0:1], s[0:1], s[36:37]
	v_addc_co_u32_e64 v25, s[0:1], v25, v28, s[0:1]
	ds_bpermute_b32 v28, v17, v10
	v_cmp_eq_f32_e64 s[36:37], v9, v26
	v_cmp_lt_f32_e64 s[0:1], v9, v26
	s_and_b64 s[34:35], s[34:35], s[36:37]
	s_or_b64 s[0:1], s[0:1], s[34:35]
	s_waitcnt lgkmcnt(0)
	v_cmp_eq_f32_e64 s[36:37], v14, v28
	v_cmp_lt_i32_e64 s[34:35], 16, v32
	v_cndmask_b32_e64 v26, 0, 1, s[0:1]
	v_cmp_lt_f32_e64 s[0:1], v14, v28
	s_and_b64 s[36:37], s[34:35], s[36:37]
	s_or_b64 s[0:1], s[0:1], s[36:37]
	v_cmp_eq_f32_e64 s[36:37], v15, v28
	v_add_u32_e32 v22, v22, v29
	v_cndmask_b32_e64 v29, 0, 1, s[0:1]
	v_cmp_lt_f32_e64 s[0:1], v15, v28
	s_and_b64 s[36:37], s[30:31], s[36:37]
	s_or_b64 s[0:1], s[0:1], s[36:37]
	v_cmp_eq_f32_e64 s[36:37], v12, v28
	v_cndmask_b32_e64 v30, 0, 1, s[0:1]
	v_cmp_lt_f32_e64 s[0:1], v12, v28
	s_and_b64 s[36:37], s[26:27], s[36:37]
	s_or_b64 s[0:1], s[0:1], s[36:37]
	v_cmp_eq_f32_e64 s[36:37], v13, v28
	v_cndmask_b32_e64 v31, 0, 1, s[0:1]
	v_cmp_lt_f32_e64 s[0:1], v13, v28
	s_and_b64 s[36:37], s[22:23], s[36:37]
	s_or_b64 s[0:1], s[0:1], s[36:37]
	v_cmp_eq_f32_e64 s[36:37], v10, v28
	v_cndmask_b32_e64 v38, 0, 1, s[0:1]
	v_cmp_lt_f32_e64 s[0:1], v10, v28
	s_and_b64 s[36:37], s[18:19], s[36:37]
	s_or_b64 s[0:1], s[0:1], s[36:37]
	v_cmp_eq_f32_e64 s[36:37], v11, v28
	v_cndmask_b32_e64 v39, 0, 1, s[0:1]
	v_cmp_lt_f32_e64 s[0:1], v11, v28
	s_and_b64 s[36:37], s[20:21], s[36:37]
	s_or_b64 s[0:1], s[0:1], s[36:37]
	v_addc_co_u32_e64 v24, s[0:1], v24, v27, s[0:1]
	v_cmp_eq_f32_e64 s[36:37], v16, v28
	v_cmp_lt_f32_e64 s[0:1], v16, v28
	s_and_b64 s[36:37], s[24:25], s[36:37]
	s_or_b64 s[0:1], s[0:1], s[36:37]
	v_cmp_eq_f32_e64 s[36:37], v9, v28
	v_cndmask_b32_e64 v27, 0, 1, s[0:1]
	v_cmp_lt_f32_e64 s[0:1], v9, v28
	s_and_b64 s[28:29], s[28:29], s[36:37]
	s_or_b64 s[0:1], s[0:1], s[28:29]
	v_addc_co_u32_e64 v18, s[0:1], v18, v26, s[0:1]
	ds_bpermute_b32 v26, v17, v11
	v_cmp_lt_i32_e64 s[0:1], 20, v32
	v_lshlrev_b64 v[0:1], 10, v[0:1]
	s_mov_b32 s38, 1
	v_lshl_add_u64 v[0:1], s[86:87], 0, v[0:1]
	s_waitcnt lgkmcnt(0)
	v_cmp_eq_f32_e64 s[36:37], v14, v26
	v_cmp_lt_f32_e64 s[28:29], v14, v26
	s_and_b64 s[36:37], s[0:1], s[36:37]
	s_or_b64 s[28:29], s[28:29], s[36:37]
	v_addc_co_u32_e64 v19, s[28:29], v19, v29, s[28:29]
	v_cmp_eq_f32_e64 s[36:37], v15, v26
	v_cmp_lt_f32_e64 s[28:29], v15, v26
	s_and_b64 s[36:37], s[34:35], s[36:37]
	s_or_b64 s[28:29], s[28:29], s[36:37]
	v_addc_co_u32_e64 v20, s[28:29], v20, v30, s[28:29]
	v_cmp_eq_f32_e64 s[36:37], v12, v26
	v_cmp_lt_f32_e64 s[28:29], v12, v26
	s_and_b64 s[36:37], s[30:31], s[36:37]
	s_or_b64 s[28:29], s[28:29], s[36:37]
	v_addc_co_u32_e64 v21, s[28:29], v21, v31, s[28:29]
	v_cmp_eq_f32_e64 s[36:37], v13, v26
	v_cmp_lt_f32_e64 s[28:29], v13, v26
	s_and_b64 s[36:37], s[26:27], s[36:37]
	s_or_b64 s[28:29], s[28:29], s[36:37]
	v_addc_co_u32_e64 v22, s[28:29], v22, v38, s[28:29]
	v_cmp_eq_f32_e64 s[36:37], v10, v26
	v_cmp_lt_f32_e64 s[28:29], v10, v26
	s_and_b64 s[36:37], s[22:23], s[36:37]
	s_or_b64 s[28:29], s[28:29], s[36:37]
	v_addc_co_u32_e64 v23, s[28:29], v23, v39, s[28:29]
	v_cmp_eq_f32_e64 s[36:37], v11, v26
	v_cmp_lt_f32_e64 s[28:29], v11, v26
	s_and_b64 s[36:37], s[18:19], s[36:37]
	s_or_b64 s[28:29], s[28:29], s[36:37]
	v_cmp_eq_f32_e64 s[36:37], v16, v26
	v_cndmask_b32_e64 v28, 0, 1, s[28:29]
	v_cmp_lt_f32_e64 s[28:29], v16, v26
	s_and_b64 s[36:37], s[20:21], s[36:37]
	s_or_b64 s[28:29], s[28:29], s[36:37]
	v_addc_co_u32_e64 v25, s[28:29], v25, v27, s[28:29]
	ds_bpermute_b32 v27, v17, v16
	v_cmp_eq_f32_e64 s[36:37], v9, v26
	v_cmp_lt_f32_e64 s[28:29], v9, v26
	s_and_b64 s[24:25], s[24:25], s[36:37]
	s_or_b64 s[24:25], s[28:29], s[24:25]
	s_waitcnt lgkmcnt(0)
	v_cmp_eq_f32_e64 s[28:29], v14, v27
	v_cmp_lt_i32_e64 s[36:37], 24, v32
	v_cndmask_b32_e64 v26, 0, 1, s[24:25]
	v_cmp_lt_f32_e64 s[24:25], v14, v27
	s_and_b64 s[28:29], s[36:37], s[28:29]
	s_or_b64 s[24:25], s[24:25], s[28:29]
	v_cmp_eq_f32_e64 s[28:29], v15, v27
	v_add_u32_e32 v24, v24, v28
	v_cndmask_b32_e64 v28, 0, 1, s[24:25]
	v_cmp_lt_f32_e64 s[24:25], v15, v27
	s_and_b64 s[28:29], s[0:1], s[28:29]
	s_or_b64 s[24:25], s[24:25], s[28:29]
	v_cmp_eq_f32_e64 s[28:29], v12, v27
	v_cndmask_b32_e64 v29, 0, 1, s[24:25]
	v_cmp_lt_f32_e64 s[24:25], v12, v27
	s_and_b64 s[28:29], s[34:35], s[28:29]
	s_or_b64 s[24:25], s[24:25], s[28:29]
	v_cmp_eq_f32_e64 s[28:29], v13, v27
	v_cndmask_b32_e64 v30, 0, 1, s[24:25]
	v_cmp_lt_f32_e64 s[24:25], v13, v27
	s_and_b64 s[28:29], s[30:31], s[28:29]
	s_or_b64 s[24:25], s[24:25], s[28:29]
	v_cmp_eq_f32_e64 s[28:29], v10, v27
	v_cndmask_b32_e64 v31, 0, 1, s[24:25]
	v_cmp_lt_f32_e64 s[24:25], v10, v27
	s_and_b64 s[28:29], s[26:27], s[28:29]
	s_or_b64 s[24:25], s[24:25], s[28:29]
	v_cmp_eq_f32_e64 s[28:29], v11, v27
	v_cndmask_b32_e64 v38, 0, 1, s[24:25]
	v_cmp_lt_f32_e64 s[24:25], v11, v27
	s_and_b64 s[28:29], s[22:23], s[28:29]
	s_or_b64 s[24:25], s[24:25], s[28:29]
	v_cmp_eq_f32_e64 s[28:29], v16, v27
	v_cndmask_b32_e64 v39, 0, 1, s[24:25]
	v_cmp_lt_f32_e64 s[24:25], v16, v27
	s_and_b64 s[28:29], s[18:19], s[28:29]
	s_or_b64 s[24:25], s[24:25], s[28:29]
	v_cmp_eq_f32_e64 s[28:29], v9, v27
	v_cndmask_b32_e64 v40, 0, 1, s[24:25]
	v_cmp_lt_f32_e64 s[24:25], v9, v27
	s_and_b64 s[20:21], s[20:21], s[28:29]
	s_or_b64 s[20:21], s[24:25], s[20:21]
	v_addc_co_u32_e64 v18, s[20:21], v18, v26, s[20:21]
	ds_bpermute_b32 v26, v17, v9
	v_cmp_lt_i32_e64 s[28:29], 28, v32
	v_ashrrev_i32_e32 v33, 31, v32
	s_waitcnt lgkmcnt(0)
	v_cmp_eq_f32_e64 s[24:25], v14, v26
	v_cmp_lt_f32_e64 s[20:21], v14, v26
	s_and_b64 s[24:25], s[28:29], s[24:25]
	s_or_b64 s[20:21], s[20:21], s[24:25]
	v_addc_co_u32_e64 v19, s[20:21], v19, v28, s[20:21]
	v_cmp_eq_f32_e64 s[24:25], v15, v26
	v_cmp_lt_f32_e64 s[20:21], v15, v26
	s_and_b64 s[24:25], s[36:37], s[24:25]
	s_or_b64 s[20:21], s[20:21], s[24:25]
	v_addc_co_u32_e64 v20, s[20:21], v20, v29, s[20:21]
	v_cmp_eq_f32_e64 s[24:25], v12, v26
	v_cmp_lt_f32_e64 s[20:21], v12, v26
	s_and_b64 s[0:1], s[0:1], s[24:25]
	s_or_b64 s[0:1], s[20:21], s[0:1]
	v_addc_co_u32_e64 v21, s[0:1], v21, v30, s[0:1]
	v_cmp_eq_f32_e64 s[20:21], v13, v26
	v_cmp_lt_f32_e64 s[0:1], v13, v26
	s_and_b64 s[20:21], s[34:35], s[20:21]
	s_or_b64 s[0:1], s[0:1], s[20:21]
	v_addc_co_u32_e64 v22, s[0:1], v22, v31, s[0:1]
	v_cmp_eq_f32_e64 s[20:21], v10, v26
	v_cmp_lt_f32_e64 s[0:1], v10, v26
	s_and_b64 s[20:21], s[30:31], s[20:21]
	s_or_b64 s[0:1], s[0:1], s[20:21]
	v_addc_co_u32_e64 v23, s[0:1], v23, v38, s[0:1]
	v_cmp_eq_f32_e64 s[20:21], v11, v26
	v_cmp_lt_f32_e64 s[0:1], v11, v26
	s_and_b64 s[20:21], s[26:27], s[20:21]
	s_or_b64 s[0:1], s[0:1], s[20:21]
	v_addc_co_u32_e64 v24, s[0:1], v24, v39, s[0:1]
	v_cmp_eq_f32_e64 s[20:21], v16, v26
	v_cmp_lt_f32_e64 s[0:1], v16, v26
	s_and_b64 s[20:21], s[22:23], s[20:21]
	s_or_b64 s[0:1], s[0:1], s[20:21]
	v_addc_co_u32_e64 v25, s[0:1], v25, v40, s[0:1]
	v_cmp_eq_f32_e64 s[20:21], v9, v26
	v_cmp_lt_f32_e64 s[0:1], v9, v26
	s_and_b64 s[18:19], s[18:19], s[20:21]
	s_or_b64 s[0:1], s[0:1], s[18:19]
	v_cndmask_b32_e64 v26, 0, 1, s[0:1]
	v_add_u32_e32 v18, v18, v26
	ds_bpermute_b32 v26, v17, v14 offset:64
	v_cmp_lt_i32_e64 s[18:19], 1, v32
	v_cmp_lt_i32_e64 s[24:25], -7, v32
	v_cmp_lt_i32_e64 s[28:29], -11, v32
	v_cmp_lt_i32_e64 s[34:35], -15, v32
	s_waitcnt lgkmcnt(0)
	v_cmp_eq_f32_e64 s[20:21], v14, v26
	v_cmp_lt_f32_e64 s[0:1], v14, v26
	s_and_b64 s[20:21], s[18:19], s[20:21]
	s_or_b64 s[0:1], s[0:1], s[20:21]
	v_cmp_eq_f32_e64 s[22:23], v15, v26
	v_cmp_lt_i32_e64 s[20:21], -3, v32
	v_cndmask_b32_e64 v27, 0, 1, s[0:1]
	v_cmp_lt_f32_e64 s[0:1], v15, v26
	s_and_b64 s[22:23], s[20:21], s[22:23]
	s_or_b64 s[0:1], s[0:1], s[22:23]
	v_cmp_eq_f32_e64 s[22:23], v12, v26
	v_cndmask_b32_e64 v28, 0, 1, s[0:1]
	v_cmp_lt_f32_e64 s[0:1], v12, v26
	s_and_b64 s[22:23], s[24:25], s[22:23]
	s_or_b64 s[0:1], s[0:1], s[22:23]
	v_cmp_eq_f32_e64 s[22:23], v13, v26
	v_cndmask_b32_e64 v29, 0, 1, s[0:1]
	v_cmp_lt_f32_e64 s[0:1], v13, v26
	s_and_b64 s[22:23], s[28:29], s[22:23]
	s_or_b64 s[0:1], s[0:1], s[22:23]
	v_cmp_eq_f32_e64 s[22:23], v10, v26
	v_cndmask_b32_e64 v30, 0, 1, s[0:1]
	v_cmp_lt_f32_e64 s[0:1], v10, v26
	s_and_b64 s[22:23], s[34:35], s[22:23]
	s_or_b64 s[0:1], s[0:1], s[22:23]
	v_cndmask_b32_e64 v31, 0, 1, s[0:1]
	s_movk_i32 s0, 0xffed
	v_cmp_eq_f32_e64 s[26:27], v11, v26
	v_cmp_lt_i32_e64 s[0:1], s0, v32
	v_cmp_lt_f32_e64 s[22:23], v11, v26
	s_and_b64 s[26:27], s[0:1], s[26:27]
	s_movk_i32 s30, 0xffe9
	s_or_b64 s[22:23], s[22:23], s[26:27]
	v_cmp_eq_f32_e64 s[26:27], v16, v26
	v_cmp_lt_i32_e64 s[30:31], s30, v32
	ds_bpermute_b32 v40, v17, v15 offset:64
	v_cndmask_b32_e64 v38, 0, 1, s[22:23]
	v_cmp_lt_f32_e64 s[22:23], v16, v26
	s_and_b64 s[26:27], s[30:31], s[26:27]
	s_movk_i32 s36, 0xffe5
	s_or_b64 s[22:23], s[22:23], s[26:27]
	v_cmp_eq_f32_e64 s[26:27], v9, v26
	v_cmp_lt_i32_e64 s[36:37], s36, v32
	v_cndmask_b32_e64 v39, 0, 1, s[22:23]
	v_cmp_lt_f32_e64 s[22:23], v9, v26
	s_and_b64 s[26:27], s[36:37], s[26:27]
	s_or_b64 s[22:23], s[22:23], s[26:27]
	v_cndmask_b32_e64 v26, 0, 1, s[22:23]
	s_waitcnt lgkmcnt(0)
	v_cmp_eq_f32_e64 s[36:37], v14, v40
	v_cmp_lt_i32_e64 s[22:23], 5, v32
	v_cmp_lt_f32_e64 s[26:27], v14, v40
	s_and_b64 s[36:37], s[22:23], s[36:37]
	s_or_b64 s[26:27], s[26:27], s[36:37]
	v_addc_co_u32_e64 v19, s[26:27], v19, v27, s[26:27]
	v_cmp_eq_f32_e64 s[36:37], v15, v40
	v_cmp_lt_f32_e64 s[26:27], v15, v40
	s_and_b64 s[36:37], s[18:19], s[36:37]
	s_or_b64 s[26:27], s[26:27], s[36:37]
	v_addc_co_u32_e64 v20, s[26:27], v20, v28, s[26:27]
	v_cmp_eq_f32_e64 s[36:37], v12, v40
	v_cmp_lt_f32_e64 s[26:27], v12, v40
	s_and_b64 s[36:37], s[20:21], s[36:37]
	s_or_b64 s[26:27], s[26:27], s[36:37]
	v_addc_co_u32_e64 v21, s[26:27], v21, v29, s[26:27]
	v_cmp_eq_f32_e64 s[36:37], v13, v40
	v_cmp_lt_f32_e64 s[26:27], v13, v40
	s_and_b64 s[36:37], s[24:25], s[36:37]
	s_or_b64 s[26:27], s[26:27], s[36:37]
	v_addc_co_u32_e64 v22, s[26:27], v22, v30, s[26:27]
	v_cmp_eq_f32_e64 s[36:37], v10, v40
	v_cmp_lt_f32_e64 s[26:27], v10, v40
	s_and_b64 s[36:37], s[28:29], s[36:37]
	s_or_b64 s[26:27], s[26:27], s[36:37]
	v_addc_co_u32_e64 v23, s[26:27], v23, v31, s[26:27]
	v_cmp_eq_f32_e64 s[36:37], v11, v40
	v_cmp_lt_f32_e64 s[26:27], v11, v40
	s_and_b64 s[36:37], s[34:35], s[36:37]
	s_or_b64 s[26:27], s[26:27], s[36:37]
	v_addc_co_u32_e64 v24, s[26:27], v24, v38, s[26:27]
	v_cmp_eq_f32_e64 s[36:37], v16, v40
	v_cmp_lt_f32_e64 s[26:27], v16, v40
	s_and_b64 s[36:37], s[0:1], s[36:37]
	s_or_b64 s[26:27], s[26:27], s[36:37]
	v_addc_co_u32_e64 v25, s[26:27], v25, v39, s[26:27]
	v_cmp_eq_f32_e64 s[36:37], v9, v40
	v_cmp_lt_f32_e64 s[26:27], v9, v40
	s_and_b64 s[30:31], s[30:31], s[36:37]
	s_or_b64 s[26:27], s[26:27], s[30:31]
	v_addc_co_u32_e64 v18, s[26:27], v18, v26, s[26:27]
	ds_bpermute_b32 v26, v17, v12 offset:64
	v_cmp_lt_i32_e64 s[26:27], 9, v32
	ds_bpermute_b32 v40, v17, v13 offset:64
	s_waitcnt lgkmcnt(1)
	v_cmp_eq_f32_e64 s[36:37], v14, v26
	v_cmp_lt_f32_e64 s[30:31], v14, v26
	s_and_b64 s[36:37], s[26:27], s[36:37]
	s_or_b64 s[30:31], s[30:31], s[36:37]
	v_cmp_eq_f32_e64 s[36:37], v15, v26
	v_cndmask_b32_e64 v27, 0, 1, s[30:31]
	v_cmp_lt_f32_e64 s[30:31], v15, v26
	s_and_b64 s[36:37], s[22:23], s[36:37]
	s_or_b64 s[30:31], s[30:31], s[36:37]
	v_cmp_eq_f32_e64 s[36:37], v12, v26
	v_cndmask_b32_e64 v28, 0, 1, s[30:31]
	v_cmp_lt_f32_e64 s[30:31], v12, v26
	s_and_b64 s[36:37], s[18:19], s[36:37]
	s_or_b64 s[30:31], s[30:31], s[36:37]
	v_cmp_eq_f32_e64 s[36:37], v13, v26
	v_cndmask_b32_e64 v29, 0, 1, s[30:31]
	v_cmp_lt_f32_e64 s[30:31], v13, v26
	s_and_b64 s[36:37], s[20:21], s[36:37]
	s_or_b64 s[30:31], s[30:31], s[36:37]
	v_cmp_eq_f32_e64 s[36:37], v10, v26
	v_cndmask_b32_e64 v30, 0, 1, s[30:31]
	v_cmp_lt_f32_e64 s[30:31], v10, v26
	s_and_b64 s[36:37], s[24:25], s[36:37]
	s_or_b64 s[30:31], s[30:31], s[36:37]
	v_cmp_eq_f32_e64 s[36:37], v11, v26
	v_cndmask_b32_e64 v31, 0, 1, s[30:31]
	v_cmp_lt_f32_e64 s[30:31], v11, v26
	s_and_b64 s[36:37], s[28:29], s[36:37]
	s_or_b64 s[30:31], s[30:31], s[36:37]
	v_cmp_eq_f32_e64 s[36:37], v16, v26
	v_cndmask_b32_e64 v38, 0, 1, s[30:31]
	v_cmp_lt_f32_e64 s[30:31], v16, v26
	s_and_b64 s[36:37], s[34:35], s[36:37]
	s_or_b64 s[30:31], s[30:31], s[36:37]
	v_cmp_eq_f32_e64 s[36:37], v9, v26
	v_cndmask_b32_e64 v39, 0, 1, s[30:31]
	v_cmp_lt_f32_e64 s[30:31], v9, v26
	s_and_b64 s[0:1], s[0:1], s[36:37]
	s_or_b64 s[0:1], s[30:31], s[0:1]
	s_waitcnt lgkmcnt(0)
	v_cmp_eq_f32_e64 s[36:37], v14, v40
	v_cmp_lt_i32_e64 s[30:31], 13, v32
	v_cndmask_b32_e64 v26, 0, 1, s[0:1]
	v_cmp_lt_f32_e64 s[0:1], v14, v40
	s_and_b64 s[36:37], s[30:31], s[36:37]
	s_or_b64 s[0:1], s[0:1], s[36:37]
	v_addc_co_u32_e64 v19, s[0:1], v19, v27, s[0:1]
	v_cmp_eq_f32_e64 s[36:37], v15, v40
	v_cmp_lt_f32_e64 s[0:1], v15, v40
	s_and_b64 s[36:37], s[26:27], s[36:37]
	s_or_b64 s[0:1], s[0:1], s[36:37]
	v_addc_co_u32_e64 v20, s[0:1], v20, v28, s[0:1]
	v_cmp_eq_f32_e64 s[36:37], v12, v40
	v_cmp_lt_f32_e64 s[0:1], v12, v40
	s_and_b64 s[36:37], s[22:23], s[36:37]
	s_or_b64 s[0:1], s[0:1], s[36:37]
	v_addc_co_u32_e64 v21, s[0:1], v21, v29, s[0:1]
	v_cmp_eq_f32_e64 s[36:37], v13, v40
	v_cmp_lt_f32_e64 s[0:1], v13, v40
	s_and_b64 s[36:37], s[18:19], s[36:37]
	s_or_b64 s[0:1], s[0:1], s[36:37]
	v_addc_co_u32_e64 v22, s[0:1], v22, v30, s[0:1]
	v_cmp_eq_f32_e64 s[36:37], v10, v40
	v_cmp_lt_f32_e64 s[0:1], v10, v40
	s_and_b64 s[36:37], s[20:21], s[36:37]
	s_or_b64 s[0:1], s[0:1], s[36:37]
	v_addc_co_u32_e64 v23, s[0:1], v23, v31, s[0:1]
	v_cmp_eq_f32_e64 s[36:37], v11, v40
	v_cmp_lt_f32_e64 s[0:1], v11, v40
	s_and_b64 s[36:37], s[24:25], s[36:37]
	s_or_b64 s[0:1], s[0:1], s[36:37]
	v_addc_co_u32_e64 v24, s[0:1], v24, v38, s[0:1]
	v_cmp_eq_f32_e64 s[36:37], v16, v40
	v_cmp_lt_f32_e64 s[0:1], v16, v40
	s_and_b64 s[36:37], s[28:29], s[36:37]
	s_or_b64 s[0:1], s[0:1], s[36:37]
	v_addc_co_u32_e64 v25, s[0:1], v25, v39, s[0:1]
	v_cmp_eq_f32_e64 s[36:37], v9, v40
	v_cmp_lt_f32_e64 s[0:1], v9, v40
	s_and_b64 s[34:35], s[34:35], s[36:37]
	s_or_b64 s[0:1], s[0:1], s[34:35]
	v_addc_co_u32_e64 v18, s[0:1], v18, v26, s[0:1]
	ds_bpermute_b32 v26, v17, v10 offset:64
	v_cmp_lt_i32_e64 s[34:35], 17, v32
	ds_bpermute_b32 v40, v17, v11 offset:64
	s_waitcnt lgkmcnt(1)
	v_cmp_eq_f32_e64 s[36:37], v14, v26
	v_cmp_lt_f32_e64 s[0:1], v14, v26
	s_and_b64 s[36:37], s[34:35], s[36:37]
	s_or_b64 s[0:1], s[0:1], s[36:37]
	v_cmp_eq_f32_e64 s[36:37], v15, v26
	v_cndmask_b32_e64 v27, 0, 1, s[0:1]
	v_cmp_lt_f32_e64 s[0:1], v15, v26
	s_and_b64 s[36:37], s[30:31], s[36:37]
	s_or_b64 s[0:1], s[0:1], s[36:37]
	v_cmp_eq_f32_e64 s[36:37], v12, v26
	v_cndmask_b32_e64 v28, 0, 1, s[0:1]
	v_cmp_lt_f32_e64 s[0:1], v12, v26
	s_and_b64 s[36:37], s[26:27], s[36:37]
	s_or_b64 s[0:1], s[0:1], s[36:37]
	v_cmp_eq_f32_e64 s[36:37], v13, v26
	v_cndmask_b32_e64 v29, 0, 1, s[0:1]
	v_cmp_lt_f32_e64 s[0:1], v13, v26
	s_and_b64 s[36:37], s[22:23], s[36:37]
	s_or_b64 s[0:1], s[0:1], s[36:37]
	v_cmp_eq_f32_e64 s[36:37], v10, v26
	v_cndmask_b32_e64 v30, 0, 1, s[0:1]
	v_cmp_lt_f32_e64 s[0:1], v10, v26
	s_and_b64 s[36:37], s[18:19], s[36:37]
	s_or_b64 s[0:1], s[0:1], s[36:37]
	v_cmp_eq_f32_e64 s[36:37], v11, v26
	v_cndmask_b32_e64 v31, 0, 1, s[0:1]
	v_cmp_lt_f32_e64 s[0:1], v11, v26
	s_and_b64 s[36:37], s[20:21], s[36:37]
	s_or_b64 s[0:1], s[0:1], s[36:37]
	v_cmp_eq_f32_e64 s[36:37], v16, v26
	v_cndmask_b32_e64 v38, 0, 1, s[0:1]
	v_cmp_lt_f32_e64 s[0:1], v16, v26
	s_and_b64 s[36:37], s[24:25], s[36:37]
	s_or_b64 s[0:1], s[0:1], s[36:37]
	v_cmp_eq_f32_e64 s[36:37], v9, v26
	v_cndmask_b32_e64 v39, 0, 1, s[0:1]
	v_cmp_lt_f32_e64 s[0:1], v9, v26
	s_and_b64 s[28:29], s[28:29], s[36:37]
	s_or_b64 s[0:1], s[0:1], s[28:29]
	v_cndmask_b32_e64 v26, 0, 1, s[0:1]
	s_waitcnt lgkmcnt(0)
	v_cmp_eq_f32_e64 s[36:37], v14, v40
	v_cmp_lt_i32_e64 s[0:1], 21, v32
	v_cmp_lt_f32_e64 s[28:29], v14, v40
	s_and_b64 s[36:37], s[0:1], s[36:37]
	s_or_b64 s[28:29], s[28:29], s[36:37]
	v_addc_co_u32_e64 v19, s[28:29], v19, v27, s[28:29]
	v_cmp_eq_f32_e64 s[36:37], v15, v40
	v_cmp_lt_f32_e64 s[28:29], v15, v40
	s_and_b64 s[36:37], s[34:35], s[36:37]
	s_or_b64 s[28:29], s[28:29], s[36:37]
	v_addc_co_u32_e64 v20, s[28:29], v20, v28, s[28:29]
	v_cmp_eq_f32_e64 s[36:37], v12, v40
	v_cmp_lt_f32_e64 s[28:29], v12, v40
	s_and_b64 s[36:37], s[30:31], s[36:37]
	s_or_b64 s[28:29], s[28:29], s[36:37]
	v_addc_co_u32_e64 v21, s[28:29], v21, v29, s[28:29]
	v_cmp_eq_f32_e64 s[36:37], v13, v40
	v_cmp_lt_f32_e64 s[28:29], v13, v40
	s_and_b64 s[36:37], s[26:27], s[36:37]
	s_or_b64 s[28:29], s[28:29], s[36:37]
	v_addc_co_u32_e64 v22, s[28:29], v22, v30, s[28:29]
	v_cmp_eq_f32_e64 s[36:37], v10, v40
	v_cmp_lt_f32_e64 s[28:29], v10, v40
	s_and_b64 s[36:37], s[22:23], s[36:37]
	s_or_b64 s[28:29], s[28:29], s[36:37]
	v_addc_co_u32_e64 v23, s[28:29], v23, v31, s[28:29]
	v_cmp_eq_f32_e64 s[36:37], v11, v40
	v_cmp_lt_f32_e64 s[28:29], v11, v40
	s_and_b64 s[36:37], s[18:19], s[36:37]
	s_or_b64 s[28:29], s[28:29], s[36:37]
	v_addc_co_u32_e64 v24, s[28:29], v24, v38, s[28:29]
	v_cmp_eq_f32_e64 s[36:37], v16, v40
	v_cmp_lt_f32_e64 s[28:29], v16, v40
	s_and_b64 s[36:37], s[20:21], s[36:37]
	s_or_b64 s[28:29], s[28:29], s[36:37]
	v_addc_co_u32_e64 v25, s[28:29], v25, v39, s[28:29]
	v_cmp_eq_f32_e64 s[36:37], v9, v40
	v_cmp_lt_f32_e64 s[28:29], v9, v40
	s_and_b64 s[24:25], s[24:25], s[36:37]
	s_or_b64 s[24:25], s[28:29], s[24:25]
	v_addc_co_u32_e64 v18, s[24:25], v18, v26, s[24:25]
	ds_bpermute_b32 v26, v17, v16 offset:64
	v_cmp_lt_i32_e64 s[36:37], 25, v32
	ds_bpermute_b32 v40, v17, v9 offset:64
	s_waitcnt lgkmcnt(1)
	v_cmp_eq_f32_e64 s[28:29], v14, v26
	v_cmp_lt_f32_e64 s[24:25], v14, v26
	s_and_b64 s[28:29], s[36:37], s[28:29]
	s_or_b64 s[24:25], s[24:25], s[28:29]
	v_cmp_eq_f32_e64 s[28:29], v15, v26
	v_cndmask_b32_e64 v27, 0, 1, s[24:25]
	v_cmp_lt_f32_e64 s[24:25], v15, v26
	s_and_b64 s[28:29], s[0:1], s[28:29]
	s_or_b64 s[24:25], s[24:25], s[28:29]
	v_cmp_eq_f32_e64 s[28:29], v12, v26
	v_cndmask_b32_e64 v28, 0, 1, s[24:25]
	v_cmp_lt_f32_e64 s[24:25], v12, v26
	s_and_b64 s[28:29], s[34:35], s[28:29]
	s_or_b64 s[24:25], s[24:25], s[28:29]
	v_cmp_eq_f32_e64 s[28:29], v13, v26
	v_cndmask_b32_e64 v29, 0, 1, s[24:25]
	v_cmp_lt_f32_e64 s[24:25], v13, v26
	s_and_b64 s[28:29], s[30:31], s[28:29]
	s_or_b64 s[24:25], s[24:25], s[28:29]
	v_cmp_eq_f32_e64 s[28:29], v10, v26
	v_cndmask_b32_e64 v30, 0, 1, s[24:25]
	v_cmp_lt_f32_e64 s[24:25], v10, v26
	s_and_b64 s[28:29], s[26:27], s[28:29]
	s_or_b64 s[24:25], s[24:25], s[28:29]
	v_cmp_eq_f32_e64 s[28:29], v11, v26
	v_cndmask_b32_e64 v31, 0, 1, s[24:25]
	v_cmp_lt_f32_e64 s[24:25], v11, v26
	s_and_b64 s[28:29], s[22:23], s[28:29]
	s_or_b64 s[24:25], s[24:25], s[28:29]
	v_cmp_eq_f32_e64 s[28:29], v16, v26
	v_cndmask_b32_e64 v38, 0, 1, s[24:25]
	v_cmp_lt_f32_e64 s[24:25], v16, v26
	s_and_b64 s[28:29], s[18:19], s[28:29]
	s_or_b64 s[24:25], s[24:25], s[28:29]
	v_cmp_eq_f32_e64 s[28:29], v9, v26
	v_cndmask_b32_e64 v39, 0, 1, s[24:25]
	v_cmp_lt_f32_e64 s[24:25], v9, v26
	s_and_b64 s[20:21], s[20:21], s[28:29]
	s_or_b64 s[20:21], s[24:25], s[20:21]
	s_waitcnt lgkmcnt(0)
	v_cmp_eq_f32_e64 s[24:25], v14, v40
	v_cmp_lt_i32_e64 s[28:29], 29, v32
	v_cndmask_b32_e64 v26, 0, 1, s[20:21]
	v_cmp_lt_f32_e64 s[20:21], v14, v40
	s_and_b64 s[24:25], s[28:29], s[24:25]
	s_or_b64 s[20:21], s[20:21], s[24:25]
	v_addc_co_u32_e64 v19, s[20:21], v19, v27, s[20:21]
	v_cmp_eq_f32_e64 s[24:25], v15, v40
	v_cmp_lt_f32_e64 s[20:21], v15, v40
	s_and_b64 s[24:25], s[36:37], s[24:25]
	s_or_b64 s[20:21], s[20:21], s[24:25]
	v_addc_co_u32_e64 v20, s[20:21], v20, v28, s[20:21]
	v_cmp_eq_f32_e64 s[24:25], v12, v40
	v_cmp_lt_f32_e64 s[20:21], v12, v40
	s_and_b64 s[0:1], s[0:1], s[24:25]
	s_or_b64 s[0:1], s[20:21], s[0:1]
	v_addc_co_u32_e64 v21, s[0:1], v21, v29, s[0:1]
	v_cmp_eq_f32_e64 s[20:21], v13, v40
	v_cmp_lt_f32_e64 s[0:1], v13, v40
	s_and_b64 s[20:21], s[34:35], s[20:21]
	s_or_b64 s[0:1], s[0:1], s[20:21]
	v_addc_co_u32_e64 v22, s[0:1], v22, v30, s[0:1]
	v_cmp_eq_f32_e64 s[20:21], v10, v40
	v_cmp_lt_f32_e64 s[0:1], v10, v40
	s_and_b64 s[20:21], s[30:31], s[20:21]
	s_or_b64 s[0:1], s[0:1], s[20:21]
	v_addc_co_u32_e64 v23, s[0:1], v23, v31, s[0:1]
	v_cmp_eq_f32_e64 s[20:21], v11, v40
	v_cmp_lt_f32_e64 s[0:1], v11, v40
	s_and_b64 s[20:21], s[26:27], s[20:21]
	s_or_b64 s[0:1], s[0:1], s[20:21]
	v_addc_co_u32_e64 v24, s[0:1], v24, v38, s[0:1]
	v_cmp_eq_f32_e64 s[20:21], v16, v40
	v_cmp_lt_f32_e64 s[0:1], v16, v40
	s_and_b64 s[20:21], s[22:23], s[20:21]
	s_or_b64 s[0:1], s[0:1], s[20:21]
	v_addc_co_u32_e64 v25, s[0:1], v25, v39, s[0:1]
	v_cmp_eq_f32_e64 s[20:21], v9, v40
	v_cmp_lt_f32_e64 s[0:1], v9, v40
	s_and_b64 s[18:19], s[18:19], s[20:21]
	s_or_b64 s[0:1], s[0:1], s[18:19]
	v_addc_co_u32_e64 v18, s[0:1], v18, v26, s[0:1]
	ds_bpermute_b32 v26, v17, v14 offset:128
	v_cmp_lt_i32_e64 s[18:19], 2, v32
	v_cmp_lt_i32_e64 s[24:25], -6, v32
	v_cmp_lt_i32_e64 s[28:29], -10, v32
	v_cmp_lt_i32_e64 s[34:35], -14, v32
	s_waitcnt lgkmcnt(0)
	v_cmp_eq_f32_e64 s[20:21], v14, v26
	v_cmp_lt_f32_e64 s[0:1], v14, v26
	s_and_b64 s[20:21], s[18:19], s[20:21]
	s_or_b64 s[0:1], s[0:1], s[20:21]
	v_cmp_eq_f32_e64 s[22:23], v15, v26
	v_cmp_lt_i32_e64 s[20:21], -2, v32
	v_cndmask_b32_e64 v27, 0, 1, s[0:1]
	v_cmp_lt_f32_e64 s[0:1], v15, v26
	s_and_b64 s[22:23], s[20:21], s[22:23]
	s_or_b64 s[0:1], s[0:1], s[22:23]
	v_cmp_eq_f32_e64 s[22:23], v12, v26
	v_cndmask_b32_e64 v28, 0, 1, s[0:1]
	v_cmp_lt_f32_e64 s[0:1], v12, v26
	s_and_b64 s[22:23], s[24:25], s[22:23]
	s_or_b64 s[0:1], s[0:1], s[22:23]
	v_cmp_eq_f32_e64 s[22:23], v13, v26
	v_cndmask_b32_e64 v29, 0, 1, s[0:1]
	v_cmp_lt_f32_e64 s[0:1], v13, v26
	s_and_b64 s[22:23], s[28:29], s[22:23]
	s_or_b64 s[0:1], s[0:1], s[22:23]
	v_cmp_eq_f32_e64 s[22:23], v10, v26
	v_cndmask_b32_e64 v30, 0, 1, s[0:1]
	v_cmp_lt_f32_e64 s[0:1], v10, v26
	s_and_b64 s[22:23], s[34:35], s[22:23]
	s_or_b64 s[0:1], s[0:1], s[22:23]
	v_cndmask_b32_e64 v31, 0, 1, s[0:1]
	s_movk_i32 s0, 0xffee
	v_cmp_eq_f32_e64 s[26:27], v11, v26
	v_cmp_lt_i32_e64 s[0:1], s0, v32
	v_cmp_lt_f32_e64 s[22:23], v11, v26
	s_and_b64 s[26:27], s[0:1], s[26:27]
	s_movk_i32 s30, 0xffea
	s_or_b64 s[22:23], s[22:23], s[26:27]
	v_cmp_eq_f32_e64 s[26:27], v16, v26
	v_cmp_lt_i32_e64 s[30:31], s30, v32
	ds_bpermute_b32 v40, v17, v15 offset:128
	v_cndmask_b32_e64 v38, 0, 1, s[22:23]
	v_cmp_lt_f32_e64 s[22:23], v16, v26
	s_and_b64 s[26:27], s[30:31], s[26:27]
	s_movk_i32 s36, 0xffe6
	s_or_b64 s[22:23], s[22:23], s[26:27]
	v_cmp_eq_f32_e64 s[26:27], v9, v26
	v_cmp_lt_i32_e64 s[36:37], s36, v32
	v_cndmask_b32_e64 v39, 0, 1, s[22:23]
	v_cmp_lt_f32_e64 s[22:23], v9, v26
	s_and_b64 s[26:27], s[36:37], s[26:27]
	s_or_b64 s[22:23], s[22:23], s[26:27]
	v_cndmask_b32_e64 v26, 0, 1, s[22:23]
	s_waitcnt lgkmcnt(0)
	v_cmp_eq_f32_e64 s[36:37], v14, v40
	v_cmp_lt_i32_e64 s[22:23], 6, v32
	v_cmp_lt_f32_e64 s[26:27], v14, v40
	s_and_b64 s[36:37], s[22:23], s[36:37]
	s_or_b64 s[26:27], s[26:27], s[36:37]
	v_addc_co_u32_e64 v19, s[26:27], v19, v27, s[26:27]
	v_cmp_eq_f32_e64 s[36:37], v15, v40
	v_cmp_lt_f32_e64 s[26:27], v15, v40
	s_and_b64 s[36:37], s[18:19], s[36:37]
	s_or_b64 s[26:27], s[26:27], s[36:37]
	v_addc_co_u32_e64 v20, s[26:27], v20, v28, s[26:27]
	v_cmp_eq_f32_e64 s[36:37], v12, v40
	v_cmp_lt_f32_e64 s[26:27], v12, v40
	s_and_b64 s[36:37], s[20:21], s[36:37]
	s_or_b64 s[26:27], s[26:27], s[36:37]
	v_addc_co_u32_e64 v21, s[26:27], v21, v29, s[26:27]
	v_cmp_eq_f32_e64 s[36:37], v13, v40
	v_cmp_lt_f32_e64 s[26:27], v13, v40
	s_and_b64 s[36:37], s[24:25], s[36:37]
	s_or_b64 s[26:27], s[26:27], s[36:37]
	v_addc_co_u32_e64 v22, s[26:27], v22, v30, s[26:27]
	v_cmp_eq_f32_e64 s[36:37], v10, v40
	v_cmp_lt_f32_e64 s[26:27], v10, v40
	s_and_b64 s[36:37], s[28:29], s[36:37]
	s_or_b64 s[26:27], s[26:27], s[36:37]
	v_addc_co_u32_e64 v23, s[26:27], v23, v31, s[26:27]
	v_cmp_eq_f32_e64 s[36:37], v11, v40
	v_cmp_lt_f32_e64 s[26:27], v11, v40
	s_and_b64 s[36:37], s[34:35], s[36:37]
	s_or_b64 s[26:27], s[26:27], s[36:37]
	v_addc_co_u32_e64 v24, s[26:27], v24, v38, s[26:27]
	v_cmp_eq_f32_e64 s[36:37], v16, v40
	v_cmp_lt_f32_e64 s[26:27], v16, v40
	s_and_b64 s[36:37], s[0:1], s[36:37]
	s_or_b64 s[26:27], s[26:27], s[36:37]
	v_addc_co_u32_e64 v25, s[26:27], v25, v39, s[26:27]
	v_cmp_eq_f32_e64 s[36:37], v9, v40
	v_cmp_lt_f32_e64 s[26:27], v9, v40
	s_and_b64 s[30:31], s[30:31], s[36:37]
	s_or_b64 s[26:27], s[26:27], s[30:31]
	v_addc_co_u32_e64 v18, s[26:27], v18, v26, s[26:27]
	ds_bpermute_b32 v26, v17, v12 offset:128
	v_cmp_lt_i32_e64 s[26:27], 10, v32
	ds_bpermute_b32 v40, v17, v13 offset:128
	s_waitcnt lgkmcnt(1)
	v_cmp_eq_f32_e64 s[36:37], v14, v26
	v_cmp_lt_f32_e64 s[30:31], v14, v26
	s_and_b64 s[36:37], s[26:27], s[36:37]
	s_or_b64 s[30:31], s[30:31], s[36:37]
	v_cmp_eq_f32_e64 s[36:37], v15, v26
	v_cndmask_b32_e64 v27, 0, 1, s[30:31]
	v_cmp_lt_f32_e64 s[30:31], v15, v26
	s_and_b64 s[36:37], s[22:23], s[36:37]
	s_or_b64 s[30:31], s[30:31], s[36:37]
	v_cmp_eq_f32_e64 s[36:37], v12, v26
	v_cndmask_b32_e64 v28, 0, 1, s[30:31]
	v_cmp_lt_f32_e64 s[30:31], v12, v26
	s_and_b64 s[36:37], s[18:19], s[36:37]
	s_or_b64 s[30:31], s[30:31], s[36:37]
	v_cmp_eq_f32_e64 s[36:37], v13, v26
	v_cndmask_b32_e64 v29, 0, 1, s[30:31]
	v_cmp_lt_f32_e64 s[30:31], v13, v26
	s_and_b64 s[36:37], s[20:21], s[36:37]
	s_or_b64 s[30:31], s[30:31], s[36:37]
	v_cmp_eq_f32_e64 s[36:37], v10, v26
	v_cndmask_b32_e64 v30, 0, 1, s[30:31]
	v_cmp_lt_f32_e64 s[30:31], v10, v26
	s_and_b64 s[36:37], s[24:25], s[36:37]
	s_or_b64 s[30:31], s[30:31], s[36:37]
	v_cmp_eq_f32_e64 s[36:37], v11, v26
	v_cndmask_b32_e64 v31, 0, 1, s[30:31]
	v_cmp_lt_f32_e64 s[30:31], v11, v26
	s_and_b64 s[36:37], s[28:29], s[36:37]
	s_or_b64 s[30:31], s[30:31], s[36:37]
	v_cmp_eq_f32_e64 s[36:37], v16, v26
	v_cndmask_b32_e64 v38, 0, 1, s[30:31]
	v_cmp_lt_f32_e64 s[30:31], v16, v26
	s_and_b64 s[36:37], s[34:35], s[36:37]
	s_or_b64 s[30:31], s[30:31], s[36:37]
	v_cmp_eq_f32_e64 s[36:37], v9, v26
	v_cndmask_b32_e64 v39, 0, 1, s[30:31]
	v_cmp_lt_f32_e64 s[30:31], v9, v26
	s_and_b64 s[0:1], s[0:1], s[36:37]
	s_or_b64 s[0:1], s[30:31], s[0:1]
	s_waitcnt lgkmcnt(0)
	v_cmp_eq_f32_e64 s[36:37], v14, v40
	v_cmp_lt_i32_e64 s[30:31], 14, v32
	v_cndmask_b32_e64 v26, 0, 1, s[0:1]
	v_cmp_lt_f32_e64 s[0:1], v14, v40
	s_and_b64 s[36:37], s[30:31], s[36:37]
	s_or_b64 s[0:1], s[0:1], s[36:37]
	v_addc_co_u32_e64 v19, s[0:1], v19, v27, s[0:1]
	v_cmp_eq_f32_e64 s[36:37], v15, v40
	v_cmp_lt_f32_e64 s[0:1], v15, v40
	s_and_b64 s[36:37], s[26:27], s[36:37]
	s_or_b64 s[0:1], s[0:1], s[36:37]
	v_addc_co_u32_e64 v20, s[0:1], v20, v28, s[0:1]
	v_cmp_eq_f32_e64 s[36:37], v12, v40
	v_cmp_lt_f32_e64 s[0:1], v12, v40
	s_and_b64 s[36:37], s[22:23], s[36:37]
	s_or_b64 s[0:1], s[0:1], s[36:37]
	v_addc_co_u32_e64 v21, s[0:1], v21, v29, s[0:1]
	v_cmp_eq_f32_e64 s[36:37], v13, v40
	v_cmp_lt_f32_e64 s[0:1], v13, v40
	s_and_b64 s[36:37], s[18:19], s[36:37]
	s_or_b64 s[0:1], s[0:1], s[36:37]
	v_addc_co_u32_e64 v22, s[0:1], v22, v30, s[0:1]
	v_cmp_eq_f32_e64 s[36:37], v10, v40
	v_cmp_lt_f32_e64 s[0:1], v10, v40
	s_and_b64 s[36:37], s[20:21], s[36:37]
	s_or_b64 s[0:1], s[0:1], s[36:37]
	v_addc_co_u32_e64 v23, s[0:1], v23, v31, s[0:1]
	v_cmp_eq_f32_e64 s[36:37], v11, v40
	v_cmp_lt_f32_e64 s[0:1], v11, v40
	s_and_b64 s[36:37], s[24:25], s[36:37]
	s_or_b64 s[0:1], s[0:1], s[36:37]
	v_addc_co_u32_e64 v24, s[0:1], v24, v38, s[0:1]
	v_cmp_eq_f32_e64 s[36:37], v16, v40
	v_cmp_lt_f32_e64 s[0:1], v16, v40
	s_and_b64 s[36:37], s[28:29], s[36:37]
	s_or_b64 s[0:1], s[0:1], s[36:37]
	v_addc_co_u32_e64 v25, s[0:1], v25, v39, s[0:1]
	v_cmp_eq_f32_e64 s[36:37], v9, v40
	v_cmp_lt_f32_e64 s[0:1], v9, v40
	s_and_b64 s[34:35], s[34:35], s[36:37]
	s_or_b64 s[0:1], s[0:1], s[34:35]
	v_addc_co_u32_e64 v18, s[0:1], v18, v26, s[0:1]
	ds_bpermute_b32 v26, v17, v10 offset:128
	v_cmp_lt_i32_e64 s[34:35], 18, v32
	ds_bpermute_b32 v40, v17, v11 offset:128
	s_waitcnt lgkmcnt(1)
	v_cmp_eq_f32_e64 s[36:37], v14, v26
	v_cmp_lt_f32_e64 s[0:1], v14, v26
	s_and_b64 s[36:37], s[34:35], s[36:37]
	s_or_b64 s[0:1], s[0:1], s[36:37]
	v_cmp_eq_f32_e64 s[36:37], v15, v26
	v_cndmask_b32_e64 v27, 0, 1, s[0:1]
	v_cmp_lt_f32_e64 s[0:1], v15, v26
	s_and_b64 s[36:37], s[30:31], s[36:37]
	s_or_b64 s[0:1], s[0:1], s[36:37]
	v_cmp_eq_f32_e64 s[36:37], v12, v26
	v_cndmask_b32_e64 v28, 0, 1, s[0:1]
	v_cmp_lt_f32_e64 s[0:1], v12, v26
	s_and_b64 s[36:37], s[26:27], s[36:37]
	s_or_b64 s[0:1], s[0:1], s[36:37]
	v_cmp_eq_f32_e64 s[36:37], v13, v26
	v_cndmask_b32_e64 v29, 0, 1, s[0:1]
	v_cmp_lt_f32_e64 s[0:1], v13, v26
	s_and_b64 s[36:37], s[22:23], s[36:37]
	s_or_b64 s[0:1], s[0:1], s[36:37]
	v_cmp_eq_f32_e64 s[36:37], v10, v26
	v_cndmask_b32_e64 v30, 0, 1, s[0:1]
	v_cmp_lt_f32_e64 s[0:1], v10, v26
	s_and_b64 s[36:37], s[18:19], s[36:37]
	s_or_b64 s[0:1], s[0:1], s[36:37]
	v_cmp_eq_f32_e64 s[36:37], v11, v26
	v_cndmask_b32_e64 v31, 0, 1, s[0:1]
	v_cmp_lt_f32_e64 s[0:1], v11, v26
	s_and_b64 s[36:37], s[20:21], s[36:37]
	s_or_b64 s[0:1], s[0:1], s[36:37]
	v_cmp_eq_f32_e64 s[36:37], v16, v26
	v_cndmask_b32_e64 v38, 0, 1, s[0:1]
	v_cmp_lt_f32_e64 s[0:1], v16, v26
	s_and_b64 s[36:37], s[24:25], s[36:37]
	s_or_b64 s[0:1], s[0:1], s[36:37]
	v_cmp_eq_f32_e64 s[36:37], v9, v26
	v_cndmask_b32_e64 v39, 0, 1, s[0:1]
	v_cmp_lt_f32_e64 s[0:1], v9, v26
	s_and_b64 s[28:29], s[28:29], s[36:37]
	s_or_b64 s[0:1], s[0:1], s[28:29]
	v_cndmask_b32_e64 v26, 0, 1, s[0:1]
	s_waitcnt lgkmcnt(0)
	v_cmp_eq_f32_e64 s[36:37], v14, v40
	v_cmp_lt_i32_e64 s[0:1], 22, v32
	v_cmp_lt_f32_e64 s[28:29], v14, v40
	s_and_b64 s[36:37], s[0:1], s[36:37]
	s_or_b64 s[28:29], s[28:29], s[36:37]
	v_addc_co_u32_e64 v19, s[28:29], v19, v27, s[28:29]
	v_cmp_eq_f32_e64 s[36:37], v15, v40
	v_cmp_lt_f32_e64 s[28:29], v15, v40
	s_and_b64 s[36:37], s[34:35], s[36:37]
	s_or_b64 s[28:29], s[28:29], s[36:37]
	v_addc_co_u32_e64 v20, s[28:29], v20, v28, s[28:29]
	v_cmp_eq_f32_e64 s[36:37], v12, v40
	v_cmp_lt_f32_e64 s[28:29], v12, v40
	s_and_b64 s[36:37], s[30:31], s[36:37]
	s_or_b64 s[28:29], s[28:29], s[36:37]
	v_addc_co_u32_e64 v21, s[28:29], v21, v29, s[28:29]
	v_cmp_eq_f32_e64 s[36:37], v13, v40
	v_cmp_lt_f32_e64 s[28:29], v13, v40
	s_and_b64 s[36:37], s[26:27], s[36:37]
	s_or_b64 s[28:29], s[28:29], s[36:37]
	v_addc_co_u32_e64 v22, s[28:29], v22, v30, s[28:29]
	v_cmp_eq_f32_e64 s[36:37], v10, v40
	v_cmp_lt_f32_e64 s[28:29], v10, v40
	s_and_b64 s[36:37], s[22:23], s[36:37]
	s_or_b64 s[28:29], s[28:29], s[36:37]
	v_addc_co_u32_e64 v23, s[28:29], v23, v31, s[28:29]
	v_cmp_eq_f32_e64 s[36:37], v11, v40
	v_cmp_lt_f32_e64 s[28:29], v11, v40
	s_and_b64 s[36:37], s[18:19], s[36:37]
	s_or_b64 s[28:29], s[28:29], s[36:37]
	v_addc_co_u32_e64 v24, s[28:29], v24, v38, s[28:29]
	v_cmp_eq_f32_e64 s[36:37], v16, v40
	v_cmp_lt_f32_e64 s[28:29], v16, v40
	s_and_b64 s[36:37], s[20:21], s[36:37]
	s_or_b64 s[28:29], s[28:29], s[36:37]
	v_addc_co_u32_e64 v25, s[28:29], v25, v39, s[28:29]
	v_cmp_eq_f32_e64 s[36:37], v9, v40
	v_cmp_lt_f32_e64 s[28:29], v9, v40
	s_and_b64 s[24:25], s[24:25], s[36:37]
	s_or_b64 s[24:25], s[28:29], s[24:25]
	v_addc_co_u32_e64 v18, s[24:25], v18, v26, s[24:25]
	ds_bpermute_b32 v26, v17, v16 offset:128
	v_cmp_lt_i32_e64 s[36:37], 26, v32
	ds_bpermute_b32 v40, v17, v9 offset:128
	s_waitcnt lgkmcnt(1)
	v_cmp_eq_f32_e64 s[28:29], v14, v26
	v_cmp_lt_f32_e64 s[24:25], v14, v26
	s_and_b64 s[28:29], s[36:37], s[28:29]
	s_or_b64 s[24:25], s[24:25], s[28:29]
	v_cmp_eq_f32_e64 s[28:29], v15, v26
	v_cndmask_b32_e64 v27, 0, 1, s[24:25]
	v_cmp_lt_f32_e64 s[24:25], v15, v26
	s_and_b64 s[28:29], s[0:1], s[28:29]
	s_or_b64 s[24:25], s[24:25], s[28:29]
	v_cmp_eq_f32_e64 s[28:29], v12, v26
	v_cndmask_b32_e64 v28, 0, 1, s[24:25]
	v_cmp_lt_f32_e64 s[24:25], v12, v26
	s_and_b64 s[28:29], s[34:35], s[28:29]
	s_or_b64 s[24:25], s[24:25], s[28:29]
	v_cmp_eq_f32_e64 s[28:29], v13, v26
	v_cndmask_b32_e64 v29, 0, 1, s[24:25]
	v_cmp_lt_f32_e64 s[24:25], v13, v26
	s_and_b64 s[28:29], s[30:31], s[28:29]
	s_or_b64 s[24:25], s[24:25], s[28:29]
	v_cmp_eq_f32_e64 s[28:29], v10, v26
	v_cndmask_b32_e64 v30, 0, 1, s[24:25]
	v_cmp_lt_f32_e64 s[24:25], v10, v26
	s_and_b64 s[28:29], s[26:27], s[28:29]
	s_or_b64 s[24:25], s[24:25], s[28:29]
	v_cmp_eq_f32_e64 s[28:29], v11, v26
	v_cndmask_b32_e64 v31, 0, 1, s[24:25]
	v_cmp_lt_f32_e64 s[24:25], v11, v26
	s_and_b64 s[28:29], s[22:23], s[28:29]
	s_or_b64 s[24:25], s[24:25], s[28:29]
	v_cmp_eq_f32_e64 s[28:29], v16, v26
	v_cndmask_b32_e64 v38, 0, 1, s[24:25]
	v_cmp_lt_f32_e64 s[24:25], v16, v26
	s_and_b64 s[28:29], s[18:19], s[28:29]
	s_or_b64 s[24:25], s[24:25], s[28:29]
	v_cmp_eq_f32_e64 s[28:29], v9, v26
	v_cndmask_b32_e64 v39, 0, 1, s[24:25]
	v_cmp_lt_f32_e64 s[24:25], v9, v26
	s_and_b64 s[20:21], s[20:21], s[28:29]
	s_or_b64 s[20:21], s[24:25], s[20:21]
	s_waitcnt lgkmcnt(0)
	v_cmp_eq_f32_e64 s[24:25], v14, v40
	v_cmp_lt_i32_e64 s[28:29], 30, v32
	v_cndmask_b32_e64 v26, 0, 1, s[20:21]
	v_cmp_lt_f32_e64 s[20:21], v14, v40
	s_and_b64 s[24:25], s[28:29], s[24:25]
	s_or_b64 s[20:21], s[20:21], s[24:25]
	v_addc_co_u32_e64 v19, s[20:21], v19, v27, s[20:21]
	v_cmp_eq_f32_e64 s[24:25], v15, v40
	v_cmp_lt_f32_e64 s[20:21], v15, v40
	s_and_b64 s[24:25], s[36:37], s[24:25]
	s_or_b64 s[20:21], s[20:21], s[24:25]
	v_addc_co_u32_e64 v20, s[20:21], v20, v28, s[20:21]
	v_cmp_eq_f32_e64 s[24:25], v12, v40
	v_cmp_lt_f32_e64 s[20:21], v12, v40
	s_and_b64 s[0:1], s[0:1], s[24:25]
	s_or_b64 s[0:1], s[20:21], s[0:1]
	v_addc_co_u32_e64 v21, s[0:1], v21, v29, s[0:1]
	v_cmp_eq_f32_e64 s[20:21], v13, v40
	v_cmp_lt_f32_e64 s[0:1], v13, v40
	s_and_b64 s[20:21], s[34:35], s[20:21]
	s_or_b64 s[0:1], s[0:1], s[20:21]
	v_addc_co_u32_e64 v22, s[0:1], v22, v30, s[0:1]
	v_cmp_eq_f32_e64 s[20:21], v10, v40
	v_cmp_lt_f32_e64 s[0:1], v10, v40
	s_and_b64 s[20:21], s[30:31], s[20:21]
	s_or_b64 s[0:1], s[0:1], s[20:21]
	v_addc_co_u32_e64 v23, s[0:1], v23, v31, s[0:1]
	v_cmp_eq_f32_e64 s[20:21], v11, v40
	v_cmp_lt_f32_e64 s[0:1], v11, v40
	s_and_b64 s[20:21], s[26:27], s[20:21]
	s_or_b64 s[0:1], s[0:1], s[20:21]
	v_addc_co_u32_e64 v24, s[0:1], v24, v38, s[0:1]
	v_cmp_eq_f32_e64 s[20:21], v16, v40
	v_cmp_lt_f32_e64 s[0:1], v16, v40
	s_and_b64 s[20:21], s[22:23], s[20:21]
	s_or_b64 s[0:1], s[0:1], s[20:21]
	v_addc_co_u32_e64 v25, s[0:1], v25, v39, s[0:1]
	v_cmp_eq_f32_e64 s[20:21], v9, v40
	v_cmp_lt_f32_e64 s[0:1], v9, v40
	s_and_b64 s[18:19], s[18:19], s[20:21]
	s_or_b64 s[0:1], s[0:1], s[18:19]
	v_addc_co_u32_e64 v18, s[0:1], v18, v26, s[0:1]
	ds_bpermute_b32 v26, v17, v14 offset:192
	v_cmp_lt_i32_e64 s[18:19], 3, v32
	v_cmp_lt_i32_e64 s[24:25], -5, v32
	v_cmp_lt_i32_e64 s[28:29], -9, v32
	v_cmp_lt_i32_e64 s[34:35], -13, v32
	s_waitcnt lgkmcnt(0)
	v_cmp_eq_f32_e64 s[20:21], v14, v26
	v_cmp_lt_f32_e64 s[0:1], v14, v26
	s_and_b64 s[20:21], s[18:19], s[20:21]
	s_or_b64 s[0:1], s[0:1], s[20:21]
	v_cmp_eq_f32_e64 s[22:23], v15, v26
	v_cmp_lt_i32_e64 s[20:21], -1, v32
	v_cndmask_b32_e64 v27, 0, 1, s[0:1]
	v_cmp_lt_f32_e64 s[0:1], v15, v26
	s_and_b64 s[22:23], s[20:21], s[22:23]
	s_or_b64 s[0:1], s[0:1], s[22:23]
	v_cmp_eq_f32_e64 s[22:23], v12, v26
	v_cndmask_b32_e64 v28, 0, 1, s[0:1]
	v_cmp_lt_f32_e64 s[0:1], v12, v26
	s_and_b64 s[22:23], s[24:25], s[22:23]
	s_or_b64 s[0:1], s[0:1], s[22:23]
	v_cmp_eq_f32_e64 s[22:23], v13, v26
	v_cndmask_b32_e64 v29, 0, 1, s[0:1]
	v_cmp_lt_f32_e64 s[0:1], v13, v26
	s_and_b64 s[22:23], s[28:29], s[22:23]
	s_or_b64 s[0:1], s[0:1], s[22:23]
	v_cmp_eq_f32_e64 s[22:23], v10, v26
	v_cndmask_b32_e64 v30, 0, 1, s[0:1]
	v_cmp_lt_f32_e64 s[0:1], v10, v26
	s_and_b64 s[22:23], s[34:35], s[22:23]
	s_or_b64 s[0:1], s[0:1], s[22:23]
	v_cndmask_b32_e64 v31, 0, 1, s[0:1]
	s_movk_i32 s0, 0xffef
	v_cmp_eq_f32_e64 s[26:27], v11, v26
	v_cmp_lt_i32_e64 s[0:1], s0, v32
	v_cmp_lt_f32_e64 s[22:23], v11, v26
	s_and_b64 s[26:27], s[0:1], s[26:27]
	s_movk_i32 s30, 0xffeb
	s_or_b64 s[22:23], s[22:23], s[26:27]
	v_cmp_eq_f32_e64 s[26:27], v16, v26
	v_cmp_lt_i32_e64 s[30:31], s30, v32
	ds_bpermute_b32 v40, v17, v15 offset:192
	v_cndmask_b32_e64 v38, 0, 1, s[22:23]
	v_cmp_lt_f32_e64 s[22:23], v16, v26
	s_and_b64 s[26:27], s[30:31], s[26:27]
	s_movk_i32 s36, 0xffe7
	s_or_b64 s[22:23], s[22:23], s[26:27]
	v_cmp_eq_f32_e64 s[26:27], v9, v26
	v_cmp_lt_i32_e64 s[36:37], s36, v32
	v_cndmask_b32_e64 v39, 0, 1, s[22:23]
	v_cmp_lt_f32_e64 s[22:23], v9, v26
	s_and_b64 s[26:27], s[36:37], s[26:27]
	s_or_b64 s[22:23], s[22:23], s[26:27]
	v_cndmask_b32_e64 v26, 0, 1, s[22:23]
	s_waitcnt lgkmcnt(0)
	v_cmp_eq_f32_e64 s[36:37], v14, v40
	v_cmp_lt_i32_e64 s[22:23], 7, v32
	v_cmp_lt_f32_e64 s[26:27], v14, v40
	s_and_b64 s[36:37], s[22:23], s[36:37]
	s_or_b64 s[26:27], s[26:27], s[36:37]
	v_addc_co_u32_e64 v19, s[26:27], v19, v27, s[26:27]
	v_cmp_eq_f32_e64 s[36:37], v15, v40
	v_cmp_lt_f32_e64 s[26:27], v15, v40
	s_and_b64 s[36:37], s[18:19], s[36:37]
	s_or_b64 s[26:27], s[26:27], s[36:37]
	v_addc_co_u32_e64 v20, s[26:27], v20, v28, s[26:27]
	v_cmp_eq_f32_e64 s[36:37], v12, v40
	v_cmp_lt_f32_e64 s[26:27], v12, v40
	s_and_b64 s[36:37], s[20:21], s[36:37]
	s_or_b64 s[26:27], s[26:27], s[36:37]
	v_addc_co_u32_e64 v21, s[26:27], v21, v29, s[26:27]
	v_cmp_eq_f32_e64 s[36:37], v13, v40
	v_cmp_lt_f32_e64 s[26:27], v13, v40
	s_and_b64 s[36:37], s[24:25], s[36:37]
	s_or_b64 s[26:27], s[26:27], s[36:37]
	v_addc_co_u32_e64 v22, s[26:27], v22, v30, s[26:27]
	v_cmp_eq_f32_e64 s[36:37], v10, v40
	v_cmp_lt_f32_e64 s[26:27], v10, v40
	s_and_b64 s[36:37], s[28:29], s[36:37]
	s_or_b64 s[26:27], s[26:27], s[36:37]
	v_addc_co_u32_e64 v23, s[26:27], v23, v31, s[26:27]
	v_cmp_eq_f32_e64 s[36:37], v11, v40
	v_cmp_lt_f32_e64 s[26:27], v11, v40
	s_and_b64 s[36:37], s[34:35], s[36:37]
	s_or_b64 s[26:27], s[26:27], s[36:37]
	v_addc_co_u32_e64 v24, s[26:27], v24, v38, s[26:27]
	v_cmp_eq_f32_e64 s[36:37], v16, v40
	v_cmp_lt_f32_e64 s[26:27], v16, v40
	s_and_b64 s[36:37], s[0:1], s[36:37]
	s_or_b64 s[26:27], s[26:27], s[36:37]
	v_addc_co_u32_e64 v25, s[26:27], v25, v39, s[26:27]
	v_cmp_eq_f32_e64 s[36:37], v9, v40
	v_cmp_lt_f32_e64 s[26:27], v9, v40
	s_and_b64 s[30:31], s[30:31], s[36:37]
	s_or_b64 s[26:27], s[26:27], s[30:31]
	v_addc_co_u32_e64 v18, s[26:27], v18, v26, s[26:27]
	ds_bpermute_b32 v26, v17, v12 offset:192
	v_cmp_lt_i32_e64 s[26:27], 11, v32
	ds_bpermute_b32 v40, v17, v13 offset:192
	s_waitcnt lgkmcnt(1)
	v_cmp_eq_f32_e64 s[36:37], v14, v26
	v_cmp_lt_f32_e64 s[30:31], v14, v26
	s_and_b64 s[36:37], s[26:27], s[36:37]
	s_or_b64 s[30:31], s[30:31], s[36:37]
	v_cmp_eq_f32_e64 s[36:37], v15, v26
	v_cndmask_b32_e64 v27, 0, 1, s[30:31]
	v_cmp_lt_f32_e64 s[30:31], v15, v26
	s_and_b64 s[36:37], s[22:23], s[36:37]
	s_or_b64 s[30:31], s[30:31], s[36:37]
	v_cmp_eq_f32_e64 s[36:37], v12, v26
	v_cndmask_b32_e64 v28, 0, 1, s[30:31]
	v_cmp_lt_f32_e64 s[30:31], v12, v26
	s_and_b64 s[36:37], s[18:19], s[36:37]
	s_or_b64 s[30:31], s[30:31], s[36:37]
	v_cmp_eq_f32_e64 s[36:37], v13, v26
	v_cndmask_b32_e64 v29, 0, 1, s[30:31]
	v_cmp_lt_f32_e64 s[30:31], v13, v26
	s_and_b64 s[36:37], s[20:21], s[36:37]
	s_or_b64 s[30:31], s[30:31], s[36:37]
	v_cmp_eq_f32_e64 s[36:37], v10, v26
	v_cndmask_b32_e64 v30, 0, 1, s[30:31]
	v_cmp_lt_f32_e64 s[30:31], v10, v26
	s_and_b64 s[36:37], s[24:25], s[36:37]
	s_or_b64 s[30:31], s[30:31], s[36:37]
	v_cmp_eq_f32_e64 s[36:37], v11, v26
	v_cndmask_b32_e64 v31, 0, 1, s[30:31]
	v_cmp_lt_f32_e64 s[30:31], v11, v26
	s_and_b64 s[36:37], s[28:29], s[36:37]
	s_or_b64 s[30:31], s[30:31], s[36:37]
	v_cmp_eq_f32_e64 s[36:37], v16, v26
	v_cndmask_b32_e64 v38, 0, 1, s[30:31]
	v_cmp_lt_f32_e64 s[30:31], v16, v26
	s_and_b64 s[36:37], s[34:35], s[36:37]
	s_or_b64 s[30:31], s[30:31], s[36:37]
	v_cmp_eq_f32_e64 s[36:37], v9, v26
	v_cndmask_b32_e64 v39, 0, 1, s[30:31]
	v_cmp_lt_f32_e64 s[30:31], v9, v26
	s_and_b64 s[0:1], s[0:1], s[36:37]
	s_or_b64 s[0:1], s[30:31], s[0:1]
	s_waitcnt lgkmcnt(0)
	v_cmp_eq_f32_e64 s[36:37], v14, v40
	v_cmp_lt_i32_e64 s[30:31], 15, v32
	v_cndmask_b32_e64 v26, 0, 1, s[0:1]
	v_cmp_lt_f32_e64 s[0:1], v14, v40
	s_and_b64 s[36:37], s[30:31], s[36:37]
	s_or_b64 s[0:1], s[0:1], s[36:37]
	v_addc_co_u32_e64 v19, s[0:1], v19, v27, s[0:1]
	v_cmp_eq_f32_e64 s[36:37], v15, v40
	v_cmp_lt_f32_e64 s[0:1], v15, v40
	s_and_b64 s[36:37], s[26:27], s[36:37]
	s_or_b64 s[0:1], s[0:1], s[36:37]
	v_addc_co_u32_e64 v20, s[0:1], v20, v28, s[0:1]
	v_cmp_eq_f32_e64 s[36:37], v12, v40
	v_cmp_lt_f32_e64 s[0:1], v12, v40
	s_and_b64 s[36:37], s[22:23], s[36:37]
	s_or_b64 s[0:1], s[0:1], s[36:37]
	v_addc_co_u32_e64 v21, s[0:1], v21, v29, s[0:1]
	v_cmp_eq_f32_e64 s[36:37], v13, v40
	v_cmp_lt_f32_e64 s[0:1], v13, v40
	s_and_b64 s[36:37], s[18:19], s[36:37]
	s_or_b64 s[0:1], s[0:1], s[36:37]
	v_addc_co_u32_e64 v22, s[0:1], v22, v30, s[0:1]
	v_cmp_eq_f32_e64 s[36:37], v10, v40
	v_cmp_lt_f32_e64 s[0:1], v10, v40
	s_and_b64 s[36:37], s[20:21], s[36:37]
	s_or_b64 s[0:1], s[0:1], s[36:37]
	v_addc_co_u32_e64 v23, s[0:1], v23, v31, s[0:1]
	v_cmp_eq_f32_e64 s[36:37], v11, v40
	v_cmp_lt_f32_e64 s[0:1], v11, v40
	s_and_b64 s[36:37], s[24:25], s[36:37]
	s_or_b64 s[0:1], s[0:1], s[36:37]
	v_addc_co_u32_e64 v24, s[0:1], v24, v38, s[0:1]
	v_cmp_eq_f32_e64 s[36:37], v16, v40
	v_cmp_lt_f32_e64 s[0:1], v16, v40
	s_and_b64 s[36:37], s[28:29], s[36:37]
	s_or_b64 s[0:1], s[0:1], s[36:37]
	v_addc_co_u32_e64 v25, s[0:1], v25, v39, s[0:1]
	v_cmp_eq_f32_e64 s[36:37], v9, v40
	v_cmp_lt_f32_e64 s[0:1], v9, v40
	s_and_b64 s[34:35], s[34:35], s[36:37]
	s_or_b64 s[0:1], s[0:1], s[34:35]
	v_addc_co_u32_e64 v18, s[0:1], v18, v26, s[0:1]
	ds_bpermute_b32 v26, v17, v10 offset:192
	v_cmp_lt_i32_e64 s[34:35], 19, v32
	ds_bpermute_b32 v40, v17, v11 offset:192
	s_waitcnt lgkmcnt(1)
	v_cmp_eq_f32_e64 s[36:37], v14, v26
	v_cmp_lt_f32_e64 s[0:1], v14, v26
	s_and_b64 s[36:37], s[34:35], s[36:37]
	s_or_b64 s[0:1], s[0:1], s[36:37]
	v_cmp_eq_f32_e64 s[36:37], v15, v26
	v_cndmask_b32_e64 v27, 0, 1, s[0:1]
	v_cmp_lt_f32_e64 s[0:1], v15, v26
	s_and_b64 s[36:37], s[30:31], s[36:37]
	s_or_b64 s[0:1], s[0:1], s[36:37]
	v_cmp_eq_f32_e64 s[36:37], v12, v26
	v_cndmask_b32_e64 v28, 0, 1, s[0:1]
	v_cmp_lt_f32_e64 s[0:1], v12, v26
	s_and_b64 s[36:37], s[26:27], s[36:37]
	s_or_b64 s[0:1], s[0:1], s[36:37]
	v_cmp_eq_f32_e64 s[36:37], v13, v26
	v_cndmask_b32_e64 v29, 0, 1, s[0:1]
	v_cmp_lt_f32_e64 s[0:1], v13, v26
	s_and_b64 s[36:37], s[22:23], s[36:37]
	s_or_b64 s[0:1], s[0:1], s[36:37]
	v_cmp_eq_f32_e64 s[36:37], v10, v26
	v_cndmask_b32_e64 v30, 0, 1, s[0:1]
	v_cmp_lt_f32_e64 s[0:1], v10, v26
	s_and_b64 s[36:37], s[18:19], s[36:37]
	s_or_b64 s[0:1], s[0:1], s[36:37]
	v_cmp_eq_f32_e64 s[36:37], v11, v26
	v_cndmask_b32_e64 v31, 0, 1, s[0:1]
	v_cmp_lt_f32_e64 s[0:1], v11, v26
	s_and_b64 s[36:37], s[20:21], s[36:37]
	s_or_b64 s[0:1], s[0:1], s[36:37]
	v_cmp_eq_f32_e64 s[36:37], v16, v26
	v_cndmask_b32_e64 v38, 0, 1, s[0:1]
	v_cmp_lt_f32_e64 s[0:1], v16, v26
	s_and_b64 s[36:37], s[24:25], s[36:37]
	s_or_b64 s[0:1], s[0:1], s[36:37]
	v_cmp_eq_f32_e64 s[36:37], v9, v26
	v_cndmask_b32_e64 v39, 0, 1, s[0:1]
	v_cmp_lt_f32_e64 s[0:1], v9, v26
	s_and_b64 s[28:29], s[28:29], s[36:37]
	s_or_b64 s[0:1], s[0:1], s[28:29]
	v_cndmask_b32_e64 v26, 0, 1, s[0:1]
	s_waitcnt lgkmcnt(0)
	v_cmp_eq_f32_e64 s[36:37], v14, v40
	v_cmp_lt_i32_e64 s[0:1], 23, v32
	v_cmp_lt_f32_e64 s[28:29], v14, v40
	s_and_b64 s[36:37], s[0:1], s[36:37]
	s_or_b64 s[28:29], s[28:29], s[36:37]
	v_addc_co_u32_e64 v19, s[28:29], v19, v27, s[28:29]
	v_cmp_eq_f32_e64 s[36:37], v15, v40
	v_cmp_lt_f32_e64 s[28:29], v15, v40
	s_and_b64 s[36:37], s[34:35], s[36:37]
	s_or_b64 s[28:29], s[28:29], s[36:37]
	v_addc_co_u32_e64 v20, s[28:29], v20, v28, s[28:29]
	v_cmp_eq_f32_e64 s[36:37], v12, v40
	v_cmp_lt_f32_e64 s[28:29], v12, v40
	s_and_b64 s[36:37], s[30:31], s[36:37]
	s_or_b64 s[28:29], s[28:29], s[36:37]
	v_addc_co_u32_e64 v21, s[28:29], v21, v29, s[28:29]
	v_cmp_eq_f32_e64 s[36:37], v13, v40
	v_cmp_lt_f32_e64 s[28:29], v13, v40
	s_and_b64 s[36:37], s[26:27], s[36:37]
	s_or_b64 s[28:29], s[28:29], s[36:37]
	v_addc_co_u32_e64 v22, s[28:29], v22, v30, s[28:29]
	v_cmp_eq_f32_e64 s[36:37], v10, v40
	v_cmp_lt_f32_e64 s[28:29], v10, v40
	s_and_b64 s[36:37], s[22:23], s[36:37]
	s_or_b64 s[28:29], s[28:29], s[36:37]
	v_addc_co_u32_e64 v23, s[28:29], v23, v31, s[28:29]
	v_cmp_eq_f32_e64 s[36:37], v11, v40
	v_cmp_lt_f32_e64 s[28:29], v11, v40
	s_and_b64 s[36:37], s[18:19], s[36:37]
	s_or_b64 s[28:29], s[28:29], s[36:37]
	v_addc_co_u32_e64 v24, s[28:29], v24, v38, s[28:29]
	v_cmp_eq_f32_e64 s[36:37], v16, v40
	v_cmp_lt_f32_e64 s[28:29], v16, v40
	s_and_b64 s[36:37], s[20:21], s[36:37]
	s_or_b64 s[28:29], s[28:29], s[36:37]
	v_addc_co_u32_e64 v25, s[28:29], v25, v39, s[28:29]
	v_cmp_eq_f32_e64 s[36:37], v9, v40
	v_cmp_lt_f32_e64 s[28:29], v9, v40
	s_and_b64 s[24:25], s[24:25], s[36:37]
	s_or_b64 s[24:25], s[28:29], s[24:25]
	v_addc_co_u32_e64 v18, s[24:25], v18, v26, s[24:25]
	ds_bpermute_b32 v26, v17, v16 offset:192
	v_cmp_lt_i32_e64 s[36:37], 27, v32
	ds_bpermute_b32 v17, v17, v9 offset:192
	s_waitcnt lgkmcnt(1)
	v_cmp_eq_f32_e64 s[28:29], v14, v26
	v_cmp_lt_f32_e64 s[24:25], v14, v26
	s_and_b64 s[28:29], s[36:37], s[28:29]
	s_or_b64 s[24:25], s[24:25], s[28:29]
	v_cmp_eq_f32_e64 s[28:29], v15, v26
	v_cndmask_b32_e64 v27, 0, 1, s[24:25]
	v_cmp_lt_f32_e64 s[24:25], v15, v26
	s_and_b64 s[28:29], s[0:1], s[28:29]
	s_or_b64 s[24:25], s[24:25], s[28:29]
	v_cmp_eq_f32_e64 s[28:29], v12, v26
	v_cndmask_b32_e64 v28, 0, 1, s[24:25]
	v_cmp_lt_f32_e64 s[24:25], v12, v26
	s_and_b64 s[28:29], s[34:35], s[28:29]
	s_or_b64 s[24:25], s[24:25], s[28:29]
	v_cmp_eq_f32_e64 s[28:29], v13, v26
	v_cndmask_b32_e64 v29, 0, 1, s[24:25]
	v_cmp_lt_f32_e64 s[24:25], v13, v26
	s_and_b64 s[28:29], s[30:31], s[28:29]
	s_or_b64 s[24:25], s[24:25], s[28:29]
	v_cmp_eq_f32_e64 s[28:29], v10, v26
	v_cndmask_b32_e64 v30, 0, 1, s[24:25]
	v_cmp_lt_f32_e64 s[24:25], v10, v26
	s_and_b64 s[28:29], s[26:27], s[28:29]
	s_or_b64 s[24:25], s[24:25], s[28:29]
	v_cmp_eq_f32_e64 s[28:29], v11, v26
	v_cndmask_b32_e64 v31, 0, 1, s[24:25]
	v_cmp_lt_f32_e64 s[24:25], v11, v26
	s_and_b64 s[28:29], s[22:23], s[28:29]
	s_or_b64 s[24:25], s[24:25], s[28:29]
	v_cmp_eq_f32_e64 s[28:29], v16, v26
	v_cndmask_b32_e64 v38, 0, 1, s[24:25]
	v_cmp_lt_f32_e64 s[24:25], v16, v26
	s_and_b64 s[28:29], s[18:19], s[28:29]
	s_or_b64 s[24:25], s[24:25], s[28:29]
	v_cmp_eq_f32_e64 s[28:29], v9, v26
	v_cndmask_b32_e64 v39, 0, 1, s[24:25]
	v_cmp_lt_f32_e64 s[24:25], v9, v26
	s_and_b64 s[20:21], s[20:21], s[28:29]
	s_or_b64 s[20:21], s[24:25], s[20:21]
	s_waitcnt lgkmcnt(0)
	v_cmp_eq_f32_e64 s[24:25], v14, v17
	v_cmp_lt_i32_e64 s[28:29], 31, v32
	v_cndmask_b32_e64 v26, 0, 1, s[20:21]
	v_cmp_lt_f32_e64 s[20:21], v14, v17
	s_and_b64 s[24:25], s[28:29], s[24:25]
	s_or_b64 s[20:21], s[20:21], s[24:25]
	v_addc_co_u32_e64 v14, s[20:21], v19, v27, s[20:21]
	v_cmp_eq_f32_e64 s[24:25], v15, v17
	v_cmp_lt_f32_e64 s[20:21], v15, v17
	s_and_b64 s[24:25], s[36:37], s[24:25]
	s_or_b64 s[20:21], s[20:21], s[24:25]
	v_addc_co_u32_e64 v15, s[20:21], v20, v28, s[20:21]
	v_cmp_eq_f32_e64 s[24:25], v12, v17
	v_cmp_lt_f32_e64 s[20:21], v12, v17
	s_and_b64 s[0:1], s[0:1], s[24:25]
	s_or_b64 s[0:1], s[20:21], s[0:1]
	v_addc_co_u32_e64 v12, s[0:1], v21, v29, s[0:1]
	v_cmp_eq_f32_e64 s[20:21], v13, v17
	v_cmp_lt_f32_e64 s[0:1], v13, v17
	s_and_b64 s[20:21], s[34:35], s[20:21]
	s_or_b64 s[0:1], s[0:1], s[20:21]
	v_addc_co_u32_e64 v13, s[0:1], v22, v30, s[0:1]
	v_cmp_eq_f32_e64 s[20:21], v10, v17
	v_cmp_lt_f32_e64 s[0:1], v10, v17
	s_and_b64 s[20:21], s[30:31], s[20:21]
	s_or_b64 s[0:1], s[0:1], s[20:21]
	v_addc_co_u32_e64 v10, s[0:1], v23, v31, s[0:1]
	v_cmp_eq_f32_e64 s[20:21], v11, v17
	v_cmp_lt_f32_e64 s[0:1], v11, v17
	s_and_b64 s[20:21], s[26:27], s[20:21]
	s_or_b64 s[0:1], s[0:1], s[20:21]
	v_addc_co_u32_e64 v11, s[0:1], v24, v38, s[0:1]
	v_cmp_eq_f32_e64 s[20:21], v16, v17
	v_cmp_lt_f32_e64 s[0:1], v16, v17
	s_and_b64 s[20:21], s[22:23], s[20:21]
	s_or_b64 s[0:1], s[0:1], s[20:21]
	v_addc_co_u32_e64 v16, s[0:1], v25, v39, s[0:1]
	v_cmp_eq_f32_e64 s[20:21], v9, v17
	v_cmp_lt_f32_e64 s[0:1], v9, v17
	s_and_b64 s[18:19], s[18:19], s[20:21]
	s_or_b64 s[0:1], s[0:1], s[18:19]
	v_addc_co_u32_e64 v9, s[0:1], v18, v26, s[0:1]
	v_cmp_lt_u32_e64 s[0:1], 7, v14
	s_or_b64 s[0:1], vcc, s[0:1]
	v_lshlrev_b32_e64 v14, v32, 1
	v_cmp_lt_u32_e32 vcc, 7, v15
	v_cndmask_b32_e64 v14, v14, 0, s[0:1]
	s_or_b64 s[0:1], s[4:5], vcc
	v_cmp_lt_u32_e32 vcc, 7, v12
	v_cndmask_b32_e64 v2, v2, 0, s[0:1]
	s_or_b64 s[0:1], s[6:7], vcc
	v_cmp_lt_u32_e32 vcc, 7, v13
	v_cndmask_b32_e64 v3, v3, 0, s[0:1]
	s_or_b64 s[0:1], s[8:9], vcc
	v_or_b32_e32 v2, v2, v14
	v_cndmask_b32_e64 v4, v4, 0, s[0:1]
	v_cmp_lt_u32_e32 vcc, 7, v10
	v_or3_b32 v2, v2, v3, v4
	s_or_b64 s[0:1], s[10:11], vcc
	v_lshlrev_b32_e64 v3, v5, 1
	v_cmp_lt_u32_e32 vcc, 7, v11
	v_cndmask_b32_e64 v3, v3, 0, s[0:1]
	s_or_b64 s[0:1], s[12:13], vcc
	v_lshlrev_b32_e64 v4, v6, 1
	v_cndmask_b32_e64 v4, v4, 0, s[0:1]
	v_cmp_lt_u32_e32 vcc, 7, v16
	v_or3_b32 v2, v2, v3, v4
	s_or_b64 s[0:1], s[14:15], vcc
	v_lshlrev_b32_e64 v3, v7, 1
	v_cmp_lt_u32_e32 vcc, 7, v9
	v_cndmask_b32_e64 v3, v3, 0, s[0:1]
	s_or_b64 s[0:1], s[16:17], vcc
	v_lshlrev_b32_e64 v4, v8, 1
	v_cndmask_b32_e64 v4, v4, 0, s[0:1]
	v_or3_b32 v2, v2, v3, v4
	ds_bpermute_b32 v3, v193, v2
	v_cmp_lt_i32_e32 vcc, v214, v213
	s_waitcnt lgkmcnt(0)
	v_or_b32_e32 v2, v2, v3
	ds_bpermute_b32 v3, v194, v2
	s_waitcnt lgkmcnt(0)
	v_or_b32_e32 v195, v2, v3
	v_cndmask_b32_e32 v2, v211, v214, vcc
	v_lshlrev_b32_e32 v2, 2, v2
	ds_bpermute_b32 v2, v2, v195
	v_cmp_lt_i32_e32 vcc, v215, v213
	s_waitcnt lgkmcnt(0)
	v_or_b32_e32 v2, v195, v2
	v_cndmask_b32_e32 v3, v211, v215, vcc
	v_lshlrev_b32_e32 v3, 2, v3
	ds_bpermute_b32 v3, v3, v2
	v_cmp_lt_i32_e32 vcc, v216, v213
	s_waitcnt lgkmcnt(0)
	v_or_b32_e32 v2, v2, v3
	v_cndmask_b32_e32 v3, v211, v216, vcc
	v_lshlrev_b32_e32 v3, 2, v3
	ds_bpermute_b32 v3, v3, v2
	v_cmp_lt_i32_e32 vcc, v217, v213
	s_waitcnt lgkmcnt(0)
	v_or_b32_e32 v2, v2, v3
	v_cndmask_b32_e32 v3, v211, v217, vcc
	v_lshlrev_b32_e32 v3, 2, v3
	ds_bpermute_b32 v3, v3, v2
	s_waitcnt lgkmcnt(0)
	v_or_b32_e32 v40, v2, v3
	s_add_u32 s16, s86, 0x29200000
	v_lshl_add_u64 v[0:1], v[146:147], 1, v[0:1]
	s_mov_b64 s[0:1], 0x15200000
	s_addc_u32 s17, s87, 0
	v_lshl_add_u64 v[38:39], v[0:1], 0, s[0:1]
	s_lshl_b32 s82, s2, 9
	v_lshl_add_u64 v[28:29], v[38:39], 0, s[82:83]
	global_load_dwordx4 v[0:3], v[28:29], off
	global_load_dwordx4 v[4:7], v[28:29], off offset:64
	global_load_dwordx4 v[8:11], v[28:29], off offset:128
	global_load_dwordx4 v[12:15], v[28:29], off offset:192
	global_load_dwordx4 v[16:19], v[28:29], off offset:256
	global_load_dwordx4 v[20:23], v[28:29], off offset:320
	global_load_dwordx4 v[24:27], v[28:29], off offset:384
	s_nop 0
	global_load_dwordx4 v[28:31], v[28:29], off offset:448
	v_lshlrev_b64 v[32:33], 3, v[32:33]
	v_sub_co_u32_e32 v32, vcc, 0, v32
	v_mul_f32_e32 v196, 0x3fb8aa3b, v34
	v_readfirstlane_b32 s18, v40
	v_subb_co_u32_e32 v33, vcc, 0, v33, vcc
	v_mov_b32_e32 v34, 0x1ff
	s_ff1_i32_b32 s0, s18
	v_sub_co_u32_e32 v34, vcc, s81, v34
	s_ashr_i32 s95, s94, 31
	s_lshl_b32 s19, s0, 6
	v_readfirstlane_b32 s0, v34
	s_lshl_b64 s[6:7], s[94:95], 19
	s_lshl_b32 s4, s2, 6
	s_lshl_b64 s[8:9], s[84:85], 18
	s_sub_i32 s2, s81, 17
	s_add_i32 s20, s18, -1
	s_and_b32 s5, s0, 0xffffffe0
	v_lshl_add_u64 v[32:33], v[38:39], 0, v[32:33]
	s_and_b64 s[0:1], vcc, exec
	v_lshlrev_b32_e32 v34, 11, v190
	v_mul_f32_e32 v197, 0x3fb8aa3b, v35
	v_mul_f32_e32 v198, 0x3fb8aa3b, v36
	v_mul_f32_e32 v199, 0x3fb8aa3b, v37
	s_cselect_b32 s21, 0, s5
	v_add_u32_e32 v200, 0xfffffe01, v191
	v_lshl_add_u64 v[150:151], v[32:33], 0, s[82:83]
	s_mov_b64 s[10:11], 0
	s_lshl_b32 s22, s4, 1
	v_lshlrev_b32_e32 v152, 1, v34
	v_readlane_b32 s56, v252, 21
	v_readlane_b32 s57, v252, 22
	s_branch .LBB0_191

.LBB0_191:
	s_xor_b64 s[12:13], s[10:11], -1
	s_and_b64 s[0:1], s[10:11], exec
	s_cselect_b32 s82, s21, s19
	s_cmp_lt_i32 s82, 0
	s_cbranch_scc1 .LBB0_202
	s_lshl_b32 s0, s38, 25
	s_add_u32 s4, s16, s0
	s_addc_u32 s5, s17, 0
	s_add_u32 s0, s4, s6
	s_addc_u32 s1, s5, s7
	s_add_u32 s0, s0, s22
	v_or_b32_e32 v32, s82, v190
	s_addc_u32 s1, s1, 0
	v_or_b32_e32 v160, 16, v32
	v_mov_b32_e32 v33, v161
	v_lshl_add_u64 v[158:159], v[146:147], 1, s[0:1]
	v_lshlrev_b64 v[34:35], 8, v[160:161]
	v_lshlrev_b64 v[32:33], 8, v[32:33]
	v_lshl_add_u64 v[34:35], v[158:159], 0, v[34:35]
	v_lshl_add_u64 v[32:33], v[158:159], 0, v[32:33]
	global_load_dwordx4 v[96:99], v[34:35], off offset:64
	global_load_dwordx4 v[100:103], v[34:35], off
	global_load_dwordx4 v[104:107], v[32:33], off offset:64
	global_load_dwordx4 v[108:111], v[32:33], off
	s_add_u32 s0, s4, s8
	s_addc_u32 s1, s5, s9
	v_lshl_add_u64 v[32:33], v[144:145], 1, s[0:1]
	v_mov_b32_e32 v153, v161
	s_and_b64 s[4:5], s[10:11], exec
	v_lshl_add_u64 v[32:33], v[32:33], 0, v[152:153]
	s_mov_b64 s[0:1], 0x1000000
	s_cselect_b32 s4, -1, s20
	v_cndmask_b32_e64 v160, 0, v200, s[10:11]
	v_lshl_add_u64 v[170:171], v[32:33], 0, s[0:1]
	v_mov_b32_e32 v32, 0
	s_and_b32 s4, s4, s18
	v_add_u32_e32 v153, -1, v160
	v_mov_b32_e32 v172, 0xf149f2ca
	v_mov_b32_e32 v177, 0xf149f2ca
	v_mov_b32_e32 v175, 0xf149f2ca
	v_mov_b32_e32 v173, 0xf149f2ca
	v_mov_b32_e32 v33, v32
	v_mov_b32_e32 v34, v32
	v_mov_b32_e32 v35, v32
	v_mov_b32_e32 v36, v32
	v_mov_b32_e32 v37, v32
	v_mov_b32_e32 v38, v32
	v_mov_b32_e32 v39, v32
	v_mov_b32_e32 v40, v32
	v_mov_b32_e32 v41, v32
	v_mov_b32_e32 v42, v32
	v_mov_b32_e32 v43, v32
	v_mov_b32_e32 v44, v32
	v_mov_b32_e32 v45, v32
	v_mov_b32_e32 v46, v32
	v_mov_b32_e32 v47, v32
	v_mov_b32_e32 v48, v32
	v_mov_b32_e32 v49, v32
	v_mov_b32_e32 v50, v32
	v_mov_b32_e32 v51, v32
	v_mov_b32_e32 v52, v32
	v_mov_b32_e32 v53, v32
	v_mov_b32_e32 v54, v32
	v_mov_b32_e32 v55, v32
	v_mov_b32_e32 v56, v32
	v_mov_b32_e32 v57, v32
	v_mov_b32_e32 v58, v32
	v_mov_b32_e32 v59, v32
	v_mov_b32_e32 v60, v32
	v_mov_b32_e32 v61, v32
	v_mov_b32_e32 v62, v32
	v_mov_b32_e32 v63, v32
	v_mov_b32_e32 v64, v32
	v_mov_b32_e32 v65, v32
	v_mov_b32_e32 v66, v32
	v_mov_b32_e32 v67, v32
	v_mov_b32_e32 v68, v32
	v_mov_b32_e32 v69, v32
	v_mov_b32_e32 v70, v32
	v_mov_b32_e32 v71, v32
	v_mov_b32_e32 v72, v32
	v_mov_b32_e32 v73, v32
	v_mov_b32_e32 v74, v32
	v_mov_b32_e32 v75, v32
	v_mov_b32_e32 v76, v32
	v_mov_b32_e32 v77, v32
	v_mov_b32_e32 v78, v32
	v_mov_b32_e32 v79, v32
	v_mov_b32_e32 v80, v32
	v_mov_b32_e32 v81, v32
	v_mov_b32_e32 v82, v32
	v_mov_b32_e32 v83, v32
	v_mov_b32_e32 v84, v32
	v_mov_b32_e32 v85, v32
	v_mov_b32_e32 v86, v32
	v_mov_b32_e32 v87, v32
	v_mov_b32_e32 v88, v32
	v_mov_b32_e32 v89, v32
	v_mov_b32_e32 v90, v32
	v_mov_b32_e32 v91, v32
	v_mov_b32_e32 v92, v32
	v_mov_b32_e32 v93, v32
	v_mov_b32_e32 v94, v32
	v_mov_b32_e32 v95, v32
	v_mov_b32_e32 v156, v32
	v_mov_b32_e32 v157, v32
	v_mov_b32_e32 v154, v32
	v_mov_b32_e32 v155, v32
	s_andn2_b64 vcc, exec, s[12:13]
	s_mov_b64 s[0:1], -1
	s_cbranch_vccnz .LBB0_198

.LBB0_200:
	s_lshr_b32 s0, s82, 6
	s_lshl_b32 s0, 1, s0
	v_and_b32_e32 v112, s0, v195
	v_cmp_ne_u32_e32 vcc, 0, v112
	s_or_b64 s[14:15], s[10:11], vcc
	s_cmp_lt_i32 s23, 0
	s_cselect_b64 s[4:5], -1, 0
	s_and_b64 s[0:1], s[4:5], exec
	s_cselect_b32 s0, s82, s23
	v_add_u32_e32 v120, s0, v190
	v_ashrrev_i32_e32 v121, 31, v120
	v_lshlrev_b64 v[112:113], 8, v[120:121]
	v_add_u32_e32 v120, 16, v120
	v_ashrrev_i32_e32 v121, 31, v120
	v_lshl_add_u64 v[128:129], s[82:83], 1, v[170:171]
	v_lshlrev_b64 v[120:121], 8, v[120:121]
	v_add_co_u32_e32 v130, vcc, s3, v128
	v_lshl_add_u64 v[116:117], v[158:159], 0, v[112:113]
	v_lshl_add_u64 v[124:125], v[158:159], 0, v[120:121]
	v_addc_co_u32_e32 v131, vcc, 0, v129, vcc
	s_mov_b32 s0, 0x20000
	global_load_dwordx4 v[112:115], v[116:117], off
	s_nop 0
	global_load_dwordx4 v[116:119], v[116:117], off offset:64
	s_nop 0
	global_load_dwordx4 v[120:123], v[124:125], off
	s_nop 0
	global_load_dwordx4 v[124:127], v[124:125], off offset:64
	s_nop 0
	global_load_dwordx2 v[136:137], v[128:129], off
	global_load_dwordx2 v[138:139], v[128:129], off offset:32
	global_load_dwordx2 v[140:141], v[130:131], off
	global_load_dwordx2 v[142:143], v[130:131], off offset:32
	v_add_co_u32_e32 v130, vcc, s0, v128
	s_mov_b32 s0, 0x30000
	s_nop 0
	v_addc_co_u32_e32 v131, vcc, 0, v129, vcc
	global_load_dwordx2 v[132:133], v[130:131], off
	global_load_dwordx2 v[134:135], v[130:131], off offset:32
	v_add_co_u32_e32 v130, vcc, s0, v128
	v_add_u32_e32 v166, s82, v144
	s_nop 0
	v_addc_co_u32_e32 v131, vcc, 0, v129, vcc
	global_load_dwordx2 v[128:129], v[130:131], off
	s_nop 0
	global_load_dwordx2 v[130:131], v[130:131], off offset:32
	v_cmp_ge_i32_e32 vcc, v166, v160
	v_cmp_lt_i32_e64 s[0:1], v191, v166
	v_add_u32_e32 v167, 16, v166
	s_and_b64 vcc, s[14:15], vcc
	v_cndmask_b32_e64 v168, 0, v223, s[0:1]
	v_cndmask_b32_e32 v179, v223, v168, vcc
	v_cmp_ge_i32_e32 vcc, v167, v160
	v_cmp_gt_i32_e64 s[0:1], v167, v191
	s_and_b64 vcc, s[14:15], vcc
	v_add_u32_e32 v168, 18, v166
	v_cndmask_b32_e64 v167, 0, v223, s[0:1]
	v_cndmask_b32_e32 v181, v223, v167, vcc
	v_cmp_ge_i32_e32 vcc, v166, v153
	v_cmp_gt_i32_e64 s[0:1], v191, v166
	s_and_b64 s[0:1], s[0:1], vcc
	v_add_u32_e32 v167, 17, v166
	s_and_b64 s[0:1], s[14:15], s[0:1]
	v_cndmask_b32_e64 v183, v223, 0, s[0:1]
	v_cmp_ge_i32_e32 vcc, v167, v160
	v_cmp_gt_i32_e64 s[0:1], v167, v191
	s_and_b64 vcc, s[14:15], vcc
	s_waitcnt vmcnt(0) lgkmcnt(0)
	v_mfma_f32_16x16x32_bf16 v[228:231], v[108:111], v[0:3], 0
	v_cndmask_b32_e64 v167, 0, v223, s[0:1]
	v_cndmask_b32_e32 v185, v223, v167, vcc
	v_add_u32_e32 v167, 2, v166
	v_cmp_ge_i32_e32 vcc, v167, v160
	v_cmp_gt_i32_e64 s[0:1], v167, v191
	s_and_b64 vcc, s[14:15], vcc
	v_mfma_f32_16x16x32_bf16 v[232:235], v[100:103], v[0:3], 0
	v_cndmask_b32_e64 v167, 0, v223, s[0:1]
	v_cndmask_b32_e32 v187, v223, v167, vcc
	v_cmp_ge_i32_e32 vcc, v168, v160
	v_cmp_gt_i32_e64 s[0:1], v168, v191
	s_and_b64 vcc, s[14:15], vcc
	v_add_u32_e32 v168, 19, v166
	v_cndmask_b32_e64 v167, 0, v223, s[0:1]
	v_cndmask_b32_e32 v189, v223, v167, vcc
	v_add_u32_e32 v167, 3, v166
	v_sub_u32_e32 v166, v191, v166
	v_cvt_f32_i32_e32 v204, v166
	v_cmp_ge_i32_e32 vcc, v167, v160
	v_cmp_gt_i32_e64 s[0:1], v167, v191
	s_and_b64 vcc, s[14:15], vcc
	v_mfma_f32_16x16x32_bf16 v[228:231], v[104:107], v[4:7], v[228:231]
	v_cndmask_b32_e64 v167, 0, v223, s[0:1]
	v_cndmask_b32_e32 v202, v223, v167, vcc
	v_cmp_ge_i32_e32 vcc, v168, v160
	v_mfma_f32_16x16x32_bf16 v[232:235], v[96:99], v[4:7], v[232:235]
	v_cmp_gt_i32_e64 s[0:1], v168, v191
	s_and_b64 vcc, s[14:15], vcc
	v_mul_f32_e64 v166, -v196, v204
	v_cndmask_b32_e64 v167, 0, v223, s[0:1]
	v_cndmask_b32_e32 v203, v223, v167, vcc
	v_fma_f32 v167, 0, v196, v166
	v_fmamk_f32 v168, v196, 0x41800000, v166
	v_fma_f32 v174, -v196, v204, v196
	v_fmamk_f32 v176, v196, 0x41880000, v166
	v_fmac_f32_e32 v167, 0x3e38aa3b, v228
	v_fmac_f32_e32 v168, 0x3e38aa3b, v232
	v_fmac_f32_e32 v174, 0x3e38aa3b, v229
	v_fmac_f32_e32 v176, 0x3e38aa3b, v233
	v_add_f32_e32 v167, v179, v167
	v_add_f32_e32 v168, v181, v168
	v_add_f32_e32 v174, v183, v174
	v_add_f32_e32 v182, v185, v176
	v_max_f32_e32 v169, v167, v168
	v_max_f32_e32 v176, v174, v182
	v_max3_f32 v169, v169, s73, v176
	v_fma_f32 v176, 2.0, v196, v166
	v_fmamk_f32 v178, v196, 0x41900000, v166
	v_fmamk_f32 v180, v196, 0x40400000, v166
	v_fmac_f32_e32 v166, 0x41980000, v196
	v_fmac_f32_e32 v176, 0x3e38aa3b, v230
	v_fmac_f32_e32 v178, 0x3e38aa3b, v234
	v_fmac_f32_e32 v180, 0x3e38aa3b, v231
	v_fmac_f32_e32 v166, 0x3e38aa3b, v235
	v_add_f32_e32 v176, v187, v176
	v_add_f32_e32 v186, v189, v178
	v_add_f32_e32 v180, v202, v180
	v_add_f32_e32 v166, v203, v166
	v_max_f32_e32 v178, v176, v186
	v_max_f32_e32 v184, v180, v166
	v_max3_f32 v169, v169, v178, v184
	ds_bpermute_b32 v178, v193, v169
	v_mfma_f32_16x16x32_bf16 v[232:235], v[100:103], v[8:11], 0
	v_fma_f32 v205, -v197, v204, v197
	s_waitcnt lgkmcnt(0)
	v_max_f32_e32 v178, v178, v178
	v_max_f32_e32 v169, v169, v178
	ds_bpermute_b32 v178, v194, v169
	v_mfma_f32_16x16x32_bf16 v[232:235], v[96:99], v[12:15], v[232:235]
	s_waitcnt lgkmcnt(0)
	v_max3_f32 v201, v172, v169, v178
	v_sub_f32_e32 v167, v167, v201
	v_sub_f32_e32 v169, v172, v201
	v_exp_f32_e32 v172, v167
	v_sub_f32_e32 v167, v174, v201
	v_exp_f32_e32 v174, v167
	v_sub_f32_e32 v167, v176, v201
	v_exp_f32_e32 v176, v167
	v_sub_f32_e32 v167, v180, v201
	v_exp_f32_e32 v178, v167
	v_sub_f32_e32 v167, v168, v201
	v_exp_f32_e32 v180, v167
	v_sub_f32_e32 v167, v182, v201
	v_exp_f32_e32 v184, v167
	v_sub_f32_e32 v167, v186, v201
	v_sub_f32_e32 v166, v166, v201
	v_exp_f32_e32 v186, v167
	v_exp_f32_e32 v188, v166
	v_exp_f32_e32 v182, v169
	v_cvt_pk_bf16_f32 v228, v172, v174
	v_cvt_pk_bf16_f32 v229, v176, v178
	v_cvt_pk_bf16_f32 v230, v180, v184
	v_cvt_pk_bf16_f32 v231, v186, v188
	v_pk_mul_f32 v[94:95], v[94:95], v[182:183] op_sel_hi:[1,0]
	v_pk_mul_f32 v[92:93], v[92:93], v[182:183] op_sel_hi:[1,0]
	v_pk_mul_f32 v[90:91], v[90:91], v[182:183] op_sel_hi:[1,0]
	v_pk_mul_f32 v[88:89], v[88:89], v[182:183] op_sel_hi:[1,0]
	v_pk_mul_f32 v[86:87], v[86:87], v[182:183] op_sel_hi:[1,0]
	v_pk_mul_f32 v[84:85], v[84:85], v[182:183] op_sel_hi:[1,0]
	v_pk_mul_f32 v[82:83], v[82:83], v[182:183] op_sel_hi:[1,0]
	v_pk_mul_f32 v[80:81], v[80:81], v[182:183] op_sel_hi:[1,0]
	v_mfma_f32_16x16x32_bf16 v[92:95], v[136:139], v[228:231], v[92:95]
	v_mul_f32_e64 v166, -v197, v204
	v_fma_f32 v167, 0, v197, v166
	v_fmamk_f32 v168, v197, 0x41800000, v166
	v_mfma_f32_16x16x32_bf16 v[88:91], v[140:143], v[228:231], v[88:91]
	v_fmac_f32_e32 v168, 0x3e38aa3b, v232
	v_add_f32_e32 v169, v181, v168
	v_mfma_f32_16x16x32_bf16 v[84:87], v[132:135], v[228:231], v[84:87]
	v_mfma_f32_16x16x32_bf16 v[80:83], v[128:131], v[228:231], v[80:83]
	v_mfma_f32_16x16x32_bf16 v[228:231], v[108:111], v[8:11], 0
	v_mfma_f32_16x16x32_bf16 v[228:231], v[104:107], v[12:15], v[228:231]
	s_nop 7
	v_fmac_f32_e32 v205, 0x3e38aa3b, v229
	v_add_f32_e32 v206, v183, v205
	v_fmamk_f32 v205, v197, 0x41880000, v166
	v_fmac_f32_e32 v167, 0x3e38aa3b, v228
	v_fmac_f32_e32 v205, 0x3e38aa3b, v233
	v_add_f32_e32 v167, v179, v167
	v_add_f32_e32 v207, v185, v205
	v_max_f32_e32 v168, v167, v169
	v_max_f32_e32 v205, v206, v207
	v_max3_f32 v168, v168, s73, v205
	v_fma_f32 v205, 2.0, v197, v166
	v_fmac_f32_e32 v205, 0x3e38aa3b, v230
	v_add_f32_e32 v228, v187, v205
	v_fmamk_f32 v205, v197, 0x41900000, v166
	v_fmamk_f32 v230, v197, 0x40400000, v166
	v_fmac_f32_e32 v166, 0x41980000, v197
	v_fmac_f32_e32 v205, 0x3e38aa3b, v234
	v_fmac_f32_e32 v230, 0x3e38aa3b, v231
	v_fmac_f32_e32 v166, 0x3e38aa3b, v235
	v_add_f32_e32 v229, v189, v205
	v_add_f32_e32 v230, v202, v230
	v_add_f32_e32 v231, v203, v166
	v_max_f32_e32 v205, v228, v229
	v_max_f32_e32 v166, v230, v231
	v_max3_f32 v166, v168, v205, v166
	ds_bpermute_b32 v168, v193, v166
	s_waitcnt lgkmcnt(0)
	v_max_f32_e32 v168, v168, v168
	v_max_f32_e32 v166, v166, v168
	ds_bpermute_b32 v168, v194, v166
	s_waitcnt lgkmcnt(0)
	v_max3_f32 v205, v177, v166, v168
	v_sub_f32_e32 v166, v167, v205
	v_sub_f32_e32 v167, v206, v205
	v_exp_f32_e32 v168, v167
	v_sub_f32_e32 v167, v228, v205
	v_exp_f32_e32 v236, v167
	v_sub_f32_e32 v167, v230, v205
	v_exp_f32_e32 v238, v167
	v_sub_f32_e32 v167, v169, v205
	v_exp_f32_e32 v240, v167
	v_sub_f32_e32 v167, v207, v205
	v_exp_f32_e32 v242, v167
	v_sub_f32_e32 v167, v229, v205
	v_sub_f32_e32 v177, v177, v205
	v_exp_f32_e32 v244, v167
	v_sub_f32_e32 v167, v231, v205
	v_exp_f32_e32 v166, v166
	v_exp_f32_e32 v246, v167
	v_exp_f32_e32 v248, v177
	v_cvt_pk_bf16_f32 v229, v236, v238
	v_cvt_pk_bf16_f32 v228, v166, v168
	v_cvt_pk_bf16_f32 v230, v240, v242
	v_cvt_pk_bf16_f32 v231, v244, v246
	v_pk_mul_f32 v[78:79], v[78:79], v[248:249] op_sel_hi:[1,0]
	v_pk_mul_f32 v[76:77], v[76:77], v[248:249] op_sel_hi:[1,0]
	v_pk_mul_f32 v[74:75], v[74:75], v[248:249] op_sel_hi:[1,0]
	v_pk_mul_f32 v[72:73], v[72:73], v[248:249] op_sel_hi:[1,0]
	v_pk_mul_f32 v[70:71], v[70:71], v[248:249] op_sel_hi:[1,0]
	v_pk_mul_f32 v[68:69], v[68:69], v[248:249] op_sel_hi:[1,0]
	v_pk_mul_f32 v[66:67], v[66:67], v[248:249] op_sel_hi:[1,0]
	v_pk_mul_f32 v[64:65], v[64:65], v[248:249] op_sel_hi:[1,0]
	v_mfma_f32_16x16x32_bf16 v[76:79], v[136:139], v[228:231], v[76:79]
	v_mfma_f32_16x16x32_bf16 v[72:75], v[140:143], v[228:231], v[72:75]
	v_mfma_f32_16x16x32_bf16 v[68:71], v[132:135], v[228:231], v[68:71]
	v_mfma_f32_16x16x32_bf16 v[64:67], v[128:131], v[228:231], v[64:67]
	v_mfma_f32_16x16x32_bf16 v[228:231], v[108:111], v[16:19], 0
	v_mul_f32_e64 v167, -v198, v204
	v_fma_f32 v169, 0, v198, v167
	v_fmamk_f32 v177, v198, 0x41800000, v167
	v_mfma_f32_16x16x32_bf16 v[232:235], v[100:103], v[16:19], 0
	v_fma_f32 v207, -v198, v204, v198
	v_mfma_f32_16x16x32_bf16 v[108:111], v[108:111], v[24:27], 0
	v_mfma_f32_16x16x32_bf16 v[100:103], v[100:103], v[24:27], 0
	v_mfma_f32_16x16x32_bf16 v[228:231], v[104:107], v[20:23], v[228:231]
	v_mfma_f32_16x16x32_bf16 v[232:235], v[96:99], v[20:23], v[232:235]
	v_mfma_f32_16x16x32_bf16 v[104:107], v[104:107], v[28:31], v[108:111]
	s_nop 5
	v_fmac_f32_e32 v169, 0x3e38aa3b, v228
	v_fmamk_f32 v228, v198, 0x41880000, v167
	v_fmac_f32_e32 v177, 0x3e38aa3b, v232
	v_mfma_f32_16x16x32_bf16 v[96:99], v[96:99], v[28:31], v[100:103]
	v_fmac_f32_e32 v207, 0x3e38aa3b, v229
	v_fmac_f32_e32 v228, 0x3e38aa3b, v233
	v_add_f32_e32 v169, v179, v169
	v_mul_f32_e64 v100, -v199, v204
	v_fma_f32 v101, 0, v199, v100
	v_fmac_f32_e32 v101, 0x3e38aa3b, v104
	v_fmamk_f32 v102, v199, 0x41800000, v100
	v_fma_f32 v103, -v199, v204, v199
	v_fmamk_f32 v104, v199, 0x41880000, v100
	v_add_f32_e32 v177, v181, v177
	v_add_f32_e32 v207, v183, v207
	v_add_f32_e32 v228, v185, v228
	v_fmac_f32_e32 v102, 0x3e38aa3b, v96
	v_fmac_f32_e32 v103, 0x3e38aa3b, v105
	v_fmac_f32_e32 v104, 0x3e38aa3b, v97
	v_max_f32_e32 v206, v169, v177
	v_max_f32_e32 v229, v207, v228
	v_add_f32_e32 v101, v179, v101
	v_add_f32_e32 v96, v181, v102
	v_add_f32_e32 v103, v183, v103
	v_add_f32_e32 v97, v185, v104
	v_max3_f32 v206, v206, s73, v229
	v_fma_f32 v229, 2.0, v198, v167
	v_max_f32_e32 v102, v101, v96
	v_max_f32_e32 v104, v103, v97
	v_fmac_f32_e32 v229, 0x3e38aa3b, v230
	v_fmamk_f32 v230, v198, 0x41900000, v167
	v_fmamk_f32 v233, v198, 0x40400000, v167
	v_fmac_f32_e32 v167, 0x41980000, v198
	v_max3_f32 v102, v102, s73, v104
	v_fma_f32 v104, 2.0, v199, v100
	v_fmac_f32_e32 v230, 0x3e38aa3b, v234
	v_fmac_f32_e32 v233, 0x3e38aa3b, v231
	v_fmac_f32_e32 v167, 0x3e38aa3b, v235
	v_fmac_f32_e32 v104, 0x3e38aa3b, v106
	v_fmamk_f32 v105, v199, 0x41900000, v100
	v_fmamk_f32 v106, v199, 0x40400000, v100
	v_fmac_f32_e32 v100, 0x41980000, v199
	v_add_f32_e32 v229, v187, v229
	v_add_f32_e32 v230, v189, v230
	v_add_f32_e32 v231, v202, v233
	v_add_f32_e32 v233, v203, v167
	v_fmac_f32_e32 v105, 0x3e38aa3b, v98
	v_fmac_f32_e32 v106, 0x3e38aa3b, v107
	v_fmac_f32_e32 v100, 0x3e38aa3b, v99
	v_max_f32_e32 v232, v229, v230
	v_max_f32_e32 v167, v231, v233
	v_add_f32_e32 v104, v187, v104
	v_add_f32_e32 v98, v189, v105
	v_add_f32_e32 v106, v202, v106
	v_add_f32_e32 v99, v203, v100
	v_max3_f32 v167, v206, v232, v167
	v_max_f32_e32 v105, v104, v98
	v_max_f32_e32 v100, v106, v99
	ds_bpermute_b32 v206, v193, v167
	v_max3_f32 v100, v102, v105, v100
	ds_bpermute_b32 v102, v193, v100
	s_waitcnt lgkmcnt(1)
	v_max_f32_e32 v206, v206, v206
	v_max_f32_e32 v167, v167, v206
	s_waitcnt lgkmcnt(0)
	v_max_f32_e32 v102, v102, v102
	ds_bpermute_b32 v206, v194, v167
	v_max_f32_e32 v100, v100, v102
	ds_bpermute_b32 v102, v194, v100
	s_waitcnt lgkmcnt(1)
	v_max3_f32 v206, v175, v167, v206
	v_sub_f32_e32 v177, v177, v206
	s_waitcnt lgkmcnt(0)
	v_max3_f32 v202, v173, v100, v102
	v_sub_f32_e32 v167, v169, v206
	v_exp_f32_e32 v241, v177
	v_sub_f32_e32 v177, v228, v206
	v_sub_f32_e32 v101, v101, v202
	v_sub_f32_e32 v175, v175, v206
	v_exp_f32_e32 v167, v167
	v_sub_f32_e32 v169, v207, v206
	v_exp_f32_e32 v243, v177
	v_sub_f32_e32 v177, v230, v206
	v_sub_f32_e32 v100, v173, v202
	v_exp_f32_e32 v173, v101
	v_sub_f32_e32 v101, v103, v202
	v_sub_f32_e32 v96, v96, v202
	v_exp_f32_e32 v169, v169
	v_sub_f32_e32 v207, v229, v206
	v_exp_f32_e32 v245, v177
	v_sub_f32_e32 v177, v233, v206
	v_exp_f32_e32 v249, v175
	v_exp_f32_e32 v175, v101
	v_sub_f32_e32 v101, v104, v202
	v_exp_f32_e32 v181, v96
	v_sub_f32_e32 v96, v97, v202
	v_exp_f32_e32 v237, v207
	v_sub_f32_e32 v207, v231, v206
	v_exp_f32_e32 v247, v177
	v_exp_f32_e32 v177, v101
	v_sub_f32_e32 v101, v106, v202
	v_exp_f32_e32 v185, v96
	v_sub_f32_e32 v96, v98, v202
	v_exp_f32_e32 v239, v207
	v_exp_f32_e32 v179, v101
	v_exp_f32_e32 v187, v96
	v_sub_f32_e32 v96, v99, v202
	v_pk_add_f32 v[228:229], v[166:167], 0 op_sel_hi:[1,0]
	v_exp_f32_e32 v189, v96
	v_pk_add_f32 v[96:97], v[172:173], 0 op_sel_hi:[1,0]
	v_pk_add_f32 v[228:229], v[168:169], v[228:229]
	v_pk_add_f32 v[96:97], v[174:175], v[96:97]
	v_pk_add_f32 v[228:229], v[236:237], v[228:229]
	v_pk_add_f32 v[96:97], v[176:177], v[96:97]
	v_pk_add_f32 v[228:229], v[238:239], v[228:229]
	v_exp_f32_e32 v183, v100
	v_pk_add_f32 v[96:97], v[178:179], v[96:97]
	v_pk_add_f32 v[228:229], v[240:241], v[228:229]
	v_pk_add_f32 v[96:97], v[180:181], v[96:97]
	v_pk_add_f32 v[228:229], v[242:243], v[228:229]
	v_pk_add_f32 v[96:97], v[184:185], v[96:97]
	v_pk_add_f32 v[228:229], v[244:245], v[228:229]
	v_pk_add_f32 v[96:97], v[186:187], v[96:97]
	v_pk_add_f32 v[228:229], v[246:247], v[228:229]
	v_mov_b32_e32 v166, v249
	v_pk_add_f32 v[96:97], v[188:189], v[96:97]
	v_mov_b32_e32 v100, v183
	v_pk_fma_f32 v[156:157], v[156:157], v[248:249], v[228:229]
	v_cvt_pk_bf16_f32 v228, v167, v169
	v_cvt_pk_bf16_f32 v229, v237, v239
	v_cvt_pk_bf16_f32 v230, v241, v243
	v_cvt_pk_bf16_f32 v231, v245, v247
	v_pk_mul_f32 v[62:63], v[62:63], v[166:167] op_sel_hi:[1,0]
	v_pk_mul_f32 v[60:61], v[60:61], v[166:167] op_sel_hi:[1,0]
	v_pk_mul_f32 v[58:59], v[58:59], v[166:167] op_sel_hi:[1,0]
	v_pk_mul_f32 v[56:57], v[56:57], v[166:167] op_sel_hi:[1,0]
	v_pk_mul_f32 v[54:55], v[54:55], v[166:167] op_sel_hi:[1,0]
	v_pk_mul_f32 v[52:53], v[52:53], v[166:167] op_sel_hi:[1,0]
	v_pk_mul_f32 v[50:51], v[50:51], v[166:167] op_sel_hi:[1,0]
	v_pk_mul_f32 v[48:49], v[48:49], v[166:167] op_sel_hi:[1,0]
	v_pk_fma_f32 v[154:155], v[154:155], v[182:183], v[96:97]
	v_cvt_pk_bf16_f32 v96, v173, v175
	v_cvt_pk_bf16_f32 v97, v177, v179
	v_cvt_pk_bf16_f32 v98, v181, v185
	v_cvt_pk_bf16_f32 v99, v187, v189
	v_pk_mul_f32 v[46:47], v[46:47], v[100:101] op_sel_hi:[1,0]
	v_pk_mul_f32 v[44:45], v[44:45], v[100:101] op_sel_hi:[1,0]
	v_pk_mul_f32 v[42:43], v[42:43], v[100:101] op_sel_hi:[1,0]
	v_pk_mul_f32 v[40:41], v[40:41], v[100:101] op_sel_hi:[1,0]
	v_pk_mul_f32 v[38:39], v[38:39], v[100:101] op_sel_hi:[1,0]
	v_pk_mul_f32 v[36:37], v[36:37], v[100:101] op_sel_hi:[1,0]
	v_pk_mul_f32 v[34:35], v[34:35], v[100:101] op_sel_hi:[1,0]
	v_pk_mul_f32 v[32:33], v[32:33], v[100:101] op_sel_hi:[1,0]
	v_mfma_f32_16x16x32_bf16 v[60:63], v[136:139], v[228:231], v[60:63]
	v_mfma_f32_16x16x32_bf16 v[56:59], v[140:143], v[228:231], v[56:59]
	v_mfma_f32_16x16x32_bf16 v[52:55], v[132:135], v[228:231], v[52:55]
	v_mfma_f32_16x16x32_bf16 v[48:51], v[128:131], v[228:231], v[48:51]
	v_mfma_f32_16x16x32_bf16 v[44:47], v[136:139], v[96:99], v[44:47]
	v_mfma_f32_16x16x32_bf16 v[40:43], v[140:143], v[96:99], v[40:43]
	v_mfma_f32_16x16x32_bf16 v[36:39], v[132:135], v[96:99], v[36:39]
	v_mfma_f32_16x16x32_bf16 v[32:35], v[128:131], v[96:99], v[32:35]
	s_and_b64 vcc, exec, s[4:5]
	s_cbranch_vccnz .LBB0_203
	v_mov_b64_e32 v[108:109], v[112:113]
	v_mov_b64_e32 v[104:105], v[116:117]
	v_mov_b64_e32 v[100:101], v[120:121]
	v_mov_b64_e32 v[96:97], v[124:125]
	s_mov_b32 s82, s23
	s_mov_b32 s4, s24
	v_mov_b64_e32 v[110:111], v[114:115]
	v_mov_b64_e32 v[106:107], v[118:119]
	v_mov_b64_e32 v[102:103], v[122:123]
	v_mov_b64_e32 v[98:99], v[126:127]
	v_mov_b32_e32 v172, v201
	v_mov_b32_e32 v177, v205
	v_mov_b32_e32 v175, v206
	v_mov_b32_e32 v173, v202
	s_andn2_b64 vcc, exec, s[12:13]
	s_mov_b64 s[0:1], -1
	s_cbranch_vccz .LBB0_193
	s_branch .LBB0_198

.LBB0_203:
	ds_bpermute_b32 v96, v193, v154
	s_mov_b32 s39, s83
	s_waitcnt lgkmcnt(0)
	v_add_f32_e32 v96, v154, v96
	ds_bpermute_b32 v97, v194, v96
	s_waitcnt lgkmcnt(0)
	v_add_f32_e32 v98, v96, v97
	v_lshl_add_u64 v[96:97], s[38:39], 2, v[148:149]
	global_load_dword v99, v[96:97], off
	s_waitcnt vmcnt(0) lgkmcnt(0)
	v_mul_f32_e32 v99, 0xbfb8aa3b, v99
	v_exp_f32_e32 v99, v99
	s_nop 0
	v_add_f32_e32 v99, 1.0, v99
	v_rcp_f32_e32 v99, v99
	s_nop 0
	v_div_scale_f32 v100, s[0:1], v98, v98, v99
	v_rcp_f32_e32 v101, v100
	s_mov_b64 s[0:1], -1
	v_fma_f32 v102, -v100, v101, 1.0
	v_fmac_f32_e32 v101, v102, v101
	v_div_scale_f32 v102, vcc, v99, v98, v99
	v_mul_f32_e32 v103, v102, v101
	v_fma_f32 v104, -v100, v103, v102
	v_fmac_f32_e32 v103, v104, v101
	v_fma_f32 v100, -v100, v103, v102
	v_div_fmas_f32 v100, v100, v101, v103
	v_div_fixup_f32 v98, v100, v98, v99
	v_mul_f32_e32 v93, v93, v98
	s_and_b64 vcc, exec, s[12:13]
	s_cbranch_vccz .LBB0_205
	ds_read2st64_b32 v[100:101], v192 offset1:1
	s_mov_b64 s[0:1], 0
	s_waitcnt lgkmcnt(0)
	v_add_f32_e32 v99, v93, v101
	v_fmac_f32_e32 v100, v92, v98
	ds_write2st64_b32 v192, v100, v99 offset1:1
	ds_read2st64_b32 v[100:101], v192 offset0:2 offset1:3
	s_waitcnt lgkmcnt(0)
	v_fma_f32 v99, v94, v98, v100
	v_fmac_f32_e32 v101, v95, v98
	ds_write2st64_b32 v192, v99, v101 offset0:2 offset1:3
.LBB0_205:
	s_andn2_b64 vcc, exec, s[0:1]
	s_cbranch_vccnz .LBB0_207
	ds_read2st64_b32 v[100:101], v192 offset1:1
	v_mul_f32_e32 v92, v92, v98
	s_waitcnt lgkmcnt(0)
	v_pk_add_f32 v[92:93], v[92:93], v[100:101]
	ds_read2st64_b32 v[100:101], v192 offset0:2 offset1:3
	v_cvt_pk_bf16_f32 v92, v92, v93
	s_waitcnt lgkmcnt(0)
	v_pk_fma_f32 v[94:95], v[94:95], v[98:99], v[100:101] op_sel_hi:[1,0,1]
	s_nop 0
	v_cvt_pk_bf16_f32 v93, v94, v95
	global_store_dwordx2 v[150:151], v[92:93], off

.LBB0_213:
	ds_read2st64_b32 v[84:85], v192 offset0:12 offset1:13
	v_mul_f32_e32 v80, v80, v98
	s_waitcnt lgkmcnt(0)
	v_pk_add_f32 v[80:81], v[80:81], v[84:85]
	ds_read2st64_b32 v[84:85], v192 offset0:14 offset1:15
	v_cvt_pk_bf16_f32 v80, v80, v81
	s_waitcnt lgkmcnt(0)
	v_pk_fma_f32 v[82:83], v[82:83], v[98:99], v[84:85] op_sel_hi:[1,0,1]
	s_nop 0
	v_cvt_pk_bf16_f32 v81, v82, v83
	global_store_dwordx2 v[150:151], v[80:81], off offset:96
.LBB0_214:
	global_load_dword v80, v[96:97], off offset:12
	ds_bpermute_b32 v81, v193, v156
	s_waitcnt lgkmcnt(0)
	v_add_f32_e32 v81, v156, v81
	ds_bpermute_b32 v82, v194, v81
	s_waitcnt lgkmcnt(0)
	v_add_f32_e32 v81, v81, v82
	s_waitcnt vmcnt(0)
	v_mul_f32_e32 v80, 0xbfb8aa3b, v80
	v_exp_f32_e32 v80, v80
	s_nop 0
	v_add_f32_e32 v80, 1.0, v80
	v_rcp_f32_e32 v80, v80
	s_nop 0
	v_div_scale_f32 v82, s[0:1], v81, v81, v80
	v_rcp_f32_e32 v83, v82
	v_div_scale_f32 v84, vcc, v80, v81, v80
	s_mov_b64 s[0:1], -1
	v_fma_f32 v85, -v82, v83, 1.0
	v_fmac_f32_e32 v83, v85, v83
	v_mul_f32_e32 v85, v84, v83
	v_fma_f32 v86, -v82, v85, v84
	v_fmac_f32_e32 v85, v86, v83
	v_fma_f32 v82, -v82, v85, v84
	v_div_fmas_f32 v82, v82, v83, v85
	v_div_fixup_f32 v80, v82, v81, v80
	s_and_b64 vcc, exec, s[4:5]
	v_mul_f32_e32 v77, v77, v80
	s_cbranch_vccz .LBB0_245
	s_andn2_b64 vcc, exec, s[0:1]
	s_cbranch_vccz .LBB0_246

.LBB0_222:
	ds_read2st64_b32 v[68:69], v192 offset0:28 offset1:29
	v_mul_f32_e32 v64, v64, v80
	s_waitcnt lgkmcnt(0)
	v_pk_add_f32 v[64:65], v[64:65], v[68:69]
	ds_read2st64_b32 v[68:69], v192 offset0:30 offset1:31
	v_cvt_pk_bf16_f32 v64, v64, v65
	s_waitcnt lgkmcnt(0)
	v_pk_fma_f32 v[66:67], v[66:67], v[80:81], v[68:69] op_sel_hi:[1,0,1]
	s_nop 0
	v_cvt_pk_bf16_f32 v65, v66, v67
	global_store_dwordx2 v[150:151], v[64:65], off offset:224
.LBB0_223:
	global_load_dword v64, v[96:97], off offset:24
	ds_bpermute_b32 v65, v193, v157
	s_waitcnt lgkmcnt(0)
	v_add_f32_e32 v65, v157, v65
	ds_bpermute_b32 v66, v194, v65
	s_waitcnt lgkmcnt(0)
	v_add_f32_e32 v65, v65, v66
	s_waitcnt vmcnt(0)
	v_mul_f32_e32 v64, 0xbfb8aa3b, v64
	v_exp_f32_e32 v64, v64
	s_nop 0
	v_add_f32_e32 v64, 1.0, v64
	v_rcp_f32_e32 v64, v64
	s_nop 0
	v_div_scale_f32 v66, s[0:1], v65, v65, v64
	v_rcp_f32_e32 v67, v66
	v_div_scale_f32 v68, vcc, v64, v65, v64
	s_mov_b64 s[0:1], -1
	v_fma_f32 v69, -v66, v67, 1.0
	v_fmac_f32_e32 v67, v69, v67
	v_mul_f32_e32 v69, v68, v67
	v_fma_f32 v70, -v66, v69, v68
	v_fmac_f32_e32 v69, v70, v67
	v_fma_f32 v66, -v66, v69, v68
	v_div_fmas_f32 v66, v66, v67, v69
	v_div_fixup_f32 v64, v66, v65, v64
	s_and_b64 vcc, exec, s[4:5]
	v_mul_f32_e32 v61, v61, v64
	s_cbranch_vccz .LBB0_252
	s_andn2_b64 vcc, exec, s[0:1]
	s_cbranch_vccz .LBB0_253

.LBB0_231:
	ds_read2st64_b32 v[52:53], v192 offset0:44 offset1:45
	v_mul_f32_e32 v48, v48, v64
	s_waitcnt lgkmcnt(0)
	v_pk_add_f32 v[48:49], v[48:49], v[52:53]
	ds_read2st64_b32 v[52:53], v192 offset0:46 offset1:47
	v_cvt_pk_bf16_f32 v48, v48, v49
	s_waitcnt lgkmcnt(0)
	v_pk_fma_f32 v[50:51], v[50:51], v[64:65], v[52:53] op_sel_hi:[1,0,1]
	s_nop 0
	v_cvt_pk_bf16_f32 v49, v50, v51
	global_store_dwordx2 v[150:151], v[48:49], off offset:352
.LBB0_232:
	global_load_dword v48, v[96:97], off offset:36
	ds_bpermute_b32 v49, v193, v155
	s_waitcnt lgkmcnt(0)
	v_add_f32_e32 v49, v155, v49
	ds_bpermute_b32 v50, v194, v49
	s_waitcnt lgkmcnt(0)
	v_add_f32_e32 v49, v49, v50
	s_waitcnt vmcnt(0)
	v_mul_f32_e32 v48, 0xbfb8aa3b, v48
	v_exp_f32_e32 v48, v48
	s_nop 0
	v_add_f32_e32 v48, 1.0, v48
	v_rcp_f32_e32 v48, v48
	s_nop 0
	v_div_scale_f32 v50, s[0:1], v49, v49, v48
	v_rcp_f32_e32 v51, v50
	v_div_scale_f32 v52, vcc, v48, v49, v48
	s_mov_b64 s[0:1], -1
	v_fma_f32 v53, -v50, v51, 1.0
	v_fmac_f32_e32 v51, v53, v51
	v_mul_f32_e32 v53, v52, v51
	v_fma_f32 v54, -v50, v53, v52
	v_fmac_f32_e32 v53, v54, v51
	v_fma_f32 v50, -v50, v53, v52
	v_div_fmas_f32 v50, v50, v51, v53
	v_div_fixup_f32 v48, v50, v49, v48
	s_and_b64 vcc, exec, s[4:5]
	v_mul_f32_e32 v45, v45, v48
	s_cbranch_vccz .LBB0_259
	s_andn2_b64 vcc, exec, s[0:1]
	s_cbranch_vccz .LBB0_260

.LBB0_241:
	ds_read2st64_b32 v[92:93], v192 offset0:4 offset1:5
	v_mul_f32_e32 v88, v88, v98
	s_waitcnt lgkmcnt(0)
	v_pk_add_f32 v[88:89], v[88:89], v[92:93]
	ds_read2st64_b32 v[92:93], v192 offset0:6 offset1:7
	v_cvt_pk_bf16_f32 v88, v88, v89
	s_waitcnt lgkmcnt(0)
	v_pk_fma_f32 v[90:91], v[90:91], v[98:99], v[92:93] op_sel_hi:[1,0,1]
	s_nop 0
	v_cvt_pk_bf16_f32 v89, v90, v91
	global_store_dwordx2 v[150:151], v[88:89], off offset:32
	v_mul_f32_e32 v85, v85, v98
	s_and_b64 vcc, exec, s[4:5]
	s_mov_b64 s[0:1], -1
	s_cbranch_vccnz .LBB0_210

.LBB0_243:
	ds_read2st64_b32 v[88:89], v192 offset0:8 offset1:9
	v_mul_f32_e32 v84, v84, v98
	s_waitcnt lgkmcnt(0)
	v_pk_add_f32 v[84:85], v[84:85], v[88:89]
	ds_read2st64_b32 v[88:89], v192 offset0:10 offset1:11
	v_cvt_pk_bf16_f32 v84, v84, v85
	s_waitcnt lgkmcnt(0)
	v_pk_fma_f32 v[86:87], v[86:87], v[98:99], v[88:89] op_sel_hi:[1,0,1]
	s_nop 0
	v_cvt_pk_bf16_f32 v85, v86, v87
	global_store_dwordx2 v[150:151], v[84:85], off offset:64
	v_mul_f32_e32 v81, v81, v98
	s_and_b64 vcc, exec, s[4:5]
	s_mov_b64 s[0:1], -1
	s_cbranch_vccnz .LBB0_212

.LBB0_246:
	ds_read2st64_b32 v[82:83], v192 offset0:16 offset1:17
	v_mul_f32_e32 v76, v76, v80
	s_waitcnt lgkmcnt(0)
	v_pk_add_f32 v[76:77], v[76:77], v[82:83]
	ds_read2st64_b32 v[82:83], v192 offset0:18 offset1:19
	v_cvt_pk_bf16_f32 v76, v76, v77
	s_waitcnt lgkmcnt(0)
	v_pk_fma_f32 v[78:79], v[78:79], v[80:81], v[82:83] op_sel_hi:[1,0,1]
	s_nop 0
	v_cvt_pk_bf16_f32 v77, v78, v79
	global_store_dwordx2 v[150:151], v[76:77], off offset:128
	v_mul_f32_e32 v73, v73, v80
	s_and_b64 vcc, exec, s[4:5]
	s_mov_b64 s[0:1], -1
	s_cbranch_vccnz .LBB0_217

.LBB0_248:
	ds_read2st64_b32 v[76:77], v192 offset0:20 offset1:21
	v_mul_f32_e32 v72, v72, v80
	s_waitcnt lgkmcnt(0)
	v_pk_add_f32 v[72:73], v[72:73], v[76:77]
	ds_read2st64_b32 v[76:77], v192 offset0:22 offset1:23
	v_cvt_pk_bf16_f32 v72, v72, v73
	s_waitcnt lgkmcnt(0)
	v_pk_fma_f32 v[74:75], v[74:75], v[80:81], v[76:77] op_sel_hi:[1,0,1]
	s_nop 0
	v_cvt_pk_bf16_f32 v73, v74, v75
	global_store_dwordx2 v[150:151], v[72:73], off offset:160
	v_mul_f32_e32 v69, v69, v80
	s_and_b64 vcc, exec, s[4:5]
	s_mov_b64 s[0:1], -1
	s_cbranch_vccnz .LBB0_219

.LBB0_250:
	ds_read2st64_b32 v[72:73], v192 offset0:24 offset1:25
	v_mul_f32_e32 v68, v68, v80
	s_waitcnt lgkmcnt(0)
	v_pk_add_f32 v[68:69], v[68:69], v[72:73]
	ds_read2st64_b32 v[72:73], v192 offset0:26 offset1:27
	v_cvt_pk_bf16_f32 v68, v68, v69
	s_waitcnt lgkmcnt(0)
	v_pk_fma_f32 v[70:71], v[70:71], v[80:81], v[72:73] op_sel_hi:[1,0,1]
	s_nop 0
	v_cvt_pk_bf16_f32 v69, v70, v71
	global_store_dwordx2 v[150:151], v[68:69], off offset:192
	v_mul_f32_e32 v65, v65, v80
	s_and_b64 vcc, exec, s[4:5]
	s_mov_b64 s[0:1], -1
	s_cbranch_vccnz .LBB0_221

.LBB0_253:
	ds_read2st64_b32 v[66:67], v192 offset0:32 offset1:33
	v_mul_f32_e32 v60, v60, v64
	s_waitcnt lgkmcnt(0)
	v_pk_add_f32 v[60:61], v[60:61], v[66:67]
	ds_read2st64_b32 v[66:67], v192 offset0:34 offset1:35
	v_cvt_pk_bf16_f32 v60, v60, v61
	s_waitcnt lgkmcnt(0)
	v_pk_fma_f32 v[62:63], v[62:63], v[64:65], v[66:67] op_sel_hi:[1,0,1]
	s_nop 0
	v_cvt_pk_bf16_f32 v61, v62, v63
	global_store_dwordx2 v[150:151], v[60:61], off offset:256
	v_mul_f32_e32 v57, v57, v64
	s_and_b64 vcc, exec, s[4:5]
	s_mov_b64 s[0:1], -1
	s_cbranch_vccnz .LBB0_226

.LBB0_255:
	ds_read2st64_b32 v[60:61], v192 offset0:36 offset1:37
	v_mul_f32_e32 v56, v56, v64
	s_waitcnt lgkmcnt(0)
	v_pk_add_f32 v[56:57], v[56:57], v[60:61]
	ds_read2st64_b32 v[60:61], v192 offset0:38 offset1:39
	v_cvt_pk_bf16_f32 v56, v56, v57
	s_waitcnt lgkmcnt(0)
	v_pk_fma_f32 v[58:59], v[58:59], v[64:65], v[60:61] op_sel_hi:[1,0,1]
	s_nop 0
	v_cvt_pk_bf16_f32 v57, v58, v59
	global_store_dwordx2 v[150:151], v[56:57], off offset:288
	v_mul_f32_e32 v53, v53, v64
	s_and_b64 vcc, exec, s[4:5]
	s_mov_b64 s[0:1], -1
	s_cbranch_vccnz .LBB0_228

.LBB0_257:
	ds_read2st64_b32 v[56:57], v192 offset0:40 offset1:41
	v_mul_f32_e32 v52, v52, v64
	s_waitcnt lgkmcnt(0)
	v_pk_add_f32 v[52:53], v[52:53], v[56:57]
	ds_read2st64_b32 v[56:57], v192 offset0:42 offset1:43
	v_cvt_pk_bf16_f32 v52, v52, v53
	s_waitcnt lgkmcnt(0)
	v_pk_fma_f32 v[54:55], v[54:55], v[64:65], v[56:57] op_sel_hi:[1,0,1]
	s_nop 0
	v_cvt_pk_bf16_f32 v53, v54, v55
	global_store_dwordx2 v[150:151], v[52:53], off offset:320
	v_mul_f32_e32 v49, v49, v64
	s_and_b64 vcc, exec, s[4:5]
	s_mov_b64 s[0:1], -1
	s_cbranch_vccnz .LBB0_230

.LBB0_260:
	ds_read2st64_b32 v[50:51], v192 offset0:48 offset1:49
	v_mul_f32_e32 v44, v44, v48
	s_waitcnt lgkmcnt(0)
	v_pk_add_f32 v[44:45], v[44:45], v[50:51]
	ds_read2st64_b32 v[50:51], v192 offset0:50 offset1:51
	v_cvt_pk_bf16_f32 v44, v44, v45
	s_waitcnt lgkmcnt(0)
	v_pk_fma_f32 v[46:47], v[46:47], v[48:49], v[50:51] op_sel_hi:[1,0,1]
	s_nop 0
	v_cvt_pk_bf16_f32 v45, v46, v47
	global_store_dwordx2 v[150:151], v[44:45], off offset:384
	v_mul_f32_e32 v41, v41, v48
	s_and_b64 vcc, exec, s[4:5]
	s_mov_b64 s[0:1], -1
	s_cbranch_vccnz .LBB0_235

.LBB0_262:
	ds_read2st64_b32 v[44:45], v192 offset0:52 offset1:53
	v_mul_f32_e32 v40, v40, v48
	s_waitcnt lgkmcnt(0)
	v_pk_add_f32 v[40:41], v[40:41], v[44:45]
	ds_read2st64_b32 v[44:45], v192 offset0:54 offset1:55
	v_cvt_pk_bf16_f32 v40, v40, v41
	s_waitcnt lgkmcnt(0)
	v_pk_fma_f32 v[42:43], v[42:43], v[48:49], v[44:45] op_sel_hi:[1,0,1]
	s_nop 0
	v_cvt_pk_bf16_f32 v41, v42, v43
	global_store_dwordx2 v[150:151], v[40:41], off offset:416
	v_mul_f32_e32 v37, v37, v48
	s_and_b64 vcc, exec, s[4:5]
	s_mov_b64 s[0:1], -1
	s_cbranch_vccnz .LBB0_237

.LBB0_264:
	ds_read2st64_b32 v[40:41], v192 offset0:56 offset1:57
	v_mul_f32_e32 v36, v36, v48
	s_waitcnt lgkmcnt(0)
	v_pk_add_f32 v[36:37], v[36:37], v[40:41]
	ds_read2st64_b32 v[40:41], v192 offset0:58 offset1:59
	v_cvt_pk_bf16_f32 v36, v36, v37
	s_waitcnt lgkmcnt(0)
	v_pk_fma_f32 v[38:39], v[38:39], v[48:49], v[40:41] op_sel_hi:[1,0,1]
	s_nop 0
	v_cvt_pk_bf16_f32 v37, v38, v39
	global_store_dwordx2 v[150:151], v[36:37], off offset:448
	v_mul_f32_e32 v33, v33, v48
	s_and_b64 vcc, exec, s[4:5]
	s_mov_b64 s[0:1], -1
	s_cbranch_vccnz .LBB0_239

.LBB0_266:
	ds_read2st64_b32 v[36:37], v192 offset0:60 offset1:61
	v_mul_f32_e32 v32, v32, v48
	s_waitcnt lgkmcnt(0)
	v_pk_add_f32 v[32:33], v[32:33], v[36:37]
	ds_read2st64_b32 v[36:37], v192 offset0:62 offset1:63
	v_cvt_pk_bf16_f32 v32, v32, v33
	s_waitcnt lgkmcnt(0)
	v_pk_fma_f32 v[34:35], v[34:35], v[48:49], v[36:37] op_sel_hi:[1,0,1]
	s_nop 0
	v_cvt_pk_bf16_f32 v33, v34, v35
	global_store_dwordx2 v[150:151], v[32:33], off offset:480
	s_branch .LBB0_190

.LBB0_275:
	s_ashr_i32 s14, s36, 2
	s_ashr_i32 s15, s14, 31
	s_lshl_b64 s[16:17], s[14:15], 27
	s_add_u32 s1, s27, s16
	s_addc_u32 s9, s28, s17
	s_cmp_lt_i32 s14, 2
	v_mul_f32_e32 v120, 0xbfb8aa3b, v120
	s_cselect_b32 s9, s9, s30
	s_cselect_b32 s1, s1, s29
	s_lshl_b32 s14, s36, 9
	v_exp_f32_e32 v120, v120
	v_mul_f32_e32 v121, 0xbfb8aa3b, v121
	s_and_b32 s14, s14, 0x600
	v_exp_f32_e32 v121, v121
	v_lshl_add_u32 v142, s37, 8, v144
	s_add_u32 s14, s1, s14
	s_addc_u32 s15, s9, 0
	v_ashrrev_i32_e32 v143, 31, v142
	v_mul_f32_e32 v124, 0xbfb8aa3b, v124
	v_lshl_add_u64 v[140:141], v[134:135], 1, s[14:15]
	v_lshlrev_b64 v[148:149], 11, v[142:143]
	v_exp_f32_e32 v143, v124
	v_mul_f32_e32 v124, 0xbfb8aa3b, v125
	v_add_f32_e32 v120, 1.0, v120
	v_exp_f32_e32 v147, v124
	v_lshl_add_u64 v[124:125], v[140:141], 0, v[148:149]
	v_rcp_f32_e32 v148, v120
	v_add_f32_e32 v120, 1.0, v121
	v_mul_f32_e32 v121, 0xbfb8aa3b, v122
	v_mul_f32_e32 v126, 0xbfb8aa3b, v126
	v_mul_f32_e32 v127, 0xbfb8aa3b, v127
	v_exp_f32_e32 v121, v121
	v_mul_f32_e32 v122, 0xbfb8aa3b, v123
	v_exp_f32_e32 v126, v126
	v_exp_f32_e32 v127, v127
	v_exp_f32_e32 v122, v122
	v_rcp_f32_e32 v123, v120
	v_add_f32_e32 v120, 1.0, v121
	v_add_f32_e32 v143, 1.0, v143
	v_add_f32_e32 v147, 1.0, v147
	v_add_f32_e32 v126, 1.0, v126
	v_add_f32_e32 v127, 1.0, v127
	v_rcp_f32_e32 v149, v120
	v_add_f32_e32 v120, 1.0, v122
	v_mul_f32_e32 v112, 0xbfb8aa3b, v112
	v_rcp_f32_e32 v143, v143
	v_rcp_f32_e32 v147, v147
	v_rcp_f32_e32 v126, v126
	v_rcp_f32_e32 v127, v127
	v_rcp_f32_e32 v150, v120
	v_exp_f32_e32 v112, v112
	v_mul_f32_e32 v113, 0xbfb8aa3b, v113
	v_exp_f32_e32 v113, v113
	v_cvt_pk_bf16_f32 v120, v143, v147
	v_cvt_pk_bf16_f32 v121, v126, v127
	v_cvt_pk_bf16_f32 v122, v148, v123
	v_cvt_pk_bf16_f32 v123, v149, v150
	v_add_f32_e32 v112, 1.0, v112
	global_store_dwordx4 v[124:125], v[120:123], off
	v_mul_f32_e32 v116, 0xbfb8aa3b, v116
	v_mul_f32_e32 v117, 0xbfb8aa3b, v117
	v_rcp_f32_e32 v120, v112
	v_add_f32_e32 v112, 1.0, v113
	v_mul_f32_e32 v113, 0xbfb8aa3b, v114
	v_mul_f32_e32 v118, 0xbfb8aa3b, v118
	v_mul_f32_e32 v119, 0xbfb8aa3b, v119
	v_exp_f32_e32 v113, v113
	v_mul_f32_e32 v114, 0xbfb8aa3b, v115
	v_exp_f32_e32 v116, v116
	v_exp_f32_e32 v117, v117
	v_exp_f32_e32 v118, v118
	v_exp_f32_e32 v119, v119
	v_exp_f32_e32 v114, v114
	v_rcp_f32_e32 v115, v112
	v_add_f32_e32 v112, 1.0, v113
	v_add_f32_e32 v116, 1.0, v116
	v_add_f32_e32 v117, 1.0, v117
	v_add_f32_e32 v118, 1.0, v118
	v_add_f32_e32 v119, 1.0, v119
	v_rcp_f32_e32 v121, v112
	v_add_f32_e32 v112, 1.0, v114
	v_rcp_f32_e32 v116, v116
	v_rcp_f32_e32 v117, v117
	v_rcp_f32_e32 v118, v118
	v_rcp_f32_e32 v119, v119
	v_rcp_f32_e32 v122, v112
	v_mul_f32_e32 v104, 0xbfb8aa3b, v104
	v_cvt_pk_bf16_f32 v112, v116, v117
	v_cvt_pk_bf16_f32 v113, v118, v119
	v_cvt_pk_bf16_f32 v114, v120, v115
	v_cvt_pk_bf16_f32 v115, v121, v122
	v_mul_f32_e32 v108, 0xbfb8aa3b, v108
	v_exp_f32_e32 v104, v104
	v_mul_f32_e32 v105, 0xbfb8aa3b, v105
	global_store_dwordx4 v[124:125], v[112:115], off offset:256
	v_exp_f32_e32 v105, v105
	v_add_f32_e32 v104, 1.0, v104
	v_exp_f32_e32 v114, v108
	v_or_b32_e32 v112, 16, v142
	v_ashrrev_i32_e32 v113, 31, v112
	v_lshlrev_b64 v[112:113], 11, v[112:113]
	v_mul_f32_e32 v108, 0xbfb8aa3b, v109
	v_exp_f32_e32 v115, v108
	v_lshl_add_u64 v[108:109], v[140:141], 0, v[112:113]
	v_add_f32_e32 v112, 1.0, v114
	v_rcp_f32_e32 v114, v104
	v_add_f32_e32 v104, 1.0, v105
	v_mul_f32_e32 v105, 0xbfb8aa3b, v106
	v_mul_f32_e32 v110, 0xbfb8aa3b, v110
	v_mul_f32_e32 v111, 0xbfb8aa3b, v111
	v_exp_f32_e32 v105, v105
	v_mul_f32_e32 v106, 0xbfb8aa3b, v107
	v_exp_f32_e32 v110, v110
	v_exp_f32_e32 v111, v111
	v_exp_f32_e32 v106, v106
	v_rcp_f32_e32 v107, v104
	v_add_f32_e32 v104, 1.0, v105
	v_add_f32_e32 v113, 1.0, v115
	v_add_f32_e32 v110, 1.0, v110
	v_add_f32_e32 v111, 1.0, v111
	v_rcp_f32_e32 v115, v104
	v_add_f32_e32 v104, 1.0, v106
	v_mul_f32_e32 v96, 0xbfb8aa3b, v96
	v_rcp_f32_e32 v112, v112
	v_rcp_f32_e32 v113, v113
	v_rcp_f32_e32 v110, v110
	v_rcp_f32_e32 v111, v111
	v_rcp_f32_e32 v116, v104
	v_exp_f32_e32 v96, v96
	v_mul_f32_e32 v97, 0xbfb8aa3b, v97
	v_exp_f32_e32 v97, v97
	v_cvt_pk_bf16_f32 v104, v112, v113
	v_cvt_pk_bf16_f32 v105, v110, v111
	v_cvt_pk_bf16_f32 v106, v114, v107
	v_cvt_pk_bf16_f32 v107, v115, v116
	v_add_f32_e32 v96, 1.0, v96
	global_store_dwordx4 v[108:109], v[104:107], off
	v_mul_f32_e32 v100, 0xbfb8aa3b, v100
	v_mul_f32_e32 v101, 0xbfb8aa3b, v101
	v_rcp_f32_e32 v104, v96
	v_add_f32_e32 v96, 1.0, v97
	v_mul_f32_e32 v97, 0xbfb8aa3b, v98
	v_mul_f32_e32 v102, 0xbfb8aa3b, v102
	v_mul_f32_e32 v103, 0xbfb8aa3b, v103
	v_exp_f32_e32 v97, v97
	v_mul_f32_e32 v98, 0xbfb8aa3b, v99
	v_exp_f32_e32 v100, v100
	v_exp_f32_e32 v101, v101
	v_exp_f32_e32 v102, v102
	v_exp_f32_e32 v103, v103
	v_exp_f32_e32 v98, v98
	v_rcp_f32_e32 v99, v96
	v_add_f32_e32 v96, 1.0, v97
	v_add_f32_e32 v100, 1.0, v100
	v_add_f32_e32 v101, 1.0, v101
	v_add_f32_e32 v102, 1.0, v102
	v_add_f32_e32 v103, 1.0, v103
	v_rcp_f32_e32 v105, v96
	v_add_f32_e32 v96, 1.0, v98
	v_rcp_f32_e32 v100, v100
	v_rcp_f32_e32 v101, v101
	v_rcp_f32_e32 v102, v102
	v_rcp_f32_e32 v103, v103
	v_rcp_f32_e32 v106, v96
	v_mul_f32_e32 v88, 0xbfb8aa3b, v88
	v_cvt_pk_bf16_f32 v96, v100, v101
	v_cvt_pk_bf16_f32 v97, v102, v103
	v_cvt_pk_bf16_f32 v98, v104, v99
	v_cvt_pk_bf16_f32 v99, v105, v106
	v_mul_f32_e32 v92, 0xbfb8aa3b, v92
	v_exp_f32_e32 v88, v88
	v_mul_f32_e32 v89, 0xbfb8aa3b, v89
	global_store_dwordx4 v[108:109], v[96:99], off offset:256
	v_exp_f32_e32 v89, v89
	v_add_f32_e32 v88, 1.0, v88
	v_exp_f32_e32 v98, v92
	v_or_b32_e32 v96, 32, v142
	v_ashrrev_i32_e32 v97, 31, v96
	v_lshlrev_b64 v[96:97], 11, v[96:97]
	v_mul_f32_e32 v92, 0xbfb8aa3b, v93
	v_exp_f32_e32 v99, v92
	v_lshl_add_u64 v[92:93], v[140:141], 0, v[96:97]
	v_add_f32_e32 v96, 1.0, v98
	v_rcp_f32_e32 v98, v88
	v_add_f32_e32 v88, 1.0, v89
	v_mul_f32_e32 v89, 0xbfb8aa3b, v90
	v_mul_f32_e32 v94, 0xbfb8aa3b, v94
	v_mul_f32_e32 v95, 0xbfb8aa3b, v95
	v_exp_f32_e32 v89, v89
	v_mul_f32_e32 v90, 0xbfb8aa3b, v91
	v_exp_f32_e32 v94, v94
	v_exp_f32_e32 v95, v95
	v_exp_f32_e32 v90, v90
	v_rcp_f32_e32 v91, v88
	v_add_f32_e32 v88, 1.0, v89
	v_add_f32_e32 v97, 1.0, v99
	v_add_f32_e32 v94, 1.0, v94
	v_add_f32_e32 v95, 1.0, v95
	v_rcp_f32_e32 v99, v88
	v_add_f32_e32 v88, 1.0, v90
	v_mul_f32_e32 v80, 0xbfb8aa3b, v80
	v_rcp_f32_e32 v96, v96
	v_rcp_f32_e32 v97, v97
	v_rcp_f32_e32 v94, v94
	v_rcp_f32_e32 v95, v95
	v_rcp_f32_e32 v100, v88
	v_exp_f32_e32 v80, v80
	v_mul_f32_e32 v81, 0xbfb8aa3b, v81
	v_exp_f32_e32 v81, v81
	v_cvt_pk_bf16_f32 v88, v96, v97
	v_cvt_pk_bf16_f32 v89, v94, v95
	v_cvt_pk_bf16_f32 v90, v98, v91
	v_cvt_pk_bf16_f32 v91, v99, v100
	v_add_f32_e32 v80, 1.0, v80
	global_store_dwordx4 v[92:93], v[88:91], off
	v_mul_f32_e32 v84, 0xbfb8aa3b, v84
	v_mul_f32_e32 v85, 0xbfb8aa3b, v85
	v_rcp_f32_e32 v88, v80
	v_add_f32_e32 v80, 1.0, v81
	v_mul_f32_e32 v81, 0xbfb8aa3b, v82
	v_mul_f32_e32 v86, 0xbfb8aa3b, v86
	v_mul_f32_e32 v87, 0xbfb8aa3b, v87
	v_exp_f32_e32 v81, v81
	v_mul_f32_e32 v82, 0xbfb8aa3b, v83
	v_exp_f32_e32 v84, v84
	v_exp_f32_e32 v85, v85
	v_exp_f32_e32 v86, v86
	v_exp_f32_e32 v87, v87
	v_exp_f32_e32 v82, v82
	v_rcp_f32_e32 v83, v80
	v_add_f32_e32 v80, 1.0, v81
	v_add_f32_e32 v84, 1.0, v84
	v_add_f32_e32 v85, 1.0, v85
	v_add_f32_e32 v86, 1.0, v86
	v_add_f32_e32 v87, 1.0, v87
	v_rcp_f32_e32 v89, v80
	v_add_f32_e32 v80, 1.0, v82
	v_rcp_f32_e32 v84, v84
	v_rcp_f32_e32 v85, v85
	v_rcp_f32_e32 v86, v86
	v_rcp_f32_e32 v87, v87
	v_rcp_f32_e32 v90, v80
	v_mul_f32_e32 v72, 0xbfb8aa3b, v72
	v_cvt_pk_bf16_f32 v80, v84, v85
	v_cvt_pk_bf16_f32 v81, v86, v87
	v_cvt_pk_bf16_f32 v82, v88, v83
	v_cvt_pk_bf16_f32 v83, v89, v90
	v_mul_f32_e32 v76, 0xbfb8aa3b, v76
	v_exp_f32_e32 v72, v72
	v_mul_f32_e32 v73, 0xbfb8aa3b, v73
	global_store_dwordx4 v[92:93], v[80:83], off offset:256
	v_exp_f32_e32 v73, v73
	v_add_f32_e32 v72, 1.0, v72
	v_exp_f32_e32 v82, v76
	v_or_b32_e32 v80, 48, v142
	v_ashrrev_i32_e32 v81, 31, v80
	v_lshlrev_b64 v[80:81], 11, v[80:81]
	v_mul_f32_e32 v76, 0xbfb8aa3b, v77
	v_exp_f32_e32 v83, v76
	v_lshl_add_u64 v[76:77], v[140:141], 0, v[80:81]
	v_add_f32_e32 v80, 1.0, v82
	v_rcp_f32_e32 v82, v72
	v_add_f32_e32 v72, 1.0, v73
	v_mul_f32_e32 v73, 0xbfb8aa3b, v74
	v_mul_f32_e32 v78, 0xbfb8aa3b, v78
	v_mul_f32_e32 v79, 0xbfb8aa3b, v79
	v_exp_f32_e32 v73, v73
	v_mul_f32_e32 v74, 0xbfb8aa3b, v75
	v_exp_f32_e32 v78, v78
	v_exp_f32_e32 v79, v79
	v_exp_f32_e32 v74, v74
	v_rcp_f32_e32 v75, v72
	v_add_f32_e32 v72, 1.0, v73
	v_add_f32_e32 v81, 1.0, v83
	v_add_f32_e32 v78, 1.0, v78
	v_add_f32_e32 v79, 1.0, v79
	v_rcp_f32_e32 v83, v72
	v_add_f32_e32 v72, 1.0, v74
	v_mul_f32_e32 v64, 0xbfb8aa3b, v64
	v_rcp_f32_e32 v80, v80
	v_rcp_f32_e32 v81, v81
	v_rcp_f32_e32 v78, v78
	v_rcp_f32_e32 v79, v79
	v_rcp_f32_e32 v84, v72
	v_exp_f32_e32 v64, v64
	v_mul_f32_e32 v65, 0xbfb8aa3b, v65
	v_exp_f32_e32 v65, v65
	v_cvt_pk_bf16_f32 v72, v80, v81
	v_cvt_pk_bf16_f32 v73, v78, v79
	v_cvt_pk_bf16_f32 v74, v82, v75
	v_cvt_pk_bf16_f32 v75, v83, v84
	v_add_f32_e32 v64, 1.0, v64
	global_store_dwordx4 v[76:77], v[72:75], off
	v_mul_f32_e32 v68, 0xbfb8aa3b, v68
	v_mul_f32_e32 v69, 0xbfb8aa3b, v69
	v_rcp_f32_e32 v72, v64
	v_add_f32_e32 v64, 1.0, v65
	v_mul_f32_e32 v65, 0xbfb8aa3b, v66
	v_mul_f32_e32 v70, 0xbfb8aa3b, v70
	v_mul_f32_e32 v71, 0xbfb8aa3b, v71
	v_exp_f32_e32 v65, v65
	v_mul_f32_e32 v66, 0xbfb8aa3b, v67
	v_exp_f32_e32 v68, v68
	v_exp_f32_e32 v69, v69
	v_exp_f32_e32 v70, v70
	v_exp_f32_e32 v71, v71
	v_exp_f32_e32 v66, v66
	v_rcp_f32_e32 v67, v64
	v_add_f32_e32 v64, 1.0, v65
	v_add_f32_e32 v68, 1.0, v68
	v_add_f32_e32 v69, 1.0, v69
	v_add_f32_e32 v70, 1.0, v70
	v_add_f32_e32 v71, 1.0, v71
	v_rcp_f32_e32 v73, v64
	v_add_f32_e32 v64, 1.0, v66
	v_mul_f32_e32 v56, 0xbfb8aa3b, v56
	v_rcp_f32_e32 v68, v68
	v_rcp_f32_e32 v69, v69
	v_rcp_f32_e32 v70, v70
	v_rcp_f32_e32 v71, v71
	v_rcp_f32_e32 v74, v64
	v_exp_f32_e32 v56, v56
	v_mul_f32_e32 v57, 0xbfb8aa3b, v57
	v_exp_f32_e32 v57, v57
	v_cvt_pk_bf16_f32 v64, v68, v69
	v_cvt_pk_bf16_f32 v65, v70, v71
	v_cvt_pk_bf16_f32 v66, v72, v67
	v_cvt_pk_bf16_f32 v67, v73, v74
	v_add_f32_e32 v56, 1.0, v56
	global_store_dwordx4 v[76:77], v[64:67], off offset:256
	v_mul_f32_e32 v60, 0xbfb8aa3b, v60
	v_mul_f32_e32 v62, 0xbfb8aa3b, v62
	v_mul_f32_e32 v63, 0xbfb8aa3b, v63
	v_rcp_f32_e32 v66, v56
	v_add_f32_e32 v56, 1.0, v57
	v_mul_f32_e32 v57, 0xbfb8aa3b, v58
	v_exp_f32_e32 v64, v60
	v_mul_f32_e32 v60, 0xbfb8aa3b, v61
	v_exp_f32_e32 v62, v62
	v_exp_f32_e32 v63, v63
	v_exp_f32_e32 v57, v57
	v_mul_f32_e32 v58, 0xbfb8aa3b, v59
	v_exp_f32_e32 v65, v60
	v_exp_f32_e32 v58, v58
	v_add_f32_e32 v62, 1.0, v62
	v_add_f32_e32 v63, 1.0, v63
	v_rcp_f32_e32 v59, v56
	v_add_f32_e32 v56, 1.0, v57
	v_add_f32_e32 v64, 1.0, v64
	v_add_f32_e32 v65, 1.0, v65
	v_rcp_f32_e32 v62, v62
	v_rcp_f32_e32 v63, v63
	v_rcp_f32_e32 v67, v56
	v_add_f32_e32 v56, 1.0, v58
	v_mul_f32_e32 v48, 0xbfb8aa3b, v48
	v_rcp_f32_e32 v64, v64
	v_rcp_f32_e32 v65, v65
	v_rcp_f32_e32 v68, v56
	v_exp_f32_e32 v48, v48
	v_mul_f32_e32 v49, 0xbfb8aa3b, v49
	v_exp_f32_e32 v49, v49
	s_mov_b32 s1, 0x40000
	v_cvt_pk_bf16_f32 v57, v62, v63
	v_add_co_u32_e32 v62, vcc, s1, v124
	v_cvt_pk_bf16_f32 v56, v64, v65
	v_cvt_pk_bf16_f32 v58, v66, v59
	v_cvt_pk_bf16_f32 v59, v67, v68
	v_addc_co_u32_e32 v63, vcc, 0, v125, vcc
	v_add_f32_e32 v48, 1.0, v48
	global_store_dwordx4 v[62:63], v[56:59], off
	v_mul_f32_e32 v52, 0xbfb8aa3b, v52
	v_mul_f32_e32 v53, 0xbfb8aa3b, v53
	v_rcp_f32_e32 v56, v48
	v_add_f32_e32 v48, 1.0, v49
	v_mul_f32_e32 v49, 0xbfb8aa3b, v50
	v_mul_f32_e32 v54, 0xbfb8aa3b, v54
	v_mul_f32_e32 v55, 0xbfb8aa3b, v55
	v_exp_f32_e32 v49, v49
	v_mul_f32_e32 v50, 0xbfb8aa3b, v51
	v_exp_f32_e32 v52, v52
	v_exp_f32_e32 v53, v53
	v_exp_f32_e32 v54, v54
	v_exp_f32_e32 v55, v55
	v_exp_f32_e32 v50, v50
	v_rcp_f32_e32 v51, v48
	v_add_f32_e32 v48, 1.0, v49
	v_add_f32_e32 v52, 1.0, v52
	v_add_f32_e32 v53, 1.0, v53
	v_add_f32_e32 v54, 1.0, v54
	v_add_f32_e32 v55, 1.0, v55
	v_rcp_f32_e32 v57, v48
	v_add_f32_e32 v48, 1.0, v50
	v_mul_f32_e32 v40, 0xbfb8aa3b, v40
	v_rcp_f32_e32 v52, v52
	v_rcp_f32_e32 v53, v53
	v_rcp_f32_e32 v54, v54
	v_rcp_f32_e32 v55, v55
	v_rcp_f32_e32 v58, v48
	v_exp_f32_e32 v40, v40
	v_mul_f32_e32 v41, 0xbfb8aa3b, v41
	v_exp_f32_e32 v41, v41
	s_mov_b64 s[14:15], 0x40000
	v_lshl_add_u64 v[60:61], v[124:125], 0, s[14:15]
	v_cvt_pk_bf16_f32 v48, v52, v53
	v_cvt_pk_bf16_f32 v49, v54, v55
	v_cvt_pk_bf16_f32 v50, v56, v51
	v_cvt_pk_bf16_f32 v51, v57, v58
	v_add_f32_e32 v40, 1.0, v40
	global_store_dwordx4 v[60:61], v[48:51], off offset:256
	v_mul_f32_e32 v44, 0xbfb8aa3b, v44
	v_mul_f32_e32 v46, 0xbfb8aa3b, v46
	v_mul_f32_e32 v47, 0xbfb8aa3b, v47
	v_rcp_f32_e32 v50, v40
	v_add_f32_e32 v40, 1.0, v41
	v_mul_f32_e32 v41, 0xbfb8aa3b, v42
	v_exp_f32_e32 v48, v44
	v_mul_f32_e32 v44, 0xbfb8aa3b, v45
	v_exp_f32_e32 v46, v46
	v_exp_f32_e32 v47, v47
	v_exp_f32_e32 v41, v41
	v_mul_f32_e32 v42, 0xbfb8aa3b, v43
	v_exp_f32_e32 v49, v44
	v_exp_f32_e32 v42, v42
	v_add_f32_e32 v46, 1.0, v46
	v_add_f32_e32 v47, 1.0, v47
	v_rcp_f32_e32 v43, v40
	v_add_f32_e32 v40, 1.0, v41
	v_add_f32_e32 v48, 1.0, v48
	v_add_f32_e32 v49, 1.0, v49
	v_rcp_f32_e32 v46, v46
	v_rcp_f32_e32 v47, v47
	v_rcp_f32_e32 v51, v40
	v_add_f32_e32 v40, 1.0, v42
	v_mul_f32_e32 v32, 0xbfb8aa3b, v32
	v_rcp_f32_e32 v48, v48
	v_rcp_f32_e32 v49, v49
	v_rcp_f32_e32 v52, v40
	v_exp_f32_e32 v32, v32
	v_mul_f32_e32 v33, 0xbfb8aa3b, v33
	v_exp_f32_e32 v33, v33
	s_mov_b32 s1, 0x48000
	v_cvt_pk_bf16_f32 v41, v46, v47
	v_add_co_u32_e32 v46, vcc, s1, v124
	v_cvt_pk_bf16_f32 v40, v48, v49
	v_cvt_pk_bf16_f32 v42, v50, v43
	v_cvt_pk_bf16_f32 v43, v51, v52
	v_addc_co_u32_e32 v47, vcc, 0, v125, vcc
	v_add_f32_e32 v32, 1.0, v32
	global_store_dwordx4 v[46:47], v[40:43], off
	v_mul_f32_e32 v36, 0xbfb8aa3b, v36
	v_mul_f32_e32 v37, 0xbfb8aa3b, v37
	v_rcp_f32_e32 v40, v32
	v_add_f32_e32 v32, 1.0, v33
	v_mul_f32_e32 v33, 0xbfb8aa3b, v34
	v_mul_f32_e32 v38, 0xbfb8aa3b, v38
	v_mul_f32_e32 v39, 0xbfb8aa3b, v39
	v_exp_f32_e32 v33, v33
	v_mul_f32_e32 v34, 0xbfb8aa3b, v35
	v_exp_f32_e32 v36, v36
	v_exp_f32_e32 v37, v37
	v_exp_f32_e32 v38, v38
	v_exp_f32_e32 v39, v39
	v_exp_f32_e32 v34, v34
	v_rcp_f32_e32 v35, v32
	v_add_f32_e32 v32, 1.0, v33
	v_add_f32_e32 v36, 1.0, v36
	v_add_f32_e32 v37, 1.0, v37
	v_add_f32_e32 v38, 1.0, v38
	v_add_f32_e32 v39, 1.0, v39
	v_rcp_f32_e32 v41, v32
	v_add_f32_e32 v32, 1.0, v34
	v_mul_f32_e32 v24, 0xbfb8aa3b, v24
	v_rcp_f32_e32 v36, v36
	v_rcp_f32_e32 v37, v37
	v_rcp_f32_e32 v38, v38
	v_rcp_f32_e32 v39, v39
	v_rcp_f32_e32 v42, v32
	v_exp_f32_e32 v24, v24
	v_mul_f32_e32 v25, 0xbfb8aa3b, v25
	v_exp_f32_e32 v25, v25
	s_mov_b64 s[14:15], 0x48000
	v_lshl_add_u64 v[44:45], v[124:125], 0, s[14:15]
	v_cvt_pk_bf16_f32 v32, v36, v37
	v_cvt_pk_bf16_f32 v33, v38, v39
	v_cvt_pk_bf16_f32 v34, v40, v35
	v_cvt_pk_bf16_f32 v35, v41, v42
	v_add_f32_e32 v24, 1.0, v24
	global_store_dwordx4 v[44:45], v[32:35], off offset:256
	v_mul_f32_e32 v28, 0xbfb8aa3b, v28
	v_mul_f32_e32 v30, 0xbfb8aa3b, v30
	v_mul_f32_e32 v31, 0xbfb8aa3b, v31
	v_rcp_f32_e32 v34, v24
	v_add_f32_e32 v24, 1.0, v25
	v_mul_f32_e32 v25, 0xbfb8aa3b, v26
	v_exp_f32_e32 v32, v28
	v_mul_f32_e32 v28, 0xbfb8aa3b, v29
	v_exp_f32_e32 v30, v30
	v_exp_f32_e32 v31, v31
	v_exp_f32_e32 v25, v25
	v_mul_f32_e32 v26, 0xbfb8aa3b, v27
	v_exp_f32_e32 v33, v28
	v_exp_f32_e32 v26, v26
	v_add_f32_e32 v30, 1.0, v30
	v_add_f32_e32 v31, 1.0, v31
	v_rcp_f32_e32 v27, v24
	v_add_f32_e32 v24, 1.0, v25
	v_add_f32_e32 v32, 1.0, v32
	v_add_f32_e32 v33, 1.0, v33
	v_rcp_f32_e32 v30, v30
	v_rcp_f32_e32 v31, v31
	v_rcp_f32_e32 v35, v24
	v_add_f32_e32 v24, 1.0, v26
	v_mul_f32_e32 v16, 0xbfb8aa3b, v16
	v_rcp_f32_e32 v32, v32
	v_rcp_f32_e32 v33, v33
	v_rcp_f32_e32 v36, v24
	v_exp_f32_e32 v16, v16
	v_mul_f32_e32 v17, 0xbfb8aa3b, v17
	v_exp_f32_e32 v17, v17
	s_mov_b32 s1, 0x50000
	v_cvt_pk_bf16_f32 v25, v30, v31
	v_add_co_u32_e32 v30, vcc, s1, v124
	v_cvt_pk_bf16_f32 v24, v32, v33
	v_cvt_pk_bf16_f32 v26, v34, v27
	v_cvt_pk_bf16_f32 v27, v35, v36
	v_addc_co_u32_e32 v31, vcc, 0, v125, vcc
	v_add_f32_e32 v16, 1.0, v16
	global_store_dwordx4 v[30:31], v[24:27], off
	v_mul_f32_e32 v20, 0xbfb8aa3b, v20
	v_mul_f32_e32 v21, 0xbfb8aa3b, v21
	v_rcp_f32_e32 v24, v16
	v_add_f32_e32 v16, 1.0, v17
	v_mul_f32_e32 v17, 0xbfb8aa3b, v18
	v_mul_f32_e32 v22, 0xbfb8aa3b, v22
	v_mul_f32_e32 v23, 0xbfb8aa3b, v23
	v_exp_f32_e32 v17, v17
	v_mul_f32_e32 v18, 0xbfb8aa3b, v19
	v_exp_f32_e32 v20, v20
	v_exp_f32_e32 v21, v21
	v_exp_f32_e32 v22, v22
	v_exp_f32_e32 v23, v23
	v_exp_f32_e32 v18, v18
	v_rcp_f32_e32 v19, v16
	v_add_f32_e32 v16, 1.0, v17
	v_add_f32_e32 v20, 1.0, v20
	v_add_f32_e32 v21, 1.0, v21
	v_add_f32_e32 v22, 1.0, v22
	v_add_f32_e32 v23, 1.0, v23
	v_rcp_f32_e32 v25, v16
	v_add_f32_e32 v16, 1.0, v18
	v_mul_f32_e32 v8, 0xbfb8aa3b, v8
	v_rcp_f32_e32 v20, v20
	v_rcp_f32_e32 v21, v21
	v_rcp_f32_e32 v22, v22
	v_rcp_f32_e32 v23, v23
	v_rcp_f32_e32 v26, v16
	v_exp_f32_e32 v8, v8
	v_mul_f32_e32 v9, 0xbfb8aa3b, v9
	v_exp_f32_e32 v9, v9
	s_mov_b64 s[14:15], 0x50000
	v_lshl_add_u64 v[28:29], v[124:125], 0, s[14:15]
	v_cvt_pk_bf16_f32 v16, v20, v21
	v_cvt_pk_bf16_f32 v17, v22, v23
	v_cvt_pk_bf16_f32 v18, v24, v19
	v_cvt_pk_bf16_f32 v19, v25, v26
	v_add_f32_e32 v8, 1.0, v8
	global_store_dwordx4 v[28:29], v[16:19], off offset:256
	v_mul_f32_e32 v12, 0xbfb8aa3b, v12
	v_mul_f32_e32 v14, 0xbfb8aa3b, v14
	v_mul_f32_e32 v15, 0xbfb8aa3b, v15
	v_rcp_f32_e32 v18, v8
	v_add_f32_e32 v8, 1.0, v9
	v_mul_f32_e32 v9, 0xbfb8aa3b, v10
	v_exp_f32_e32 v16, v12
	v_mul_f32_e32 v12, 0xbfb8aa3b, v13
	v_exp_f32_e32 v14, v14
	v_exp_f32_e32 v15, v15
	v_exp_f32_e32 v9, v9
	v_mul_f32_e32 v10, 0xbfb8aa3b, v11
	v_exp_f32_e32 v17, v12
	v_exp_f32_e32 v10, v10
	v_add_f32_e32 v14, 1.0, v14
	v_add_f32_e32 v15, 1.0, v15
	v_rcp_f32_e32 v11, v8
	v_add_f32_e32 v8, 1.0, v9
	v_add_f32_e32 v16, 1.0, v16
	v_add_f32_e32 v17, 1.0, v17
	v_rcp_f32_e32 v14, v14
	v_rcp_f32_e32 v15, v15
	v_rcp_f32_e32 v19, v8
	v_add_f32_e32 v8, 1.0, v10
	v_mul_f32_e32 v0, 0xbfb8aa3b, v0
	v_rcp_f32_e32 v16, v16
	v_rcp_f32_e32 v17, v17
	v_rcp_f32_e32 v20, v8
	v_exp_f32_e32 v0, v0
	v_mul_f32_e32 v1, 0xbfb8aa3b, v1
	v_exp_f32_e32 v1, v1
	s_mov_b32 s1, 0x58000
	v_cvt_pk_bf16_f32 v9, v14, v15
	v_add_co_u32_e32 v14, vcc, s1, v124
	v_cvt_pk_bf16_f32 v8, v16, v17
	v_cvt_pk_bf16_f32 v10, v18, v11
	v_cvt_pk_bf16_f32 v11, v19, v20
	v_addc_co_u32_e32 v15, vcc, 0, v125, vcc
	v_add_f32_e32 v0, 1.0, v0
	global_store_dwordx4 v[14:15], v[8:11], off
	v_mul_f32_e32 v4, 0xbfb8aa3b, v4
	v_mul_f32_e32 v5, 0xbfb8aa3b, v5
	v_rcp_f32_e32 v8, v0
	v_add_f32_e32 v0, 1.0, v1
	v_mul_f32_e32 v1, 0xbfb8aa3b, v2
	v_mul_f32_e32 v6, 0xbfb8aa3b, v6
	v_mul_f32_e32 v7, 0xbfb8aa3b, v7
	v_exp_f32_e32 v1, v1
	v_mul_f32_e32 v2, 0xbfb8aa3b, v3
	v_exp_f32_e32 v4, v4
	v_exp_f32_e32 v5, v5
	v_exp_f32_e32 v6, v6
	v_exp_f32_e32 v7, v7
	v_exp_f32_e32 v2, v2
	v_rcp_f32_e32 v3, v0
	v_add_f32_e32 v0, 1.0, v1
	v_add_f32_e32 v4, 1.0, v4
	v_add_f32_e32 v5, 1.0, v5
	v_add_f32_e32 v6, 1.0, v6
	v_add_f32_e32 v7, 1.0, v7
	v_rcp_f32_e32 v9, v0
	v_add_f32_e32 v0, 1.0, v2
	v_rcp_f32_e32 v4, v4
	v_rcp_f32_e32 v5, v5
	v_rcp_f32_e32 v6, v6
	v_rcp_f32_e32 v7, v7
	v_rcp_f32_e32 v10, v0
	s_mov_b64 s[14:15], 0x58000
	v_lshl_add_u64 v[12:13], v[124:125], 0, s[14:15]
	v_cvt_pk_bf16_f32 v0, v4, v5
	v_cvt_pk_bf16_f32 v1, v6, v7
	v_cvt_pk_bf16_f32 v2, v8, v3
	v_cvt_pk_bf16_f32 v3, v9, v10
	s_andn2_b64 vcc, exec, s[6:7]
	s_mov_b64 s[6:7], -1
	global_store_dwordx4 v[12:13], v[0:3], off offset:256
	s_cbranch_vccnz .LBB0_268
	s_and_b64 vcc, exec, s[4:5]
	s_cbranch_vccnz .LBB0_267
	s_barrier
	s_branch .LBB0_267

.LBB0_293:
	s_add_i32 s1, s36, 2
	s_ashr_i32 s14, s1, 2
	s_ashr_i32 s15, s14, 31
	s_lshl_b64 s[16:17], s[14:15], 27
	s_add_u32 s9, s27, s16
	s_addc_u32 s15, s28, s17
	s_cmp_lt_i32 s14, 2
	v_mul_f32_e32 v120, 0xbfb8aa3b, v120
	s_cselect_b32 s15, s15, s30
	s_cselect_b32 s9, s9, s29
	s_lshl_b32 s1, s1, 9
	v_exp_f32_e32 v120, v120
	v_mul_f32_e32 v121, 0xbfb8aa3b, v121
	s_and_b32 s1, s1, 0x600
	v_exp_f32_e32 v121, v121
	v_lshl_add_u32 v142, s35, 8, v144
	s_add_u32 s14, s9, s1
	s_addc_u32 s15, s15, 0
	v_ashrrev_i32_e32 v143, 31, v142
	v_mul_f32_e32 v124, 0xbfb8aa3b, v124
	v_lshl_add_u64 v[140:141], v[134:135], 1, s[14:15]
	v_lshlrev_b64 v[148:149], 11, v[142:143]
	v_exp_f32_e32 v143, v124
	v_mul_f32_e32 v124, 0xbfb8aa3b, v125
	v_add_f32_e32 v120, 1.0, v120
	v_exp_f32_e32 v147, v124
	v_lshl_add_u64 v[124:125], v[140:141], 0, v[148:149]
	v_rcp_f32_e32 v148, v120
	v_add_f32_e32 v120, 1.0, v121
	v_mul_f32_e32 v121, 0xbfb8aa3b, v122
	v_mul_f32_e32 v126, 0xbfb8aa3b, v126
	v_mul_f32_e32 v127, 0xbfb8aa3b, v127
	v_exp_f32_e32 v121, v121
	v_mul_f32_e32 v122, 0xbfb8aa3b, v123
	v_exp_f32_e32 v126, v126
	v_exp_f32_e32 v127, v127
	v_exp_f32_e32 v122, v122
	v_rcp_f32_e32 v123, v120
	v_add_f32_e32 v120, 1.0, v121
	v_add_f32_e32 v143, 1.0, v143
	v_add_f32_e32 v147, 1.0, v147
	v_add_f32_e32 v126, 1.0, v126
	v_add_f32_e32 v127, 1.0, v127
	v_rcp_f32_e32 v149, v120
	v_add_f32_e32 v120, 1.0, v122
	v_mul_f32_e32 v112, 0xbfb8aa3b, v112
	v_rcp_f32_e32 v143, v143
	v_rcp_f32_e32 v147, v147
	v_rcp_f32_e32 v126, v126
	v_rcp_f32_e32 v127, v127
	v_rcp_f32_e32 v150, v120
	v_exp_f32_e32 v112, v112
	v_mul_f32_e32 v113, 0xbfb8aa3b, v113
	v_exp_f32_e32 v113, v113
	v_cvt_pk_bf16_f32 v120, v143, v147
	v_cvt_pk_bf16_f32 v121, v126, v127
	v_cvt_pk_bf16_f32 v122, v148, v123
	v_cvt_pk_bf16_f32 v123, v149, v150
	v_add_f32_e32 v112, 1.0, v112
	global_store_dwordx4 v[124:125], v[120:123], off
	v_mul_f32_e32 v116, 0xbfb8aa3b, v116
	v_mul_f32_e32 v117, 0xbfb8aa3b, v117
	v_rcp_f32_e32 v120, v112
	v_add_f32_e32 v112, 1.0, v113
	v_mul_f32_e32 v113, 0xbfb8aa3b, v114
	v_mul_f32_e32 v118, 0xbfb8aa3b, v118
	v_mul_f32_e32 v119, 0xbfb8aa3b, v119
	v_exp_f32_e32 v113, v113
	v_mul_f32_e32 v114, 0xbfb8aa3b, v115
	v_exp_f32_e32 v116, v116
	v_exp_f32_e32 v117, v117
	v_exp_f32_e32 v118, v118
	v_exp_f32_e32 v119, v119
	v_exp_f32_e32 v114, v114
	v_rcp_f32_e32 v115, v112
	v_add_f32_e32 v112, 1.0, v113
	v_add_f32_e32 v116, 1.0, v116
	v_add_f32_e32 v117, 1.0, v117
	v_add_f32_e32 v118, 1.0, v118
	v_add_f32_e32 v119, 1.0, v119
	v_rcp_f32_e32 v121, v112
	v_add_f32_e32 v112, 1.0, v114
	v_rcp_f32_e32 v116, v116
	v_rcp_f32_e32 v117, v117
	v_rcp_f32_e32 v118, v118
	v_rcp_f32_e32 v119, v119
	v_rcp_f32_e32 v122, v112
	v_mul_f32_e32 v104, 0xbfb8aa3b, v104
	v_cvt_pk_bf16_f32 v112, v116, v117
	v_cvt_pk_bf16_f32 v113, v118, v119
	v_cvt_pk_bf16_f32 v114, v120, v115
	v_cvt_pk_bf16_f32 v115, v121, v122
	v_mul_f32_e32 v108, 0xbfb8aa3b, v108
	v_exp_f32_e32 v104, v104
	v_mul_f32_e32 v105, 0xbfb8aa3b, v105
	global_store_dwordx4 v[124:125], v[112:115], off offset:256
	v_exp_f32_e32 v105, v105
	v_add_f32_e32 v104, 1.0, v104
	v_exp_f32_e32 v114, v108
	v_or_b32_e32 v112, 16, v142
	v_ashrrev_i32_e32 v113, 31, v112
	v_lshlrev_b64 v[112:113], 11, v[112:113]
	v_mul_f32_e32 v108, 0xbfb8aa3b, v109
	v_exp_f32_e32 v115, v108
	v_lshl_add_u64 v[108:109], v[140:141], 0, v[112:113]
	v_add_f32_e32 v112, 1.0, v114
	v_rcp_f32_e32 v114, v104
	v_add_f32_e32 v104, 1.0, v105
	v_mul_f32_e32 v105, 0xbfb8aa3b, v106
	v_mul_f32_e32 v110, 0xbfb8aa3b, v110
	v_mul_f32_e32 v111, 0xbfb8aa3b, v111
	v_exp_f32_e32 v105, v105
	v_mul_f32_e32 v106, 0xbfb8aa3b, v107
	v_exp_f32_e32 v110, v110
	v_exp_f32_e32 v111, v111
	v_exp_f32_e32 v106, v106
	v_rcp_f32_e32 v107, v104
	v_add_f32_e32 v104, 1.0, v105
	v_add_f32_e32 v113, 1.0, v115
	v_add_f32_e32 v110, 1.0, v110
	v_add_f32_e32 v111, 1.0, v111
	v_rcp_f32_e32 v115, v104
	v_add_f32_e32 v104, 1.0, v106
	v_mul_f32_e32 v96, 0xbfb8aa3b, v96
	v_rcp_f32_e32 v112, v112
	v_rcp_f32_e32 v113, v113
	v_rcp_f32_e32 v110, v110
	v_rcp_f32_e32 v111, v111
	v_rcp_f32_e32 v116, v104
	v_exp_f32_e32 v96, v96
	v_mul_f32_e32 v97, 0xbfb8aa3b, v97
	v_exp_f32_e32 v97, v97
	v_cvt_pk_bf16_f32 v104, v112, v113
	v_cvt_pk_bf16_f32 v105, v110, v111
	v_cvt_pk_bf16_f32 v106, v114, v107
	v_cvt_pk_bf16_f32 v107, v115, v116
	v_add_f32_e32 v96, 1.0, v96
	global_store_dwordx4 v[108:109], v[104:107], off
	v_mul_f32_e32 v100, 0xbfb8aa3b, v100
	v_mul_f32_e32 v101, 0xbfb8aa3b, v101
	v_rcp_f32_e32 v104, v96
	v_add_f32_e32 v96, 1.0, v97
	v_mul_f32_e32 v97, 0xbfb8aa3b, v98
	v_mul_f32_e32 v102, 0xbfb8aa3b, v102
	v_mul_f32_e32 v103, 0xbfb8aa3b, v103
	v_exp_f32_e32 v97, v97
	v_mul_f32_e32 v98, 0xbfb8aa3b, v99
	v_exp_f32_e32 v100, v100
	v_exp_f32_e32 v101, v101
	v_exp_f32_e32 v102, v102
	v_exp_f32_e32 v103, v103
	v_exp_f32_e32 v98, v98
	v_rcp_f32_e32 v99, v96
	v_add_f32_e32 v96, 1.0, v97
	v_add_f32_e32 v100, 1.0, v100
	v_add_f32_e32 v101, 1.0, v101
	v_add_f32_e32 v102, 1.0, v102
	v_add_f32_e32 v103, 1.0, v103
	v_rcp_f32_e32 v105, v96
	v_add_f32_e32 v96, 1.0, v98
	v_rcp_f32_e32 v100, v100
	v_rcp_f32_e32 v101, v101
	v_rcp_f32_e32 v102, v102
	v_rcp_f32_e32 v103, v103
	v_rcp_f32_e32 v106, v96
	v_mul_f32_e32 v88, 0xbfb8aa3b, v88
	v_cvt_pk_bf16_f32 v96, v100, v101
	v_cvt_pk_bf16_f32 v97, v102, v103
	v_cvt_pk_bf16_f32 v98, v104, v99
	v_cvt_pk_bf16_f32 v99, v105, v106
	v_mul_f32_e32 v92, 0xbfb8aa3b, v92
	v_exp_f32_e32 v88, v88
	v_mul_f32_e32 v89, 0xbfb8aa3b, v89
	global_store_dwordx4 v[108:109], v[96:99], off offset:256
	v_exp_f32_e32 v89, v89
	v_add_f32_e32 v88, 1.0, v88
	v_exp_f32_e32 v98, v92
	v_or_b32_e32 v96, 32, v142
	v_ashrrev_i32_e32 v97, 31, v96
	v_lshlrev_b64 v[96:97], 11, v[96:97]
	v_mul_f32_e32 v92, 0xbfb8aa3b, v93
	v_exp_f32_e32 v99, v92
	v_lshl_add_u64 v[92:93], v[140:141], 0, v[96:97]
	v_add_f32_e32 v96, 1.0, v98
	v_rcp_f32_e32 v98, v88
	v_add_f32_e32 v88, 1.0, v89
	v_mul_f32_e32 v89, 0xbfb8aa3b, v90
	v_mul_f32_e32 v94, 0xbfb8aa3b, v94
	v_mul_f32_e32 v95, 0xbfb8aa3b, v95
	v_exp_f32_e32 v89, v89
	v_mul_f32_e32 v90, 0xbfb8aa3b, v91
	v_exp_f32_e32 v94, v94
	v_exp_f32_e32 v95, v95
	v_exp_f32_e32 v90, v90
	v_rcp_f32_e32 v91, v88
	v_add_f32_e32 v88, 1.0, v89
	v_add_f32_e32 v97, 1.0, v99
	v_add_f32_e32 v94, 1.0, v94
	v_add_f32_e32 v95, 1.0, v95
	v_rcp_f32_e32 v99, v88
	v_add_f32_e32 v88, 1.0, v90
	v_mul_f32_e32 v80, 0xbfb8aa3b, v80
	v_rcp_f32_e32 v96, v96
	v_rcp_f32_e32 v97, v97
	v_rcp_f32_e32 v94, v94
	v_rcp_f32_e32 v95, v95
	v_rcp_f32_e32 v100, v88
	v_exp_f32_e32 v80, v80
	v_mul_f32_e32 v81, 0xbfb8aa3b, v81
	v_exp_f32_e32 v81, v81
	v_cvt_pk_bf16_f32 v88, v96, v97
	v_cvt_pk_bf16_f32 v89, v94, v95
	v_cvt_pk_bf16_f32 v90, v98, v91
	v_cvt_pk_bf16_f32 v91, v99, v100
	v_add_f32_e32 v80, 1.0, v80
	global_store_dwordx4 v[92:93], v[88:91], off
	v_mul_f32_e32 v84, 0xbfb8aa3b, v84
	v_mul_f32_e32 v85, 0xbfb8aa3b, v85
	v_rcp_f32_e32 v88, v80
	v_add_f32_e32 v80, 1.0, v81
	v_mul_f32_e32 v81, 0xbfb8aa3b, v82
	v_mul_f32_e32 v86, 0xbfb8aa3b, v86
	v_mul_f32_e32 v87, 0xbfb8aa3b, v87
	v_exp_f32_e32 v81, v81
	v_mul_f32_e32 v82, 0xbfb8aa3b, v83
	v_exp_f32_e32 v84, v84
	v_exp_f32_e32 v85, v85
	v_exp_f32_e32 v86, v86
	v_exp_f32_e32 v87, v87
	v_exp_f32_e32 v82, v82
	v_rcp_f32_e32 v83, v80
	v_add_f32_e32 v80, 1.0, v81
	v_add_f32_e32 v84, 1.0, v84
	v_add_f32_e32 v85, 1.0, v85
	v_add_f32_e32 v86, 1.0, v86
	v_add_f32_e32 v87, 1.0, v87
	v_rcp_f32_e32 v89, v80
	v_add_f32_e32 v80, 1.0, v82
	v_rcp_f32_e32 v84, v84
	v_rcp_f32_e32 v85, v85
	v_rcp_f32_e32 v86, v86
	v_rcp_f32_e32 v87, v87
	v_rcp_f32_e32 v90, v80
	v_mul_f32_e32 v72, 0xbfb8aa3b, v72
	v_cvt_pk_bf16_f32 v80, v84, v85
	v_cvt_pk_bf16_f32 v81, v86, v87
	v_cvt_pk_bf16_f32 v82, v88, v83
	v_cvt_pk_bf16_f32 v83, v89, v90
	v_mul_f32_e32 v76, 0xbfb8aa3b, v76
	v_exp_f32_e32 v72, v72
	v_mul_f32_e32 v73, 0xbfb8aa3b, v73
	global_store_dwordx4 v[92:93], v[80:83], off offset:256
	v_exp_f32_e32 v73, v73
	v_add_f32_e32 v72, 1.0, v72
	v_exp_f32_e32 v82, v76
	v_or_b32_e32 v80, 48, v142
	v_ashrrev_i32_e32 v81, 31, v80
	v_lshlrev_b64 v[80:81], 11, v[80:81]
	v_mul_f32_e32 v76, 0xbfb8aa3b, v77
	v_exp_f32_e32 v83, v76
	v_lshl_add_u64 v[76:77], v[140:141], 0, v[80:81]
	v_add_f32_e32 v80, 1.0, v82
	v_rcp_f32_e32 v82, v72
	v_add_f32_e32 v72, 1.0, v73
	v_mul_f32_e32 v73, 0xbfb8aa3b, v74
	v_mul_f32_e32 v78, 0xbfb8aa3b, v78
	v_mul_f32_e32 v79, 0xbfb8aa3b, v79
	v_exp_f32_e32 v73, v73
	v_mul_f32_e32 v74, 0xbfb8aa3b, v75
	v_exp_f32_e32 v78, v78
	v_exp_f32_e32 v79, v79
	v_exp_f32_e32 v74, v74
	v_rcp_f32_e32 v75, v72
	v_add_f32_e32 v72, 1.0, v73
	v_add_f32_e32 v81, 1.0, v83
	v_add_f32_e32 v78, 1.0, v78
	v_add_f32_e32 v79, 1.0, v79
	v_rcp_f32_e32 v83, v72
	v_add_f32_e32 v72, 1.0, v74
	v_mul_f32_e32 v64, 0xbfb8aa3b, v64
	v_rcp_f32_e32 v80, v80
	v_rcp_f32_e32 v81, v81
	v_rcp_f32_e32 v78, v78
	v_rcp_f32_e32 v79, v79
	v_rcp_f32_e32 v84, v72
	v_exp_f32_e32 v64, v64
	v_mul_f32_e32 v65, 0xbfb8aa3b, v65
	v_exp_f32_e32 v65, v65
	v_cvt_pk_bf16_f32 v72, v80, v81
	v_cvt_pk_bf16_f32 v73, v78, v79
	v_cvt_pk_bf16_f32 v74, v82, v75
	v_cvt_pk_bf16_f32 v75, v83, v84
	v_add_f32_e32 v64, 1.0, v64
	global_store_dwordx4 v[76:77], v[72:75], off
	v_mul_f32_e32 v68, 0xbfb8aa3b, v68
	v_mul_f32_e32 v69, 0xbfb8aa3b, v69
	v_rcp_f32_e32 v72, v64
	v_add_f32_e32 v64, 1.0, v65
	v_mul_f32_e32 v65, 0xbfb8aa3b, v66
	v_mul_f32_e32 v70, 0xbfb8aa3b, v70
	v_mul_f32_e32 v71, 0xbfb8aa3b, v71
	v_exp_f32_e32 v65, v65
	v_mul_f32_e32 v66, 0xbfb8aa3b, v67
	v_exp_f32_e32 v68, v68
	v_exp_f32_e32 v69, v69
	v_exp_f32_e32 v70, v70
	v_exp_f32_e32 v71, v71
	v_exp_f32_e32 v66, v66
	v_rcp_f32_e32 v67, v64
	v_add_f32_e32 v64, 1.0, v65
	v_add_f32_e32 v68, 1.0, v68
	v_add_f32_e32 v69, 1.0, v69
	v_add_f32_e32 v70, 1.0, v70
	v_add_f32_e32 v71, 1.0, v71
	v_rcp_f32_e32 v73, v64
	v_add_f32_e32 v64, 1.0, v66
	v_mul_f32_e32 v56, 0xbfb8aa3b, v56
	v_rcp_f32_e32 v68, v68
	v_rcp_f32_e32 v69, v69
	v_rcp_f32_e32 v70, v70
	v_rcp_f32_e32 v71, v71
	v_rcp_f32_e32 v74, v64
	v_exp_f32_e32 v56, v56
	v_mul_f32_e32 v57, 0xbfb8aa3b, v57
	v_exp_f32_e32 v57, v57
	v_cvt_pk_bf16_f32 v64, v68, v69
	v_cvt_pk_bf16_f32 v65, v70, v71
	v_cvt_pk_bf16_f32 v66, v72, v67
	v_cvt_pk_bf16_f32 v67, v73, v74
	v_add_f32_e32 v56, 1.0, v56
	global_store_dwordx4 v[76:77], v[64:67], off offset:256
	v_mul_f32_e32 v60, 0xbfb8aa3b, v60
	v_mul_f32_e32 v62, 0xbfb8aa3b, v62
	v_mul_f32_e32 v63, 0xbfb8aa3b, v63
	v_rcp_f32_e32 v66, v56
	v_add_f32_e32 v56, 1.0, v57
	v_mul_f32_e32 v57, 0xbfb8aa3b, v58
	v_exp_f32_e32 v64, v60
	v_mul_f32_e32 v60, 0xbfb8aa3b, v61
	v_exp_f32_e32 v62, v62
	v_exp_f32_e32 v63, v63
	v_exp_f32_e32 v57, v57
	v_mul_f32_e32 v58, 0xbfb8aa3b, v59
	v_exp_f32_e32 v65, v60
	v_exp_f32_e32 v58, v58
	v_add_f32_e32 v62, 1.0, v62
	v_add_f32_e32 v63, 1.0, v63
	v_rcp_f32_e32 v59, v56
	v_add_f32_e32 v56, 1.0, v57
	v_add_f32_e32 v64, 1.0, v64
	v_add_f32_e32 v65, 1.0, v65
	v_rcp_f32_e32 v62, v62
	v_rcp_f32_e32 v63, v63
	v_rcp_f32_e32 v67, v56
	v_add_f32_e32 v56, 1.0, v58
	v_mul_f32_e32 v48, 0xbfb8aa3b, v48
	v_rcp_f32_e32 v64, v64
	v_rcp_f32_e32 v65, v65
	v_rcp_f32_e32 v68, v56
	v_exp_f32_e32 v48, v48
	v_mul_f32_e32 v49, 0xbfb8aa3b, v49
	v_exp_f32_e32 v49, v49
	s_mov_b32 s1, 0x40000
	v_cvt_pk_bf16_f32 v57, v62, v63
	v_add_co_u32_e32 v62, vcc, s1, v124
	v_cvt_pk_bf16_f32 v56, v64, v65
	v_cvt_pk_bf16_f32 v58, v66, v59
	v_cvt_pk_bf16_f32 v59, v67, v68
	v_addc_co_u32_e32 v63, vcc, 0, v125, vcc
	v_add_f32_e32 v48, 1.0, v48
	global_store_dwordx4 v[62:63], v[56:59], off
	v_mul_f32_e32 v52, 0xbfb8aa3b, v52
	v_mul_f32_e32 v53, 0xbfb8aa3b, v53
	v_rcp_f32_e32 v56, v48
	v_add_f32_e32 v48, 1.0, v49
	v_mul_f32_e32 v49, 0xbfb8aa3b, v50
	v_mul_f32_e32 v54, 0xbfb8aa3b, v54
	v_mul_f32_e32 v55, 0xbfb8aa3b, v55
	v_exp_f32_e32 v49, v49
	v_mul_f32_e32 v50, 0xbfb8aa3b, v51
	v_exp_f32_e32 v52, v52
	v_exp_f32_e32 v53, v53
	v_exp_f32_e32 v54, v54
	v_exp_f32_e32 v55, v55
	v_exp_f32_e32 v50, v50
	v_rcp_f32_e32 v51, v48
	v_add_f32_e32 v48, 1.0, v49
	v_add_f32_e32 v52, 1.0, v52
	v_add_f32_e32 v53, 1.0, v53
	v_add_f32_e32 v54, 1.0, v54
	v_add_f32_e32 v55, 1.0, v55
	v_rcp_f32_e32 v57, v48
	v_add_f32_e32 v48, 1.0, v50
	v_mul_f32_e32 v40, 0xbfb8aa3b, v40
	v_rcp_f32_e32 v52, v52
	v_rcp_f32_e32 v53, v53
	v_rcp_f32_e32 v54, v54
	v_rcp_f32_e32 v55, v55
	v_rcp_f32_e32 v58, v48
	v_exp_f32_e32 v40, v40
	v_mul_f32_e32 v41, 0xbfb8aa3b, v41
	v_exp_f32_e32 v41, v41
	s_mov_b64 s[14:15], 0x40000
	v_lshl_add_u64 v[60:61], v[124:125], 0, s[14:15]
	v_cvt_pk_bf16_f32 v48, v52, v53
	v_cvt_pk_bf16_f32 v49, v54, v55
	v_cvt_pk_bf16_f32 v50, v56, v51
	v_cvt_pk_bf16_f32 v51, v57, v58
	v_add_f32_e32 v40, 1.0, v40
	global_store_dwordx4 v[60:61], v[48:51], off offset:256
	v_mul_f32_e32 v44, 0xbfb8aa3b, v44
	v_mul_f32_e32 v46, 0xbfb8aa3b, v46
	v_mul_f32_e32 v47, 0xbfb8aa3b, v47
	v_rcp_f32_e32 v50, v40
	v_add_f32_e32 v40, 1.0, v41
	v_mul_f32_e32 v41, 0xbfb8aa3b, v42
	v_exp_f32_e32 v48, v44
	v_mul_f32_e32 v44, 0xbfb8aa3b, v45
	v_exp_f32_e32 v46, v46
	v_exp_f32_e32 v47, v47
	v_exp_f32_e32 v41, v41
	v_mul_f32_e32 v42, 0xbfb8aa3b, v43
	v_exp_f32_e32 v49, v44
	v_exp_f32_e32 v42, v42
	v_add_f32_e32 v46, 1.0, v46
	v_add_f32_e32 v47, 1.0, v47
	v_rcp_f32_e32 v43, v40
	v_add_f32_e32 v40, 1.0, v41
	v_add_f32_e32 v48, 1.0, v48
	v_add_f32_e32 v49, 1.0, v49
	v_rcp_f32_e32 v46, v46
	v_rcp_f32_e32 v47, v47
	v_rcp_f32_e32 v51, v40
	v_add_f32_e32 v40, 1.0, v42
	v_mul_f32_e32 v32, 0xbfb8aa3b, v32
	v_rcp_f32_e32 v48, v48
	v_rcp_f32_e32 v49, v49
	v_rcp_f32_e32 v52, v40
	v_exp_f32_e32 v32, v32
	v_mul_f32_e32 v33, 0xbfb8aa3b, v33
	v_exp_f32_e32 v33, v33
	s_mov_b32 s1, 0x48000
	v_cvt_pk_bf16_f32 v41, v46, v47
	v_add_co_u32_e32 v46, vcc, s1, v124
	v_cvt_pk_bf16_f32 v40, v48, v49
	v_cvt_pk_bf16_f32 v42, v50, v43
	v_cvt_pk_bf16_f32 v43, v51, v52
	v_addc_co_u32_e32 v47, vcc, 0, v125, vcc
	v_add_f32_e32 v32, 1.0, v32
	global_store_dwordx4 v[46:47], v[40:43], off
	v_mul_f32_e32 v36, 0xbfb8aa3b, v36
	v_mul_f32_e32 v37, 0xbfb8aa3b, v37
	v_rcp_f32_e32 v40, v32
	v_add_f32_e32 v32, 1.0, v33
	v_mul_f32_e32 v33, 0xbfb8aa3b, v34
	v_mul_f32_e32 v38, 0xbfb8aa3b, v38
	v_mul_f32_e32 v39, 0xbfb8aa3b, v39
	v_exp_f32_e32 v33, v33
	v_mul_f32_e32 v34, 0xbfb8aa3b, v35
	v_exp_f32_e32 v36, v36
	v_exp_f32_e32 v37, v37
	v_exp_f32_e32 v38, v38
	v_exp_f32_e32 v39, v39
	v_exp_f32_e32 v34, v34
	v_rcp_f32_e32 v35, v32
	v_add_f32_e32 v32, 1.0, v33
	v_add_f32_e32 v36, 1.0, v36
	v_add_f32_e32 v37, 1.0, v37
	v_add_f32_e32 v38, 1.0, v38
	v_add_f32_e32 v39, 1.0, v39
	v_rcp_f32_e32 v41, v32
	v_add_f32_e32 v32, 1.0, v34
	v_mul_f32_e32 v24, 0xbfb8aa3b, v24
	v_rcp_f32_e32 v36, v36
	v_rcp_f32_e32 v37, v37
	v_rcp_f32_e32 v38, v38
	v_rcp_f32_e32 v39, v39
	v_rcp_f32_e32 v42, v32
	v_exp_f32_e32 v24, v24
	v_mul_f32_e32 v25, 0xbfb8aa3b, v25
	v_exp_f32_e32 v25, v25
	s_mov_b64 s[14:15], 0x48000
	v_lshl_add_u64 v[44:45], v[124:125], 0, s[14:15]
	v_cvt_pk_bf16_f32 v32, v36, v37
	v_cvt_pk_bf16_f32 v33, v38, v39
	v_cvt_pk_bf16_f32 v34, v40, v35
	v_cvt_pk_bf16_f32 v35, v41, v42
	v_add_f32_e32 v24, 1.0, v24
	global_store_dwordx4 v[44:45], v[32:35], off offset:256
	v_mul_f32_e32 v28, 0xbfb8aa3b, v28
	v_mul_f32_e32 v30, 0xbfb8aa3b, v30
	v_mul_f32_e32 v31, 0xbfb8aa3b, v31
	v_rcp_f32_e32 v34, v24
	v_add_f32_e32 v24, 1.0, v25
	v_mul_f32_e32 v25, 0xbfb8aa3b, v26
	v_exp_f32_e32 v32, v28
	v_mul_f32_e32 v28, 0xbfb8aa3b, v29
	v_exp_f32_e32 v30, v30
	v_exp_f32_e32 v31, v31
	v_exp_f32_e32 v25, v25
	v_mul_f32_e32 v26, 0xbfb8aa3b, v27
	v_exp_f32_e32 v33, v28
	v_exp_f32_e32 v26, v26
	v_add_f32_e32 v30, 1.0, v30
	v_add_f32_e32 v31, 1.0, v31
	v_rcp_f32_e32 v27, v24
	v_add_f32_e32 v24, 1.0, v25
	v_add_f32_e32 v32, 1.0, v32
	v_add_f32_e32 v33, 1.0, v33
	v_rcp_f32_e32 v30, v30
	v_rcp_f32_e32 v31, v31
	v_rcp_f32_e32 v35, v24
	v_add_f32_e32 v24, 1.0, v26
	v_mul_f32_e32 v16, 0xbfb8aa3b, v16
	v_rcp_f32_e32 v32, v32
	v_rcp_f32_e32 v33, v33
	v_rcp_f32_e32 v36, v24
	v_exp_f32_e32 v16, v16
	v_mul_f32_e32 v17, 0xbfb8aa3b, v17
	v_exp_f32_e32 v17, v17
	s_mov_b32 s1, 0x50000
	v_cvt_pk_bf16_f32 v25, v30, v31
	v_add_co_u32_e32 v30, vcc, s1, v124
	v_cvt_pk_bf16_f32 v24, v32, v33
	v_cvt_pk_bf16_f32 v26, v34, v27
	v_cvt_pk_bf16_f32 v27, v35, v36
	v_addc_co_u32_e32 v31, vcc, 0, v125, vcc
	v_add_f32_e32 v16, 1.0, v16
	global_store_dwordx4 v[30:31], v[24:27], off
	v_mul_f32_e32 v20, 0xbfb8aa3b, v20
	v_mul_f32_e32 v21, 0xbfb8aa3b, v21
	v_rcp_f32_e32 v24, v16
	v_add_f32_e32 v16, 1.0, v17
	v_mul_f32_e32 v17, 0xbfb8aa3b, v18
	v_mul_f32_e32 v22, 0xbfb8aa3b, v22
	v_mul_f32_e32 v23, 0xbfb8aa3b, v23
	v_exp_f32_e32 v17, v17
	v_mul_f32_e32 v18, 0xbfb8aa3b, v19
	v_exp_f32_e32 v20, v20
	v_exp_f32_e32 v21, v21
	v_exp_f32_e32 v22, v22
	v_exp_f32_e32 v23, v23
	v_exp_f32_e32 v18, v18
	v_rcp_f32_e32 v19, v16
	v_add_f32_e32 v16, 1.0, v17
	v_add_f32_e32 v20, 1.0, v20
	v_add_f32_e32 v21, 1.0, v21
	v_add_f32_e32 v22, 1.0, v22
	v_add_f32_e32 v23, 1.0, v23
	v_rcp_f32_e32 v25, v16
	v_add_f32_e32 v16, 1.0, v18
	v_mul_f32_e32 v8, 0xbfb8aa3b, v8
	v_rcp_f32_e32 v20, v20
	v_rcp_f32_e32 v21, v21
	v_rcp_f32_e32 v22, v22
	v_rcp_f32_e32 v23, v23
	v_rcp_f32_e32 v26, v16
	v_exp_f32_e32 v8, v8
	v_mul_f32_e32 v9, 0xbfb8aa3b, v9
	v_exp_f32_e32 v9, v9
	s_mov_b64 s[14:15], 0x50000
	v_lshl_add_u64 v[28:29], v[124:125], 0, s[14:15]
	v_cvt_pk_bf16_f32 v16, v20, v21
	v_cvt_pk_bf16_f32 v17, v22, v23
	v_cvt_pk_bf16_f32 v18, v24, v19
	v_cvt_pk_bf16_f32 v19, v25, v26
	v_add_f32_e32 v8, 1.0, v8
	global_store_dwordx4 v[28:29], v[16:19], off offset:256
	v_mul_f32_e32 v12, 0xbfb8aa3b, v12
	v_mul_f32_e32 v14, 0xbfb8aa3b, v14
	v_mul_f32_e32 v15, 0xbfb8aa3b, v15
	v_rcp_f32_e32 v18, v8
	v_add_f32_e32 v8, 1.0, v9
	v_mul_f32_e32 v9, 0xbfb8aa3b, v10
	v_exp_f32_e32 v16, v12
	v_mul_f32_e32 v12, 0xbfb8aa3b, v13
	v_exp_f32_e32 v14, v14
	v_exp_f32_e32 v15, v15
	v_exp_f32_e32 v9, v9
	v_mul_f32_e32 v10, 0xbfb8aa3b, v11
	v_exp_f32_e32 v17, v12
	v_exp_f32_e32 v10, v10
	v_add_f32_e32 v14, 1.0, v14
	v_add_f32_e32 v15, 1.0, v15
	v_rcp_f32_e32 v11, v8
	v_add_f32_e32 v8, 1.0, v9
	v_add_f32_e32 v16, 1.0, v16
	v_add_f32_e32 v17, 1.0, v17
	v_rcp_f32_e32 v14, v14
	v_rcp_f32_e32 v15, v15
	v_rcp_f32_e32 v19, v8
	v_add_f32_e32 v8, 1.0, v10
	v_mul_f32_e32 v0, 0xbfb8aa3b, v0
	v_rcp_f32_e32 v16, v16
	v_rcp_f32_e32 v17, v17
	v_rcp_f32_e32 v20, v8
	v_exp_f32_e32 v0, v0
	v_mul_f32_e32 v1, 0xbfb8aa3b, v1
	v_exp_f32_e32 v1, v1
	s_mov_b32 s1, 0x58000
	v_cvt_pk_bf16_f32 v9, v14, v15
	v_add_co_u32_e32 v14, vcc, s1, v124
	v_cvt_pk_bf16_f32 v8, v16, v17
	v_cvt_pk_bf16_f32 v10, v18, v11
	v_cvt_pk_bf16_f32 v11, v19, v20
	v_addc_co_u32_e32 v15, vcc, 0, v125, vcc
	v_add_f32_e32 v0, 1.0, v0
	global_store_dwordx4 v[14:15], v[8:11], off
	v_mul_f32_e32 v4, 0xbfb8aa3b, v4
	v_mul_f32_e32 v5, 0xbfb8aa3b, v5
	v_rcp_f32_e32 v8, v0
	v_add_f32_e32 v0, 1.0, v1
	v_mul_f32_e32 v1, 0xbfb8aa3b, v2
	v_mul_f32_e32 v6, 0xbfb8aa3b, v6
	v_mul_f32_e32 v7, 0xbfb8aa3b, v7
	v_exp_f32_e32 v1, v1
	v_mul_f32_e32 v2, 0xbfb8aa3b, v3
	v_exp_f32_e32 v4, v4
	v_exp_f32_e32 v5, v5
	v_exp_f32_e32 v6, v6
	v_exp_f32_e32 v7, v7
	v_exp_f32_e32 v2, v2
	v_rcp_f32_e32 v3, v0
	v_add_f32_e32 v0, 1.0, v1
	v_add_f32_e32 v4, 1.0, v4
	v_add_f32_e32 v5, 1.0, v5
	v_add_f32_e32 v6, 1.0, v6
	v_add_f32_e32 v7, 1.0, v7
	v_rcp_f32_e32 v9, v0
	v_add_f32_e32 v0, 1.0, v2
	v_rcp_f32_e32 v4, v4
	v_rcp_f32_e32 v5, v5
	v_rcp_f32_e32 v6, v6
	v_rcp_f32_e32 v7, v7
	v_rcp_f32_e32 v10, v0
	s_mov_b64 s[14:15], 0x58000
	v_lshl_add_u64 v[12:13], v[124:125], 0, s[14:15]
	v_cvt_pk_bf16_f32 v0, v4, v5
	v_cvt_pk_bf16_f32 v1, v6, v7
	v_cvt_pk_bf16_f32 v2, v8, v3
	v_cvt_pk_bf16_f32 v3, v9, v10
	s_andn2_b64 vcc, exec, s[6:7]
	s_mov_b64 s[6:7], -1
	global_store_dwordx4 v[12:13], v[0:3], off offset:256
	s_cbranch_vccnz .LBB0_286
	s_and_b64 vcc, exec, s[4:5]
	s_cbranch_vccnz .LBB0_285
	s_barrier
	s_branch .LBB0_285

.LBB0_308:
	v_lshl_add_u64 v[20:21], v[16:17], 0, v[160:161]
	v_add_co_u32_e32 v20, vcc, s13, v20
	v_lshl_add_u64 v[42:43], v[18:19], 0, v[160:161]
	s_nop 0
	v_addc_co_u32_e32 v21, vcc, 0, v21, vcc
	v_add_co_u32_e32 v22, vcc, s12, v42
	global_load_dwordx4 v[34:37], v[20:21], off
	s_nop 0
	v_addc_co_u32_e32 v23, vcc, 0, v43, vcc
	global_load_dwordx4 v[24:27], v[22:23], off
	s_add_i32 s11, s11, -8
	v_lshl_add_u64 v[16:17], v[16:17], 0, s[18:19]
	v_lshl_add_u64 v[18:19], v[18:19], 0, s[30:31]
	s_cmp_eq_u32 s11, 0
	s_waitcnt vmcnt(0) lgkmcnt(0)
	v_mfma_f32_16x16x32_bf16 v[12:15], v[24:27], v[34:37], v[12:15]
	v_add_co_u32_e32 v24, vcc, s14, v42
	s_nop 1
	v_addc_co_u32_e32 v25, vcc, 0, v43, vcc
	global_load_dwordx4 v[26:29], v[24:25], off
	s_waitcnt vmcnt(0) lgkmcnt(0)
	v_mfma_f32_16x16x32_bf16 v[8:11], v[26:29], v[34:37], v[8:11]
	v_add_co_u32_e32 v26, vcc, s15, v42
	s_nop 1
	v_addc_co_u32_e32 v27, vcc, 0, v43, vcc
	global_load_dwordx4 v[38:41], v[26:27], off
	v_add_co_u32_e32 v28, vcc, s16, v42
	s_waitcnt vmcnt(0) lgkmcnt(0)
	v_mfma_f32_16x16x32_bf16 v[4:7], v[38:41], v[34:37], v[4:7]
	v_addc_co_u32_e32 v29, vcc, 0, v43, vcc
	global_load_dwordx4 v[38:41], v[28:29], off
	s_waitcnt vmcnt(0) lgkmcnt(0)
	v_mfma_f32_16x16x32_bf16 v[0:3], v[38:41], v[34:37], v[0:3]
	global_load_dwordx4 v[34:37], v[20:21], off offset:64
	global_load_dwordx4 v[38:41], v[22:23], off offset:64
	s_waitcnt vmcnt(0) lgkmcnt(0)
	v_mfma_f32_16x16x32_bf16 v[12:15], v[38:41], v[34:37], v[12:15]
	global_load_dwordx4 v[38:41], v[24:25], off offset:64
	s_waitcnt vmcnt(0) lgkmcnt(0)
	v_mfma_f32_16x16x32_bf16 v[8:11], v[38:41], v[34:37], v[8:11]
	global_load_dwordx4 v[38:41], v[26:27], off offset:64
	s_waitcnt vmcnt(0) lgkmcnt(0)
	v_mfma_f32_16x16x32_bf16 v[4:7], v[38:41], v[34:37], v[4:7]
	global_load_dwordx4 v[38:41], v[28:29], off offset:64
	s_waitcnt vmcnt(0) lgkmcnt(0)
	v_mfma_f32_16x16x32_bf16 v[0:3], v[38:41], v[34:37], v[0:3]
	global_load_dwordx4 v[34:37], v[20:21], off offset:256
	global_load_dwordx4 v[38:41], v[22:23], off offset:128
	s_waitcnt vmcnt(0) lgkmcnt(0)
	v_mfma_f32_16x16x32_bf16 v[12:15], v[38:41], v[34:37], v[12:15]
	global_load_dwordx4 v[38:41], v[24:25], off offset:128
	s_waitcnt vmcnt(0) lgkmcnt(0)
	v_mfma_f32_16x16x32_bf16 v[8:11], v[38:41], v[34:37], v[8:11]
	global_load_dwordx4 v[38:41], v[26:27], off offset:128
	s_waitcnt vmcnt(0) lgkmcnt(0)
	v_mfma_f32_16x16x32_bf16 v[4:7], v[38:41], v[34:37], v[4:7]
	global_load_dwordx4 v[38:41], v[28:29], off offset:128
	s_waitcnt vmcnt(0) lgkmcnt(0)
	v_mfma_f32_16x16x32_bf16 v[0:3], v[38:41], v[34:37], v[0:3]
	global_load_dwordx4 v[34:37], v[20:21], off offset:320
	global_load_dwordx4 v[38:41], v[22:23], off offset:192
	s_waitcnt vmcnt(0) lgkmcnt(0)
	v_mfma_f32_16x16x32_bf16 v[12:15], v[38:41], v[34:37], v[12:15]
	global_load_dwordx4 v[38:41], v[24:25], off offset:192
	s_waitcnt vmcnt(0) lgkmcnt(0)
	v_mfma_f32_16x16x32_bf16 v[8:11], v[38:41], v[34:37], v[8:11]
	global_load_dwordx4 v[38:41], v[26:27], off offset:192
	s_waitcnt vmcnt(0) lgkmcnt(0)
	v_mfma_f32_16x16x32_bf16 v[4:7], v[38:41], v[34:37], v[4:7]
	global_load_dwordx4 v[38:41], v[28:29], off offset:192
	s_waitcnt vmcnt(0) lgkmcnt(0)
	v_mfma_f32_16x16x32_bf16 v[0:3], v[38:41], v[34:37], v[0:3]
	global_load_dwordx4 v[34:37], v[20:21], off offset:512
	global_load_dwordx4 v[38:41], v[22:23], off offset:256
	s_waitcnt vmcnt(0) lgkmcnt(0)
	v_mfma_f32_16x16x32_bf16 v[12:15], v[38:41], v[34:37], v[12:15]
	global_load_dwordx4 v[38:41], v[24:25], off offset:256
	s_waitcnt vmcnt(0) lgkmcnt(0)
	v_mfma_f32_16x16x32_bf16 v[8:11], v[38:41], v[34:37], v[8:11]
	global_load_dwordx4 v[38:41], v[26:27], off offset:256
	s_waitcnt vmcnt(0) lgkmcnt(0)
	v_mfma_f32_16x16x32_bf16 v[4:7], v[38:41], v[34:37], v[4:7]
	global_load_dwordx4 v[38:41], v[28:29], off offset:256
	s_waitcnt vmcnt(0) lgkmcnt(0)
	v_mfma_f32_16x16x32_bf16 v[0:3], v[38:41], v[34:37], v[0:3]
	global_load_dwordx4 v[34:37], v[20:21], off offset:576
	global_load_dwordx4 v[38:41], v[22:23], off offset:320
	s_waitcnt vmcnt(0) lgkmcnt(0)
	v_mfma_f32_16x16x32_bf16 v[12:15], v[38:41], v[34:37], v[12:15]
	global_load_dwordx4 v[38:41], v[24:25], off offset:320
	s_waitcnt vmcnt(0) lgkmcnt(0)
	v_mfma_f32_16x16x32_bf16 v[8:11], v[38:41], v[34:37], v[8:11]
	global_load_dwordx4 v[38:41], v[26:27], off offset:320
	s_waitcnt vmcnt(0) lgkmcnt(0)
	v_mfma_f32_16x16x32_bf16 v[4:7], v[38:41], v[34:37], v[4:7]
	global_load_dwordx4 v[38:41], v[28:29], off offset:320
	s_waitcnt vmcnt(0) lgkmcnt(0)
	v_mfma_f32_16x16x32_bf16 v[0:3], v[38:41], v[34:37], v[0:3]
	global_load_dwordx4 v[34:37], v[20:21], off offset:768
	global_load_dwordx4 v[38:41], v[22:23], off offset:384
	s_waitcnt vmcnt(0) lgkmcnt(0)
	v_mfma_f32_16x16x32_bf16 v[12:15], v[38:41], v[34:37], v[12:15]
	global_load_dwordx4 v[38:41], v[24:25], off offset:384
	s_waitcnt vmcnt(0) lgkmcnt(0)
	v_mfma_f32_16x16x32_bf16 v[8:11], v[38:41], v[34:37], v[8:11]
	global_load_dwordx4 v[38:41], v[26:27], off offset:384
	s_waitcnt vmcnt(0) lgkmcnt(0)
	v_mfma_f32_16x16x32_bf16 v[4:7], v[38:41], v[34:37], v[4:7]
	global_load_dwordx4 v[38:41], v[28:29], off offset:384
	s_waitcnt vmcnt(0) lgkmcnt(0)
	v_mfma_f32_16x16x32_bf16 v[0:3], v[38:41], v[34:37], v[0:3]
	global_load_dwordx4 v[34:37], v[20:21], off offset:832
	s_nop 0
	global_load_dwordx4 v[20:23], v[22:23], off offset:448
	s_waitcnt vmcnt(0) lgkmcnt(0)
	v_mfma_f32_16x16x32_bf16 v[12:15], v[20:23], v[34:37], v[12:15]
	global_load_dwordx4 v[20:23], v[24:25], off offset:448
	s_waitcnt vmcnt(0) lgkmcnt(0)
	v_mfma_f32_16x16x32_bf16 v[8:11], v[20:23], v[34:37], v[8:11]
	global_load_dwordx4 v[20:23], v[26:27], off offset:448
	s_waitcnt vmcnt(0) lgkmcnt(0)
	v_mfma_f32_16x16x32_bf16 v[4:7], v[20:23], v[34:37], v[4:7]
	global_load_dwordx4 v[20:23], v[28:29], off offset:448
	s_waitcnt vmcnt(0) lgkmcnt(0)
	v_mfma_f32_16x16x32_bf16 v[0:3], v[20:23], v[34:37], v[0:3]
	s_cbranch_scc0 .LBB0_308
	s_lshr_b32 s82, s8, 4
	v_readlane_b32 s8, v252, 27
	s_add_u32 s8, s10, s8
	v_readlane_b32 s11, v252, 28
	s_addc_u32 s11, s2, s11
	s_and_b64 s[0:1], s[0:1], exec
	s_mov_b32 s0, 0x2480000
	s_cselect_b32 s1, s0, 0x2482000
	s_lshl_b32 s0, s9, 6
	s_or_b32 s0, s0, s38
	s_add_u32 s8, s8, s1
	s_addc_u32 s9, s11, 0
	s_ashr_i32 s1, s0, 31
	s_lshl_b64 s[0:1], s[0:1], 2
	v_and_b32_e32 v22, 3, v32
	s_add_u32 s0, s10, s0
	s_addc_u32 s1, s2, s1
	v_lshlrev_b32_e32 v160, 4, v22
	v_lshl_add_u64 v[18:19], s[0:1], 0, v[160:161]
	s_mov_b64 s[0:1], 0x300000
	v_lshl_add_u64 v[16:17], v[18:19], 0, s[0:1]
	s_mov_b32 s0, 0x300000
	v_add_co_u32_e32 v18, vcc, s0, v18
	s_lshl_b64 s[0:1], s[82:83], 14
	s_nop 0
	v_addc_co_u32_e32 v19, vcc, 0, v19, vcc
	global_load_dwordx4 v[18:21], v[18:19], off
	s_add_u32 s0, s10, s0
	s_addc_u32 s1, s2, s1
	v_lshlrev_b32_e32 v160, 1, v30
	s_mov_b64 s[10:11], 0x600000
	v_lshlrev_b32_e32 v28, 9, v22
	s_waitcnt vmcnt(0) lgkmcnt(0)
	v_pk_add_f32 v[12:13], v[12:13], v[18:19]
	s_nop 0
	v_mul_f32_e32 v18, v12, v12
	v_mul_f32_e32 v19, v13, v13
	v_fmamk_f32 v18, v18, 0xbdd2d3e8, v209
	v_fmamk_f32 v19, v19, 0xbdd2d3e8, v209
	v_mul_f32_e32 v18, v12, v18
	v_mul_f32_e32 v19, v13, v19
	v_exp_f32_e32 v18, v18
	v_exp_f32_e32 v19, v19
	v_pk_add_f32 v[14:15], v[14:15], v[20:21]
	v_add_f32_e32 v18, 1.0, v18
	v_add_f32_e32 v19, 1.0, v19
	v_rcp_f32_e32 v18, v18
	v_rcp_f32_e32 v19, v19
	s_nop 0
	v_pk_mul_f32 v[24:25], v[12:13], v[18:19]
	v_mul_f32_e32 v12, v14, v14
	v_mul_f32_e32 v13, v15, v15
	v_fmamk_f32 v12, v12, 0xbdd2d3e8, v209
	v_fmamk_f32 v13, v13, 0xbdd2d3e8, v209
	v_mul_f32_e32 v12, v14, v12
	v_mul_f32_e32 v13, v15, v13
	v_exp_f32_e32 v12, v12
	v_exp_f32_e32 v13, v13
	v_add_f32_e32 v12, 1.0, v12
	v_add_f32_e32 v13, 1.0, v13
	v_rcp_f32_e32 v12, v12
	v_rcp_f32_e32 v13, v13
	s_nop 0
	v_pk_mul_f32 v[26:27], v[14:15], v[12:13]
	global_load_dwordx4 v[12:15], v[16:17], off offset:64
	s_waitcnt vmcnt(0) lgkmcnt(0)
	v_pk_add_f32 v[8:9], v[8:9], v[12:13]
	s_nop 0
	v_mul_f32_e32 v12, v8, v8
	v_mul_f32_e32 v13, v9, v9
	v_fmamk_f32 v12, v12, 0xbdd2d3e8, v209
	v_fmamk_f32 v13, v13, 0xbdd2d3e8, v209
	v_mul_f32_e32 v12, v8, v12
	v_mul_f32_e32 v13, v9, v13
	v_exp_f32_e32 v12, v12
	v_exp_f32_e32 v13, v13
	v_pk_add_f32 v[10:11], v[10:11], v[14:15]
	v_add_f32_e32 v12, 1.0, v12
	v_add_f32_e32 v13, 1.0, v13
	v_rcp_f32_e32 v12, v12
	v_rcp_f32_e32 v13, v13
	s_nop 0
	v_pk_mul_f32 v[8:9], v[8:9], v[12:13]
	v_mul_f32_e32 v12, v10, v10
	v_mul_f32_e32 v13, v11, v11
	v_fmamk_f32 v12, v12, 0xbdd2d3e8, v209
	v_fmamk_f32 v13, v13, 0xbdd2d3e8, v209
	v_mul_f32_e32 v12, v10, v12
	v_mul_f32_e32 v13, v11, v13
	v_exp_f32_e32 v12, v12
	v_exp_f32_e32 v13, v13
	v_add_f32_e32 v12, 1.0, v12
	v_add_f32_e32 v13, 1.0, v13
	v_rcp_f32_e32 v12, v12
	v_rcp_f32_e32 v13, v13
	s_nop 0
	v_pk_mul_f32 v[10:11], v[10:11], v[12:13]
	global_load_dwordx4 v[12:15], v[16:17], off offset:128
	s_waitcnt vmcnt(0) lgkmcnt(0)
	v_pk_add_f32 v[4:5], v[4:5], v[12:13]
	s_nop 0
	v_mul_f32_e32 v12, v4, v4
	v_mul_f32_e32 v13, v5, v5
	v_fmamk_f32 v12, v12, 0xbdd2d3e8, v209
	v_fmamk_f32 v13, v13, 0xbdd2d3e8, v209
	v_mul_f32_e32 v12, v4, v12
	v_mul_f32_e32 v13, v5, v13
	v_exp_f32_e32 v12, v12
	v_exp_f32_e32 v13, v13
	v_pk_add_f32 v[6:7], v[6:7], v[14:15]
	v_add_f32_e32 v12, 1.0, v12
	v_add_f32_e32 v13, 1.0, v13
	v_rcp_f32_e32 v12, v12
	v_rcp_f32_e32 v13, v13
	s_nop 0
	v_pk_mul_f32 v[12:13], v[4:5], v[12:13]
	v_mul_f32_e32 v4, v6, v6
	v_mul_f32_e32 v5, v7, v7
	v_fmamk_f32 v4, v4, 0xbdd2d3e8, v209
	v_fmamk_f32 v5, v5, 0xbdd2d3e8, v209
	v_mul_f32_e32 v4, v6, v4
	v_mul_f32_e32 v5, v7, v5
	v_exp_f32_e32 v4, v4
	v_exp_f32_e32 v5, v5
	v_cvt_pk_bf16_f32 v12, v12, v13
	v_add_f32_e32 v4, 1.0, v4
	v_add_f32_e32 v5, 1.0, v5
	v_rcp_f32_e32 v4, v4
	v_rcp_f32_e32 v5, v5
	s_nop 0
	v_pk_mul_f32 v[14:15], v[6:7], v[4:5]
	global_load_dwordx4 v[4:7], v[16:17], off offset:192
	v_cvt_pk_bf16_f32 v13, v14, v15
	s_waitcnt vmcnt(0) lgkmcnt(0)
	v_pk_add_f32 v[0:1], v[0:1], v[4:5]
	s_nop 0
	v_mul_f32_e32 v4, v0, v0
	v_mul_f32_e32 v5, v1, v1
	v_fmamk_f32 v4, v4, 0xbdd2d3e8, v209
	v_fmamk_f32 v5, v5, 0xbdd2d3e8, v209
	v_mul_f32_e32 v4, v0, v4
	v_mul_f32_e32 v5, v1, v5
	v_exp_f32_e32 v4, v4
	v_exp_f32_e32 v5, v5
	v_pk_add_f32 v[2:3], v[2:3], v[6:7]
	v_add_f32_e32 v4, 1.0, v4
	v_add_f32_e32 v5, 1.0, v5
	v_rcp_f32_e32 v4, v4
	v_rcp_f32_e32 v5, v5
	s_nop 0
	v_pk_mul_f32 v[18:19], v[0:1], v[4:5]
	v_mul_f32_e32 v0, v2, v2
	v_mul_f32_e32 v1, v3, v3
	v_fmamk_f32 v0, v0, 0xbdd2d3e8, v209
	v_fmamk_f32 v1, v1, 0xbdd2d3e8, v209
	v_mul_f32_e32 v0, v2, v0
	v_mul_f32_e32 v1, v3, v1
	v_exp_f32_e32 v0, v0
	v_exp_f32_e32 v1, v1
	v_cvt_pk_bf16_f32 v14, v18, v19
	v_add_f32_e32 v0, 1.0, v0
	v_add_f32_e32 v1, 1.0, v1
	v_rcp_f32_e32 v0, v0
	v_rcp_f32_e32 v1, v1
	s_nop 0
	v_pk_mul_f32 v[20:21], v[2:3], v[0:1]
	v_lshl_add_u64 v[0:1], s[0:1], 0, v[160:161]
	v_lshlrev_b32_e32 v160, 3, v22
	v_lshl_add_u64 v[16:17], v[0:1], 0, s[10:11]
	v_lshl_add_u64 v[0:1], s[8:9], 0, v[160:161]
	v_lshlrev_b32_e32 v2, 7, v31
	v_mov_b32_e32 v3, v161
	v_lshl_add_u64 v[0:1], v[0:1], 0, v[2:3]
	s_mov_b64 s[8:9], 0x800000
	v_lshl_add_u64 v[22:23], v[0:1], 0, s[8:9]
	v_add_co_u32_e32 v0, vcc, s12, v0
	v_cvt_pk_bf16_f32 v2, v8, v9
	s_nop 0
	v_addc_co_u32_e32 v1, vcc, 0, v1, vcc
	global_load_dwordx2 v[4:5], v[0:1], off
	global_load_dwordx2 v[6:7], v[22:23], off offset:32
	v_cvt_pk_bf16_f32 v3, v10, v11
	global_load_dwordx2 v[8:9], v[22:23], off offset:64
	global_load_dwordx2 v[10:11], v[22:23], off offset:96
	v_cvt_pk_bf16_f32 v0, v24, v25
	v_cvt_pk_bf16_f32 v1, v26, v27
	v_cvt_pk_bf16_f32 v15, v20, v21
	s_mov_b64 s[8:9], -1
	s_and_b64 vcc, exec, s[6:7]
	s_waitcnt vmcnt(0) lgkmcnt(0)
	v_mfma_f32_16x16x32_bf16 v[4:7], v[4:7], v[0:3], 0
	v_mfma_f32_16x16x32_bf16 v[18:21], v[8:11], v[12:15], v[4:7]
	s_nop 7
	v_cndmask_b32_e64 v6, v21, 0, s[4:5]
	v_cndmask_b32_e64 v7, v20, 0, s[4:5]
	v_cndmask_b32_e64 v8, v19, 0, s[4:5]
	v_cndmask_b32_e64 v9, v18, 0, s[4:5]
	s_cbranch_vccz .LBB0_311
	v_lshlrev_b32_e32 v4, 1, v28
	v_mov_b32_e32 v5, v161
	v_lshl_add_u64 v[4:5], v[16:17], 0, v[4:5]
	v_cvt_pk_bf16_f32 v10, v9, v8
	global_store_short v[4:5], v10, off
	v_cvt_pk_bf16_f32 v10, v8, s0
	global_store_short v[4:5], v10, off offset:256
	v_cvt_pk_bf16_f32 v10, v7, v6
	global_store_short v[4:5], v10, off offset:512
	v_cvt_pk_bf16_f32 v10, v6, s0
	global_store_short v[4:5], v10, off offset:768
	s_mov_b64 s[8:9], 0
.LBB0_311:
	v_lshlrev_b32_e32 v4, 7, v30
	v_mov_b32_e32 v5, v161
	v_lshl_add_u64 v[4:5], s[0:1], 0, v[4:5]
	v_lshl_add_u64 v[4:5], v[4:5], 0, v[160:161]
	s_mov_b64 s[0:1], 0x400000
	s_andn2_b64 vcc, exec, s[8:9]
	v_lshl_add_u64 v[4:5], v[4:5], 0, s[0:1]
	s_cbranch_vccnz .LBB0_313
	v_cvt_pk_bf16_f32 v8, v9, v8
	v_cvt_pk_bf16_f32 v9, v7, v6
	global_store_dwordx2 v[4:5], v[8:9], off
.LBB0_313:
	global_load_dwordx2 v[6:7], v[22:23], off offset:2048
	s_nop 0
	global_load_dwordx2 v[8:9], v[22:23], off offset:2080
	global_load_dwordx2 v[18:19], v[22:23], off offset:2112
	global_load_dwordx2 v[20:21], v[22:23], off offset:2144
	v_cndmask_b32_e64 v10, 0, 1, s[6:7]
	v_cmp_ne_u32_e64 s[0:1], 1, v10
	s_andn2_b64 vcc, exec, s[6:7]
	s_mov_b64 s[6:7], -1
	s_waitcnt vmcnt(0) lgkmcnt(0)
	v_mfma_f32_16x16x32_bf16 v[6:9], v[6:9], v[0:3], 0
	v_mfma_f32_16x16x32_bf16 v[18:21], v[18:21], v[12:15], v[6:9]
	s_nop 7
	v_cndmask_b32_e64 v6, v21, 0, s[4:5]
	v_cndmask_b32_e64 v7, v20, 0, s[4:5]
	v_cndmask_b32_e64 v8, v19, 0, s[4:5]
	v_cndmask_b32_e64 v9, v18, 0, s[4:5]
	s_cbranch_vccnz .LBB0_315
	v_lshlrev_b32_e32 v160, 1, v28
	v_lshl_add_u64 v[10:11], v[16:17], 0, v[160:161]
	v_add_co_u32_e32 v10, vcc, 0x1000, v10
	v_cvt_pk_bf16_f32 v18, v9, v8
	s_nop 0
	v_addc_co_u32_e32 v11, vcc, 0, v11, vcc
	global_store_short v[10:11], v18, off
	v_cvt_pk_bf16_f32 v18, v8, s0
	global_store_short v[10:11], v18, off offset:256
	v_cvt_pk_bf16_f32 v18, v7, v6
	global_store_short v[10:11], v18, off offset:512
	v_cvt_pk_bf16_f32 v18, v6, s0
	s_mov_b64 s[6:7], 0
	global_store_short v[10:11], v18, off offset:768
.LBB0_315:
	s_andn2_b64 vcc, exec, s[6:7]
	s_cbranch_vccnz .LBB0_317
	v_cvt_pk_bf16_f32 v8, v9, v8
	v_cvt_pk_bf16_f32 v9, v7, v6
	global_store_dwordx2 v[4:5], v[8:9], off offset:32
.LBB0_317:
	v_add_co_u32_e32 v10, vcc, 0x1000, v22
	s_mov_b64 s[6:7], -1
	s_nop 0
	v_addc_co_u32_e32 v11, vcc, 0, v23, vcc
	global_load_dwordx2 v[6:7], v[10:11], off
	global_load_dwordx2 v[8:9], v[10:11], off offset:32
	global_load_dwordx2 v[18:19], v[10:11], off offset:64
	global_load_dwordx2 v[20:21], v[10:11], off offset:96
	s_and_b64 vcc, exec, s[0:1]
	s_waitcnt vmcnt(0) lgkmcnt(0)
	v_mfma_f32_16x16x32_bf16 v[6:9], v[6:9], v[0:3], 0
	v_mfma_f32_16x16x32_bf16 v[18:21], v[18:21], v[12:15], v[6:9]
	s_nop 7
	v_cndmask_b32_e64 v6, v21, 0, s[4:5]
	v_cndmask_b32_e64 v7, v20, 0, s[4:5]
	v_cndmask_b32_e64 v8, v19, 0, s[4:5]
	v_cndmask_b32_e64 v9, v18, 0, s[4:5]
	s_cbranch_vccnz .LBB0_319
	v_lshlrev_b32_e32 v160, 1, v28
	v_lshl_add_u64 v[10:11], v[16:17], 0, v[160:161]
	v_add_co_u32_e32 v10, vcc, 0x2000, v10
	v_cvt_pk_bf16_f32 v18, v9, v8
	s_nop 0
	v_addc_co_u32_e32 v11, vcc, 0, v11, vcc
	global_store_short v[10:11], v18, off
	v_cvt_pk_bf16_f32 v18, v8, s0
	global_store_short v[10:11], v18, off offset:256
	v_cvt_pk_bf16_f32 v18, v7, v6
	global_store_short v[10:11], v18, off offset:512
	v_cvt_pk_bf16_f32 v18, v6, s0
	s_mov_b64 s[6:7], 0
	global_store_short v[10:11], v18, off offset:768
.LBB0_319:
	s_andn2_b64 vcc, exec, s[6:7]
	s_cbranch_vccnz .LBB0_321
	v_cvt_pk_bf16_f32 v8, v9, v8
	v_cvt_pk_bf16_f32 v9, v7, v6
	global_store_dwordx2 v[4:5], v[8:9], off offset:64
.LBB0_321:
	v_add_co_u32_e32 v10, vcc, 0x1000, v22
	s_nop 1
	v_addc_co_u32_e32 v11, vcc, 0, v23, vcc
	global_load_dwordx2 v[6:7], v[10:11], off offset:2048
	global_load_dwordx2 v[8:9], v[10:11], off offset:2080
	s_and_b64 vcc, exec, s[0:1]
	s_waitcnt vmcnt(0) lgkmcnt(0)
	v_mfma_f32_16x16x32_bf16 v[0:3], v[6:9], v[0:3], 0
	global_load_dwordx2 v[6:7], v[10:11], off offset:2112
	global_load_dwordx2 v[8:9], v[10:11], off offset:2144
	s_waitcnt vmcnt(0) lgkmcnt(0)
	v_mfma_f32_16x16x32_bf16 v[6:9], v[6:9], v[12:15], v[0:3]
	s_nop 7
	v_cndmask_b32_e64 v0, v9, 0, s[4:5]
	v_cndmask_b32_e64 v1, v8, 0, s[4:5]
	v_cndmask_b32_e64 v2, v7, 0, s[4:5]
	v_cndmask_b32_e64 v3, v6, 0, s[4:5]
	s_mov_b64 s[4:5], -1
	s_cbranch_vccnz .LBB0_323
	v_lshlrev_b32_e32 v160, 1, v28
	v_lshl_add_u64 v[6:7], v[16:17], 0, v[160:161]
	v_add_co_u32_e32 v6, vcc, 0x3000, v6
	v_cvt_pk_bf16_f32 v8, v3, v2
	s_nop 0
	v_addc_co_u32_e32 v7, vcc, 0, v7, vcc
	global_store_short v[6:7], v8, off
	v_cvt_pk_bf16_f32 v8, v2, s0
	global_store_short v[6:7], v8, off offset:256
	v_cvt_pk_bf16_f32 v8, v1, v0
	global_store_short v[6:7], v8, off offset:512
	v_cvt_pk_bf16_f32 v8, v0, s0
	s_mov_b64 s[4:5], 0
	global_store_short v[6:7], v8, off offset:768
.LBB0_323:
	s_andn2_b64 vcc, exec, s[4:5]
	s_cbranch_vccnz .LBB0_325
	v_cvt_pk_bf16_f32 v2, v3, v2
	v_cvt_pk_bf16_f32 v3, v1, v0
	global_store_dwordx2 v[4:5], v[2:3], off offset:96

.LBB0_326:
	s_and_b64 vcc, exec, s[0:1]
	s_cbranch_vccz .LBB0_340
	v_mov_b32_e32 v0, 0xe8
	s_lshl_b32 s2, s42, 5
	v_add_u32_e32 v0, s91, v0
	ds_read_b64 v[0:1], v0
	v_mbcnt_lo_u32_b32 v13, -1, 0
	v_mbcnt_hi_u32_b32 v13, -1, v13
	s_add_i32 s2, s2, 0x7ffff000
	v_add_u32_e32 v2, s57, v13
	s_and_b32 s2, s2, 0x7fffff80
	v_ashrrev_i32_e32 v9, 2, v2
	s_waitcnt lgkmcnt(0)
	v_readfirstlane_b32 s0, v0
	v_add_u32_e32 v0, s2, v9
	v_readfirstlane_b32 s1, v1
	v_ashrrev_i32_e32 v1, 31, v0
	v_lshlrev_b64 v[0:1], 10, v[0:1]
	v_and_b32_e32 v8, 3, v13
	v_lshl_add_u64 v[0:1], s[0:1], 0, v[0:1]
	s_mov_b64 s[4:5], 0x19200000
	v_lshl_add_u64 v[4:5], v[0:1], 0, s[4:5]
	v_lshlrev_b32_e32 v0, 8, v8
	v_mov_b32_e32 v1, v161
	v_lshl_add_u64 v[6:7], v[4:5], 0, v[0:1]
	s_barrier
	global_load_dwordx4 v[14:17], v[6:7], off
	global_load_dwordx4 v[18:21], v[6:7], off offset:16
	global_load_dwordx4 v[22:25], v[6:7], off offset:32
	global_load_dwordx4 v[26:29], v[6:7], off offset:48
	global_load_dwordx4 v[30:33], v[6:7], off offset:64
	global_load_dwordx4 v[34:37], v[6:7], off offset:80
	global_load_dwordx4 v[0:3], v[6:7], off offset:96
	s_and_b32 s6, s42, 3
	s_lshl_b32 s82, s6, 8
	v_lshl_add_u64 v[4:5], v[4:5], 0, s[82:83]
	s_lshl_b64 s[4:5], s[22:23], 2
	v_lshlrev_b32_e32 v160, 7, v8
	v_cmp_lt_i32_e32 vcc, v214, v213
	v_lshlrev_b32_e32 v9, 1, v9
	v_readlane_b32 s12, v253, 39
	s_waitcnt vmcnt(0) lgkmcnt(0)
	v_lshlrev_b32_e32 v11, 16, v14
	v_and_b32_e32 v12, 0xffff0000, v14
	v_add_f32_e32 v52, 0, v11
	v_mul_f32_e32 v10, v12, v12
	v_lshlrev_b32_e32 v14, 16, v15
	v_add_f32_e32 v12, v52, v12
	v_fmac_f32_e32 v10, v11, v11
	v_and_b32_e32 v15, 0xffff0000, v15
	v_add_f32_e32 v11, v12, v14
	v_fmac_f32_e32 v10, v14, v14
	v_lshlrev_b32_e32 v38, 16, v16
	v_add_f32_e32 v11, v11, v15
	v_fmac_f32_e32 v10, v15, v15
	v_and_b32_e32 v16, 0xffff0000, v16
	v_add_f32_e32 v11, v11, v38
	v_fmac_f32_e32 v10, v38, v38
	v_lshlrev_b32_e32 v39, 16, v17
	v_add_f32_e32 v11, v11, v16
	v_fmac_f32_e32 v10, v16, v16
	v_and_b32_e32 v17, 0xffff0000, v17
	v_add_f32_e32 v11, v11, v39
	v_fmac_f32_e32 v10, v39, v39
	v_lshlrev_b32_e32 v40, 16, v18
	v_add_f32_e32 v11, v11, v17
	v_fmac_f32_e32 v10, v17, v17
	v_and_b32_e32 v18, 0xffff0000, v18
	v_add_f32_e32 v11, v11, v40
	v_fmac_f32_e32 v10, v40, v40
	v_lshlrev_b32_e32 v41, 16, v19
	v_add_f32_e32 v11, v11, v18
	v_fmac_f32_e32 v10, v18, v18
	v_and_b32_e32 v19, 0xffff0000, v19
	v_add_f32_e32 v11, v11, v41
	v_fmac_f32_e32 v10, v41, v41
	v_lshlrev_b32_e32 v42, 16, v20
	v_add_f32_e32 v11, v11, v19
	v_fmac_f32_e32 v10, v19, v19
	v_and_b32_e32 v20, 0xffff0000, v20
	v_add_f32_e32 v11, v11, v42
	v_fmac_f32_e32 v10, v42, v42
	v_lshlrev_b32_e32 v43, 16, v21
	v_add_f32_e32 v11, v11, v20
	v_fmac_f32_e32 v10, v20, v20
	v_and_b32_e32 v21, 0xffff0000, v21
	v_add_f32_e32 v11, v11, v43
	v_fmac_f32_e32 v10, v43, v43
	v_lshlrev_b32_e32 v44, 16, v22
	v_add_f32_e32 v11, v11, v21
	v_fmac_f32_e32 v10, v21, v21
	v_and_b32_e32 v22, 0xffff0000, v22
	v_add_f32_e32 v11, v11, v44
	v_fmac_f32_e32 v10, v44, v44
	v_lshlrev_b32_e32 v45, 16, v23
	v_add_f32_e32 v11, v11, v22
	v_fmac_f32_e32 v10, v22, v22
	v_and_b32_e32 v23, 0xffff0000, v23
	v_add_f32_e32 v11, v11, v45
	v_fmac_f32_e32 v10, v45, v45
	v_lshlrev_b32_e32 v46, 16, v24
	v_add_f32_e32 v11, v11, v23
	v_fmac_f32_e32 v10, v23, v23
	v_and_b32_e32 v24, 0xffff0000, v24
	v_add_f32_e32 v11, v11, v46
	v_fmac_f32_e32 v10, v46, v46
	v_lshlrev_b32_e32 v47, 16, v25
	v_add_f32_e32 v11, v11, v24
	v_fmac_f32_e32 v10, v24, v24
	v_and_b32_e32 v25, 0xffff0000, v25
	v_add_f32_e32 v11, v11, v47
	v_fmac_f32_e32 v10, v47, v47
	v_lshlrev_b32_e32 v48, 16, v26
	v_add_f32_e32 v11, v11, v25
	v_fmac_f32_e32 v10, v25, v25
	v_and_b32_e32 v26, 0xffff0000, v26
	v_add_f32_e32 v11, v11, v48
	v_fmac_f32_e32 v10, v48, v48
	v_lshlrev_b32_e32 v49, 16, v27
	v_add_f32_e32 v11, v11, v26
	v_fmac_f32_e32 v10, v26, v26
	v_and_b32_e32 v27, 0xffff0000, v27
	v_add_f32_e32 v11, v11, v49
	v_fmac_f32_e32 v10, v49, v49
	global_load_dwordx4 v[14:17], v[6:7], off offset:112
	v_lshlrev_b32_e32 v50, 16, v28
	v_add_f32_e32 v11, v11, v27
	v_fmac_f32_e32 v10, v27, v27
	v_and_b32_e32 v28, 0xffff0000, v28
	v_add_f32_e32 v11, v11, v50
	v_fmac_f32_e32 v10, v50, v50
	v_lshlrev_b32_e32 v51, 16, v29
	v_add_f32_e32 v11, v11, v28
	v_fmac_f32_e32 v10, v28, v28
	v_and_b32_e32 v29, 0xffff0000, v29
	v_add_f32_e32 v11, v11, v51
	v_fmac_f32_e32 v10, v51, v51
	v_add_f32_e32 v11, v11, v29
	v_fmac_f32_e32 v10, v29, v29
	v_lshlrev_b32_e32 v12, 16, v30
	v_and_b32_e32 v18, 0xffff0000, v30
	v_add_f32_e32 v11, v11, v12
	v_fmac_f32_e32 v10, v12, v12
	v_lshlrev_b32_e32 v19, 16, v31
	v_add_f32_e32 v11, v11, v18
	v_fmac_f32_e32 v10, v18, v18
	v_and_b32_e32 v20, 0xffff0000, v31
	v_add_f32_e32 v11, v11, v19
	v_fmac_f32_e32 v10, v19, v19
	v_lshlrev_b32_e32 v21, 16, v32
	v_add_f32_e32 v11, v11, v20
	v_fmac_f32_e32 v10, v20, v20
	v_add_f32_e32 v11, v11, v21
	v_fmac_f32_e32 v10, v21, v21
	global_load_dwordx4 v[18:21], v[6:7], off offset:128
	v_and_b32_e32 v22, 0xffff0000, v32
	v_lshlrev_b32_e32 v23, 16, v33
	v_add_f32_e32 v11, v11, v22
	v_fmac_f32_e32 v10, v22, v22
	v_and_b32_e32 v24, 0xffff0000, v33
	v_add_f32_e32 v11, v11, v23
	v_fmac_f32_e32 v10, v23, v23
	v_add_f32_e32 v11, v11, v24
	v_fmac_f32_e32 v10, v24, v24
	v_lshlrev_b32_e32 v12, 16, v34
	v_and_b32_e32 v22, 0xffff0000, v34
	v_add_f32_e32 v11, v11, v12
	v_fmac_f32_e32 v10, v12, v12
	v_lshlrev_b32_e32 v23, 16, v35
	v_add_f32_e32 v11, v11, v22
	v_fmac_f32_e32 v10, v22, v22
	v_and_b32_e32 v24, 0xffff0000, v35
	v_add_f32_e32 v11, v11, v23
	v_fmac_f32_e32 v10, v23, v23
	v_lshlrev_b32_e32 v25, 16, v36
	v_add_f32_e32 v11, v11, v24
	v_fmac_f32_e32 v10, v24, v24
	v_and_b32_e32 v26, 0xffff0000, v36
	v_add_f32_e32 v11, v11, v25
	v_fmac_f32_e32 v10, v25, v25
	v_lshlrev_b32_e32 v27, 16, v37
	v_add_f32_e32 v11, v11, v26
	v_fmac_f32_e32 v10, v26, v26
	global_load_dwordx4 v[22:25], v[6:7], off offset:144
	v_and_b32_e32 v28, 0xffff0000, v37
	v_add_f32_e32 v11, v11, v27
	v_fmac_f32_e32 v10, v27, v27
	v_add_f32_e32 v11, v11, v28
	v_fmac_f32_e32 v10, v28, v28
	v_lshlrev_b32_e32 v12, 16, v0
	v_and_b32_e32 v0, 0xffff0000, v0
	v_lshlrev_b32_e32 v28, 16, v3
	v_and_b32_e32 v29, 0xffff0000, v3
	v_add_f32_e32 v3, v11, v12
	v_fmac_f32_e32 v10, v12, v12
	v_lshlrev_b32_e32 v26, 16, v1
	v_add_f32_e32 v3, v3, v0
	v_fmac_f32_e32 v10, v0, v0
	v_and_b32_e32 v1, 0xffff0000, v1
	v_add_f32_e32 v0, v3, v26
	v_fmac_f32_e32 v10, v26, v26
	v_lshlrev_b32_e32 v27, 16, v2
	v_add_f32_e32 v0, v0, v1
	v_fmac_f32_e32 v10, v1, v1
	v_and_b32_e32 v2, 0xffff0000, v2
	v_add_f32_e32 v0, v0, v27
	v_fmac_f32_e32 v10, v27, v27
	v_add_f32_e32 v11, v0, v2
	v_fmac_f32_e32 v10, v2, v2
	global_load_dwordx4 v[0:3], v[6:7], off offset:160
	v_add_f32_e32 v11, v11, v28
	v_fmac_f32_e32 v10, v28, v28
	v_add_f32_e32 v11, v11, v29
	v_fmac_f32_e32 v10, v29, v29
	s_waitcnt vmcnt(0) lgkmcnt(0)
	v_lshlrev_b32_e32 v12, 16, v14
	v_and_b32_e32 v14, 0xffff0000, v14
	v_add_f32_e32 v11, v11, v12
	v_fmac_f32_e32 v10, v12, v12
	v_lshlrev_b32_e32 v26, 16, v15
	v_add_f32_e32 v11, v11, v14
	v_fmac_f32_e32 v10, v14, v14
	v_and_b32_e32 v15, 0xffff0000, v15
	v_add_f32_e32 v11, v11, v26
	v_fmac_f32_e32 v10, v26, v26
	v_lshlrev_b32_e32 v27, 16, v16
	v_add_f32_e32 v11, v11, v15
	v_fmac_f32_e32 v10, v15, v15
	v_and_b32_e32 v16, 0xffff0000, v16
	v_add_f32_e32 v11, v11, v27
	v_fmac_f32_e32 v10, v27, v27
	v_lshlrev_b32_e32 v28, 16, v17
	v_and_b32_e32 v29, 0xffff0000, v17
	v_add_f32_e32 v11, v11, v16
	v_fmac_f32_e32 v10, v16, v16
	global_load_dwordx4 v[14:17], v[6:7], off offset:176
	v_add_f32_e32 v11, v11, v28
	v_fmac_f32_e32 v10, v28, v28
	v_add_f32_e32 v11, v11, v29
	v_fmac_f32_e32 v10, v29, v29
	v_lshlrev_b32_e32 v12, 16, v18
	v_and_b32_e32 v18, 0xffff0000, v18
	v_add_f32_e32 v11, v11, v12
	v_fmac_f32_e32 v10, v12, v12
	v_lshlrev_b32_e32 v26, 16, v19
	v_add_f32_e32 v11, v11, v18
	v_fmac_f32_e32 v10, v18, v18
	v_and_b32_e32 v19, 0xffff0000, v19
	v_add_f32_e32 v11, v11, v26
	v_fmac_f32_e32 v10, v26, v26
	v_lshlrev_b32_e32 v27, 16, v20
	v_and_b32_e32 v28, 0xffff0000, v20
	v_lshlrev_b32_e32 v29, 16, v21
	v_and_b32_e32 v30, 0xffff0000, v21
	v_add_f32_e32 v11, v11, v19
	v_fmac_f32_e32 v10, v19, v19
	global_load_dwordx4 v[18:21], v[6:7], off offset:192
	v_add_f32_e32 v11, v11, v27
	v_fmac_f32_e32 v10, v27, v27
	v_add_f32_e32 v11, v11, v28
	v_fmac_f32_e32 v10, v28, v28
	v_add_f32_e32 v11, v11, v29
	v_fmac_f32_e32 v10, v29, v29
	v_add_f32_e32 v11, v11, v30
	v_lshlrev_b32_e32 v12, 16, v22
	v_fmac_f32_e32 v10, v30, v30
	v_and_b32_e32 v22, 0xffff0000, v22
	v_add_f32_e32 v11, v11, v12
	v_lshlrev_b32_e32 v26, 16, v23
	v_fmac_f32_e32 v10, v12, v12
	v_add_f32_e32 v11, v11, v22
	v_and_b32_e32 v23, 0xffff0000, v23
	v_fmac_f32_e32 v10, v22, v22
	v_add_f32_e32 v11, v11, v26
	v_lshlrev_b32_e32 v27, 16, v24
	v_fmac_f32_e32 v10, v26, v26
	v_add_f32_e32 v11, v11, v23
	v_and_b32_e32 v28, 0xffff0000, v24
	v_lshlrev_b32_e32 v29, 16, v25
	v_and_b32_e32 v30, 0xffff0000, v25
	v_fmac_f32_e32 v10, v23, v23
	v_add_f32_e32 v11, v11, v27
	global_load_dwordx4 v[22:25], v[6:7], off offset:208
	v_fmac_f32_e32 v10, v27, v27
	v_add_f32_e32 v11, v11, v28
	v_fmac_f32_e32 v10, v28, v28
	v_add_f32_e32 v11, v11, v29
	v_fmac_f32_e32 v10, v29, v29
	v_add_f32_e32 v11, v11, v30
	v_fmac_f32_e32 v10, v30, v30
	v_lshlrev_b32_e32 v12, 16, v0
	v_and_b32_e32 v0, 0xffff0000, v0
	v_lshlrev_b32_e32 v27, 16, v2
	v_and_b32_e32 v28, 0xffff0000, v2
	v_add_f32_e32 v2, v11, v12
	v_lshlrev_b32_e32 v26, 16, v1
	v_fmac_f32_e32 v10, v12, v12
	v_add_f32_e32 v2, v2, v0
	v_and_b32_e32 v1, 0xffff0000, v1
	v_fmac_f32_e32 v10, v0, v0
	v_add_f32_e32 v0, v2, v26
	v_fmac_f32_e32 v10, v26, v26
	v_add_f32_e32 v0, v0, v1
	v_lshlrev_b32_e32 v29, 16, v3
	v_and_b32_e32 v30, 0xffff0000, v3
	v_fmac_f32_e32 v10, v1, v1
	v_add_f32_e32 v11, v0, v27
	global_load_dwordx4 v[0:3], v[6:7], off offset:224
	v_fmac_f32_e32 v10, v27, v27
	v_add_f32_e32 v11, v11, v28
	v_fmac_f32_e32 v10, v28, v28
	v_add_f32_e32 v11, v11, v29
	v_fmac_f32_e32 v10, v29, v29
	v_add_f32_e32 v11, v11, v30
	v_fmac_f32_e32 v10, v30, v30
	s_waitcnt vmcnt(0) lgkmcnt(0)
	v_lshlrev_b32_e32 v12, 16, v14
	v_and_b32_e32 v14, 0xffff0000, v14
	v_add_f32_e32 v11, v11, v12
	v_fmac_f32_e32 v10, v12, v12
	v_lshlrev_b32_e32 v26, 16, v15
	v_add_f32_e32 v11, v11, v14
	v_fmac_f32_e32 v10, v14, v14
	v_and_b32_e32 v15, 0xffff0000, v15
	v_add_f32_e32 v11, v11, v26
	v_fmac_f32_e32 v10, v26, v26
	v_lshlrev_b32_e32 v27, 16, v16
	v_add_f32_e32 v11, v11, v15
	v_fmac_f32_e32 v10, v15, v15
	v_and_b32_e32 v16, 0xffff0000, v16
	v_add_f32_e32 v11, v11, v27
	v_fmac_f32_e32 v10, v27, v27
	v_lshlrev_b32_e32 v28, 16, v17
	v_add_f32_e32 v11, v11, v16
	v_fmac_f32_e32 v10, v16, v16
	v_and_b32_e32 v17, 0xffff0000, v17
	v_add_f32_e32 v11, v11, v28
	v_fmac_f32_e32 v10, v28, v28
	v_add_f32_e32 v11, v11, v17
	v_fmac_f32_e32 v10, v17, v17
	v_lshlrev_b32_e32 v12, 16, v18
	v_and_b32_e32 v14, 0xffff0000, v18
	v_add_f32_e32 v11, v11, v12
	v_fmac_f32_e32 v10, v12, v12
	v_lshlrev_b32_e32 v15, 16, v19
	v_add_f32_e32 v11, v11, v14
	v_fmac_f32_e32 v10, v14, v14
	v_and_b32_e32 v16, 0xffff0000, v19
	v_add_f32_e32 v11, v11, v15
	v_fmac_f32_e32 v10, v15, v15
	v_lshlrev_b32_e32 v17, 16, v20
	v_add_f32_e32 v11, v11, v16
	v_fmac_f32_e32 v10, v16, v16
	v_add_f32_e32 v11, v11, v17
	v_fmac_f32_e32 v10, v17, v17
	global_load_dwordx4 v[14:17], v[6:7], off offset:240
	v_and_b32_e32 v18, 0xffff0000, v20
	v_lshlrev_b32_e32 v19, 16, v21
	v_add_f32_e32 v11, v11, v18
	v_and_b32_e32 v20, 0xffff0000, v21
	v_fmac_f32_e32 v10, v18, v18
	v_add_f32_e32 v11, v11, v19
	v_fmac_f32_e32 v10, v19, v19
	v_add_f32_e32 v11, v11, v20
	v_lshlrev_b32_e32 v12, 16, v22
	v_fmac_f32_e32 v10, v20, v20
	v_and_b32_e32 v6, 0xffff0000, v22
	v_add_f32_e32 v11, v11, v12
	v_lshlrev_b32_e32 v7, 16, v23
	v_fmac_f32_e32 v10, v12, v12
	v_add_f32_e32 v11, v11, v6
	v_and_b32_e32 v18, 0xffff0000, v23
	v_fmac_f32_e32 v10, v6, v6
	v_add_f32_e32 v6, v11, v7
	v_lshlrev_b32_e32 v19, 16, v24
	v_fmac_f32_e32 v10, v7, v7
	v_add_f32_e32 v6, v6, v18
	v_and_b32_e32 v20, 0xffff0000, v24
	v_fmac_f32_e32 v10, v18, v18
	v_add_f32_e32 v6, v6, v19
	v_lshlrev_b32_e32 v21, 16, v25
	v_fmac_f32_e32 v10, v19, v19
	v_add_f32_e32 v6, v6, v20
	v_and_b32_e32 v22, 0xffff0000, v25
	v_fmac_f32_e32 v10, v20, v20
	v_add_f32_e32 v6, v6, v21
	v_fmac_f32_e32 v10, v21, v21
	v_add_f32_e32 v6, v6, v22
	v_lshlrev_b32_e32 v7, 16, v0
	v_fmac_f32_e32 v10, v22, v22
	v_and_b32_e32 v0, 0xffff0000, v0
	v_add_f32_e32 v6, v6, v7
	v_lshlrev_b32_e32 v11, 16, v1
	v_fmac_f32_e32 v10, v7, v7
	v_add_f32_e32 v6, v6, v0
	v_fmac_f32_e32 v10, v0, v0
	v_add_f32_e32 v0, v6, v11
	v_lshlrev_b32_e32 v7, 16, v2
	v_and_b32_e32 v6, 0xffff0000, v1
	v_fmac_f32_e32 v10, v11, v11
	v_add_f32_e32 v11, v0, v6
	v_pk_mul_f32 v[0:1], v[6:7], v[6:7]
	v_add_f32_e32 v12, v11, v7
	v_add_f32_e32 v0, v0, v10
	v_add_f32_e32 v32, v1, v0
	v_mov_b32_e32 v0, 56
	v_lshlrev_b32_e32 v6, 6, v8
	v_add_u32_e32 v0, s91, v0
	ds_read_b64 v[0:1], v0
	v_mov_b32_e32 v7, v161
	v_lshl_add_u64 v[4:5], v[4:5], 0, v[6:7]
	v_lshlrev_b32_e32 v11, 16, v3
	v_and_b32_e32 v10, 0xffff0000, v2
	s_waitcnt lgkmcnt(0)
	v_readfirstlane_b32 s8, v0
	v_mov_b32_e32 v0, 64
	v_readfirstlane_b32 s7, v1
	v_add_u32_e32 v0, s91, v0
	ds_read_b64 v[6:7], v0
	s_add_u32 s8, s8, s4
	s_addc_u32 s7, s7, s5
	s_lshl_b32 s10, s6, 9
	s_add_u32 s8, s8, s10
	s_addc_u32 s9, s7, 0
	v_lshl_add_u64 v[0:1], s[8:9], 0, v[160:161]
	s_waitcnt lgkmcnt(0)
	v_readfirstlane_b32 s8, v6
	v_readfirstlane_b32 s7, v7
	s_add_u32 s4, s8, s4
	global_load_dwordx4 v[18:21], v[4:5], off
	s_addc_u32 s5, s7, s5
	s_add_u32 s4, s4, s10
	s_addc_u32 s5, s5, 0
	v_lshl_add_u64 v[6:7], s[4:5], 0, v[160:161]
	global_load_dwordx4 v[22:25], v[0:1], off
	global_load_dwordx4 v[26:29], v[6:7], off
	v_add_f32_e32 v2, v12, v10
	v_pk_mul_f32 v[30:31], v[10:11], v[10:11]
	v_add_f32_e32 v12, v2, v11
	v_add_f32_e32 v10, v30, v32
	s_waitcnt vmcnt(0)
	v_lshlrev_b32_e32 v2, 16, v14
	v_and_b32_e32 v3, 0xffff0000, v3
	v_add_f32_e32 v10, v31, v10
	v_pk_mul_f32 v[30:31], v[2:3], v[2:3]
	v_add_f32_e32 v12, v12, v3
	v_add_f32_e32 v3, v31, v10
	v_add_f32_e32 v10, v12, v2
	v_add_f32_e32 v12, v30, v3
	v_lshlrev_b32_e32 v3, 16, v15
	v_and_b32_e32 v2, 0xffff0000, v14
	v_pk_mul_f32 v[30:31], v[2:3], v[2:3]
	v_add_f32_e32 v10, v10, v2
	v_add_f32_e32 v2, v30, v12
	v_add_f32_e32 v12, v31, v2
	global_load_dwordx4 v[30:33], v[0:1], off offset:16
	global_load_dwordx4 v[34:37], v[6:7], off offset:16
	v_add_f32_e32 v10, v10, v3
	v_lshlrev_b32_e32 v3, 16, v16
	v_and_b32_e32 v2, 0xffff0000, v15
	v_pk_mul_f32 v[14:15], v[2:3], v[2:3]
	v_add_f32_e32 v10, v10, v2
	v_add_f32_e32 v2, v14, v12
	v_add_f32_e32 v10, v10, v3
	v_add_f32_e32 v12, v15, v2
	v_lshlrev_b32_e32 v3, 16, v17
	v_and_b32_e32 v2, 0xffff0000, v16
	v_pk_mul_f32 v[14:15], v[2:3], v[2:3]
	v_and_b32_e32 v11, 0xffff0000, v17
	v_add_f32_e32 v10, v10, v2
	v_add_f32_e32 v2, v14, v12
	v_add_f32_e32 v3, v10, v3
	v_add_f32_e32 v10, v15, v2
	v_mul_f32_e32 v2, v11, v11
	v_cndmask_b32_e32 v12, v211, v214, vcc
	v_lshlrev_b32_e32 v12, 2, v12
	v_pk_add_f32 v[2:3], v[2:3], v[10:11]
	ds_bpermute_b32 v11, v12, v3
	ds_bpermute_b32 v10, v12, v2
	v_cmp_lt_i32_e32 vcc, v215, v213
	s_mov_b32 s4, 0x3b000000
	v_mul_u32_u24_e32 v8, 0x2200, v8
	v_cndmask_b32_e32 v12, v211, v215, vcc
	v_lshlrev_b32_e32 v12, 2, v12
	s_waitcnt lgkmcnt(0)
	v_pk_add_f32 v[2:3], v[2:3], v[10:11]
	ds_bpermute_b32 v11, v12, v3
	ds_bpermute_b32 v10, v12, v2
	v_add3_u32 v38, 0, v9, v8
	s_or_b32 s6, s6, s39
	s_ashr_i32 s7, s6, 31
	s_lshl_b64 s[8:9], s[6:7], 16
	s_waitcnt lgkmcnt(0)
	v_pk_add_f32 v[2:3], v[2:3], v[10:11]
	s_lshl_b32 s6, s6, 7
	v_pk_mul_f32 v[2:3], v[2:3], s[4:5] op_sel_hi:[1,0]
	s_mov_b32 s4, 0x800000
	v_fma_f32 v2, -v3, v3, v2
	v_max_f32_e32 v2, 0, v2
	v_add_f32_e32 v2, 0x358637bd, v2
	v_mul_f32_e32 v10, 0x4b800000, v2
	v_cmp_gt_f32_e32 vcc, s4, v2
	s_ashr_i32 s7, s6, 31
	s_lshl_b64 s[6:7], s[6:7], 2
	v_cndmask_b32_e32 v2, v2, v10, vcc
	v_rsq_f32_e32 v2, v2
	v_mov_b32_e32 v41, v161
	v_mov_b32_e32 v43, v161
	v_mul_f32_e32 v10, 0x45800000, v2
	v_cndmask_b32_e32 v2, v2, v10, vcc
	v_and_b32_e32 v11, 0xffff0000, v18
	v_sub_f32_e32 v8, v11, v3
	v_mul_f32_e32 v8, v8, v2
	v_lshlrev_b32_e32 v12, 16, v19
	v_and_b32_e32 v14, 0xffff0000, v19
	v_fma_f32 v8, v23, v8, v27
	v_cvt_pk_bf16_f32 v8, v8, s0
	ds_write_b16 v38, v8 offset:272
	v_sub_f32_e32 v8, v12, v3
	v_mul_f32_e32 v8, v8, v2
	v_fma_f32 v8, v24, v8, v28
	v_cvt_pk_bf16_f32 v8, v8, s0
	ds_write_b16 v38, v8 offset:544
	v_sub_f32_e32 v8, v14, v3
	v_mul_f32_e32 v8, v8, v2
	v_fmac_f32_e32 v29, v25, v8
	v_lshlrev_b32_e32 v15, 16, v20
	v_cvt_pk_bf16_f32 v8, v29, s0
	ds_write_b16 v38, v8 offset:816
	v_sub_f32_e32 v8, v15, v3
	v_mul_f32_e32 v8, v8, v2
	v_and_b32_e32 v16, 0xffff0000, v20
	v_lshlrev_b32_e32 v17, 16, v21
	v_lshlrev_b32_e32 v10, 16, v18
	s_waitcnt vmcnt(0)
	v_fma_f32 v8, v30, v8, v34
	v_cvt_pk_bf16_f32 v8, v8, s0
	ds_write_b16 v38, v8 offset:1088
	v_sub_f32_e32 v8, v16, v3
	v_mul_f32_e32 v8, v8, v2
	v_fma_f32 v8, v31, v8, v35
	v_cvt_pk_bf16_f32 v8, v8, s0
	ds_write_b16 v38, v8 offset:1360
	v_sub_f32_e32 v8, v17, v3
	v_mul_f32_e32 v8, v8, v2
	v_fma_f32 v8, v32, v8, v36
	v_and_b32_e32 v18, 0xffff0000, v21
	v_cvt_pk_bf16_f32 v8, v8, s0
	v_sub_f32_e32 v10, v10, v3
	ds_write_b16 v38, v8 offset:1632
	v_sub_f32_e32 v8, v18, v3
	v_mul_f32_e32 v10, v10, v2
	v_mul_f32_e32 v8, v8, v2
	v_fma_f32 v10, v22, v10, v26
	v_fmac_f32_e32 v37, v33, v8
	v_cvt_pk_bf16_f32 v10, v10, s0
	v_cvt_pk_bf16_f32 v8, v37, s0
	ds_write_b16 v38, v10
	ds_write_b16 v38, v8 offset:1904
	global_load_dwordx4 v[8:11], v[4:5], off offset:16
	global_load_dwordx4 v[14:17], v[6:7], off offset:32
	global_load_dwordx4 v[18:21], v[0:1], off offset:32
	global_load_dwordx4 v[22:25], v[0:1], off offset:48
	global_load_dwordx4 v[26:29], v[6:7], off offset:48
	s_waitcnt vmcnt(0) lgkmcnt(0)
	v_lshlrev_b32_e32 v12, 16, v8
	v_and_b32_e32 v8, 0xffff0000, v8
	v_sub_f32_e32 v8, v8, v3
	v_mul_f32_e32 v8, v8, v2
	v_fma_f32 v8, v19, v8, v15
	v_lshlrev_b32_e32 v30, 16, v9
	v_cvt_pk_bf16_f32 v8, v8, s0
	ds_write_b16 v38, v8 offset:2448
	v_sub_f32_e32 v8, v30, v3
	v_mul_f32_e32 v8, v8, v2
	v_fma_f32 v8, v20, v8, v16
	v_and_b32_e32 v9, 0xffff0000, v9
	v_cvt_pk_bf16_f32 v8, v8, s0
	ds_write_b16 v38, v8 offset:2720
	v_sub_f32_e32 v8, v9, v3
	v_mul_f32_e32 v8, v8, v2
	v_fmac_f32_e32 v17, v21, v8
	v_lshlrev_b32_e32 v31, 16, v10
	v_cvt_pk_bf16_f32 v8, v17, s0
	ds_write_b16 v38, v8 offset:2992
	v_sub_f32_e32 v8, v31, v3
	v_mul_f32_e32 v8, v8, v2
	v_fma_f32 v8, v22, v8, v26
	v_and_b32_e32 v10, 0xffff0000, v10
	v_cvt_pk_bf16_f32 v8, v8, s0
	ds_write_b16 v38, v8 offset:3264
	v_sub_f32_e32 v8, v10, v3
	v_mul_f32_e32 v8, v8, v2
	v_fma_f32 v8, v23, v8, v27
	v_lshlrev_b32_e32 v32, 16, v11
	v_cvt_pk_bf16_f32 v8, v8, s0
	ds_write_b16 v38, v8 offset:3536
	v_sub_f32_e32 v8, v32, v3
	v_mul_f32_e32 v8, v8, v2
	v_fma_f32 v8, v24, v8, v28
	v_and_b32_e32 v11, 0xffff0000, v11
	v_cvt_pk_bf16_f32 v8, v8, s0
	v_sub_f32_e32 v12, v12, v3
	ds_write_b16 v38, v8 offset:3808
	v_sub_f32_e32 v8, v11, v3
	v_mul_f32_e32 v12, v12, v2
	v_mul_f32_e32 v8, v8, v2
	v_fma_f32 v12, v18, v12, v14
	v_fmac_f32_e32 v29, v25, v8
	v_cvt_pk_bf16_f32 v12, v12, s0
	v_cvt_pk_bf16_f32 v8, v29, s0
	ds_write_b16 v38, v12 offset:2176
	ds_write_b16 v38, v8 offset:4080
	global_load_dwordx4 v[8:11], v[4:5], off offset:32
	global_load_dwordx4 v[14:17], v[6:7], off offset:64
	global_load_dwordx4 v[18:21], v[0:1], off offset:64
	global_load_dwordx4 v[22:25], v[0:1], off offset:80
	global_load_dwordx4 v[26:29], v[6:7], off offset:80
	s_waitcnt vmcnt(0) lgkmcnt(0)
	v_lshlrev_b32_e32 v12, 16, v8
	v_and_b32_e32 v8, 0xffff0000, v8
	v_sub_f32_e32 v8, v8, v3
	v_mul_f32_e32 v8, v8, v2
	v_fma_f32 v8, v19, v8, v15
	v_lshlrev_b32_e32 v30, 16, v9
	v_cvt_pk_bf16_f32 v8, v8, s0
	ds_write_b16 v38, v8 offset:4624
	v_sub_f32_e32 v8, v30, v3
	v_mul_f32_e32 v8, v8, v2
	v_fma_f32 v8, v20, v8, v16
	v_and_b32_e32 v9, 0xffff0000, v9
	v_cvt_pk_bf16_f32 v8, v8, s0
	ds_write_b16 v38, v8 offset:4896
	v_sub_f32_e32 v8, v9, v3
	v_mul_f32_e32 v8, v8, v2
	v_fmac_f32_e32 v17, v21, v8
	v_lshlrev_b32_e32 v31, 16, v10
	v_cvt_pk_bf16_f32 v8, v17, s0
	ds_write_b16 v38, v8 offset:5168
	v_sub_f32_e32 v8, v31, v3
	v_mul_f32_e32 v8, v8, v2
	v_fma_f32 v8, v22, v8, v26
	v_and_b32_e32 v10, 0xffff0000, v10
	v_cvt_pk_bf16_f32 v8, v8, s0
	ds_write_b16 v38, v8 offset:5440
	v_sub_f32_e32 v8, v10, v3
	v_mul_f32_e32 v8, v8, v2
	v_fma_f32 v8, v23, v8, v27
	v_lshlrev_b32_e32 v32, 16, v11
	v_cvt_pk_bf16_f32 v8, v8, s0
	ds_write_b16 v38, v8 offset:5712
	v_sub_f32_e32 v8, v32, v3
	v_mul_f32_e32 v8, v8, v2
	v_fma_f32 v8, v24, v8, v28
	v_and_b32_e32 v11, 0xffff0000, v11
	v_cvt_pk_bf16_f32 v8, v8, s0
	v_sub_f32_e32 v12, v12, v3
	ds_write_b16 v38, v8 offset:5984
	v_sub_f32_e32 v8, v11, v3
	v_mul_f32_e32 v12, v12, v2
	v_mul_f32_e32 v8, v8, v2
	v_fma_f32 v12, v18, v12, v14
	v_fmac_f32_e32 v29, v25, v8
	v_cvt_pk_bf16_f32 v12, v12, s0
	v_cvt_pk_bf16_f32 v8, v29, s0
	ds_write_b16 v38, v12 offset:4352
	ds_write_b16 v38, v8 offset:6256
	global_load_dwordx4 v[8:11], v[4:5], off offset:48
	global_load_dwordx4 v[14:17], v[6:7], off offset:96
	global_load_dwordx4 v[18:21], v[0:1], off offset:96
	global_load_dwordx4 v[22:25], v[0:1], off offset:112
	s_nop 0
	global_load_dwordx4 v[4:7], v[6:7], off offset:112
	v_mov_b32_e32 v29, v161
	s_waitcnt vmcnt(0) lgkmcnt(0)
	v_lshlrev_b32_e32 v0, 16, v8
	v_sub_f32_e32 v0, v0, v3
	v_mul_f32_e32 v0, v0, v2
	v_fma_f32 v0, v18, v0, v14
	v_and_b32_e32 v1, 0xffff0000, v8
	v_cvt_pk_bf16_f32 v0, v0, s0
	ds_write_b16 v38, v0 offset:6528
	v_sub_f32_e32 v0, v1, v3
	v_mul_f32_e32 v0, v0, v2
	v_fma_f32 v0, v19, v0, v15
	v_lshlrev_b32_e32 v8, 16, v9
	v_cvt_pk_bf16_f32 v0, v0, s0
	ds_write_b16 v38, v0 offset:6800
	v_sub_f32_e32 v0, v8, v3
	v_mul_f32_e32 v0, v0, v2
	v_fma_f32 v0, v20, v0, v16
	v_and_b32_e32 v9, 0xffff0000, v9
	v_cvt_pk_bf16_f32 v0, v0, s0
	ds_write_b16 v38, v0 offset:7072
	v_sub_f32_e32 v0, v9, v3
	v_mul_f32_e32 v0, v0, v2
	v_fmac_f32_e32 v17, v21, v0
	v_lshlrev_b32_e32 v12, 16, v10
	v_cvt_pk_bf16_f32 v0, v17, s0
	ds_write_b16 v38, v0 offset:7344
	v_sub_f32_e32 v0, v12, v3
	v_mul_f32_e32 v0, v0, v2
	v_fma_f32 v0, v22, v0, v4
	v_and_b32_e32 v10, 0xffff0000, v10
	v_cvt_pk_bf16_f32 v0, v0, s0
	ds_write_b16 v38, v0 offset:7616
	v_sub_f32_e32 v0, v10, v3
	v_mul_f32_e32 v0, v0, v2
	v_fma_f32 v0, v23, v0, v5
	v_lshlrev_b32_e32 v26, 16, v11
	v_cvt_pk_bf16_f32 v0, v0, s0
	ds_write_b16 v38, v0 offset:7888
	v_sub_f32_e32 v0, v26, v3
	v_mul_f32_e32 v0, v0, v2
	v_fma_f32 v0, v24, v0, v6
	v_and_b32_e32 v11, 0xffff0000, v11
	v_cvt_pk_bf16_f32 v0, v0, s0
	ds_write_b16 v38, v0 offset:8160
	v_sub_f32_e32 v0, v11, v3
	v_mul_f32_e32 v0, v0, v2
	v_fmac_f32_e32 v7, v25, v0
	v_cvt_pk_bf16_f32 v0, v7, s0
	ds_write_b16 v38, v0 offset:8432
	v_mov_b32_e32 v0, 0x48
	s_waitcnt lgkmcnt(0)
	s_barrier
	v_and_b32_e32 v7, 15, v13
	v_add_u32_e32 v0, s91, v0
	ds_read_b64 v[0:1], v0
	v_or_b32_e32 v160, s2, v7
	v_bfe_u32 v17, v13, 4, 2
	v_lshlrev_b64 v[10:11], 10, v[160:161]
	v_or_b32_e32 v14, 16, v160
	s_waitcnt lgkmcnt(0)
	v_readfirstlane_b32 s5, v1
	v_mov_b32_e32 v1, 0x50
	v_readfirstlane_b32 s4, v0
	v_add_u32_e32 v1, s91, v1
	ds_read_b64 v[2:3], v1
	v_or_b32_e32 v18, 32, v160
	v_or_b32_e32 v22, 48, v160
	v_or_b32_e32 v28, 64, v160
	v_or_b32_e32 v40, 0x50, v160
	s_waitcnt lgkmcnt(0)
	v_readfirstlane_b32 s11, v2
	v_readfirstlane_b32 s10, v3
	s_add_u32 s6, s11, s6
	s_addc_u32 s7, s10, s7
	s_add_u32 s0, s0, s82
	s_addc_u32 s1, s1, 0
	s_lshl_b32 s10, s12, 1
	s_add_u32 s10, s0, s10
	s_addc_u32 s11, s1, 0
	s_add_u32 s0, s4, s8
	v_or_b32_e32 v42, 0x60, v160
	v_or_b32_e32 v160, 0x70, v160
	s_addc_u32 s1, s5, s9
	v_lshlrev_b32_e32 v24, 9, v7
	v_mov_b32_e32 v25, v161
	v_lshlrev_b64 v[44:45], 10, v[160:161]
	v_lshl_add_u64 v[0:1], s[0:1], 0, v[24:25]
	v_lshlrev_b32_e32 v160, 5, v17
	v_lshl_add_u64 v[4:5], v[0:1], 0, v[160:161]
	global_load_dwordx4 v[0:3], v[4:5], off
	global_load_dwordx4 v[32:35], v[4:5], off offset:16
	v_lshlrev_b32_e32 v8, 3, v17
	v_mov_b32_e32 v9, v161
	v_lshl_add_u64 v[4:5], s[10:11], 0, v[8:9]
	s_mov_b64 s[8:9], 0xd200000
	v_lshl_add_u64 v[4:5], v[4:5], 0, s[8:9]
	v_lshlrev_b32_e32 v20, 2, v7
	v_mov_b32_e32 v21, v161
	v_lshl_add_u64 v[10:11], v[4:5], 0, v[10:11]
	v_lshl_add_u64 v[36:37], s[6:7], 0, v[20:21]
	global_load_dwordx2 v[46:47], v[10:11], off
	global_load_dword v48, v[36:37], off
	v_or_b32_e32 v9, s12, v7
	v_mul_lo_u32 v9, v9, s93
	v_add_u32_e32 v9, 0, v9
	v_lshl_add_u32 v27, v17, 4, v9
	v_cmp_le_u32_e32 vcc, v8, v7
	global_load_dword v50, v[36:37], off offset:64
	global_load_dword v30, v[36:37], off offset:128
	global_load_dword v26, v[36:37], off offset:192
	global_load_dword v20, v[36:37], off offset:256
	global_load_dword v16, v[36:37], off offset:320
	global_load_dword v12, v[36:37], off offset:384
	global_load_dword v6, v[36:37], off offset:448
	ds_read_b128 v[36:39], v27
	v_or_b32_e32 v31, 2, v8
	v_or_b32_e32 v49, 3, v8
	v_or_b32_e32 v51, 4, v8
	v_or_b32_e32 v52, 5, v8
	v_or_b32_e32 v53, 6, v8
	v_or_b32_e32 v54, 7, v8
	v_or_b32_e32 v25, 16, v7
	s_mov_b32 s8, 0
	s_mov_b64 s[6:7], 0
	s_waitcnt vmcnt(0) lgkmcnt(0)
	v_cndmask_b32_e32 v0, 0, v0, vcc
	v_cmp_lt_u32_e32 vcc, v8, v7
	s_nop 1
	v_cndmask_b32_e32 v1, 0, v1, vcc
	v_cmp_le_u32_e32 vcc, v31, v7
	v_cvt_pk_bf16_f32 v0, v0, v1
	s_nop 0
	v_cndmask_b32_e32 v2, 0, v2, vcc
	v_cmp_le_u32_e32 vcc, v49, v7
	s_nop 1
	v_cndmask_b32_e32 v3, 0, v3, vcc
	v_cmp_le_u32_e32 vcc, v51, v7
	v_cvt_pk_bf16_f32 v1, v2, v3
	s_nop 0
	v_cndmask_b32_e32 v15, 0, v32, vcc
	v_cmp_le_u32_e32 vcc, v52, v7
	v_lshlrev_b32_e32 v32, 16, v46
	s_nop 0
	v_cndmask_b32_e32 v19, 0, v33, vcc
	v_cmp_le_u32_e32 vcc, v53, v7
	v_cvt_pk_bf16_f32 v2, v15, v19
	v_and_b32_e32 v33, 0xffff0000, v46
	v_cndmask_b32_e32 v21, 0, v34, vcc
	v_cmp_le_u32_e32 vcc, v54, v7
	v_mov_b32_e32 v15, v161
	v_mov_b32_e32 v19, v161
	v_cndmask_b32_e32 v23, 0, v35, vcc
	v_cvt_pk_bf16_f32 v3, v21, v23
	v_mov_b32_e32 v23, v161
	v_cmp_le_u32_e32 vcc, v8, v25
	v_mfma_f32_16x16x32_bf16 v[0:3], v[36:39], v[0:3], 0
	v_lshl_add_u64 v[38:39], v[4:5], 0, v[44:45]
	v_or_b32_e32 v21, 32, v7
	s_nop 5
	v_pk_add_f32 v[0:1], v[48:49], v[0:1] op_sel_hi:[0,1]
	v_pk_mul_f32 v[0:1], v[0:1], v[32:33]
	v_lshlrev_b32_e32 v32, 16, v47
	v_and_b32_e32 v33, 0xffff0000, v47
	v_pk_add_f32 v[2:3], v[48:49], v[2:3] op_sel_hi:[0,1]
	v_pk_mul_f32 v[2:3], v[2:3], v[32:33]
	v_cvt_pk_bf16_f32 v0, v0, v1
	v_cvt_pk_bf16_f32 v1, v2, v3
	global_store_dwordx2 v[10:11], v[0:1], off
	v_lshlrev_b32_e32 v0, 9, v25
	v_mov_b32_e32 v1, v161
	v_lshl_add_u64 v[0:1], s[0:1], 0, v[0:1]
	v_lshl_add_u64 v[10:11], v[0:1], 0, v[160:161]
	global_load_dwordx4 v[0:3], v[10:11], off
	global_load_dwordx4 v[34:37], v[10:11], off offset:16
	v_lshlrev_b64 v[10:11], 10, v[14:15]
	v_lshl_add_u64 v[10:11], v[4:5], 0, v[10:11]
	global_load_dwordx2 v[46:47], v[10:11], off
	v_lshlrev_b64 v[10:11], 10, v[18:19]
	v_lshlrev_b64 v[14:15], 10, v[22:23]
	v_lshl_add_u64 v[10:11], v[4:5], 0, v[10:11]
	v_lshl_add_u64 v[14:15], v[4:5], 0, v[14:15]
	v_lshlrev_b64 v[18:19], 10, v[28:29]
	v_lshl_add_u64 v[18:19], v[4:5], 0, v[18:19]
	global_load_dwordx2 v[32:33], v[10:11], off
	global_load_dwordx2 v[28:29], v[14:15], off
	global_load_dwordx2 v[22:23], v[18:19], off
	v_lshlrev_b64 v[10:11], 10, v[40:41]
	v_lshlrev_b64 v[14:15], 10, v[42:43]
	v_lshl_add_u64 v[10:11], v[4:5], 0, v[10:11]
	v_lshl_add_u64 v[14:15], v[4:5], 0, v[14:15]
	global_load_dwordx2 v[18:19], v[10:11], off
	s_nop 0
	global_load_dwordx2 v[14:15], v[14:15], off
	s_nop 0
	global_load_dwordx2 v[10:11], v[38:39], off
	ds_read_b128 v[38:41], v27
	v_or_b32_e32 v160, s2, v25
	s_waitcnt vmcnt(0) lgkmcnt(0)
	v_cndmask_b32_e32 v0, 0, v0, vcc
	v_cmp_lt_u32_e32 vcc, v8, v25
	s_nop 1
	v_cndmask_b32_e32 v1, 0, v1, vcc
	v_cmp_le_u32_e32 vcc, v31, v25
	v_cvt_pk_bf16_f32 v0, v0, v1
	s_nop 0
	v_cndmask_b32_e32 v2, 0, v2, vcc
	v_cmp_le_u32_e32 vcc, v49, v25
	s_nop 1
	v_cndmask_b32_e32 v3, 0, v3, vcc
	v_cmp_le_u32_e32 vcc, v51, v25
	v_cvt_pk_bf16_f32 v1, v2, v3
	s_nop 0
	v_cndmask_b32_e32 v27, 0, v34, vcc
	v_cmp_le_u32_e32 vcc, v52, v25
	s_nop 1
	v_cndmask_b32_e32 v31, 0, v35, vcc
	v_cmp_le_u32_e32 vcc, v53, v25
	v_cvt_pk_bf16_f32 v2, v27, v31
	s_nop 0
	v_cndmask_b32_e32 v34, 0, v36, vcc
	v_cmp_le_u32_e32 vcc, v54, v25
	s_nop 1
	v_cndmask_b32_e32 v35, 0, v37, vcc
	v_cvt_pk_bf16_f32 v3, v34, v35
	v_lshlrev_b32_e32 v34, 16, v46
	v_and_b32_e32 v35, 0xffff0000, v46
	v_mfma_f32_16x16x32_bf16 v[0:3], v[38:41], v[0:3], 0
	s_nop 7
	v_pk_add_f32 v[0:1], v[50:51], v[0:1] op_sel_hi:[0,1]
	v_pk_mul_f32 v[0:1], v[0:1], v[34:35]
	v_lshlrev_b32_e32 v34, 16, v47
	v_and_b32_e32 v35, 0xffff0000, v47
	v_pk_add_f32 v[2:3], v[50:51], v[2:3] op_sel_hi:[0,1]
	v_pk_mul_f32 v[2:3], v[2:3], v[34:35]
	v_cvt_pk_bf16_f32 v0, v0, v1
	v_cvt_pk_bf16_f32 v1, v2, v3
	v_lshlrev_b64 v[2:3], 10, v[160:161]
	v_lshl_add_u64 v[2:3], v[4:5], 0, v[2:3]
	global_store_dwordx2 v[2:3], v[0:1], off
	v_lshlrev_b32_e32 v160, 9, v21
	v_mov_b32_e32 v0, 0
	v_lshl_add_u64 v[34:35], s[0:1], 0, v[160:161]
	v_mov_b32_e32 v1, v0
	v_mov_b32_e32 v2, v0
	v_mov_b32_e32 v3, v0
.LBB0_328:
	v_or_b32_e32 v160, s8, v8
	v_lshl_add_u32 v25, v160, 1, v9
	v_lshl_add_u64 v[44:45], v[160:161], 2, v[34:35]
	ds_read_b128 v[36:39], v25
	global_load_dwordx4 v[40:43], v[44:45], off
	s_nop 0
	global_load_dwordx4 v[44:47], v[44:45], off offset:16
	v_cmp_le_u32_e32 vcc, v160, v21
	v_or_b32_e32 v31, 2, v160
	s_mov_b32 s8, 32
	s_waitcnt vmcnt(0) lgkmcnt(0)
	v_cndmask_b32_e32 v25, 0, v40, vcc
	v_cmp_lt_u32_e32 vcc, v160, v21
	v_or_b32_e32 v40, 3, v160
	s_nop 0
	v_cndmask_b32_e32 v27, 0, v41, vcc
	v_cmp_le_u32_e32 vcc, v31, v21
	s_nop 1
	v_cndmask_b32_e32 v31, 0, v42, vcc
	v_cmp_le_u32_e32 vcc, v40, v21
	v_or_b32_e32 v40, 4, v160
	s_nop 0
	v_cndmask_b32_e32 v41, 0, v43, vcc
	v_cmp_le_u32_e32 vcc, v40, v21
	v_or_b32_e32 v40, 5, v160
	v_cvt_pk_bf16_f32 v41, v31, v41
	v_cndmask_b32_e32 v42, 0, v44, vcc
	v_cmp_le_u32_e32 vcc, v40, v21
	v_or_b32_e32 v40, 6, v160
	s_nop 0
	v_cndmask_b32_e32 v43, 0, v45, vcc
	v_cmp_le_u32_e32 vcc, v40, v21
	v_or_b32_e32 v40, 7, v160
	v_cvt_pk_bf16_f32 v42, v42, v43
	v_cndmask_b32_e32 v44, 0, v46, vcc
	v_cmp_le_u32_e32 vcc, v40, v21
	v_cvt_pk_bf16_f32 v40, v25, v27
	s_nop 0
	v_cndmask_b32_e32 v45, 0, v47, vcc
	v_cvt_pk_bf16_f32 v43, v44, v45
	s_andn2_b64 vcc, exec, s[6:7]
	s_mov_b64 s[6:7], -1
	v_mfma_f32_16x16x32_bf16 v[0:3], v[36:39], v[40:43], v[0:3]
	s_cbranch_vccnz .LBB0_328
	v_lshlrev_b32_e32 v34, 16, v32
	v_and_b32_e32 v35, 0xffff0000, v32
	s_nop 4
	v_pk_add_f32 v[0:1], v[30:31], v[0:1] op_sel_hi:[0,1]
	v_lshlrev_b32_e32 v32, 16, v33
	v_and_b32_e32 v33, 0xffff0000, v33
	v_pk_add_f32 v[2:3], v[30:31], v[2:3] op_sel_hi:[0,1]
	v_or_b32_e32 v160, s2, v21
	v_pk_mul_f32 v[0:1], v[0:1], v[34:35]
	v_pk_mul_f32 v[2:3], v[2:3], v[32:33]
	v_cvt_pk_bf16_f32 v0, v0, v1
	v_cvt_pk_bf16_f32 v1, v2, v3
	v_lshlrev_b64 v[2:3], 10, v[160:161]
	v_or_b32_e32 v25, 48, v7
	v_lshl_add_u64 v[2:3], v[4:5], 0, v[2:3]
	global_store_dwordx2 v[2:3], v[0:1], off
	v_lshlrev_b32_e32 v160, 9, v25
	v_mov_b32_e32 v0, 0
	v_lshl_add_u64 v[30:31], s[0:1], 0, v[160:161]
	s_mov_b32 s6, 0
	s_mov_b64 s[0:1], 0
	v_mov_b32_e32 v1, v0
	v_mov_b32_e32 v2, v0
	v_mov_b32_e32 v3, v0
.LBB0_330:
	v_or_b32_e32 v160, s6, v8
	v_lshl_add_u32 v21, v160, 1, v9
	v_lshl_add_u64 v[40:41], v[160:161], 2, v[30:31]
	ds_read_b128 v[32:35], v21
	global_load_dwordx4 v[36:39], v[40:41], off
	s_nop 0
	global_load_dwordx4 v[40:43], v[40:41], off offset:16
	v_cmp_le_u32_e32 vcc, v160, v25
	s_mov_b32 s6, 32
	s_waitcnt vmcnt(0) lgkmcnt(0)
	v_cndmask_b32_e32 v21, 0, v36, vcc
	v_cmp_lt_u32_e32 vcc, v160, v25
	v_or_b32_e32 v36, 2, v160
	s_nop 0
	v_cndmask_b32_e32 v27, 0, v37, vcc
	v_cmp_le_u32_e32 vcc, v36, v25
	v_or_b32_e32 v36, 3, v160
	s_nop 0
	v_cndmask_b32_e32 v37, 0, v38, vcc
	v_cmp_le_u32_e32 vcc, v36, v25
	v_or_b32_e32 v36, 4, v160
	s_nop 0
	v_cndmask_b32_e32 v38, 0, v39, vcc
	v_cmp_le_u32_e32 vcc, v36, v25
	v_or_b32_e32 v36, 5, v160
	v_cvt_pk_bf16_f32 v37, v37, v38
	v_cndmask_b32_e32 v39, 0, v40, vcc
	v_cmp_le_u32_e32 vcc, v36, v25
	v_or_b32_e32 v36, 6, v160
	s_nop 0
	v_cndmask_b32_e32 v40, 0, v41, vcc
	v_cmp_le_u32_e32 vcc, v36, v25
	v_or_b32_e32 v36, 7, v160
	v_cvt_pk_bf16_f32 v38, v39, v40
	v_cndmask_b32_e32 v41, 0, v42, vcc
	v_cmp_le_u32_e32 vcc, v36, v25
	v_cvt_pk_bf16_f32 v36, v21, v27
	s_nop 0
	v_cndmask_b32_e32 v42, 0, v43, vcc
	v_cvt_pk_bf16_f32 v39, v41, v42
	s_andn2_b64 vcc, exec, s[0:1]
	s_mov_b64 s[0:1], -1
	v_mfma_f32_16x16x32_bf16 v[0:3], v[32:35], v[36:39], v[0:3]
	s_cbranch_vccnz .LBB0_330
	v_lshlrev_b32_e32 v30, 16, v28
	v_and_b32_e32 v31, 0xffff0000, v28
	s_nop 4
	v_pk_add_f32 v[0:1], v[26:27], v[0:1] op_sel_hi:[0,1]
	v_lshlrev_b32_e32 v28, 16, v29
	v_and_b32_e32 v29, 0xffff0000, v29
	v_pk_add_f32 v[2:3], v[26:27], v[2:3] op_sel_hi:[0,1]
	v_or_b32_e32 v160, s2, v25
	v_pk_mul_f32 v[0:1], v[0:1], v[30:31]
	v_pk_mul_f32 v[2:3], v[2:3], v[28:29]
	s_and_b32 s0, s40, 3
	v_cvt_pk_bf16_f32 v0, v0, v1
	v_cvt_pk_bf16_f32 v1, v2, v3
	v_lshlrev_b64 v[2:3], 10, v[160:161]
	s_add_i32 s0, s39, s0
	v_lshl_add_u64 v[2:3], v[4:5], 0, v[2:3]
	s_ashr_i32 s1, s0, 31
	global_store_dwordx2 v[2:3], v[0:1], off
	v_lshlrev_b32_e32 v0, 1, v13
	s_lshl_b64 s[0:1], s[0:1], 16
	v_and_b32_e32 v0, 0x60, v0
	v_or3_b32 v0, s0, v24, v0
	v_mov_b32_e32 v1, s1
	v_lshl_add_u64 v[24:25], s[4:5], 0, v[0:1]
	s_mov_b64 s[0:1], 0x8010
	v_lshl_add_u64 v[26:27], v[24:25], 0, s[0:1]
	v_mul_u32_u24_e32 v0, 0x110, v7
	v_lshlrev_b32_e32 v1, 4, v17
	v_readlane_b32 s0, v254, 54
	v_or_b32_e32 v21, 64, v7
	s_nop 0
	v_add3_u32 v9, v0, v1, s0
	v_mov_b32_e32 v0, 0
	s_mov_b32 s0, 0
	v_mov_b32_e32 v13, v9
	v_mov_b32_e32 v1, v0
	v_mov_b32_e32 v2, v0
	v_mov_b32_e32 v3, v0
.LBB0_332:
	v_add_co_u32_e32 v32, vcc, -16, v26
	ds_read_b128 v[28:31], v13
	s_nop 0
	v_addc_co_u32_e32 v33, vcc, -1, v27, vcc
	global_load_dwordx4 v[32:35], v[32:33], off
	s_nop 0
	global_load_dwordx4 v[36:39], v[26:27], off
	v_add_u32_e32 v17, s0, v8
	v_cmp_le_u32_e32 vcc, v17, v21
	v_add_u32_e32 v40, 2, v17
	s_add_i32 s0, s0, 32
	v_lshl_add_u64 v[26:27], v[26:27], 0, s[96:97]
	v_add_u32_e32 v13, 64, v13
	s_cmpk_lg_i32 s0, 0x60
	s_waitcnt vmcnt(0) lgkmcnt(0)
	v_cndmask_b32_e32 v32, 0, v32, vcc
	v_cmp_lt_u32_e32 vcc, v17, v21
	s_nop 1
	v_cndmask_b32_e32 v33, 0, v33, vcc
	v_cmp_le_u32_e32 vcc, v40, v21
	v_add_u32_e32 v40, 3, v17
	v_cvt_pk_bf16_f32 v32, v32, v33
	v_cndmask_b32_e32 v34, 0, v34, vcc
	v_cmp_le_u32_e32 vcc, v40, v21
	v_add_u32_e32 v40, 4, v17
	s_nop 0
	v_cndmask_b32_e32 v35, 0, v35, vcc
	v_cmp_le_u32_e32 vcc, v40, v21
	v_add_u32_e32 v40, 5, v17
	v_cvt_pk_bf16_f32 v33, v34, v35
	v_cndmask_b32_e32 v36, 0, v36, vcc
	v_cmp_le_u32_e32 vcc, v40, v21
	v_add_u32_e32 v40, 6, v17
	v_add_u32_e32 v17, 7, v17
	v_cndmask_b32_e32 v37, 0, v37, vcc
	v_cmp_le_u32_e32 vcc, v40, v21
	v_cvt_pk_bf16_f32 v34, v36, v37
	s_nop 0
	v_cndmask_b32_e32 v38, 0, v38, vcc
	v_cmp_le_u32_e32 vcc, v17, v21
	s_nop 1
	v_cndmask_b32_e32 v17, 0, v39, vcc
	v_cvt_pk_bf16_f32 v35, v38, v17
	s_nop 1
	v_mfma_f32_16x16x32_bf16 v[0:3], v[28:31], v[32:35], v[0:3]
	s_cbranch_scc1 .LBB0_332
	v_lshlrev_b32_e32 v26, 16, v22
	v_and_b32_e32 v27, 0xffff0000, v22
	s_nop 4
	v_pk_add_f32 v[0:1], v[20:21], v[0:1] op_sel_hi:[0,1]
	v_lshlrev_b32_e32 v22, 16, v23
	v_and_b32_e32 v23, 0xffff0000, v23
	v_pk_add_f32 v[2:3], v[20:21], v[2:3] op_sel_hi:[0,1]
	v_or_b32_e32 v160, s2, v21
	v_pk_mul_f32 v[0:1], v[0:1], v[26:27]
	v_pk_mul_f32 v[2:3], v[2:3], v[22:23]
	v_cvt_pk_bf16_f32 v0, v0, v1
	v_cvt_pk_bf16_f32 v1, v2, v3
	v_lshlrev_b64 v[2:3], 10, v[160:161]
	v_lshl_add_u64 v[2:3], v[4:5], 0, v[2:3]
	global_store_dwordx2 v[2:3], v[0:1], off
	s_mov_b64 s[0:1], 0xa010
	v_mov_b32_e32 v0, 0
	v_or_b32_e32 v13, 0x50, v7
	v_lshl_add_u64 v[20:21], v[24:25], 0, s[0:1]
	s_mov_b32 s0, 0
	v_mov_b32_e32 v17, v9
	v_mov_b32_e32 v1, v0
	v_mov_b32_e32 v2, v0
	v_mov_b32_e32 v3, v0
.LBB0_334:
	v_add_co_u32_e32 v22, vcc, -16, v20
	ds_read_b128 v[26:29], v17
	s_nop 0
	v_addc_co_u32_e32 v23, vcc, -1, v21, vcc
	global_load_dwordx4 v[30:33], v[22:23], off
	global_load_dwordx4 v[34:37], v[20:21], off
	v_add_u32_e32 v38, s0, v8
	v_cmp_le_u32_e32 vcc, v38, v13
	s_add_i32 s0, s0, 32
	v_lshl_add_u64 v[20:21], v[20:21], 0, s[96:97]
	v_add_u32_e32 v17, 64, v17
	s_cmpk_lg_i32 s0, 0x60
	s_waitcnt vmcnt(0) lgkmcnt(0)
	v_cndmask_b32_e32 v22, 0, v30, vcc
	v_cmp_lt_u32_e32 vcc, v38, v13
	v_add_u32_e32 v30, 2, v38
	s_nop 0
	v_cndmask_b32_e32 v23, 0, v31, vcc
	v_cmp_le_u32_e32 vcc, v30, v13
	v_add_u32_e32 v30, 3, v38
	s_nop 0
	v_cndmask_b32_e32 v31, 0, v32, vcc
	v_cmp_le_u32_e32 vcc, v30, v13
	v_add_u32_e32 v30, 4, v38
	s_nop 0
	v_cndmask_b32_e32 v32, 0, v33, vcc
	v_cmp_le_u32_e32 vcc, v30, v13
	v_add_u32_e32 v30, 5, v38
	v_cvt_pk_bf16_f32 v31, v31, v32
	v_cndmask_b32_e32 v33, 0, v34, vcc
	v_cmp_le_u32_e32 vcc, v30, v13
	v_add_u32_e32 v30, 6, v38
	s_nop 0
	v_cndmask_b32_e32 v34, 0, v35, vcc
	v_cmp_le_u32_e32 vcc, v30, v13
	v_add_u32_e32 v30, 7, v38
	v_cvt_pk_bf16_f32 v32, v33, v34
	v_cndmask_b32_e32 v35, 0, v36, vcc
	v_cmp_le_u32_e32 vcc, v30, v13
	v_cvt_pk_bf16_f32 v30, v22, v23
	s_nop 0
	v_cndmask_b32_e32 v36, 0, v37, vcc
	v_cvt_pk_bf16_f32 v33, v35, v36
	s_nop 1
	v_mfma_f32_16x16x32_bf16 v[0:3], v[26:29], v[30:33], v[0:3]
	s_cbranch_scc1 .LBB0_334
	v_lshlrev_b32_e32 v22, 16, v18
	v_and_b32_e32 v23, 0xffff0000, v18
	s_nop 4
	v_pk_add_f32 v[0:1], v[16:17], v[0:1] op_sel_hi:[0,1]
	v_lshlrev_b32_e32 v18, 16, v19
	v_and_b32_e32 v19, 0xffff0000, v19
	v_pk_add_f32 v[2:3], v[16:17], v[2:3] op_sel_hi:[0,1]
	v_or_b32_e32 v160, s2, v13
	v_pk_mul_f32 v[0:1], v[0:1], v[22:23]
	v_pk_mul_f32 v[2:3], v[2:3], v[18:19]
	v_cvt_pk_bf16_f32 v0, v0, v1
	v_cvt_pk_bf16_f32 v1, v2, v3
	v_lshlrev_b64 v[2:3], 10, v[160:161]
	v_lshl_add_u64 v[2:3], v[4:5], 0, v[2:3]
	global_store_dwordx2 v[2:3], v[0:1], off
	s_mov_b64 s[0:1], 0xc010
	v_mov_b32_e32 v0, 0
	v_or_b32_e32 v20, 0x60, v7
	v_lshl_add_u64 v[16:17], v[24:25], 0, s[0:1]
	s_mov_b32 s0, 0
	v_mov_b32_e32 v13, v9
	v_mov_b32_e32 v1, v0
	v_mov_b32_e32 v2, v0
	v_mov_b32_e32 v3, v0
.LBB0_336:
	v_add_co_u32_e32 v18, vcc, -16, v16
	ds_read_b128 v[26:29], v13
	s_nop 0
	v_addc_co_u32_e32 v19, vcc, -1, v17, vcc
	global_load_dwordx4 v[30:33], v[18:19], off
	global_load_dwordx4 v[34:37], v[16:17], off
	v_add_u32_e32 v21, s0, v8
	v_cmp_le_u32_e32 vcc, v21, v20
	v_add_u32_e32 v22, 2, v21
	v_add_u32_e32 v23, 3, v21
	s_add_i32 s0, s0, 32
	v_lshl_add_u64 v[16:17], v[16:17], 0, s[96:97]
	v_add_u32_e32 v13, 64, v13
	s_cmpk_lg_i32 s0, 0x80
	s_waitcnt vmcnt(0) lgkmcnt(0)
	v_cndmask_b32_e32 v18, 0, v30, vcc
	v_cmp_lt_u32_e32 vcc, v21, v20
	v_add_u32_e32 v30, 4, v21
	s_nop 0
	v_cndmask_b32_e32 v19, 0, v31, vcc
	v_cmp_le_u32_e32 vcc, v22, v20
	s_nop 1
	v_cndmask_b32_e32 v22, 0, v32, vcc
	v_cmp_le_u32_e32 vcc, v23, v20
	s_nop 1
	v_cndmask_b32_e32 v23, 0, v33, vcc
	v_cmp_le_u32_e32 vcc, v30, v20
	v_add_u32_e32 v30, 5, v21
	v_cvt_pk_bf16_f32 v31, v22, v23
	v_cndmask_b32_e32 v32, 0, v34, vcc
	v_cmp_le_u32_e32 vcc, v30, v20
	v_add_u32_e32 v30, 6, v21
	v_add_u32_e32 v21, 7, v21
	v_cndmask_b32_e32 v33, 0, v35, vcc
	v_cmp_le_u32_e32 vcc, v30, v20
	v_cvt_pk_bf16_f32 v30, v18, v19
	v_cvt_pk_bf16_f32 v32, v32, v33
	v_cndmask_b32_e32 v34, 0, v36, vcc
	v_cmp_le_u32_e32 vcc, v21, v20
	s_nop 1
	v_cndmask_b32_e32 v21, 0, v37, vcc
	v_cvt_pk_bf16_f32 v33, v34, v21
	s_nop 1
	v_mfma_f32_16x16x32_bf16 v[0:3], v[26:29], v[30:33], v[0:3]
	s_cbranch_scc1 .LBB0_336
	v_lshlrev_b32_e32 v16, 16, v14
	v_and_b32_e32 v17, 0xffff0000, v14
	s_nop 4
	v_pk_add_f32 v[0:1], v[12:13], v[0:1] op_sel_hi:[0,1]
	v_lshlrev_b32_e32 v14, 16, v15
	v_and_b32_e32 v15, 0xffff0000, v15
	v_pk_add_f32 v[2:3], v[12:13], v[2:3] op_sel_hi:[0,1]
	v_or_b32_e32 v160, s2, v20
	v_pk_mul_f32 v[0:1], v[0:1], v[16:17]
	v_pk_mul_f32 v[2:3], v[2:3], v[14:15]
	v_cvt_pk_bf16_f32 v0, v0, v1
	v_cvt_pk_bf16_f32 v1, v2, v3
	v_lshlrev_b64 v[2:3], 10, v[160:161]
	v_lshl_add_u64 v[2:3], v[4:5], 0, v[2:3]
	global_store_dwordx2 v[2:3], v[0:1], off
	s_mov_b64 s[0:1], 0xe010
	v_mov_b32_e32 v0, 0
	v_or_b32_e32 v7, 0x70, v7
	v_lshl_add_u64 v[12:13], v[24:25], 0, s[0:1]
	s_mov_b32 s0, 0
	v_mov_b32_e32 v1, v0
	v_mov_b32_e32 v2, v0
	v_mov_b32_e32 v3, v0
.LBB0_338:
	v_add_co_u32_e32 v18, vcc, -16, v12
	ds_read_b128 v[14:17], v9
	s_nop 0
	v_addc_co_u32_e32 v19, vcc, -1, v13, vcc
	global_load_dwordx4 v[18:21], v[18:19], off
	s_nop 0
	global_load_dwordx4 v[22:25], v[12:13], off
	v_add_u32_e32 v26, s0, v8
	v_cmp_le_u32_e32 vcc, v26, v7
	v_add_u32_e32 v27, 2, v26
	s_add_i32 s0, s0, 32
	v_lshl_add_u64 v[12:13], v[12:13], 0, s[96:97]
	v_add_u32_e32 v9, 64, v9
	s_cmpk_lg_i32 s0, 0x80
	s_waitcnt vmcnt(0) lgkmcnt(0)
	v_cndmask_b32_e32 v18, 0, v18, vcc
	v_cmp_lt_u32_e32 vcc, v26, v7
	s_nop 1
	v_cndmask_b32_e32 v19, 0, v19, vcc
	v_cmp_le_u32_e32 vcc, v27, v7
	v_add_u32_e32 v27, 3, v26
	v_cvt_pk_bf16_f32 v18, v18, v19
	v_cndmask_b32_e32 v20, 0, v20, vcc
	v_cmp_le_u32_e32 vcc, v27, v7
	v_add_u32_e32 v27, 4, v26
	s_nop 0
	v_cndmask_b32_e32 v21, 0, v21, vcc
	v_cmp_le_u32_e32 vcc, v27, v7
	v_add_u32_e32 v27, 5, v26
	v_cvt_pk_bf16_f32 v19, v20, v21
	v_cndmask_b32_e32 v22, 0, v22, vcc
	v_cmp_le_u32_e32 vcc, v27, v7
	v_add_u32_e32 v27, 6, v26
	v_add_u32_e32 v26, 7, v26
	v_cndmask_b32_e32 v23, 0, v23, vcc
	v_cmp_le_u32_e32 vcc, v27, v7
	v_cvt_pk_bf16_f32 v20, v22, v23
	s_nop 0
	v_cndmask_b32_e32 v24, 0, v24, vcc
	v_cmp_le_u32_e32 vcc, v26, v7
	s_nop 1
	v_cndmask_b32_e32 v25, 0, v25, vcc
	v_cvt_pk_bf16_f32 v21, v24, v25
	s_nop 1
	v_mfma_f32_16x16x32_bf16 v[0:3], v[14:17], v[18:21], v[0:3]
	s_cbranch_scc1 .LBB0_338
	v_lshlrev_b32_e32 v8, 16, v10
	v_and_b32_e32 v9, 0xffff0000, v10
	s_nop 4
	v_pk_add_f32 v[0:1], v[6:7], v[0:1] op_sel_hi:[0,1]
	v_pk_mul_f32 v[0:1], v[0:1], v[8:9]
	v_lshlrev_b32_e32 v8, 16, v11
	v_and_b32_e32 v9, 0xffff0000, v11
	v_pk_add_f32 v[2:3], v[6:7], v[2:3] op_sel_hi:[0,1]
	v_or_b32_e32 v160, s2, v7
	v_pk_mul_f32 v[2:3], v[2:3], v[8:9]
	v_cvt_pk_bf16_f32 v0, v0, v1
	v_cvt_pk_bf16_f32 v1, v2, v3
	v_lshlrev_b64 v[2:3], 10, v[160:161]
	v_lshl_add_u64 v[2:3], v[4:5], 0, v[2:3]
	global_store_dwordx2 v[2:3], v[0:1], off

.LBB0_349:
	v_mul_hi_i32 v3, v2, s17
	v_lshrrev_b32_e32 v4, 31, v3
	v_ashrrev_i32_e32 v3, 8, v3
	v_add_u32_e32 v3, v3, v4
	v_mul_i32_i24_e32 v4, 0x280, v3
	v_sub_u32_e32 v4, v2, v4
	v_ashrrev_i32_e32 v4, 7, v4
	v_cmp_gt_i32_e32 vcc, 4, v4
	v_lshlrev_b32_e32 v4, 10, v4
	v_and_b32_e32 v6, 0x7f, v2
	v_cndmask_b32_e32 v4, 0, v4, vcc
	v_lshl_add_u32 v3, v3, 9, v4
	v_mov_b32_e32 v4, s16
	v_mov_b32_e32 v5, s14
	v_cndmask_b32_e32 v5, v4, v5, vcc
	v_mov_b32_e32 v4, s15
	v_mov_b32_e32 v7, s13
	v_or3_b32 v6, v3, v6, s2
	v_cndmask_b32_e32 v4, v4, v7, vcc
	v_ashrrev_i32_e32 v7, 31, v6
	v_lshl_add_u64 v[4:5], v[6:7], 2, v[4:5]
	global_load_dword v3, v[4:5], off
	v_cmp_lt_i32_e32 vcc, s18, v2
	s_or_b64 s[6:7], vcc, s[6:7]
	s_waitcnt vmcnt(0) lgkmcnt(0)
	ds_write_b32 v1, v3
	v_add_u32_e32 v3, 0x200, v2
	v_add_u32_e32 v1, 0x800, v1
	v_mov_b32_e32 v2, v3
	s_andn2_b64 exec, exec, s[6:7]
	s_cbranch_execnz .LBB0_349
.LBB0_350:
	s_or_b64 exec, exec, s[4:5]
	s_add_u32 s6, s0, 0x1d200000
	s_addc_u32 s7, s1, 0
	s_add_u32 s4, s0, 0x2f200000
	s_addc_u32 s5, s1, 0
	v_ashrrev_i32_e32 v58, 2, v0
	s_add_u32 s13, s10, s28
	v_and_b32_e32 v59, -8, v58
	s_addc_u32 s16, s9, s29
	s_lshl_b64 s[14:15], s[22:23], 2
	v_add_u32_e32 v0, s2, v59
	v_lshlrev_b32_e32 v1, 1, v48
	s_add_u32 s12, s12, s14
	v_and_b32_e32 v172, 62, v1
	v_ashrrev_i32_e32 v1, 31, v0
	s_addc_u32 s14, s11, s15
	v_lshl_add_u64 v[0:1], v[0:1], 1, s[0:1]
	s_mov_b64 s[10:11], 0x21200000
	s_lshl_b32 s9, s42, 9
	v_add_u32_e32 v173, -3, v172
	v_lshl_add_u64 v[116:117], v[0:1], 0, s[10:11]
	s_mov_b64 s[10:11], 0x25200000
	s_and_b32 s43, s9, 0xfffff800
	v_lshl_add_u64 v[118:119], v[0:1], 0, s[10:11]
	v_max_i32_e32 v0, 0, v173
	v_or_b32_e32 v0, s43, v0
	v_ashrrev_i32_e32 v1, 31, v0
	v_lshlrev_b64 v[0:1], 10, v[0:1]
	v_lshl_add_u64 v[2:3], v[116:117], 0, v[0:1]
	v_lshl_add_u64 v[0:1], v[118:119], 0, v[0:1]
	global_load_dwordx4 v[28:31], v[2:3], off
	global_load_dwordx4 v[24:27], v[0:1], off
	v_sub_u32_e64 v0, v172, 2 clamp
	v_or_b32_e32 v0, s43, v0
	v_ashrrev_i32_e32 v1, 31, v0
	v_lshlrev_b64 v[0:1], 10, v[0:1]
	v_lshl_add_u64 v[2:3], v[116:117], 0, v[0:1]
	v_lshl_add_u64 v[0:1], v[118:119], 0, v[0:1]
	global_load_dwordx4 v[32:35], v[2:3], off
	global_load_dwordx4 v[8:11], v[0:1], off
	v_sub_u32_e64 v0, v172, 1 clamp
	v_or_b32_e32 v0, s43, v0
	v_ashrrev_i32_e32 v1, 31, v0
	v_lshlrev_b64 v[0:1], 10, v[0:1]
	v_or_b32_e32 v120, s43, v172
	v_lshl_add_u64 v[2:3], v[116:117], 0, v[0:1]
	v_lshl_add_u64 v[0:1], v[118:119], 0, v[0:1]
	v_ashrrev_i32_e32 v121, 31, v120
	global_load_dwordx4 v[36:39], v[2:3], off
	global_load_dwordx4 v[12:15], v[0:1], off
	v_lshlrev_b64 v[0:1], 10, v[120:121]
	v_lshl_add_u64 v[2:3], v[116:117], 0, v[0:1]
	v_lshl_add_u64 v[0:1], v[118:119], 0, v[0:1]
	global_load_dwordx4 v[40:43], v[2:3], off
	global_load_dwordx4 v[16:19], v[0:1], off
	v_or_b32_e32 v0, 1, v120
	v_readlane_b32 s18, v253, 39
	v_and_b32_e32 v170, 63, v48
	v_ashrrev_i32_e32 v1, 31, v0
	s_lshl_b32 s82, s2, 1
	s_lshl_b32 s10, s18, 1
	s_lshl_b32 s8, s8, 2
	v_lshlrev_b64 v[0:1], 10, v[0:1]
	v_or_b32_e32 v50, s43, v170
	s_add_u32 s0, s0, s82
	v_and_b32_e32 v171, 15, v48
	v_lshl_add_u64 v[2:3], v[116:117], 0, v[0:1]
	v_lshl_add_u64 v[0:1], v[118:119], 0, v[0:1]
	v_ashrrev_i32_e32 v51, 31, v50
	s_addc_u32 s1, s1, 0
	v_bfe_u32 v49, v48, 4, 2
	global_load_dwordx4 v[44:47], v[2:3], off
	global_load_dwordx4 v[20:23], v[0:1], off
	v_lshlrev_b64 v[0:1], 10, v[50:51]
	v_or_b32_e32 v52, s43, v171
	s_add_u32 s0, s0, s10
	v_lshl_add_u64 v[0:1], s[6:7], 0, v[0:1]
	v_lshlrev_b64 v[50:51], 7, v[50:51]
	s_addc_u32 s1, s1, 0
	v_lshlrev_b32_e32 v160, 3, v49
	v_or_b32_e32 v56, 16, v52
	v_lshl_add_u64 v[0:1], v[0:1], 0, s[82:83]
	s_mov_b32 s11, s83
	v_lshl_add_u64 v[50:51], s[4:5], 0, v[50:51]
	s_mov_b32 s9, s83
	v_lshl_add_u64 v[54:55], s[0:1], 0, v[160:161]
	s_mov_b64 s[0:1], 0x11200000
	v_ashrrev_i32_e32 v53, 31, v52
	v_ashrrev_i32_e32 v57, 31, v56
	v_lshl_add_u64 v[0:1], v[0:1], 0, s[10:11]
	v_lshl_add_u64 v[50:51], v[50:51], 0, s[8:9]
	v_lshl_add_u64 v[122:123], v[54:55], 0, s[0:1]
	v_lshlrev_b64 v[54:55], 10, v[52:53]
	v_lshlrev_b64 v[56:57], 10, v[56:57]
	global_load_dwordx4 v[4:7], v[0:1], off
	s_nop 0
	global_load_dwordx4 v[0:3], v[0:1], off offset:16
	v_lshl_add_u64 v[54:55], v[122:123], 0, v[54:55]
	v_lshl_add_u64 v[56:57], v[122:123], 0, v[56:57]
	global_load_dword v195, v[50:51], off
	global_load_dword v204, v[50:51], off offset:16
	global_load_dwordx2 v[142:143], v[54:55], off
	global_load_dwordx2 v[140:141], v[56:57], off
	v_or_b32_e32 v50, 32, v52
	v_ashrrev_i32_e32 v51, 31, v50
	v_or_b32_e32 v52, 48, v52
	v_lshlrev_b64 v[50:51], 10, v[50:51]
	v_ashrrev_i32_e32 v53, 31, v52
	v_lshl_add_u64 v[50:51], v[122:123], 0, v[50:51]
	v_lshlrev_b64 v[52:53], 10, v[52:53]
	v_lshl_add_u64 v[52:53], v[122:123], 0, v[52:53]
	global_load_dwordx2 v[138:139], v[50:51], off
	global_load_dwordx2 v[128:129], v[52:53], off
	s_add_u32 s0, s6, s82
	s_addc_u32 s1, s7, 0
	s_add_u32 s30, s0, s10
	s_addc_u32 s31, s1, 0
	v_lshlrev_b32_e32 v50, 2, v59
	v_readlane_b32 s0, v254, 57
	s_add_u32 s34, s4, s8
	s_addc_u32 s35, s5, 0
	v_add_u32_e32 v121, s0, v50
	v_readlane_b32 s0, v254, 56
	v_lshlrev_b32_e32 v52, 2, v171
	v_and_b32_e32 v124, 48, v48
	v_lshl_add_u32 v175, v170, 3, s0
	v_readlane_b32 s0, v254, 58
	v_or_b32_e32 v48, s18, v171
	s_add_u32 s36, s13, s8
	v_add_u32_e32 v176, s0, v52
	v_mul_lo_u32 v53, v48, s93
	v_readlane_b32 s0, v254, 51
	s_addc_u32 s37, s16, 0
	v_mov_b32_e32 v125, v161
	v_add3_u32 v178, s0, v53, v124
	v_mov_b32_e32 v53, s0
	s_lshl_b32 s0, s2, 2
	s_add_u32 s0, s12, s0
	s_addc_u32 s1, s14, 0
	s_lshl_b32 s2, s18, 2
	s_add_u32 s0, s0, s2
	s_addc_u32 s1, s1, 0
	v_mad_u32_u24 v53, v171, s93, v53
	v_lshl_add_u64 v[126:127], s[0:1], 0, v[124:125]
	s_movk_i32 s0, 0xfef2
	v_mad_i32_i24 v86, v171, s0, v53
	v_readlane_b32 s0, v253, 43
	s_movk_i32 s8, 0x90
	v_lshlrev_b32_e32 v60, 2, v49
	v_lshl_add_u32 v182, v171, 1, s0
	v_readlane_b32 s0, v254, 59
	v_mul_u32_u24_e32 v51, 0x110, v172
	v_mul_lo_u32 v48, v48, s8
	v_add_u32_e32 v183, s0, v50
	v_readlane_b32 s0, v254, 60
	v_lshl_add_u32 v125, v49, 5, s33
	v_lshlrev_b32_e32 v49, 1, v59
	v_add_u32_e32 v185, s0, v50
	v_readlane_b32 s0, v253, 44
	v_add3_u32 v181, 0, v48, v160
	v_or_b32_e32 v48, s18, v60
	v_add3_u32 v184, 0, v51, v49
	v_or_b32_e32 v49, 7, v58
	v_lshl_add_u32 v186, v170, 1, s0
	v_or_b32_e32 v188, 16, v171
	v_readlane_b32 s0, v254, 55
	v_lshl_add_u32 v84, v172, 1, 0
	v_add_u32_e32 v177, 0, v124
	v_mul_u32_u24_e32 v85, 0x110, v171
	v_mul_lo_u32 v87, v59, s8
	v_mul_lo_u32 v88, v49, s8
	v_or_b32_e32 v49, s57, v171
	v_mul_u32_u24_e32 v89, 0x110, v188
	v_or_b32_e32 v189, 32, v171
	v_or_b32_e32 v190, 48, v171
	v_mul_u32_u24_e32 v90, 0x90, v171
	v_mul_lo_u32 v91, v48, s93
	v_mov_b32_e32 v48, s0
	s_mov_b32 s44, 0
	v_lshl_add_u32 v174, v170, 2, s33
	v_cmp_gt_u32_e64 s[4:5], 16, v170
	v_add_u32_e32 v179, v53, v124
	v_add_u32_e32 v180, s33, v52
	v_cmp_eq_u32_e64 s[6:7], 0, v171
	s_or_b32 s45, s43, 1
	s_or_b32 s46, s43, 2
	s_or_b32 s47, s43, 4
	v_cmp_eq_u32_e64 s[8:9], 0, v170
	v_cmp_gt_u32_e64 s[10:11], 2, v170
	v_cmp_gt_u32_e64 s[12:13], 4, v170
	v_cmp_gt_u32_e64 s[14:15], 8, v170
	v_cmp_gt_u32_e64 s[16:17], 32, v170
	v_lshlrev_b32_e32 v187, 3, v49
	v_lshlrev_b32_e32 v191, 3, v171
	v_lshlrev_b32_e32 v192, 3, v188
	v_lshlrev_b32_e32 v193, 3, v189
	v_lshlrev_b32_e32 v194, 3, v190
	v_add_u32_e32 v196, s18, v60
	v_mad_u32_u24 v197, v171, s93, v48
	v_mov_b32_e32 v48, 0
	v_mov_b32_e32 v49, 0
	v_mov_b32_e32 v50, 0
	v_mov_b32_e32 v51, 0
	v_mov_b32_e32 v76, 0
	v_mov_b32_e32 v77, 0
	v_mov_b32_e32 v78, 0
	v_mov_b32_e32 v79, 0
	v_mov_b32_e32 v72, 0
	v_mov_b32_e32 v73, 0
	v_mov_b32_e32 v74, 0
	v_mov_b32_e32 v75, 0
	v_mov_b32_e32 v68, 0
	v_mov_b32_e32 v69, 0
	v_mov_b32_e32 v70, 0
	v_mov_b32_e32 v71, 0
	v_mov_b32_e32 v64, 0
	v_mov_b32_e32 v65, 0
	v_mov_b32_e32 v66, 0
	v_mov_b32_e32 v67, 0
	v_mov_b32_e32 v60, 0
	v_mov_b32_e32 v61, 0
	v_mov_b32_e32 v62, 0
	v_mov_b32_e32 v63, 0
	v_mov_b32_e32 v56, 0
	v_mov_b32_e32 v57, 0
	v_mov_b32_e32 v58, 0
	v_mov_b32_e32 v59, 0
	v_mov_b32_e32 v52, 0
	v_mov_b32_e32 v53, 0
	v_mov_b32_e32 v54, 0
	v_mov_b32_e32 v55, 0
	v_mov_b32_e32 v80, 0
	v_mov_b32_e32 v81, 0
	v_mov_b32_e32 v82, 0
	v_mov_b32_e32 v83, 0
	v_add_u32_e32 v198, v84, v87
	v_add_u32_e32 v199, v84, v88
	v_add_u32_e32 v200, v177, v85
	v_add_u32_e32 v201, v177, v90
	v_add_u32_e32 v202, v86, v91
	v_add_u32_e32 v203, v177, v89
	s_mov_b32 s2, 0
	s_branch .LBB0_352

.LBB0_352:
	s_lshl_b32 s48, s2, 6
	s_waitcnt lgkmcnt(0)
	s_barrier
	v_or_b32_e32 v136, s48, v172
	ds_read_b128 v[94:97], v183
	ds_read_b128 v[84:87], v183 offset:16
	ds_read_b128 v[98:101], v121
	ds_read_b128 v[88:91], v121 offset:16
	ds_read_b128 v[102:105], v121 offset:512
	ds_read_b128 v[106:109], v121 offset:1024
	ds_read_b128 v[110:113], v121 offset:1536
	s_waitcnt vmcnt(0) lgkmcnt(0)
	v_lshlrev_b32_e32 v92, 16, v32
	v_and_b32_e32 v32, 0xffff0000, v32
	v_cmp_eq_u32_e32 vcc, 0, v136
	v_lshlrev_b32_e32 v130, 16, v40
	v_and_b32_e32 v131, 0xffff0000, v40
	v_cndmask_b32_e64 v93, v32, 0, vcc
	v_cndmask_b32_e64 v92, v92, 0, vcc
	v_lshlrev_b32_e32 v32, 16, v36
	v_and_b32_e32 v36, 0xffff0000, v36
	v_cndmask_b32_e64 v115, v36, 0, vcc
	v_cndmask_b32_e64 v114, v32, 0, vcc
	v_pk_fma_f32 v[134:135], v[92:93], v[98:99], v[94:95]
	v_lshlrev_b32_e32 v132, 16, v44
	v_pk_fma_f32 v[134:135], v[114:115], v[102:103], v[134:135]
	v_and_b32_e32 v133, 0xffff0000, v44
	v_pk_fma_f32 v[134:135], v[106:107], v[130:131], v[134:135]
	v_lshlrev_b32_e32 v36, 16, v28
	v_pk_fma_f32 v[144:145], v[110:111], v[132:133], v[134:135]
	v_and_b32_e32 v28, 0xffff0000, v28
	v_cmp_lt_u32_e64 s[18:19], 2, v136
	v_mul_f32_e32 v32, 0xbfb8aa3b, v144
	v_exp_f32_e32 v32, v32
	v_cndmask_b32_e64 v133, 0, v28, s[18:19]
	v_cndmask_b32_e64 v132, 0, v36, s[18:19]
	v_pk_fma_f32 v[94:95], v[132:133], v[98:99], v[94:95]
	v_add_f32_e32 v32, 1.0, v32
	v_pk_fma_f32 v[92:93], v[92:93], v[102:103], v[94:95]
	v_rcp_f32_e32 v102, v32
	v_pk_fma_f32 v[92:93], v[114:115], v[106:107], v[92:93]
	v_mul_f32_e32 v36, 0xbfb8aa3b, v145
	v_pk_fma_f32 v[98:99], v[110:111], v[130:131], v[92:93]
	v_exp_f32_e32 v36, v36
	v_mul_f32_e32 v28, 0xbfb8aa3b, v98
	v_exp_f32_e32 v28, v28
	v_mul_f32_e32 v32, 0xbfb8aa3b, v99
	v_exp_f32_e32 v32, v32
	v_lshlrev_b32_e32 v40, 16, v41
	v_add_f32_e32 v28, 1.0, v28
	v_rcp_f32_e32 v106, v28
	v_add_f32_e32 v28, 1.0, v32
	v_rcp_f32_e32 v107, v28
	v_add_f32_e32 v28, 1.0, v36
	v_rcp_f32_e32 v103, v28
	v_lshlrev_b32_e32 v28, 16, v33
	v_and_b32_e32 v32, 0xffff0000, v33
	v_cndmask_b32_e64 v33, v32, 0, vcc
	v_cndmask_b32_e64 v32, v28, 0, vcc
	v_lshlrev_b32_e32 v28, 16, v37
	v_and_b32_e32 v36, 0xffff0000, v37
	v_cndmask_b32_e64 v37, v36, 0, vcc
	v_cndmask_b32_e64 v36, v28, 0, vcc
	v_lshlrev_b32_e32 v28, 16, v29
	v_and_b32_e32 v29, 0xffff0000, v29
	v_cndmask_b32_e64 v29, 0, v29, s[18:19]
	v_cndmask_b32_e64 v28, 0, v28, s[18:19]
	v_pk_fma_f32 v[28:29], v[28:29], v[100:101], v[96:97]
	v_and_b32_e32 v41, 0xffff0000, v41
	v_pk_fma_f32 v[28:29], v[32:33], v[104:105], v[28:29]
	v_pk_mul_f32 v[98:99], v[98:99], v[106:107]
	v_pk_fma_f32 v[28:29], v[36:37], v[108:109], v[28:29]
	v_pk_fma_f32 v[106:107], v[32:33], v[100:101], v[96:97]
	v_pk_fma_f32 v[28:29], v[112:113], v[40:41], v[28:29]
	v_pk_fma_f32 v[106:107], v[36:37], v[104:105], v[106:107]
	v_mul_f32_e32 v32, 0xbfb8aa3b, v28
	v_mul_f32_e32 v33, 0xbfb8aa3b, v29
	v_exp_f32_e32 v32, v32
	v_exp_f32_e32 v33, v33
	v_lshlrev_b32_e32 v44, 16, v45
	v_and_b32_e32 v45, 0xffff0000, v45
	v_pk_fma_f32 v[106:107], v[108:109], v[40:41], v[106:107]
	v_add_f32_e32 v32, 1.0, v32
	v_pk_fma_f32 v[44:45], v[112:113], v[44:45], v[106:107]
	v_add_f32_e32 v33, 1.0, v33
	v_mul_f32_e32 v37, 0xbfb8aa3b, v45
	v_rcp_f32_e32 v32, v32
	v_rcp_f32_e32 v33, v33
	v_exp_f32_e32 v37, v37
	ds_read_b128 v[92:95], v121 offset:528
	ds_read_b128 v[130:133], v121 offset:1040
	ds_read_b128 v[134:137], v121 offset:1552
	v_pk_mul_f32 v[32:33], v[28:29], v[32:33]
	v_add_f32_e32 v28, 1.0, v37
	v_rcp_f32_e32 v37, v28
	v_lshlrev_b32_e32 v28, 16, v34
	v_and_b32_e32 v29, 0xffff0000, v34
	v_cndmask_b32_e64 v29, v29, 0, vcc
	v_cndmask_b32_e64 v28, v28, 0, vcc
	v_lshlrev_b32_e32 v34, 16, v38
	v_and_b32_e32 v38, 0xffff0000, v38
	v_cndmask_b32_e64 v41, v38, 0, vcc
	v_cndmask_b32_e64 v40, v34, 0, vcc
	v_pk_fma_f32 v[104:105], v[28:29], v[88:89], v[84:85]
	v_lshlrev_b32_e32 v96, 16, v42
	v_and_b32_e32 v97, 0xffff0000, v42
	s_waitcnt lgkmcnt(2)
	v_pk_fma_f32 v[104:105], v[40:41], v[92:93], v[104:105]
	v_lshlrev_b32_e32 v100, 16, v46
	v_and_b32_e32 v101, 0xffff0000, v46
	s_waitcnt lgkmcnt(1)
	v_pk_fma_f32 v[104:105], v[130:131], v[96:97], v[104:105]
	v_lshlrev_b32_e32 v38, 16, v30
	v_and_b32_e32 v30, 0xffff0000, v30
	s_waitcnt lgkmcnt(0)
	v_pk_fma_f32 v[100:101], v[134:135], v[100:101], v[104:105]
	v_cndmask_b32_e64 v105, 0, v30, s[18:19]
	v_cndmask_b32_e64 v104, 0, v38, s[18:19]
	v_pk_fma_f32 v[84:85], v[104:105], v[88:89], v[84:85]
	v_mul_f32_e32 v34, 0xbfb8aa3b, v100
	v_pk_fma_f32 v[28:29], v[28:29], v[92:93], v[84:85]
	v_exp_f32_e32 v34, v34
	v_pk_fma_f32 v[28:29], v[40:41], v[130:131], v[28:29]
	v_mul_f32_e32 v106, 0xbfb8aa3b, v44
	v_pk_fma_f32 v[28:29], v[134:135], v[96:97], v[28:29]
	v_exp_f32_e32 v36, v106
	v_mul_f32_e32 v30, 0xbfb8aa3b, v28
	v_exp_f32_e32 v38, v30
	v_add_f32_e32 v30, 1.0, v34
	v_add_f32_e32 v36, 1.0, v36
	v_rcp_f32_e32 v36, v36
	v_add_f32_e32 v34, 1.0, v38
	v_mul_f32_e32 v38, 0xbfb8aa3b, v29
	v_exp_f32_e32 v38, v38
	v_mul_f32_e32 v40, 0xbfb8aa3b, v101
	v_exp_f32_e32 v42, v40
	v_rcp_f32_e32 v40, v34
	v_add_f32_e32 v34, 1.0, v38
	v_rcp_f32_e32 v41, v34
	v_lshlrev_b32_e32 v34, 16, v35
	v_and_b32_e32 v35, 0xffff0000, v35
	v_cndmask_b32_e64 v35, v35, 0, vcc
	v_cndmask_b32_e64 v34, v34, 0, vcc
	v_lshlrev_b32_e32 v38, 16, v39
	v_and_b32_e32 v39, 0xffff0000, v39
	v_pk_mul_f32 v[36:37], v[44:45], v[36:37]
	v_cndmask_b32_e64 v39, v39, 0, vcc
	v_cndmask_b32_e64 v38, v38, 0, vcc
	v_lshlrev_b32_e32 v44, 16, v47
	v_and_b32_e32 v45, 0xffff0000, v47
	v_pk_fma_f32 v[46:47], v[34:35], v[90:91], v[86:87]
	v_add_f32_e32 v84, 1.0, v42
	v_lshlrev_b32_e32 v42, 16, v43
	v_and_b32_e32 v43, 0xffff0000, v43
	v_pk_fma_f32 v[46:47], v[38:39], v[94:95], v[46:47]
	v_rcp_f32_e32 v30, v30
	v_pk_fma_f32 v[46:47], v[132:133], v[42:43], v[46:47]
	v_pk_mul_f32 v[40:41], v[28:29], v[40:41]
	v_pk_fma_f32 v[44:45], v[136:137], v[44:45], v[46:47]
	v_pk_mul_f32 v[102:103], v[144:145], v[102:103]
	v_mul_f32_e32 v46, 0xbfb8aa3b, v44
	v_exp_f32_e32 v85, v46
	v_lshlrev_b32_e32 v46, 16, v31
	v_and_b32_e32 v31, 0xffff0000, v31
	v_cndmask_b32_e64 v47, 0, v31, s[18:19]
	v_cndmask_b32_e64 v46, 0, v46, s[18:19]
	v_pk_fma_f32 v[46:47], v[46:47], v[90:91], v[86:87]
	v_cvt_pk_bf16_f32 v28, v98, v99
	v_pk_fma_f32 v[34:35], v[34:35], v[94:95], v[46:47]
	v_cvt_pk_bf16_f32 v29, v32, v33
	v_pk_fma_f32 v[34:35], v[38:39], v[132:133], v[34:35]
	v_add_f32_e32 v38, 1.0, v85
	v_pk_fma_f32 v[34:35], v[136:137], v[42:43], v[34:35]
	v_rcp_f32_e32 v38, v38
	v_mul_f32_e32 v31, 0xbfb8aa3b, v34
	v_exp_f32_e32 v39, v31
	v_mul_f32_e32 v42, 0xbfb8aa3b, v35
	v_exp_f32_e32 v43, v42
	v_mul_f32_e32 v42, 0xbfb8aa3b, v45
	v_exp_f32_e32 v46, v42
	v_add_f32_e32 v39, 1.0, v39
	v_rcp_f32_e32 v42, v39
	v_add_f32_e32 v39, 1.0, v43
	v_rcp_f32_e32 v43, v39
	v_add_f32_e32 v39, 1.0, v46
	v_rcp_f32_e32 v31, v84
	v_rcp_f32_e32 v39, v39
	v_pk_mul_f32 v[34:35], v[34:35], v[42:43]
	v_cvt_pk_bf16_f32 v32, v102, v103
	v_pk_mul_f32 v[46:47], v[100:101], v[30:31]
	v_pk_mul_f32 v[38:39], v[44:45], v[38:39]
	v_cvt_pk_bf16_f32 v30, v40, v41
	v_cvt_pk_bf16_f32 v31, v34, v35
	v_cvt_pk_bf16_f32 v33, v36, v37
	v_cvt_pk_bf16_f32 v34, v46, v47
	v_cvt_pk_bf16_f32 v35, v38, v39
	ds_write_b128 v184, v[28:31]
	ds_write_b128 v184, v[32:35] offset:272
	v_lshlrev_b32_e32 v28, 16, v24
	v_and_b32_e32 v24, 0xffff0000, v24
	v_cndmask_b32_e64 v106, 0, v24, s[18:19]
	v_and_b32_e32 v24, 0xffff0000, v25
	v_cndmask_b32_e64 v44, 0, v28, s[18:19]
	v_lshlrev_b32_e32 v28, 16, v25
	v_lshlrev_b32_e32 v25, 16, v26
	v_cndmask_b32_e64 v110, 0, v24, s[18:19]
	v_and_b32_e32 v24, 0xffff0000, v26
	v_lshlrev_b32_e32 v45, 16, v8
	v_cndmask_b32_e64 v112, 0, v25, s[18:19]
	v_lshlrev_b32_e32 v25, 16, v27
	v_cndmask_b32_e64 v114, 0, v24, s[18:19]
	v_and_b32_e32 v24, 0xffff0000, v27
	v_cndmask_b32_e64 v130, v45, 0, vcc
	v_cndmask_b32_e64 v108, 0, v28, s[18:19]
	v_cndmask_b32_e64 v84, 0, v25, s[18:19]
	v_cndmask_b32_e64 v46, 0, v24, s[18:19]
	ds_read_b128 v[86:89], v185
	ds_read_b128 v[32:35], v185 offset:16
	ds_read_b128 v[90:93], v121 offset:2560
	ds_read_b128 v[40:43], v121 offset:2576
	ds_read_b128 v[94:97], v121 offset:3072
	ds_read_b128 v[36:39], v121 offset:3088
	ds_read_b128 v[98:101], v121 offset:3584
	ds_read_b128 v[24:27], v121 offset:3600
	ds_read_b128 v[102:105], v121 offset:4096
	ds_read_b128 v[28:31], v121 offset:4112
	v_and_b32_e32 v8, 0xffff0000, v8
	v_mov_b32_e32 v45, v130
	s_waitcnt lgkmcnt(7)
	v_mov_b32_e32 v146, v90
	s_waitcnt lgkmcnt(5)
	v_mov_b32_e32 v147, v94
	v_cndmask_b32_e64 v131, v8, 0, vcc
	v_lshlrev_b32_e32 v8, 16, v12
	v_pk_mul_f32 v[44:45], v[44:45], v[146:147]
	v_cndmask_b32_e64 v132, v8, 0, vcc
	v_add_f32_e32 v8, v86, v44
	v_add_f32_e32 v8, v8, v45
	v_mov_b32_e32 v107, v131
	v_mov_b32_e32 v44, v91
	v_mov_b32_e32 v45, v95
	v_and_b32_e32 v12, 0xffff0000, v12
	v_lshlrev_b32_e32 v134, 16, v16
	v_pk_mul_f32 v[44:45], v[106:107], v[44:45]
	v_cndmask_b32_e64 v133, v12, 0, vcc
	v_pk_fma_f32 v[144:145], v[130:131], v[90:91], v[86:87]
	v_add_f32_e32 v12, v87, v44
	v_mov_b32_e32 v86, v132
	s_waitcnt lgkmcnt(1)
	v_mov_b32_e32 v87, v102
	v_mov_b32_e32 v90, v98
	v_mov_b32_e32 v91, v134
	v_pk_mul_f32 v[86:87], v[86:87], v[90:91]
	v_and_b32_e32 v135, 0xffff0000, v16
	v_add_f32_e32 v8, v8, v86
	v_add_f32_e32 v8, v8, v87
	v_mul_f32_e32 v16, 0xbfb8aa3b, v8
	v_exp_f32_e32 v16, v16
	v_add_f32_e32 v12, v12, v45
	v_pk_fma_f32 v[44:45], v[132:133], v[94:95], v[144:145]
	v_lshlrev_b32_e32 v136, 16, v20
	v_and_b32_e32 v137, 0xffff0000, v20
	v_pk_fma_f32 v[44:45], v[98:99], v[134:135], v[44:45]
	v_add_f32_e32 v16, 1.0, v16
	v_pk_fma_f32 v[44:45], v[102:103], v[136:137], v[44:45]
	v_mov_b32_e32 v86, v133
	v_mul_f32_e32 v20, 0xbfb8aa3b, v44
	v_mov_b32_e32 v87, v103
	v_mov_b32_e32 v134, v99
	v_rcp_f32_e32 v16, v16
	v_exp_f32_e32 v20, v20
	v_pk_mul_f32 v[86:87], v[86:87], v[134:135]
	v_mul_f32_e32 v47, 0xbfb8aa3b, v45
	v_add_f32_e32 v12, v12, v86
	v_add_f32_e32 v12, v12, v87
	v_mul_f32_e32 v8, v8, v16
	v_add_f32_e32 v16, 1.0, v20
	v_mul_f32_e32 v20, 0xbfb8aa3b, v12
	v_exp_f32_e32 v20, v20
	v_rcp_f32_e32 v86, v16
	v_exp_f32_e32 v47, v47
	v_mul_f32_e32 v94, 0x3db504f3, v8
	v_add_f32_e32 v16, 1.0, v20
	v_rcp_f32_e32 v16, v16
	v_add_f32_e32 v20, 1.0, v47
	v_rcp_f32_e32 v87, v20
	v_mov_b32_e32 v90, v92
	v_mul_f32_e32 v8, v12, v16
	v_mul_f32_e32 v95, 0x3db504f3, v8
	v_lshlrev_b32_e32 v8, 16, v9
	v_cndmask_b32_e64 v8, v8, 0, vcc
	v_and_b32_e32 v9, 0xffff0000, v9
	v_mov_b32_e32 v109, v8
	v_mov_b32_e32 v91, v96
	v_cndmask_b32_e64 v9, v9, 0, vcc
	v_pk_mul_f32 v[90:91], v[108:109], v[90:91]
	v_pk_mul_f32 v[44:45], v[44:45], v[86:87]
	v_pk_fma_f32 v[86:87], v[8:9], v[92:93], v[88:89]
	v_add_f32_e32 v8, v88, v90
	v_add_f32_e32 v47, v8, v91
	v_mov_b32_e32 v111, v9
	v_mov_b32_e32 v8, v93
	v_mov_b32_e32 v9, v97
	v_lshlrev_b32_e32 v12, 16, v13
	v_and_b32_e32 v13, 0xffff0000, v13
	v_pk_mul_f32 v[8:9], v[110:111], v[8:9]
	v_cndmask_b32_e64 v13, v13, 0, vcc
	v_cndmask_b32_e64 v12, v12, 0, vcc
	v_lshlrev_b32_e32 v16, 16, v17
	v_add_f32_e32 v8, v89, v8
	v_add_f32_e32 v85, v8, v9
	v_pk_fma_f32 v[8:9], v[12:13], v[96:97], v[86:87]
	v_mov_b32_e32 v86, v12
	v_mov_b32_e32 v87, v104
	v_mov_b32_e32 v88, v100
	v_mov_b32_e32 v89, v16
	v_pk_mul_f32 v[86:87], v[86:87], v[88:89]
	v_and_b32_e32 v17, 0xffff0000, v17
	v_add_f32_e32 v12, v47, v86
	v_add_f32_e32 v47, v12, v87
	v_lshlrev_b32_e32 v20, 16, v21
	v_and_b32_e32 v21, 0xffff0000, v21
	v_pk_fma_f32 v[8:9], v[100:101], v[16:17], v[8:9]
	v_mul_f32_e32 v16, 0xbfb8aa3b, v47
	v_mov_b32_e32 v12, v13
	v_mov_b32_e32 v13, v105
	v_exp_f32_e32 v86, v16
	v_mov_b32_e32 v16, v101
	v_pk_fma_f32 v[8:9], v[104:105], v[20:21], v[8:9]
	v_pk_mul_f32 v[12:13], v[12:13], v[16:17]
	v_mul_f32_e32 v17, 0xbfb8aa3b, v8
	v_exp_f32_e32 v17, v17
	v_add_f32_e32 v12, v85, v12
	v_add_f32_e32 v20, v12, v13
	v_mul_f32_e32 v13, 0xbfb8aa3b, v20
	v_add_f32_e32 v12, 1.0, v17
	v_exp_f32_e32 v13, v13
	v_mul_f32_e32 v17, 0xbfb8aa3b, v9
	v_exp_f32_e32 v17, v17
	v_rcp_f32_e32 v12, v12
	v_add_f32_e32 v13, 1.0, v13
	v_rcp_f32_e32 v21, v13
	v_add_f32_e32 v13, 1.0, v17
	v_rcp_f32_e32 v13, v13
	v_add_f32_e32 v16, 1.0, v86
	v_rcp_f32_e32 v16, v16
	v_mov_b32_e32 v90, v40
	v_pk_mul_f32 v[8:9], v[8:9], v[12:13]
	v_lshlrev_b32_e32 v12, 16, v10
	v_and_b32_e32 v10, 0xffff0000, v10
	v_cndmask_b32_e64 v13, v10, 0, vcc
	v_cndmask_b32_e64 v12, v12, 0, vcc
	v_mul_f32_e32 v16, v47, v16
	v_pk_fma_f32 v[88:89], v[12:13], v[40:41], v[32:33]
	v_mov_b32_e32 v113, v12
	v_mov_b32_e32 v115, v13
	v_mov_b32_e32 v12, v41
	v_mov_b32_e32 v13, v37
	v_mul_f32_e32 v92, 0x3db504f3, v16
	v_mul_f32_e32 v16, v20, v21
	v_lshlrev_b32_e32 v10, 16, v14
	v_and_b32_e32 v14, 0xffff0000, v14
	v_mov_b32_e32 v91, v36
	v_pk_mul_f32 v[12:13], v[114:115], v[12:13]
	v_mul_f32_e32 v93, 0x3db504f3, v16
	v_cndmask_b32_e64 v17, v14, 0, vcc
	v_cndmask_b32_e64 v16, v10, 0, vcc
	v_lshlrev_b32_e32 v20, 16, v18
	v_pk_mul_f32 v[90:91], v[112:113], v[90:91]
	v_add_f32_e32 v12, v33, v12
	v_add_f32_e32 v10, v32, v90
	v_add_f32_e32 v14, v12, v13
	v_pk_fma_f32 v[12:13], v[16:17], v[36:37], v[88:89]
	v_mov_b32_e32 v32, v16
	s_waitcnt lgkmcnt(0)
	v_mov_b32_e32 v33, v28
	v_mov_b32_e32 v36, v24
	v_mov_b32_e32 v37, v20
	v_add_f32_e32 v10, v10, v91
	v_pk_mul_f32 v[32:33], v[32:33], v[36:37]
	v_and_b32_e32 v21, 0xffff0000, v18
	v_add_f32_e32 v10, v10, v32
	v_add_f32_e32 v10, v10, v33
	v_mul_f32_e32 v18, 0xbfb8aa3b, v10
	v_exp_f32_e32 v18, v18
	v_pk_fma_f32 v[12:13], v[24:25], v[20:21], v[12:13]
	v_mov_b32_e32 v16, v17
	v_mov_b32_e32 v17, v29
	v_mov_b32_e32 v20, v25
	v_pk_mul_f32 v[16:17], v[16:17], v[20:21]
	v_add_f32_e32 v18, 1.0, v18
	v_add_f32_e32 v14, v14, v16
	v_lshlrev_b32_e32 v86, 16, v22
	v_and_b32_e32 v87, 0xffff0000, v22
	v_rcp_f32_e32 v18, v18
	v_add_f32_e32 v14, v14, v17
	v_pk_fma_f32 v[12:13], v[28:29], v[86:87], v[12:13]
	v_mul_f32_e32 v17, 0xbfb8aa3b, v14
	v_mul_f32_e32 v20, 0xbfb8aa3b, v12
	v_exp_f32_e32 v17, v17
	v_exp_f32_e32 v20, v20
	v_mul_f32_e32 v10, v10, v18
	v_mul_f32_e32 v18, 0xbfb8aa3b, v13
	v_exp_f32_e32 v18, v18
	v_add_f32_e32 v17, 1.0, v17
	v_add_f32_e32 v16, 1.0, v20
	v_rcp_f32_e32 v20, v17
	v_add_f32_e32 v17, 1.0, v18
	v_rcp_f32_e32 v16, v16
	v_rcp_f32_e32 v17, v17
	v_mul_f32_e32 v24, 0x3db504f3, v10
	v_mul_f32_e32 v10, v14, v20
	v_mul_f32_e32 v25, 0x3db504f3, v10
	v_lshlrev_b32_e32 v10, 16, v11
	v_cndmask_b32_e64 v10, v10, 0, vcc
	v_pk_mul_f32 v[12:13], v[12:13], v[16:17]
	v_and_b32_e32 v11, 0xffff0000, v11
	v_lshlrev_b32_e32 v16, 16, v23
	v_and_b32_e32 v17, 0xffff0000, v23
	v_mov_b32_e32 v85, v10
	v_mov_b32_e32 v22, v42
	v_mov_b32_e32 v23, v38
	s_mov_b32 s0, s2
	s_mov_b32 s2, 0x3db504f3
	v_cndmask_b32_e64 v11, v11, 0, vcc
	v_pk_mul_f32 v[22:23], v[84:85], v[22:23]
	v_pk_mul_f32 v[20:21], v[12:13], s[2:3] op_sel_hi:[1,0]
	v_lshlrev_b32_e32 v12, 16, v15
	v_and_b32_e32 v13, 0xffff0000, v15
	v_lshlrev_b32_e32 v14, 16, v19
	v_and_b32_e32 v15, 0xffff0000, v19
	v_pk_fma_f32 v[18:19], v[10:11], v[42:43], v[34:35]
	v_add_f32_e32 v10, v34, v22
	v_add_f32_e32 v28, v10, v23
	v_mov_b32_e32 v47, v11
	v_mov_b32_e32 v10, v43
	v_mov_b32_e32 v11, v39
	v_pk_mul_f32 v[10:11], v[46:47], v[10:11]
	v_cndmask_b32_e64 v13, v13, 0, vcc
	v_cndmask_b32_e64 v12, v12, 0, vcc
	v_add_f32_e32 v10, v35, v10
	v_add_f32_e32 v29, v10, v11
	v_pk_fma_f32 v[10:11], v[12:13], v[38:39], v[18:19]
	v_mov_b32_e32 v18, v12
	v_mov_b32_e32 v19, v30
	v_mov_b32_e32 v22, v26
	v_mov_b32_e32 v23, v14
	v_pk_mul_f32 v[18:19], v[18:19], v[22:23]
	v_pk_fma_f32 v[10:11], v[26:27], v[14:15], v[10:11]
	v_add_f32_e32 v12, v28, v18
	v_add_f32_e32 v18, v12, v19
	v_mul_f32_e32 v14, 0xbfb8aa3b, v18
	v_mov_b32_e32 v12, v13
	v_mov_b32_e32 v13, v31
	v_exp_f32_e32 v19, v14
	v_mov_b32_e32 v14, v27
	v_pk_fma_f32 v[10:11], v[30:31], v[16:17], v[10:11]
	v_pk_mul_f32 v[12:13], v[12:13], v[14:15]
	v_mul_f32_e32 v15, 0xbfb8aa3b, v10
	v_exp_f32_e32 v15, v15
	v_add_f32_e32 v12, v29, v12
	v_add_f32_e32 v16, v12, v13
	v_mul_f32_e32 v13, 0xbfb8aa3b, v16
	v_add_f32_e32 v12, 1.0, v15
	v_exp_f32_e32 v13, v13
	v_mul_f32_e32 v15, 0xbfb8aa3b, v11
	v_exp_f32_e32 v15, v15
	v_add_f32_e32 v14, 1.0, v19
	v_rcp_f32_e32 v14, v14
	v_add_f32_e32 v13, 1.0, v13
	v_rcp_f32_e32 v17, v13
	v_add_f32_e32 v13, 1.0, v15
	v_rcp_f32_e32 v12, v12
	v_rcp_f32_e32 v13, v13
	v_mul_f32_e32 v14, v18, v14
	v_mul_f32_e32 v22, 0x3db504f3, v14
	v_mul_f32_e32 v14, v16, v17
	v_mul_f32_e32 v23, 0x3db504f3, v14
	v_pk_mul_f32 v[10:11], v[10:11], v[12:13]
	v_pk_mul_f32 v[44:45], v[44:45], s[2:3] op_sel_hi:[1,0]
	v_pk_mul_f32 v[8:9], v[8:9], s[2:3] op_sel_hi:[1,0]
	v_pk_mul_f32 v[18:19], v[10:11], s[2:3] op_sel_hi:[1,0]
	v_cvt_pk_bf16_f32 v10, v94, v95
	v_cvt_pk_bf16_f32 v11, v92, v93
	v_cvt_pk_bf16_f32 v12, v24, v25
	v_cvt_pk_bf16_f32 v13, v22, v23
	v_cvt_pk_bf16_f32 v14, v44, v45
	v_cvt_pk_bf16_f32 v15, v8, v9
	v_cvt_pk_bf16_f32 v16, v20, v21
	v_cvt_pk_bf16_f32 v17, v18, v19
	ds_write_b128 v184, v[10:13] offset:17408
	ds_write_b128 v184, v[14:17] offset:17680
	v_mov_b64_e32 v[10:11], s[36:37]
	global_load_dword v84, v[10:11], off
	global_load_dword v85, v[10:11], off offset:16
	v_add_u32_e32 v12, 0x8800, v198
	v_cvt_pk_bf16_f32 v8, v92, v8
	v_cvt_pk_bf16_f32 v9, v93, v9
	s_add_i32 s2, s0, 1
	ds_write2_b32 v12, v8, v9 offset0:72 offset1:108
	v_cvt_pk_bf16_f32 v8, v24, v20
	v_cvt_pk_bf16_f32 v9, v25, v21
	s_lshl_b32 s1, s2, 6
	ds_write2_b32 v12, v8, v9 offset0:144 offset1:180
	v_cvt_pk_bf16_f32 v8, v22, v18
	s_cmp_lg_u32 s0, 31
	v_cvt_pk_bf16_f32 v10, v94, v44
	v_cvt_pk_bf16_f32 v11, v95, v45
	ds_write_b32 v198, v8 offset:35680
	v_cvt_pk_bf16_f32 v8, v23, v19
	s_cselect_b32 s0, s1, 0x7c0
	ds_write2_b32 v12, v10, v11 offset1:36
	ds_write_b32 v199, v8 offset:34816
	ds_write_b16 v186, v4 offset:53248
	ds_write_b16_d16_hi v186, v4 offset:53392
	ds_write_b16 v186, v5 offset:53536
	ds_write_b16_d16_hi v186, v5 offset:53680
	ds_write_b16 v186, v6 offset:53824
	ds_write_b16_d16_hi v186, v6 offset:53968
	ds_write_b16 v186, v7 offset:54112
	ds_write_b16_d16_hi v186, v7 offset:54256
	ds_write_b16 v186, v0 offset:54400
	ds_write_b16_d16_hi v186, v0 offset:54544
	ds_write_b16 v186, v1 offset:54688
	ds_write_b16_d16_hi v186, v1 offset:54832
	ds_write_b16 v186, v2 offset:54976
	ds_write_b16_d16_hi v186, v2 offset:55120
	ds_write_b16 v186, v3 offset:55264
	ds_write_b16_d16_hi v186, v3 offset:55408
	v_add_u32_e32 v4, s0, v173
	v_max_i32_e32 v0, 0, v4
	v_add_u32_e32 v0, s43, v0
	v_ashrrev_i32_e32 v1, 31, v0
	v_lshlrev_b64 v[0:1], 10, v[0:1]
	v_lshl_add_u64 v[2:3], v[116:117], 0, v[0:1]
	v_lshl_add_u64 v[0:1], v[118:119], 0, v[0:1]
	global_load_dwordx4 v[28:31], v[2:3], off
	global_load_dwordx4 v[24:27], v[0:1], off
	v_max_i32_e32 v0, -1, v4
	v_add_u32_e32 v0, s45, v0
	v_ashrrev_i32_e32 v1, 31, v0
	v_lshlrev_b64 v[0:1], 10, v[0:1]
	v_lshl_add_u64 v[2:3], v[116:117], 0, v[0:1]
	v_lshl_add_u64 v[0:1], v[118:119], 0, v[0:1]
	global_load_dwordx4 v[32:35], v[2:3], off
	global_load_dwordx4 v[8:11], v[0:1], off
	v_max_i32_e32 v0, -2, v4
	v_add_u32_e32 v0, s46, v0
	v_ashrrev_i32_e32 v1, 31, v0
	v_lshlrev_b64 v[0:1], 10, v[0:1]
	v_lshl_add_u64 v[2:3], v[116:117], 0, v[0:1]
	v_lshl_add_u64 v[0:1], v[118:119], 0, v[0:1]
	global_load_dwordx4 v[36:39], v[2:3], off
	global_load_dwordx4 v[12:15], v[0:1], off
	v_add_u32_e32 v0, s0, v120
	v_ashrrev_i32_e32 v1, 31, v0
	v_lshlrev_b64 v[0:1], 10, v[0:1]
	v_lshl_add_u64 v[2:3], v[116:117], 0, v[0:1]
	v_lshl_add_u64 v[0:1], v[118:119], 0, v[0:1]
	global_load_dwordx4 v[40:43], v[2:3], off
	global_load_dwordx4 v[16:19], v[0:1], off
	v_max_i32_e32 v0, -4, v4
	v_add_u32_e32 v0, s47, v0
	v_ashrrev_i32_e32 v1, 31, v0
	v_lshlrev_b64 v[0:1], 10, v[0:1]
	v_lshl_add_u64 v[2:3], v[116:117], 0, v[0:1]
	v_lshl_add_u64 v[0:1], v[118:119], 0, v[0:1]
	global_load_dwordx4 v[44:47], v[2:3], off
	global_load_dwordx4 v[20:23], v[0:1], off
	s_mov_b32 s1, 0xbfb8aa3b
	s_add_i32 s18, s0, s43
	s_mov_b32 s0, 0x800000
	s_waitcnt vmcnt(0) lgkmcnt(0)
	v_add_f32_e32 v92, v195, v84
	v_add_f32_e32 v2, v204, v85
	v_mul_f32_e64 v0, |v2|, s1
	v_exp_f32_e32 v0, v0
	v_min_f32_e32 v2, 0, v2
	v_or_b32_e32 v84, s18, v170
	v_ashrrev_i32_e32 v85, 31, v84
	v_add_f32_e32 v0, 1.0, v0
	v_cmp_gt_f32_e32 vcc, s0, v0
	s_mov_b32 s0, 0x3f317217
	s_nop 0
	v_cndmask_b32_e64 v1, 0, 32, vcc
	v_ldexp_f32 v0, v0, v1
	v_log_f32_e32 v3, v0
	v_lshlrev_b64 v[0:1], 10, v[84:85]
	v_lshlrev_b64 v[84:85], 7, v[84:85]
	v_lshl_add_u64 v[0:1], s[30:31], 0, v[0:1]
	v_mul_f32_e32 v4, 0x3f317217, v3
	v_fma_f32 v4, v3, s0, -v4
	v_fmac_f32_e32 v4, 0x3377d1cf, v3
	s_mov_b32 s0, 0x7f800000
	v_fmac_f32_e32 v4, 0x3f317217, v3
	v_cmp_lt_f32_e64 s[0:1], |v3|, s0
	v_lshl_add_u64 v[84:85], s[34:35], 0, v[84:85]
	s_nop 0
	v_cndmask_b32_e64 v3, v3, v4, s[0:1]
	v_cndmask_b32_e32 v4, 0, v225, vcc
	v_sub_f32_e32 v3, v3, v4
	v_sub_f32_e32 v86, v2, v3
	v_add_u32_e32 v2, -1, v211
	v_cmp_lt_i32_e32 vcc, v2, v212
	v_readlane_b32 s0, v253, 41
	v_readlane_b32 s1, v253, 42
	v_cndmask_b32_e32 v2, v2, v211, vcc
	v_lshlrev_b32_e32 v93, 2, v2
	ds_bpermute_b32 v87, v93, v86
	global_load_dwordx4 v[4:7], v[0:1], off
	s_nop 0
	global_load_dwordx4 v[0:3], v[0:1], off offset:16
	s_waitcnt lgkmcnt(0)
	v_add_f32_e32 v87, v86, v87
	v_cndmask_b32_e64 v90, v87, v86, s[8:9]
	v_add_u32_e32 v86, -2, v211
	v_cmp_lt_i32_e32 vcc, v86, v212
	s_nop 1
	v_cndmask_b32_e32 v86, v86, v211, vcc
	v_lshlrev_b32_e32 v94, 2, v86
	ds_bpermute_b32 v91, v94, v90
	v_or_b32_e32 v86, s18, v171
	v_ashrrev_i32_e32 v87, 31, v86
	v_lshlrev_b64 v[88:89], 10, v[86:87]
	v_lshl_add_u64 v[88:89], v[122:123], 0, v[88:89]
	s_waitcnt lgkmcnt(0)
	v_add_f32_e32 v87, v90, v91
	v_cndmask_b32_e64 v87, v87, v90, s[10:11]
	v_add_u32_e32 v90, -4, v211
	v_cmp_lt_i32_e32 vcc, v90, v212
	s_nop 1
	v_cndmask_b32_e32 v90, v90, v211, vcc
	v_lshlrev_b32_e32 v95, 2, v90
	ds_bpermute_b32 v96, v95, v87
	v_or_b32_e32 v90, 16, v86
	v_ashrrev_i32_e32 v91, 31, v90
	v_lshlrev_b64 v[90:91], 10, v[90:91]
	v_lshl_add_u64 v[90:91], v[122:123], 0, v[90:91]
	s_waitcnt lgkmcnt(0)
	v_add_f32_e32 v96, v87, v96
	v_cndmask_b32_e64 v87, v96, v87, s[12:13]
	v_add_u32_e32 v96, -8, v211
	v_cmp_lt_i32_e32 vcc, v96, v212
	global_load_dword v195, v[84:85], off
	global_load_dword v204, v[84:85], off offset:16
	global_load_dwordx2 v[130:131], v[88:89], off
	global_load_dwordx2 v[132:133], v[90:91], off
	v_cndmask_b32_e32 v96, v96, v211, vcc
	v_lshlrev_b32_e32 v96, 2, v96
	ds_bpermute_b32 v97, v96, v87
	v_or_b32_e32 v84, 32, v86
	v_ashrrev_i32_e32 v85, 31, v84
	v_or_b32_e32 v86, 48, v86
	v_lshlrev_b64 v[84:85], 10, v[84:85]
	s_waitcnt lgkmcnt(0)
	v_add_f32_e32 v88, v87, v97
	v_cndmask_b32_e64 v88, v88, v87, s[14:15]
	v_add_u32_e32 v87, -16, v211
	v_cmp_lt_i32_e32 vcc, v87, v212
	v_lshl_add_u64 v[84:85], v[122:123], 0, v[84:85]
	s_nop 0
	v_cndmask_b32_e32 v87, v87, v211, vcc
	v_lshlrev_b32_e32 v89, 2, v87
	v_ashrrev_i32_e32 v87, 31, v86
	ds_bpermute_b32 v90, v89, v88
	v_lshlrev_b64 v[86:87], 10, v[86:87]
	v_lshl_add_u64 v[86:87], v[122:123], 0, v[86:87]
	global_load_dwordx2 v[134:135], v[84:85], off
	global_load_dwordx2 v[136:137], v[86:87], off
	s_waitcnt lgkmcnt(0)
	v_add_f32_e32 v90, v88, v90
	v_cndmask_b32_e64 v88, v90, v88, s[4:5]
	v_subrev_u32_e32 v90, 32, v211
	v_cmp_lt_i32_e32 vcc, v90, v212
	s_nop 1
	v_cndmask_b32_e32 v90, v90, v211, vcc
	v_lshlrev_b32_e32 v90, 2, v90
	ds_bpermute_b32 v91, v90, v88
	s_andn2_b64 vcc, exec, s[0:1]
	s_mov_b64 s[0:1], -1
	s_waitcnt lgkmcnt(0)
	v_add_f32_e32 v84, v88, v91
	v_cndmask_b32_e64 v84, v84, v88, s[16:17]
	v_sub_f32_e32 v85, v92, v84
	ds_bpermute_b32 v86, v93, v85
	s_waitcnt lgkmcnt(0)
	v_max_f32_e32 v86, v86, v86
	v_max_f32_e32 v86, v85, v86
	v_cndmask_b32_e64 v86, v86, v85, s[8:9]
	ds_bpermute_b32 v87, v94, v86
	s_waitcnt lgkmcnt(0)
	v_max_f32_e32 v87, v87, v87
	v_max_f32_e32 v87, v86, v87
	v_cndmask_b32_e64 v86, v87, v86, s[10:11]
	ds_bpermute_b32 v87, v95, v86
	s_waitcnt lgkmcnt(0)
	v_max_f32_e32 v87, v87, v87
	v_max_f32_e32 v87, v86, v87
	v_cndmask_b32_e64 v86, v87, v86, s[12:13]
	ds_bpermute_b32 v87, v96, v86
	s_waitcnt lgkmcnt(0)
	v_max_f32_e32 v87, v87, v87
	v_max_f32_e32 v87, v86, v87
	v_cndmask_b32_e64 v86, v87, v86, s[14:15]
	ds_bpermute_b32 v87, v89, v86
	s_waitcnt lgkmcnt(0)
	v_max_f32_e32 v87, v87, v87
	v_max_f32_e32 v87, v86, v87
	v_cndmask_b32_e64 v86, v87, v86, s[4:5]
	ds_bpermute_b32 v87, v90, v86
	v_max_f32_e32 v88, v86, v86
	s_waitcnt lgkmcnt(0)
	v_max_f32_e32 v87, v87, v87
	v_max_f32_e32 v87, v88, v87
	v_cndmask_b32_e64 v86, v87, v86, s[16:17]
	v_max_f32_e32 v86, v86, v86
	v_max_f32_e64 v87, s44, s44
	v_max_f32_e32 v86, v87, v86
	v_lshl_or_b32 v87, v211, 2, v226
	ds_bpermute_b32 v88, v87, v86
	v_add_f32_e32 v84, v84, v86
	v_sub_f32_e32 v89, s44, v86
	v_mul_f32_e32 v89, 0x3fb8aa3b, v89
	v_mul_f32_e32 v90, 0xbfb8aa3b, v84
	s_waitcnt lgkmcnt(0)
	v_sub_f32_e32 v91, v85, v88
	v_exp_f32_e32 v89, v89
	v_exp_f32_e32 v90, v90
	v_mul_f32_e32 v91, 0x3fb8aa3b, v91
	v_sub_f32_e32 v88, s44, v88
	v_exp_f32_e32 v91, v91
	v_mul_f32_e32 v88, 0x3fb8aa3b, v88
	ds_bpermute_b32 v84, v87, v84
	v_exp_f32_e32 v88, v88
	ds_write2st64_b32 v174, v86, v85 offset1:1
	ds_write2st64_b32 v174, v89, v90 offset0:2 offset1:3
	ds_write_b32 v174, v91 offset:1024
	s_waitcnt lgkmcnt(0)
	s_barrier
	v_readfirstlane_b32 s18, v88
	s_waitcnt lgkmcnt(0)
	v_readfirstlane_b32 s44, v84
	s_cbranch_vccnz .LBB0_354
	v_xor_b32_e32 v144, 32, v211
	s_mov_b64 s[0:1], 0

.LBB0_375:
	s_or_b64 exec, exec, s[0:1]
	s_or_b32 s0, s48, s43
	s_add_i32 s1, 0, 0x1b100
	s_waitcnt lgkmcnt(0)
	s_barrier
	v_add_u32_e32 v94, s1, v191
	s_waitcnt lgkmcnt(0)
	ds_read2st64_b64 v[88:91], v94 offset1:1
	s_brev_b32 s48, 60
	s_mov_b32 s19, 0x800000
	v_pk_mul_f32 v[50:51], v[50:51], s[18:19] op_sel_hi:[1,0]
	v_pk_mul_f32 v[48:49], v[48:49], s[18:19] op_sel_hi:[1,0]
	s_waitcnt lgkmcnt(0)
	v_pk_add_f32 v[88:89], v[88:89], 0 op_sel_hi:[1,0]
	v_pk_mul_f32 v[74:75], v[74:75], s[18:19] op_sel_hi:[1,0]
	v_pk_add_f32 v[92:93], v[88:89], v[90:91]
	ds_read2st64_b64 v[88:91], v94 offset0:2 offset1:3
	v_pk_mul_f32 v[72:73], v[72:73], s[18:19] op_sel_hi:[1,0]
	v_pk_mul_f32 v[70:71], v[70:71], s[18:19] op_sel_hi:[1,0]
	v_pk_mul_f32 v[68:69], v[68:69], s[18:19] op_sel_hi:[1,0]
	v_pk_mul_f32 v[66:67], v[66:67], s[18:19] op_sel_hi:[1,0]
	s_waitcnt lgkmcnt(0)
	v_pk_add_f32 v[88:89], v[92:93], v[88:89]
	v_pk_mul_f32 v[64:65], v[64:65], s[18:19] op_sel_hi:[1,0]
	v_pk_add_f32 v[92:93], v[88:89], v[90:91]
	ds_read2st64_b64 v[88:91], v94 offset0:4 offset1:5
	v_pk_mul_f32 v[78:79], v[78:79], s[18:19] op_sel_hi:[1,0]
	v_pk_mul_f32 v[76:77], v[76:77], s[18:19] op_sel_hi:[1,0]
	v_pk_mul_f32 v[82:83], v[82:83], s[18:19] op_sel_hi:[1,0]
	v_pk_mul_f32 v[80:81], v[80:81], s[18:19] op_sel_hi:[1,0]
	s_waitcnt lgkmcnt(0)
	v_pk_add_f32 v[88:89], v[92:93], v[88:89]
	s_nop 0
	v_pk_add_f32 v[92:93], v[88:89], v[90:91]
	ds_read2st64_b64 v[88:91], v94 offset0:6 offset1:7
	global_load_dwordx4 v[94:97], v[126:127], off
	s_waitcnt lgkmcnt(0)
	v_pk_add_f32 v[88:89], v[92:93], v[88:89]
	v_lshlrev_b32_e32 v93, 16, v142
	v_mul_f32_e32 v93, 0xbfb8aa3b, v93
	v_exp_f32_e32 v93, v93
	v_pk_add_f32 v[88:89], v[88:89], v[90:91]
	v_add_f32_e32 v93, 1.0, v93
	v_pk_mul_f32 v[90:91], v[88:89], s[48:49] op_sel_hi:[1,0]
	v_rcp_f32_e32 v98, v93
	v_and_b32_e32 v93, 0xffff0000, v142
	v_fma_f32 v88, -v90, v90, v91
	v_mul_f32_e32 v93, 0xbfb8aa3b, v93
	v_max_f32_e32 v88, 0, v88
	v_exp_f32_e32 v93, v93
	v_add_f32_e32 v88, 0x358637bd, v88
	v_cmp_gt_f32_e32 vcc, s19, v88
	v_mul_f32_e32 v89, 0x4b800000, v88
	v_add_f32_e32 v93, 1.0, v93
	v_cndmask_b32_e32 v88, v88, v89, vcc
	v_rsq_f32_e32 v88, v88
	v_rcp_f32_e32 v99, v93
	v_pk_add_f32 v[100:101], v[154:155], v[90:91] op_sel_hi:[1,0] neg_lo:[0,1] neg_hi:[0,1]
	v_pk_add_f32 v[90:91], v[152:153], v[90:91] op_sel_hi:[1,0] neg_lo:[0,1] neg_hi:[0,1]
	v_mul_f32_e32 v89, 0x45800000, v88
	v_cndmask_b32_e32 v92, v88, v89, vcc
	v_pk_mul_f32 v[98:99], v[98:99], v[100:101]
	v_or_b32_e32 v88, s0, v171
	v_pk_mul_f32 v[98:99], v[98:99], v[92:93] op_sel_hi:[1,0]
	v_lshlrev_b32_e32 v93, 16, v143
	v_mul_f32_e32 v93, 0xbfb8aa3b, v93
	v_exp_f32_e32 v93, v93
	v_ashrrev_i32_e32 v89, 31, v88
	v_lshlrev_b64 v[88:89], 10, v[88:89]
	v_lshl_add_u64 v[88:89], v[122:123], 0, v[88:89]
	v_add_f32_e32 v93, 1.0, v93
	s_waitcnt vmcnt(0)
	v_pk_mul_f32 v[94:95], v[94:95], v[98:99]
	v_rcp_f32_e32 v98, v93
	v_and_b32_e32 v93, 0xffff0000, v143
	v_mul_f32_e32 v93, 0xbfb8aa3b, v93
	v_exp_f32_e32 v93, v93
	s_nop 0
	v_add_f32_e32 v93, 1.0, v93
	v_rcp_f32_e32 v99, v93
	s_nop 0
	v_pk_mul_f32 v[90:91], v[98:99], v[90:91]
	s_nop 0
	v_pk_mul_f32 v[90:91], v[90:91], v[92:93] op_sel_hi:[1,0]
	v_cvt_pk_bf16_f32 v92, v94, v95
	v_pk_mul_f32 v[90:91], v[96:97], v[90:91]
	v_add_u32_e32 v94, s1, v192
	v_cvt_pk_bf16_f32 v93, v90, v91
	global_store_dwordx2 v[88:89], v[92:93], off
	ds_read2st64_b64 v[88:91], v94 offset1:1
	v_lshlrev_b32_e32 v97, 16, v140
	v_mul_f32_e32 v97, 0xbfb8aa3b, v97
	v_exp_f32_e32 v97, v97
	s_waitcnt lgkmcnt(0)
	v_pk_add_f32 v[88:89], v[88:89], 0 op_sel_hi:[1,0]
	s_nop 0
	v_pk_add_f32 v[92:93], v[88:89], v[90:91]
	ds_read2st64_b64 v[88:91], v94 offset0:2 offset1:3
	v_add_f32_e32 v97, 1.0, v97
	v_rcp_f32_e32 v98, v97
	v_and_b32_e32 v97, 0xffff0000, v140
	v_mul_f32_e32 v97, 0xbfb8aa3b, v97
	s_waitcnt lgkmcnt(0)
	v_pk_add_f32 v[88:89], v[92:93], v[88:89]
	v_exp_f32_e32 v97, v97
	v_pk_add_f32 v[92:93], v[88:89], v[90:91]
	ds_read2st64_b64 v[88:91], v94 offset0:4 offset1:5
	v_add_f32_e32 v97, 1.0, v97
	v_rcp_f32_e32 v99, v97
	s_waitcnt lgkmcnt(0)
	v_pk_add_f32 v[88:89], v[92:93], v[88:89]
	s_nop 0
	v_pk_add_f32 v[92:93], v[88:89], v[90:91]
	ds_read2st64_b64 v[88:91], v94 offset0:6 offset1:7
	s_waitcnt lgkmcnt(0)
	v_pk_add_f32 v[88:89], v[92:93], v[88:89]
	s_nop 0
	v_pk_add_f32 v[88:89], v[88:89], v[90:91]
	global_load_dwordx4 v[90:93], v[126:127], off
	v_pk_mul_f32 v[94:95], v[88:89], s[48:49] op_sel_hi:[1,0]
	s_nop 0
	v_fma_f32 v88, -v94, v94, v95
	v_max_f32_e32 v88, 0, v88
	v_add_f32_e32 v88, 0x358637bd, v88
	v_cmp_gt_f32_e32 vcc, s19, v88
	v_mul_f32_e32 v89, 0x4b800000, v88
	v_pk_add_f32 v[100:101], v[150:151], v[94:95] op_sel_hi:[1,0] neg_lo:[0,1] neg_hi:[0,1]
	v_cndmask_b32_e32 v88, v88, v89, vcc
	v_rsq_f32_e32 v88, v88
	v_pk_mul_f32 v[98:99], v[98:99], v[100:101]
	v_pk_add_f32 v[94:95], v[148:149], v[94:95] op_sel_hi:[1,0] neg_lo:[0,1] neg_hi:[0,1]
	v_mul_f32_e32 v89, 0x45800000, v88
	v_cndmask_b32_e32 v96, v88, v89, vcc
	v_pk_mul_f32 v[98:99], v[98:99], v[96:97] op_sel_hi:[1,0]
	v_lshlrev_b32_e32 v97, 16, v141
	v_mul_f32_e32 v97, 0xbfb8aa3b, v97
	v_exp_f32_e32 v97, v97
	v_or_b32_e32 v88, s0, v188
	v_ashrrev_i32_e32 v89, 31, v88
	v_lshlrev_b64 v[88:89], 10, v[88:89]
	v_add_f32_e32 v97, 1.0, v97
	v_lshl_add_u64 v[88:89], v[122:123], 0, v[88:89]
	s_waitcnt vmcnt(0) lgkmcnt(0)
	v_pk_mul_f32 v[90:91], v[90:91], v[98:99]
	v_rcp_f32_e32 v98, v97
	v_and_b32_e32 v97, 0xffff0000, v141
	v_mul_f32_e32 v97, 0xbfb8aa3b, v97
	v_exp_f32_e32 v97, v97
	v_cvt_pk_bf16_f32 v90, v90, v91
	v_add_f32_e32 v97, 1.0, v97
	v_rcp_f32_e32 v99, v97
	s_nop 0
	v_pk_mul_f32 v[94:95], v[98:99], v[94:95]
	s_nop 0
	v_pk_mul_f32 v[94:95], v[94:95], v[96:97] op_sel_hi:[1,0]
	v_lshlrev_b32_e32 v97, 16, v138
	v_pk_mul_f32 v[92:93], v[92:93], v[94:95]
	v_add_u32_e32 v94, s1, v193
	v_cvt_pk_bf16_f32 v91, v92, v93
	global_store_dwordx2 v[88:89], v[90:91], off
	ds_read2st64_b64 v[88:91], v94 offset1:1
	v_mul_f32_e32 v97, 0xbfb8aa3b, v97
	v_exp_f32_e32 v97, v97
	s_waitcnt lgkmcnt(0)
	v_pk_add_f32 v[88:89], v[88:89], 0 op_sel_hi:[1,0]
	s_nop 0
	v_pk_add_f32 v[92:93], v[88:89], v[90:91]
	ds_read2st64_b64 v[88:91], v94 offset0:2 offset1:3
	v_add_f32_e32 v97, 1.0, v97
	v_rcp_f32_e32 v98, v97
	v_and_b32_e32 v97, 0xffff0000, v138
	v_mul_f32_e32 v97, 0xbfb8aa3b, v97
	s_waitcnt lgkmcnt(0)
	v_pk_add_f32 v[88:89], v[92:93], v[88:89]
	v_exp_f32_e32 v97, v97
	v_pk_add_f32 v[92:93], v[88:89], v[90:91]
	ds_read2st64_b64 v[88:91], v94 offset0:4 offset1:5
	v_add_f32_e32 v97, 1.0, v97
	v_rcp_f32_e32 v99, v97
	s_waitcnt lgkmcnt(0)
	v_pk_add_f32 v[88:89], v[92:93], v[88:89]
	s_nop 0
	v_pk_add_f32 v[92:93], v[88:89], v[90:91]
	ds_read2st64_b64 v[88:91], v94 offset0:6 offset1:7
	s_waitcnt lgkmcnt(0)
	v_pk_add_f32 v[88:89], v[92:93], v[88:89]
	s_nop 0
	v_pk_add_f32 v[88:89], v[88:89], v[90:91]
	global_load_dwordx4 v[90:93], v[126:127], off
	v_pk_mul_f32 v[94:95], v[88:89], s[48:49] op_sel_hi:[1,0]
	s_nop 0
	v_fma_f32 v88, -v94, v94, v95
	v_max_f32_e32 v88, 0, v88
	v_add_f32_e32 v88, 0x358637bd, v88
	v_cmp_gt_f32_e32 vcc, s19, v88
	v_mul_f32_e32 v89, 0x4b800000, v88
	v_pk_add_f32 v[100:101], v[146:147], v[94:95] op_sel_hi:[1,0] neg_lo:[0,1] neg_hi:[0,1]
	v_cndmask_b32_e32 v88, v88, v89, vcc
	v_rsq_f32_e32 v88, v88
	v_pk_mul_f32 v[98:99], v[98:99], v[100:101]
	v_pk_add_f32 v[94:95], v[144:145], v[94:95] op_sel_hi:[1,0] neg_lo:[0,1] neg_hi:[0,1]
	v_mul_f32_e32 v89, 0x45800000, v88
	v_cndmask_b32_e32 v96, v88, v89, vcc
	v_pk_mul_f32 v[98:99], v[98:99], v[96:97] op_sel_hi:[1,0]
	v_lshlrev_b32_e32 v97, 16, v139
	v_mul_f32_e32 v97, 0xbfb8aa3b, v97
	v_exp_f32_e32 v97, v97
	v_or_b32_e32 v88, s0, v189
	v_ashrrev_i32_e32 v89, 31, v88
	v_lshlrev_b64 v[88:89], 10, v[88:89]
	v_add_f32_e32 v97, 1.0, v97
	v_lshl_add_u64 v[88:89], v[122:123], 0, v[88:89]
	s_waitcnt vmcnt(0) lgkmcnt(0)
	v_pk_mul_f32 v[90:91], v[90:91], v[98:99]
	v_rcp_f32_e32 v98, v97
	v_and_b32_e32 v97, 0xffff0000, v139
	v_mul_f32_e32 v97, 0xbfb8aa3b, v97
	v_exp_f32_e32 v97, v97
	v_cvt_pk_bf16_f32 v90, v90, v91
	v_add_f32_e32 v97, 1.0, v97
	v_rcp_f32_e32 v99, v97
	s_nop 0
	v_pk_mul_f32 v[94:95], v[98:99], v[94:95]
	s_nop 0
	v_pk_mul_f32 v[94:95], v[94:95], v[96:97] op_sel_hi:[1,0]
	v_or_b32_e32 v96, s0, v190
	v_pk_mul_f32 v[92:93], v[92:93], v[94:95]
	v_add_u32_e32 v94, s1, v194
	v_cvt_pk_bf16_f32 v91, v92, v93
	global_store_dwordx2 v[88:89], v[90:91], off
	ds_read2st64_b64 v[88:91], v94 offset1:1
	v_lshlrev_b32_e32 v95, 16, v128
	v_mul_f32_e32 v95, 0xbfb8aa3b, v95
	v_exp_f32_e32 v95, v95
	v_ashrrev_i32_e32 v97, 31, v96
	s_waitcnt lgkmcnt(0)
	v_pk_add_f32 v[88:89], v[88:89], 0 op_sel_hi:[1,0]
	v_add_f32_e32 v95, 1.0, v95
	v_pk_add_f32 v[92:93], v[88:89], v[90:91]
	ds_read2st64_b64 v[88:91], v94 offset0:2 offset1:3
	v_rcp_f32_e32 v98, v95
	v_and_b32_e32 v95, 0xffff0000, v128
	v_mul_f32_e32 v95, 0xbfb8aa3b, v95
	v_exp_f32_e32 v95, v95
	s_waitcnt lgkmcnt(0)
	v_pk_add_f32 v[88:89], v[92:93], v[88:89]
	v_add_f32_e32 v95, 1.0, v95
	v_pk_add_f32 v[92:93], v[88:89], v[90:91]
	ds_read2st64_b64 v[88:91], v94 offset0:4 offset1:5
	v_rcp_f32_e32 v99, v95
	s_waitcnt lgkmcnt(0)
	v_pk_add_f32 v[88:89], v[92:93], v[88:89]
	s_nop 0
	v_pk_add_f32 v[92:93], v[88:89], v[90:91]
	ds_read2st64_b64 v[88:91], v94 offset0:6 offset1:7
	s_waitcnt lgkmcnt(0)
	v_pk_add_f32 v[88:89], v[92:93], v[88:89]
	s_nop 0
	v_pk_add_f32 v[88:89], v[88:89], v[90:91]
	s_nop 0
	v_pk_mul_f32 v[92:93], v[88:89], s[48:49] op_sel_hi:[1,0]
	s_nop 0
	v_fma_f32 v88, -v92, v92, v93
	v_max_f32_e32 v88, 0, v88
	v_add_f32_e32 v88, 0x358637bd, v88
	v_cmp_gt_f32_e32 vcc, s19, v88
	v_mul_f32_e32 v89, 0x4b800000, v88
	v_pk_add_f32 v[86:87], v[86:87], v[92:93] op_sel_hi:[1,0] neg_lo:[0,1] neg_hi:[0,1]
	v_cndmask_b32_e32 v88, v88, v89, vcc
	v_rsq_f32_e32 v88, v88
	v_pk_mul_f32 v[86:87], v[98:99], v[86:87]
	v_pk_add_f32 v[84:85], v[84:85], v[92:93] op_sel_hi:[1,0] neg_lo:[0,1] neg_hi:[0,1]
	v_pk_mul_f32 v[92:93], v[52:53], s[18:19] op_sel_hi:[1,0]
	v_mul_f32_e32 v89, 0x45800000, v88
	v_cndmask_b32_e32 v94, v88, v89, vcc
	global_load_dwordx4 v[88:91], v[126:127], off
	v_pk_mul_f32 v[86:87], v[86:87], v[94:95] op_sel_hi:[1,0]
	s_waitcnt vmcnt(0) lgkmcnt(0)
	v_pk_mul_f32 v[86:87], v[88:89], v[86:87]
	v_lshlrev_b32_e32 v88, 16, v129
	v_and_b32_e32 v89, 0xffff0000, v129
	v_mul_f32_e32 v88, 0xbfb8aa3b, v88
	v_mul_f32_e32 v89, 0xbfb8aa3b, v89
	v_exp_f32_e32 v88, v88
	v_exp_f32_e32 v89, v89
	v_cvt_pk_bf16_f32 v86, v86, v87
	v_add_f32_e32 v88, 1.0, v88
	v_add_f32_e32 v89, 1.0, v89
	v_rcp_f32_e32 v88, v88
	v_rcp_f32_e32 v89, v89
	s_nop 0
	v_pk_mul_f32 v[84:85], v[88:89], v[84:85]
	s_nop 0
	v_pk_mul_f32 v[84:85], v[84:85], v[94:95] op_sel_hi:[1,0]
	v_pk_mul_f32 v[88:89], v[56:57], s[18:19] op_sel_hi:[1,0]
	v_pk_mul_f32 v[84:85], v[90:91], v[84:85]
	v_pk_mul_f32 v[90:91], v[58:59], s[18:19] op_sel_hi:[1,0]
	v_cvt_pk_bf16_f32 v87, v84, v85
	v_lshlrev_b64 v[84:85], 10, v[96:97]
	v_lshl_add_u64 v[84:85], v[122:123], 0, v[84:85]
	global_store_dwordx2 v[84:85], v[86:87], off
	v_add_u32_e32 v96, v181, v160
	v_pk_mul_f32 v[86:87], v[62:63], s[18:19] op_sel_hi:[1,0]
	v_pk_mul_f32 v[84:85], v[60:61], s[18:19] op_sel_hi:[1,0]
	v_pk_mul_f32 v[94:95], v[54:55], s[18:19] op_sel_hi:[1,0]
	ds_read_b128 v[52:55], v125 offset:1024
	ds_read_b128 v[56:59], v125 offset:1040
	ds_read_b128 v[60:63], v96 offset:53248
	s_waitcnt lgkmcnt(0)
	v_cvt_pk_bf16_f32 v97, v52, v53
	v_cvt_pk_bf16_f32 v102, v54, v55
	v_lshlrev_b32_e32 v98, 16, v60
	v_and_b32_e32 v99, 0xffff0000, v60
	v_lshlrev_b32_e32 v60, 16, v61
	v_and_b32_e32 v61, 0xffff0000, v61
	v_pk_mul_f32 v[98:99], v[52:53], v[98:99]
	v_pk_mul_f32 v[60:61], v[54:55], v[60:61]
	v_cvt_pk_bf16_f32 v98, v98, v99
	v_cvt_pk_bf16_f32 v99, v60, v61
	v_lshlrev_b32_e32 v60, 16, v62
	v_and_b32_e32 v61, 0xffff0000, v62
	v_pk_mul_f32 v[60:61], v[56:57], v[60:61]
	v_cvt_pk_bf16_f32 v103, v56, v57
	v_cvt_pk_bf16_f32 v100, v60, v61
	v_lshlrev_b32_e32 v60, 16, v63
	v_and_b32_e32 v61, 0xffff0000, v63
	v_pk_mul_f32 v[60:61], v[58:59], v[60:61]
	v_cvt_pk_bf16_f32 v104, v58, v59
	v_cvt_pk_bf16_f32 v101, v60, v61
	ds_read_b128 v[52:55], v201 offset:34816
	ds_read_b128 v[56:59], v201 offset:39424
	s_waitcnt lgkmcnt(0)
	v_mfma_f32_16x16x32_bf16 v[56:59], v[98:101], v[56:59], v[72:75]
	ds_read_b128 v[60:63], v201 offset:41728
	s_nop 1
	ds_read_b128 v[72:75], v96 offset:34816
	v_mfma_f32_16x16x32_bf16 v[48:51], v[98:101], v[52:55], v[48:51]
	ds_read_b128 v[52:55], v201 offset:37120
	s_waitcnt lgkmcnt(0)
	v_mfma_f32_16x16x32_bf16 v[60:63], v[98:101], v[60:63], v[68:71]
	s_nop 2
	ds_read_b128 v[68:71], v201 offset:44032
	s_waitcnt lgkmcnt(0)
	v_mfma_f32_16x16x32_bf16 v[64:67], v[98:101], v[68:71], v[64:67]
	ds_read_b128 v[68:71], v201 offset:46336
	s_waitcnt lgkmcnt(0)
	v_mfma_f32_16x16x32_bf16 v[84:87], v[98:101], v[68:71], v[84:87]
	ds_read_b128 v[68:71], v201 offset:48640
	s_waitcnt lgkmcnt(0)
	v_mfma_f32_16x16x32_bf16 v[88:91], v[98:101], v[68:71], v[88:91]
	ds_read_b128 v[68:71], v201 offset:50944
	s_waitcnt lgkmcnt(0)
	v_mfma_f32_16x16x32_bf16 v[92:95], v[98:101], v[68:71], v[92:95]
	v_cndmask_b32_e64 v71, 0, v104, s[6:7]
	v_cndmask_b32_e64 v70, 0, v103, s[6:7]
	v_cndmask_b32_e64 v69, 0, v102, s[6:7]
	v_cndmask_b32_e64 v68, 0, v97, s[6:7]
	v_mfma_f32_16x16x32_bf16 v[52:55], v[98:101], v[52:55], v[76:79]
	s_nop 0
	v_mfma_f32_16x16x32_bf16 v[80:83], v[68:71], v[72:75], v[80:83]
	ds_read_b128 v[68:71], v125 offset:1152
	ds_read_b128 v[72:75], v125 offset:1168
	ds_read_b128 v[76:79], v96 offset:53312
	s_waitcnt lgkmcnt(0)
	v_cvt_pk_bf16_f32 v97, v68, v69
	v_cvt_pk_bf16_f32 v102, v70, v71
	v_lshlrev_b32_e32 v98, 16, v76
	v_and_b32_e32 v99, 0xffff0000, v76
	v_lshlrev_b32_e32 v76, 16, v77
	v_and_b32_e32 v77, 0xffff0000, v77
	v_pk_mul_f32 v[98:99], v[68:69], v[98:99]
	v_pk_mul_f32 v[76:77], v[70:71], v[76:77]
	v_cvt_pk_bf16_f32 v98, v98, v99
	v_cvt_pk_bf16_f32 v99, v76, v77
	v_lshlrev_b32_e32 v76, 16, v78
	v_and_b32_e32 v77, 0xffff0000, v78
	v_pk_mul_f32 v[76:77], v[72:73], v[76:77]
	ds_read_b128 v[68:71], v201 offset:34880
	v_cvt_pk_bf16_f32 v100, v76, v77
	v_lshlrev_b32_e32 v76, 16, v79
	v_and_b32_e32 v77, 0xffff0000, v79
	v_pk_mul_f32 v[76:77], v[74:75], v[76:77]
	v_cvt_pk_bf16_f32 v103, v72, v73
	v_cvt_pk_bf16_f32 v101, v76, v77
	v_cvt_pk_bf16_f32 v104, v74, v75
	s_waitcnt lgkmcnt(0)
	v_mfma_f32_16x16x32_bf16 v[48:51], v[98:101], v[68:71], v[48:51]
	ds_read_b128 v[68:71], v201 offset:37184
	s_waitcnt lgkmcnt(0)
	v_mfma_f32_16x16x32_bf16 v[76:79], v[98:101], v[68:71], v[52:55]
	s_nop 2
	ds_read_b128 v[52:55], v201 offset:39488
	s_waitcnt lgkmcnt(0)
	v_mfma_f32_16x16x32_bf16 v[72:75], v[98:101], v[52:55], v[56:59]
	ds_read_b128 v[52:55], v201 offset:41792
	s_waitcnt lgkmcnt(0)
	v_mfma_f32_16x16x32_bf16 v[68:71], v[98:101], v[52:55], v[60:63]
	ds_read_b128 v[52:55], v201 offset:44096
	s_waitcnt lgkmcnt(0)
	v_mfma_f32_16x16x32_bf16 v[64:67], v[98:101], v[52:55], v[64:67]
	ds_read_b128 v[52:55], v201 offset:46400
	s_waitcnt lgkmcnt(0)
	v_mfma_f32_16x16x32_bf16 v[60:63], v[98:101], v[52:55], v[84:87]
	ds_read_b128 v[52:55], v201 offset:48704
	s_nop 1
	v_cndmask_b32_e64 v87, 0, v104, s[6:7]
	v_cndmask_b32_e64 v86, 0, v103, s[6:7]
	s_waitcnt lgkmcnt(0)
	v_mfma_f32_16x16x32_bf16 v[56:59], v[98:101], v[52:55], v[88:91]
	ds_read_b128 v[52:55], v201 offset:51008
	s_nop 1
	ds_read_b128 v[88:91], v96 offset:34880
	v_cndmask_b32_e64 v85, 0, v102, s[6:7]
	s_waitcnt lgkmcnt(0)
	v_mfma_f32_16x16x32_bf16 v[52:55], v[98:101], v[52:55], v[92:95]
	v_cndmask_b32_e64 v84, 0, v97, s[6:7]
	s_nop 1
	v_cvt_pk_bf16_f32 v92, v48, s0
	ds_write_b16 v202, v92
	v_cvt_pk_bf16_f32 v92, v49, s0
	ds_write_b16 v202, v92 offset:272
	v_cvt_pk_bf16_f32 v92, v50, s0
	ds_write_b16 v202, v92 offset:544
	v_cvt_pk_bf16_f32 v92, v51, s0
	ds_write_b16 v202, v92 offset:816
	v_cvt_pk_bf16_f32 v92, v76, s0
	ds_write_b16 v202, v92 offset:32
	v_cvt_pk_bf16_f32 v92, v77, s0
	ds_write_b16 v202, v92 offset:304
	v_cvt_pk_bf16_f32 v92, v78, s0
	ds_write_b16 v202, v92 offset:576
	v_cvt_pk_bf16_f32 v92, v79, s0
	ds_write_b16 v202, v92 offset:848
	v_cvt_pk_bf16_f32 v92, v72, s0
	ds_write_b16 v202, v92 offset:64
	v_cvt_pk_bf16_f32 v92, v73, s0
	ds_write_b16 v202, v92 offset:336
	v_cvt_pk_bf16_f32 v92, v74, s0
	ds_write_b16 v202, v92 offset:608
	v_cvt_pk_bf16_f32 v92, v75, s0
	ds_write_b16 v202, v92 offset:880
	v_cvt_pk_bf16_f32 v92, v68, s0
	ds_write_b16 v202, v92 offset:96
	v_cvt_pk_bf16_f32 v92, v69, s0
	ds_write_b16 v202, v92 offset:368
	v_cvt_pk_bf16_f32 v92, v70, s0
	ds_write_b16 v202, v92 offset:640
	v_cvt_pk_bf16_f32 v92, v71, s0
	ds_write_b16 v202, v92 offset:912
	v_cvt_pk_bf16_f32 v92, v64, s0
	ds_write_b16 v202, v92 offset:128
	v_cvt_pk_bf16_f32 v92, v65, s0
	ds_write_b16 v202, v92 offset:400
	v_cvt_pk_bf16_f32 v92, v66, s0
	ds_write_b16 v202, v92 offset:672
	v_cvt_pk_bf16_f32 v92, v67, s0
	ds_write_b16 v202, v92 offset:944
	v_cvt_pk_bf16_f32 v92, v60, s0
	ds_write_b16 v202, v92 offset:160
	v_cvt_pk_bf16_f32 v92, v61, s0
	ds_write_b16 v202, v92 offset:432
	v_cvt_pk_bf16_f32 v92, v62, s0
	ds_write_b16 v202, v92 offset:704
	v_cvt_pk_bf16_f32 v92, v63, s0
	ds_write_b16 v202, v92 offset:976
	v_cvt_pk_bf16_f32 v92, v56, s0
	ds_write_b16 v202, v92 offset:192
	v_cvt_pk_bf16_f32 v92, v57, s0
	ds_write_b16 v202, v92 offset:464
	v_cvt_pk_bf16_f32 v92, v58, s0
	ds_write_b16 v202, v92 offset:736
	v_cvt_pk_bf16_f32 v92, v59, s0
	ds_write_b16 v202, v92 offset:1008
	v_cvt_pk_bf16_f32 v92, v52, s0
	v_mfma_f32_16x16x32_bf16 v[80:83], v[84:87], v[88:91], v[80:83]
	ds_write_b16 v202, v92 offset:224
	v_cvt_pk_bf16_f32 v92, v53, s0
	ds_write_b16 v202, v92 offset:496
	v_cvt_pk_bf16_f32 v92, v54, s0
	ds_write_b16 v202, v92 offset:768
	v_cvt_pk_bf16_f32 v92, v55, s0
	ds_write_b16 v202, v92 offset:1040
	s_and_saveexec_b64 s[0:1], s[4:5]
	s_cbranch_execz .LBB0_351
	v_cvt_pk_bf16_f32 v84, v80, v81
	ds_write_b16 v182, v84 offset:34816
	s_branch .LBB0_351

.LBB0_381:
	v_lshl_add_u64 v[20:21], v[16:17], 0, v[160:161]
	v_add_co_u32_e32 v20, vcc, s6, v20
	v_lshl_add_u64 v[42:43], v[18:19], 0, v[160:161]
	s_nop 0
	v_addc_co_u32_e32 v21, vcc, 0, v21, vcc
	v_add_co_u32_e32 v22, vcc, s10, v42
	global_load_dwordx4 v[34:37], v[20:21], off
	s_nop 0
	v_addc_co_u32_e32 v23, vcc, 0, v43, vcc
	global_load_dwordx4 v[24:27], v[22:23], off
	s_add_i32 s2, s2, -8
	v_lshl_add_u64 v[16:17], v[16:17], 0, s[12:13]
	v_lshl_add_u64 v[18:19], v[18:19], 0, s[14:15]
	s_cmp_eq_u32 s2, 0
	s_waitcnt vmcnt(0) lgkmcnt(0)
	v_mfma_f32_16x16x32_bf16 v[12:15], v[24:27], v[34:37], v[12:15]
	v_add_co_u32_e32 v24, vcc, s7, v42
	s_nop 1
	v_addc_co_u32_e32 v25, vcc, 0, v43, vcc
	global_load_dwordx4 v[26:29], v[24:25], off
	s_waitcnt vmcnt(0) lgkmcnt(0)
	v_mfma_f32_16x16x32_bf16 v[8:11], v[26:29], v[34:37], v[8:11]
	v_add_co_u32_e32 v26, vcc, s8, v42
	s_nop 1
	v_addc_co_u32_e32 v27, vcc, 0, v43, vcc
	global_load_dwordx4 v[38:41], v[26:27], off
	v_add_co_u32_e32 v28, vcc, s9, v42
	s_waitcnt vmcnt(0) lgkmcnt(0)
	v_mfma_f32_16x16x32_bf16 v[4:7], v[38:41], v[34:37], v[4:7]
	v_addc_co_u32_e32 v29, vcc, 0, v43, vcc
	global_load_dwordx4 v[38:41], v[28:29], off
	s_waitcnt vmcnt(0) lgkmcnt(0)
	v_mfma_f32_16x16x32_bf16 v[0:3], v[38:41], v[34:37], v[0:3]
	global_load_dwordx4 v[34:37], v[20:21], off offset:64
	global_load_dwordx4 v[38:41], v[22:23], off offset:64
	s_waitcnt vmcnt(0) lgkmcnt(0)
	v_mfma_f32_16x16x32_bf16 v[12:15], v[38:41], v[34:37], v[12:15]
	global_load_dwordx4 v[38:41], v[24:25], off offset:64
	s_waitcnt vmcnt(0) lgkmcnt(0)
	v_mfma_f32_16x16x32_bf16 v[8:11], v[38:41], v[34:37], v[8:11]
	global_load_dwordx4 v[38:41], v[26:27], off offset:64
	s_waitcnt vmcnt(0) lgkmcnt(0)
	v_mfma_f32_16x16x32_bf16 v[4:7], v[38:41], v[34:37], v[4:7]
	global_load_dwordx4 v[38:41], v[28:29], off offset:64
	s_waitcnt vmcnt(0) lgkmcnt(0)
	v_mfma_f32_16x16x32_bf16 v[0:3], v[38:41], v[34:37], v[0:3]
	global_load_dwordx4 v[34:37], v[20:21], off offset:256
	global_load_dwordx4 v[38:41], v[22:23], off offset:128
	s_waitcnt vmcnt(0) lgkmcnt(0)
	v_mfma_f32_16x16x32_bf16 v[12:15], v[38:41], v[34:37], v[12:15]
	global_load_dwordx4 v[38:41], v[24:25], off offset:128
	s_waitcnt vmcnt(0) lgkmcnt(0)
	v_mfma_f32_16x16x32_bf16 v[8:11], v[38:41], v[34:37], v[8:11]
	global_load_dwordx4 v[38:41], v[26:27], off offset:128
	s_waitcnt vmcnt(0) lgkmcnt(0)
	v_mfma_f32_16x16x32_bf16 v[4:7], v[38:41], v[34:37], v[4:7]
	global_load_dwordx4 v[38:41], v[28:29], off offset:128
	s_waitcnt vmcnt(0) lgkmcnt(0)
	v_mfma_f32_16x16x32_bf16 v[0:3], v[38:41], v[34:37], v[0:3]
	global_load_dwordx4 v[34:37], v[20:21], off offset:320
	global_load_dwordx4 v[38:41], v[22:23], off offset:192
	s_waitcnt vmcnt(0) lgkmcnt(0)
	v_mfma_f32_16x16x32_bf16 v[12:15], v[38:41], v[34:37], v[12:15]
	global_load_dwordx4 v[38:41], v[24:25], off offset:192
	s_waitcnt vmcnt(0) lgkmcnt(0)
	v_mfma_f32_16x16x32_bf16 v[8:11], v[38:41], v[34:37], v[8:11]
	global_load_dwordx4 v[38:41], v[26:27], off offset:192
	s_waitcnt vmcnt(0) lgkmcnt(0)
	v_mfma_f32_16x16x32_bf16 v[4:7], v[38:41], v[34:37], v[4:7]
	global_load_dwordx4 v[38:41], v[28:29], off offset:192
	s_waitcnt vmcnt(0) lgkmcnt(0)
	v_mfma_f32_16x16x32_bf16 v[0:3], v[38:41], v[34:37], v[0:3]
	global_load_dwordx4 v[34:37], v[20:21], off offset:512
	global_load_dwordx4 v[38:41], v[22:23], off offset:256
	s_waitcnt vmcnt(0) lgkmcnt(0)
	v_mfma_f32_16x16x32_bf16 v[12:15], v[38:41], v[34:37], v[12:15]
	global_load_dwordx4 v[38:41], v[24:25], off offset:256
	s_waitcnt vmcnt(0) lgkmcnt(0)
	v_mfma_f32_16x16x32_bf16 v[8:11], v[38:41], v[34:37], v[8:11]
	global_load_dwordx4 v[38:41], v[26:27], off offset:256
	s_waitcnt vmcnt(0) lgkmcnt(0)
	v_mfma_f32_16x16x32_bf16 v[4:7], v[38:41], v[34:37], v[4:7]
	global_load_dwordx4 v[38:41], v[28:29], off offset:256
	s_waitcnt vmcnt(0) lgkmcnt(0)
	v_mfma_f32_16x16x32_bf16 v[0:3], v[38:41], v[34:37], v[0:3]
	global_load_dwordx4 v[34:37], v[20:21], off offset:576
	global_load_dwordx4 v[38:41], v[22:23], off offset:320
	s_waitcnt vmcnt(0) lgkmcnt(0)
	v_mfma_f32_16x16x32_bf16 v[12:15], v[38:41], v[34:37], v[12:15]
	global_load_dwordx4 v[38:41], v[24:25], off offset:320
	s_waitcnt vmcnt(0) lgkmcnt(0)
	v_mfma_f32_16x16x32_bf16 v[8:11], v[38:41], v[34:37], v[8:11]
	global_load_dwordx4 v[38:41], v[26:27], off offset:320
	s_waitcnt vmcnt(0) lgkmcnt(0)
	v_mfma_f32_16x16x32_bf16 v[4:7], v[38:41], v[34:37], v[4:7]
	global_load_dwordx4 v[38:41], v[28:29], off offset:320
	s_waitcnt vmcnt(0) lgkmcnt(0)
	v_mfma_f32_16x16x32_bf16 v[0:3], v[38:41], v[34:37], v[0:3]
	global_load_dwordx4 v[34:37], v[20:21], off offset:768
	global_load_dwordx4 v[38:41], v[22:23], off offset:384
	s_waitcnt vmcnt(0) lgkmcnt(0)
	v_mfma_f32_16x16x32_bf16 v[12:15], v[38:41], v[34:37], v[12:15]
	global_load_dwordx4 v[38:41], v[24:25], off offset:384
	s_waitcnt vmcnt(0) lgkmcnt(0)
	v_mfma_f32_16x16x32_bf16 v[8:11], v[38:41], v[34:37], v[8:11]
	global_load_dwordx4 v[38:41], v[26:27], off offset:384
	s_waitcnt vmcnt(0) lgkmcnt(0)
	v_mfma_f32_16x16x32_bf16 v[4:7], v[38:41], v[34:37], v[4:7]
	global_load_dwordx4 v[38:41], v[28:29], off offset:384
	s_waitcnt vmcnt(0) lgkmcnt(0)
	v_mfma_f32_16x16x32_bf16 v[0:3], v[38:41], v[34:37], v[0:3]
	global_load_dwordx4 v[34:37], v[20:21], off offset:832
	s_nop 0
	global_load_dwordx4 v[20:23], v[22:23], off offset:448
	s_waitcnt vmcnt(0) lgkmcnt(0)
	v_mfma_f32_16x16x32_bf16 v[12:15], v[20:23], v[34:37], v[12:15]
	global_load_dwordx4 v[20:23], v[24:25], off offset:448
	s_waitcnt vmcnt(0) lgkmcnt(0)
	v_mfma_f32_16x16x32_bf16 v[8:11], v[20:23], v[34:37], v[8:11]
	global_load_dwordx4 v[20:23], v[26:27], off offset:448
	s_waitcnt vmcnt(0) lgkmcnt(0)
	v_mfma_f32_16x16x32_bf16 v[4:7], v[20:23], v[34:37], v[4:7]
	global_load_dwordx4 v[20:23], v[28:29], off offset:448
	s_waitcnt vmcnt(0) lgkmcnt(0)
	v_mfma_f32_16x16x32_bf16 v[0:3], v[20:23], v[34:37], v[0:3]
	s_cbranch_scc0 .LBB0_381
	v_readlane_b32 s2, v252, 27
	s_add_u32 s2, s0, s2
	v_readlane_b32 s6, v252, 28
	s_addc_u32 s7, s1, s6
	v_readlane_b32 s6, v252, 31
	s_lshl_b32 s6, s6, 7
	v_readlane_b32 s8, v253, 49
	s_or_b32 s8, s6, s8
	v_readlane_b32 s6, v253, 48
	s_add_u32 s6, s2, s6
	s_addc_u32 s7, s7, 0
	s_ashr_i32 s9, s8, 31
	s_lshl_b64 s[8:9], s[8:9], 2
	v_and_b32_e32 v22, 3, v32
	s_add_u32 s8, s0, s8
	s_addc_u32 s9, s1, s9
	v_lshlrev_b32_e32 v160, 4, v22
	v_lshl_add_u64 v[18:19], s[8:9], 0, v[160:161]
	s_mov_b64 s[8:9], 0x300000
	s_mov_b32 s2, 0x300000
	v_lshl_add_u64 v[16:17], v[18:19], 0, s[8:9]
	v_add_co_u32_e32 v18, vcc, s2, v18
	v_readlane_b32 s8, v253, 51
	s_nop 0
	v_addc_co_u32_e32 v19, vcc, 0, v19, vcc
	global_load_dwordx4 v[18:21], v[18:19], off
	v_readlane_b32 s9, v253, 52
	s_add_u32 s0, s0, s8
	s_addc_u32 s1, s1, s9
	v_lshlrev_b32_e32 v160, 1, v30
	s_mov_b64 s[8:9], 0x600000
	v_lshlrev_b32_e32 v28, 9, v22
	s_waitcnt vmcnt(0) lgkmcnt(0)
	v_pk_add_f32 v[12:13], v[12:13], v[18:19]
	s_nop 0
	v_mul_f32_e32 v18, v12, v12
	v_mul_f32_e32 v19, v13, v13
	v_fmamk_f32 v18, v18, 0xbdd2d3e8, v209
	v_fmamk_f32 v19, v19, 0xbdd2d3e8, v209
	v_mul_f32_e32 v18, v12, v18
	v_mul_f32_e32 v19, v13, v19
	v_exp_f32_e32 v18, v18
	v_exp_f32_e32 v19, v19
	v_pk_add_f32 v[14:15], v[14:15], v[20:21]
	v_add_f32_e32 v18, 1.0, v18
	v_add_f32_e32 v19, 1.0, v19
	v_rcp_f32_e32 v18, v18
	v_rcp_f32_e32 v19, v19
	s_nop 0
	v_pk_mul_f32 v[24:25], v[12:13], v[18:19]
	v_mul_f32_e32 v12, v14, v14
	v_mul_f32_e32 v13, v15, v15
	v_fmamk_f32 v12, v12, 0xbdd2d3e8, v209
	v_fmamk_f32 v13, v13, 0xbdd2d3e8, v209
	v_mul_f32_e32 v12, v14, v12
	v_mul_f32_e32 v13, v15, v13
	v_exp_f32_e32 v12, v12
	v_exp_f32_e32 v13, v13
	v_add_f32_e32 v12, 1.0, v12
	v_add_f32_e32 v13, 1.0, v13
	v_rcp_f32_e32 v12, v12
	v_rcp_f32_e32 v13, v13
	s_nop 0
	v_pk_mul_f32 v[26:27], v[14:15], v[12:13]
	global_load_dwordx4 v[12:15], v[16:17], off offset:64
	s_waitcnt vmcnt(0) lgkmcnt(0)
	v_pk_add_f32 v[8:9], v[8:9], v[12:13]
	s_nop 0
	v_mul_f32_e32 v12, v8, v8
	v_mul_f32_e32 v13, v9, v9
	v_fmamk_f32 v12, v12, 0xbdd2d3e8, v209
	v_fmamk_f32 v13, v13, 0xbdd2d3e8, v209
	v_mul_f32_e32 v12, v8, v12
	v_mul_f32_e32 v13, v9, v13
	v_exp_f32_e32 v12, v12
	v_exp_f32_e32 v13, v13
	v_pk_add_f32 v[10:11], v[10:11], v[14:15]
	v_add_f32_e32 v12, 1.0, v12
	v_add_f32_e32 v13, 1.0, v13
	v_rcp_f32_e32 v12, v12
	v_rcp_f32_e32 v13, v13
	s_nop 0
	v_pk_mul_f32 v[8:9], v[8:9], v[12:13]
	v_mul_f32_e32 v12, v10, v10
	v_mul_f32_e32 v13, v11, v11
	v_fmamk_f32 v12, v12, 0xbdd2d3e8, v209
	v_fmamk_f32 v13, v13, 0xbdd2d3e8, v209
	v_mul_f32_e32 v12, v10, v12
	v_mul_f32_e32 v13, v11, v13
	v_exp_f32_e32 v12, v12
	v_exp_f32_e32 v13, v13
	v_add_f32_e32 v12, 1.0, v12
	v_add_f32_e32 v13, 1.0, v13
	v_rcp_f32_e32 v12, v12
	v_rcp_f32_e32 v13, v13
	s_nop 0
	v_pk_mul_f32 v[10:11], v[10:11], v[12:13]
	global_load_dwordx4 v[12:15], v[16:17], off offset:128
	s_waitcnt vmcnt(0) lgkmcnt(0)
	v_pk_add_f32 v[4:5], v[4:5], v[12:13]
	s_nop 0
	v_mul_f32_e32 v12, v4, v4
	v_mul_f32_e32 v13, v5, v5
	v_fmamk_f32 v12, v12, 0xbdd2d3e8, v209
	v_fmamk_f32 v13, v13, 0xbdd2d3e8, v209
	v_mul_f32_e32 v12, v4, v12
	v_mul_f32_e32 v13, v5, v13
	v_exp_f32_e32 v12, v12
	v_exp_f32_e32 v13, v13
	v_pk_add_f32 v[6:7], v[6:7], v[14:15]
	v_add_f32_e32 v12, 1.0, v12
	v_add_f32_e32 v13, 1.0, v13
	v_rcp_f32_e32 v12, v12
	v_rcp_f32_e32 v13, v13
	s_nop 0
	v_pk_mul_f32 v[12:13], v[4:5], v[12:13]
	v_mul_f32_e32 v4, v6, v6
	v_mul_f32_e32 v5, v7, v7
	v_fmamk_f32 v4, v4, 0xbdd2d3e8, v209
	v_fmamk_f32 v5, v5, 0xbdd2d3e8, v209
	v_mul_f32_e32 v4, v6, v4
	v_mul_f32_e32 v5, v7, v5
	v_exp_f32_e32 v4, v4
	v_exp_f32_e32 v5, v5
	v_cvt_pk_bf16_f32 v12, v12, v13
	v_add_f32_e32 v4, 1.0, v4
	v_add_f32_e32 v5, 1.0, v5
	v_rcp_f32_e32 v4, v4
	v_rcp_f32_e32 v5, v5
	s_nop 0
	v_pk_mul_f32 v[14:15], v[6:7], v[4:5]
	global_load_dwordx4 v[4:7], v[16:17], off offset:192
	v_cvt_pk_bf16_f32 v13, v14, v15
	s_waitcnt vmcnt(0) lgkmcnt(0)
	v_pk_add_f32 v[0:1], v[0:1], v[4:5]
	s_nop 0
	v_mul_f32_e32 v4, v0, v0
	v_mul_f32_e32 v5, v1, v1
	v_fmamk_f32 v4, v4, 0xbdd2d3e8, v209
	v_fmamk_f32 v5, v5, 0xbdd2d3e8, v209
	v_mul_f32_e32 v4, v0, v4
	v_mul_f32_e32 v5, v1, v5
	v_exp_f32_e32 v4, v4
	v_exp_f32_e32 v5, v5
	v_pk_add_f32 v[2:3], v[2:3], v[6:7]
	v_add_f32_e32 v4, 1.0, v4
	v_add_f32_e32 v5, 1.0, v5
	v_rcp_f32_e32 v4, v4
	v_rcp_f32_e32 v5, v5
	s_nop 0
	v_pk_mul_f32 v[18:19], v[0:1], v[4:5]
	v_mul_f32_e32 v0, v2, v2
	v_mul_f32_e32 v1, v3, v3
	v_fmamk_f32 v0, v0, 0xbdd2d3e8, v209
	v_fmamk_f32 v1, v1, 0xbdd2d3e8, v209
	v_mul_f32_e32 v0, v2, v0
	v_mul_f32_e32 v1, v3, v1
	v_exp_f32_e32 v0, v0
	v_exp_f32_e32 v1, v1
	v_cvt_pk_bf16_f32 v14, v18, v19
	v_add_f32_e32 v0, 1.0, v0
	v_add_f32_e32 v1, 1.0, v1
	v_rcp_f32_e32 v0, v0
	v_rcp_f32_e32 v1, v1
	s_nop 0
	v_pk_mul_f32 v[20:21], v[2:3], v[0:1]
	v_lshl_add_u64 v[0:1], s[0:1], 0, v[160:161]
	v_lshlrev_b32_e32 v160, 3, v22
	v_lshl_add_u64 v[16:17], v[0:1], 0, s[8:9]
	v_lshl_add_u64 v[0:1], s[6:7], 0, v[160:161]
	v_lshlrev_b32_e32 v2, 7, v31
	v_mov_b32_e32 v3, v161
	v_lshl_add_u64 v[0:1], v[0:1], 0, v[2:3]
	s_mov_b64 s[6:7], 0x800000
	v_lshl_add_u64 v[22:23], v[0:1], 0, s[6:7]
	v_add_co_u32_e32 v0, vcc, s10, v0
	v_cvt_pk_bf16_f32 v2, v8, v9
	s_nop 0
	v_addc_co_u32_e32 v1, vcc, 0, v1, vcc
	global_load_dwordx2 v[4:5], v[0:1], off
	global_load_dwordx2 v[6:7], v[22:23], off offset:32
	v_cvt_pk_bf16_f32 v3, v10, v11
	global_load_dwordx2 v[8:9], v[22:23], off offset:64
	global_load_dwordx2 v[10:11], v[22:23], off offset:96
	v_cvt_pk_bf16_f32 v0, v24, v25
	v_cvt_pk_bf16_f32 v1, v26, v27
	v_cvt_pk_bf16_f32 v15, v20, v21
	v_readlane_b32 s8, v253, 45
	v_readlane_b32 s9, v253, 46
	s_mov_b64 s[6:7], -1
	s_and_b64 vcc, exec, s[8:9]
	s_waitcnt vmcnt(0) lgkmcnt(0)
	v_mfma_f32_16x16x32_bf16 v[4:7], v[4:7], v[0:3], 0
	v_mfma_f32_16x16x32_bf16 v[8:11], v[8:11], v[12:15], v[4:7]
	s_nop 6
	v_lshlrev_b32_e32 v4, 1, v28
	v_cndmask_b32_e64 v6, v11, 0, s[4:5]
	v_cndmask_b32_e64 v5, v10, 0, s[4:5]
	v_cndmask_b32_e64 v7, v9, 0, s[4:5]
	v_cndmask_b32_e64 v8, v8, 0, s[4:5]
	v_cvt_pk_bf16_f32 v8, v8, v7
	v_cvt_pk_bf16_f32 v9, v5, v6
	s_cbranch_vccz .LBB0_384
	v_mov_b32_e32 v5, v161
	v_lshl_add_u64 v[10:11], v[16:17], 0, v[4:5]
	v_cvt_pk_bf16_f32 v5, v7, s0
	global_store_short v[10:11], v8, off
	global_store_short v[10:11], v5, off offset:256
	global_store_short v[10:11], v9, off offset:512
	v_cvt_pk_bf16_f32 v5, v6, s0
	global_store_short v[10:11], v5, off offset:768
	s_mov_b64 s[6:7], 0
.LBB0_384:
	v_lshlrev_b32_e32 v6, 7, v30
	v_mov_b32_e32 v7, v161
	v_lshl_add_u64 v[6:7], s[0:1], 0, v[6:7]
	v_lshl_add_u64 v[6:7], v[6:7], 0, v[160:161]
	s_mov_b64 s[0:1], 0x400000
	s_andn2_b64 vcc, exec, s[6:7]
	v_lshl_add_u64 v[6:7], v[6:7], 0, s[0:1]
	s_cbranch_vccnz .LBB0_386
	global_store_dwordx2 v[6:7], v[8:9], off
.LBB0_386:
	global_load_dwordx2 v[8:9], v[22:23], off offset:2048
	s_nop 0
	global_load_dwordx2 v[10:11], v[22:23], off offset:2080
	global_load_dwordx2 v[18:19], v[22:23], off offset:2112
	global_load_dwordx2 v[20:21], v[22:23], off offset:2144
	v_readlane_b32 s8, v253, 45
	v_readlane_b32 s9, v253, 46
	s_mov_b64 s[6:7], -1
	s_andn2_b64 vcc, exec, s[8:9]
	v_cndmask_b32_e64 v5, 0, 1, s[8:9]
	v_cmp_ne_u32_e64 s[0:1], 1, v5
	s_waitcnt vmcnt(0) lgkmcnt(0)
	v_mfma_f32_16x16x32_bf16 v[8:11], v[8:11], v[0:3], 0
	v_mfma_f32_16x16x32_bf16 v[18:21], v[18:21], v[12:15], v[8:11]
	s_nop 7
	v_cndmask_b32_e64 v10, v21, 0, s[4:5]
	v_cndmask_b32_e64 v5, v20, 0, s[4:5]
	v_cndmask_b32_e64 v11, v19, 0, s[4:5]
	v_cndmask_b32_e64 v8, v18, 0, s[4:5]
	v_cvt_pk_bf16_f32 v8, v8, v11
	v_cvt_pk_bf16_f32 v9, v5, v10
	s_cbranch_vccnz .LBB0_388
	v_mov_b32_e32 v5, v161
	v_lshl_add_u64 v[18:19], v[16:17], 0, v[4:5]
	v_add_co_u32_e32 v18, vcc, 0x1000, v18
	v_cvt_pk_bf16_f32 v5, v11, s0
	s_nop 0
	v_addc_co_u32_e32 v19, vcc, 0, v19, vcc
	global_store_short v[18:19], v8, off
	global_store_short v[18:19], v5, off offset:256
	global_store_short v[18:19], v9, off offset:512
	v_cvt_pk_bf16_f32 v5, v10, s0
	s_mov_b64 s[6:7], 0
	global_store_short v[18:19], v5, off offset:768
.LBB0_388:
	s_andn2_b64 vcc, exec, s[6:7]
	s_cbranch_vccnz .LBB0_390
	global_store_dwordx2 v[6:7], v[8:9], off offset:32
.LBB0_390:
	v_add_co_u32_e32 v20, vcc, 0x1000, v22
	s_mov_b64 s[6:7], -1
	s_nop 0
	v_addc_co_u32_e32 v21, vcc, 0, v23, vcc
	global_load_dwordx2 v[8:9], v[20:21], off
	global_load_dwordx2 v[10:11], v[20:21], off offset:32
	global_load_dwordx2 v[18:19], v[20:21], off offset:64
	s_nop 0
	global_load_dwordx2 v[20:21], v[20:21], off offset:96
	s_and_b64 vcc, exec, s[0:1]
	s_waitcnt vmcnt(0) lgkmcnt(0)
	v_mfma_f32_16x16x32_bf16 v[8:11], v[8:11], v[0:3], 0
	v_mfma_f32_16x16x32_bf16 v[18:21], v[18:21], v[12:15], v[8:11]
	s_nop 7
	v_cndmask_b32_e64 v10, v21, 0, s[4:5]
	v_cndmask_b32_e64 v5, v20, 0, s[4:5]
	v_cndmask_b32_e64 v11, v19, 0, s[4:5]
	v_cndmask_b32_e64 v8, v18, 0, s[4:5]
	v_cvt_pk_bf16_f32 v8, v8, v11
	v_cvt_pk_bf16_f32 v9, v5, v10
	s_cbranch_vccnz .LBB0_392
	v_mov_b32_e32 v5, v161
	v_lshl_add_u64 v[18:19], v[16:17], 0, v[4:5]
	v_add_co_u32_e32 v18, vcc, 0x2000, v18
	v_cvt_pk_bf16_f32 v5, v11, s0
	s_nop 0
	v_addc_co_u32_e32 v19, vcc, 0, v19, vcc
	global_store_short v[18:19], v8, off
	global_store_short v[18:19], v5, off offset:256
	global_store_short v[18:19], v9, off offset:512
	v_cvt_pk_bf16_f32 v5, v10, s0
	s_mov_b64 s[6:7], 0
	global_store_short v[18:19], v5, off offset:768
.LBB0_392:
	s_andn2_b64 vcc, exec, s[6:7]
	s_cbranch_vccnz .LBB0_394
	global_store_dwordx2 v[6:7], v[8:9], off offset:64
.LBB0_394:
	v_add_co_u32_e32 v18, vcc, 0x1000, v22
	s_nop 1
	v_addc_co_u32_e32 v19, vcc, 0, v23, vcc
	global_load_dwordx2 v[8:9], v[18:19], off offset:2048
	global_load_dwordx2 v[10:11], v[18:19], off offset:2080
	s_and_b64 vcc, exec, s[0:1]
	s_waitcnt vmcnt(0) lgkmcnt(0)
	v_mfma_f32_16x16x32_bf16 v[0:3], v[8:11], v[0:3], 0
	global_load_dwordx2 v[8:9], v[18:19], off offset:2112
	global_load_dwordx2 v[10:11], v[18:19], off offset:2144
	s_waitcnt vmcnt(0) lgkmcnt(0)
	v_mfma_f32_16x16x32_bf16 v[8:11], v[8:11], v[12:15], v[0:3]
	s_nop 7
	v_cndmask_b32_e64 v2, v11, 0, s[4:5]
	v_cndmask_b32_e64 v1, v10, 0, s[4:5]
	v_cndmask_b32_e64 v3, v9, 0, s[4:5]
	v_cndmask_b32_e64 v0, v8, 0, s[4:5]
	s_mov_b64 s[4:5], -1
	v_cvt_pk_bf16_f32 v0, v0, v3
	v_cvt_pk_bf16_f32 v1, v1, v2
	s_cbranch_vccnz .LBB0_396
	v_mov_b32_e32 v5, v161
	v_lshl_add_u64 v[4:5], v[16:17], 0, v[4:5]
	v_add_co_u32_e32 v4, vcc, 0x3000, v4
	v_cvt_pk_bf16_f32 v3, v3, s0
	s_nop 0
	v_addc_co_u32_e32 v5, vcc, 0, v5, vcc
	v_cvt_pk_bf16_f32 v2, v2, s0
	s_mov_b64 s[4:5], 0
	global_store_short v[4:5], v0, off
	global_store_short v[4:5], v3, off offset:256
	global_store_short v[4:5], v1, off offset:512
	global_store_short v[4:5], v2, off offset:768
.LBB0_396:
	s_andn2_b64 vcc, exec, s[4:5]
	s_cbranch_vccnz .LBB0_398
	global_store_dwordx2 v[6:7], v[0:1], off offset:96

.LBB0_400:
	v_ashrrev_i32_e32 v6, 5, v0
	v_lshlrev_b32_e32 v2, 7, v6
	v_and_b32_e32 v7, 0x7c, v1
	v_ashrrev_i32_e32 v3, 31, v2
	v_lshl_add_u64 v[2:3], v[2:3], 2, s[6:7]
	v_lshlrev_b32_e32 v160, 2, v7
	v_lshl_add_u64 v[2:3], v[2:3], 0, v[160:161]
	global_load_dwordx4 v[2:5], v[2:3], off
	v_cmp_le_i32_e32 vcc, v7, v6
	s_movk_i32 s1, 0xdff
	v_add_u32_e32 v1, 0x800, v1
	s_waitcnt vmcnt(0) lgkmcnt(0)
	v_cndmask_b32_e32 v2, 0, v2, vcc
	v_cmp_lt_i32_e32 vcc, v7, v6
	s_nop 1
	v_cndmask_b32_e32 v3, 0, v3, vcc
	v_cvt_pk_bf16_f32 v2, v2, v3
	v_or_b32_e32 v3, 2, v7
	v_cmp_le_i32_e32 vcc, v3, v6
	s_nop 1
	v_cndmask_b32_e32 v3, 0, v4, vcc
	v_or_b32_e32 v4, 3, v7
	v_cmp_le_i32_e32 vcc, v4, v6
	s_nop 1
	v_cndmask_b32_e32 v4, 0, v5, vcc
	v_cvt_pk_bf16_f32 v3, v3, v4
	v_mul_lo_u32 v4, v6, s93
	v_lshlrev_b32_e32 v5, 1, v7
	v_add3_u32 v4, 0, v4, v5
	ds_write_b64 v4, v[2:3] offset:34816
	v_add_u32_e32 v2, 0x200, v0
	v_cmp_lt_i32_e32 vcc, s1, v0
	s_or_b64 s[8:9], vcc, s[8:9]
	v_mov_b32_e32 v0, v2
	s_andn2_b64 exec, exec, s[8:9]
	s_cbranch_execnz .LBB0_400

.LBB0_402:
	v_mov_b32_e32 v0, 0xe8
	s_lshl_b32 s8, s2, 12
	v_add_u32_e32 v0, s91, v0
	ds_read_b64 v[0:1], v0
	v_readlane_b32 s9, v253, 53
	v_mbcnt_lo_u32_b32 v8, -1, 0
	v_mbcnt_hi_u32_b32 v8, -1, v8
	s_add_i32 s8, s8, s9
	v_add_u32_e32 v2, s57, v8
	s_and_b32 s8, s8, 0xffffff80
	v_ashrrev_i32_e32 v10, 2, v2
	s_waitcnt lgkmcnt(0)
	v_readfirstlane_b32 s6, v0
	v_add_u32_e32 v0, s8, v10
	v_readfirstlane_b32 s7, v1
	v_ashrrev_i32_e32 v1, 31, v0
	v_lshlrev_b64 v[0:1], 10, v[0:1]
	v_and_b32_e32 v9, 3, v8
	v_lshl_add_u64 v[0:1], s[6:7], 0, v[0:1]
	s_mov_b64 s[10:11], 0x19200000
	v_lshl_add_u64 v[4:5], v[0:1], 0, s[10:11]
	v_lshlrev_b32_e32 v0, 8, v9
	v_mov_b32_e32 v1, v161
	v_lshl_add_u64 v[6:7], v[4:5], 0, v[0:1]
	s_barrier
	global_load_dwordx4 v[12:15], v[6:7], off
	global_load_dwordx4 v[16:19], v[6:7], off offset:16
	global_load_dwordx4 v[20:23], v[6:7], off offset:32
	global_load_dwordx4 v[24:27], v[6:7], off offset:48
	global_load_dwordx4 v[28:31], v[6:7], off offset:64
	global_load_dwordx4 v[32:35], v[6:7], off offset:80
	global_load_dwordx4 v[0:3], v[6:7], off offset:96
	v_readlane_b32 s11, v253, 55
	s_lshl_b32 s82, s11, 1
	v_lshl_add_u64 v[4:5], v[4:5], 0, s[82:83]
	v_lshlrev_b32_e32 v160, 7, v9
	v_cmp_lt_i32_e32 vcc, v214, v213
	v_lshlrev_b32_e32 v10, 1, v10
	s_waitcnt vmcnt(0) lgkmcnt(0)
	v_lshlrev_b32_e32 v36, 16, v12
	v_and_b32_e32 v12, 0xffff0000, v12
	v_add_f32_e32 v52, 0, v36
	v_lshlrev_b32_e32 v37, 16, v13
	v_mul_f32_e32 v11, v12, v12
	v_add_f32_e32 v12, v52, v12
	v_and_b32_e32 v13, 0xffff0000, v13
	v_add_f32_e32 v12, v12, v37
	v_lshlrev_b32_e32 v38, 16, v14
	v_fmac_f32_e32 v11, v36, v36
	v_add_f32_e32 v12, v12, v13
	v_and_b32_e32 v14, 0xffff0000, v14
	v_fmac_f32_e32 v11, v37, v37
	v_add_f32_e32 v12, v12, v38
	v_lshlrev_b32_e32 v39, 16, v15
	v_fmac_f32_e32 v11, v13, v13
	v_add_f32_e32 v12, v12, v14
	v_and_b32_e32 v15, 0xffff0000, v15
	v_fmac_f32_e32 v11, v38, v38
	v_add_f32_e32 v12, v12, v39
	v_lshlrev_b32_e32 v40, 16, v16
	v_fmac_f32_e32 v11, v14, v14
	v_add_f32_e32 v12, v12, v15
	v_and_b32_e32 v16, 0xffff0000, v16
	v_fmac_f32_e32 v11, v39, v39
	v_add_f32_e32 v12, v12, v40
	v_lshlrev_b32_e32 v41, 16, v17
	v_fmac_f32_e32 v11, v15, v15
	v_add_f32_e32 v12, v12, v16
	v_and_b32_e32 v17, 0xffff0000, v17
	v_fmac_f32_e32 v11, v40, v40
	v_add_f32_e32 v12, v12, v41
	v_lshlrev_b32_e32 v42, 16, v18
	v_fmac_f32_e32 v11, v16, v16
	v_add_f32_e32 v12, v12, v17
	v_and_b32_e32 v18, 0xffff0000, v18
	v_fmac_f32_e32 v11, v41, v41
	v_add_f32_e32 v12, v12, v42
	v_lshlrev_b32_e32 v43, 16, v19
	v_fmac_f32_e32 v11, v17, v17
	v_add_f32_e32 v12, v12, v18
	v_and_b32_e32 v19, 0xffff0000, v19
	v_fmac_f32_e32 v11, v42, v42
	v_add_f32_e32 v12, v12, v43
	v_lshlrev_b32_e32 v44, 16, v20
	v_fmac_f32_e32 v11, v18, v18
	v_add_f32_e32 v12, v12, v19
	v_and_b32_e32 v20, 0xffff0000, v20
	v_fmac_f32_e32 v11, v43, v43
	v_add_f32_e32 v12, v12, v44
	v_lshlrev_b32_e32 v45, 16, v21
	v_fmac_f32_e32 v11, v19, v19
	v_add_f32_e32 v12, v12, v20
	v_and_b32_e32 v21, 0xffff0000, v21
	v_fmac_f32_e32 v11, v44, v44
	v_add_f32_e32 v12, v12, v45
	v_lshlrev_b32_e32 v46, 16, v22
	v_fmac_f32_e32 v11, v20, v20
	v_add_f32_e32 v12, v12, v21
	v_and_b32_e32 v22, 0xffff0000, v22
	v_fmac_f32_e32 v11, v45, v45
	v_add_f32_e32 v12, v12, v46
	v_lshlrev_b32_e32 v47, 16, v23
	v_fmac_f32_e32 v11, v21, v21
	v_add_f32_e32 v12, v12, v22
	v_and_b32_e32 v23, 0xffff0000, v23
	v_fmac_f32_e32 v11, v46, v46
	v_add_f32_e32 v12, v12, v47
	v_lshlrev_b32_e32 v48, 16, v24
	v_fmac_f32_e32 v11, v22, v22
	v_add_f32_e32 v12, v12, v23
	v_and_b32_e32 v24, 0xffff0000, v24
	v_fmac_f32_e32 v11, v47, v47
	v_add_f32_e32 v12, v12, v48
	v_lshlrev_b32_e32 v49, 16, v25
	v_fmac_f32_e32 v11, v23, v23
	v_add_f32_e32 v12, v12, v24
	v_and_b32_e32 v25, 0xffff0000, v25
	v_fmac_f32_e32 v11, v48, v48
	v_add_f32_e32 v12, v12, v49
	v_lshlrev_b32_e32 v50, 16, v26
	v_fmac_f32_e32 v11, v24, v24
	v_add_f32_e32 v12, v12, v25
	v_and_b32_e32 v26, 0xffff0000, v26
	v_fmac_f32_e32 v11, v49, v49
	v_add_f32_e32 v12, v12, v50
	v_lshlrev_b32_e32 v51, 16, v27
	v_fmac_f32_e32 v11, v25, v25
	v_add_f32_e32 v16, v12, v26
	global_load_dwordx4 v[12:15], v[6:7], off offset:112
	v_and_b32_e32 v27, 0xffff0000, v27
	v_fmac_f32_e32 v11, v50, v50
	v_add_f32_e32 v16, v16, v51
	v_fmac_f32_e32 v11, v26, v26
	v_add_f32_e32 v16, v16, v27
	v_lshlrev_b32_e32 v17, 16, v28
	v_fmac_f32_e32 v11, v51, v51
	v_and_b32_e32 v18, 0xffff0000, v28
	v_add_f32_e32 v16, v16, v17
	v_fmac_f32_e32 v11, v27, v27
	v_lshlrev_b32_e32 v19, 16, v29
	v_add_f32_e32 v16, v16, v18
	v_and_b32_e32 v20, 0xffff0000, v29
	v_fmac_f32_e32 v11, v17, v17
	v_add_f32_e32 v16, v16, v19
	v_lshlrev_b32_e32 v21, 16, v30
	v_fmac_f32_e32 v11, v18, v18
	v_add_f32_e32 v16, v16, v20
	v_and_b32_e32 v22, 0xffff0000, v30
	v_fmac_f32_e32 v11, v19, v19
	v_add_f32_e32 v16, v16, v21
	v_fmac_f32_e32 v11, v20, v20
	v_add_f32_e32 v20, v16, v22
	global_load_dwordx4 v[16:19], v[6:7], off offset:128
	v_lshlrev_b32_e32 v23, 16, v31
	v_fmac_f32_e32 v11, v21, v21
	v_and_b32_e32 v24, 0xffff0000, v31
	v_fmac_f32_e32 v11, v22, v22
	v_add_f32_e32 v20, v20, v23
	v_fmac_f32_e32 v11, v23, v23
	v_add_f32_e32 v20, v20, v24
	v_lshlrev_b32_e32 v21, 16, v32
	v_fmac_f32_e32 v11, v24, v24
	v_and_b32_e32 v22, 0xffff0000, v32
	v_add_f32_e32 v20, v20, v21
	v_lshlrev_b32_e32 v23, 16, v33
	v_fmac_f32_e32 v11, v21, v21
	v_add_f32_e32 v20, v20, v22
	v_and_b32_e32 v24, 0xffff0000, v33
	v_fmac_f32_e32 v11, v22, v22
	v_add_f32_e32 v20, v20, v23
	v_lshlrev_b32_e32 v25, 16, v34
	v_fmac_f32_e32 v11, v23, v23
	v_add_f32_e32 v20, v20, v24
	v_and_b32_e32 v26, 0xffff0000, v34
	v_fmac_f32_e32 v11, v24, v24
	v_add_f32_e32 v20, v20, v25
	v_fmac_f32_e32 v11, v25, v25
	v_add_f32_e32 v24, v20, v26
	global_load_dwordx4 v[20:23], v[6:7], off offset:144
	v_lshlrev_b32_e32 v27, 16, v35
	v_fmac_f32_e32 v11, v26, v26
	v_and_b32_e32 v28, 0xffff0000, v35
	v_add_f32_e32 v24, v24, v27
	v_fmac_f32_e32 v11, v27, v27
	v_add_f32_e32 v24, v24, v28
	v_fmac_f32_e32 v11, v28, v28
	v_lshlrev_b32_e32 v25, 16, v0
	v_and_b32_e32 v0, 0xffff0000, v0
	v_lshlrev_b32_e32 v28, 16, v3
	v_and_b32_e32 v29, 0xffff0000, v3
	v_add_f32_e32 v3, v24, v25
	v_fmac_f32_e32 v11, v25, v25
	v_lshlrev_b32_e32 v26, 16, v1
	v_add_f32_e32 v3, v3, v0
	v_fmac_f32_e32 v11, v0, v0
	v_and_b32_e32 v1, 0xffff0000, v1
	v_add_f32_e32 v0, v3, v26
	v_fmac_f32_e32 v11, v26, v26
	v_lshlrev_b32_e32 v27, 16, v2
	v_add_f32_e32 v0, v0, v1
	v_fmac_f32_e32 v11, v1, v1
	v_and_b32_e32 v2, 0xffff0000, v2
	v_add_f32_e32 v0, v0, v27
	v_fmac_f32_e32 v11, v27, v27
	v_add_f32_e32 v24, v0, v2
	v_fmac_f32_e32 v11, v2, v2
	global_load_dwordx4 v[0:3], v[6:7], off offset:160
	v_add_f32_e32 v24, v24, v28
	v_fmac_f32_e32 v11, v28, v28
	v_add_f32_e32 v24, v24, v29
	v_fmac_f32_e32 v11, v29, v29
	s_waitcnt vmcnt(0) lgkmcnt(0)
	v_lshlrev_b32_e32 v25, 16, v12
	v_and_b32_e32 v12, 0xffff0000, v12
	v_lshlrev_b32_e32 v28, 16, v15
	v_and_b32_e32 v29, 0xffff0000, v15
	v_add_f32_e32 v15, v24, v25
	v_fmac_f32_e32 v11, v25, v25
	v_lshlrev_b32_e32 v26, 16, v13
	v_add_f32_e32 v15, v15, v12
	v_fmac_f32_e32 v11, v12, v12
	v_and_b32_e32 v13, 0xffff0000, v13
	v_add_f32_e32 v12, v15, v26
	v_fmac_f32_e32 v11, v26, v26
	v_lshlrev_b32_e32 v27, 16, v14
	v_add_f32_e32 v12, v12, v13
	v_fmac_f32_e32 v11, v13, v13
	v_and_b32_e32 v14, 0xffff0000, v14
	v_add_f32_e32 v12, v12, v27
	v_fmac_f32_e32 v11, v27, v27
	v_add_f32_e32 v24, v12, v14
	v_fmac_f32_e32 v11, v14, v14
	global_load_dwordx4 v[12:15], v[6:7], off offset:176
	v_add_f32_e32 v24, v24, v28
	v_fmac_f32_e32 v11, v28, v28
	v_add_f32_e32 v24, v24, v29
	v_lshlrev_b32_e32 v25, 16, v16
	v_fmac_f32_e32 v11, v29, v29
	v_and_b32_e32 v16, 0xffff0000, v16
	v_lshlrev_b32_e32 v27, 16, v18
	v_and_b32_e32 v28, 0xffff0000, v18
	v_add_f32_e32 v18, v24, v25
	v_lshlrev_b32_e32 v26, 16, v17
	v_fmac_f32_e32 v11, v25, v25
	v_add_f32_e32 v18, v18, v16
	v_and_b32_e32 v17, 0xffff0000, v17
	v_fmac_f32_e32 v11, v16, v16
	v_add_f32_e32 v16, v18, v26
	v_add_f32_e32 v16, v16, v17
	v_fmac_f32_e32 v11, v26, v26
	v_add_f32_e32 v16, v16, v27
	v_lshlrev_b32_e32 v29, 16, v19
	v_and_b32_e32 v30, 0xffff0000, v19
	v_fmac_f32_e32 v11, v17, v17
	v_add_f32_e32 v24, v16, v28
	global_load_dwordx4 v[16:19], v[6:7], off offset:192
	v_fmac_f32_e32 v11, v27, v27
	v_fmac_f32_e32 v11, v28, v28
	v_add_f32_e32 v24, v24, v29
	v_fmac_f32_e32 v11, v29, v29
	v_add_f32_e32 v24, v24, v30
	v_lshlrev_b32_e32 v25, 16, v20
	v_fmac_f32_e32 v11, v30, v30
	v_and_b32_e32 v20, 0xffff0000, v20
	v_lshlrev_b32_e32 v27, 16, v22
	v_and_b32_e32 v28, 0xffff0000, v22
	v_add_f32_e32 v22, v24, v25
	v_lshlrev_b32_e32 v26, 16, v21
	v_fmac_f32_e32 v11, v25, v25
	v_add_f32_e32 v22, v22, v20
	v_and_b32_e32 v21, 0xffff0000, v21
	v_fmac_f32_e32 v11, v20, v20
	v_add_f32_e32 v20, v22, v26
	v_add_f32_e32 v20, v20, v21
	v_fmac_f32_e32 v11, v26, v26
	v_add_f32_e32 v20, v20, v27
	v_lshlrev_b32_e32 v29, 16, v23
	v_and_b32_e32 v30, 0xffff0000, v23
	v_fmac_f32_e32 v11, v21, v21
	v_add_f32_e32 v24, v20, v28
	global_load_dwordx4 v[20:23], v[6:7], off offset:208
	v_fmac_f32_e32 v11, v27, v27
	v_fmac_f32_e32 v11, v28, v28
	v_add_f32_e32 v24, v24, v29
	v_fmac_f32_e32 v11, v29, v29
	v_add_f32_e32 v24, v24, v30
	v_fmac_f32_e32 v11, v30, v30
	v_lshlrev_b32_e32 v25, 16, v0
	v_and_b32_e32 v0, 0xffff0000, v0
	v_lshlrev_b32_e32 v27, 16, v2
	v_and_b32_e32 v28, 0xffff0000, v2
	v_add_f32_e32 v2, v24, v25
	v_lshlrev_b32_e32 v26, 16, v1
	v_fmac_f32_e32 v11, v25, v25
	v_add_f32_e32 v2, v2, v0
	v_and_b32_e32 v1, 0xffff0000, v1
	v_fmac_f32_e32 v11, v0, v0
	v_add_f32_e32 v0, v2, v26
	v_fmac_f32_e32 v11, v26, v26
	v_add_f32_e32 v0, v0, v1
	v_lshlrev_b32_e32 v29, 16, v3
	v_and_b32_e32 v30, 0xffff0000, v3
	v_fmac_f32_e32 v11, v1, v1
	v_add_f32_e32 v24, v0, v27
	global_load_dwordx4 v[0:3], v[6:7], off offset:224
	v_fmac_f32_e32 v11, v27, v27
	v_add_f32_e32 v24, v24, v28
	v_fmac_f32_e32 v11, v28, v28
	v_add_f32_e32 v24, v24, v29
	v_fmac_f32_e32 v11, v29, v29
	v_add_f32_e32 v24, v24, v30
	v_fmac_f32_e32 v11, v30, v30
	s_waitcnt vmcnt(0) lgkmcnt(0)
	v_lshlrev_b32_e32 v25, 16, v12
	v_and_b32_e32 v12, 0xffff0000, v12
	v_add_f32_e32 v24, v24, v25
	v_lshlrev_b32_e32 v26, 16, v13
	v_fmac_f32_e32 v11, v25, v25
	v_add_f32_e32 v24, v24, v12
	v_and_b32_e32 v13, 0xffff0000, v13
	v_fmac_f32_e32 v11, v12, v12
	v_add_f32_e32 v12, v24, v26
	v_lshlrev_b32_e32 v27, 16, v14
	v_add_f32_e32 v12, v12, v13
	v_and_b32_e32 v14, 0xffff0000, v14
	v_fmac_f32_e32 v11, v26, v26
	v_add_f32_e32 v12, v12, v27
	v_lshlrev_b32_e32 v28, 16, v15
	v_fmac_f32_e32 v11, v13, v13
	v_add_f32_e32 v12, v12, v14
	v_and_b32_e32 v15, 0xffff0000, v15
	v_fmac_f32_e32 v11, v27, v27
	v_add_f32_e32 v12, v12, v28
	v_fmac_f32_e32 v11, v14, v14
	v_add_f32_e32 v12, v12, v15
	v_fmac_f32_e32 v11, v28, v28
	v_lshlrev_b32_e32 v13, 16, v16
	v_and_b32_e32 v14, 0xffff0000, v16
	v_add_f32_e32 v12, v12, v13
	v_fmac_f32_e32 v11, v15, v15
	v_lshlrev_b32_e32 v15, 16, v17
	v_add_f32_e32 v12, v12, v14
	v_and_b32_e32 v16, 0xffff0000, v17
	v_add_f32_e32 v12, v12, v15
	v_lshlrev_b32_e32 v17, 16, v18
	v_add_f32_e32 v12, v12, v16
	v_and_b32_e32 v18, 0xffff0000, v18
	v_fmac_f32_e32 v11, v13, v13
	v_add_f32_e32 v12, v12, v17
	v_lshlrev_b32_e32 v24, 16, v19
	v_fmac_f32_e32 v11, v14, v14
	v_add_f32_e32 v12, v12, v18
	v_and_b32_e32 v19, 0xffff0000, v19
	v_fmac_f32_e32 v11, v15, v15
	v_add_f32_e32 v12, v12, v24
	v_fmac_f32_e32 v11, v16, v16
	v_add_f32_e32 v16, v12, v19
	global_load_dwordx4 v[12:15], v[6:7], off offset:240
	v_fmac_f32_e32 v11, v17, v17
	v_fmac_f32_e32 v11, v18, v18
	v_fmac_f32_e32 v11, v24, v24
	v_lshlrev_b32_e32 v6, 16, v20
	v_fmac_f32_e32 v11, v19, v19
	v_and_b32_e32 v7, 0xffff0000, v20
	v_add_f32_e32 v16, v16, v6
	v_lshlrev_b32_e32 v17, 16, v21
	v_fmac_f32_e32 v11, v6, v6
	v_add_f32_e32 v6, v16, v7
	v_and_b32_e32 v18, 0xffff0000, v21
	v_fmac_f32_e32 v11, v7, v7
	v_add_f32_e32 v6, v6, v17
	v_lshlrev_b32_e32 v19, 16, v22
	v_fmac_f32_e32 v11, v17, v17
	v_add_f32_e32 v6, v6, v18
	v_and_b32_e32 v20, 0xffff0000, v22
	v_fmac_f32_e32 v11, v18, v18
	v_add_f32_e32 v6, v6, v19
	v_lshlrev_b32_e32 v21, 16, v23
	v_fmac_f32_e32 v11, v19, v19
	v_add_f32_e32 v6, v6, v20
	v_and_b32_e32 v22, 0xffff0000, v23
	v_fmac_f32_e32 v11, v20, v20
	v_add_f32_e32 v6, v6, v21
	v_fmac_f32_e32 v11, v21, v21
	v_add_f32_e32 v6, v6, v22
	v_lshlrev_b32_e32 v7, 16, v0
	v_fmac_f32_e32 v11, v22, v22
	v_and_b32_e32 v0, 0xffff0000, v0
	v_add_f32_e32 v6, v6, v7
	v_lshlrev_b32_e32 v16, 16, v1
	v_fmac_f32_e32 v11, v7, v7
	v_add_f32_e32 v6, v6, v0
	v_fmac_f32_e32 v11, v0, v0
	v_add_f32_e32 v0, v6, v16
	v_lshlrev_b32_e32 v7, 16, v2
	v_and_b32_e32 v6, 0xffff0000, v1
	v_fmac_f32_e32 v11, v16, v16
	v_add_f32_e32 v16, v0, v6
	v_pk_mul_f32 v[0:1], v[6:7], v[6:7]
	v_lshlrev_b32_e32 v6, 6, v9
	v_add_f32_e32 v0, v0, v11
	v_add_f32_e32 v32, v1, v0
	v_mov_b32_e32 v0, 56
	v_add_f32_e32 v11, v16, v7
	v_add_u32_e32 v0, s91, v0
	ds_read_b64 v[0:1], v0
	v_mov_b32_e32 v7, v161
	v_lshl_add_u64 v[4:5], v[4:5], 0, v[6:7]
	v_lshlrev_b32_e32 v29, 16, v3
	v_and_b32_e32 v28, 0xffff0000, v2
	s_waitcnt lgkmcnt(0)
	v_readfirstlane_b32 s10, v0
	v_mov_b32_e32 v0, 64
	v_readfirstlane_b32 s9, v1
	v_add_u32_e32 v0, s91, v0
	ds_read_b64 v[6:7], v0
	s_add_u32 s10, s10, s0
	s_addc_u32 s9, s9, s1
	s_lshl_b32 s12, s11, 2
	s_add_u32 s10, s10, s12
	s_addc_u32 s11, s9, 0
	v_lshl_add_u64 v[0:1], s[10:11], 0, v[160:161]
	s_waitcnt lgkmcnt(0)
	v_readfirstlane_b32 s10, v6
	v_readfirstlane_b32 s9, v7
	s_add_u32 s10, s10, s0
	global_load_dwordx4 v[16:19], v[4:5], off
	s_addc_u32 s9, s9, s1
	s_add_u32 s10, s10, s12
	s_addc_u32 s11, s9, 0
	v_lshl_add_u64 v[6:7], s[10:11], 0, v[160:161]
	global_load_dwordx4 v[20:23], v[0:1], off
	global_load_dwordx4 v[24:27], v[6:7], off
	v_add_f32_e32 v2, v11, v28
	v_pk_mul_f32 v[30:31], v[28:29], v[28:29]
	v_add_f32_e32 v28, v2, v29
	v_add_f32_e32 v11, v30, v32
	v_and_b32_e32 v3, 0xffff0000, v3
	s_waitcnt vmcnt(0)
	v_lshlrev_b32_e32 v2, 16, v12
	v_add_f32_e32 v11, v31, v11
	v_add_f32_e32 v30, v28, v3
	v_pk_mul_f32 v[28:29], v[2:3], v[2:3]
	v_and_b32_e32 v37, 0xffff0000, v15
	v_add_f32_e32 v3, v29, v11
	v_add_f32_e32 v11, v30, v2
	v_add_f32_e32 v30, v28, v3
	v_lshlrev_b32_e32 v3, 16, v13
	v_and_b32_e32 v2, 0xffff0000, v12
	v_pk_mul_f32 v[28:29], v[2:3], v[2:3]
	v_add_f32_e32 v11, v11, v2
	v_add_f32_e32 v2, v28, v30
	v_add_f32_e32 v36, v29, v2
	global_load_dwordx4 v[28:31], v[0:1], off offset:16
	global_load_dwordx4 v[32:35], v[6:7], off offset:16
	v_add_f32_e32 v11, v11, v3
	v_lshlrev_b32_e32 v3, 16, v14
	v_and_b32_e32 v2, 0xffff0000, v13
	v_pk_mul_f32 v[12:13], v[2:3], v[2:3]
	v_add_f32_e32 v11, v11, v2
	v_add_f32_e32 v2, v12, v36
	v_add_f32_e32 v11, v11, v3
	v_add_f32_e32 v36, v13, v2
	v_lshlrev_b32_e32 v3, 16, v15
	v_and_b32_e32 v2, 0xffff0000, v14
	v_pk_mul_f32 v[12:13], v[2:3], v[2:3]
	v_add_f32_e32 v11, v11, v2
	v_add_f32_e32 v2, v12, v36
	v_add_f32_e32 v3, v11, v3
	v_add_f32_e32 v36, v13, v2
	v_mul_f32_e32 v2, v37, v37
	v_cndmask_b32_e32 v11, v211, v214, vcc
	v_lshlrev_b32_e32 v11, 2, v11
	v_pk_add_f32 v[2:3], v[2:3], v[36:37]
	ds_bpermute_b32 v13, v11, v3
	ds_bpermute_b32 v12, v11, v2
	v_cmp_lt_i32_e32 vcc, v215, v213
	s_mov_b32 s10, 0x3b000000
	s_mov_b32 s9, 0x800000
	v_cndmask_b32_e32 v11, v211, v215, vcc
	v_lshlrev_b32_e32 v11, 2, v11
	s_waitcnt lgkmcnt(0)
	v_pk_add_f32 v[2:3], v[2:3], v[12:13]
	ds_bpermute_b32 v13, v11, v3
	ds_bpermute_b32 v12, v11, v2
	v_mul_u32_u24_e32 v9, 0x2200, v9
	v_add3_u32 v9, 0, v10, v9
	v_readlane_b32 s12, v253, 39
	s_waitcnt lgkmcnt(0)
	v_pk_add_f32 v[2:3], v[2:3], v[12:13]
	s_nop 0
	v_pk_mul_f32 v[2:3], v[2:3], s[10:11] op_sel_hi:[1,0]
	v_and_b32_e32 v12, 0xffff0000, v16
	v_fma_f32 v2, -v3, v3, v2
	v_max_f32_e32 v2, 0, v2
	v_add_f32_e32 v2, 0x358637bd, v2
	v_mul_f32_e32 v11, 0x4b800000, v2
	v_cmp_gt_f32_e32 vcc, s9, v2
	v_sub_f32_e32 v10, v12, v3
	v_lshlrev_b32_e32 v13, 16, v17
	v_cndmask_b32_e32 v2, v2, v11, vcc
	v_rsq_f32_e32 v2, v2
	v_and_b32_e32 v14, 0xffff0000, v17
	v_lshlrev_b32_e32 v15, 16, v18
	v_lshlrev_b32_e32 v17, 16, v19
	v_mul_f32_e32 v11, 0x45800000, v2
	v_cndmask_b32_e32 v2, v2, v11, vcc
	v_mul_f32_e32 v10, v10, v2
	v_fma_f32 v10, v21, v10, v25
	v_cvt_pk_bf16_f32 v10, v10, s0
	ds_write_b16 v9, v10 offset:272
	v_sub_f32_e32 v10, v13, v3
	v_mul_f32_e32 v10, v10, v2
	v_fma_f32 v10, v22, v10, v26
	v_cvt_pk_bf16_f32 v10, v10, s0
	ds_write_b16 v9, v10 offset:544
	v_sub_f32_e32 v10, v14, v3
	v_mul_f32_e32 v10, v10, v2
	v_fmac_f32_e32 v27, v23, v10
	v_cvt_pk_bf16_f32 v10, v27, s0
	ds_write_b16 v9, v10 offset:816
	v_sub_f32_e32 v10, v15, v3
	v_mul_f32_e32 v10, v10, v2
	s_waitcnt vmcnt(0)
	v_fma_f32 v10, v28, v10, v32
	v_lshlrev_b32_e32 v11, 16, v16
	v_and_b32_e32 v16, 0xffff0000, v18
	v_cvt_pk_bf16_f32 v10, v10, s0
	ds_write_b16 v9, v10 offset:1088
	v_sub_f32_e32 v10, v16, v3
	v_mul_f32_e32 v10, v10, v2
	v_fma_f32 v10, v29, v10, v33
	v_cvt_pk_bf16_f32 v10, v10, s0
	ds_write_b16 v9, v10 offset:1360
	v_sub_f32_e32 v10, v17, v3
	v_mul_f32_e32 v10, v10, v2
	v_fma_f32 v10, v30, v10, v34
	v_and_b32_e32 v18, 0xffff0000, v19
	v_cvt_pk_bf16_f32 v10, v10, s0
	v_sub_f32_e32 v11, v11, v3
	ds_write_b16 v9, v10 offset:1632
	v_sub_f32_e32 v10, v18, v3
	v_mul_f32_e32 v11, v11, v2
	v_mul_f32_e32 v10, v10, v2
	v_fma_f32 v11, v20, v11, v24
	v_fmac_f32_e32 v35, v31, v10
	v_cvt_pk_bf16_f32 v11, v11, s0
	v_cvt_pk_bf16_f32 v10, v35, s0
	ds_write_b16 v9, v11
	ds_write_b16 v9, v10 offset:1904
	global_load_dwordx4 v[10:13], v[4:5], off offset:16
	global_load_dwordx4 v[14:17], v[6:7], off offset:32
	global_load_dwordx4 v[18:21], v[0:1], off offset:32
	global_load_dwordx4 v[22:25], v[0:1], off offset:48
	global_load_dwordx4 v[26:29], v[6:7], off offset:48
	s_waitcnt vmcnt(0) lgkmcnt(0)
	v_lshlrev_b32_e32 v30, 16, v10
	v_and_b32_e32 v10, 0xffff0000, v10
	v_sub_f32_e32 v10, v10, v3
	v_mul_f32_e32 v10, v10, v2
	v_fma_f32 v10, v19, v10, v15
	v_lshlrev_b32_e32 v31, 16, v11
	v_cvt_pk_bf16_f32 v10, v10, s0
	ds_write_b16 v9, v10 offset:2448
	v_sub_f32_e32 v10, v31, v3
	v_mul_f32_e32 v10, v10, v2
	v_fma_f32 v10, v20, v10, v16
	v_and_b32_e32 v11, 0xffff0000, v11
	v_cvt_pk_bf16_f32 v10, v10, s0
	ds_write_b16 v9, v10 offset:2720
	v_sub_f32_e32 v10, v11, v3
	v_mul_f32_e32 v10, v10, v2
	v_fmac_f32_e32 v17, v21, v10
	v_lshlrev_b32_e32 v32, 16, v12
	v_cvt_pk_bf16_f32 v10, v17, s0
	ds_write_b16 v9, v10 offset:2992
	v_sub_f32_e32 v10, v32, v3
	v_mul_f32_e32 v10, v10, v2
	v_fma_f32 v10, v22, v10, v26
	v_and_b32_e32 v12, 0xffff0000, v12
	v_cvt_pk_bf16_f32 v10, v10, s0
	ds_write_b16 v9, v10 offset:3264
	v_sub_f32_e32 v10, v12, v3
	v_mul_f32_e32 v10, v10, v2
	v_fma_f32 v10, v23, v10, v27
	v_lshlrev_b32_e32 v33, 16, v13
	v_cvt_pk_bf16_f32 v10, v10, s0
	ds_write_b16 v9, v10 offset:3536
	v_sub_f32_e32 v10, v33, v3
	v_mul_f32_e32 v10, v10, v2
	v_fma_f32 v10, v24, v10, v28
	v_and_b32_e32 v13, 0xffff0000, v13
	v_cvt_pk_bf16_f32 v10, v10, s0
	v_sub_f32_e32 v30, v30, v3
	ds_write_b16 v9, v10 offset:3808
	v_sub_f32_e32 v10, v13, v3
	v_mul_f32_e32 v30, v30, v2
	v_mul_f32_e32 v10, v10, v2
	v_fma_f32 v14, v18, v30, v14
	v_fmac_f32_e32 v29, v25, v10
	v_cvt_pk_bf16_f32 v14, v14, s0
	v_cvt_pk_bf16_f32 v10, v29, s0
	ds_write_b16 v9, v14 offset:2176
	ds_write_b16 v9, v10 offset:4080
	global_load_dwordx4 v[10:13], v[4:5], off offset:32
	global_load_dwordx4 v[14:17], v[6:7], off offset:64
	global_load_dwordx4 v[18:21], v[0:1], off offset:64
	global_load_dwordx4 v[22:25], v[0:1], off offset:80
	global_load_dwordx4 v[26:29], v[6:7], off offset:80
	s_waitcnt vmcnt(0) lgkmcnt(0)
	v_lshlrev_b32_e32 v30, 16, v10
	v_and_b32_e32 v10, 0xffff0000, v10
	v_sub_f32_e32 v10, v10, v3
	v_mul_f32_e32 v10, v10, v2
	v_fma_f32 v10, v19, v10, v15
	v_lshlrev_b32_e32 v31, 16, v11
	v_cvt_pk_bf16_f32 v10, v10, s0
	ds_write_b16 v9, v10 offset:4624
	v_sub_f32_e32 v10, v31, v3
	v_mul_f32_e32 v10, v10, v2
	v_fma_f32 v10, v20, v10, v16
	v_and_b32_e32 v11, 0xffff0000, v11
	v_cvt_pk_bf16_f32 v10, v10, s0
	ds_write_b16 v9, v10 offset:4896
	v_sub_f32_e32 v10, v11, v3
	v_mul_f32_e32 v10, v10, v2
	v_fmac_f32_e32 v17, v21, v10
	v_lshlrev_b32_e32 v32, 16, v12
	v_cvt_pk_bf16_f32 v10, v17, s0
	ds_write_b16 v9, v10 offset:5168
	v_sub_f32_e32 v10, v32, v3
	v_mul_f32_e32 v10, v10, v2
	v_fma_f32 v10, v22, v10, v26
	v_and_b32_e32 v12, 0xffff0000, v12
	v_cvt_pk_bf16_f32 v10, v10, s0
	ds_write_b16 v9, v10 offset:5440
	v_sub_f32_e32 v10, v12, v3
	v_mul_f32_e32 v10, v10, v2
	v_fma_f32 v10, v23, v10, v27
	v_lshlrev_b32_e32 v33, 16, v13
	v_cvt_pk_bf16_f32 v10, v10, s0
	ds_write_b16 v9, v10 offset:5712
	v_sub_f32_e32 v10, v33, v3
	v_mul_f32_e32 v10, v10, v2
	v_fma_f32 v10, v24, v10, v28
	v_and_b32_e32 v13, 0xffff0000, v13
	v_cvt_pk_bf16_f32 v10, v10, s0
	v_sub_f32_e32 v30, v30, v3
	ds_write_b16 v9, v10 offset:5984
	v_sub_f32_e32 v10, v13, v3
	v_mul_f32_e32 v30, v30, v2
	v_mul_f32_e32 v10, v10, v2
	v_fma_f32 v14, v18, v30, v14
	v_fmac_f32_e32 v29, v25, v10
	v_cvt_pk_bf16_f32 v14, v14, s0
	v_cvt_pk_bf16_f32 v10, v29, s0
	ds_write_b16 v9, v14 offset:4352
	ds_write_b16 v9, v10 offset:6256
	global_load_dwordx4 v[10:13], v[4:5], off offset:48
	global_load_dwordx4 v[14:17], v[6:7], off offset:96
	global_load_dwordx4 v[18:21], v[0:1], off offset:96
	global_load_dwordx4 v[22:25], v[0:1], off offset:112
	s_nop 0
	global_load_dwordx4 v[4:7], v[6:7], off offset:112
	s_waitcnt vmcnt(0) lgkmcnt(0)
	v_lshlrev_b32_e32 v0, 16, v10
	v_sub_f32_e32 v0, v0, v3
	v_mul_f32_e32 v0, v0, v2
	v_fma_f32 v0, v18, v0, v14
	v_and_b32_e32 v1, 0xffff0000, v10
	v_cvt_pk_bf16_f32 v0, v0, s0
	ds_write_b16 v9, v0 offset:6528
	v_sub_f32_e32 v0, v1, v3
	v_mul_f32_e32 v0, v0, v2
	v_fma_f32 v0, v19, v0, v15
	v_lshlrev_b32_e32 v10, 16, v11
	v_cvt_pk_bf16_f32 v0, v0, s0
	ds_write_b16 v9, v0 offset:6800
	v_sub_f32_e32 v0, v10, v3
	v_mul_f32_e32 v0, v0, v2
	v_fma_f32 v0, v20, v0, v16
	v_and_b32_e32 v11, 0xffff0000, v11
	v_cvt_pk_bf16_f32 v0, v0, s0
	ds_write_b16 v9, v0 offset:7072
	v_sub_f32_e32 v0, v11, v3
	v_mul_f32_e32 v0, v0, v2
	v_fmac_f32_e32 v17, v21, v0
	v_lshlrev_b32_e32 v26, 16, v12
	v_cvt_pk_bf16_f32 v0, v17, s0
	ds_write_b16 v9, v0 offset:7344
	v_sub_f32_e32 v0, v26, v3
	v_mul_f32_e32 v0, v0, v2
	v_fma_f32 v0, v22, v0, v4
	v_and_b32_e32 v12, 0xffff0000, v12
	v_cvt_pk_bf16_f32 v0, v0, s0
	ds_write_b16 v9, v0 offset:7616
	v_sub_f32_e32 v0, v12, v3
	v_mul_f32_e32 v0, v0, v2
	v_fma_f32 v0, v23, v0, v5
	v_lshlrev_b32_e32 v27, 16, v13
	v_cvt_pk_bf16_f32 v0, v0, s0
	ds_write_b16 v9, v0 offset:7888
	v_sub_f32_e32 v0, v27, v3
	v_mul_f32_e32 v0, v0, v2
	v_fma_f32 v0, v24, v0, v6
	v_and_b32_e32 v13, 0xffff0000, v13
	v_cvt_pk_bf16_f32 v0, v0, s0
	ds_write_b16 v9, v0 offset:8160
	v_sub_f32_e32 v0, v13, v3
	v_mul_f32_e32 v0, v0, v2
	v_fmac_f32_e32 v7, v25, v0
	v_cvt_pk_bf16_f32 v0, v7, s0
	ds_write_b16 v9, v0 offset:8432
	v_mov_b32_e32 v0, 0x48
	s_waitcnt lgkmcnt(0)
	s_barrier
	v_bfe_u32 v23, v8, 4, 2
	v_mov_b32_e32 v0, 0x50
	v_and_b32_e32 v11, 15, v8
	v_add_u32_e32 v0, s91, v0
	ds_read_b64 v[0:1], v0
	v_or_b32_e32 v14, s8, v11
	v_lshlrev_b32_e32 v160, 3, v23
	v_ashrrev_i32_e32 v15, 31, v14
	v_or_b32_e32 v2, 16, v14
	s_waitcnt lgkmcnt(0)
	v_readfirstlane_b32 s10, v0
	v_readfirstlane_b32 s9, v1
	s_add_u32 s10, s10, s4
	s_addc_u32 s11, s9, s5
	s_add_u32 s6, s6, s82
	s_addc_u32 s7, s7, 0
	s_lshl_b32 s9, s12, 1
	s_add_u32 s6, s6, s9
	s_addc_u32 s7, s7, 0
	v_lshl_add_u64 v[0:1], s[6:7], 0, v[160:161]
	s_mov_b64 s[6:7], 0xd200000
	v_lshl_add_u64 v[4:5], v[0:1], 0, s[6:7]
	v_lshlrev_b64 v[0:1], 10, v[14:15]
	v_lshl_add_u64 v[40:41], v[4:5], 0, v[0:1]
	v_lshlrev_b32_e32 v0, 2, v11
	v_mov_b32_e32 v1, v161
	global_load_dwordx2 v[42:43], v[40:41], off
	v_lshl_add_u64 v[0:1], s[10:11], 0, v[0:1]
	global_load_dword v46, v[0:1], off
	global_load_dword v48, v[0:1], off offset:64
	v_ashrrev_i32_e32 v3, 31, v2
	v_lshlrev_b64 v[2:3], 10, v[2:3]
	v_or_b32_e32 v6, 48, v14
	v_lshl_add_u64 v[44:45], v[4:5], 0, v[2:3]
	v_or_b32_e32 v2, 32, v14
	v_ashrrev_i32_e32 v7, 31, v6
	v_or_b32_e32 v8, 64, v14
	v_ashrrev_i32_e32 v3, 31, v2
	v_lshlrev_b64 v[6:7], 10, v[6:7]
	v_ashrrev_i32_e32 v9, 31, v8
	v_or_b32_e32 v12, 0x60, v14
	v_lshlrev_b64 v[2:3], 10, v[2:3]
	v_lshl_add_u64 v[6:7], v[4:5], 0, v[6:7]
	v_lshlrev_b64 v[8:9], 10, v[8:9]
	v_ashrrev_i32_e32 v13, 31, v12
	v_lshl_add_u64 v[2:3], v[4:5], 0, v[2:3]
	v_lshl_add_u64 v[8:9], v[4:5], 0, v[8:9]
	global_load_dwordx2 v[50:51], v[44:45], off
	global_load_dwordx2 v[32:33], v[2:3], off
	global_load_dwordx2 v[28:29], v[6:7], off
	global_load_dwordx2 v[24:25], v[8:9], off
	v_lshlrev_b64 v[6:7], 10, v[12:13]
	v_or_b32_e32 v2, 0x50, v14
	v_lshl_add_u64 v[8:9], v[4:5], 0, v[6:7]
	v_or_b32_e32 v6, 0x70, v14
	v_ashrrev_i32_e32 v3, 31, v2
	v_ashrrev_i32_e32 v7, 31, v6
	v_lshlrev_b64 v[2:3], 10, v[2:3]
	v_lshlrev_b64 v[16:17], 10, v[6:7]
	v_lshl_add_u64 v[2:3], v[4:5], 0, v[2:3]
	v_lshl_add_u64 v[18:19], v[4:5], 0, v[16:17]
	global_load_dwordx2 v[20:21], v[2:3], off
	global_load_dwordx2 v[16:17], v[8:9], off
	s_nop 0
	global_load_dwordx2 v[8:9], v[18:19], off
	global_load_dword v34, v[0:1], off offset:128
	global_load_dword v30, v[0:1], off offset:192
	global_load_dword v26, v[0:1], off offset:256
	global_load_dword v22, v[0:1], off offset:320
	s_nop 0
	global_load_dword v18, v[0:1], off offset:384
	global_load_dword v10, v[0:1], off offset:448
	v_or_b32_e32 v0, s12, v11
	v_mul_lo_u32 v0, v0, s93
	v_add_u32_e32 v19, 0, v0
	v_lshlrev_b32_e32 v15, 4, v23
	v_add_u32_e32 v23, v19, v15
	ds_read_b128 v[0:3], v23
	v_mad_u32_u24 v27, v11, s93, 0
	v_add_u32_e32 v31, v27, v15
	ds_read_b128 v[36:39], v31 offset:34816
	s_waitcnt lgkmcnt(0)
	v_mfma_f32_16x16x32_bf16 v[0:3], v[0:3], v[36:39], 0
	v_add_u32_e32 v27, 0x2200, v27
	s_mov_b64 s[6:7], 0
	s_mov_b32 s9, 0
	s_waitcnt vmcnt(0)
	v_lshlrev_b32_e32 v36, 16, v42
	v_and_b32_e32 v37, 0xffff0000, v42
	s_nop 1
	v_pk_add_f32 v[0:1], v[46:47], v[0:1] op_sel_hi:[0,1]
	v_pk_mul_f32 v[0:1], v[0:1], v[36:37]
	v_lshlrev_b32_e32 v36, 16, v43
	v_and_b32_e32 v37, 0xffff0000, v43
	v_pk_add_f32 v[2:3], v[46:47], v[2:3] op_sel_hi:[0,1]
	v_pk_mul_f32 v[2:3], v[2:3], v[36:37]
	v_cvt_pk_bf16_f32 v0, v0, v1
	v_cvt_pk_bf16_f32 v1, v2, v3
	global_store_dwordx2 v[40:41], v[0:1], off
	ds_read_b128 v[36:39], v23
	ds_read_b128 v[40:43], v31 offset:39168
	s_waitcnt lgkmcnt(0)
	v_mfma_f32_16x16x32_bf16 v[36:39], v[36:39], v[40:43], 0
	v_lshlrev_b32_e32 v2, 16, v50
	v_and_b32_e32 v3, 0xffff0000, v50
	v_mov_b32_e32 v0, 0
	s_nop 4
	v_pk_add_f32 v[36:37], v[48:49], v[36:37] op_sel_hi:[0,1]
	v_pk_mul_f32 v[2:3], v[36:37], v[2:3]
	v_lshlrev_b32_e32 v36, 16, v51
	v_and_b32_e32 v37, 0xffff0000, v51
	v_pk_add_f32 v[38:39], v[48:49], v[38:39] op_sel_hi:[0,1]
	v_pk_mul_f32 v[36:37], v[38:39], v[36:37]
	v_cvt_pk_bf16_f32 v2, v2, v3
	v_cvt_pk_bf16_f32 v3, v36, v37
	v_mul_u32_u24_e32 v23, 0x110, v11
	global_store_dwordx2 v[44:45], v[2:3], off
	v_mov_b32_e32 v1, v0
	v_mov_b32_e32 v2, v0
	v_mov_b32_e32 v3, v0
.LBB0_403:
	v_or_b32_e32 v31, s9, v160
	v_lshlrev_b32_e32 v31, 1, v31
	v_add_u32_e32 v35, v19, v31
	ds_read_b128 v[36:39], v35
	v_add_u32_e32 v31, v27, v31
	ds_read_b128 v[40:43], v31 offset:34816
	s_mov_b32 s9, 32
	s_andn2_b64 vcc, exec, s[6:7]
	s_mov_b64 s[6:7], -1
	s_waitcnt lgkmcnt(0)
	v_mfma_f32_16x16x32_bf16 v[0:3], v[36:39], v[40:43], v[0:3]
	s_cbranch_vccnz .LBB0_403
	v_or3_b32 v36, v11, s8, 32
	v_lshlrev_b32_e32 v38, 16, v32
	v_and_b32_e32 v39, 0xffff0000, v32
	s_nop 3
	v_pk_add_f32 v[0:1], v[34:35], v[0:1] op_sel_hi:[0,1]
	v_lshlrev_b32_e32 v32, 16, v33
	v_and_b32_e32 v33, 0xffff0000, v33
	v_pk_add_f32 v[2:3], v[34:35], v[2:3] op_sel_hi:[0,1]
	v_ashrrev_i32_e32 v37, 31, v36
	v_pk_mul_f32 v[0:1], v[0:1], v[38:39]
	v_pk_mul_f32 v[2:3], v[2:3], v[32:33]
	v_cvt_pk_bf16_f32 v0, v0, v1
	v_cvt_pk_bf16_f32 v1, v2, v3
	v_lshlrev_b64 v[2:3], 10, v[36:37]
	v_lshl_add_u64 v[2:3], v[4:5], 0, v[2:3]
	global_store_dwordx2 v[2:3], v[0:1], off
	v_mov_b32_e32 v0, 0
	v_add_u32_e32 v27, 0x1100, v27
	s_mov_b32 s9, 0
	s_mov_b64 s[6:7], 0
	v_mov_b32_e32 v1, v0
	v_mov_b32_e32 v2, v0
	v_mov_b32_e32 v3, v0
.LBB0_405:
	v_or_b32_e32 v31, s9, v160
	v_lshlrev_b32_e32 v31, 1, v31
	v_add_u32_e32 v32, v19, v31
	ds_read_b128 v[32:35], v32
	v_add_u32_e32 v31, v27, v31
	ds_read_b128 v[36:39], v31 offset:34816
	s_mov_b32 s9, 32
	s_andn2_b64 vcc, exec, s[6:7]
	s_mov_b64 s[6:7], -1
	s_waitcnt lgkmcnt(0)
	v_mfma_f32_16x16x32_bf16 v[0:3], v[32:35], v[36:39], v[0:3]
	s_cbranch_vccnz .LBB0_405
	v_or3_b32 v32, v11, s8, 48
	v_lshlrev_b32_e32 v34, 16, v28
	v_and_b32_e32 v35, 0xffff0000, v28
	s_nop 3
	v_pk_add_f32 v[0:1], v[30:31], v[0:1] op_sel_hi:[0,1]
	v_lshlrev_b32_e32 v28, 16, v29
	v_and_b32_e32 v29, 0xffff0000, v29
	v_pk_add_f32 v[2:3], v[30:31], v[2:3] op_sel_hi:[0,1]
	v_ashrrev_i32_e32 v33, 31, v32
	v_pk_mul_f32 v[0:1], v[0:1], v[34:35]
	v_pk_mul_f32 v[2:3], v[2:3], v[28:29]
	v_cvt_pk_bf16_f32 v0, v0, v1
	v_cvt_pk_bf16_f32 v1, v2, v3
	v_lshlrev_b64 v[2:3], 10, v[32:33]
	v_lshl_add_u64 v[2:3], v[4:5], 0, v[2:3]
	v_add_u32_e32 v19, v23, v15
	v_readlane_b32 s6, v254, 61
	global_store_dwordx2 v[2:3], v[0:1], off
	v_mov_b32_e32 v0, 0
	v_add_u32_e32 v27, s6, v19
	v_readlane_b32 s6, v254, 54
	v_mov_b32_e32 v1, v0
	v_mov_b32_e32 v2, v0
	v_add3_u32 v15, v23, v15, s6
	s_mov_b32 s6, 0
	v_mov_b32_e32 v3, v0
.LBB0_407:
	v_add_u32_e32 v23, s6, v15
	ds_read_b128 v[28:31], v23
	v_add_u32_e32 v23, s6, v27
	ds_read_b128 v[32:35], v23
	s_add_i32 s6, s6, 64
	s_cmpk_lg_i32 s6, 0xc0
	s_waitcnt lgkmcnt(0)
	v_mfma_f32_16x16x32_bf16 v[0:3], v[28:31], v[32:35], v[0:3]
	s_cbranch_scc1 .LBB0_407
	v_or3_b32 v28, v11, s8, 64
	v_lshlrev_b32_e32 v30, 16, v24
	v_and_b32_e32 v31, 0xffff0000, v24
	s_nop 3
	v_pk_add_f32 v[0:1], v[26:27], v[0:1] op_sel_hi:[0,1]
	v_lshlrev_b32_e32 v24, 16, v25
	v_and_b32_e32 v25, 0xffff0000, v25
	v_pk_add_f32 v[2:3], v[26:27], v[2:3] op_sel_hi:[0,1]
	v_ashrrev_i32_e32 v29, 31, v28
	v_pk_mul_f32 v[0:1], v[0:1], v[30:31]
	v_pk_mul_f32 v[2:3], v[2:3], v[24:25]
	v_cvt_pk_bf16_f32 v0, v0, v1
	v_cvt_pk_bf16_f32 v1, v2, v3
	v_lshlrev_b64 v[2:3], 10, v[28:29]
	v_lshl_add_u64 v[2:3], v[4:5], 0, v[2:3]
	global_store_dwordx2 v[2:3], v[0:1], off
	v_readlane_b32 s6, v254, 62
	v_mov_b32_e32 v0, 0
	v_mov_b32_e32 v1, v0
	v_add_u32_e32 v11, s6, v19
	s_mov_b32 s6, 0
	v_mov_b32_e32 v2, v0
	v_mov_b32_e32 v3, v0
.LBB0_409:
	v_add_u32_e32 v23, s6, v15
	ds_read_b128 v[24:27], v23
	v_add_u32_e32 v23, s6, v11
	ds_read_b128 v[28:31], v23
	s_add_i32 s6, s6, 64
	s_cmpk_lg_i32 s6, 0xc0
	s_waitcnt lgkmcnt(0)
	v_mfma_f32_16x16x32_bf16 v[0:3], v[24:27], v[28:31], v[0:3]
	s_cbranch_scc1 .LBB0_409
	v_or_b32_e32 v24, 0x50, v14
	v_lshlrev_b32_e32 v26, 16, v20
	v_and_b32_e32 v27, 0xffff0000, v20
	s_nop 3
	v_pk_add_f32 v[0:1], v[22:23], v[0:1] op_sel_hi:[0,1]
	v_lshlrev_b32_e32 v20, 16, v21
	v_and_b32_e32 v21, 0xffff0000, v21
	v_pk_add_f32 v[2:3], v[22:23], v[2:3] op_sel_hi:[0,1]
	v_ashrrev_i32_e32 v25, 31, v24
	v_pk_mul_f32 v[0:1], v[0:1], v[26:27]
	v_pk_mul_f32 v[2:3], v[2:3], v[20:21]
	v_cvt_pk_bf16_f32 v0, v0, v1
	v_cvt_pk_bf16_f32 v1, v2, v3
	v_lshlrev_b64 v[2:3], 10, v[24:25]
	v_lshl_add_u64 v[2:3], v[4:5], 0, v[2:3]
	global_store_dwordx2 v[2:3], v[0:1], off
	v_readlane_b32 s6, v254, 63
	v_mov_b32_e32 v0, 0
	v_mov_b32_e32 v1, v0
	v_add_u32_e32 v11, s6, v19
	s_mov_b32 s6, 0
	v_mov_b32_e32 v2, v0
	v_mov_b32_e32 v3, v0
.LBB0_411:
	v_add_u32_e32 v14, s6, v15
	ds_read_b128 v[20:23], v14
	v_add_u32_e32 v14, s6, v11
	ds_read_b128 v[24:27], v14
	s_add_i32 s6, s6, 64
	s_cmpk_lg_i32 s6, 0x100
	s_waitcnt lgkmcnt(0)
	v_mfma_f32_16x16x32_bf16 v[0:3], v[20:23], v[24:27], v[0:3]
	s_cbranch_scc1 .LBB0_411
	v_lshlrev_b32_e32 v20, 16, v16
	v_and_b32_e32 v21, 0xffff0000, v16
	s_nop 4
	v_pk_add_f32 v[0:1], v[18:19], v[0:1] op_sel_hi:[0,1]
	v_lshlrev_b32_e32 v16, 16, v17
	v_and_b32_e32 v17, 0xffff0000, v17
	v_pk_add_f32 v[2:3], v[18:19], v[2:3] op_sel_hi:[0,1]
	v_pk_mul_f32 v[0:1], v[0:1], v[20:21]
	v_pk_mul_f32 v[2:3], v[2:3], v[16:17]
	v_cvt_pk_bf16_f32 v0, v0, v1
	v_cvt_pk_bf16_f32 v1, v2, v3
	v_lshlrev_b64 v[2:3], 10, v[12:13]
	v_lshl_add_u64 v[2:3], v[4:5], 0, v[2:3]
	global_store_dwordx2 v[2:3], v[0:1], off
	v_readlane_b32 s6, v252, 0
	v_mov_b32_e32 v0, 0
	v_mov_b32_e32 v1, v0
	v_add_u32_e32 v11, s6, v19
	s_mov_b32 s6, 0
	v_mov_b32_e32 v2, v0
	v_mov_b32_e32 v3, v0
.LBB0_413:
	v_add_u32_e32 v12, s6, v15
	ds_read_b128 v[16:19], v12
	v_add_u32_e32 v12, s6, v11
	ds_read_b128 v[20:23], v12
	s_add_i32 s6, s6, 64
	s_cmpk_lg_i32 s6, 0x100
	s_waitcnt lgkmcnt(0)
	v_mfma_f32_16x16x32_bf16 v[0:3], v[16:19], v[20:23], v[0:3]
	s_cbranch_scc1 .LBB0_413
	v_lshlrev_b32_e32 v12, 16, v8
	v_and_b32_e32 v13, 0xffff0000, v8
	s_nop 4
	v_pk_add_f32 v[0:1], v[10:11], v[0:1] op_sel_hi:[0,1]
	v_lshlrev_b32_e32 v8, 16, v9
	v_and_b32_e32 v9, 0xffff0000, v9
	v_pk_add_f32 v[2:3], v[10:11], v[2:3] op_sel_hi:[0,1]
	v_pk_mul_f32 v[0:1], v[0:1], v[12:13]
	v_pk_mul_f32 v[2:3], v[2:3], v[8:9]
	v_cvt_pk_bf16_f32 v0, v0, v1
	v_cvt_pk_bf16_f32 v1, v2, v3
	v_lshlrev_b64 v[2:3], 10, v[6:7]
	s_add_i32 s2, s2, 1
	v_lshl_add_u64 v[2:3], v[4:5], 0, v[2:3]
	s_cmp_eq_u32 s2, 16
	global_store_dwordx2 v[2:3], v[0:1], off
	s_cbranch_scc0 .LBB0_402
	s_mov_b64 s[0:1], 0

.LBB0_424:
	v_mul_hi_i32 v3, v2, s16
	v_lshrrev_b32_e32 v4, 31, v3
	v_ashrrev_i32_e32 v3, 8, v3
	v_add_u32_e32 v3, v3, v4
	v_mul_i32_i24_e32 v4, 0x280, v3
	v_sub_u32_e32 v4, v2, v4
	v_ashrrev_i32_e32 v4, 7, v4
	v_cmp_gt_i32_e32 vcc, 4, v4
	v_lshlrev_b32_e32 v4, 10, v4
	v_and_b32_e32 v6, 0x7f, v2
	v_cndmask_b32_e32 v4, 0, v4, vcc
	v_lshl_add_u32 v3, v3, 9, v4
	v_mov_b32_e32 v4, s14
	v_mov_b32_e32 v5, s12
	v_cndmask_b32_e32 v5, v4, v5, vcc
	v_mov_b32_e32 v4, s13
	v_mov_b32_e32 v7, s11
	v_or3_b32 v6, v3, v6, s15
	v_cndmask_b32_e32 v4, v4, v7, vcc
	v_ashrrev_i32_e32 v7, 31, v6
	v_lshl_add_u64 v[4:5], v[6:7], 2, v[4:5]
	global_load_dword v3, v[4:5], off
	v_cmp_lt_i32_e32 vcc, s17, v2
	s_or_b64 s[6:7], vcc, s[6:7]
	s_waitcnt vmcnt(0) lgkmcnt(0)
	ds_write_b32 v1, v3
	v_add_u32_e32 v3, 0x200, v2
	v_add_u32_e32 v1, 0x800, v1
	v_mov_b32_e32 v2, v3
	s_andn2_b64 exec, exec, s[6:7]
	s_cbranch_execnz .LBB0_424
.LBB0_425:
	s_or_b64 exec, exec, s[4:5]
	s_add_u32 s6, s0, 0x1d200000
	s_addc_u32 s7, s1, 0
	s_add_u32 s4, s0, 0x2f200000
	v_readlane_b32 s11, v252, 31
	s_addc_u32 s5, s1, 0
	s_lshl_b32 s12, s11, 3
	s_ashr_i32 s13, s12, 31
	s_lshl_b64 s[12:13], s[12:13], 2
	s_add_u32 s14, s8, s12
	s_addc_u32 s2, s2, s13
	s_lshl_b32 s12, s11, 9
	v_ashrrev_i32_e32 v58, 2, v0
	s_ashr_i32 s13, s12, 31
	v_and_b32_e32 v59, -8, v58
	v_readlane_b32 s16, v253, 55
	s_lshl_b64 s[12:13], s[12:13], 2
	v_lshlrev_b32_e32 v1, 1, v48
	v_add_u32_e32 v0, s16, v59
	s_add_u32 s12, s10, s12
	v_and_b32_e32 v172, 62, v1
	v_ashrrev_i32_e32 v1, 31, v0
	s_addc_u32 s13, s9, s13
	v_lshl_add_u64 v[0:1], v[0:1], 1, s[0:1]
	s_mov_b64 s[8:9], 0x21200000
	v_add_u32_e32 v173, -3, v172
	v_lshl_add_u64 v[116:117], v[0:1], 0, s[8:9]
	s_mov_b64 s[8:9], 0x25200000
	v_lshl_add_u64 v[118:119], v[0:1], 0, s[8:9]
	v_max_i32_e32 v0, 0, v173
	v_readlane_b32 s15, v253, 58
	v_and_b32_e32 v170, 63, v48
	s_lshl_b32 s82, s16, 1
	v_add_u32_e32 v0, s15, v0
	v_ashrrev_i32_e32 v1, 31, v0
	v_lshlrev_b64 v[0:1], 10, v[0:1]
	v_lshl_add_u64 v[2:3], v[116:117], 0, v[0:1]
	v_lshl_add_u64 v[0:1], v[118:119], 0, v[0:1]
	global_load_dwordx4 v[28:31], v[2:3], off
	global_load_dwordx4 v[24:27], v[0:1], off
	v_sub_u32_e64 v0, v172, 2 clamp
	v_or_b32_e32 v0, s15, v0
	v_ashrrev_i32_e32 v1, 31, v0
	v_lshlrev_b64 v[0:1], 10, v[0:1]
	v_lshl_add_u64 v[2:3], v[116:117], 0, v[0:1]
	v_lshl_add_u64 v[0:1], v[118:119], 0, v[0:1]
	global_load_dwordx4 v[32:35], v[2:3], off
	global_load_dwordx4 v[8:11], v[0:1], off
	v_sub_u32_e64 v0, v172, 1 clamp
	v_or_b32_e32 v0, s15, v0
	v_ashrrev_i32_e32 v1, 31, v0
	v_lshlrev_b64 v[0:1], 10, v[0:1]
	v_or_b32_e32 v120, s15, v172
	v_lshl_add_u64 v[2:3], v[116:117], 0, v[0:1]
	v_lshl_add_u64 v[0:1], v[118:119], 0, v[0:1]
	v_ashrrev_i32_e32 v121, 31, v120
	global_load_dwordx4 v[36:39], v[2:3], off
	global_load_dwordx4 v[12:15], v[0:1], off
	v_lshlrev_b64 v[0:1], 10, v[120:121]
	v_lshl_add_u64 v[2:3], v[116:117], 0, v[0:1]
	v_lshl_add_u64 v[0:1], v[118:119], 0, v[0:1]
	global_load_dwordx4 v[40:43], v[2:3], off
	global_load_dwordx4 v[16:19], v[0:1], off
	v_or_b32_e32 v0, 1, v120
	v_ashrrev_i32_e32 v1, 31, v0
	v_lshlrev_b64 v[0:1], 10, v[0:1]
	v_or_b32_e32 v50, s15, v170
	v_lshl_add_u64 v[2:3], v[116:117], 0, v[0:1]
	v_lshl_add_u64 v[0:1], v[118:119], 0, v[0:1]
	v_ashrrev_i32_e32 v51, 31, v50
	global_load_dwordx4 v[44:47], v[2:3], off
	global_load_dwordx4 v[20:23], v[0:1], off
	v_lshlrev_b64 v[0:1], 10, v[50:51]
	v_lshl_add_u64 v[0:1], s[6:7], 0, v[0:1]
	v_readlane_b32 s18, v253, 39
	v_lshl_add_u64 v[0:1], v[0:1], 0, s[82:83]
	s_lshl_b32 s8, s18, 1
	s_mov_b32 s9, s83
	v_lshl_add_u64 v[0:1], v[0:1], 0, s[8:9]
	v_readlane_b32 s9, v253, 54
	s_lshl_b32 s10, s9, 2
	s_add_u32 s0, s0, s82
	v_and_b32_e32 v171, 15, v48
	s_addc_u32 s1, s1, 0
	v_bfe_u32 v49, v48, 4, 2
	v_or_b32_e32 v52, s15, v171
	s_add_u32 s0, s0, s8
	v_lshlrev_b64 v[50:51], 7, v[50:51]
	s_addc_u32 s1, s1, 0
	v_lshlrev_b32_e32 v160, 3, v49
	v_or_b32_e32 v56, 16, v52
	v_lshl_add_u64 v[50:51], s[4:5], 0, v[50:51]
	s_mov_b32 s11, s83
	v_lshl_add_u64 v[54:55], s[0:1], 0, v[160:161]
	s_mov_b64 s[0:1], 0x11200000
	v_ashrrev_i32_e32 v53, 31, v52
	v_ashrrev_i32_e32 v57, 31, v56
	v_lshl_add_u64 v[50:51], v[50:51], 0, s[10:11]
	v_lshl_add_u64 v[122:123], v[54:55], 0, s[0:1]
	v_lshlrev_b64 v[54:55], 10, v[52:53]
	v_lshlrev_b64 v[56:57], 10, v[56:57]
	global_load_dwordx4 v[4:7], v[0:1], off
	s_nop 0
	global_load_dwordx4 v[0:3], v[0:1], off offset:16
	v_lshl_add_u64 v[54:55], v[122:123], 0, v[54:55]
	v_lshl_add_u64 v[56:57], v[122:123], 0, v[56:57]
	global_load_dword v196, v[50:51], off
	global_load_dword v204, v[50:51], off offset:16
	global_load_dwordx2 v[142:143], v[54:55], off
	global_load_dwordx2 v[140:141], v[56:57], off
	v_or_b32_e32 v50, 32, v52
	v_ashrrev_i32_e32 v51, 31, v50
	v_or_b32_e32 v52, 48, v52
	v_lshlrev_b64 v[50:51], 10, v[50:51]
	v_ashrrev_i32_e32 v53, 31, v52
	v_lshl_add_u64 v[50:51], v[122:123], 0, v[50:51]
	v_lshlrev_b64 v[52:53], 10, v[52:53]
	v_lshl_add_u64 v[52:53], v[122:123], 0, v[52:53]
	global_load_dwordx2 v[138:139], v[50:51], off
	global_load_dwordx2 v[128:129], v[52:53], off
	s_add_u32 s0, s6, s82
	s_addc_u32 s1, s7, 0
	s_add_u32 s22, s0, s8
	s_addc_u32 s23, s1, 0
	v_lshlrev_b32_e32 v50, 2, v59
	v_readlane_b32 s0, v254, 57
	s_add_u32 s24, s4, s10
	s_addc_u32 s25, s5, 0
	v_add_u32_e32 v121, s0, v50
	v_readlane_b32 s0, v254, 56
	v_lshlrev_b32_e32 v52, 2, v171
	v_and_b32_e32 v124, 48, v48
	v_lshl_add_u32 v175, v170, 3, s0
	v_readlane_b32 s0, v254, 58
	v_or_b32_e32 v48, s18, v171
	s_add_u32 s26, s14, s10
	v_add_u32_e32 v176, s0, v52
	v_mul_lo_u32 v53, v48, s93
	v_readlane_b32 s0, v254, 51
	s_addc_u32 s27, s2, 0
	v_mov_b32_e32 v125, v161
	v_add3_u32 v178, s0, v53, v124
	v_mov_b32_e32 v53, s0
	s_lshl_b32 s0, s16, 2
	s_add_u32 s0, s12, s0
	s_addc_u32 s1, s13, 0
	s_lshl_b32 s2, s18, 2
	s_add_u32 s0, s0, s2
	s_addc_u32 s1, s1, 0
	v_mad_u32_u24 v53, v171, s93, v53
	v_lshl_add_u64 v[126:127], s[0:1], 0, v[124:125]
	s_movk_i32 s0, 0xfef2
	v_mad_i32_i24 v86, v171, s0, v53
	v_readlane_b32 s0, v253, 43
	s_movk_i32 s8, 0x90
	v_lshlrev_b32_e32 v60, 2, v49
	v_lshl_add_u32 v182, v171, 1, s0
	v_readlane_b32 s0, v254, 59
	v_mul_u32_u24_e32 v51, 0x110, v172
	v_mul_lo_u32 v48, v48, s8
	v_add_u32_e32 v183, s0, v50
	v_readlane_b32 s0, v254, 60
	v_lshl_add_u32 v125, v49, 5, s33
	v_lshlrev_b32_e32 v49, 1, v59
	v_add_u32_e32 v185, s0, v50
	v_readlane_b32 s0, v253, 44
	v_add3_u32 v181, 0, v48, v160
	v_or_b32_e32 v48, s18, v60
	v_add3_u32 v184, 0, v51, v49
	v_or_b32_e32 v49, 7, v58
	v_lshl_add_u32 v186, v170, 1, s0
	v_or_b32_e32 v188, 16, v171
	v_readlane_b32 s0, v254, 55
	v_lshl_add_u32 v84, v172, 1, 0
	v_add_u32_e32 v177, 0, v124
	v_mul_u32_u24_e32 v85, 0x110, v171
	v_mul_lo_u32 v87, v59, s8
	v_mul_lo_u32 v88, v49, s8
	v_or_b32_e32 v49, s57, v171
	v_mul_u32_u24_e32 v89, 0x110, v188
	v_or_b32_e32 v189, 32, v171
	v_or_b32_e32 v190, 48, v171
	v_mul_u32_u24_e32 v90, 0x90, v171
	v_mul_lo_u32 v91, v48, s93
	v_mov_b32_e32 v48, s0
	s_mov_b32 s28, 0
	v_lshl_add_u32 v174, v170, 2, s33
	v_cmp_gt_u32_e64 s[4:5], 16, v170
	v_add_u32_e32 v179, v53, v124
	v_add_u32_e32 v180, s33, v52
	v_cmp_eq_u32_e64 s[6:7], 0, v171
	v_cmp_eq_u32_e64 s[8:9], 0, v170
	v_cmp_gt_u32_e64 s[10:11], 2, v170
	v_cmp_gt_u32_e64 s[12:13], 4, v170
	v_cmp_gt_u32_e64 s[14:15], 8, v170
	v_cmp_gt_u32_e64 s[16:17], 32, v170
	v_lshlrev_b32_e32 v187, 3, v49
	v_lshlrev_b32_e32 v191, 3, v171
	v_lshlrev_b32_e32 v192, 3, v188
	v_lshlrev_b32_e32 v193, 3, v189
	v_lshlrev_b32_e32 v194, 3, v190
	v_add_u32_e32 v195, s18, v60
	v_mad_u32_u24 v197, v171, s93, v48
	v_mov_b32_e32 v48, 0
	v_mov_b32_e32 v49, 0
	v_mov_b32_e32 v50, 0
	v_mov_b32_e32 v51, 0
	v_mov_b32_e32 v76, 0
	v_mov_b32_e32 v77, 0
	v_mov_b32_e32 v78, 0
	v_mov_b32_e32 v79, 0
	v_mov_b32_e32 v72, 0
	v_mov_b32_e32 v73, 0
	v_mov_b32_e32 v74, 0
	v_mov_b32_e32 v75, 0
	v_mov_b32_e32 v68, 0
	v_mov_b32_e32 v69, 0
	v_mov_b32_e32 v70, 0
	v_mov_b32_e32 v71, 0
	v_mov_b32_e32 v64, 0
	v_mov_b32_e32 v65, 0
	v_mov_b32_e32 v66, 0
	v_mov_b32_e32 v67, 0
	v_mov_b32_e32 v60, 0
	v_mov_b32_e32 v61, 0
	v_mov_b32_e32 v62, 0
	v_mov_b32_e32 v63, 0
	v_mov_b32_e32 v56, 0
	v_mov_b32_e32 v57, 0
	v_mov_b32_e32 v58, 0
	v_mov_b32_e32 v59, 0
	v_mov_b32_e32 v52, 0
	v_mov_b32_e32 v53, 0
	v_mov_b32_e32 v54, 0
	v_mov_b32_e32 v55, 0
	v_mov_b32_e32 v80, 0
	v_mov_b32_e32 v81, 0
	v_mov_b32_e32 v82, 0
	v_mov_b32_e32 v83, 0
	v_add_u32_e32 v198, v84, v87
	v_add_u32_e32 v199, v84, v88
	v_add_u32_e32 v200, v177, v85
	v_add_u32_e32 v201, v177, v90
	v_add_u32_e32 v202, v86, v91
	v_add_u32_e32 v203, v177, v89
	s_mov_b32 s2, 0
	s_branch .LBB0_427

.LBB0_427:
	s_lshl_b32 s29, s2, 6
	s_waitcnt lgkmcnt(0)
	s_barrier
	v_or_b32_e32 v136, s29, v172
	ds_read_b128 v[94:97], v183
	ds_read_b128 v[84:87], v183 offset:16
	ds_read_b128 v[98:101], v121
	ds_read_b128 v[88:91], v121 offset:16
	ds_read_b128 v[102:105], v121 offset:512
	ds_read_b128 v[106:109], v121 offset:1024
	ds_read_b128 v[110:113], v121 offset:1536
	s_waitcnt vmcnt(0) lgkmcnt(0)
	v_lshlrev_b32_e32 v92, 16, v32
	v_and_b32_e32 v32, 0xffff0000, v32
	v_cmp_eq_u32_e32 vcc, 0, v136
	v_lshlrev_b32_e32 v130, 16, v40
	v_and_b32_e32 v131, 0xffff0000, v40
	v_cndmask_b32_e64 v93, v32, 0, vcc
	v_cndmask_b32_e64 v92, v92, 0, vcc
	v_lshlrev_b32_e32 v32, 16, v36
	v_and_b32_e32 v36, 0xffff0000, v36
	v_cndmask_b32_e64 v115, v36, 0, vcc
	v_cndmask_b32_e64 v114, v32, 0, vcc
	v_pk_fma_f32 v[134:135], v[92:93], v[98:99], v[94:95]
	v_lshlrev_b32_e32 v132, 16, v44
	v_pk_fma_f32 v[134:135], v[114:115], v[102:103], v[134:135]
	v_and_b32_e32 v133, 0xffff0000, v44
	v_pk_fma_f32 v[134:135], v[106:107], v[130:131], v[134:135]
	v_lshlrev_b32_e32 v36, 16, v28
	v_pk_fma_f32 v[144:145], v[110:111], v[132:133], v[134:135]
	v_and_b32_e32 v28, 0xffff0000, v28
	v_cmp_lt_u32_e64 s[18:19], 2, v136
	v_mul_f32_e32 v32, 0xbfb8aa3b, v144
	v_exp_f32_e32 v32, v32
	v_cndmask_b32_e64 v133, 0, v28, s[18:19]
	v_cndmask_b32_e64 v132, 0, v36, s[18:19]
	v_pk_fma_f32 v[94:95], v[132:133], v[98:99], v[94:95]
	v_add_f32_e32 v32, 1.0, v32
	v_pk_fma_f32 v[92:93], v[92:93], v[102:103], v[94:95]
	v_rcp_f32_e32 v102, v32
	v_pk_fma_f32 v[92:93], v[114:115], v[106:107], v[92:93]
	v_mul_f32_e32 v36, 0xbfb8aa3b, v145
	v_pk_fma_f32 v[98:99], v[110:111], v[130:131], v[92:93]
	v_exp_f32_e32 v36, v36
	v_mul_f32_e32 v28, 0xbfb8aa3b, v98
	v_exp_f32_e32 v28, v28
	v_mul_f32_e32 v32, 0xbfb8aa3b, v99
	v_exp_f32_e32 v32, v32
	v_lshlrev_b32_e32 v40, 16, v41
	v_add_f32_e32 v28, 1.0, v28
	v_rcp_f32_e32 v106, v28
	v_add_f32_e32 v28, 1.0, v32
	v_rcp_f32_e32 v107, v28
	v_add_f32_e32 v28, 1.0, v36
	v_rcp_f32_e32 v103, v28
	v_lshlrev_b32_e32 v28, 16, v33
	v_and_b32_e32 v32, 0xffff0000, v33
	v_cndmask_b32_e64 v33, v32, 0, vcc
	v_cndmask_b32_e64 v32, v28, 0, vcc
	v_lshlrev_b32_e32 v28, 16, v37
	v_and_b32_e32 v36, 0xffff0000, v37
	v_cndmask_b32_e64 v37, v36, 0, vcc
	v_cndmask_b32_e64 v36, v28, 0, vcc
	v_lshlrev_b32_e32 v28, 16, v29
	v_and_b32_e32 v29, 0xffff0000, v29
	v_cndmask_b32_e64 v29, 0, v29, s[18:19]
	v_cndmask_b32_e64 v28, 0, v28, s[18:19]
	v_pk_fma_f32 v[28:29], v[28:29], v[100:101], v[96:97]
	v_and_b32_e32 v41, 0xffff0000, v41
	v_pk_fma_f32 v[28:29], v[32:33], v[104:105], v[28:29]
	v_pk_mul_f32 v[98:99], v[98:99], v[106:107]
	v_pk_fma_f32 v[28:29], v[36:37], v[108:109], v[28:29]
	v_pk_fma_f32 v[106:107], v[32:33], v[100:101], v[96:97]
	v_pk_fma_f32 v[28:29], v[112:113], v[40:41], v[28:29]
	v_pk_fma_f32 v[106:107], v[36:37], v[104:105], v[106:107]
	v_mul_f32_e32 v32, 0xbfb8aa3b, v28
	v_mul_f32_e32 v33, 0xbfb8aa3b, v29
	v_exp_f32_e32 v32, v32
	v_exp_f32_e32 v33, v33
	v_lshlrev_b32_e32 v44, 16, v45
	v_and_b32_e32 v45, 0xffff0000, v45
	v_pk_fma_f32 v[106:107], v[108:109], v[40:41], v[106:107]
	v_add_f32_e32 v32, 1.0, v32
	v_pk_fma_f32 v[44:45], v[112:113], v[44:45], v[106:107]
	v_add_f32_e32 v33, 1.0, v33
	v_mul_f32_e32 v37, 0xbfb8aa3b, v45
	v_rcp_f32_e32 v32, v32
	v_rcp_f32_e32 v33, v33
	v_exp_f32_e32 v37, v37
	ds_read_b128 v[92:95], v121 offset:528
	ds_read_b128 v[130:133], v121 offset:1040
	ds_read_b128 v[134:137], v121 offset:1552
	v_pk_mul_f32 v[32:33], v[28:29], v[32:33]
	v_add_f32_e32 v28, 1.0, v37
	v_rcp_f32_e32 v37, v28
	v_lshlrev_b32_e32 v28, 16, v34
	v_and_b32_e32 v29, 0xffff0000, v34
	v_cndmask_b32_e64 v29, v29, 0, vcc
	v_cndmask_b32_e64 v28, v28, 0, vcc
	v_lshlrev_b32_e32 v34, 16, v38
	v_and_b32_e32 v38, 0xffff0000, v38
	v_cndmask_b32_e64 v41, v38, 0, vcc
	v_cndmask_b32_e64 v40, v34, 0, vcc
	v_pk_fma_f32 v[104:105], v[28:29], v[88:89], v[84:85]
	v_lshlrev_b32_e32 v96, 16, v42
	v_and_b32_e32 v97, 0xffff0000, v42
	s_waitcnt lgkmcnt(2)
	v_pk_fma_f32 v[104:105], v[40:41], v[92:93], v[104:105]
	v_lshlrev_b32_e32 v100, 16, v46
	v_and_b32_e32 v101, 0xffff0000, v46
	s_waitcnt lgkmcnt(1)
	v_pk_fma_f32 v[104:105], v[130:131], v[96:97], v[104:105]
	v_lshlrev_b32_e32 v38, 16, v30
	v_and_b32_e32 v30, 0xffff0000, v30
	s_waitcnt lgkmcnt(0)
	v_pk_fma_f32 v[100:101], v[134:135], v[100:101], v[104:105]
	v_cndmask_b32_e64 v105, 0, v30, s[18:19]
	v_cndmask_b32_e64 v104, 0, v38, s[18:19]
	v_pk_fma_f32 v[84:85], v[104:105], v[88:89], v[84:85]
	v_mul_f32_e32 v34, 0xbfb8aa3b, v100
	v_pk_fma_f32 v[28:29], v[28:29], v[92:93], v[84:85]
	v_exp_f32_e32 v34, v34
	v_pk_fma_f32 v[28:29], v[40:41], v[130:131], v[28:29]
	v_mul_f32_e32 v106, 0xbfb8aa3b, v44
	v_pk_fma_f32 v[28:29], v[134:135], v[96:97], v[28:29]
	v_exp_f32_e32 v36, v106
	v_mul_f32_e32 v30, 0xbfb8aa3b, v28
	v_exp_f32_e32 v38, v30
	v_add_f32_e32 v30, 1.0, v34
	v_add_f32_e32 v36, 1.0, v36
	v_rcp_f32_e32 v36, v36
	v_add_f32_e32 v34, 1.0, v38
	v_mul_f32_e32 v38, 0xbfb8aa3b, v29
	v_exp_f32_e32 v38, v38
	v_mul_f32_e32 v40, 0xbfb8aa3b, v101
	v_exp_f32_e32 v42, v40
	v_rcp_f32_e32 v40, v34
	v_add_f32_e32 v34, 1.0, v38
	v_rcp_f32_e32 v41, v34
	v_lshlrev_b32_e32 v34, 16, v35
	v_and_b32_e32 v35, 0xffff0000, v35
	v_cndmask_b32_e64 v35, v35, 0, vcc
	v_cndmask_b32_e64 v34, v34, 0, vcc
	v_lshlrev_b32_e32 v38, 16, v39
	v_and_b32_e32 v39, 0xffff0000, v39
	v_pk_mul_f32 v[36:37], v[44:45], v[36:37]
	v_cndmask_b32_e64 v39, v39, 0, vcc
	v_cndmask_b32_e64 v38, v38, 0, vcc
	v_lshlrev_b32_e32 v44, 16, v47
	v_and_b32_e32 v45, 0xffff0000, v47
	v_pk_fma_f32 v[46:47], v[34:35], v[90:91], v[86:87]
	v_add_f32_e32 v84, 1.0, v42
	v_lshlrev_b32_e32 v42, 16, v43
	v_and_b32_e32 v43, 0xffff0000, v43
	v_pk_fma_f32 v[46:47], v[38:39], v[94:95], v[46:47]
	v_rcp_f32_e32 v30, v30
	v_pk_fma_f32 v[46:47], v[132:133], v[42:43], v[46:47]
	v_pk_mul_f32 v[40:41], v[28:29], v[40:41]
	v_pk_fma_f32 v[44:45], v[136:137], v[44:45], v[46:47]
	v_pk_mul_f32 v[102:103], v[144:145], v[102:103]
	v_mul_f32_e32 v46, 0xbfb8aa3b, v44
	v_exp_f32_e32 v85, v46
	v_lshlrev_b32_e32 v46, 16, v31
	v_and_b32_e32 v31, 0xffff0000, v31
	v_cndmask_b32_e64 v47, 0, v31, s[18:19]
	v_cndmask_b32_e64 v46, 0, v46, s[18:19]
	v_pk_fma_f32 v[46:47], v[46:47], v[90:91], v[86:87]
	v_cvt_pk_bf16_f32 v28, v98, v99
	v_pk_fma_f32 v[34:35], v[34:35], v[94:95], v[46:47]
	v_cvt_pk_bf16_f32 v29, v32, v33
	v_pk_fma_f32 v[34:35], v[38:39], v[132:133], v[34:35]
	v_add_f32_e32 v38, 1.0, v85
	v_pk_fma_f32 v[34:35], v[136:137], v[42:43], v[34:35]
	v_rcp_f32_e32 v38, v38
	v_mul_f32_e32 v31, 0xbfb8aa3b, v34
	v_exp_f32_e32 v39, v31
	v_mul_f32_e32 v42, 0xbfb8aa3b, v35
	v_exp_f32_e32 v43, v42
	v_mul_f32_e32 v42, 0xbfb8aa3b, v45
	v_exp_f32_e32 v46, v42
	v_add_f32_e32 v39, 1.0, v39
	v_rcp_f32_e32 v42, v39
	v_add_f32_e32 v39, 1.0, v43
	v_rcp_f32_e32 v43, v39
	v_add_f32_e32 v39, 1.0, v46
	v_rcp_f32_e32 v31, v84
	v_rcp_f32_e32 v39, v39
	v_pk_mul_f32 v[34:35], v[34:35], v[42:43]
	v_cvt_pk_bf16_f32 v32, v102, v103
	v_pk_mul_f32 v[46:47], v[100:101], v[30:31]
	v_pk_mul_f32 v[38:39], v[44:45], v[38:39]
	v_cvt_pk_bf16_f32 v30, v40, v41
	v_cvt_pk_bf16_f32 v31, v34, v35
	v_cvt_pk_bf16_f32 v33, v36, v37
	v_cvt_pk_bf16_f32 v34, v46, v47
	v_cvt_pk_bf16_f32 v35, v38, v39
	ds_write_b128 v184, v[28:31]
	ds_write_b128 v184, v[32:35] offset:272
	v_lshlrev_b32_e32 v28, 16, v24
	v_and_b32_e32 v24, 0xffff0000, v24
	v_cndmask_b32_e64 v106, 0, v24, s[18:19]
	v_and_b32_e32 v24, 0xffff0000, v25
	v_cndmask_b32_e64 v44, 0, v28, s[18:19]
	v_lshlrev_b32_e32 v28, 16, v25
	v_lshlrev_b32_e32 v25, 16, v26
	v_cndmask_b32_e64 v110, 0, v24, s[18:19]
	v_and_b32_e32 v24, 0xffff0000, v26
	v_lshlrev_b32_e32 v45, 16, v8
	v_cndmask_b32_e64 v112, 0, v25, s[18:19]
	v_lshlrev_b32_e32 v25, 16, v27
	v_cndmask_b32_e64 v114, 0, v24, s[18:19]
	v_and_b32_e32 v24, 0xffff0000, v27
	v_cndmask_b32_e64 v130, v45, 0, vcc
	v_cndmask_b32_e64 v108, 0, v28, s[18:19]
	v_cndmask_b32_e64 v84, 0, v25, s[18:19]
	v_cndmask_b32_e64 v46, 0, v24, s[18:19]
	ds_read_b128 v[86:89], v185
	ds_read_b128 v[32:35], v185 offset:16
	ds_read_b128 v[90:93], v121 offset:2560
	ds_read_b128 v[40:43], v121 offset:2576
	ds_read_b128 v[94:97], v121 offset:3072
	ds_read_b128 v[36:39], v121 offset:3088
	ds_read_b128 v[98:101], v121 offset:3584
	ds_read_b128 v[24:27], v121 offset:3600
	ds_read_b128 v[102:105], v121 offset:4096
	ds_read_b128 v[28:31], v121 offset:4112
	v_and_b32_e32 v8, 0xffff0000, v8
	v_mov_b32_e32 v45, v130
	s_waitcnt lgkmcnt(7)
	v_mov_b32_e32 v146, v90
	s_waitcnt lgkmcnt(5)
	v_mov_b32_e32 v147, v94
	v_cndmask_b32_e64 v131, v8, 0, vcc
	v_lshlrev_b32_e32 v8, 16, v12
	v_pk_mul_f32 v[44:45], v[44:45], v[146:147]
	v_cndmask_b32_e64 v132, v8, 0, vcc
	v_add_f32_e32 v8, v86, v44
	v_add_f32_e32 v8, v8, v45
	v_mov_b32_e32 v107, v131
	v_mov_b32_e32 v44, v91
	v_mov_b32_e32 v45, v95
	v_and_b32_e32 v12, 0xffff0000, v12
	v_lshlrev_b32_e32 v134, 16, v16
	v_pk_mul_f32 v[44:45], v[106:107], v[44:45]
	v_cndmask_b32_e64 v133, v12, 0, vcc
	v_pk_fma_f32 v[144:145], v[130:131], v[90:91], v[86:87]
	v_add_f32_e32 v12, v87, v44
	v_mov_b32_e32 v86, v132
	s_waitcnt lgkmcnt(1)
	v_mov_b32_e32 v87, v102
	v_mov_b32_e32 v90, v98
	v_mov_b32_e32 v91, v134
	v_pk_mul_f32 v[86:87], v[86:87], v[90:91]
	v_and_b32_e32 v135, 0xffff0000, v16
	v_add_f32_e32 v8, v8, v86
	v_add_f32_e32 v8, v8, v87
	v_mul_f32_e32 v16, 0xbfb8aa3b, v8
	v_exp_f32_e32 v16, v16
	v_add_f32_e32 v12, v12, v45
	v_pk_fma_f32 v[44:45], v[132:133], v[94:95], v[144:145]
	v_lshlrev_b32_e32 v136, 16, v20
	v_and_b32_e32 v137, 0xffff0000, v20
	v_pk_fma_f32 v[44:45], v[98:99], v[134:135], v[44:45]
	v_add_f32_e32 v16, 1.0, v16
	v_pk_fma_f32 v[44:45], v[102:103], v[136:137], v[44:45]
	v_mov_b32_e32 v86, v133
	v_mul_f32_e32 v20, 0xbfb8aa3b, v44
	v_mov_b32_e32 v87, v103
	v_mov_b32_e32 v134, v99
	v_rcp_f32_e32 v16, v16
	v_exp_f32_e32 v20, v20
	v_pk_mul_f32 v[86:87], v[86:87], v[134:135]
	v_mul_f32_e32 v47, 0xbfb8aa3b, v45
	v_add_f32_e32 v12, v12, v86
	v_add_f32_e32 v12, v12, v87
	v_mul_f32_e32 v8, v8, v16
	v_add_f32_e32 v16, 1.0, v20
	v_mul_f32_e32 v20, 0xbfb8aa3b, v12
	v_exp_f32_e32 v20, v20
	v_rcp_f32_e32 v86, v16
	v_exp_f32_e32 v47, v47
	v_mul_f32_e32 v94, 0x3db504f3, v8
	v_add_f32_e32 v16, 1.0, v20
	v_rcp_f32_e32 v16, v16
	v_add_f32_e32 v20, 1.0, v47
	v_rcp_f32_e32 v87, v20
	v_mov_b32_e32 v90, v92
	v_mul_f32_e32 v8, v12, v16
	v_mul_f32_e32 v95, 0x3db504f3, v8
	v_lshlrev_b32_e32 v8, 16, v9
	v_cndmask_b32_e64 v8, v8, 0, vcc
	v_and_b32_e32 v9, 0xffff0000, v9
	v_mov_b32_e32 v109, v8
	v_mov_b32_e32 v91, v96
	v_cndmask_b32_e64 v9, v9, 0, vcc
	v_pk_mul_f32 v[90:91], v[108:109], v[90:91]
	v_pk_mul_f32 v[44:45], v[44:45], v[86:87]
	v_pk_fma_f32 v[86:87], v[8:9], v[92:93], v[88:89]
	v_add_f32_e32 v8, v88, v90
	v_add_f32_e32 v47, v8, v91
	v_mov_b32_e32 v111, v9
	v_mov_b32_e32 v8, v93
	v_mov_b32_e32 v9, v97
	v_lshlrev_b32_e32 v12, 16, v13
	v_and_b32_e32 v13, 0xffff0000, v13
	v_pk_mul_f32 v[8:9], v[110:111], v[8:9]
	v_cndmask_b32_e64 v13, v13, 0, vcc
	v_cndmask_b32_e64 v12, v12, 0, vcc
	v_lshlrev_b32_e32 v16, 16, v17
	v_add_f32_e32 v8, v89, v8
	v_add_f32_e32 v85, v8, v9
	v_pk_fma_f32 v[8:9], v[12:13], v[96:97], v[86:87]
	v_mov_b32_e32 v86, v12
	v_mov_b32_e32 v87, v104
	v_mov_b32_e32 v88, v100
	v_mov_b32_e32 v89, v16
	v_pk_mul_f32 v[86:87], v[86:87], v[88:89]
	v_and_b32_e32 v17, 0xffff0000, v17
	v_add_f32_e32 v12, v47, v86
	v_add_f32_e32 v47, v12, v87
	v_lshlrev_b32_e32 v20, 16, v21
	v_and_b32_e32 v21, 0xffff0000, v21
	v_pk_fma_f32 v[8:9], v[100:101], v[16:17], v[8:9]
	v_mul_f32_e32 v16, 0xbfb8aa3b, v47
	v_mov_b32_e32 v12, v13
	v_mov_b32_e32 v13, v105
	v_exp_f32_e32 v86, v16
	v_mov_b32_e32 v16, v101
	v_pk_fma_f32 v[8:9], v[104:105], v[20:21], v[8:9]
	v_pk_mul_f32 v[12:13], v[12:13], v[16:17]
	v_mul_f32_e32 v17, 0xbfb8aa3b, v8
	v_exp_f32_e32 v17, v17
	v_add_f32_e32 v12, v85, v12
	v_add_f32_e32 v20, v12, v13
	v_mul_f32_e32 v13, 0xbfb8aa3b, v20
	v_add_f32_e32 v12, 1.0, v17
	v_exp_f32_e32 v13, v13
	v_mul_f32_e32 v17, 0xbfb8aa3b, v9
	v_exp_f32_e32 v17, v17
	v_rcp_f32_e32 v12, v12
	v_add_f32_e32 v13, 1.0, v13
	v_rcp_f32_e32 v21, v13
	v_add_f32_e32 v13, 1.0, v17
	v_rcp_f32_e32 v13, v13
	v_add_f32_e32 v16, 1.0, v86
	v_rcp_f32_e32 v16, v16
	v_mov_b32_e32 v90, v40
	v_pk_mul_f32 v[8:9], v[8:9], v[12:13]
	v_lshlrev_b32_e32 v12, 16, v10
	v_and_b32_e32 v10, 0xffff0000, v10
	v_cndmask_b32_e64 v13, v10, 0, vcc
	v_cndmask_b32_e64 v12, v12, 0, vcc
	v_mul_f32_e32 v16, v47, v16
	v_pk_fma_f32 v[88:89], v[12:13], v[40:41], v[32:33]
	v_mov_b32_e32 v113, v12
	v_mov_b32_e32 v115, v13
	v_mov_b32_e32 v12, v41
	v_mov_b32_e32 v13, v37
	v_mul_f32_e32 v92, 0x3db504f3, v16
	v_mul_f32_e32 v16, v20, v21
	v_lshlrev_b32_e32 v10, 16, v14
	v_and_b32_e32 v14, 0xffff0000, v14
	v_mov_b32_e32 v91, v36
	v_pk_mul_f32 v[12:13], v[114:115], v[12:13]
	v_mul_f32_e32 v93, 0x3db504f3, v16
	v_cndmask_b32_e64 v17, v14, 0, vcc
	v_cndmask_b32_e64 v16, v10, 0, vcc
	v_lshlrev_b32_e32 v20, 16, v18
	v_pk_mul_f32 v[90:91], v[112:113], v[90:91]
	v_add_f32_e32 v12, v33, v12
	v_add_f32_e32 v10, v32, v90
	v_add_f32_e32 v14, v12, v13
	v_pk_fma_f32 v[12:13], v[16:17], v[36:37], v[88:89]
	v_mov_b32_e32 v32, v16
	s_waitcnt lgkmcnt(0)
	v_mov_b32_e32 v33, v28
	v_mov_b32_e32 v36, v24
	v_mov_b32_e32 v37, v20
	v_add_f32_e32 v10, v10, v91
	v_pk_mul_f32 v[32:33], v[32:33], v[36:37]
	v_and_b32_e32 v21, 0xffff0000, v18
	v_add_f32_e32 v10, v10, v32
	v_add_f32_e32 v10, v10, v33
	v_mul_f32_e32 v18, 0xbfb8aa3b, v10
	v_exp_f32_e32 v18, v18
	v_pk_fma_f32 v[12:13], v[24:25], v[20:21], v[12:13]
	v_mov_b32_e32 v16, v17
	v_mov_b32_e32 v17, v29
	v_mov_b32_e32 v20, v25
	v_pk_mul_f32 v[16:17], v[16:17], v[20:21]
	v_add_f32_e32 v18, 1.0, v18
	v_add_f32_e32 v14, v14, v16
	v_lshlrev_b32_e32 v86, 16, v22
	v_and_b32_e32 v87, 0xffff0000, v22
	v_rcp_f32_e32 v18, v18
	v_add_f32_e32 v14, v14, v17
	v_pk_fma_f32 v[12:13], v[28:29], v[86:87], v[12:13]
	v_mul_f32_e32 v17, 0xbfb8aa3b, v14
	v_mul_f32_e32 v20, 0xbfb8aa3b, v12
	v_exp_f32_e32 v17, v17
	v_exp_f32_e32 v20, v20
	v_mul_f32_e32 v10, v10, v18
	v_mul_f32_e32 v18, 0xbfb8aa3b, v13
	v_exp_f32_e32 v18, v18
	v_add_f32_e32 v17, 1.0, v17
	v_add_f32_e32 v16, 1.0, v20
	v_rcp_f32_e32 v20, v17
	v_add_f32_e32 v17, 1.0, v18
	v_rcp_f32_e32 v16, v16
	v_rcp_f32_e32 v17, v17
	v_mul_f32_e32 v24, 0x3db504f3, v10
	v_mul_f32_e32 v10, v14, v20
	v_mul_f32_e32 v25, 0x3db504f3, v10
	v_lshlrev_b32_e32 v10, 16, v11
	v_cndmask_b32_e64 v10, v10, 0, vcc
	v_pk_mul_f32 v[12:13], v[12:13], v[16:17]
	v_and_b32_e32 v11, 0xffff0000, v11
	v_lshlrev_b32_e32 v16, 16, v23
	v_and_b32_e32 v17, 0xffff0000, v23
	v_mov_b32_e32 v85, v10
	v_mov_b32_e32 v22, v42
	v_mov_b32_e32 v23, v38
	s_mov_b32 s0, s2
	s_mov_b32 s2, 0x3db504f3
	v_cndmask_b32_e64 v11, v11, 0, vcc
	v_pk_mul_f32 v[22:23], v[84:85], v[22:23]
	v_pk_mul_f32 v[20:21], v[12:13], s[2:3] op_sel_hi:[1,0]
	v_lshlrev_b32_e32 v12, 16, v15
	v_and_b32_e32 v13, 0xffff0000, v15
	v_lshlrev_b32_e32 v14, 16, v19
	v_and_b32_e32 v15, 0xffff0000, v19
	v_pk_fma_f32 v[18:19], v[10:11], v[42:43], v[34:35]
	v_add_f32_e32 v10, v34, v22
	v_add_f32_e32 v28, v10, v23
	v_mov_b32_e32 v47, v11
	v_mov_b32_e32 v10, v43
	v_mov_b32_e32 v11, v39
	v_pk_mul_f32 v[10:11], v[46:47], v[10:11]
	v_cndmask_b32_e64 v13, v13, 0, vcc
	v_cndmask_b32_e64 v12, v12, 0, vcc
	v_add_f32_e32 v10, v35, v10
	v_add_f32_e32 v29, v10, v11
	v_pk_fma_f32 v[10:11], v[12:13], v[38:39], v[18:19]
	v_mov_b32_e32 v18, v12
	v_mov_b32_e32 v19, v30
	v_mov_b32_e32 v22, v26
	v_mov_b32_e32 v23, v14
	v_pk_mul_f32 v[18:19], v[18:19], v[22:23]
	v_pk_fma_f32 v[10:11], v[26:27], v[14:15], v[10:11]
	v_add_f32_e32 v12, v28, v18
	v_add_f32_e32 v18, v12, v19
	v_mul_f32_e32 v14, 0xbfb8aa3b, v18
	v_mov_b32_e32 v12, v13
	v_mov_b32_e32 v13, v31
	v_exp_f32_e32 v19, v14
	v_mov_b32_e32 v14, v27
	v_pk_fma_f32 v[10:11], v[30:31], v[16:17], v[10:11]
	v_pk_mul_f32 v[12:13], v[12:13], v[14:15]
	v_mul_f32_e32 v15, 0xbfb8aa3b, v10
	v_exp_f32_e32 v15, v15
	v_add_f32_e32 v12, v29, v12
	v_add_f32_e32 v16, v12, v13
	v_mul_f32_e32 v13, 0xbfb8aa3b, v16
	v_add_f32_e32 v12, 1.0, v15
	v_exp_f32_e32 v13, v13
	v_mul_f32_e32 v15, 0xbfb8aa3b, v11
	v_exp_f32_e32 v15, v15
	v_add_f32_e32 v14, 1.0, v19
	v_rcp_f32_e32 v14, v14
	v_add_f32_e32 v13, 1.0, v13
	v_rcp_f32_e32 v17, v13
	v_add_f32_e32 v13, 1.0, v15
	v_rcp_f32_e32 v12, v12
	v_rcp_f32_e32 v13, v13
	v_mul_f32_e32 v14, v18, v14
	v_mul_f32_e32 v22, 0x3db504f3, v14
	v_mul_f32_e32 v14, v16, v17
	v_mul_f32_e32 v23, 0x3db504f3, v14
	v_pk_mul_f32 v[10:11], v[10:11], v[12:13]
	v_pk_mul_f32 v[44:45], v[44:45], s[2:3] op_sel_hi:[1,0]
	v_pk_mul_f32 v[8:9], v[8:9], s[2:3] op_sel_hi:[1,0]
	v_pk_mul_f32 v[18:19], v[10:11], s[2:3] op_sel_hi:[1,0]
	v_cvt_pk_bf16_f32 v10, v94, v95
	v_cvt_pk_bf16_f32 v11, v92, v93
	v_cvt_pk_bf16_f32 v12, v24, v25
	v_cvt_pk_bf16_f32 v13, v22, v23
	v_cvt_pk_bf16_f32 v14, v44, v45
	v_cvt_pk_bf16_f32 v15, v8, v9
	v_cvt_pk_bf16_f32 v16, v20, v21
	v_cvt_pk_bf16_f32 v17, v18, v19
	ds_write_b128 v184, v[10:13] offset:17408
	ds_write_b128 v184, v[14:17] offset:17680
	v_mov_b64_e32 v[10:11], s[26:27]
	global_load_dword v84, v[10:11], off
	global_load_dword v85, v[10:11], off offset:16
	v_add_u32_e32 v12, 0x8800, v198
	v_cvt_pk_bf16_f32 v8, v92, v8
	v_cvt_pk_bf16_f32 v9, v93, v9
	s_add_i32 s2, s0, 1
	ds_write2_b32 v12, v8, v9 offset0:72 offset1:108
	v_cvt_pk_bf16_f32 v8, v24, v20
	v_cvt_pk_bf16_f32 v9, v25, v21
	s_lshl_b32 s1, s2, 6
	ds_write2_b32 v12, v8, v9 offset0:144 offset1:180
	v_cvt_pk_bf16_f32 v8, v22, v18
	s_cmp_lg_u32 s0, 31
	v_cvt_pk_bf16_f32 v10, v94, v44
	v_cvt_pk_bf16_f32 v11, v95, v45
	ds_write_b32 v198, v8 offset:35680
	v_cvt_pk_bf16_f32 v8, v23, v19
	s_cselect_b32 s0, s1, 0x7c0
	ds_write2_b32 v12, v10, v11 offset1:36
	ds_write_b32 v199, v8 offset:34816
	ds_write_b16 v186, v4 offset:53248
	ds_write_b16_d16_hi v186, v4 offset:53392
	ds_write_b16 v186, v5 offset:53536
	ds_write_b16_d16_hi v186, v5 offset:53680
	ds_write_b16 v186, v6 offset:53824
	ds_write_b16_d16_hi v186, v6 offset:53968
	ds_write_b16 v186, v7 offset:54112
	ds_write_b16_d16_hi v186, v7 offset:54256
	ds_write_b16 v186, v0 offset:54400
	ds_write_b16_d16_hi v186, v0 offset:54544
	ds_write_b16 v186, v1 offset:54688
	ds_write_b16_d16_hi v186, v1 offset:54832
	ds_write_b16 v186, v2 offset:54976
	ds_write_b16_d16_hi v186, v2 offset:55120
	ds_write_b16 v186, v3 offset:55264
	ds_write_b16_d16_hi v186, v3 offset:55408
	v_add_u32_e32 v4, s0, v173
	v_max_i32_e32 v0, 0, v4
	v_readlane_b32 s1, v253, 58
	v_readlane_b32 s18, v253, 56
	s_waitcnt vmcnt(0) lgkmcnt(0)
	v_add_f32_e32 v92, v196, v84
	v_add_u32_e32 v0, s1, v0
	v_ashrrev_i32_e32 v1, 31, v0
	v_lshlrev_b64 v[0:1], 10, v[0:1]
	v_lshl_add_u64 v[2:3], v[116:117], 0, v[0:1]
	v_lshl_add_u64 v[0:1], v[118:119], 0, v[0:1]
	global_load_dwordx4 v[28:31], v[2:3], off
	global_load_dwordx4 v[24:27], v[0:1], off
	v_max_i32_e32 v0, -1, v4
	v_add_u32_e32 v0, s18, v0
	v_ashrrev_i32_e32 v1, 31, v0
	v_lshlrev_b64 v[0:1], 10, v[0:1]
	v_lshl_add_u64 v[2:3], v[116:117], 0, v[0:1]
	v_lshl_add_u64 v[0:1], v[118:119], 0, v[0:1]
	global_load_dwordx4 v[32:35], v[2:3], off
	global_load_dwordx4 v[8:11], v[0:1], off
	v_max_i32_e32 v0, -2, v4
	v_readlane_b32 s18, v253, 57
	s_nop 1
	v_add_u32_e32 v0, s18, v0
	v_ashrrev_i32_e32 v1, 31, v0
	v_lshlrev_b64 v[0:1], 10, v[0:1]
	v_lshl_add_u64 v[2:3], v[116:117], 0, v[0:1]
	v_lshl_add_u64 v[0:1], v[118:119], 0, v[0:1]
	global_load_dwordx4 v[36:39], v[2:3], off
	global_load_dwordx4 v[12:15], v[0:1], off
	v_add_u32_e32 v0, s0, v120
	v_ashrrev_i32_e32 v1, 31, v0
	v_lshlrev_b64 v[0:1], 10, v[0:1]
	v_lshl_add_u64 v[2:3], v[116:117], 0, v[0:1]
	v_lshl_add_u64 v[0:1], v[118:119], 0, v[0:1]
	global_load_dwordx4 v[40:43], v[2:3], off
	global_load_dwordx4 v[16:19], v[0:1], off
	v_max_i32_e32 v0, -4, v4
	v_readlane_b32 s18, v253, 59
	s_nop 1
	v_add_u32_e32 v0, s18, v0
	v_ashrrev_i32_e32 v1, 31, v0
	v_lshlrev_b64 v[0:1], 10, v[0:1]
	v_lshl_add_u64 v[2:3], v[116:117], 0, v[0:1]
	v_lshl_add_u64 v[0:1], v[118:119], 0, v[0:1]
	global_load_dwordx4 v[44:47], v[2:3], off
	global_load_dwordx4 v[20:23], v[0:1], off
	v_add_f32_e32 v2, v204, v85
	s_mov_b32 s18, 0xbfb8aa3b
	v_mul_f32_e64 v0, |v2|, s18
	v_exp_f32_e32 v0, v0
	s_add_i32 s18, s0, s1
	s_mov_b32 s0, 0x800000
	v_min_f32_e32 v2, 0, v2
	v_add_f32_e32 v0, 1.0, v0
	v_cmp_gt_f32_e32 vcc, s0, v0
	s_mov_b32 s0, 0x3f317217
	v_or_b32_e32 v84, s18, v170
	v_cndmask_b32_e64 v1, 0, 32, vcc
	v_ldexp_f32 v0, v0, v1
	v_log_f32_e32 v3, v0
	v_ashrrev_i32_e32 v85, 31, v84
	v_lshlrev_b64 v[0:1], 10, v[84:85]
	v_lshlrev_b64 v[84:85], 7, v[84:85]
	v_mul_f32_e32 v4, 0x3f317217, v3
	v_fma_f32 v4, v3, s0, -v4
	v_fmac_f32_e32 v4, 0x3377d1cf, v3
	s_mov_b32 s0, 0x7f800000
	v_fmac_f32_e32 v4, 0x3f317217, v3
	v_cmp_lt_f32_e64 s[0:1], |v3|, s0
	v_lshl_add_u64 v[0:1], s[22:23], 0, v[0:1]
	v_lshl_add_u64 v[84:85], s[24:25], 0, v[84:85]
	v_cndmask_b32_e64 v3, v3, v4, s[0:1]
	v_cndmask_b32_e32 v4, 0, v225, vcc
	v_sub_f32_e32 v3, v3, v4
	v_sub_f32_e32 v86, v2, v3
	v_add_u32_e32 v2, -1, v211
	v_cmp_lt_i32_e32 vcc, v2, v212
	v_readlane_b32 s0, v253, 41
	v_readlane_b32 s1, v253, 42
	v_cndmask_b32_e32 v2, v2, v211, vcc
	v_lshlrev_b32_e32 v93, 2, v2
	ds_bpermute_b32 v87, v93, v86
	global_load_dwordx4 v[4:7], v[0:1], off
	s_nop 0
	global_load_dwordx4 v[0:3], v[0:1], off offset:16
	s_waitcnt lgkmcnt(0)
	v_add_f32_e32 v87, v86, v87
	v_cndmask_b32_e64 v90, v87, v86, s[8:9]
	v_add_u32_e32 v86, -2, v211
	v_cmp_lt_i32_e32 vcc, v86, v212
	s_nop 1
	v_cndmask_b32_e32 v86, v86, v211, vcc
	v_lshlrev_b32_e32 v94, 2, v86
	ds_bpermute_b32 v91, v94, v90
	v_or_b32_e32 v86, s18, v171
	v_ashrrev_i32_e32 v87, 31, v86
	v_lshlrev_b64 v[88:89], 10, v[86:87]
	v_lshl_add_u64 v[88:89], v[122:123], 0, v[88:89]
	s_waitcnt lgkmcnt(0)
	v_add_f32_e32 v87, v90, v91
	v_cndmask_b32_e64 v87, v87, v90, s[10:11]
	v_add_u32_e32 v90, -4, v211
	v_cmp_lt_i32_e32 vcc, v90, v212
	s_nop 1
	v_cndmask_b32_e32 v90, v90, v211, vcc
	v_lshlrev_b32_e32 v95, 2, v90
	ds_bpermute_b32 v96, v95, v87
	v_or_b32_e32 v90, 16, v86
	v_ashrrev_i32_e32 v91, 31, v90
	v_lshlrev_b64 v[90:91], 10, v[90:91]
	v_lshl_add_u64 v[90:91], v[122:123], 0, v[90:91]
	s_waitcnt lgkmcnt(0)
	v_add_f32_e32 v96, v87, v96
	v_cndmask_b32_e64 v87, v96, v87, s[12:13]
	v_add_u32_e32 v96, -8, v211
	v_cmp_lt_i32_e32 vcc, v96, v212
	global_load_dword v196, v[84:85], off
	global_load_dword v204, v[84:85], off offset:16
	global_load_dwordx2 v[130:131], v[88:89], off
	global_load_dwordx2 v[132:133], v[90:91], off
	v_cndmask_b32_e32 v96, v96, v211, vcc
	v_lshlrev_b32_e32 v96, 2, v96
	ds_bpermute_b32 v97, v96, v87
	v_or_b32_e32 v84, 32, v86
	v_ashrrev_i32_e32 v85, 31, v84
	v_or_b32_e32 v86, 48, v86
	v_lshlrev_b64 v[84:85], 10, v[84:85]
	s_waitcnt lgkmcnt(0)
	v_add_f32_e32 v88, v87, v97
	v_cndmask_b32_e64 v88, v88, v87, s[14:15]
	v_add_u32_e32 v87, -16, v211
	v_cmp_lt_i32_e32 vcc, v87, v212
	v_lshl_add_u64 v[84:85], v[122:123], 0, v[84:85]
	s_nop 0
	v_cndmask_b32_e32 v87, v87, v211, vcc
	v_lshlrev_b32_e32 v89, 2, v87
	v_ashrrev_i32_e32 v87, 31, v86
	ds_bpermute_b32 v90, v89, v88
	v_lshlrev_b64 v[86:87], 10, v[86:87]
	v_lshl_add_u64 v[86:87], v[122:123], 0, v[86:87]
	global_load_dwordx2 v[134:135], v[84:85], off
	global_load_dwordx2 v[136:137], v[86:87], off
	s_waitcnt lgkmcnt(0)
	v_add_f32_e32 v90, v88, v90
	v_cndmask_b32_e64 v88, v90, v88, s[4:5]
	v_subrev_u32_e32 v90, 32, v211
	v_cmp_lt_i32_e32 vcc, v90, v212
	s_nop 1
	v_cndmask_b32_e32 v90, v90, v211, vcc
	v_lshlrev_b32_e32 v90, 2, v90
	ds_bpermute_b32 v91, v90, v88
	s_andn2_b64 vcc, exec, s[0:1]
	s_mov_b64 s[0:1], -1
	s_waitcnt lgkmcnt(0)
	v_add_f32_e32 v84, v88, v91
	v_cndmask_b32_e64 v84, v84, v88, s[16:17]
	v_sub_f32_e32 v85, v92, v84
	ds_bpermute_b32 v86, v93, v85
	s_waitcnt lgkmcnt(0)
	v_max_f32_e32 v86, v86, v86
	v_max_f32_e32 v86, v85, v86
	v_cndmask_b32_e64 v86, v86, v85, s[8:9]
	ds_bpermute_b32 v87, v94, v86
	s_waitcnt lgkmcnt(0)
	v_max_f32_e32 v87, v87, v87
	v_max_f32_e32 v87, v86, v87
	v_cndmask_b32_e64 v86, v87, v86, s[10:11]
	ds_bpermute_b32 v87, v95, v86
	s_waitcnt lgkmcnt(0)
	v_max_f32_e32 v87, v87, v87
	v_max_f32_e32 v87, v86, v87
	v_cndmask_b32_e64 v86, v87, v86, s[12:13]
	ds_bpermute_b32 v87, v96, v86
	s_waitcnt lgkmcnt(0)
	v_max_f32_e32 v87, v87, v87
	v_max_f32_e32 v87, v86, v87
	v_cndmask_b32_e64 v86, v87, v86, s[14:15]
	ds_bpermute_b32 v87, v89, v86
	s_waitcnt lgkmcnt(0)
	v_max_f32_e32 v87, v87, v87
	v_max_f32_e32 v87, v86, v87
	v_cndmask_b32_e64 v86, v87, v86, s[4:5]
	ds_bpermute_b32 v87, v90, v86
	v_max_f32_e32 v88, v86, v86
	s_waitcnt lgkmcnt(0)
	v_max_f32_e32 v87, v87, v87
	v_max_f32_e32 v87, v88, v87
	v_cndmask_b32_e64 v86, v87, v86, s[16:17]
	v_max_f32_e32 v86, v86, v86
	v_max_f32_e64 v87, s28, s28
	v_max_f32_e32 v86, v87, v86
	v_lshl_or_b32 v87, v211, 2, v226
	ds_bpermute_b32 v88, v87, v86
	v_add_f32_e32 v84, v84, v86
	v_sub_f32_e32 v89, s28, v86
	v_mul_f32_e32 v89, 0x3fb8aa3b, v89
	v_mul_f32_e32 v90, 0xbfb8aa3b, v84
	s_waitcnt lgkmcnt(0)
	v_sub_f32_e32 v91, v85, v88
	v_exp_f32_e32 v89, v89
	v_exp_f32_e32 v90, v90
	v_mul_f32_e32 v91, 0x3fb8aa3b, v91
	v_sub_f32_e32 v88, s28, v88
	v_exp_f32_e32 v91, v91
	v_mul_f32_e32 v88, 0x3fb8aa3b, v88
	ds_bpermute_b32 v84, v87, v84
	v_exp_f32_e32 v88, v88
	ds_write2st64_b32 v174, v86, v85 offset1:1
	ds_write2st64_b32 v174, v89, v90 offset0:2 offset1:3
	ds_write_b32 v174, v91 offset:1024
	s_waitcnt lgkmcnt(0)
	s_barrier
	v_readfirstlane_b32 s18, v88
	s_waitcnt lgkmcnt(0)
	v_readfirstlane_b32 s28, v84
	s_cbranch_vccnz .LBB0_429
	v_xor_b32_e32 v144, 32, v211
	s_mov_b64 s[0:1], 0

.LBB0_450:
	s_or_b64 exec, exec, s[0:1]
	v_readlane_b32 s0, v253, 58
	s_or_b32 s0, s29, s0
	s_add_i32 s1, 0, 0x1b100
	s_waitcnt lgkmcnt(0)
	s_barrier
	v_add_u32_e32 v94, s1, v191
	s_waitcnt lgkmcnt(0)
	ds_read2st64_b64 v[88:91], v94 offset1:1
	s_brev_b32 s30, 60
	s_mov_b32 s19, 0x800000
	v_pk_mul_f32 v[50:51], v[50:51], s[18:19] op_sel_hi:[1,0]
	v_pk_mul_f32 v[48:49], v[48:49], s[18:19] op_sel_hi:[1,0]
	s_waitcnt lgkmcnt(0)
	v_pk_add_f32 v[88:89], v[88:89], 0 op_sel_hi:[1,0]
	v_pk_mul_f32 v[74:75], v[74:75], s[18:19] op_sel_hi:[1,0]
	v_pk_add_f32 v[92:93], v[88:89], v[90:91]
	ds_read2st64_b64 v[88:91], v94 offset0:2 offset1:3
	v_pk_mul_f32 v[72:73], v[72:73], s[18:19] op_sel_hi:[1,0]
	v_pk_mul_f32 v[70:71], v[70:71], s[18:19] op_sel_hi:[1,0]
	v_pk_mul_f32 v[68:69], v[68:69], s[18:19] op_sel_hi:[1,0]
	v_pk_mul_f32 v[66:67], v[66:67], s[18:19] op_sel_hi:[1,0]
	s_waitcnt lgkmcnt(0)
	v_pk_add_f32 v[88:89], v[92:93], v[88:89]
	v_pk_mul_f32 v[64:65], v[64:65], s[18:19] op_sel_hi:[1,0]
	v_pk_add_f32 v[92:93], v[88:89], v[90:91]
	ds_read2st64_b64 v[88:91], v94 offset0:4 offset1:5
	v_pk_mul_f32 v[78:79], v[78:79], s[18:19] op_sel_hi:[1,0]
	v_pk_mul_f32 v[76:77], v[76:77], s[18:19] op_sel_hi:[1,0]
	v_pk_mul_f32 v[82:83], v[82:83], s[18:19] op_sel_hi:[1,0]
	v_pk_mul_f32 v[80:81], v[80:81], s[18:19] op_sel_hi:[1,0]
	s_waitcnt lgkmcnt(0)
	v_pk_add_f32 v[88:89], v[92:93], v[88:89]
	s_nop 0
	v_pk_add_f32 v[92:93], v[88:89], v[90:91]
	ds_read2st64_b64 v[88:91], v94 offset0:6 offset1:7
	global_load_dwordx4 v[94:97], v[126:127], off
	s_waitcnt lgkmcnt(0)
	v_pk_add_f32 v[88:89], v[92:93], v[88:89]
	v_lshlrev_b32_e32 v93, 16, v142
	v_mul_f32_e32 v93, 0xbfb8aa3b, v93
	v_exp_f32_e32 v93, v93
	v_pk_add_f32 v[88:89], v[88:89], v[90:91]
	v_add_f32_e32 v93, 1.0, v93
	v_pk_mul_f32 v[90:91], v[88:89], s[30:31] op_sel_hi:[1,0]
	v_rcp_f32_e32 v98, v93
	v_and_b32_e32 v93, 0xffff0000, v142
	v_fma_f32 v88, -v90, v90, v91
	v_mul_f32_e32 v93, 0xbfb8aa3b, v93
	v_max_f32_e32 v88, 0, v88
	v_exp_f32_e32 v93, v93
	v_add_f32_e32 v88, 0x358637bd, v88
	v_cmp_gt_f32_e32 vcc, s19, v88
	v_mul_f32_e32 v89, 0x4b800000, v88
	v_add_f32_e32 v93, 1.0, v93
	v_cndmask_b32_e32 v88, v88, v89, vcc
	v_rsq_f32_e32 v88, v88
	v_rcp_f32_e32 v99, v93
	v_pk_add_f32 v[100:101], v[154:155], v[90:91] op_sel_hi:[1,0] neg_lo:[0,1] neg_hi:[0,1]
	v_pk_add_f32 v[90:91], v[152:153], v[90:91] op_sel_hi:[1,0] neg_lo:[0,1] neg_hi:[0,1]
	v_mul_f32_e32 v89, 0x45800000, v88
	v_cndmask_b32_e32 v92, v88, v89, vcc
	v_pk_mul_f32 v[98:99], v[98:99], v[100:101]
	v_or_b32_e32 v88, s0, v171
	v_pk_mul_f32 v[98:99], v[98:99], v[92:93] op_sel_hi:[1,0]
	v_lshlrev_b32_e32 v93, 16, v143
	v_mul_f32_e32 v93, 0xbfb8aa3b, v93
	v_exp_f32_e32 v93, v93
	v_ashrrev_i32_e32 v89, 31, v88
	v_lshlrev_b64 v[88:89], 10, v[88:89]
	v_lshl_add_u64 v[88:89], v[122:123], 0, v[88:89]
	v_add_f32_e32 v93, 1.0, v93
	s_waitcnt vmcnt(0)
	v_pk_mul_f32 v[94:95], v[94:95], v[98:99]
	v_rcp_f32_e32 v98, v93
	v_and_b32_e32 v93, 0xffff0000, v143
	v_mul_f32_e32 v93, 0xbfb8aa3b, v93
	v_exp_f32_e32 v93, v93
	s_nop 0
	v_add_f32_e32 v93, 1.0, v93
	v_rcp_f32_e32 v99, v93
	s_nop 0
	v_pk_mul_f32 v[90:91], v[98:99], v[90:91]
	s_nop 0
	v_pk_mul_f32 v[90:91], v[90:91], v[92:93] op_sel_hi:[1,0]
	v_cvt_pk_bf16_f32 v92, v94, v95
	v_pk_mul_f32 v[90:91], v[96:97], v[90:91]
	v_add_u32_e32 v94, s1, v192
	v_cvt_pk_bf16_f32 v93, v90, v91
	global_store_dwordx2 v[88:89], v[92:93], off
	ds_read2st64_b64 v[88:91], v94 offset1:1
	v_lshlrev_b32_e32 v97, 16, v140
	v_mul_f32_e32 v97, 0xbfb8aa3b, v97
	v_exp_f32_e32 v97, v97
	s_waitcnt lgkmcnt(0)
	v_pk_add_f32 v[88:89], v[88:89], 0 op_sel_hi:[1,0]
	s_nop 0
	v_pk_add_f32 v[92:93], v[88:89], v[90:91]
	ds_read2st64_b64 v[88:91], v94 offset0:2 offset1:3
	v_add_f32_e32 v97, 1.0, v97
	v_rcp_f32_e32 v98, v97
	v_and_b32_e32 v97, 0xffff0000, v140
	v_mul_f32_e32 v97, 0xbfb8aa3b, v97
	s_waitcnt lgkmcnt(0)
	v_pk_add_f32 v[88:89], v[92:93], v[88:89]
	v_exp_f32_e32 v97, v97
	v_pk_add_f32 v[92:93], v[88:89], v[90:91]
	ds_read2st64_b64 v[88:91], v94 offset0:4 offset1:5
	v_add_f32_e32 v97, 1.0, v97
	v_rcp_f32_e32 v99, v97
	s_waitcnt lgkmcnt(0)
	v_pk_add_f32 v[88:89], v[92:93], v[88:89]
	s_nop 0
	v_pk_add_f32 v[92:93], v[88:89], v[90:91]
	ds_read2st64_b64 v[88:91], v94 offset0:6 offset1:7
	s_waitcnt lgkmcnt(0)
	v_pk_add_f32 v[88:89], v[92:93], v[88:89]
	s_nop 0
	v_pk_add_f32 v[88:89], v[88:89], v[90:91]
	global_load_dwordx4 v[90:93], v[126:127], off
	v_pk_mul_f32 v[94:95], v[88:89], s[30:31] op_sel_hi:[1,0]
	s_nop 0
	v_fma_f32 v88, -v94, v94, v95
	v_max_f32_e32 v88, 0, v88
	v_add_f32_e32 v88, 0x358637bd, v88
	v_cmp_gt_f32_e32 vcc, s19, v88
	v_mul_f32_e32 v89, 0x4b800000, v88
	v_pk_add_f32 v[100:101], v[150:151], v[94:95] op_sel_hi:[1,0] neg_lo:[0,1] neg_hi:[0,1]
	v_cndmask_b32_e32 v88, v88, v89, vcc
	v_rsq_f32_e32 v88, v88
	v_pk_mul_f32 v[98:99], v[98:99], v[100:101]
	v_pk_add_f32 v[94:95], v[148:149], v[94:95] op_sel_hi:[1,0] neg_lo:[0,1] neg_hi:[0,1]
	v_mul_f32_e32 v89, 0x45800000, v88
	v_cndmask_b32_e32 v96, v88, v89, vcc
	v_pk_mul_f32 v[98:99], v[98:99], v[96:97] op_sel_hi:[1,0]
	v_lshlrev_b32_e32 v97, 16, v141
	v_mul_f32_e32 v97, 0xbfb8aa3b, v97
	v_exp_f32_e32 v97, v97
	v_or_b32_e32 v88, s0, v188
	v_ashrrev_i32_e32 v89, 31, v88
	v_lshlrev_b64 v[88:89], 10, v[88:89]
	v_add_f32_e32 v97, 1.0, v97
	v_lshl_add_u64 v[88:89], v[122:123], 0, v[88:89]
	s_waitcnt vmcnt(0) lgkmcnt(0)
	v_pk_mul_f32 v[90:91], v[90:91], v[98:99]
	v_rcp_f32_e32 v98, v97
	v_and_b32_e32 v97, 0xffff0000, v141
	v_mul_f32_e32 v97, 0xbfb8aa3b, v97
	v_exp_f32_e32 v97, v97
	v_cvt_pk_bf16_f32 v90, v90, v91
	v_add_f32_e32 v97, 1.0, v97
	v_rcp_f32_e32 v99, v97
	s_nop 0
	v_pk_mul_f32 v[94:95], v[98:99], v[94:95]
	s_nop 0
	v_pk_mul_f32 v[94:95], v[94:95], v[96:97] op_sel_hi:[1,0]
	v_lshlrev_b32_e32 v97, 16, v138
	v_pk_mul_f32 v[92:93], v[92:93], v[94:95]
	v_add_u32_e32 v94, s1, v193
	v_cvt_pk_bf16_f32 v91, v92, v93
	global_store_dwordx2 v[88:89], v[90:91], off
	ds_read2st64_b64 v[88:91], v94 offset1:1
	v_mul_f32_e32 v97, 0xbfb8aa3b, v97
	v_exp_f32_e32 v97, v97
	s_waitcnt lgkmcnt(0)
	v_pk_add_f32 v[88:89], v[88:89], 0 op_sel_hi:[1,0]
	s_nop 0
	v_pk_add_f32 v[92:93], v[88:89], v[90:91]
	ds_read2st64_b64 v[88:91], v94 offset0:2 offset1:3
	v_add_f32_e32 v97, 1.0, v97
	v_rcp_f32_e32 v98, v97
	v_and_b32_e32 v97, 0xffff0000, v138
	v_mul_f32_e32 v97, 0xbfb8aa3b, v97
	s_waitcnt lgkmcnt(0)
	v_pk_add_f32 v[88:89], v[92:93], v[88:89]
	v_exp_f32_e32 v97, v97
	v_pk_add_f32 v[92:93], v[88:89], v[90:91]
	ds_read2st64_b64 v[88:91], v94 offset0:4 offset1:5
	v_add_f32_e32 v97, 1.0, v97
	v_rcp_f32_e32 v99, v97
	s_waitcnt lgkmcnt(0)
	v_pk_add_f32 v[88:89], v[92:93], v[88:89]
	s_nop 0
	v_pk_add_f32 v[92:93], v[88:89], v[90:91]
	ds_read2st64_b64 v[88:91], v94 offset0:6 offset1:7
	s_waitcnt lgkmcnt(0)
	v_pk_add_f32 v[88:89], v[92:93], v[88:89]
	s_nop 0
	v_pk_add_f32 v[88:89], v[88:89], v[90:91]
	global_load_dwordx4 v[90:93], v[126:127], off
	v_pk_mul_f32 v[94:95], v[88:89], s[30:31] op_sel_hi:[1,0]
	s_nop 0
	v_fma_f32 v88, -v94, v94, v95
	v_max_f32_e32 v88, 0, v88
	v_add_f32_e32 v88, 0x358637bd, v88
	v_cmp_gt_f32_e32 vcc, s19, v88
	v_mul_f32_e32 v89, 0x4b800000, v88
	v_pk_add_f32 v[100:101], v[146:147], v[94:95] op_sel_hi:[1,0] neg_lo:[0,1] neg_hi:[0,1]
	v_cndmask_b32_e32 v88, v88, v89, vcc
	v_rsq_f32_e32 v88, v88
	v_pk_mul_f32 v[98:99], v[98:99], v[100:101]
	v_pk_add_f32 v[94:95], v[144:145], v[94:95] op_sel_hi:[1,0] neg_lo:[0,1] neg_hi:[0,1]
	v_mul_f32_e32 v89, 0x45800000, v88
	v_cndmask_b32_e32 v96, v88, v89, vcc
	v_pk_mul_f32 v[98:99], v[98:99], v[96:97] op_sel_hi:[1,0]
	v_lshlrev_b32_e32 v97, 16, v139
	v_mul_f32_e32 v97, 0xbfb8aa3b, v97
	v_exp_f32_e32 v97, v97
	v_or_b32_e32 v88, s0, v189
	v_ashrrev_i32_e32 v89, 31, v88
	v_lshlrev_b64 v[88:89], 10, v[88:89]
	v_add_f32_e32 v97, 1.0, v97
	v_lshl_add_u64 v[88:89], v[122:123], 0, v[88:89]
	s_waitcnt vmcnt(0) lgkmcnt(0)
	v_pk_mul_f32 v[90:91], v[90:91], v[98:99]
	v_rcp_f32_e32 v98, v97
	v_and_b32_e32 v97, 0xffff0000, v139
	v_mul_f32_e32 v97, 0xbfb8aa3b, v97
	v_exp_f32_e32 v97, v97
	v_cvt_pk_bf16_f32 v90, v90, v91
	v_add_f32_e32 v97, 1.0, v97
	v_rcp_f32_e32 v99, v97
	s_nop 0
	v_pk_mul_f32 v[94:95], v[98:99], v[94:95]
	s_nop 0
	v_pk_mul_f32 v[94:95], v[94:95], v[96:97] op_sel_hi:[1,0]
	v_or_b32_e32 v96, s0, v190
	v_pk_mul_f32 v[92:93], v[92:93], v[94:95]
	v_add_u32_e32 v94, s1, v194
	v_cvt_pk_bf16_f32 v91, v92, v93
	global_store_dwordx2 v[88:89], v[90:91], off
	ds_read2st64_b64 v[88:91], v94 offset1:1
	v_lshlrev_b32_e32 v95, 16, v128
	v_mul_f32_e32 v95, 0xbfb8aa3b, v95
	v_exp_f32_e32 v95, v95
	v_ashrrev_i32_e32 v97, 31, v96
	s_waitcnt lgkmcnt(0)
	v_pk_add_f32 v[88:89], v[88:89], 0 op_sel_hi:[1,0]
	v_add_f32_e32 v95, 1.0, v95
	v_pk_add_f32 v[92:93], v[88:89], v[90:91]
	ds_read2st64_b64 v[88:91], v94 offset0:2 offset1:3
	v_rcp_f32_e32 v98, v95
	v_and_b32_e32 v95, 0xffff0000, v128
	v_mul_f32_e32 v95, 0xbfb8aa3b, v95
	v_exp_f32_e32 v95, v95
	s_waitcnt lgkmcnt(0)
	v_pk_add_f32 v[88:89], v[92:93], v[88:89]
	v_add_f32_e32 v95, 1.0, v95
	v_pk_add_f32 v[92:93], v[88:89], v[90:91]
	ds_read2st64_b64 v[88:91], v94 offset0:4 offset1:5
	v_rcp_f32_e32 v99, v95
	s_waitcnt lgkmcnt(0)
	v_pk_add_f32 v[88:89], v[92:93], v[88:89]
	s_nop 0
	v_pk_add_f32 v[92:93], v[88:89], v[90:91]
	ds_read2st64_b64 v[88:91], v94 offset0:6 offset1:7
	s_waitcnt lgkmcnt(0)
	v_pk_add_f32 v[88:89], v[92:93], v[88:89]
	s_nop 0
	v_pk_add_f32 v[88:89], v[88:89], v[90:91]
	s_nop 0
	v_pk_mul_f32 v[92:93], v[88:89], s[30:31] op_sel_hi:[1,0]
	s_nop 0
	v_fma_f32 v88, -v92, v92, v93
	v_max_f32_e32 v88, 0, v88
	v_add_f32_e32 v88, 0x358637bd, v88
	v_cmp_gt_f32_e32 vcc, s19, v88
	v_mul_f32_e32 v89, 0x4b800000, v88
	v_pk_add_f32 v[86:87], v[86:87], v[92:93] op_sel_hi:[1,0] neg_lo:[0,1] neg_hi:[0,1]
	v_cndmask_b32_e32 v88, v88, v89, vcc
	v_rsq_f32_e32 v88, v88
	v_pk_mul_f32 v[86:87], v[98:99], v[86:87]
	v_pk_add_f32 v[84:85], v[84:85], v[92:93] op_sel_hi:[1,0] neg_lo:[0,1] neg_hi:[0,1]
	v_pk_mul_f32 v[92:93], v[52:53], s[18:19] op_sel_hi:[1,0]
	v_mul_f32_e32 v89, 0x45800000, v88
	v_cndmask_b32_e32 v94, v88, v89, vcc
	global_load_dwordx4 v[88:91], v[126:127], off
	v_pk_mul_f32 v[86:87], v[86:87], v[94:95] op_sel_hi:[1,0]
	s_waitcnt vmcnt(0) lgkmcnt(0)
	v_pk_mul_f32 v[86:87], v[88:89], v[86:87]
	v_lshlrev_b32_e32 v88, 16, v129
	v_and_b32_e32 v89, 0xffff0000, v129
	v_mul_f32_e32 v88, 0xbfb8aa3b, v88
	v_mul_f32_e32 v89, 0xbfb8aa3b, v89
	v_exp_f32_e32 v88, v88
	v_exp_f32_e32 v89, v89
	v_cvt_pk_bf16_f32 v86, v86, v87
	v_add_f32_e32 v88, 1.0, v88
	v_add_f32_e32 v89, 1.0, v89
	v_rcp_f32_e32 v88, v88
	v_rcp_f32_e32 v89, v89
	s_nop 0
	v_pk_mul_f32 v[84:85], v[88:89], v[84:85]
	s_nop 0
	v_pk_mul_f32 v[84:85], v[84:85], v[94:95] op_sel_hi:[1,0]
	v_pk_mul_f32 v[88:89], v[56:57], s[18:19] op_sel_hi:[1,0]
	v_pk_mul_f32 v[84:85], v[90:91], v[84:85]
	v_pk_mul_f32 v[90:91], v[58:59], s[18:19] op_sel_hi:[1,0]
	v_cvt_pk_bf16_f32 v87, v84, v85
	v_lshlrev_b64 v[84:85], 10, v[96:97]
	v_lshl_add_u64 v[84:85], v[122:123], 0, v[84:85]
	global_store_dwordx2 v[84:85], v[86:87], off
	v_add_u32_e32 v96, v181, v160
	v_pk_mul_f32 v[86:87], v[62:63], s[18:19] op_sel_hi:[1,0]
	v_pk_mul_f32 v[84:85], v[60:61], s[18:19] op_sel_hi:[1,0]
	v_pk_mul_f32 v[94:95], v[54:55], s[18:19] op_sel_hi:[1,0]
	ds_read_b128 v[52:55], v125 offset:1024
	ds_read_b128 v[56:59], v125 offset:1040
	ds_read_b128 v[60:63], v96 offset:53248
	s_waitcnt lgkmcnt(0)
	v_cvt_pk_bf16_f32 v97, v52, v53
	v_cvt_pk_bf16_f32 v102, v54, v55
	v_lshlrev_b32_e32 v98, 16, v60
	v_and_b32_e32 v99, 0xffff0000, v60
	v_lshlrev_b32_e32 v60, 16, v61
	v_and_b32_e32 v61, 0xffff0000, v61
	v_pk_mul_f32 v[98:99], v[52:53], v[98:99]
	v_pk_mul_f32 v[60:61], v[54:55], v[60:61]
	v_cvt_pk_bf16_f32 v98, v98, v99
	v_cvt_pk_bf16_f32 v99, v60, v61
	v_lshlrev_b32_e32 v60, 16, v62
	v_and_b32_e32 v61, 0xffff0000, v62
	v_pk_mul_f32 v[60:61], v[56:57], v[60:61]
	v_cvt_pk_bf16_f32 v103, v56, v57
	v_cvt_pk_bf16_f32 v100, v60, v61
	v_lshlrev_b32_e32 v60, 16, v63
	v_and_b32_e32 v61, 0xffff0000, v63
	v_pk_mul_f32 v[60:61], v[58:59], v[60:61]
	v_cvt_pk_bf16_f32 v104, v58, v59
	v_cvt_pk_bf16_f32 v101, v60, v61
	ds_read_b128 v[52:55], v201 offset:34816
	ds_read_b128 v[56:59], v201 offset:39424
	s_waitcnt lgkmcnt(0)
	v_mfma_f32_16x16x32_bf16 v[56:59], v[98:101], v[56:59], v[72:75]
	ds_read_b128 v[60:63], v201 offset:41728
	s_nop 1
	ds_read_b128 v[72:75], v96 offset:34816
	v_mfma_f32_16x16x32_bf16 v[48:51], v[98:101], v[52:55], v[48:51]
	ds_read_b128 v[52:55], v201 offset:37120
	s_waitcnt lgkmcnt(0)
	v_mfma_f32_16x16x32_bf16 v[60:63], v[98:101], v[60:63], v[68:71]
	s_nop 2
	ds_read_b128 v[68:71], v201 offset:44032
	s_waitcnt lgkmcnt(0)
	v_mfma_f32_16x16x32_bf16 v[64:67], v[98:101], v[68:71], v[64:67]
	ds_read_b128 v[68:71], v201 offset:46336
	s_waitcnt lgkmcnt(0)
	v_mfma_f32_16x16x32_bf16 v[84:87], v[98:101], v[68:71], v[84:87]
	ds_read_b128 v[68:71], v201 offset:48640
	s_waitcnt lgkmcnt(0)
	v_mfma_f32_16x16x32_bf16 v[88:91], v[98:101], v[68:71], v[88:91]
	ds_read_b128 v[68:71], v201 offset:50944
	s_waitcnt lgkmcnt(0)
	v_mfma_f32_16x16x32_bf16 v[92:95], v[98:101], v[68:71], v[92:95]
	v_cndmask_b32_e64 v71, 0, v104, s[6:7]
	v_cndmask_b32_e64 v70, 0, v103, s[6:7]
	v_cndmask_b32_e64 v69, 0, v102, s[6:7]
	v_cndmask_b32_e64 v68, 0, v97, s[6:7]
	v_mfma_f32_16x16x32_bf16 v[52:55], v[98:101], v[52:55], v[76:79]
	s_nop 0
	v_mfma_f32_16x16x32_bf16 v[80:83], v[68:71], v[72:75], v[80:83]
	ds_read_b128 v[68:71], v125 offset:1152
	ds_read_b128 v[72:75], v125 offset:1168
	ds_read_b128 v[76:79], v96 offset:53312
	s_waitcnt lgkmcnt(0)
	v_cvt_pk_bf16_f32 v97, v68, v69
	v_cvt_pk_bf16_f32 v102, v70, v71
	v_lshlrev_b32_e32 v98, 16, v76
	v_and_b32_e32 v99, 0xffff0000, v76
	v_lshlrev_b32_e32 v76, 16, v77
	v_and_b32_e32 v77, 0xffff0000, v77
	v_pk_mul_f32 v[98:99], v[68:69], v[98:99]
	v_pk_mul_f32 v[76:77], v[70:71], v[76:77]
	v_cvt_pk_bf16_f32 v98, v98, v99
	v_cvt_pk_bf16_f32 v99, v76, v77
	v_lshlrev_b32_e32 v76, 16, v78
	v_and_b32_e32 v77, 0xffff0000, v78
	v_pk_mul_f32 v[76:77], v[72:73], v[76:77]
	ds_read_b128 v[68:71], v201 offset:34880
	v_cvt_pk_bf16_f32 v100, v76, v77
	v_lshlrev_b32_e32 v76, 16, v79
	v_and_b32_e32 v77, 0xffff0000, v79
	v_pk_mul_f32 v[76:77], v[74:75], v[76:77]
	v_cvt_pk_bf16_f32 v103, v72, v73
	v_cvt_pk_bf16_f32 v101, v76, v77
	v_cvt_pk_bf16_f32 v104, v74, v75
	s_waitcnt lgkmcnt(0)
	v_mfma_f32_16x16x32_bf16 v[48:51], v[98:101], v[68:71], v[48:51]
	ds_read_b128 v[68:71], v201 offset:37184
	s_waitcnt lgkmcnt(0)
	v_mfma_f32_16x16x32_bf16 v[76:79], v[98:101], v[68:71], v[52:55]
	s_nop 2
	ds_read_b128 v[52:55], v201 offset:39488
	s_waitcnt lgkmcnt(0)
	v_mfma_f32_16x16x32_bf16 v[72:75], v[98:101], v[52:55], v[56:59]
	ds_read_b128 v[52:55], v201 offset:41792
	s_waitcnt lgkmcnt(0)
	v_mfma_f32_16x16x32_bf16 v[68:71], v[98:101], v[52:55], v[60:63]
	ds_read_b128 v[52:55], v201 offset:44096
	s_waitcnt lgkmcnt(0)
	v_mfma_f32_16x16x32_bf16 v[64:67], v[98:101], v[52:55], v[64:67]
	ds_read_b128 v[52:55], v201 offset:46400
	s_waitcnt lgkmcnt(0)
	v_mfma_f32_16x16x32_bf16 v[60:63], v[98:101], v[52:55], v[84:87]
	ds_read_b128 v[52:55], v201 offset:48704
	s_nop 1
	v_cndmask_b32_e64 v87, 0, v104, s[6:7]
	v_cndmask_b32_e64 v86, 0, v103, s[6:7]
	s_waitcnt lgkmcnt(0)
	v_mfma_f32_16x16x32_bf16 v[56:59], v[98:101], v[52:55], v[88:91]
	ds_read_b128 v[52:55], v201 offset:51008
	s_nop 1
	ds_read_b128 v[88:91], v96 offset:34880
	v_cndmask_b32_e64 v85, 0, v102, s[6:7]
	s_waitcnt lgkmcnt(0)
	v_mfma_f32_16x16x32_bf16 v[52:55], v[98:101], v[52:55], v[92:95]
	v_cndmask_b32_e64 v84, 0, v97, s[6:7]
	s_nop 1
	v_cvt_pk_bf16_f32 v92, v48, s0
	ds_write_b16 v202, v92
	v_cvt_pk_bf16_f32 v92, v49, s0
	ds_write_b16 v202, v92 offset:272
	v_cvt_pk_bf16_f32 v92, v50, s0
	ds_write_b16 v202, v92 offset:544
	v_cvt_pk_bf16_f32 v92, v51, s0
	ds_write_b16 v202, v92 offset:816
	v_cvt_pk_bf16_f32 v92, v76, s0
	ds_write_b16 v202, v92 offset:32
	v_cvt_pk_bf16_f32 v92, v77, s0
	ds_write_b16 v202, v92 offset:304
	v_cvt_pk_bf16_f32 v92, v78, s0
	ds_write_b16 v202, v92 offset:576
	v_cvt_pk_bf16_f32 v92, v79, s0
	ds_write_b16 v202, v92 offset:848
	v_cvt_pk_bf16_f32 v92, v72, s0
	ds_write_b16 v202, v92 offset:64
	v_cvt_pk_bf16_f32 v92, v73, s0
	ds_write_b16 v202, v92 offset:336
	v_cvt_pk_bf16_f32 v92, v74, s0
	ds_write_b16 v202, v92 offset:608
	v_cvt_pk_bf16_f32 v92, v75, s0
	ds_write_b16 v202, v92 offset:880
	v_cvt_pk_bf16_f32 v92, v68, s0
	ds_write_b16 v202, v92 offset:96
	v_cvt_pk_bf16_f32 v92, v69, s0
	ds_write_b16 v202, v92 offset:368
	v_cvt_pk_bf16_f32 v92, v70, s0
	ds_write_b16 v202, v92 offset:640
	v_cvt_pk_bf16_f32 v92, v71, s0
	ds_write_b16 v202, v92 offset:912
	v_cvt_pk_bf16_f32 v92, v64, s0
	ds_write_b16 v202, v92 offset:128
	v_cvt_pk_bf16_f32 v92, v65, s0
	ds_write_b16 v202, v92 offset:400
	v_cvt_pk_bf16_f32 v92, v66, s0
	ds_write_b16 v202, v92 offset:672
	v_cvt_pk_bf16_f32 v92, v67, s0
	ds_write_b16 v202, v92 offset:944
	v_cvt_pk_bf16_f32 v92, v60, s0
	ds_write_b16 v202, v92 offset:160
	v_cvt_pk_bf16_f32 v92, v61, s0
	ds_write_b16 v202, v92 offset:432
	v_cvt_pk_bf16_f32 v92, v62, s0
	ds_write_b16 v202, v92 offset:704
	v_cvt_pk_bf16_f32 v92, v63, s0
	ds_write_b16 v202, v92 offset:976
	v_cvt_pk_bf16_f32 v92, v56, s0
	ds_write_b16 v202, v92 offset:192
	v_cvt_pk_bf16_f32 v92, v57, s0
	ds_write_b16 v202, v92 offset:464
	v_cvt_pk_bf16_f32 v92, v58, s0
	ds_write_b16 v202, v92 offset:736
	v_cvt_pk_bf16_f32 v92, v59, s0
	ds_write_b16 v202, v92 offset:1008
	v_cvt_pk_bf16_f32 v92, v52, s0
	v_mfma_f32_16x16x32_bf16 v[80:83], v[84:87], v[88:91], v[80:83]
	ds_write_b16 v202, v92 offset:224
	v_cvt_pk_bf16_f32 v92, v53, s0
	ds_write_b16 v202, v92 offset:496
	v_cvt_pk_bf16_f32 v92, v54, s0
	ds_write_b16 v202, v92 offset:768
	v_cvt_pk_bf16_f32 v92, v55, s0
	ds_write_b16 v202, v92 offset:1040
	s_and_saveexec_b64 s[0:1], s[4:5]
	s_cbranch_execz .LBB0_426
	v_cvt_pk_bf16_f32 v84, v80, v81
	ds_write_b16 v182, v84 offset:34816
	s_branch .LBB0_426

.LBB0_466:
	s_ashr_i32 s14, s35, 2
	s_ashr_i32 s15, s14, 31
	s_lshl_b64 s[16:17], s[14:15], 27
	s_add_u32 s1, s27, s16
	s_addc_u32 s9, s28, s17
	s_cmp_lt_i32 s14, 2
	v_mul_f32_e32 v120, 0xbfb8aa3b, v120
	s_cselect_b32 s9, s9, s30
	s_cselect_b32 s1, s1, s29
	s_lshl_b32 s14, s35, 9
	v_exp_f32_e32 v120, v120
	v_mul_f32_e32 v121, 0xbfb8aa3b, v121
	s_and_b32 s14, s14, 0x600
	v_exp_f32_e32 v121, v121
	v_lshl_add_u32 v142, s36, 8, v144
	s_add_u32 s14, s1, s14
	s_addc_u32 s15, s9, 0
	v_ashrrev_i32_e32 v143, 31, v142
	v_mul_f32_e32 v124, 0xbfb8aa3b, v124
	v_lshl_add_u64 v[140:141], v[134:135], 1, s[14:15]
	v_lshlrev_b64 v[148:149], 11, v[142:143]
	v_exp_f32_e32 v143, v124
	v_mul_f32_e32 v124, 0xbfb8aa3b, v125
	v_add_f32_e32 v120, 1.0, v120
	v_exp_f32_e32 v147, v124
	v_lshl_add_u64 v[124:125], v[140:141], 0, v[148:149]
	v_rcp_f32_e32 v148, v120
	v_add_f32_e32 v120, 1.0, v121
	v_mul_f32_e32 v121, 0xbfb8aa3b, v122
	v_mul_f32_e32 v126, 0xbfb8aa3b, v126
	v_mul_f32_e32 v127, 0xbfb8aa3b, v127
	v_exp_f32_e32 v121, v121
	v_mul_f32_e32 v122, 0xbfb8aa3b, v123
	v_exp_f32_e32 v126, v126
	v_exp_f32_e32 v127, v127
	v_exp_f32_e32 v122, v122
	v_rcp_f32_e32 v123, v120
	v_add_f32_e32 v120, 1.0, v121
	v_add_f32_e32 v143, 1.0, v143
	v_add_f32_e32 v147, 1.0, v147
	v_add_f32_e32 v126, 1.0, v126
	v_add_f32_e32 v127, 1.0, v127
	v_rcp_f32_e32 v149, v120
	v_add_f32_e32 v120, 1.0, v122
	v_mul_f32_e32 v112, 0xbfb8aa3b, v112
	v_rcp_f32_e32 v143, v143
	v_rcp_f32_e32 v147, v147
	v_rcp_f32_e32 v126, v126
	v_rcp_f32_e32 v127, v127
	v_rcp_f32_e32 v150, v120
	v_exp_f32_e32 v112, v112
	v_mul_f32_e32 v113, 0xbfb8aa3b, v113
	v_exp_f32_e32 v113, v113
	v_cvt_pk_bf16_f32 v120, v143, v147
	v_cvt_pk_bf16_f32 v121, v126, v127
	v_cvt_pk_bf16_f32 v122, v148, v123
	v_cvt_pk_bf16_f32 v123, v149, v150
	v_add_f32_e32 v112, 1.0, v112
	global_store_dwordx4 v[124:125], v[120:123], off
	v_mul_f32_e32 v116, 0xbfb8aa3b, v116
	v_mul_f32_e32 v117, 0xbfb8aa3b, v117
	v_rcp_f32_e32 v120, v112
	v_add_f32_e32 v112, 1.0, v113
	v_mul_f32_e32 v113, 0xbfb8aa3b, v114
	v_mul_f32_e32 v118, 0xbfb8aa3b, v118
	v_mul_f32_e32 v119, 0xbfb8aa3b, v119
	v_exp_f32_e32 v113, v113
	v_mul_f32_e32 v114, 0xbfb8aa3b, v115
	v_exp_f32_e32 v116, v116
	v_exp_f32_e32 v117, v117
	v_exp_f32_e32 v118, v118
	v_exp_f32_e32 v119, v119
	v_exp_f32_e32 v114, v114
	v_rcp_f32_e32 v115, v112
	v_add_f32_e32 v112, 1.0, v113
	v_add_f32_e32 v116, 1.0, v116
	v_add_f32_e32 v117, 1.0, v117
	v_add_f32_e32 v118, 1.0, v118
	v_add_f32_e32 v119, 1.0, v119
	v_rcp_f32_e32 v121, v112
	v_add_f32_e32 v112, 1.0, v114
	v_rcp_f32_e32 v116, v116
	v_rcp_f32_e32 v117, v117
	v_rcp_f32_e32 v118, v118
	v_rcp_f32_e32 v119, v119
	v_rcp_f32_e32 v122, v112
	v_mul_f32_e32 v104, 0xbfb8aa3b, v104
	v_cvt_pk_bf16_f32 v112, v116, v117
	v_cvt_pk_bf16_f32 v113, v118, v119
	v_cvt_pk_bf16_f32 v114, v120, v115
	v_cvt_pk_bf16_f32 v115, v121, v122
	v_mul_f32_e32 v108, 0xbfb8aa3b, v108
	v_exp_f32_e32 v104, v104
	v_mul_f32_e32 v105, 0xbfb8aa3b, v105
	global_store_dwordx4 v[124:125], v[112:115], off offset:256
	v_exp_f32_e32 v105, v105
	v_add_f32_e32 v104, 1.0, v104
	v_exp_f32_e32 v114, v108
	v_or_b32_e32 v112, 16, v142
	v_ashrrev_i32_e32 v113, 31, v112
	v_lshlrev_b64 v[112:113], 11, v[112:113]
	v_mul_f32_e32 v108, 0xbfb8aa3b, v109
	v_exp_f32_e32 v115, v108
	v_lshl_add_u64 v[108:109], v[140:141], 0, v[112:113]
	v_add_f32_e32 v112, 1.0, v114
	v_rcp_f32_e32 v114, v104
	v_add_f32_e32 v104, 1.0, v105
	v_mul_f32_e32 v105, 0xbfb8aa3b, v106
	v_mul_f32_e32 v110, 0xbfb8aa3b, v110
	v_mul_f32_e32 v111, 0xbfb8aa3b, v111
	v_exp_f32_e32 v105, v105
	v_mul_f32_e32 v106, 0xbfb8aa3b, v107
	v_exp_f32_e32 v110, v110
	v_exp_f32_e32 v111, v111
	v_exp_f32_e32 v106, v106
	v_rcp_f32_e32 v107, v104
	v_add_f32_e32 v104, 1.0, v105
	v_add_f32_e32 v113, 1.0, v115
	v_add_f32_e32 v110, 1.0, v110
	v_add_f32_e32 v111, 1.0, v111
	v_rcp_f32_e32 v115, v104
	v_add_f32_e32 v104, 1.0, v106
	v_mul_f32_e32 v96, 0xbfb8aa3b, v96
	v_rcp_f32_e32 v112, v112
	v_rcp_f32_e32 v113, v113
	v_rcp_f32_e32 v110, v110
	v_rcp_f32_e32 v111, v111
	v_rcp_f32_e32 v116, v104
	v_exp_f32_e32 v96, v96
	v_mul_f32_e32 v97, 0xbfb8aa3b, v97
	v_exp_f32_e32 v97, v97
	v_cvt_pk_bf16_f32 v104, v112, v113
	v_cvt_pk_bf16_f32 v105, v110, v111
	v_cvt_pk_bf16_f32 v106, v114, v107
	v_cvt_pk_bf16_f32 v107, v115, v116
	v_add_f32_e32 v96, 1.0, v96
	global_store_dwordx4 v[108:109], v[104:107], off
	v_mul_f32_e32 v100, 0xbfb8aa3b, v100
	v_mul_f32_e32 v101, 0xbfb8aa3b, v101
	v_rcp_f32_e32 v104, v96
	v_add_f32_e32 v96, 1.0, v97
	v_mul_f32_e32 v97, 0xbfb8aa3b, v98
	v_mul_f32_e32 v102, 0xbfb8aa3b, v102
	v_mul_f32_e32 v103, 0xbfb8aa3b, v103
	v_exp_f32_e32 v97, v97
	v_mul_f32_e32 v98, 0xbfb8aa3b, v99
	v_exp_f32_e32 v100, v100
	v_exp_f32_e32 v101, v101
	v_exp_f32_e32 v102, v102
	v_exp_f32_e32 v103, v103
	v_exp_f32_e32 v98, v98
	v_rcp_f32_e32 v99, v96
	v_add_f32_e32 v96, 1.0, v97
	v_add_f32_e32 v100, 1.0, v100
	v_add_f32_e32 v101, 1.0, v101
	v_add_f32_e32 v102, 1.0, v102
	v_add_f32_e32 v103, 1.0, v103
	v_rcp_f32_e32 v105, v96
	v_add_f32_e32 v96, 1.0, v98
	v_rcp_f32_e32 v100, v100
	v_rcp_f32_e32 v101, v101
	v_rcp_f32_e32 v102, v102
	v_rcp_f32_e32 v103, v103
	v_rcp_f32_e32 v106, v96
	v_mul_f32_e32 v88, 0xbfb8aa3b, v88
	v_cvt_pk_bf16_f32 v96, v100, v101
	v_cvt_pk_bf16_f32 v97, v102, v103
	v_cvt_pk_bf16_f32 v98, v104, v99
	v_cvt_pk_bf16_f32 v99, v105, v106
	v_mul_f32_e32 v92, 0xbfb8aa3b, v92
	v_exp_f32_e32 v88, v88
	v_mul_f32_e32 v89, 0xbfb8aa3b, v89
	global_store_dwordx4 v[108:109], v[96:99], off offset:256
	v_exp_f32_e32 v89, v89
	v_add_f32_e32 v88, 1.0, v88
	v_exp_f32_e32 v98, v92
	v_or_b32_e32 v96, 32, v142
	v_ashrrev_i32_e32 v97, 31, v96
	v_lshlrev_b64 v[96:97], 11, v[96:97]
	v_mul_f32_e32 v92, 0xbfb8aa3b, v93
	v_exp_f32_e32 v99, v92
	v_lshl_add_u64 v[92:93], v[140:141], 0, v[96:97]
	v_add_f32_e32 v96, 1.0, v98
	v_rcp_f32_e32 v98, v88
	v_add_f32_e32 v88, 1.0, v89
	v_mul_f32_e32 v89, 0xbfb8aa3b, v90
	v_mul_f32_e32 v94, 0xbfb8aa3b, v94
	v_mul_f32_e32 v95, 0xbfb8aa3b, v95
	v_exp_f32_e32 v89, v89
	v_mul_f32_e32 v90, 0xbfb8aa3b, v91
	v_exp_f32_e32 v94, v94
	v_exp_f32_e32 v95, v95
	v_exp_f32_e32 v90, v90
	v_rcp_f32_e32 v91, v88
	v_add_f32_e32 v88, 1.0, v89
	v_add_f32_e32 v97, 1.0, v99
	v_add_f32_e32 v94, 1.0, v94
	v_add_f32_e32 v95, 1.0, v95
	v_rcp_f32_e32 v99, v88
	v_add_f32_e32 v88, 1.0, v90
	v_mul_f32_e32 v80, 0xbfb8aa3b, v80
	v_rcp_f32_e32 v96, v96
	v_rcp_f32_e32 v97, v97
	v_rcp_f32_e32 v94, v94
	v_rcp_f32_e32 v95, v95
	v_rcp_f32_e32 v100, v88
	v_exp_f32_e32 v80, v80
	v_mul_f32_e32 v81, 0xbfb8aa3b, v81
	v_exp_f32_e32 v81, v81
	v_cvt_pk_bf16_f32 v88, v96, v97
	v_cvt_pk_bf16_f32 v89, v94, v95
	v_cvt_pk_bf16_f32 v90, v98, v91
	v_cvt_pk_bf16_f32 v91, v99, v100
	v_add_f32_e32 v80, 1.0, v80
	global_store_dwordx4 v[92:93], v[88:91], off
	v_mul_f32_e32 v84, 0xbfb8aa3b, v84
	v_mul_f32_e32 v85, 0xbfb8aa3b, v85
	v_rcp_f32_e32 v88, v80
	v_add_f32_e32 v80, 1.0, v81
	v_mul_f32_e32 v81, 0xbfb8aa3b, v82
	v_mul_f32_e32 v86, 0xbfb8aa3b, v86
	v_mul_f32_e32 v87, 0xbfb8aa3b, v87
	v_exp_f32_e32 v81, v81
	v_mul_f32_e32 v82, 0xbfb8aa3b, v83
	v_exp_f32_e32 v84, v84
	v_exp_f32_e32 v85, v85
	v_exp_f32_e32 v86, v86
	v_exp_f32_e32 v87, v87
	v_exp_f32_e32 v82, v82
	v_rcp_f32_e32 v83, v80
	v_add_f32_e32 v80, 1.0, v81
	v_add_f32_e32 v84, 1.0, v84
	v_add_f32_e32 v85, 1.0, v85
	v_add_f32_e32 v86, 1.0, v86
	v_add_f32_e32 v87, 1.0, v87
	v_rcp_f32_e32 v89, v80
	v_add_f32_e32 v80, 1.0, v82
	v_rcp_f32_e32 v84, v84
	v_rcp_f32_e32 v85, v85
	v_rcp_f32_e32 v86, v86
	v_rcp_f32_e32 v87, v87
	v_rcp_f32_e32 v90, v80
	v_mul_f32_e32 v72, 0xbfb8aa3b, v72
	v_cvt_pk_bf16_f32 v80, v84, v85
	v_cvt_pk_bf16_f32 v81, v86, v87
	v_cvt_pk_bf16_f32 v82, v88, v83
	v_cvt_pk_bf16_f32 v83, v89, v90
	v_mul_f32_e32 v76, 0xbfb8aa3b, v76
	v_exp_f32_e32 v72, v72
	v_mul_f32_e32 v73, 0xbfb8aa3b, v73
	global_store_dwordx4 v[92:93], v[80:83], off offset:256
	v_exp_f32_e32 v73, v73
	v_add_f32_e32 v72, 1.0, v72
	v_exp_f32_e32 v82, v76
	v_or_b32_e32 v80, 48, v142
	v_ashrrev_i32_e32 v81, 31, v80
	v_lshlrev_b64 v[80:81], 11, v[80:81]
	v_mul_f32_e32 v76, 0xbfb8aa3b, v77
	v_exp_f32_e32 v83, v76
	v_lshl_add_u64 v[76:77], v[140:141], 0, v[80:81]
	v_add_f32_e32 v80, 1.0, v82
	v_rcp_f32_e32 v82, v72
	v_add_f32_e32 v72, 1.0, v73
	v_mul_f32_e32 v73, 0xbfb8aa3b, v74
	v_mul_f32_e32 v78, 0xbfb8aa3b, v78
	v_mul_f32_e32 v79, 0xbfb8aa3b, v79
	v_exp_f32_e32 v73, v73
	v_mul_f32_e32 v74, 0xbfb8aa3b, v75
	v_exp_f32_e32 v78, v78
	v_exp_f32_e32 v79, v79
	v_exp_f32_e32 v74, v74
	v_rcp_f32_e32 v75, v72
	v_add_f32_e32 v72, 1.0, v73
	v_add_f32_e32 v81, 1.0, v83
	v_add_f32_e32 v78, 1.0, v78
	v_add_f32_e32 v79, 1.0, v79
	v_rcp_f32_e32 v83, v72
	v_add_f32_e32 v72, 1.0, v74
	v_mul_f32_e32 v64, 0xbfb8aa3b, v64
	v_rcp_f32_e32 v80, v80
	v_rcp_f32_e32 v81, v81
	v_rcp_f32_e32 v78, v78
	v_rcp_f32_e32 v79, v79
	v_rcp_f32_e32 v84, v72
	v_exp_f32_e32 v64, v64
	v_mul_f32_e32 v65, 0xbfb8aa3b, v65
	v_exp_f32_e32 v65, v65
	v_cvt_pk_bf16_f32 v72, v80, v81
	v_cvt_pk_bf16_f32 v73, v78, v79
	v_cvt_pk_bf16_f32 v74, v82, v75
	v_cvt_pk_bf16_f32 v75, v83, v84
	v_add_f32_e32 v64, 1.0, v64
	global_store_dwordx4 v[76:77], v[72:75], off
	v_mul_f32_e32 v68, 0xbfb8aa3b, v68
	v_mul_f32_e32 v69, 0xbfb8aa3b, v69
	v_rcp_f32_e32 v72, v64
	v_add_f32_e32 v64, 1.0, v65
	v_mul_f32_e32 v65, 0xbfb8aa3b, v66
	v_mul_f32_e32 v70, 0xbfb8aa3b, v70
	v_mul_f32_e32 v71, 0xbfb8aa3b, v71
	v_exp_f32_e32 v65, v65
	v_mul_f32_e32 v66, 0xbfb8aa3b, v67
	v_exp_f32_e32 v68, v68
	v_exp_f32_e32 v69, v69
	v_exp_f32_e32 v70, v70
	v_exp_f32_e32 v71, v71
	v_exp_f32_e32 v66, v66
	v_rcp_f32_e32 v67, v64
	v_add_f32_e32 v64, 1.0, v65
	v_add_f32_e32 v68, 1.0, v68
	v_add_f32_e32 v69, 1.0, v69
	v_add_f32_e32 v70, 1.0, v70
	v_add_f32_e32 v71, 1.0, v71
	v_rcp_f32_e32 v73, v64
	v_add_f32_e32 v64, 1.0, v66
	v_mul_f32_e32 v56, 0xbfb8aa3b, v56
	v_rcp_f32_e32 v68, v68
	v_rcp_f32_e32 v69, v69
	v_rcp_f32_e32 v70, v70
	v_rcp_f32_e32 v71, v71
	v_rcp_f32_e32 v74, v64
	v_exp_f32_e32 v56, v56
	v_mul_f32_e32 v57, 0xbfb8aa3b, v57
	v_exp_f32_e32 v57, v57
	v_cvt_pk_bf16_f32 v64, v68, v69
	v_cvt_pk_bf16_f32 v65, v70, v71
	v_cvt_pk_bf16_f32 v66, v72, v67
	v_cvt_pk_bf16_f32 v67, v73, v74
	v_add_f32_e32 v56, 1.0, v56
	global_store_dwordx4 v[76:77], v[64:67], off offset:256
	v_mul_f32_e32 v60, 0xbfb8aa3b, v60
	v_mul_f32_e32 v62, 0xbfb8aa3b, v62
	v_mul_f32_e32 v63, 0xbfb8aa3b, v63
	v_rcp_f32_e32 v66, v56
	v_add_f32_e32 v56, 1.0, v57
	v_mul_f32_e32 v57, 0xbfb8aa3b, v58
	v_exp_f32_e32 v64, v60
	v_mul_f32_e32 v60, 0xbfb8aa3b, v61
	v_exp_f32_e32 v62, v62
	v_exp_f32_e32 v63, v63
	v_exp_f32_e32 v57, v57
	v_mul_f32_e32 v58, 0xbfb8aa3b, v59
	v_exp_f32_e32 v65, v60
	v_exp_f32_e32 v58, v58
	v_add_f32_e32 v62, 1.0, v62
	v_add_f32_e32 v63, 1.0, v63
	v_rcp_f32_e32 v59, v56
	v_add_f32_e32 v56, 1.0, v57
	v_add_f32_e32 v64, 1.0, v64
	v_add_f32_e32 v65, 1.0, v65
	v_rcp_f32_e32 v62, v62
	v_rcp_f32_e32 v63, v63
	v_rcp_f32_e32 v67, v56
	v_add_f32_e32 v56, 1.0, v58
	v_mul_f32_e32 v48, 0xbfb8aa3b, v48
	v_rcp_f32_e32 v64, v64
	v_rcp_f32_e32 v65, v65
	v_rcp_f32_e32 v68, v56
	v_exp_f32_e32 v48, v48
	v_mul_f32_e32 v49, 0xbfb8aa3b, v49
	v_exp_f32_e32 v49, v49
	s_mov_b32 s1, 0x40000
	v_cvt_pk_bf16_f32 v57, v62, v63
	v_add_co_u32_e32 v62, vcc, s1, v124
	v_cvt_pk_bf16_f32 v56, v64, v65
	v_cvt_pk_bf16_f32 v58, v66, v59
	v_cvt_pk_bf16_f32 v59, v67, v68
	v_addc_co_u32_e32 v63, vcc, 0, v125, vcc
	v_add_f32_e32 v48, 1.0, v48
	global_store_dwordx4 v[62:63], v[56:59], off
	v_mul_f32_e32 v52, 0xbfb8aa3b, v52
	v_mul_f32_e32 v53, 0xbfb8aa3b, v53
	v_rcp_f32_e32 v56, v48
	v_add_f32_e32 v48, 1.0, v49
	v_mul_f32_e32 v49, 0xbfb8aa3b, v50
	v_mul_f32_e32 v54, 0xbfb8aa3b, v54
	v_mul_f32_e32 v55, 0xbfb8aa3b, v55
	v_exp_f32_e32 v49, v49
	v_mul_f32_e32 v50, 0xbfb8aa3b, v51
	v_exp_f32_e32 v52, v52
	v_exp_f32_e32 v53, v53
	v_exp_f32_e32 v54, v54
	v_exp_f32_e32 v55, v55
	v_exp_f32_e32 v50, v50
	v_rcp_f32_e32 v51, v48
	v_add_f32_e32 v48, 1.0, v49
	v_add_f32_e32 v52, 1.0, v52
	v_add_f32_e32 v53, 1.0, v53
	v_add_f32_e32 v54, 1.0, v54
	v_add_f32_e32 v55, 1.0, v55
	v_rcp_f32_e32 v57, v48
	v_add_f32_e32 v48, 1.0, v50
	v_mul_f32_e32 v40, 0xbfb8aa3b, v40
	v_rcp_f32_e32 v52, v52
	v_rcp_f32_e32 v53, v53
	v_rcp_f32_e32 v54, v54
	v_rcp_f32_e32 v55, v55
	v_rcp_f32_e32 v58, v48
	v_exp_f32_e32 v40, v40
	v_mul_f32_e32 v41, 0xbfb8aa3b, v41
	v_exp_f32_e32 v41, v41
	s_mov_b64 s[14:15], 0x40000
	v_lshl_add_u64 v[60:61], v[124:125], 0, s[14:15]
	v_cvt_pk_bf16_f32 v48, v52, v53
	v_cvt_pk_bf16_f32 v49, v54, v55
	v_cvt_pk_bf16_f32 v50, v56, v51
	v_cvt_pk_bf16_f32 v51, v57, v58
	v_add_f32_e32 v40, 1.0, v40
	global_store_dwordx4 v[60:61], v[48:51], off offset:256
	v_mul_f32_e32 v44, 0xbfb8aa3b, v44
	v_mul_f32_e32 v46, 0xbfb8aa3b, v46
	v_mul_f32_e32 v47, 0xbfb8aa3b, v47
	v_rcp_f32_e32 v50, v40
	v_add_f32_e32 v40, 1.0, v41
	v_mul_f32_e32 v41, 0xbfb8aa3b, v42
	v_exp_f32_e32 v48, v44
	v_mul_f32_e32 v44, 0xbfb8aa3b, v45
	v_exp_f32_e32 v46, v46
	v_exp_f32_e32 v47, v47
	v_exp_f32_e32 v41, v41
	v_mul_f32_e32 v42, 0xbfb8aa3b, v43
	v_exp_f32_e32 v49, v44
	v_exp_f32_e32 v42, v42
	v_add_f32_e32 v46, 1.0, v46
	v_add_f32_e32 v47, 1.0, v47
	v_rcp_f32_e32 v43, v40
	v_add_f32_e32 v40, 1.0, v41
	v_add_f32_e32 v48, 1.0, v48
	v_add_f32_e32 v49, 1.0, v49
	v_rcp_f32_e32 v46, v46
	v_rcp_f32_e32 v47, v47
	v_rcp_f32_e32 v51, v40
	v_add_f32_e32 v40, 1.0, v42
	v_mul_f32_e32 v32, 0xbfb8aa3b, v32
	v_rcp_f32_e32 v48, v48
	v_rcp_f32_e32 v49, v49
	v_rcp_f32_e32 v52, v40
	v_exp_f32_e32 v32, v32
	v_mul_f32_e32 v33, 0xbfb8aa3b, v33
	v_exp_f32_e32 v33, v33
	s_mov_b32 s1, 0x48000
	v_cvt_pk_bf16_f32 v41, v46, v47
	v_add_co_u32_e32 v46, vcc, s1, v124
	v_cvt_pk_bf16_f32 v40, v48, v49
	v_cvt_pk_bf16_f32 v42, v50, v43
	v_cvt_pk_bf16_f32 v43, v51, v52
	v_addc_co_u32_e32 v47, vcc, 0, v125, vcc
	v_add_f32_e32 v32, 1.0, v32
	global_store_dwordx4 v[46:47], v[40:43], off
	v_mul_f32_e32 v36, 0xbfb8aa3b, v36
	v_mul_f32_e32 v37, 0xbfb8aa3b, v37
	v_rcp_f32_e32 v40, v32
	v_add_f32_e32 v32, 1.0, v33
	v_mul_f32_e32 v33, 0xbfb8aa3b, v34
	v_mul_f32_e32 v38, 0xbfb8aa3b, v38
	v_mul_f32_e32 v39, 0xbfb8aa3b, v39
	v_exp_f32_e32 v33, v33
	v_mul_f32_e32 v34, 0xbfb8aa3b, v35
	v_exp_f32_e32 v36, v36
	v_exp_f32_e32 v37, v37
	v_exp_f32_e32 v38, v38
	v_exp_f32_e32 v39, v39
	v_exp_f32_e32 v34, v34
	v_rcp_f32_e32 v35, v32
	v_add_f32_e32 v32, 1.0, v33
	v_add_f32_e32 v36, 1.0, v36
	v_add_f32_e32 v37, 1.0, v37
	v_add_f32_e32 v38, 1.0, v38
	v_add_f32_e32 v39, 1.0, v39
	v_rcp_f32_e32 v41, v32
	v_add_f32_e32 v32, 1.0, v34
	v_mul_f32_e32 v24, 0xbfb8aa3b, v24
	v_rcp_f32_e32 v36, v36
	v_rcp_f32_e32 v37, v37
	v_rcp_f32_e32 v38, v38
	v_rcp_f32_e32 v39, v39
	v_rcp_f32_e32 v42, v32
	v_exp_f32_e32 v24, v24
	v_mul_f32_e32 v25, 0xbfb8aa3b, v25
	v_exp_f32_e32 v25, v25
	s_mov_b64 s[14:15], 0x48000
	v_lshl_add_u64 v[44:45], v[124:125], 0, s[14:15]
	v_cvt_pk_bf16_f32 v32, v36, v37
	v_cvt_pk_bf16_f32 v33, v38, v39
	v_cvt_pk_bf16_f32 v34, v40, v35
	v_cvt_pk_bf16_f32 v35, v41, v42
	v_add_f32_e32 v24, 1.0, v24
	global_store_dwordx4 v[44:45], v[32:35], off offset:256
	v_mul_f32_e32 v28, 0xbfb8aa3b, v28
	v_mul_f32_e32 v30, 0xbfb8aa3b, v30
	v_mul_f32_e32 v31, 0xbfb8aa3b, v31
	v_rcp_f32_e32 v34, v24
	v_add_f32_e32 v24, 1.0, v25
	v_mul_f32_e32 v25, 0xbfb8aa3b, v26
	v_exp_f32_e32 v32, v28
	v_mul_f32_e32 v28, 0xbfb8aa3b, v29
	v_exp_f32_e32 v30, v30
	v_exp_f32_e32 v31, v31
	v_exp_f32_e32 v25, v25
	v_mul_f32_e32 v26, 0xbfb8aa3b, v27
	v_exp_f32_e32 v33, v28
	v_exp_f32_e32 v26, v26
	v_add_f32_e32 v30, 1.0, v30
	v_add_f32_e32 v31, 1.0, v31
	v_rcp_f32_e32 v27, v24
	v_add_f32_e32 v24, 1.0, v25
	v_add_f32_e32 v32, 1.0, v32
	v_add_f32_e32 v33, 1.0, v33
	v_rcp_f32_e32 v30, v30
	v_rcp_f32_e32 v31, v31
	v_rcp_f32_e32 v35, v24
	v_add_f32_e32 v24, 1.0, v26
	v_mul_f32_e32 v16, 0xbfb8aa3b, v16
	v_rcp_f32_e32 v32, v32
	v_rcp_f32_e32 v33, v33
	v_rcp_f32_e32 v36, v24
	v_exp_f32_e32 v16, v16
	v_mul_f32_e32 v17, 0xbfb8aa3b, v17
	v_exp_f32_e32 v17, v17
	s_mov_b32 s1, 0x50000
	v_cvt_pk_bf16_f32 v25, v30, v31
	v_add_co_u32_e32 v30, vcc, s1, v124
	v_cvt_pk_bf16_f32 v24, v32, v33
	v_cvt_pk_bf16_f32 v26, v34, v27
	v_cvt_pk_bf16_f32 v27, v35, v36
	v_addc_co_u32_e32 v31, vcc, 0, v125, vcc
	v_add_f32_e32 v16, 1.0, v16
	global_store_dwordx4 v[30:31], v[24:27], off
	v_mul_f32_e32 v20, 0xbfb8aa3b, v20
	v_mul_f32_e32 v21, 0xbfb8aa3b, v21
	v_rcp_f32_e32 v24, v16
	v_add_f32_e32 v16, 1.0, v17
	v_mul_f32_e32 v17, 0xbfb8aa3b, v18
	v_mul_f32_e32 v22, 0xbfb8aa3b, v22
	v_mul_f32_e32 v23, 0xbfb8aa3b, v23
	v_exp_f32_e32 v17, v17
	v_mul_f32_e32 v18, 0xbfb8aa3b, v19
	v_exp_f32_e32 v20, v20
	v_exp_f32_e32 v21, v21
	v_exp_f32_e32 v22, v22
	v_exp_f32_e32 v23, v23
	v_exp_f32_e32 v18, v18
	v_rcp_f32_e32 v19, v16
	v_add_f32_e32 v16, 1.0, v17
	v_add_f32_e32 v20, 1.0, v20
	v_add_f32_e32 v21, 1.0, v21
	v_add_f32_e32 v22, 1.0, v22
	v_add_f32_e32 v23, 1.0, v23
	v_rcp_f32_e32 v25, v16
	v_add_f32_e32 v16, 1.0, v18
	v_mul_f32_e32 v8, 0xbfb8aa3b, v8
	v_rcp_f32_e32 v20, v20
	v_rcp_f32_e32 v21, v21
	v_rcp_f32_e32 v22, v22
	v_rcp_f32_e32 v23, v23
	v_rcp_f32_e32 v26, v16
	v_exp_f32_e32 v8, v8
	v_mul_f32_e32 v9, 0xbfb8aa3b, v9
	v_exp_f32_e32 v9, v9
	s_mov_b64 s[14:15], 0x50000
	v_lshl_add_u64 v[28:29], v[124:125], 0, s[14:15]
	v_cvt_pk_bf16_f32 v16, v20, v21
	v_cvt_pk_bf16_f32 v17, v22, v23
	v_cvt_pk_bf16_f32 v18, v24, v19
	v_cvt_pk_bf16_f32 v19, v25, v26
	v_add_f32_e32 v8, 1.0, v8
	global_store_dwordx4 v[28:29], v[16:19], off offset:256
	v_mul_f32_e32 v12, 0xbfb8aa3b, v12
	v_mul_f32_e32 v14, 0xbfb8aa3b, v14
	v_mul_f32_e32 v15, 0xbfb8aa3b, v15
	v_rcp_f32_e32 v18, v8
	v_add_f32_e32 v8, 1.0, v9
	v_mul_f32_e32 v9, 0xbfb8aa3b, v10
	v_exp_f32_e32 v16, v12
	v_mul_f32_e32 v12, 0xbfb8aa3b, v13
	v_exp_f32_e32 v14, v14
	v_exp_f32_e32 v15, v15
	v_exp_f32_e32 v9, v9
	v_mul_f32_e32 v10, 0xbfb8aa3b, v11
	v_exp_f32_e32 v17, v12
	v_exp_f32_e32 v10, v10
	v_add_f32_e32 v14, 1.0, v14
	v_add_f32_e32 v15, 1.0, v15
	v_rcp_f32_e32 v11, v8
	v_add_f32_e32 v8, 1.0, v9
	v_add_f32_e32 v16, 1.0, v16
	v_add_f32_e32 v17, 1.0, v17
	v_rcp_f32_e32 v14, v14
	v_rcp_f32_e32 v15, v15
	v_rcp_f32_e32 v19, v8
	v_add_f32_e32 v8, 1.0, v10
	v_mul_f32_e32 v0, 0xbfb8aa3b, v0
	v_rcp_f32_e32 v16, v16
	v_rcp_f32_e32 v17, v17
	v_rcp_f32_e32 v20, v8
	v_exp_f32_e32 v0, v0
	v_mul_f32_e32 v1, 0xbfb8aa3b, v1
	v_exp_f32_e32 v1, v1
	s_mov_b32 s1, 0x58000
	v_cvt_pk_bf16_f32 v9, v14, v15
	v_add_co_u32_e32 v14, vcc, s1, v124
	v_cvt_pk_bf16_f32 v8, v16, v17
	v_cvt_pk_bf16_f32 v10, v18, v11
	v_cvt_pk_bf16_f32 v11, v19, v20
	v_addc_co_u32_e32 v15, vcc, 0, v125, vcc
	v_add_f32_e32 v0, 1.0, v0
	global_store_dwordx4 v[14:15], v[8:11], off
	v_mul_f32_e32 v4, 0xbfb8aa3b, v4
	v_mul_f32_e32 v5, 0xbfb8aa3b, v5
	v_rcp_f32_e32 v8, v0
	v_add_f32_e32 v0, 1.0, v1
	v_mul_f32_e32 v1, 0xbfb8aa3b, v2
	v_mul_f32_e32 v6, 0xbfb8aa3b, v6
	v_mul_f32_e32 v7, 0xbfb8aa3b, v7
	v_exp_f32_e32 v1, v1
	v_mul_f32_e32 v2, 0xbfb8aa3b, v3
	v_exp_f32_e32 v4, v4
	v_exp_f32_e32 v5, v5
	v_exp_f32_e32 v6, v6
	v_exp_f32_e32 v7, v7
	v_exp_f32_e32 v2, v2
	v_rcp_f32_e32 v3, v0
	v_add_f32_e32 v0, 1.0, v1
	v_add_f32_e32 v4, 1.0, v4
	v_add_f32_e32 v5, 1.0, v5
	v_add_f32_e32 v6, 1.0, v6
	v_add_f32_e32 v7, 1.0, v7
	v_rcp_f32_e32 v9, v0
	v_add_f32_e32 v0, 1.0, v2
	v_rcp_f32_e32 v4, v4
	v_rcp_f32_e32 v5, v5
	v_rcp_f32_e32 v6, v6
	v_rcp_f32_e32 v7, v7
	v_rcp_f32_e32 v10, v0
	s_mov_b64 s[14:15], 0x58000
	v_lshl_add_u64 v[12:13], v[124:125], 0, s[14:15]
	v_cvt_pk_bf16_f32 v0, v4, v5
	v_cvt_pk_bf16_f32 v1, v6, v7
	v_cvt_pk_bf16_f32 v2, v8, v3
	v_cvt_pk_bf16_f32 v3, v9, v10
	s_andn2_b64 vcc, exec, s[6:7]
	s_mov_b64 s[6:7], -1
	global_store_dwordx4 v[12:13], v[0:3], off offset:256
	s_cbranch_vccnz .LBB0_459
	s_and_b64 vcc, exec, s[4:5]
	s_cbranch_vccnz .LBB0_458
	s_barrier
	s_branch .LBB0_458

.LBB0_489:
	s_cmp_gt_u32 s2, 16
	s_cbranch_scc0 .LBB0_493
	v_readlane_b32 s8, v254, 6
	v_readlane_b32 s9, v254, 7
	s_andn2_b64 vcc, exec, s[8:9]
	s_cbranch_vccnz .LBB0_492
	v_or_b32_e32 v130, 16, v190
	v_ashrrev_i32_e32 v191, 31, v190
	v_ashrrev_i32_e32 v131, 31, v130
	v_lshlrev_b64 v[128:129], 7, v[190:191]
	v_lshlrev_b64 v[130:131], 7, v[130:131]
	v_lshl_add_u64 v[128:129], v[180:181], 0, v[128:129]
	v_lshl_add_u64 v[130:131], v[180:181], 0, v[130:131]
	global_store_dwordx4 v[128:129], v[124:127], off
	global_store_dwordx4 v[128:129], v[120:123], off offset:16
	global_store_dwordx4 v[130:131], v[108:111], off
	global_store_dwordx4 v[130:131], v[104:107], off offset:16
	v_or_b32_e32 v130, 32, v190
	v_ashrrev_i32_e32 v131, 31, v130
	v_lshlrev_b64 v[130:131], 7, v[130:131]
	v_lshl_add_u64 v[130:131], v[180:181], 0, v[130:131]
	global_store_dwordx4 v[130:131], v[92:95], off
	global_store_dwordx4 v[130:131], v[88:91], off offset:16
	v_or_b32_e32 v130, 48, v190
	v_ashrrev_i32_e32 v131, 31, v130
	v_lshlrev_b64 v[130:131], 7, v[130:131]
	v_lshl_add_u64 v[130:131], v[180:181], 0, v[130:131]
	s_mov_b64 s[8:9], 0x4000
	global_store_dwordx4 v[130:131], v[76:79], off
	global_store_dwordx4 v[130:131], v[72:75], off offset:16
	v_lshl_add_u64 v[130:131], v[128:129], 0, s[8:9]
	s_movk_i32 s8, 0x4000
	v_add_co_u32_e32 v132, vcc, s8, v128
	s_mov_b64 s[8:9], 0x4800
	s_nop 0
	v_addc_co_u32_e32 v133, vcc, 0, v129, vcc
	global_store_dwordx4 v[132:133], v[60:63], off
	global_store_dwordx4 v[130:131], v[56:59], off offset:16
	v_lshl_add_u64 v[130:131], v[128:129], 0, s[8:9]
	global_store_dwordx4 v[132:133], v[44:47], off offset:2048
	global_store_dwordx4 v[130:131], v[40:43], off offset:16
	s_mov_b64 s[8:9], 0x5000
	v_add_co_u32_e32 v132, vcc, 0x5000, v128
	v_lshl_add_u64 v[130:131], v[128:129], 0, s[8:9]
	s_nop 0
	v_addc_co_u32_e32 v133, vcc, 0, v129, vcc
	s_mov_b64 s[8:9], 0x5800
	global_store_dwordx4 v[132:133], v[28:31], off
	global_store_dwordx4 v[130:131], v[24:27], off offset:16
	v_lshl_add_u64 v[128:129], v[128:129], 0, s[8:9]
	global_store_dwordx4 v[132:133], v[12:15], off offset:2048
	global_store_dwordx4 v[128:129], v[8:11], off offset:16

.LBB0_493:
	s_andn2_b64 vcc, exec, s[8:9]
	s_cbranch_vccnz .LBB0_500
	s_cmp_eq_u32 s2, 14
	s_cselect_b64 s[8:9], -1, 0
	s_cmp_lg_u32 s2, 14
	v_cvt_pk_bf16_f32 v156, v116, v117
	v_cvt_pk_bf16_f32 v157, v118, v119
	v_cvt_pk_bf16_f32 v158, v112, v113
	v_cvt_pk_bf16_f32 v159, v114, v115
	v_cvt_pk_bf16_f32 v152, v100, v101
	v_cvt_pk_bf16_f32 v153, v102, v103
	v_cvt_pk_bf16_f32 v154, v96, v97
	v_cvt_pk_bf16_f32 v155, v98, v99
	v_cvt_pk_bf16_f32 v148, v84, v85
	v_cvt_pk_bf16_f32 v149, v86, v87
	v_cvt_pk_bf16_f32 v150, v80, v81
	v_cvt_pk_bf16_f32 v151, v82, v83
	v_cvt_pk_bf16_f32 v144, v68, v69
	v_cvt_pk_bf16_f32 v145, v70, v71
	v_cvt_pk_bf16_f32 v146, v64, v65
	v_cvt_pk_bf16_f32 v147, v66, v67
	v_add_u32_e32 v191, 0x80, v190
	v_cvt_pk_bf16_f32 v140, v52, v53
	v_cvt_pk_bf16_f32 v141, v54, v55
	v_cvt_pk_bf16_f32 v142, v48, v49
	v_cvt_pk_bf16_f32 v143, v50, v51
	v_cvt_pk_bf16_f32 v136, v36, v37
	v_cvt_pk_bf16_f32 v137, v38, v39
	v_cvt_pk_bf16_f32 v138, v32, v33
	v_cvt_pk_bf16_f32 v139, v34, v35
	v_cvt_pk_bf16_f32 v132, v20, v21
	v_cvt_pk_bf16_f32 v133, v22, v23
	v_cvt_pk_bf16_f32 v134, v16, v17
	v_cvt_pk_bf16_f32 v135, v18, v19
	v_cvt_pk_bf16_f32 v128, v4, v5
	v_cvt_pk_bf16_f32 v129, v6, v7
	v_cvt_pk_bf16_f32 v130, v0, v1
	v_cvt_pk_bf16_f32 v131, v2, v3
	s_cbranch_scc0 .LBB0_496
	s_lshl_b32 s11, s2, 1
	s_sub_i32 s82, s11, 27
	s_lshl_b64 s[16:17], s[82:83], 24
	v_lshl_add_u64 v[166:167], v[182:183], 0, s[16:17]
	s_ashr_i32 s16, s1, 11
	s_ashr_i32 s17, s16, 31
	s_lshl_b64 s[16:17], s[16:17], 19
	v_and_b32_e32 v160, 0x7cf, v190
	v_lshl_add_u64 v[168:169], v[166:167], 0, s[16:17]
	v_lshlrev_b32_e32 v160, 1, v160
	v_lshl_add_u64 v[168:169], v[168:169], 0, v[160:161]
	s_movk_i32 s1, 0x1000
	v_add_co_u32_e32 v192, vcc, s1, v168
	s_movk_i32 s16, 0x2000
	s_nop 0
	v_addc_co_u32_e32 v193, vcc, 0, v169, vcc
	v_add_co_u32_e32 v194, vcc, s16, v168
	s_movk_i32 s18, 0x3000
	s_nop 0
	v_addc_co_u32_e32 v195, vcc, 0, v169, vcc
	v_add_co_u32_e32 v196, vcc, s18, v168
	s_movk_i32 s17, 0x4000
	s_nop 0
	v_addc_co_u32_e32 v197, vcc, 0, v169, vcc
	v_add_co_u32_e32 v198, vcc, s17, v168
	s_movk_i32 s19, 0x5000
	s_nop 0
	v_addc_co_u32_e32 v199, vcc, 0, v169, vcc
	v_add_co_u32_e32 v200, vcc, s19, v168
	v_cvt_pk_bf16_f32 v160, v117, s0
	s_nop 0
	v_addc_co_u32_e32 v201, vcc, 0, v169, vcc
	v_add_co_u32_e32 v202, vcc, s89, v168
	global_store_short v[192:193], v160, off
	v_cvt_pk_bf16_f32 v160, v119, s0
	v_addc_co_u32_e32 v203, vcc, 0, v169, vcc
	s_movk_i32 s31, 0x7000
	global_store_short v[196:197], v160, off
	v_cvt_pk_bf16_f32 v160, v113, s0
	v_add_co_u32_e32 v204, vcc, s31, v168
	global_store_short v[200:201], v160, off
	v_cvt_pk_bf16_f32 v160, v115, s0
	v_addc_co_u32_e32 v205, vcc, 0, v169, vcc
	global_store_short v[168:169], v156, off
	global_store_short v[194:195], v157, off
	global_store_short v[198:199], v158, off
	global_store_short v[202:203], v159, off
	global_store_short v[204:205], v160, off
	global_store_short v[168:169], v152, off offset:32
	v_cvt_pk_bf16_f32 v160, v101, s0
	global_store_short v[192:193], v160, off offset:32
	global_store_short v[194:195], v153, off offset:32
	v_cvt_pk_bf16_f32 v160, v103, s0
	global_store_short v[196:197], v160, off offset:32
	global_store_short v[198:199], v154, off offset:32
	v_cvt_pk_bf16_f32 v160, v97, s0
	global_store_short v[200:201], v160, off offset:32
	global_store_short v[202:203], v155, off offset:32
	v_cvt_pk_bf16_f32 v160, v99, s0
	global_store_short v[204:205], v160, off offset:32
	global_store_short v[168:169], v148, off offset:64
	v_cvt_pk_bf16_f32 v160, v85, s0
	global_store_short v[192:193], v160, off offset:64
	global_store_short v[194:195], v149, off offset:64
	v_cvt_pk_bf16_f32 v160, v87, s0
	global_store_short v[196:197], v160, off offset:64
	global_store_short v[198:199], v150, off offset:64
	v_cvt_pk_bf16_f32 v160, v81, s0
	global_store_short v[200:201], v160, off offset:64
	global_store_short v[202:203], v151, off offset:64
	v_cvt_pk_bf16_f32 v160, v83, s0
	global_store_short v[204:205], v160, off offset:64
	global_store_short v[168:169], v144, off offset:96
	v_cvt_pk_bf16_f32 v160, v69, s0
	global_store_short v[192:193], v160, off offset:96
	global_store_short v[194:195], v145, off offset:96
	v_cvt_pk_bf16_f32 v160, v71, s0
	v_add_u32_e32 v192, 0x80, v190
	global_store_short v[196:197], v160, off offset:96
	global_store_short v[198:199], v146, off offset:96
	v_cvt_pk_bf16_f32 v160, v65, s0
	v_ashrrev_i32_e32 v168, 11, v192
	global_store_short v[200:201], v160, off offset:96
	global_store_short v[202:203], v147, off offset:96
	v_cvt_pk_bf16_f32 v160, v67, s0
	v_ashrrev_i32_e32 v169, 31, v168
	global_store_short v[204:205], v160, off offset:96
	v_lshlrev_b64 v[168:169], 19, v[168:169]
	v_and_b32_e32 v160, 0x7cf, v192
	v_lshl_add_u64 v[166:167], v[166:167], 0, v[168:169]
	v_lshlrev_b32_e32 v160, 1, v160
	v_lshl_add_u64 v[166:167], v[166:167], 0, v[160:161]
	v_add_co_u32_e32 v168, vcc, s1, v166
	v_cvt_pk_bf16_f32 v160, v53, s0
	s_nop 0
	v_addc_co_u32_e32 v169, vcc, 0, v167, vcc
	v_add_co_u32_e32 v194, vcc, s16, v166
	global_store_short v[168:169], v160, off
	s_nop 0
	v_addc_co_u32_e32 v195, vcc, 0, v167, vcc
	v_add_co_u32_e32 v196, vcc, s18, v166
	v_cvt_pk_bf16_f32 v160, v55, s0
	s_nop 0
	v_addc_co_u32_e32 v197, vcc, 0, v167, vcc
	v_add_co_u32_e32 v198, vcc, s17, v166
	global_store_short v[196:197], v160, off
	s_nop 0
	v_addc_co_u32_e32 v199, vcc, 0, v167, vcc
	v_add_co_u32_e32 v200, vcc, s19, v166
	v_cvt_pk_bf16_f32 v160, v49, s0
	s_nop 0
	v_addc_co_u32_e32 v201, vcc, 0, v167, vcc
	v_add_co_u32_e32 v202, vcc, s89, v166
	global_store_short v[200:201], v160, off
	s_nop 0
	v_addc_co_u32_e32 v203, vcc, 0, v167, vcc
	v_add_co_u32_e32 v204, vcc, s31, v166
	v_cvt_pk_bf16_f32 v160, v51, s0
	s_nop 0
	v_addc_co_u32_e32 v205, vcc, 0, v167, vcc
	global_store_short v[166:167], v140, off
	global_store_short v[194:195], v141, off
	global_store_short v[198:199], v142, off
	global_store_short v[202:203], v143, off
	global_store_short v[204:205], v160, off
	global_store_short v[166:167], v136, off offset:32
	v_cvt_pk_bf16_f32 v160, v37, s0
	global_store_short v[168:169], v160, off offset:32
	global_store_short v[194:195], v137, off offset:32
	v_cvt_pk_bf16_f32 v160, v39, s0
	global_store_short v[196:197], v160, off offset:32
	global_store_short v[198:199], v138, off offset:32
	v_cvt_pk_bf16_f32 v160, v33, s0
	global_store_short v[200:201], v160, off offset:32
	global_store_short v[202:203], v139, off offset:32
	v_cvt_pk_bf16_f32 v160, v35, s0
	global_store_short v[204:205], v160, off offset:32
	global_store_short v[166:167], v132, off offset:64
	v_cvt_pk_bf16_f32 v160, v21, s0
	global_store_short v[168:169], v160, off offset:64
	global_store_short v[194:195], v133, off offset:64
	v_cvt_pk_bf16_f32 v160, v23, s0
	global_store_short v[196:197], v160, off offset:64
	global_store_short v[198:199], v134, off offset:64
	v_cvt_pk_bf16_f32 v160, v17, s0
	global_store_short v[200:201], v160, off offset:64
	global_store_short v[202:203], v135, off offset:64
	v_cvt_pk_bf16_f32 v160, v19, s0
	global_store_short v[204:205], v160, off offset:64
	global_store_short v[166:167], v128, off offset:96
	v_cvt_pk_bf16_f32 v160, v5, s0
	global_store_short v[168:169], v160, off offset:96
	global_store_short v[194:195], v129, off offset:96
	v_cvt_pk_bf16_f32 v160, v7, s0
	global_store_short v[196:197], v160, off offset:96
	global_store_short v[198:199], v130, off offset:96
	v_cvt_pk_bf16_f32 v160, v1, s0
	global_store_short v[200:201], v160, off offset:96
	global_store_short v[202:203], v131, off offset:96
	v_cvt_pk_bf16_f32 v160, v3, s0
	global_store_short v[204:205], v160, off offset:96
	s_sub_i32 s82, s11, 28
	s_cbranch_execz .LBB0_497
	s_branch .LBB0_498

.LBB0_498:
	s_lshl_b64 s[16:17], s[82:83], 24
	v_ashrrev_i32_e32 v191, 31, v190
	v_lshl_add_u64 v[166:167], v[184:185], 0, s[16:17]
	v_lshlrev_b64 v[194:195], 8, v[190:191]
	v_cvt_pk_bf16_f32 v196, v124, v125
	v_cvt_pk_bf16_f32 v197, v126, v127
	v_cvt_pk_bf16_f32 v198, v120, v121
	v_cvt_pk_bf16_f32 v199, v122, v123
	v_lshl_add_u64 v[168:169], v[166:167], 0, v[194:195]
	global_store_dwordx4 v[168:169], v[196:199], off
	v_or_b32_e32 v168, 16, v190
	v_ashrrev_i32_e32 v169, 31, v168
	v_lshlrev_b64 v[196:197], 8, v[168:169]
	v_cvt_pk_bf16_f32 v198, v108, v109
	v_cvt_pk_bf16_f32 v199, v110, v111
	v_cvt_pk_bf16_f32 v200, v104, v105
	v_cvt_pk_bf16_f32 v201, v106, v107
	v_lshl_add_u64 v[168:169], v[166:167], 0, v[196:197]
	global_store_dwordx4 v[168:169], v[198:201], off
	v_or_b32_e32 v168, 32, v190
	v_ashrrev_i32_e32 v169, 31, v168
	v_lshlrev_b64 v[198:199], 8, v[168:169]
	v_cvt_pk_bf16_f32 v200, v92, v93
	v_cvt_pk_bf16_f32 v201, v94, v95
	v_cvt_pk_bf16_f32 v202, v88, v89
	v_cvt_pk_bf16_f32 v203, v90, v91
	v_lshl_add_u64 v[168:169], v[166:167], 0, v[198:199]
	global_store_dwordx4 v[168:169], v[200:203], off
	v_or_b32_e32 v168, 48, v190
	v_ashrrev_i32_e32 v169, 31, v168
	v_lshlrev_b64 v[200:201], 8, v[168:169]
	v_ashrrev_i32_e32 v193, 31, v192
	v_cvt_pk_bf16_f32 v202, v76, v77
	v_cvt_pk_bf16_f32 v203, v78, v79
	v_cvt_pk_bf16_f32 v204, v72, v73
	v_cvt_pk_bf16_f32 v205, v74, v75
	v_lshl_add_u64 v[168:169], v[166:167], 0, v[200:201]
	v_lshlrev_b64 v[192:193], 8, v[192:193]
	global_store_dwordx4 v[168:169], v[202:205], off
	v_lshl_add_u64 v[168:169], v[166:167], 0, v[192:193]
	s_mov_b64 s[16:17], 0x9000
	v_cvt_pk_bf16_f32 v202, v60, v61
	v_cvt_pk_bf16_f32 v203, v62, v63
	v_cvt_pk_bf16_f32 v204, v56, v57
	v_cvt_pk_bf16_f32 v205, v58, v59
	global_store_dwordx4 v[168:169], v[202:205], off
	v_cvt_pk_bf16_f32 v206, v40, v41
	v_cvt_pk_bf16_f32 v207, v42, v43
	v_lshl_add_u64 v[202:203], v[194:195], 0, s[16:17]
	v_cvt_pk_bf16_f32 v204, v44, v45
	v_cvt_pk_bf16_f32 v205, v46, v47
	v_lshl_add_u64 v[168:169], v[166:167], 0, v[202:203]
	s_mov_b64 s[16:17], 0xa000
	global_store_dwordx4 v[168:169], v[204:207], off
	v_cvt_pk_bf16_f32 v232, v28, v29
	v_cvt_pk_bf16_f32 v233, v30, v31
	v_lshl_add_u64 v[204:205], v[194:195], 0, s[16:17]
	s_mov_b64 s[16:17], 0xb000
	v_cvt_pk_bf16_f32 v234, v24, v25
	v_cvt_pk_bf16_f32 v235, v26, v27
	v_lshl_add_u64 v[168:169], v[166:167], 0, v[204:205]
	v_lshl_add_u64 v[206:207], v[194:195], 0, s[16:17]
	global_store_dwordx4 v[168:169], v[232:235], off
	v_lshl_add_u64 v[166:167], v[166:167], 0, v[206:207]
	s_andn2_b64 vcc, exec, s[8:9]
	v_cvt_pk_bf16_f32 v232, v12, v13
	v_cvt_pk_bf16_f32 v233, v14, v15
	v_cvt_pk_bf16_f32 v234, v8, v9
	v_cvt_pk_bf16_f32 v235, v10, v11
	global_store_dwordx4 v[166:167], v[232:235], off
	s_cbranch_vccnz .LBB0_500
	s_add_i32 s82, s82, 1
	s_lshl_b64 s[8:9], s[82:83], 24
	v_lshl_add_u64 v[166:167], v[184:185], 0, s[8:9]
	v_lshl_add_u64 v[168:169], v[166:167], 0, v[194:195]
	global_store_dwordx4 v[168:169], v[156:159], off
	s_nop 1
	v_lshl_add_u64 v[156:157], v[166:167], 0, v[196:197]
	global_store_dwordx4 v[156:157], v[152:155], off
	s_nop 1
	v_lshl_add_u64 v[152:153], v[166:167], 0, v[198:199]
	global_store_dwordx4 v[152:153], v[148:151], off
	s_nop 1
	v_lshl_add_u64 v[148:149], v[166:167], 0, v[200:201]
	global_store_dwordx4 v[148:149], v[144:147], off
	s_nop 1
	v_lshl_add_u64 v[144:145], v[166:167], 0, v[192:193]
	global_store_dwordx4 v[144:145], v[140:143], off
	s_nop 1
	v_lshl_add_u64 v[140:141], v[166:167], 0, v[202:203]
	global_store_dwordx4 v[140:141], v[136:139], off
	s_nop 1
	v_lshl_add_u64 v[136:137], v[166:167], 0, v[204:205]
	global_store_dwordx4 v[136:137], v[132:135], off
	s_nop 1
	v_lshl_add_u64 v[132:133], v[166:167], 0, v[206:207]
	global_store_dwordx4 v[132:133], v[128:131], off

.LBB0_503:
	s_lshl_b32 s1, s2, 1
	s_and_b32 s1, s1, -4
	s_lshr_b32 s1, 0x2146530, s1
	s_lshl_b32 s1, s1, 26
	s_and_b32 s1, s1, 0x1c000000
	s_add_u32 s1, s26, s1
	s_addc_u32 s9, s27, 0
	s_lshl_b32 s2, s2, 9
	s_and_b32 s2, s2, 0x200
	s_add_u32 s8, s1, s2
	s_addc_u32 s9, s9, 0
	v_ashrrev_i32_e32 v191, 31, v190
	v_lshl_add_u64 v[128:129], v[178:179], 1, s[8:9]
	v_lshlrev_b64 v[130:131], 10, v[190:191]
	v_cvt_pk_bf16_f32 v124, v124, v125
	v_cvt_pk_bf16_f32 v125, v126, v127
	v_cvt_pk_bf16_f32 v126, v120, v121
	v_cndmask_b32_e64 v120, 0, 1, s[16:17]
	v_lshl_add_u64 v[130:131], v[128:129], 0, v[130:131]
	v_cvt_pk_bf16_f32 v127, v122, v123
	v_cmp_ne_u32_e64 s[8:9], 1, v120
	s_andn2_b64 vcc, exec, s[16:17]
	global_store_dwordx4 v[130:131], v[124:127], off
	s_cbranch_vccnz .LBB0_505
	v_mul_f32_e32 v120, v116, v116
	v_mul_f32_e32 v121, v117, v117
	v_mul_f32_e32 v122, v118, v118
	v_mul_f32_e32 v123, v119, v119
	v_fmamk_f32 v120, v120, 0xbdd2d3e8, v209
	v_fmamk_f32 v121, v121, 0xbdd2d3e8, v209
	v_fmamk_f32 v122, v122, 0xbdd2d3e8, v209
	v_fmamk_f32 v123, v123, 0xbdd2d3e8, v209
	v_mul_f32_e32 v120, v116, v120
	v_mul_f32_e32 v121, v117, v121
	v_mul_f32_e32 v122, v118, v122
	v_mul_f32_e32 v123, v119, v123
	v_exp_f32_e32 v120, v120
	v_exp_f32_e32 v121, v121
	v_exp_f32_e32 v122, v122
	v_exp_f32_e32 v123, v123
	v_add_f32_e32 v120, 1.0, v120
	v_add_f32_e32 v121, 1.0, v121
	v_add_f32_e32 v122, 1.0, v122
	v_add_f32_e32 v123, 1.0, v123
	v_rcp_f32_e32 v120, v120
	v_rcp_f32_e32 v121, v121
	v_rcp_f32_e32 v122, v122
	v_rcp_f32_e32 v123, v123
	v_pk_mul_f32 v[116:117], v[116:117], v[120:121]
	v_mul_f32_e32 v120, v112, v112
	v_pk_mul_f32 v[118:119], v[118:119], v[122:123]
	v_mul_f32_e32 v121, v113, v113
	v_mul_f32_e32 v122, v114, v114
	v_mul_f32_e32 v123, v115, v115
	v_fmamk_f32 v120, v120, 0xbdd2d3e8, v209
	v_fmamk_f32 v121, v121, 0xbdd2d3e8, v209
	v_fmamk_f32 v122, v122, 0xbdd2d3e8, v209
	v_fmamk_f32 v123, v123, 0xbdd2d3e8, v209
	v_mul_f32_e32 v120, v112, v120
	v_mul_f32_e32 v121, v113, v121
	v_mul_f32_e32 v122, v114, v122
	v_mul_f32_e32 v123, v115, v123
	v_exp_f32_e32 v120, v120
	v_exp_f32_e32 v121, v121
	v_exp_f32_e32 v122, v122
	v_exp_f32_e32 v123, v123
	v_add_f32_e32 v120, 1.0, v120
	v_add_f32_e32 v121, 1.0, v121
	v_add_f32_e32 v122, 1.0, v122
	v_add_f32_e32 v123, 1.0, v123
	v_rcp_f32_e32 v120, v120
	v_rcp_f32_e32 v121, v121
	v_rcp_f32_e32 v122, v122
	v_rcp_f32_e32 v123, v123
	v_pk_mul_f32 v[112:113], v[112:113], v[120:121]
	v_pk_mul_f32 v[114:115], v[114:115], v[122:123]
.LBB0_505:
	v_cvt_pk_bf16_f32 v116, v116, v117
	v_cvt_pk_bf16_f32 v117, v118, v119
	v_cvt_pk_bf16_f32 v118, v112, v113
	v_cvt_pk_bf16_f32 v119, v114, v115
	s_and_b64 vcc, exec, s[8:9]
	global_store_dwordx4 v[130:131], v[116:119], off offset:256
	s_cbranch_vccnz .LBB0_507
	v_mul_f32_e32 v112, v108, v108
	v_mul_f32_e32 v113, v109, v109
	v_mul_f32_e32 v114, v110, v110
	v_mul_f32_e32 v115, v111, v111
	v_fmamk_f32 v112, v112, 0xbdd2d3e8, v209
	v_fmamk_f32 v113, v113, 0xbdd2d3e8, v209
	v_fmamk_f32 v114, v114, 0xbdd2d3e8, v209
	v_fmamk_f32 v115, v115, 0xbdd2d3e8, v209
	v_mul_f32_e32 v112, v108, v112
	v_mul_f32_e32 v113, v109, v113
	v_mul_f32_e32 v114, v110, v114
	v_mul_f32_e32 v115, v111, v115
	v_exp_f32_e32 v112, v112
	v_exp_f32_e32 v113, v113
	v_exp_f32_e32 v114, v114
	v_exp_f32_e32 v115, v115
	v_add_f32_e32 v112, 1.0, v112
	v_add_f32_e32 v113, 1.0, v113
	v_add_f32_e32 v114, 1.0, v114
	v_add_f32_e32 v115, 1.0, v115
	v_rcp_f32_e32 v112, v112
	v_rcp_f32_e32 v113, v113
	v_rcp_f32_e32 v114, v114
	v_rcp_f32_e32 v115, v115
	v_pk_mul_f32 v[108:109], v[108:109], v[112:113]
	v_mul_f32_e32 v112, v104, v104
	v_pk_mul_f32 v[110:111], v[110:111], v[114:115]
	v_mul_f32_e32 v113, v105, v105
	v_mul_f32_e32 v114, v106, v106
	v_mul_f32_e32 v115, v107, v107
	v_fmamk_f32 v112, v112, 0xbdd2d3e8, v209
	v_fmamk_f32 v113, v113, 0xbdd2d3e8, v209
	v_fmamk_f32 v114, v114, 0xbdd2d3e8, v209
	v_fmamk_f32 v115, v115, 0xbdd2d3e8, v209
	v_mul_f32_e32 v112, v104, v112
	v_mul_f32_e32 v113, v105, v113
	v_mul_f32_e32 v114, v106, v114
	v_mul_f32_e32 v115, v107, v115
	v_exp_f32_e32 v112, v112
	v_exp_f32_e32 v113, v113
	v_exp_f32_e32 v114, v114
	v_exp_f32_e32 v115, v115
	v_add_f32_e32 v112, 1.0, v112
	v_add_f32_e32 v113, 1.0, v113
	v_add_f32_e32 v114, 1.0, v114
	v_add_f32_e32 v115, 1.0, v115
	v_rcp_f32_e32 v112, v112
	v_rcp_f32_e32 v113, v113
	v_rcp_f32_e32 v114, v114
	v_rcp_f32_e32 v115, v115
	v_pk_mul_f32 v[104:105], v[104:105], v[112:113]
	v_pk_mul_f32 v[106:107], v[106:107], v[114:115]
.LBB0_507:
	v_or_b32_e32 v112, 16, v190
	v_ashrrev_i32_e32 v113, 31, v112
	v_lshlrev_b64 v[112:113], 10, v[112:113]
	v_lshl_add_u64 v[112:113], v[128:129], 0, v[112:113]
	v_cvt_pk_bf16_f32 v108, v108, v109
	v_cvt_pk_bf16_f32 v109, v110, v111
	v_cvt_pk_bf16_f32 v110, v104, v105
	v_cvt_pk_bf16_f32 v111, v106, v107
	s_and_b64 vcc, exec, s[8:9]
	global_store_dwordx4 v[112:113], v[108:111], off
	s_cbranch_vccnz .LBB0_509
	v_mul_f32_e32 v104, v100, v100
	v_mul_f32_e32 v105, v101, v101
	v_mul_f32_e32 v106, v102, v102
	v_mul_f32_e32 v107, v103, v103
	v_fmamk_f32 v104, v104, 0xbdd2d3e8, v209
	v_fmamk_f32 v105, v105, 0xbdd2d3e8, v209
	v_fmamk_f32 v106, v106, 0xbdd2d3e8, v209
	v_fmamk_f32 v107, v107, 0xbdd2d3e8, v209
	v_mul_f32_e32 v104, v100, v104
	v_mul_f32_e32 v105, v101, v105
	v_mul_f32_e32 v106, v102, v106
	v_mul_f32_e32 v107, v103, v107
	v_exp_f32_e32 v104, v104
	v_exp_f32_e32 v105, v105
	v_exp_f32_e32 v106, v106
	v_exp_f32_e32 v107, v107
	v_add_f32_e32 v104, 1.0, v104
	v_add_f32_e32 v105, 1.0, v105
	v_add_f32_e32 v106, 1.0, v106
	v_add_f32_e32 v107, 1.0, v107
	v_rcp_f32_e32 v104, v104
	v_rcp_f32_e32 v105, v105
	v_rcp_f32_e32 v106, v106
	v_rcp_f32_e32 v107, v107
	v_pk_mul_f32 v[100:101], v[100:101], v[104:105]
	v_mul_f32_e32 v104, v96, v96
	v_pk_mul_f32 v[102:103], v[102:103], v[106:107]
	v_mul_f32_e32 v105, v97, v97
	v_mul_f32_e32 v106, v98, v98
	v_mul_f32_e32 v107, v99, v99
	v_fmamk_f32 v104, v104, 0xbdd2d3e8, v209
	v_fmamk_f32 v105, v105, 0xbdd2d3e8, v209
	v_fmamk_f32 v106, v106, 0xbdd2d3e8, v209
	v_fmamk_f32 v107, v107, 0xbdd2d3e8, v209
	v_mul_f32_e32 v104, v96, v104
	v_mul_f32_e32 v105, v97, v105
	v_mul_f32_e32 v106, v98, v106
	v_mul_f32_e32 v107, v99, v107
	v_exp_f32_e32 v104, v104
	v_exp_f32_e32 v105, v105
	v_exp_f32_e32 v106, v106
	v_exp_f32_e32 v107, v107
	v_add_f32_e32 v104, 1.0, v104
	v_add_f32_e32 v105, 1.0, v105
	v_add_f32_e32 v106, 1.0, v106
	v_add_f32_e32 v107, 1.0, v107
	v_rcp_f32_e32 v104, v104
	v_rcp_f32_e32 v105, v105
	v_rcp_f32_e32 v106, v106
	v_rcp_f32_e32 v107, v107
	v_pk_mul_f32 v[96:97], v[96:97], v[104:105]
	v_pk_mul_f32 v[98:99], v[98:99], v[106:107]
.LBB0_509:
	v_cvt_pk_bf16_f32 v100, v100, v101
	v_cvt_pk_bf16_f32 v101, v102, v103
	v_cvt_pk_bf16_f32 v102, v96, v97
	v_cvt_pk_bf16_f32 v103, v98, v99
	s_and_b64 vcc, exec, s[8:9]
	global_store_dwordx4 v[112:113], v[100:103], off offset:256
	s_cbranch_vccnz .LBB0_511
	v_mul_f32_e32 v96, v92, v92
	v_mul_f32_e32 v97, v93, v93
	v_mul_f32_e32 v98, v94, v94
	v_mul_f32_e32 v99, v95, v95
	v_fmamk_f32 v96, v96, 0xbdd2d3e8, v209
	v_fmamk_f32 v97, v97, 0xbdd2d3e8, v209
	v_fmamk_f32 v98, v98, 0xbdd2d3e8, v209
	v_fmamk_f32 v99, v99, 0xbdd2d3e8, v209
	v_mul_f32_e32 v96, v92, v96
	v_mul_f32_e32 v97, v93, v97
	v_mul_f32_e32 v98, v94, v98
	v_mul_f32_e32 v99, v95, v99
	v_exp_f32_e32 v96, v96
	v_exp_f32_e32 v97, v97
	v_exp_f32_e32 v98, v98
	v_exp_f32_e32 v99, v99
	v_add_f32_e32 v96, 1.0, v96
	v_add_f32_e32 v97, 1.0, v97
	v_add_f32_e32 v98, 1.0, v98
	v_add_f32_e32 v99, 1.0, v99
	v_rcp_f32_e32 v96, v96
	v_rcp_f32_e32 v97, v97
	v_rcp_f32_e32 v98, v98
	v_rcp_f32_e32 v99, v99
	v_pk_mul_f32 v[92:93], v[92:93], v[96:97]
	v_mul_f32_e32 v96, v88, v88
	v_pk_mul_f32 v[94:95], v[94:95], v[98:99]
	v_mul_f32_e32 v97, v89, v89
	v_mul_f32_e32 v98, v90, v90
	v_mul_f32_e32 v99, v91, v91
	v_fmamk_f32 v96, v96, 0xbdd2d3e8, v209
	v_fmamk_f32 v97, v97, 0xbdd2d3e8, v209
	v_fmamk_f32 v98, v98, 0xbdd2d3e8, v209
	v_fmamk_f32 v99, v99, 0xbdd2d3e8, v209
	v_mul_f32_e32 v96, v88, v96
	v_mul_f32_e32 v97, v89, v97
	v_mul_f32_e32 v98, v90, v98
	v_mul_f32_e32 v99, v91, v99
	v_exp_f32_e32 v96, v96
	v_exp_f32_e32 v97, v97
	v_exp_f32_e32 v98, v98
	v_exp_f32_e32 v99, v99
	v_add_f32_e32 v96, 1.0, v96
	v_add_f32_e32 v97, 1.0, v97
	v_add_f32_e32 v98, 1.0, v98
	v_add_f32_e32 v99, 1.0, v99
	v_rcp_f32_e32 v96, v96
	v_rcp_f32_e32 v97, v97
	v_rcp_f32_e32 v98, v98
	v_rcp_f32_e32 v99, v99
	v_pk_mul_f32 v[88:89], v[88:89], v[96:97]
	v_pk_mul_f32 v[90:91], v[90:91], v[98:99]
.LBB0_511:
	v_or_b32_e32 v96, 32, v190
	v_ashrrev_i32_e32 v97, 31, v96
	v_lshlrev_b64 v[96:97], 10, v[96:97]
	v_lshl_add_u64 v[96:97], v[128:129], 0, v[96:97]
	v_cvt_pk_bf16_f32 v92, v92, v93
	v_cvt_pk_bf16_f32 v93, v94, v95
	v_cvt_pk_bf16_f32 v94, v88, v89
	v_cvt_pk_bf16_f32 v95, v90, v91
	s_and_b64 vcc, exec, s[8:9]
	global_store_dwordx4 v[96:97], v[92:95], off
	s_cbranch_vccnz .LBB0_513
	v_mul_f32_e32 v88, v84, v84
	v_mul_f32_e32 v89, v85, v85
	v_mul_f32_e32 v90, v86, v86
	v_mul_f32_e32 v91, v87, v87
	v_fmamk_f32 v88, v88, 0xbdd2d3e8, v209
	v_fmamk_f32 v89, v89, 0xbdd2d3e8, v209
	v_fmamk_f32 v90, v90, 0xbdd2d3e8, v209
	v_fmamk_f32 v91, v91, 0xbdd2d3e8, v209
	v_mul_f32_e32 v88, v84, v88
	v_mul_f32_e32 v89, v85, v89
	v_mul_f32_e32 v90, v86, v90
	v_mul_f32_e32 v91, v87, v91
	v_exp_f32_e32 v88, v88
	v_exp_f32_e32 v89, v89
	v_exp_f32_e32 v90, v90
	v_exp_f32_e32 v91, v91
	v_add_f32_e32 v88, 1.0, v88
	v_add_f32_e32 v89, 1.0, v89
	v_add_f32_e32 v90, 1.0, v90
	v_add_f32_e32 v91, 1.0, v91
	v_rcp_f32_e32 v88, v88
	v_rcp_f32_e32 v89, v89
	v_rcp_f32_e32 v90, v90
	v_rcp_f32_e32 v91, v91
	v_pk_mul_f32 v[84:85], v[84:85], v[88:89]
	v_mul_f32_e32 v88, v80, v80
	v_pk_mul_f32 v[86:87], v[86:87], v[90:91]
	v_mul_f32_e32 v89, v81, v81
	v_mul_f32_e32 v90, v82, v82
	v_mul_f32_e32 v91, v83, v83
	v_fmamk_f32 v88, v88, 0xbdd2d3e8, v209
	v_fmamk_f32 v89, v89, 0xbdd2d3e8, v209
	v_fmamk_f32 v90, v90, 0xbdd2d3e8, v209
	v_fmamk_f32 v91, v91, 0xbdd2d3e8, v209
	v_mul_f32_e32 v88, v80, v88
	v_mul_f32_e32 v89, v81, v89
	v_mul_f32_e32 v90, v82, v90
	v_mul_f32_e32 v91, v83, v91
	v_exp_f32_e32 v88, v88
	v_exp_f32_e32 v89, v89
	v_exp_f32_e32 v90, v90
	v_exp_f32_e32 v91, v91
	v_add_f32_e32 v88, 1.0, v88
	v_add_f32_e32 v89, 1.0, v89
	v_add_f32_e32 v90, 1.0, v90
	v_add_f32_e32 v91, 1.0, v91
	v_rcp_f32_e32 v88, v88
	v_rcp_f32_e32 v89, v89
	v_rcp_f32_e32 v90, v90
	v_rcp_f32_e32 v91, v91
	v_pk_mul_f32 v[80:81], v[80:81], v[88:89]
	v_pk_mul_f32 v[82:83], v[82:83], v[90:91]
.LBB0_513:
	v_cvt_pk_bf16_f32 v84, v84, v85
	v_cvt_pk_bf16_f32 v85, v86, v87
	v_cvt_pk_bf16_f32 v86, v80, v81
	v_cvt_pk_bf16_f32 v87, v82, v83
	s_and_b64 vcc, exec, s[8:9]
	global_store_dwordx4 v[96:97], v[84:87], off offset:256
	s_cbranch_vccnz .LBB0_515
	v_mul_f32_e32 v80, v76, v76
	v_mul_f32_e32 v81, v77, v77
	v_mul_f32_e32 v82, v78, v78
	v_mul_f32_e32 v83, v79, v79
	v_fmamk_f32 v80, v80, 0xbdd2d3e8, v209
	v_fmamk_f32 v81, v81, 0xbdd2d3e8, v209
	v_fmamk_f32 v82, v82, 0xbdd2d3e8, v209
	v_fmamk_f32 v83, v83, 0xbdd2d3e8, v209
	v_mul_f32_e32 v80, v76, v80
	v_mul_f32_e32 v81, v77, v81
	v_mul_f32_e32 v82, v78, v82
	v_mul_f32_e32 v83, v79, v83
	v_exp_f32_e32 v80, v80
	v_exp_f32_e32 v81, v81
	v_exp_f32_e32 v82, v82
	v_exp_f32_e32 v83, v83
	v_add_f32_e32 v80, 1.0, v80
	v_add_f32_e32 v81, 1.0, v81
	v_add_f32_e32 v82, 1.0, v82
	v_add_f32_e32 v83, 1.0, v83
	v_rcp_f32_e32 v80, v80
	v_rcp_f32_e32 v81, v81
	v_rcp_f32_e32 v82, v82
	v_rcp_f32_e32 v83, v83
	v_pk_mul_f32 v[76:77], v[76:77], v[80:81]
	v_mul_f32_e32 v80, v72, v72
	v_pk_mul_f32 v[78:79], v[78:79], v[82:83]
	v_mul_f32_e32 v81, v73, v73
	v_mul_f32_e32 v82, v74, v74
	v_mul_f32_e32 v83, v75, v75
	v_fmamk_f32 v80, v80, 0xbdd2d3e8, v209
	v_fmamk_f32 v81, v81, 0xbdd2d3e8, v209
	v_fmamk_f32 v82, v82, 0xbdd2d3e8, v209
	v_fmamk_f32 v83, v83, 0xbdd2d3e8, v209
	v_mul_f32_e32 v80, v72, v80
	v_mul_f32_e32 v81, v73, v81
	v_mul_f32_e32 v82, v74, v82
	v_mul_f32_e32 v83, v75, v83
	v_exp_f32_e32 v80, v80
	v_exp_f32_e32 v81, v81
	v_exp_f32_e32 v82, v82
	v_exp_f32_e32 v83, v83
	v_add_f32_e32 v80, 1.0, v80
	v_add_f32_e32 v81, 1.0, v81
	v_add_f32_e32 v82, 1.0, v82
	v_add_f32_e32 v83, 1.0, v83
	v_rcp_f32_e32 v80, v80
	v_rcp_f32_e32 v81, v81
	v_rcp_f32_e32 v82, v82
	v_rcp_f32_e32 v83, v83
	v_pk_mul_f32 v[72:73], v[72:73], v[80:81]
	v_pk_mul_f32 v[74:75], v[74:75], v[82:83]
.LBB0_515:
	v_or_b32_e32 v80, 48, v190
	v_ashrrev_i32_e32 v81, 31, v80
	v_lshlrev_b64 v[80:81], 10, v[80:81]
	v_lshl_add_u64 v[80:81], v[128:129], 0, v[80:81]
	v_cvt_pk_bf16_f32 v76, v76, v77
	v_cvt_pk_bf16_f32 v77, v78, v79
	v_cvt_pk_bf16_f32 v78, v72, v73
	v_cvt_pk_bf16_f32 v79, v74, v75
	s_and_b64 vcc, exec, s[8:9]
	global_store_dwordx4 v[80:81], v[76:79], off
	s_cbranch_vccnz .LBB0_517
	v_mul_f32_e32 v72, v68, v68
	v_mul_f32_e32 v73, v69, v69
	v_mul_f32_e32 v74, v70, v70
	v_mul_f32_e32 v75, v71, v71
	v_fmamk_f32 v72, v72, 0xbdd2d3e8, v209
	v_fmamk_f32 v73, v73, 0xbdd2d3e8, v209
	v_fmamk_f32 v74, v74, 0xbdd2d3e8, v209
	v_fmamk_f32 v75, v75, 0xbdd2d3e8, v209
	v_mul_f32_e32 v72, v68, v72
	v_mul_f32_e32 v73, v69, v73
	v_mul_f32_e32 v74, v70, v74
	v_mul_f32_e32 v75, v71, v75
	v_exp_f32_e32 v72, v72
	v_exp_f32_e32 v73, v73
	v_exp_f32_e32 v74, v74
	v_exp_f32_e32 v75, v75
	v_add_f32_e32 v72, 1.0, v72
	v_add_f32_e32 v73, 1.0, v73
	v_add_f32_e32 v74, 1.0, v74
	v_add_f32_e32 v75, 1.0, v75
	v_rcp_f32_e32 v72, v72
	v_rcp_f32_e32 v73, v73
	v_rcp_f32_e32 v74, v74
	v_rcp_f32_e32 v75, v75
	v_pk_mul_f32 v[68:69], v[68:69], v[72:73]
	v_mul_f32_e32 v72, v64, v64
	v_pk_mul_f32 v[70:71], v[70:71], v[74:75]
	v_mul_f32_e32 v73, v65, v65
	v_mul_f32_e32 v74, v66, v66
	v_mul_f32_e32 v75, v67, v67
	v_fmamk_f32 v72, v72, 0xbdd2d3e8, v209
	v_fmamk_f32 v73, v73, 0xbdd2d3e8, v209
	v_fmamk_f32 v74, v74, 0xbdd2d3e8, v209
	v_fmamk_f32 v75, v75, 0xbdd2d3e8, v209
	v_mul_f32_e32 v72, v64, v72
	v_mul_f32_e32 v73, v65, v73
	v_mul_f32_e32 v74, v66, v74
	v_mul_f32_e32 v75, v67, v75
	v_exp_f32_e32 v72, v72
	v_exp_f32_e32 v73, v73
	v_exp_f32_e32 v74, v74
	v_exp_f32_e32 v75, v75
	v_add_f32_e32 v72, 1.0, v72
	v_add_f32_e32 v73, 1.0, v73
	v_add_f32_e32 v74, 1.0, v74
	v_add_f32_e32 v75, 1.0, v75
	v_rcp_f32_e32 v72, v72
	v_rcp_f32_e32 v73, v73
	v_rcp_f32_e32 v74, v74
	v_rcp_f32_e32 v75, v75
	v_pk_mul_f32 v[64:65], v[64:65], v[72:73]
	v_pk_mul_f32 v[66:67], v[66:67], v[74:75]
.LBB0_517:
	v_cvt_pk_bf16_f32 v68, v68, v69
	v_cvt_pk_bf16_f32 v69, v70, v71
	v_cvt_pk_bf16_f32 v70, v64, v65
	v_cvt_pk_bf16_f32 v71, v66, v67
	s_and_b64 vcc, exec, s[8:9]
	global_store_dwordx4 v[80:81], v[68:71], off offset:256
	s_cbranch_vccnz .LBB0_519
	v_mul_f32_e32 v64, v60, v60
	v_mul_f32_e32 v65, v61, v61
	v_mul_f32_e32 v66, v62, v62
	v_mul_f32_e32 v67, v63, v63
	v_fmamk_f32 v64, v64, 0xbdd2d3e8, v209
	v_fmamk_f32 v65, v65, 0xbdd2d3e8, v209
	v_fmamk_f32 v66, v66, 0xbdd2d3e8, v209
	v_fmamk_f32 v67, v67, 0xbdd2d3e8, v209
	v_mul_f32_e32 v64, v60, v64
	v_mul_f32_e32 v65, v61, v65
	v_mul_f32_e32 v66, v62, v66
	v_mul_f32_e32 v67, v63, v67
	v_exp_f32_e32 v64, v64
	v_exp_f32_e32 v65, v65
	v_exp_f32_e32 v66, v66
	v_exp_f32_e32 v67, v67
	v_add_f32_e32 v64, 1.0, v64
	v_add_f32_e32 v65, 1.0, v65
	v_add_f32_e32 v66, 1.0, v66
	v_add_f32_e32 v67, 1.0, v67
	v_rcp_f32_e32 v64, v64
	v_rcp_f32_e32 v65, v65
	v_rcp_f32_e32 v66, v66
	v_rcp_f32_e32 v67, v67
	v_pk_mul_f32 v[60:61], v[60:61], v[64:65]
	v_mul_f32_e32 v64, v56, v56
	v_pk_mul_f32 v[62:63], v[62:63], v[66:67]
	v_mul_f32_e32 v65, v57, v57
	v_mul_f32_e32 v66, v58, v58
	v_mul_f32_e32 v67, v59, v59
	v_fmamk_f32 v64, v64, 0xbdd2d3e8, v209
	v_fmamk_f32 v65, v65, 0xbdd2d3e8, v209
	v_fmamk_f32 v66, v66, 0xbdd2d3e8, v209
	v_fmamk_f32 v67, v67, 0xbdd2d3e8, v209
	v_mul_f32_e32 v64, v56, v64
	v_mul_f32_e32 v65, v57, v65
	v_mul_f32_e32 v66, v58, v66
	v_mul_f32_e32 v67, v59, v67
	v_exp_f32_e32 v64, v64
	v_exp_f32_e32 v65, v65
	v_exp_f32_e32 v66, v66
	v_exp_f32_e32 v67, v67
	v_add_f32_e32 v64, 1.0, v64
	v_add_f32_e32 v65, 1.0, v65
	v_add_f32_e32 v66, 1.0, v66
	v_add_f32_e32 v67, 1.0, v67
	v_rcp_f32_e32 v64, v64
	v_rcp_f32_e32 v65, v65
	v_rcp_f32_e32 v66, v66
	v_rcp_f32_e32 v67, v67
	v_pk_mul_f32 v[56:57], v[56:57], v[64:65]
	v_pk_mul_f32 v[58:59], v[58:59], v[66:67]
.LBB0_519:
	v_lshlrev_b64 v[64:65], 10, v[190:191]
	v_lshl_add_u64 v[64:65], v[128:129], 0, v[64:65]
	v_cvt_pk_bf16_f32 v60, v60, v61
	v_cvt_pk_bf16_f32 v61, v62, v63
	v_cvt_pk_bf16_f32 v62, v56, v57
	v_add_co_u32_e32 v56, vcc, 0x20000, v64
	v_cvt_pk_bf16_f32 v63, v58, v59
	s_nop 0
	v_addc_co_u32_e32 v57, vcc, 0, v65, vcc
	s_and_b64 vcc, exec, s[8:9]
	global_store_dwordx4 v[56:57], v[60:63], off
	s_cbranch_vccnz .LBB0_521
	v_mul_f32_e32 v56, v52, v52
	v_mul_f32_e32 v57, v53, v53
	v_mul_f32_e32 v58, v54, v54
	v_mul_f32_e32 v59, v55, v55
	v_fmamk_f32 v56, v56, 0xbdd2d3e8, v209
	v_fmamk_f32 v57, v57, 0xbdd2d3e8, v209
	v_fmamk_f32 v58, v58, 0xbdd2d3e8, v209
	v_fmamk_f32 v59, v59, 0xbdd2d3e8, v209
	v_mul_f32_e32 v56, v52, v56
	v_mul_f32_e32 v57, v53, v57
	v_mul_f32_e32 v58, v54, v58
	v_mul_f32_e32 v59, v55, v59
	v_exp_f32_e32 v56, v56
	v_exp_f32_e32 v57, v57
	v_exp_f32_e32 v58, v58
	v_exp_f32_e32 v59, v59
	v_add_f32_e32 v56, 1.0, v56
	v_add_f32_e32 v57, 1.0, v57
	v_add_f32_e32 v58, 1.0, v58
	v_add_f32_e32 v59, 1.0, v59
	v_rcp_f32_e32 v56, v56
	v_rcp_f32_e32 v57, v57
	v_rcp_f32_e32 v58, v58
	v_rcp_f32_e32 v59, v59
	v_pk_mul_f32 v[52:53], v[52:53], v[56:57]
	v_mul_f32_e32 v56, v48, v48
	v_pk_mul_f32 v[54:55], v[54:55], v[58:59]
	v_mul_f32_e32 v57, v49, v49
	v_mul_f32_e32 v58, v50, v50
	v_mul_f32_e32 v59, v51, v51
	v_fmamk_f32 v56, v56, 0xbdd2d3e8, v209
	v_fmamk_f32 v57, v57, 0xbdd2d3e8, v209
	v_fmamk_f32 v58, v58, 0xbdd2d3e8, v209
	v_fmamk_f32 v59, v59, 0xbdd2d3e8, v209
	v_mul_f32_e32 v56, v48, v56
	v_mul_f32_e32 v57, v49, v57
	v_mul_f32_e32 v58, v50, v58
	v_mul_f32_e32 v59, v51, v59
	v_exp_f32_e32 v56, v56
	v_exp_f32_e32 v57, v57
	v_exp_f32_e32 v58, v58
	v_exp_f32_e32 v59, v59
	v_add_f32_e32 v56, 1.0, v56
	v_add_f32_e32 v57, 1.0, v57
	v_add_f32_e32 v58, 1.0, v58
	v_add_f32_e32 v59, 1.0, v59
	v_rcp_f32_e32 v56, v56
	v_rcp_f32_e32 v57, v57
	v_rcp_f32_e32 v58, v58
	v_rcp_f32_e32 v59, v59
	v_pk_mul_f32 v[48:49], v[48:49], v[56:57]
	v_pk_mul_f32 v[50:51], v[50:51], v[58:59]
.LBB0_521:
	s_mov_b64 s[16:17], 0x20000
	v_lshl_add_u64 v[56:57], v[64:65], 0, s[16:17]
	v_cvt_pk_bf16_f32 v52, v52, v53
	v_cvt_pk_bf16_f32 v53, v54, v55
	v_cvt_pk_bf16_f32 v54, v48, v49
	v_cvt_pk_bf16_f32 v55, v50, v51
	s_and_b64 vcc, exec, s[8:9]
	global_store_dwordx4 v[56:57], v[52:55], off offset:256
	s_cbranch_vccnz .LBB0_523
	v_mul_f32_e32 v48, v44, v44
	v_mul_f32_e32 v49, v45, v45
	v_mul_f32_e32 v50, v46, v46
	v_mul_f32_e32 v51, v47, v47
	v_fmamk_f32 v48, v48, 0xbdd2d3e8, v209
	v_fmamk_f32 v49, v49, 0xbdd2d3e8, v209
	v_fmamk_f32 v50, v50, 0xbdd2d3e8, v209
	v_fmamk_f32 v51, v51, 0xbdd2d3e8, v209
	v_mul_f32_e32 v48, v44, v48
	v_mul_f32_e32 v49, v45, v49
	v_mul_f32_e32 v50, v46, v50
	v_mul_f32_e32 v51, v47, v51
	v_exp_f32_e32 v48, v48
	v_exp_f32_e32 v49, v49
	v_exp_f32_e32 v50, v50
	v_exp_f32_e32 v51, v51
	v_add_f32_e32 v48, 1.0, v48
	v_add_f32_e32 v49, 1.0, v49
	v_add_f32_e32 v50, 1.0, v50
	v_add_f32_e32 v51, 1.0, v51
	v_rcp_f32_e32 v48, v48
	v_rcp_f32_e32 v49, v49
	v_rcp_f32_e32 v50, v50
	v_rcp_f32_e32 v51, v51
	v_pk_mul_f32 v[44:45], v[44:45], v[48:49]
	v_mul_f32_e32 v48, v40, v40
	v_pk_mul_f32 v[46:47], v[46:47], v[50:51]
	v_mul_f32_e32 v49, v41, v41
	v_mul_f32_e32 v50, v42, v42
	v_mul_f32_e32 v51, v43, v43
	v_fmamk_f32 v48, v48, 0xbdd2d3e8, v209
	v_fmamk_f32 v49, v49, 0xbdd2d3e8, v209
	v_fmamk_f32 v50, v50, 0xbdd2d3e8, v209
	v_fmamk_f32 v51, v51, 0xbdd2d3e8, v209
	v_mul_f32_e32 v48, v40, v48
	v_mul_f32_e32 v49, v41, v49
	v_mul_f32_e32 v50, v42, v50
	v_mul_f32_e32 v51, v43, v51
	v_exp_f32_e32 v48, v48
	v_exp_f32_e32 v49, v49
	v_exp_f32_e32 v50, v50
	v_exp_f32_e32 v51, v51
	v_add_f32_e32 v48, 1.0, v48
	v_add_f32_e32 v49, 1.0, v49
	v_add_f32_e32 v50, 1.0, v50
	v_add_f32_e32 v51, 1.0, v51
	v_rcp_f32_e32 v48, v48
	v_rcp_f32_e32 v49, v49
	v_rcp_f32_e32 v50, v50
	v_rcp_f32_e32 v51, v51
	v_pk_mul_f32 v[40:41], v[40:41], v[48:49]
	v_pk_mul_f32 v[42:43], v[42:43], v[50:51]
.LBB0_523:
	v_lshlrev_b64 v[48:49], 10, v[190:191]
	v_lshl_add_u64 v[48:49], v[128:129], 0, v[48:49]
	v_cvt_pk_bf16_f32 v44, v44, v45
	v_cvt_pk_bf16_f32 v45, v46, v47
	v_cvt_pk_bf16_f32 v46, v40, v41
	v_add_co_u32_e32 v40, vcc, 0x24000, v48
	v_cvt_pk_bf16_f32 v47, v42, v43
	s_nop 0
	v_addc_co_u32_e32 v41, vcc, 0, v49, vcc
	s_and_b64 vcc, exec, s[8:9]
	global_store_dwordx4 v[40:41], v[44:47], off
	s_cbranch_vccnz .LBB0_525
	v_mul_f32_e32 v40, v36, v36
	v_mul_f32_e32 v41, v37, v37
	v_mul_f32_e32 v42, v38, v38
	v_mul_f32_e32 v43, v39, v39
	v_fmamk_f32 v40, v40, 0xbdd2d3e8, v209
	v_fmamk_f32 v41, v41, 0xbdd2d3e8, v209
	v_fmamk_f32 v42, v42, 0xbdd2d3e8, v209
	v_fmamk_f32 v43, v43, 0xbdd2d3e8, v209
	v_mul_f32_e32 v40, v36, v40
	v_mul_f32_e32 v41, v37, v41
	v_mul_f32_e32 v42, v38, v42
	v_mul_f32_e32 v43, v39, v43
	v_exp_f32_e32 v40, v40
	v_exp_f32_e32 v41, v41
	v_exp_f32_e32 v42, v42
	v_exp_f32_e32 v43, v43
	v_add_f32_e32 v40, 1.0, v40
	v_add_f32_e32 v41, 1.0, v41
	v_add_f32_e32 v42, 1.0, v42
	v_add_f32_e32 v43, 1.0, v43
	v_rcp_f32_e32 v40, v40
	v_rcp_f32_e32 v41, v41
	v_rcp_f32_e32 v42, v42
	v_rcp_f32_e32 v43, v43
	v_pk_mul_f32 v[36:37], v[36:37], v[40:41]
	v_mul_f32_e32 v40, v32, v32
	v_pk_mul_f32 v[38:39], v[38:39], v[42:43]
	v_mul_f32_e32 v41, v33, v33
	v_mul_f32_e32 v42, v34, v34
	v_mul_f32_e32 v43, v35, v35
	v_fmamk_f32 v40, v40, 0xbdd2d3e8, v209
	v_fmamk_f32 v41, v41, 0xbdd2d3e8, v209
	v_fmamk_f32 v42, v42, 0xbdd2d3e8, v209
	v_fmamk_f32 v43, v43, 0xbdd2d3e8, v209
	v_mul_f32_e32 v40, v32, v40
	v_mul_f32_e32 v41, v33, v41
	v_mul_f32_e32 v42, v34, v42
	v_mul_f32_e32 v43, v35, v43
	v_exp_f32_e32 v40, v40
	v_exp_f32_e32 v41, v41
	v_exp_f32_e32 v42, v42
	v_exp_f32_e32 v43, v43
	v_add_f32_e32 v40, 1.0, v40
	v_add_f32_e32 v41, 1.0, v41
	v_add_f32_e32 v42, 1.0, v42
	v_add_f32_e32 v43, 1.0, v43
	v_rcp_f32_e32 v40, v40
	v_rcp_f32_e32 v41, v41
	v_rcp_f32_e32 v42, v42
	v_rcp_f32_e32 v43, v43
	v_pk_mul_f32 v[32:33], v[32:33], v[40:41]
	v_pk_mul_f32 v[34:35], v[34:35], v[42:43]
.LBB0_525:
	s_mov_b64 s[16:17], 0x24000
	v_lshl_add_u64 v[40:41], v[48:49], 0, s[16:17]
	v_cvt_pk_bf16_f32 v36, v36, v37
	v_cvt_pk_bf16_f32 v37, v38, v39
	v_cvt_pk_bf16_f32 v38, v32, v33
	v_cvt_pk_bf16_f32 v39, v34, v35
	s_and_b64 vcc, exec, s[8:9]
	global_store_dwordx4 v[40:41], v[36:39], off offset:256
	s_cbranch_vccnz .LBB0_527
	v_mul_f32_e32 v32, v28, v28
	v_mul_f32_e32 v33, v29, v29
	v_mul_f32_e32 v34, v30, v30
	v_mul_f32_e32 v35, v31, v31
	v_fmamk_f32 v32, v32, 0xbdd2d3e8, v209
	v_fmamk_f32 v33, v33, 0xbdd2d3e8, v209
	v_fmamk_f32 v34, v34, 0xbdd2d3e8, v209
	v_fmamk_f32 v35, v35, 0xbdd2d3e8, v209
	v_mul_f32_e32 v32, v28, v32
	v_mul_f32_e32 v33, v29, v33
	v_mul_f32_e32 v34, v30, v34
	v_mul_f32_e32 v35, v31, v35
	v_exp_f32_e32 v32, v32
	v_exp_f32_e32 v33, v33
	v_exp_f32_e32 v34, v34
	v_exp_f32_e32 v35, v35
	v_add_f32_e32 v32, 1.0, v32
	v_add_f32_e32 v33, 1.0, v33
	v_add_f32_e32 v34, 1.0, v34
	v_add_f32_e32 v35, 1.0, v35
	v_rcp_f32_e32 v32, v32
	v_rcp_f32_e32 v33, v33
	v_rcp_f32_e32 v34, v34
	v_rcp_f32_e32 v35, v35
	v_pk_mul_f32 v[28:29], v[28:29], v[32:33]
	v_mul_f32_e32 v32, v24, v24
	v_pk_mul_f32 v[30:31], v[30:31], v[34:35]
	v_mul_f32_e32 v33, v25, v25
	v_mul_f32_e32 v34, v26, v26
	v_mul_f32_e32 v35, v27, v27
	v_fmamk_f32 v32, v32, 0xbdd2d3e8, v209
	v_fmamk_f32 v33, v33, 0xbdd2d3e8, v209
	v_fmamk_f32 v34, v34, 0xbdd2d3e8, v209
	v_fmamk_f32 v35, v35, 0xbdd2d3e8, v209
	v_mul_f32_e32 v32, v24, v32
	v_mul_f32_e32 v33, v25, v33
	v_mul_f32_e32 v34, v26, v34
	v_mul_f32_e32 v35, v27, v35
	v_exp_f32_e32 v32, v32
	v_exp_f32_e32 v33, v33
	v_exp_f32_e32 v34, v34
	v_exp_f32_e32 v35, v35
	v_add_f32_e32 v32, 1.0, v32
	v_add_f32_e32 v33, 1.0, v33
	v_add_f32_e32 v34, 1.0, v34
	v_add_f32_e32 v35, 1.0, v35
	v_rcp_f32_e32 v32, v32
	v_rcp_f32_e32 v33, v33
	v_rcp_f32_e32 v34, v34
	v_rcp_f32_e32 v35, v35
	v_pk_mul_f32 v[24:25], v[24:25], v[32:33]
	v_pk_mul_f32 v[26:27], v[26:27], v[34:35]
.LBB0_527:
	v_lshlrev_b64 v[32:33], 10, v[190:191]
	v_lshl_add_u64 v[32:33], v[128:129], 0, v[32:33]
	v_cvt_pk_bf16_f32 v28, v28, v29
	v_cvt_pk_bf16_f32 v29, v30, v31
	v_cvt_pk_bf16_f32 v30, v24, v25
	v_add_co_u32_e32 v24, vcc, 0x28000, v32
	v_cvt_pk_bf16_f32 v31, v26, v27
	s_nop 0
	v_addc_co_u32_e32 v25, vcc, 0, v33, vcc
	s_and_b64 vcc, exec, s[8:9]
	global_store_dwordx4 v[24:25], v[28:31], off
	s_cbranch_vccnz .LBB0_529
	v_mul_f32_e32 v24, v20, v20
	v_mul_f32_e32 v25, v21, v21
	v_mul_f32_e32 v26, v22, v22
	v_mul_f32_e32 v27, v23, v23
	v_fmamk_f32 v24, v24, 0xbdd2d3e8, v209
	v_fmamk_f32 v25, v25, 0xbdd2d3e8, v209
	v_fmamk_f32 v26, v26, 0xbdd2d3e8, v209
	v_fmamk_f32 v27, v27, 0xbdd2d3e8, v209
	v_mul_f32_e32 v24, v20, v24
	v_mul_f32_e32 v25, v21, v25
	v_mul_f32_e32 v26, v22, v26
	v_mul_f32_e32 v27, v23, v27
	v_exp_f32_e32 v24, v24
	v_exp_f32_e32 v25, v25
	v_exp_f32_e32 v26, v26
	v_exp_f32_e32 v27, v27
	v_add_f32_e32 v24, 1.0, v24
	v_add_f32_e32 v25, 1.0, v25
	v_add_f32_e32 v26, 1.0, v26
	v_add_f32_e32 v27, 1.0, v27
	v_rcp_f32_e32 v24, v24
	v_rcp_f32_e32 v25, v25
	v_rcp_f32_e32 v26, v26
	v_rcp_f32_e32 v27, v27
	v_pk_mul_f32 v[20:21], v[20:21], v[24:25]
	v_mul_f32_e32 v24, v16, v16
	v_pk_mul_f32 v[22:23], v[22:23], v[26:27]
	v_mul_f32_e32 v25, v17, v17
	v_mul_f32_e32 v26, v18, v18
	v_mul_f32_e32 v27, v19, v19
	v_fmamk_f32 v24, v24, 0xbdd2d3e8, v209
	v_fmamk_f32 v25, v25, 0xbdd2d3e8, v209
	v_fmamk_f32 v26, v26, 0xbdd2d3e8, v209
	v_fmamk_f32 v27, v27, 0xbdd2d3e8, v209
	v_mul_f32_e32 v24, v16, v24
	v_mul_f32_e32 v25, v17, v25
	v_mul_f32_e32 v26, v18, v26
	v_mul_f32_e32 v27, v19, v27
	v_exp_f32_e32 v24, v24
	v_exp_f32_e32 v25, v25
	v_exp_f32_e32 v26, v26
	v_exp_f32_e32 v27, v27
	v_add_f32_e32 v24, 1.0, v24
	v_add_f32_e32 v25, 1.0, v25
	v_add_f32_e32 v26, 1.0, v26
	v_add_f32_e32 v27, 1.0, v27
	v_rcp_f32_e32 v24, v24
	v_rcp_f32_e32 v25, v25
	v_rcp_f32_e32 v26, v26
	v_rcp_f32_e32 v27, v27
	v_pk_mul_f32 v[16:17], v[16:17], v[24:25]
	v_pk_mul_f32 v[18:19], v[18:19], v[26:27]
.LBB0_529:
	s_mov_b64 s[16:17], 0x28000
	v_lshl_add_u64 v[24:25], v[32:33], 0, s[16:17]
	v_cvt_pk_bf16_f32 v20, v20, v21
	v_cvt_pk_bf16_f32 v21, v22, v23
	v_cvt_pk_bf16_f32 v22, v16, v17
	v_cvt_pk_bf16_f32 v23, v18, v19
	s_and_b64 vcc, exec, s[8:9]
	global_store_dwordx4 v[24:25], v[20:23], off offset:256
	s_cbranch_vccnz .LBB0_531
	v_mul_f32_e32 v16, v12, v12
	v_mul_f32_e32 v17, v13, v13
	v_mul_f32_e32 v18, v14, v14
	v_mul_f32_e32 v19, v15, v15
	v_fmamk_f32 v16, v16, 0xbdd2d3e8, v209
	v_fmamk_f32 v17, v17, 0xbdd2d3e8, v209
	v_fmamk_f32 v18, v18, 0xbdd2d3e8, v209
	v_fmamk_f32 v19, v19, 0xbdd2d3e8, v209
	v_mul_f32_e32 v16, v12, v16
	v_mul_f32_e32 v17, v13, v17
	v_mul_f32_e32 v18, v14, v18
	v_mul_f32_e32 v19, v15, v19
	v_exp_f32_e32 v16, v16
	v_exp_f32_e32 v17, v17
	v_exp_f32_e32 v18, v18
	v_exp_f32_e32 v19, v19
	v_add_f32_e32 v16, 1.0, v16
	v_add_f32_e32 v17, 1.0, v17
	v_add_f32_e32 v18, 1.0, v18
	v_add_f32_e32 v19, 1.0, v19
	v_rcp_f32_e32 v16, v16
	v_rcp_f32_e32 v17, v17
	v_rcp_f32_e32 v18, v18
	v_rcp_f32_e32 v19, v19
	v_pk_mul_f32 v[12:13], v[12:13], v[16:17]
	v_mul_f32_e32 v16, v8, v8
	v_pk_mul_f32 v[14:15], v[14:15], v[18:19]
	v_mul_f32_e32 v17, v9, v9
	v_mul_f32_e32 v18, v10, v10
	v_mul_f32_e32 v19, v11, v11
	v_fmamk_f32 v16, v16, 0xbdd2d3e8, v209
	v_fmamk_f32 v17, v17, 0xbdd2d3e8, v209
	v_fmamk_f32 v18, v18, 0xbdd2d3e8, v209
	v_fmamk_f32 v19, v19, 0xbdd2d3e8, v209
	v_mul_f32_e32 v16, v8, v16
	v_mul_f32_e32 v17, v9, v17
	v_mul_f32_e32 v18, v10, v18
	v_mul_f32_e32 v19, v11, v19
	v_exp_f32_e32 v16, v16
	v_exp_f32_e32 v17, v17
	v_exp_f32_e32 v18, v18
	v_exp_f32_e32 v19, v19
	v_add_f32_e32 v16, 1.0, v16
	v_add_f32_e32 v17, 1.0, v17
	v_add_f32_e32 v18, 1.0, v18
	v_add_f32_e32 v19, 1.0, v19
	v_rcp_f32_e32 v16, v16
	v_rcp_f32_e32 v17, v17
	v_rcp_f32_e32 v18, v18
	v_rcp_f32_e32 v19, v19
	v_pk_mul_f32 v[8:9], v[8:9], v[16:17]
	v_pk_mul_f32 v[10:11], v[10:11], v[18:19]
.LBB0_531:
	v_lshlrev_b64 v[16:17], 10, v[190:191]
	v_lshl_add_u64 v[16:17], v[128:129], 0, v[16:17]
	v_cvt_pk_bf16_f32 v12, v12, v13
	v_cvt_pk_bf16_f32 v13, v14, v15
	v_cvt_pk_bf16_f32 v14, v8, v9
	v_add_co_u32_e32 v8, vcc, 0x2c000, v16
	v_cvt_pk_bf16_f32 v15, v10, v11
	s_nop 0
	v_addc_co_u32_e32 v9, vcc, 0, v17, vcc
	s_and_b64 vcc, exec, s[8:9]
	global_store_dwordx4 v[8:9], v[12:15], off
	s_cbranch_vccnz .LBB0_533
	v_mul_f32_e32 v8, v4, v4
	v_mul_f32_e32 v9, v5, v5
	v_mul_f32_e32 v10, v6, v6
	v_mul_f32_e32 v11, v7, v7
	v_fmamk_f32 v8, v8, 0xbdd2d3e8, v209
	v_fmamk_f32 v9, v9, 0xbdd2d3e8, v209
	v_fmamk_f32 v10, v10, 0xbdd2d3e8, v209
	v_fmamk_f32 v11, v11, 0xbdd2d3e8, v209
	v_mul_f32_e32 v8, v4, v8
	v_mul_f32_e32 v9, v5, v9
	v_mul_f32_e32 v10, v6, v10
	v_mul_f32_e32 v11, v7, v11
	v_exp_f32_e32 v8, v8
	v_exp_f32_e32 v9, v9
	v_exp_f32_e32 v10, v10
	v_exp_f32_e32 v11, v11
	v_add_f32_e32 v8, 1.0, v8
	v_add_f32_e32 v9, 1.0, v9
	v_add_f32_e32 v10, 1.0, v10
	v_add_f32_e32 v11, 1.0, v11
	v_rcp_f32_e32 v8, v8
	v_rcp_f32_e32 v9, v9
	v_rcp_f32_e32 v10, v10
	v_rcp_f32_e32 v11, v11
	v_pk_mul_f32 v[4:5], v[4:5], v[8:9]
	v_mul_f32_e32 v8, v0, v0
	v_pk_mul_f32 v[6:7], v[6:7], v[10:11]
	v_mul_f32_e32 v9, v1, v1
	v_mul_f32_e32 v10, v2, v2
	v_mul_f32_e32 v11, v3, v3
	v_fmamk_f32 v8, v8, 0xbdd2d3e8, v209
	v_fmamk_f32 v9, v9, 0xbdd2d3e8, v209
	v_fmamk_f32 v10, v10, 0xbdd2d3e8, v209
	v_fmamk_f32 v11, v11, 0xbdd2d3e8, v209
	v_mul_f32_e32 v8, v0, v8
	v_mul_f32_e32 v9, v1, v9
	v_mul_f32_e32 v10, v2, v10
	v_mul_f32_e32 v11, v3, v11
	v_exp_f32_e32 v8, v8
	v_exp_f32_e32 v9, v9
	v_exp_f32_e32 v10, v10
	v_exp_f32_e32 v11, v11
	v_add_f32_e32 v8, 1.0, v8
	v_add_f32_e32 v9, 1.0, v9
	v_add_f32_e32 v10, 1.0, v10
	v_add_f32_e32 v11, 1.0, v11
	v_rcp_f32_e32 v8, v8
	v_rcp_f32_e32 v9, v9
	v_rcp_f32_e32 v10, v10
	v_rcp_f32_e32 v11, v11
	v_pk_mul_f32 v[0:1], v[0:1], v[8:9]
	v_pk_mul_f32 v[2:3], v[2:3], v[10:11]
.LBB0_533:
	s_mov_b64 s[8:9], 0x2c000
	v_lshl_add_u64 v[8:9], v[16:17], 0, s[8:9]
	v_cvt_pk_bf16_f32 v4, v4, v5
	v_cvt_pk_bf16_f32 v5, v6, v7
	v_cvt_pk_bf16_f32 v6, v0, v1
	v_cvt_pk_bf16_f32 v7, v2, v3
	global_store_dwordx4 v[8:9], v[4:7], off offset:256
	s_andn2_b64 vcc, exec, s[6:7]
	s_mov_b64 s[6:7], -1
	s_cbranch_vccnz .LBB0_479

.LBB0_557:
	v_lshl_add_u32 v154, s39, 8, v156
	v_lshl_add_u32 v152, s38, 8, v158
	s_ashr_i32 s11, s39, 3
	v_ashrrev_i32_e32 v155, 31, v154
	s_mul_hi_i32 s13, s11, 0x6000
	s_mulk_i32 s11, 0x6000
	v_ashrrev_i32_e32 v153, 31, v152
	v_lshlrev_b64 v[148:149], 10, v[154:155]
	s_add_u32 s18, s31, s11
	v_lshl_add_u64 v[148:149], v[148:149], 0, v[152:153]
	s_addc_u32 s19, s34, s13
	v_lshlrev_b64 v[150:151], 2, v[148:149]
	v_lshl_add_u64 v[146:147], v[152:153], 2, s[18:19]
	v_lshl_add_u64 v[148:149], s[0:1], 0, v[150:151]
	global_load_dwordx4 v[132:135], v[146:147], off
	global_load_dwordx4 v[128:131], v[146:147], off offset:16
	global_load_dwordx4 v[170:173], v[148:149], off
	global_load_dwordx4 v[174:177], v[148:149], off offset:16
	s_mov_b64 s[18:19], 0x80000
	s_andn2_b64 vcc, exec, s[6:7]
	s_waitcnt vmcnt(0) lgkmcnt(0)
	v_pk_fma_f32 v[170:171], v[124:125], v[132:133], v[170:171]
	v_lshl_add_u64 v[124:125], s[8:9], 0, v[150:151]
	v_pk_fma_f32 v[122:123], v[122:123], v[130:131], v[176:177]
	v_pk_fma_f32 v[120:121], v[120:121], v[128:129], v[174:175]
	global_store_dwordx4 v[124:125], v[120:123], off offset:16
	v_pk_fma_f32 v[172:173], v[126:127], v[134:135], v[172:173]
	global_store_dwordx4 v[124:125], v[170:173], off
	v_or_b32_e32 v120, 16, v154
	v_ashrrev_i32_e32 v121, 31, v120
	v_lshlrev_b64 v[120:121], 10, v[120:121]
	v_lshl_add_u64 v[120:121], v[120:121], 0, v[152:153]
	v_lshlrev_b64 v[122:123], 2, v[120:121]
	v_lshl_add_u64 v[120:121], s[0:1], 0, v[122:123]
	global_load_dwordx4 v[170:173], v[120:121], off
	global_load_dwordx4 v[174:177], v[120:121], off offset:16
	s_waitcnt vmcnt(0) lgkmcnt(0)
	v_pk_fma_f32 v[170:171], v[116:117], v[132:133], v[170:171]
	v_lshl_add_u64 v[116:117], s[8:9], 0, v[122:123]
	v_pk_fma_f32 v[114:115], v[114:115], v[130:131], v[176:177]
	v_pk_fma_f32 v[112:113], v[112:113], v[128:129], v[174:175]
	global_store_dwordx4 v[116:117], v[112:115], off offset:16
	v_pk_fma_f32 v[172:173], v[118:119], v[134:135], v[172:173]
	global_store_dwordx4 v[116:117], v[170:173], off
	v_or_b32_e32 v112, 32, v154
	v_ashrrev_i32_e32 v113, 31, v112
	v_lshlrev_b64 v[112:113], 10, v[112:113]
	v_lshl_add_u64 v[112:113], v[112:113], 0, v[152:153]
	v_lshlrev_b64 v[114:115], 2, v[112:113]
	v_lshl_add_u64 v[112:113], s[0:1], 0, v[114:115]
	global_load_dwordx4 v[170:173], v[112:113], off
	global_load_dwordx4 v[174:177], v[112:113], off offset:16
	s_waitcnt vmcnt(0) lgkmcnt(0)
	v_pk_fma_f32 v[170:171], v[108:109], v[132:133], v[170:171]
	v_lshl_add_u64 v[108:109], s[8:9], 0, v[114:115]
	v_pk_fma_f32 v[106:107], v[106:107], v[130:131], v[176:177]
	v_pk_fma_f32 v[104:105], v[104:105], v[128:129], v[174:175]
	global_store_dwordx4 v[108:109], v[104:107], off offset:16
	v_pk_fma_f32 v[172:173], v[110:111], v[134:135], v[172:173]
	global_store_dwordx4 v[108:109], v[170:173], off
	v_or_b32_e32 v104, 48, v154
	v_ashrrev_i32_e32 v105, 31, v104
	v_lshlrev_b64 v[104:105], 10, v[104:105]
	v_lshl_add_u64 v[104:105], v[104:105], 0, v[152:153]
	v_lshlrev_b64 v[106:107], 2, v[104:105]
	v_lshl_add_u64 v[104:105], s[0:1], 0, v[106:107]
	global_load_dwordx4 v[152:155], v[104:105], off
	global_load_dwordx4 v[170:173], v[104:105], off offset:16
	s_waitcnt vmcnt(0) lgkmcnt(0)
	v_pk_fma_f32 v[152:153], v[100:101], v[132:133], v[152:153]
	v_lshl_add_u64 v[100:101], s[8:9], 0, v[106:107]
	v_pk_fma_f32 v[98:99], v[98:99], v[130:131], v[172:173]
	v_pk_fma_f32 v[96:97], v[96:97], v[128:129], v[170:171]
	v_pk_fma_f32 v[154:155], v[102:103], v[134:135], v[154:155]
	global_store_dwordx4 v[100:101], v[96:99], off offset:16
	global_store_dwordx4 v[100:101], v[152:155], off
	s_nop 0
	v_lshl_add_u64 v[98:99], v[150:151], 0, s[18:19]
	v_lshl_add_u64 v[96:97], s[0:1], 0, v[98:99]
	global_load_dwordx4 v[152:155], v[96:97], off
	global_load_dwordx4 v[170:173], v[96:97], off offset:16
	s_mov_b64 s[18:19], 0x90000
	s_waitcnt vmcnt(0) lgkmcnt(0)
	v_pk_fma_f32 v[152:153], v[92:93], v[132:133], v[152:153]
	v_lshl_add_u64 v[92:93], s[8:9], 0, v[98:99]
	v_pk_fma_f32 v[90:91], v[90:91], v[130:131], v[172:173]
	v_pk_fma_f32 v[88:89], v[88:89], v[128:129], v[170:171]
	v_pk_fma_f32 v[154:155], v[94:95], v[134:135], v[154:155]
	global_store_dwordx4 v[92:93], v[88:91], off offset:16
	global_store_dwordx4 v[92:93], v[152:155], off
	s_nop 0
	v_lshl_add_u64 v[90:91], v[150:151], 0, s[18:19]
	v_lshl_add_u64 v[88:89], s[0:1], 0, v[90:91]
	global_load_dwordx4 v[152:155], v[88:89], off
	global_load_dwordx4 v[170:173], v[88:89], off offset:16
	s_mov_b64 s[18:19], 0xa0000
	s_waitcnt vmcnt(0) lgkmcnt(0)
	v_pk_fma_f32 v[152:153], v[84:85], v[132:133], v[152:153]
	v_lshl_add_u64 v[84:85], s[8:9], 0, v[90:91]
	v_pk_fma_f32 v[82:83], v[82:83], v[130:131], v[172:173]
	v_pk_fma_f32 v[80:81], v[80:81], v[128:129], v[170:171]
	v_pk_fma_f32 v[154:155], v[86:87], v[134:135], v[154:155]
	global_store_dwordx4 v[84:85], v[80:83], off offset:16
	global_store_dwordx4 v[84:85], v[152:155], off
	s_nop 0
	v_lshl_add_u64 v[82:83], v[150:151], 0, s[18:19]
	v_lshl_add_u64 v[80:81], s[0:1], 0, v[82:83]
	global_load_dwordx4 v[152:155], v[80:81], off
	global_load_dwordx4 v[170:173], v[80:81], off offset:16
	s_mov_b64 s[18:19], 0xb0000
	s_waitcnt vmcnt(0) lgkmcnt(0)
	v_pk_fma_f32 v[152:153], v[76:77], v[132:133], v[152:153]
	v_lshl_add_u64 v[76:77], s[8:9], 0, v[82:83]
	v_pk_fma_f32 v[74:75], v[74:75], v[130:131], v[172:173]
	v_pk_fma_f32 v[72:73], v[72:73], v[128:129], v[170:171]
	v_pk_fma_f32 v[154:155], v[78:79], v[134:135], v[154:155]
	global_store_dwordx4 v[76:77], v[72:75], off offset:16
	global_store_dwordx4 v[76:77], v[152:155], off
	s_nop 0
	v_lshl_add_u64 v[74:75], v[150:151], 0, s[18:19]
	v_lshl_add_u64 v[72:73], s[0:1], 0, v[74:75]
	global_load_dwordx4 v[150:153], v[72:73], off
	global_load_dwordx4 v[170:173], v[72:73], off offset:16
	s_mov_b64 s[18:19], -1
	s_waitcnt vmcnt(0) lgkmcnt(0)
	v_pk_fma_f32 v[134:135], v[70:71], v[134:135], v[152:153]
	v_pk_fma_f32 v[132:133], v[68:69], v[132:133], v[150:151]
	v_lshl_add_u64 v[68:69], s[8:9], 0, v[74:75]
	v_pk_fma_f32 v[58:59], v[58:59], v[130:131], v[172:173]
	v_pk_fma_f32 v[56:57], v[56:57], v[128:129], v[170:171]
	global_store_dwordx4 v[68:69], v[132:135], off
	global_store_dwordx4 v[68:69], v[56:59], off offset:16
	global_load_dwordx4 v[56:59], v[146:147], off offset:512
	s_nop 0
	global_load_dwordx4 v[126:129], v[146:147], off offset:528
	global_load_dwordx4 v[130:133], v[148:149], off offset:512
	s_nop 0
	global_load_dwordx4 v[146:149], v[148:149], off offset:528
	s_waitcnt vmcnt(0) lgkmcnt(0)
	v_pk_fma_f32 v[66:67], v[66:67], v[58:59], v[132:133]
	v_pk_fma_f32 v[64:65], v[64:65], v[56:57], v[130:131]
	v_pk_fma_f32 v[62:63], v[62:63], v[128:129], v[148:149]
	v_pk_fma_f32 v[60:61], v[60:61], v[126:127], v[146:147]
	global_store_dwordx4 v[124:125], v[64:67], off offset:512
	global_store_dwordx4 v[124:125], v[60:63], off offset:528
	global_load_dwordx4 v[60:63], v[120:121], off offset:512
	s_nop 0
	global_load_dwordx4 v[64:67], v[120:121], off offset:528
	s_waitcnt vmcnt(0) lgkmcnt(0)
	v_pk_fma_f32 v[54:55], v[54:55], v[58:59], v[62:63]
	v_pk_fma_f32 v[52:53], v[52:53], v[56:57], v[60:61]
	v_pk_fma_f32 v[50:51], v[50:51], v[128:129], v[66:67]
	v_pk_fma_f32 v[48:49], v[48:49], v[126:127], v[64:65]
	global_store_dwordx4 v[116:117], v[52:55], off offset:512
	global_store_dwordx4 v[116:117], v[48:51], off offset:528
	global_load_dwordx4 v[48:51], v[112:113], off offset:512
	s_nop 0
	global_load_dwordx4 v[52:55], v[112:113], off offset:528
	s_waitcnt vmcnt(0) lgkmcnt(0)
	v_pk_fma_f32 v[46:47], v[46:47], v[58:59], v[50:51]
	v_pk_fma_f32 v[44:45], v[44:45], v[56:57], v[48:49]
	v_pk_fma_f32 v[42:43], v[42:43], v[128:129], v[54:55]
	v_pk_fma_f32 v[40:41], v[40:41], v[126:127], v[52:53]
	global_store_dwordx4 v[108:109], v[44:47], off offset:512
	global_store_dwordx4 v[108:109], v[40:43], off offset:528
	global_load_dwordx4 v[40:43], v[104:105], off offset:512
	s_nop 0
	global_load_dwordx4 v[44:47], v[104:105], off offset:528
	s_waitcnt vmcnt(0) lgkmcnt(0)
	v_pk_fma_f32 v[38:39], v[38:39], v[58:59], v[42:43]
	v_pk_fma_f32 v[36:37], v[36:37], v[56:57], v[40:41]
	v_pk_fma_f32 v[34:35], v[34:35], v[128:129], v[46:47]
	v_pk_fma_f32 v[32:33], v[32:33], v[126:127], v[44:45]
	global_store_dwordx4 v[100:101], v[36:39], off offset:512
	global_store_dwordx4 v[100:101], v[32:35], off offset:528
	global_load_dwordx4 v[32:35], v[96:97], off offset:512
	s_nop 0
	global_load_dwordx4 v[36:39], v[96:97], off offset:528
	s_waitcnt vmcnt(0) lgkmcnt(0)
	v_pk_fma_f32 v[30:31], v[30:31], v[58:59], v[34:35]
	v_pk_fma_f32 v[28:29], v[28:29], v[56:57], v[32:33]
	v_pk_fma_f32 v[26:27], v[26:27], v[128:129], v[38:39]
	v_pk_fma_f32 v[24:25], v[24:25], v[126:127], v[36:37]
	global_store_dwordx4 v[92:93], v[28:31], off offset:512
	global_store_dwordx4 v[92:93], v[24:27], off offset:528
	global_load_dwordx4 v[24:27], v[88:89], off offset:512
	s_nop 0
	global_load_dwordx4 v[28:31], v[88:89], off offset:528
	s_waitcnt vmcnt(0) lgkmcnt(0)
	v_pk_fma_f32 v[22:23], v[22:23], v[58:59], v[26:27]
	v_pk_fma_f32 v[20:21], v[20:21], v[56:57], v[24:25]
	v_pk_fma_f32 v[18:19], v[18:19], v[128:129], v[30:31]
	v_pk_fma_f32 v[16:17], v[16:17], v[126:127], v[28:29]
	global_store_dwordx4 v[84:85], v[20:23], off offset:512
	global_store_dwordx4 v[84:85], v[16:19], off offset:528
	global_load_dwordx4 v[16:19], v[80:81], off offset:512
	s_nop 0
	global_load_dwordx4 v[20:23], v[80:81], off offset:528
	s_waitcnt vmcnt(0) lgkmcnt(0)
	v_pk_fma_f32 v[14:15], v[14:15], v[58:59], v[18:19]
	v_pk_fma_f32 v[12:13], v[12:13], v[56:57], v[16:17]
	v_pk_fma_f32 v[10:11], v[10:11], v[128:129], v[22:23]
	v_pk_fma_f32 v[8:9], v[8:9], v[126:127], v[20:21]
	global_store_dwordx4 v[76:77], v[12:15], off offset:512
	global_store_dwordx4 v[76:77], v[8:11], off offset:528
	global_load_dwordx4 v[8:11], v[72:73], off offset:512
	s_nop 0
	global_load_dwordx4 v[12:15], v[72:73], off offset:528
	s_waitcnt vmcnt(0) lgkmcnt(0)
	v_pk_fma_f32 v[6:7], v[6:7], v[58:59], v[10:11]
	v_pk_fma_f32 v[4:5], v[4:5], v[56:57], v[8:9]
	v_pk_fma_f32 v[2:3], v[2:3], v[128:129], v[14:15]
	v_pk_fma_f32 v[0:1], v[0:1], v[126:127], v[12:13]
	global_store_dwordx4 v[68:69], v[4:7], off offset:512
	global_store_dwordx4 v[68:69], v[0:3], off offset:528
	s_cbranch_vccnz .LBB0_546
	s_and_b64 vcc, exec, s[4:5]
	s_cbranch_vccnz .LBB0_545
	s_barrier
	s_branch .LBB0_545

.LBB0_562:
	s_and_b64 vcc, exec, s[0:1]
	s_cbranch_vccz .LBB0_569
	v_mov_b32_e32 v0, 16
	v_mov_b32_e32 v2, 0xe8
	v_add_u32_e32 v0, s91, v0
	ds_read_b64 v[0:1], v0
	v_readlane_b32 s0, v253, 11
	v_add_u32_e32 v2, s91, v2
	ds_read_b64 v[2:3], v2
	s_waitcnt lgkmcnt(0)
	v_readfirstlane_b32 s2, v1
	v_readfirstlane_b32 s6, v0
	v_mbcnt_lo_u32_b32 v0, -1, 0
	v_mbcnt_hi_u32_b32 v0, -1, v0
	v_readfirstlane_b32 s5, v3
	v_add_u32_e32 v1, s57, v0
	v_ashrrev_i32_e32 v1, 6, v1
	v_add_u32_e32 v52, s0, v1
	v_readfirstlane_b32 s4, v2
	v_cmp_gt_i32_e32 vcc, s3, v52
	s_and_saveexec_b64 s[0:1], vcc
	v_readlane_b32 s10, v252, 23
	s_cbranch_execz .LBB0_568
	v_readlane_b32 s7, v252, 31
	s_lshl_b32 s8, s7, 10
	s_ashr_i32 s9, s8, 31
	s_lshl_b64 s[8:9], s[8:9], 2
	s_add_u32 s6, s6, s8
	v_and_b32_e32 v16, 63, v0
	s_addc_u32 s7, s2, s9
	v_lshlrev_b32_e32 v160, 4, v16
	v_lshl_add_u64 v[12:13], s[6:7], 0, v[160:161]
	global_load_dwordx4 v[0:3], v[12:13], off
	global_load_dwordx4 v[4:7], v[12:13], off offset:1024
	global_load_dwordx4 v[8:11], v[12:13], off offset:2048
	s_nop 0
	global_load_dwordx4 v[12:15], v[12:13], off offset:3072
	v_cmp_lt_i32_e32 vcc, v214, v213
	v_readlane_b32 s6, v252, 25
	v_readlane_b32 s7, v252, 26
	v_cndmask_b32_e32 v17, v211, v214, vcc
	v_cmp_lt_i32_e32 vcc, v215, v213
	v_lshlrev_b32_e32 v56, 2, v17
	v_lshl_add_u64 v[44:45], s[6:7], 0, v[160:161]
	v_cndmask_b32_e32 v17, v211, v215, vcc
	v_cmp_lt_i32_e32 vcc, v216, v213
	v_lshlrev_b32_e32 v57, 2, v17
	v_readlane_b32 s6, v252, 32
	v_cndmask_b32_e32 v17, v211, v216, vcc
	v_cmp_lt_i32_e32 vcc, v217, v213
	v_lshlrev_b32_e32 v58, 2, v17
	v_readlane_b32 s7, v252, 33
	v_cndmask_b32_e32 v17, v211, v217, vcc
	v_cmp_lt_i32_e32 vcc, v218, v213
	v_lshlrev_b32_e32 v59, 2, v17
	v_lshl_add_u64 v[46:47], s[6:7], 0, v[160:161]
	v_cndmask_b32_e32 v17, v211, v218, vcc
	v_cmp_lt_i32_e32 vcc, v219, v213
	v_lshlrev_b32_e32 v60, 2, v17
	v_lshlrev_b32_e32 v160, 3, v16
	v_cndmask_b32_e32 v17, v211, v219, vcc
	v_lshlrev_b32_e32 v61, 2, v17
	s_mov_b64 s[6:7], 0x1000
	v_lshl_add_u64 v[16:17], s[4:5], 0, v[160:161]
	s_mov_b64 s[4:5], 0x5200000
	v_lshl_add_u64 v[48:49], v[46:47], 0, s[6:7]
	v_lshl_add_u64 v[50:51], v[16:17], 0, s[4:5]
	s_mov_b64 s[4:5], 0
	s_branch .LBB0_566

.LBB0_566:
	v_ashrrev_i32_e32 v53, 31, v52
	v_lshlrev_b64 v[16:17], 12, v[52:53]
	s_waitcnt lgkmcnt(0)
	v_lshl_add_u64 v[20:21], v[44:45], 0, v[16:17]
	global_load_dwordx4 v[64:67], v[20:21], off
	global_load_dwordx4 v[28:31], v[20:21], off offset:1024
	global_load_dwordx4 v[16:19], v[20:21], off offset:3072
	s_nop 0
	global_load_dwordx4 v[20:23], v[20:21], off offset:2048
	v_ashrrev_i32_e32 v24, 11, v52
	v_mul_hi_i32_i24_e32 v25, 0x1800, v24
	v_mul_i32_i24_e32 v24, 0x1800, v24
	v_lshlrev_b64 v[24:25], 2, v[24:25]
	v_lshl_add_u64 v[76:77], v[48:49], 0, v[24:25]
	global_load_dwordx4 v[68:71], v[76:77], off
	v_lshl_add_u64 v[78:79], v[46:47], 0, v[24:25]
	global_load_dwordx4 v[72:75], v[78:79], off
	v_add_u32_e32 v62, s10, v52
	v_cmp_gt_i32_e32 vcc, s3, v62
	s_mov_b32 s2, 0x800000
	s_waitcnt vmcnt(0) lgkmcnt(0)
	v_pk_mul_f32 v[24:25], v[66:67], v[66:67]
	v_pk_mul_f32 v[26:27], v[64:65], v[64:65]
	v_pk_mul_f32 v[32:33], v[30:31], v[30:31]
	v_pk_mul_f32 v[34:35], v[28:29], v[28:29]
	v_pk_mov_b32 v[40:41], v[26:27], v[24:25] op_sel:[1,0]
	v_mov_b32_e32 v27, v25
	v_pk_mov_b32 v[24:25], v[34:35], v[32:33] op_sel:[1,0]
	v_mov_b32_e32 v35, v33
	v_mul_f32_e32 v39, v16, v16
	v_mul_f32_e32 v36, v21, v21
	v_mul_f32_e32 v38, v23, v23
	v_pk_add_f32 v[26:27], v[40:41], v[26:27]
	v_pk_add_f32 v[24:25], v[24:25], v[34:35]
	v_mul_f32_e32 v42, v17, v17
	v_mul_f32_e32 v43, v18, v18
	v_mul_f32_e32 v54, v19, v19
	v_pk_fma_f32 v[32:33], v[20:21], v[20:21], v[36:37] op_sel_hi:[1,1,0]
	v_pk_fma_f32 v[36:37], v[22:23], v[22:23], v[38:39] op_sel_hi:[1,1,0]
	v_pk_add_f32 v[26:27], v[26:27], v[26:27] op_sel:[0,1] op_sel_hi:[1,0]
	v_pk_add_f32 v[24:25], v[24:25], v[24:25] op_sel:[0,1] op_sel_hi:[1,0]
	v_mov_b32_e32 v33, v43
	v_mov_b32_e32 v37, v54
	v_mov_b32_e32 v27, v39
	v_mov_b32_e32 v25, v42
	v_pk_add_f32 v[32:33], v[32:33], v[36:37]
	v_pk_add_f32 v[24:25], v[26:27], v[24:25]
	v_cndmask_b32_e32 v54, v52, v62, vcc
	v_pk_add_f32 v[24:25], v[24:25], v[32:33]
	v_ashrrev_i32_e32 v55, 31, v54
	v_add_f32_e32 v24, v24, v25
	ds_bpermute_b32 v25, v56, v24
	v_pk_add_f32 v[70:71], v[70:71], 1.0 op_sel_hi:[1,0]
	v_pk_add_f32 v[68:69], v[68:69], 1.0 op_sel_hi:[1,0]
	s_waitcnt lgkmcnt(0)
	v_add_f32_e32 v24, v24, v25
	ds_bpermute_b32 v25, v57, v24
	s_waitcnt lgkmcnt(0)
	v_add_f32_e32 v24, v24, v25
	ds_bpermute_b32 v25, v58, v24
	s_waitcnt lgkmcnt(0)
	v_add_f32_e32 v24, v24, v25
	ds_bpermute_b32 v25, v59, v24
	s_waitcnt lgkmcnt(0)
	v_add_f32_e32 v26, v24, v25
	ds_bpermute_b32 v27, v60, v26
	v_lshlrev_b64 v[24:25], 11, v[52:53]
	v_lshl_add_u64 v[80:81], v[50:51], 0, v[24:25]
	v_lshlrev_b64 v[24:25], 12, v[54:55]
	v_lshl_add_u64 v[24:25], v[44:45], 0, v[24:25]
	s_waitcnt lgkmcnt(0)
	v_add_f32_e32 v26, v26, v27
	ds_bpermute_b32 v27, v61, v26
	global_load_dwordx4 v[40:43], v[24:25], off
	global_load_dwordx4 v[36:39], v[24:25], off offset:1024
	s_waitcnt lgkmcnt(0)
	v_add_f32_e32 v26, v26, v27
	v_fmamk_f32 v26, v26, 0x3a800000, v208
	v_mul_f32_e32 v27, 0x4b800000, v26
	v_cmp_gt_f32_e32 vcc, s2, v26
	s_nop 1
	v_cndmask_b32_e32 v26, v26, v27, vcc
	v_rsq_f32_e32 v53, v26
	global_load_dwordx4 v[32:35], v[24:25], off offset:2048
	s_nop 0
	global_load_dwordx4 v[24:27], v[24:25], off offset:3072
	v_mul_f32_e32 v63, 0x45800000, v53
	v_cndmask_b32_e32 v82, v53, v63, vcc
	v_pk_mul_f32 v[66:67], v[66:67], v[82:83] op_sel_hi:[1,0]
	v_pk_mul_f32 v[64:65], v[64:65], v[82:83] op_sel_hi:[1,0]
	v_pk_mul_f32 v[66:67], v[2:3], v[66:67]
	v_pk_mul_f32 v[64:65], v[0:1], v[64:65]
	v_pk_fma_f32 v[66:67], v[70:71], v[66:67], v[74:75]
	v_pk_fma_f32 v[64:65], v[68:69], v[64:65], v[72:73]
	v_pk_mul_f32 v[30:31], v[30:31], v[82:83] op_sel_hi:[1,0]
	v_cvt_pk_bf16_f32 v64, v64, v65
	v_cvt_pk_bf16_f32 v65, v66, v67
	global_store_dwordx2 v[80:81], v[64:65], off
	global_load_dwordx4 v[64:67], v[76:77], off offset:1024
	s_nop 0
	global_load_dwordx4 v[68:71], v[78:79], off offset:1024
	v_pk_mul_f32 v[28:29], v[28:29], v[82:83] op_sel_hi:[1,0]
	v_pk_mul_f32 v[30:31], v[6:7], v[30:31]
	v_pk_mul_f32 v[28:29], v[4:5], v[28:29]
	v_pk_mul_f32 v[22:23], v[22:23], v[82:83] op_sel_hi:[1,0]
	v_pk_mul_f32 v[20:21], v[20:21], v[82:83] op_sel_hi:[1,0]
	v_pk_mul_f32 v[22:23], v[10:11], v[22:23]
	v_pk_mul_f32 v[20:21], v[8:9], v[20:21]
	v_pk_mul_f32 v[18:19], v[18:19], v[82:83] op_sel_hi:[1,0]
	v_pk_mul_f32 v[16:17], v[16:17], v[82:83] op_sel_hi:[1,0]
	v_pk_mul_f32 v[18:19], v[14:15], v[18:19]
	v_pk_mul_f32 v[16:17], v[12:13], v[16:17]
	v_cmp_ne_u32_e32 vcc, v52, v54
	s_waitcnt vmcnt(0) lgkmcnt(0)
	v_mul_f32_e32 v53, v33, v33
	v_mul_f32_e32 v63, v35, v35
	v_fmac_f32_e32 v53, v32, v32
	v_fmac_f32_e32 v63, v34, v34
	v_pk_add_f32 v[66:67], v[66:67], 1.0 op_sel_hi:[1,0]
	v_pk_add_f32 v[64:65], v[64:65], 1.0 op_sel_hi:[1,0]
	v_pk_fma_f32 v[30:31], v[66:67], v[30:31], v[70:71]
	v_pk_fma_f32 v[28:29], v[64:65], v[28:29], v[68:69]
	v_mul_f32_e32 v68, v25, v25
	v_cvt_pk_bf16_f32 v28, v28, v29
	v_cvt_pk_bf16_f32 v29, v30, v31
	global_store_dwordx2 v[80:81], v[28:29], off offset:512
	global_load_dwordx4 v[28:31], v[76:77], off offset:2048
	s_nop 0
	global_load_dwordx4 v[64:67], v[78:79], off offset:2048
	v_mul_f32_e32 v69, v27, v27
	v_fmac_f32_e32 v68, v24, v24
	v_fmac_f32_e32 v69, v26, v26
	s_waitcnt vmcnt(0) lgkmcnt(0)
	v_pk_add_f32 v[30:31], v[30:31], 1.0 op_sel_hi:[1,0]
	v_pk_add_f32 v[28:29], v[28:29], 1.0 op_sel_hi:[1,0]
	v_pk_fma_f32 v[22:23], v[30:31], v[22:23], v[66:67]
	v_pk_fma_f32 v[20:21], v[28:29], v[20:21], v[64:65]
	s_nop 0
	v_cvt_pk_bf16_f32 v20, v20, v21
	v_cvt_pk_bf16_f32 v21, v22, v23
	global_store_dwordx2 v[80:81], v[20:21], off offset:1024
	global_load_dwordx4 v[28:31], v[76:77], off offset:3072
	global_load_dwordx4 v[64:67], v[78:79], off offset:3072
	v_mul_f32_e32 v20, v41, v41
	v_mul_f32_e32 v21, v43, v43
	v_mul_f32_e32 v22, v37, v37
	v_mul_f32_e32 v23, v39, v39
	v_fmac_f32_e32 v20, v40, v40
	v_fmac_f32_e32 v21, v42, v42
	v_fmac_f32_e32 v22, v36, v36
	v_fmac_f32_e32 v23, v38, v38
	v_add_f32_e32 v20, v20, v21
	v_add_f32_e32 v21, v22, v23
	v_add_f32_e32 v22, v53, v63
	v_add_f32_e32 v20, v20, v21
	v_add_f32_e32 v23, v68, v69
	v_add_f32_e32 v20, v20, v22
	v_add_f32_e32 v20, v20, v23
	ds_bpermute_b32 v21, v56, v20
	s_waitcnt lgkmcnt(0)
	v_add_f32_e32 v20, v20, v21
	ds_bpermute_b32 v21, v57, v20
	s_waitcnt lgkmcnt(0)
	v_add_f32_e32 v20, v20, v21
	ds_bpermute_b32 v21, v58, v20
	s_waitcnt lgkmcnt(0)
	v_add_f32_e32 v20, v20, v21
	ds_bpermute_b32 v21, v59, v20
	s_waitcnt lgkmcnt(0)
	v_add_f32_e32 v20, v20, v21
	ds_bpermute_b32 v21, v60, v20
	s_waitcnt lgkmcnt(0)
	v_add_f32_e32 v20, v20, v21
	ds_bpermute_b32 v21, v61, v20
	s_waitcnt vmcnt(0)
	v_pk_add_f32 v[22:23], v[30:31], 1.0 op_sel_hi:[1,0]
	v_pk_add_f32 v[28:29], v[28:29], 1.0 op_sel_hi:[1,0]
	v_pk_fma_f32 v[18:19], v[22:23], v[18:19], v[66:67]
	v_pk_fma_f32 v[16:17], v[28:29], v[16:17], v[64:65]
	s_nop 0
	v_cvt_pk_bf16_f32 v16, v16, v17
	v_cvt_pk_bf16_f32 v17, v18, v19
	global_store_dwordx2 v[80:81], v[16:17], off offset:1536
	s_and_saveexec_b64 s[6:7], vcc
	s_cbranch_execz .LBB0_565
	v_ashrrev_i32_e32 v16, 11, v54
	v_mul_hi_i32_i24_e32 v17, 0x1800, v16
	v_mul_i32_i24_e32 v16, 0x1800, v16
	v_lshlrev_b64 v[22:23], 2, v[16:17]
	v_lshl_add_u64 v[52:53], v[48:49], 0, v[22:23]
	global_load_dwordx4 v[16:19], v[52:53], off
	v_lshl_add_u64 v[64:65], v[46:47], 0, v[22:23]
	global_load_dwordx4 v[28:31], v[64:65], off
	s_waitcnt lgkmcnt(0)
	v_add_f32_e32 v20, v20, v21
	v_fmamk_f32 v20, v20, 0x3a800000, v208
	v_mul_f32_e32 v21, 0x4b800000, v20
	v_cmp_gt_f32_e32 vcc, s2, v20
	s_waitcnt vmcnt(0)
	v_pk_add_f32 v[18:19], v[18:19], 1.0 op_sel_hi:[1,0]
	v_cndmask_b32_e32 v20, v20, v21, vcc
	v_rsq_f32_e32 v22, v20
	v_lshlrev_b64 v[20:21], 11, v[54:55]
	v_lshl_add_u64 v[54:55], v[50:51], 0, v[20:21]
	v_pk_add_f32 v[16:17], v[16:17], 1.0 op_sel_hi:[1,0]
	v_mul_f32_e32 v20, 0x45800000, v22
	v_cndmask_b32_e32 v66, v22, v20, vcc
	v_pk_mul_f32 v[20:21], v[42:43], v[66:67] op_sel_hi:[1,0]
	v_pk_mul_f32 v[22:23], v[40:41], v[66:67] op_sel_hi:[1,0]
	v_pk_mul_f32 v[20:21], v[2:3], v[20:21]
	v_pk_mul_f32 v[22:23], v[0:1], v[22:23]
	v_pk_fma_f32 v[18:19], v[20:21], v[18:19], v[30:31]
	v_pk_fma_f32 v[16:17], v[22:23], v[16:17], v[28:29]
	v_pk_mul_f32 v[28:29], v[38:39], v[66:67] op_sel_hi:[1,0]
	v_cvt_pk_bf16_f32 v16, v16, v17
	v_cvt_pk_bf16_f32 v17, v18, v19
	global_store_dwordx2 v[54:55], v[16:17], off
	global_load_dwordx4 v[16:19], v[52:53], off offset:1024
	s_nop 0
	global_load_dwordx4 v[20:23], v[64:65], off offset:1024
	v_pk_mul_f32 v[30:31], v[36:37], v[66:67] op_sel_hi:[1,0]
	v_pk_mul_f32 v[28:29], v[6:7], v[28:29]
	v_pk_mul_f32 v[30:31], v[4:5], v[30:31]
	v_pk_mul_f32 v[26:27], v[26:27], v[66:67] op_sel_hi:[1,0]
	v_pk_mul_f32 v[24:25], v[24:25], v[66:67] op_sel_hi:[1,0]
	v_pk_mul_f32 v[26:27], v[14:15], v[26:27]
	v_pk_mul_f32 v[24:25], v[12:13], v[24:25]
	s_waitcnt vmcnt(0) lgkmcnt(0)
	v_pk_add_f32 v[18:19], v[18:19], 1.0 op_sel_hi:[1,0]
	v_pk_add_f32 v[16:17], v[16:17], 1.0 op_sel_hi:[1,0]
	v_pk_fma_f32 v[18:19], v[28:29], v[18:19], v[22:23]
	v_pk_fma_f32 v[16:17], v[30:31], v[16:17], v[20:21]
	v_pk_mul_f32 v[28:29], v[34:35], v[66:67] op_sel_hi:[1,0]
	v_cvt_pk_bf16_f32 v16, v16, v17
	v_cvt_pk_bf16_f32 v17, v18, v19
	global_store_dwordx2 v[54:55], v[16:17], off offset:512
	global_load_dwordx4 v[16:19], v[52:53], off offset:2048
	s_nop 0
	global_load_dwordx4 v[20:23], v[64:65], off offset:2048
	v_pk_mul_f32 v[30:31], v[32:33], v[66:67] op_sel_hi:[1,0]
	v_pk_mul_f32 v[28:29], v[10:11], v[28:29]
	v_pk_mul_f32 v[30:31], v[8:9], v[30:31]
	s_waitcnt vmcnt(0) lgkmcnt(0)
	v_pk_add_f32 v[18:19], v[18:19], 1.0 op_sel_hi:[1,0]
	v_pk_add_f32 v[16:17], v[16:17], 1.0 op_sel_hi:[1,0]
	v_pk_fma_f32 v[18:19], v[28:29], v[18:19], v[22:23]
	v_pk_fma_f32 v[16:17], v[30:31], v[16:17], v[20:21]
	s_nop 0
	v_cvt_pk_bf16_f32 v16, v16, v17
	v_cvt_pk_bf16_f32 v17, v18, v19
	global_store_dwordx2 v[54:55], v[16:17], off offset:1024
	global_load_dwordx4 v[16:19], v[52:53], off offset:3072
	s_nop 0
	global_load_dwordx4 v[20:23], v[64:65], off offset:3072
	s_waitcnt vmcnt(0) lgkmcnt(0)
	v_pk_add_f32 v[18:19], v[18:19], 1.0 op_sel_hi:[1,0]
	v_pk_add_f32 v[16:17], v[16:17], 1.0 op_sel_hi:[1,0]
	v_pk_fma_f32 v[18:19], v[26:27], v[18:19], v[22:23]
	v_pk_fma_f32 v[16:17], v[24:25], v[16:17], v[20:21]
	s_nop 0
	v_cvt_pk_bf16_f32 v16, v16, v17
	v_cvt_pk_bf16_f32 v17, v18, v19
	global_store_dwordx2 v[54:55], v[16:17], off offset:1536
	s_branch .LBB0_565

.LBB0_576:
	global_load_dword v10, v[6:7], off
	global_load_dword v11, v[4:5], off
	v_add_u32_e32 v9, 1, v9
	s_mov_b64 s[12:13], 0x100
	v_cmp_ge_i32_e32 vcc, v9, v20
	v_lshl_add_u64 v[4:5], v[4:5], 0, s[12:13]
	v_lshl_add_u64 v[6:7], v[6:7], 0, 4
	s_or_b64 s[0:1], vcc, s[0:1]
	s_waitcnt vmcnt(0) lgkmcnt(0)
	v_fmac_f32_e32 v8, v10, v11
	s_andn2_b64 exec, exec, s[0:1]
	s_cbranch_execnz .LBB0_576
	s_or_b64 exec, exec, s[0:1]
	s_barrier
	ds_write_b32 v18, v8
	s_waitcnt lgkmcnt(0)
	s_barrier
	s_and_saveexec_b64 s[0:1], s[4:5]
	s_cbranch_execz .LBB0_579
	ds_read2st64_b32 v[4:5], v18 offset1:1
	ds_read2st64_b32 v[6:7], v18 offset0:2 offset1:3
	ds_read2st64_b32 v[8:9], v18 offset0:4 offset1:5
	ds_read2st64_b32 v[10:11], v18 offset0:6 offset1:7
	s_add_i32 s12, s14, s56
	s_lshl_b32 s12, s12, 6
	s_addk_i32 s12, 0xe800
	s_waitcnt lgkmcnt(3)
	v_add_f32_e32 v4, 0, v4
	v_add_f32_e32 v4, v4, v5
	s_waitcnt lgkmcnt(2)
	v_add_f32_e32 v4, v4, v6
	v_add_f32_e32 v4, v4, v7
	s_waitcnt lgkmcnt(1)
	v_add_f32_e32 v4, v4, v8
	v_add_f32_e32 v4, v4, v9
	s_waitcnt lgkmcnt(0)
	v_add_f32_e32 v4, v4, v10
	v_add_f32_e32 v6, v4, v11
	v_add_u32_e32 v4, s12, v16
	v_ashrrev_i32_e32 v5, 31, v4
	v_lshl_add_u64 v[4:5], v[4:5], 2, s[8:9]
	global_store_dword v[4:5], v6, off

.LBB0_580:
	s_mul_hi_i32 s0, s14, 0x2aaaaaab
	s_lshr_b32 s1, s0, 31
	s_ashr_i32 s0, s0, 3
	s_add_i32 s0, s0, s1
	s_mul_i32 s1, s0, 48
	v_mov_b32_e32 v4, 8
	s_sub_i32 s16, s14, s1
	s_waitcnt lgkmcnt(0)
	s_barrier
	s_mul_i32 s1, s16, 43
	v_add_u32_e32 v4, s91, v4
	s_sext_i32_i16 s12, s1
	ds_read_b64 v[4:5], v4
	s_ashr_i32 s17, s12, 9
	s_bfe_u32 s1, s1, 0x1000f
	s_add_i32 s17, s17, s1
	s_sext_i32_i16 s15, s17
	v_lshl_or_b32 v8, s15, 13, v19
	s_waitcnt lgkmcnt(0)
	v_readfirstlane_b32 s1, v5
	v_readfirstlane_b32 s12, v4
	v_add_u32_e32 v6, v8, v21
	v_mov_b32_e32 v5, s1
	v_mov_b32_e32 v4, s12
	v_ashrrev_i32_e32 v7, 31, v6
	v_lshl_add_u64 v[4:5], v[6:7], 2, v[4:5]
	global_load_dword v4, v[4:5], off
	v_mov_b32_e32 v6, 8
	v_mov_b32_e32 v12, 32
	s_mul_i32 s17, s17, 12
	s_sub_i32 s16, s16, s17
	s_sext_i32_i8 s16, s16
	s_mul_i32 s20, s0, 0x1800000
	s_mul_hi_i32 s19, s0, 0x1800000
	s_mov_b32 s18, 0
	s_waitcnt vmcnt(0) lgkmcnt(0)
	v_mul_f32_e32 v5, 0xbfb8aa3b, v4
	v_exp_f32_e32 v5, v5
	s_nop 0
	v_add_f32_e32 v5, 1.0, v5
	v_rcp_f32_e32 v5, v5
	s_nop 0
	v_mul_f32_e32 v4, v4, v5
	ds_write_b32 v18, v4
	s_nop 0
	v_add_u32_e32 v4, s91, v6
	ds_read_b64 v[4:5], v4
	v_add_u32_e32 v6, v8, v22
	v_ashrrev_i32_e32 v7, 31, v6
	s_waitcnt lgkmcnt(0)
	v_readfirstlane_b32 s1, v5
	v_readfirstlane_b32 s12, v4
	s_nop 0
	v_mov_b32_e32 v5, s1
	v_mov_b32_e32 v4, s12
	v_lshl_add_u64 v[4:5], v[6:7], 2, v[4:5]
	global_load_dword v4, v[4:5], off
	v_mov_b32_e32 v6, 8
	s_waitcnt vmcnt(0) lgkmcnt(0)
	v_mul_f32_e32 v5, 0xbfb8aa3b, v4
	v_exp_f32_e32 v5, v5
	s_nop 0
	v_add_f32_e32 v5, 1.0, v5
	v_rcp_f32_e32 v5, v5
	s_nop 0
	v_mul_f32_e32 v4, v4, v5
	ds_write_b32 v18, v4 offset:2048
	s_nop 0
	v_add_u32_e32 v4, s91, v6
	ds_read_b64 v[4:5], v4
	v_add_u32_e32 v6, v8, v23
	v_ashrrev_i32_e32 v7, 31, v6
	s_waitcnt lgkmcnt(0)
	v_readfirstlane_b32 s1, v5
	v_readfirstlane_b32 s12, v4
	s_nop 0
	v_mov_b32_e32 v5, s1
	v_mov_b32_e32 v4, s12
	v_lshl_add_u64 v[4:5], v[6:7], 2, v[4:5]
	global_load_dword v4, v[4:5], off
	v_mov_b32_e32 v6, 8
	s_waitcnt vmcnt(0) lgkmcnt(0)
	v_mul_f32_e32 v5, 0xbfb8aa3b, v4
	v_exp_f32_e32 v5, v5
	s_nop 0
	v_add_f32_e32 v5, 1.0, v5
	v_rcp_f32_e32 v5, v5
	s_nop 0
	v_mul_f32_e32 v4, v4, v5
	ds_write_b32 v18, v4 offset:4096
	s_nop 0
	v_add_u32_e32 v4, s91, v6
	ds_read_b64 v[4:5], v4
	v_add_u32_e32 v6, v8, v24
	v_ashrrev_i32_e32 v7, 31, v6
	s_waitcnt lgkmcnt(0)
	v_readfirstlane_b32 s1, v5
	v_readfirstlane_b32 s12, v4
	s_nop 0
	v_mov_b32_e32 v5, s1
	v_mov_b32_e32 v4, s12
	v_lshl_add_u64 v[4:5], v[6:7], 2, v[4:5]
	global_load_dword v4, v[4:5], off
	v_mov_b32_e32 v6, 8
	s_waitcnt vmcnt(0) lgkmcnt(0)
	v_mul_f32_e32 v5, 0xbfb8aa3b, v4
	v_exp_f32_e32 v5, v5
	s_nop 0
	v_add_f32_e32 v5, 1.0, v5
	v_rcp_f32_e32 v5, v5
	s_nop 0
	v_mul_f32_e32 v4, v4, v5
	ds_write_b32 v18, v4 offset:6144
	s_nop 0
	v_add_u32_e32 v4, s91, v6
	ds_read_b64 v[4:5], v4
	v_add_u32_e32 v6, v8, v25
	v_ashrrev_i32_e32 v7, 31, v6
	s_waitcnt lgkmcnt(0)
	v_readfirstlane_b32 s1, v5
	v_readfirstlane_b32 s12, v4
	s_nop 0
	v_mov_b32_e32 v5, s1
	v_mov_b32_e32 v4, s12
	v_lshl_add_u64 v[4:5], v[6:7], 2, v[4:5]
	global_load_dword v4, v[4:5], off
	v_mov_b32_e32 v6, 8
	s_waitcnt vmcnt(0) lgkmcnt(0)
	v_mul_f32_e32 v5, 0xbfb8aa3b, v4
	v_exp_f32_e32 v5, v5
	s_nop 0
	v_add_f32_e32 v5, 1.0, v5
	v_rcp_f32_e32 v5, v5
	s_nop 0
	v_mul_f32_e32 v4, v4, v5
	ds_write_b32 v18, v4 offset:8192
	s_nop 0
	v_add_u32_e32 v4, s91, v6
	ds_read_b64 v[4:5], v4
	v_add_u32_e32 v6, v8, v26
	v_ashrrev_i32_e32 v7, 31, v6
	s_waitcnt lgkmcnt(0)
	v_readfirstlane_b32 s1, v5
	v_readfirstlane_b32 s12, v4
	s_nop 0
	v_mov_b32_e32 v5, s1
	v_mov_b32_e32 v4, s12
	v_lshl_add_u64 v[4:5], v[6:7], 2, v[4:5]
	global_load_dword v4, v[4:5], off
	v_mov_b32_e32 v6, 8
	s_waitcnt vmcnt(0) lgkmcnt(0)
	v_mul_f32_e32 v5, 0xbfb8aa3b, v4
	v_exp_f32_e32 v5, v5
	s_nop 0
	v_add_f32_e32 v5, 1.0, v5
	v_rcp_f32_e32 v5, v5
	s_nop 0
	v_mul_f32_e32 v4, v4, v5
	ds_write_b32 v18, v4 offset:10240
	s_nop 0
	v_add_u32_e32 v4, s91, v6
	ds_read_b64 v[4:5], v4
	v_add_u32_e32 v6, v8, v27
	v_ashrrev_i32_e32 v7, 31, v6
	s_waitcnt lgkmcnt(0)
	v_readfirstlane_b32 s1, v5
	v_readfirstlane_b32 s12, v4
	s_nop 0
	v_mov_b32_e32 v5, s1
	v_mov_b32_e32 v4, s12
	v_lshl_add_u64 v[4:5], v[6:7], 2, v[4:5]
	global_load_dword v4, v[4:5], off
	v_mov_b32_e32 v6, 8
	s_waitcnt vmcnt(0) lgkmcnt(0)
	v_mul_f32_e32 v5, 0xbfb8aa3b, v4
	v_exp_f32_e32 v5, v5
	s_nop 0
	v_add_f32_e32 v5, 1.0, v5
	v_rcp_f32_e32 v5, v5
	s_nop 0
	v_mul_f32_e32 v4, v4, v5
	ds_write_b32 v18, v4 offset:12288
	s_nop 0
	v_add_u32_e32 v4, s91, v6
	ds_read_b64 v[4:5], v4
	v_add_u32_e32 v6, v8, v28
	v_ashrrev_i32_e32 v7, 31, v6
	s_waitcnt lgkmcnt(0)
	v_readfirstlane_b32 s1, v5
	v_readfirstlane_b32 s12, v4
	s_nop 0
	v_mov_b32_e32 v5, s1
	v_mov_b32_e32 v4, s12
	v_lshl_add_u64 v[4:5], v[6:7], 2, v[4:5]
	global_load_dword v4, v[4:5], off
	v_mov_b32_e32 v6, 8
	s_waitcnt vmcnt(0) lgkmcnt(0)
	v_mul_f32_e32 v5, 0xbfb8aa3b, v4
	v_exp_f32_e32 v5, v5
	s_nop 0
	v_add_f32_e32 v5, 1.0, v5
	v_rcp_f32_e32 v5, v5
	s_nop 0
	v_mul_f32_e32 v4, v4, v5
	ds_write_b32 v18, v4 offset:14336
	s_nop 0
	v_add_u32_e32 v4, s91, v6
	ds_read_b64 v[4:5], v4
	v_add_u32_e32 v6, v8, v29
	v_ashrrev_i32_e32 v7, 31, v6
	s_waitcnt lgkmcnt(0)
	v_readfirstlane_b32 s1, v5
	v_readfirstlane_b32 s12, v4
	s_nop 0
	v_mov_b32_e32 v5, s1
	v_mov_b32_e32 v4, s12
	v_lshl_add_u64 v[4:5], v[6:7], 2, v[4:5]
	global_load_dword v4, v[4:5], off
	v_mov_b32_e32 v6, 8
	s_waitcnt vmcnt(0) lgkmcnt(0)
	v_mul_f32_e32 v5, 0xbfb8aa3b, v4
	v_exp_f32_e32 v5, v5
	s_nop 0
	v_add_f32_e32 v5, 1.0, v5
	v_rcp_f32_e32 v5, v5
	s_nop 0
	v_mul_f32_e32 v4, v4, v5
	ds_write_b32 v18, v4 offset:16384
	s_nop 0
	v_add_u32_e32 v4, s91, v6
	ds_read_b64 v[4:5], v4
	v_add_u32_e32 v6, v8, v30
	v_ashrrev_i32_e32 v7, 31, v6
	s_waitcnt lgkmcnt(0)
	v_readfirstlane_b32 s1, v5
	v_readfirstlane_b32 s12, v4
	s_nop 0
	v_mov_b32_e32 v5, s1
	v_mov_b32_e32 v4, s12
	v_lshl_add_u64 v[4:5], v[6:7], 2, v[4:5]
	global_load_dword v4, v[4:5], off
	v_mov_b32_e32 v6, 8
	s_waitcnt vmcnt(0) lgkmcnt(0)
	v_mul_f32_e32 v5, 0xbfb8aa3b, v4
	v_exp_f32_e32 v5, v5
	s_nop 0
	v_add_f32_e32 v5, 1.0, v5
	v_rcp_f32_e32 v5, v5
	s_nop 0
	v_mul_f32_e32 v4, v4, v5
	ds_write_b32 v18, v4 offset:18432
	s_nop 0
	v_add_u32_e32 v4, s91, v6
	ds_read_b64 v[4:5], v4
	v_add_u32_e32 v6, v8, v31
	v_ashrrev_i32_e32 v7, 31, v6
	s_waitcnt lgkmcnt(0)
	v_readfirstlane_b32 s1, v5
	v_readfirstlane_b32 s12, v4
	s_nop 0
	v_mov_b32_e32 v5, s1
	v_mov_b32_e32 v4, s12
	v_lshl_add_u64 v[4:5], v[6:7], 2, v[4:5]
	global_load_dword v4, v[4:5], off
	v_mov_b32_e32 v6, 8
	s_waitcnt vmcnt(0) lgkmcnt(0)
	v_mul_f32_e32 v5, 0xbfb8aa3b, v4
	v_exp_f32_e32 v5, v5
	s_nop 0
	v_add_f32_e32 v5, 1.0, v5
	v_rcp_f32_e32 v5, v5
	s_nop 0
	v_mul_f32_e32 v4, v4, v5
	ds_write_b32 v18, v4 offset:20480
	s_nop 0
	v_add_u32_e32 v4, s91, v6
	ds_read_b64 v[4:5], v4
	v_add_u32_e32 v6, v8, v32
	v_ashrrev_i32_e32 v7, 31, v6
	s_waitcnt lgkmcnt(0)
	v_readfirstlane_b32 s1, v5
	v_readfirstlane_b32 s12, v4
	s_nop 0
	v_mov_b32_e32 v5, s1
	v_mov_b32_e32 v4, s12
	v_lshl_add_u64 v[4:5], v[6:7], 2, v[4:5]
	global_load_dword v4, v[4:5], off
	v_mov_b32_e32 v6, 8
	s_waitcnt vmcnt(0) lgkmcnt(0)
	v_mul_f32_e32 v5, 0xbfb8aa3b, v4
	v_exp_f32_e32 v5, v5
	s_nop 0
	v_add_f32_e32 v5, 1.0, v5
	v_rcp_f32_e32 v5, v5
	s_nop 0
	v_mul_f32_e32 v4, v4, v5
	ds_write_b32 v18, v4 offset:22528
	s_nop 0
	v_add_u32_e32 v4, s91, v6
	ds_read_b64 v[4:5], v4
	v_add_u32_e32 v6, v8, v33
	v_ashrrev_i32_e32 v7, 31, v6
	s_waitcnt lgkmcnt(0)
	v_readfirstlane_b32 s1, v5
	v_readfirstlane_b32 s12, v4
	s_nop 0
	v_mov_b32_e32 v5, s1
	v_mov_b32_e32 v4, s12
	v_lshl_add_u64 v[4:5], v[6:7], 2, v[4:5]
	global_load_dword v4, v[4:5], off
	v_mov_b32_e32 v6, 8
	s_waitcnt vmcnt(0) lgkmcnt(0)
	v_mul_f32_e32 v5, 0xbfb8aa3b, v4
	v_exp_f32_e32 v5, v5
	s_nop 0
	v_add_f32_e32 v5, 1.0, v5
	v_rcp_f32_e32 v5, v5
	s_nop 0
	v_mul_f32_e32 v4, v4, v5
	ds_write_b32 v18, v4 offset:24576
	s_nop 0
	v_add_u32_e32 v4, s91, v6
	ds_read_b64 v[4:5], v4
	v_add_u32_e32 v6, v8, v34
	v_ashrrev_i32_e32 v7, 31, v6
	s_waitcnt lgkmcnt(0)
	v_readfirstlane_b32 s1, v5
	v_readfirstlane_b32 s12, v4
	s_nop 0
	v_mov_b32_e32 v5, s1
	v_mov_b32_e32 v4, s12
	v_lshl_add_u64 v[4:5], v[6:7], 2, v[4:5]
	global_load_dword v4, v[4:5], off
	v_mov_b32_e32 v6, 8
	s_waitcnt vmcnt(0) lgkmcnt(0)
	v_mul_f32_e32 v5, 0xbfb8aa3b, v4
	v_exp_f32_e32 v5, v5
	s_nop 0
	v_add_f32_e32 v5, 1.0, v5
	v_rcp_f32_e32 v5, v5
	s_nop 0
	v_mul_f32_e32 v4, v4, v5
	ds_write_b32 v18, v4 offset:26624
	s_nop 0
	v_add_u32_e32 v4, s91, v6
	ds_read_b64 v[4:5], v4
	v_add_u32_e32 v6, v8, v35
	v_ashrrev_i32_e32 v7, 31, v6
	s_waitcnt lgkmcnt(0)
	v_readfirstlane_b32 s1, v5
	v_readfirstlane_b32 s12, v4
	s_nop 0
	v_mov_b32_e32 v5, s1
	v_mov_b32_e32 v4, s12
	v_lshl_add_u64 v[4:5], v[6:7], 2, v[4:5]
	global_load_dword v4, v[4:5], off
	v_mov_b32_e32 v6, 8
	s_waitcnt vmcnt(0) lgkmcnt(0)
	v_mul_f32_e32 v5, 0xbfb8aa3b, v4
	v_exp_f32_e32 v5, v5
	s_nop 0
	v_add_f32_e32 v5, 1.0, v5
	v_rcp_f32_e32 v5, v5
	s_nop 0
	v_mul_f32_e32 v4, v4, v5
	ds_write_b32 v18, v4 offset:28672
	s_nop 0
	v_add_u32_e32 v4, s91, v6
	ds_read_b64 v[4:5], v4
	v_add_u32_e32 v6, v8, v36
	v_ashrrev_i32_e32 v7, 31, v6
	s_waitcnt lgkmcnt(0)
	v_readfirstlane_b32 s1, v5
	v_readfirstlane_b32 s12, v4
	s_nop 0
	v_mov_b32_e32 v5, s1
	s_ashr_i32 s1, s0, 31
	v_mov_b32_e32 v4, s12
	v_lshl_add_u64 v[4:5], v[6:7], 2, v[4:5]
	global_load_dword v11, v[4:5], off
	v_mov_b32_e32 v4, 0
	s_mov_b64 s[12:13], 0
	v_mov_b32_e32 v5, v4
	v_mov_b32_e32 v8, v4
	v_mov_b32_e32 v9, v4
	v_mov_b32_e32 v6, v4
	v_mov_b32_e32 v10, v4
	s_waitcnt vmcnt(0) lgkmcnt(0)
	v_mul_f32_e32 v7, 0xbfb8aa3b, v11
	v_exp_f32_e32 v13, v7
	v_mov_b32_e32 v7, v4
	v_add_f32_e32 v13, 1.0, v13
	v_rcp_f32_e32 v13, v13
	s_nop 0
	v_mul_f32_e32 v11, v11, v13
	ds_write_b32 v18, v11 offset:30720
	s_waitcnt lgkmcnt(0)
	s_barrier
	s_nop 0
	v_add_u32_e32 v11, s91, v12
	ds_read_b64 v[14:15], v11
	v_lshl_add_u32 v12, s16, 9, v17
	v_ashrrev_i32_e32 v13, 31, v12
	v_mov_b32_e32 v11, v4
	s_waitcnt lgkmcnt(0)
	v_readfirstlane_b32 s16, v14
	v_readfirstlane_b32 s17, v15
	s_add_u32 s16, s16, s20
	s_addc_u32 s17, s17, s19
	v_lshl_add_u64 v[14:15], v[12:13], 2, s[16:17]
.LBB0_581:
	v_lshl_add_u64 v[38:39], v[14:15], 0, s[12:13]
	v_add_co_u32_e32 v40, vcc, s89, v38
	global_load_dword v70, v[38:39], off
	s_nop 0
	v_addc_co_u32_e32 v41, vcc, 0, v39, vcc
	v_add_co_u32_e32 v42, vcc, s80, v38
	v_mov_b32_e32 v66, s18
	s_nop 0
	v_addc_co_u32_e32 v43, vcc, 0, v39, vcc
	v_add_co_u32_e32 v38, vcc, s88, v38
	s_addk_i32 s18, 0x80
	s_nop 0
	v_addc_co_u32_e32 v39, vcc, 0, v39, vcc
	global_load_dword v72, v[40:41], off
	global_load_dword v74, v[42:43], off
	global_load_dword v76, v[38:39], off
	ds_read_b128 v[38:41], v66
	ds_read_b128 v[42:45], v66 offset:16
	ds_read_b128 v[46:49], v66 offset:32
	ds_read_b128 v[50:53], v66 offset:48
	ds_read_b128 v[54:57], v66 offset:64
	ds_read_b128 v[58:61], v66 offset:80
	ds_read_b128 v[62:65], v66 offset:96
	ds_read_b128 v[66:69], v66 offset:112
	s_add_u32 s12, s12, 0x18000
	s_addc_u32 s13, s13, 0
	s_cmp_eq_u32 s12, 0x1800000
	s_waitcnt vmcnt(0) lgkmcnt(0)
	v_pk_fma_f32 v[8:9], v[70:71], v[38:39], v[8:9] op_sel_hi:[0,1,1]
	v_pk_fma_f32 v[6:7], v[70:71], v[40:41], v[6:7] op_sel_hi:[0,1,1]
	v_pk_fma_f32 v[10:11], v[70:71], v[42:43], v[10:11] op_sel_hi:[0,1,1]
	v_pk_fma_f32 v[4:5], v[70:71], v[44:45], v[4:5] op_sel_hi:[0,1,1]
	v_pk_fma_f32 v[8:9], v[72:73], v[46:47], v[8:9] op_sel_hi:[0,1,1]
	v_pk_fma_f32 v[6:7], v[72:73], v[48:49], v[6:7] op_sel_hi:[0,1,1]
	v_pk_fma_f32 v[10:11], v[72:73], v[50:51], v[10:11] op_sel_hi:[0,1,1]
	v_pk_fma_f32 v[4:5], v[72:73], v[52:53], v[4:5] op_sel_hi:[0,1,1]
	v_pk_fma_f32 v[8:9], v[74:75], v[54:55], v[8:9] op_sel_hi:[0,1,1]
	v_pk_fma_f32 v[6:7], v[74:75], v[56:57], v[6:7] op_sel_hi:[0,1,1]
	v_pk_fma_f32 v[10:11], v[74:75], v[58:59], v[10:11] op_sel_hi:[0,1,1]
	v_pk_fma_f32 v[4:5], v[74:75], v[60:61], v[4:5] op_sel_hi:[0,1,1]
	v_pk_fma_f32 v[8:9], v[76:77], v[62:63], v[8:9] op_sel_hi:[0,1,1]
	v_pk_fma_f32 v[6:7], v[76:77], v[64:65], v[6:7] op_sel_hi:[0,1,1]
	v_pk_fma_f32 v[10:11], v[76:77], v[66:67], v[10:11] op_sel_hi:[0,1,1]
	v_pk_fma_f32 v[4:5], v[76:77], v[68:69], v[4:5] op_sel_hi:[0,1,1]
	s_cbranch_scc0 .LBB0_581
	v_mov_b32_e32 v14, 40
	s_mul_i32 s12, s0, 0x1800
	v_add_u32_e32 v14, 0, v14
	v_add_u32_e32 v14, 0x20400, v14
	ds_read_b64 v[14:15], v14
	v_add_u32_e32 v38, s12, v12
	v_ashrrev_i32_e32 v39, 31, v38
	s_lshl_b64 s[0:1], s[0:1], 5
	v_lshl_add_u64 v[12:13], v[12:13], 2, s[6:7]
	s_waitcnt lgkmcnt(0)
	v_readfirstlane_b32 s12, v15
	v_readfirstlane_b32 s13, v14
	s_nop 0
	v_mov_b32_e32 v15, s12
	v_mov_b32_e32 v14, s13
	v_lshl_add_u64 v[14:15], v[38:39], 2, v[14:15]
	global_load_dword v50, v[14:15], off
	s_lshl_b32 s12, s15, 3
	s_ashr_i32 s13, s12, 31
	s_add_u32 s0, s0, s12
	s_addc_u32 s12, s1, s13
	v_mad_u64_u32 v[12:13], s[0:1], s0, v227, v[12:13]
	s_mulk_i32 s12, 0x6000
	v_add_co_u32_e32 v14, vcc, s89, v12
	v_add_u32_e32 v13, s12, v13
	s_mov_b64 s[0:1], vcc
	v_add_co_u32_e32 v38, vcc, s80, v12
	v_addc_co_u32_e64 v15, s[0:1], 0, v13, s[0:1]
	s_nop 0
	v_addc_co_u32_e32 v39, vcc, 0, v13, vcc
	v_add_co_u32_e32 v40, vcc, s88, v12
	s_mov_b32 s0, 0x18000
	s_nop 0
	v_addc_co_u32_e32 v41, vcc, 0, v13, vcc
	v_add_co_u32_e32 v42, vcc, s0, v12
	s_waitcnt vmcnt(0) lgkmcnt(0)
	v_add_f32_e32 v8, v8, v50
	v_addc_co_u32_e32 v43, vcc, 0, v13, vcc
	v_add_co_u32_e32 v44, vcc, 0x1e000, v12
	v_add_f32_e32 v9, v9, v50
	s_nop 0
	v_addc_co_u32_e32 v45, vcc, 0, v13, vcc
	v_add_co_u32_e32 v46, vcc, 0x24000, v12
	v_add_f32_e32 v6, v6, v50
	s_nop 0
	v_addc_co_u32_e32 v47, vcc, 0, v13, vcc
	v_add_co_u32_e32 v48, vcc, 0x2a000, v12
	v_add_f32_e32 v7, v7, v50
	s_nop 0
	v_addc_co_u32_e32 v49, vcc, 0, v13, vcc
	v_add_f32_e32 v10, v10, v50
	v_add_f32_e32 v11, v11, v50
	v_add_f32_e32 v4, v4, v50
	v_add_f32_e32 v5, v5, v50
	global_store_dword v[12:13], v8, off
	global_store_dword v[14:15], v9, off
	global_store_dword v[38:39], v6, off
	global_store_dword v[40:41], v7, off
	global_store_dword v[42:43], v10, off
	global_store_dword v[44:45], v11, off
	global_store_dword v[46:47], v4, off
	global_store_dword v[48:49], v5, off
	s_branch .LBB0_572

.LBB0_636:
	global_load_dword v12, v[0:1], off
	v_add_u32_e32 v13, s1, v9
	v_lshl_add_u64 v[10:11], v[0:1], 0, s[10:11]
	s_addk_i32 s1, 0x840
	v_lshl_add_u64 v[0:1], v[0:1], 0, s[6:7]
	s_cmpk_eq_i32 s1, 0x2100
	s_waitcnt vmcnt(0) lgkmcnt(0)
	v_cndmask_b32_e32 v12, 0, v12, vcc
	ds_write_b32 v13, v12
	global_load_dword v12, v[10:11], off
	v_lshl_add_u64 v[10:11], v[10:11], 0, s[10:11]
	s_waitcnt vmcnt(0) lgkmcnt(0)
	v_cndmask_b32_e32 v12, 0, v12, vcc
	ds_write_b32 v13, v12 offset:264
	global_load_dword v12, v[10:11], off
	v_lshl_add_u64 v[10:11], v[10:11], 0, s[10:11]
	s_waitcnt vmcnt(0) lgkmcnt(0)
	v_cndmask_b32_e32 v12, 0, v12, vcc
	ds_write_b32 v13, v12 offset:528
	global_load_dword v12, v[10:11], off
	v_lshl_add_u64 v[10:11], v[10:11], 0, s[10:11]
	s_waitcnt vmcnt(0) lgkmcnt(0)
	v_cndmask_b32_e32 v12, 0, v12, vcc
	ds_write_b32 v13, v12 offset:792
	global_load_dword v12, v[10:11], off
	v_lshl_add_u64 v[10:11], v[10:11], 0, s[10:11]
	s_waitcnt vmcnt(0) lgkmcnt(0)
	v_cndmask_b32_e32 v12, 0, v12, vcc
	ds_write_b32 v13, v12 offset:1056
	global_load_dword v12, v[10:11], off
	v_lshl_add_u64 v[10:11], v[10:11], 0, s[10:11]
	s_waitcnt vmcnt(0) lgkmcnt(0)
	v_cndmask_b32_e32 v12, 0, v12, vcc
	ds_write_b32 v13, v12 offset:1320
	global_load_dword v12, v[10:11], off
	v_lshl_add_u64 v[10:11], v[10:11], 0, s[10:11]
	s_waitcnt vmcnt(0) lgkmcnt(0)
	v_cndmask_b32_e32 v12, 0, v12, vcc
	ds_write_b32 v13, v12 offset:1584
	global_load_dword v10, v[10:11], off
	s_waitcnt vmcnt(0) lgkmcnt(0)
	v_cndmask_b32_e32 v10, 0, v10, vcc
	ds_write_b32 v13, v10 offset:1848
	s_cbranch_scc0 .LBB0_636
	s_ashr_i32 s1, s0, 31
	ds_read_b32 v10, v5
	ds_read_b32 v11, v5 offset:132
	ds_read_b32 v12, v5 offset:264
	ds_read_b32 v13, v5 offset:396
	ds_read_b32 v14, v5 offset:528
	ds_read_b32 v15, v5 offset:660
	ds_read_b32 v16, v5 offset:792
	ds_read_b32 v17, v5 offset:924
	s_lshl_b64 s[0:1], s[0:1], 1
	s_add_u32 s0, s4, s0
	s_addc_u32 s1, s5, s1
	s_waitcnt lgkmcnt(6)
	v_cvt_pk_bf16_f32 v10, v10, v11
	s_waitcnt lgkmcnt(4)
	v_cvt_pk_bf16_f32 v11, v12, v13
	s_waitcnt lgkmcnt(2)
	v_cvt_pk_bf16_f32 v12, v14, v15
	v_or_b32_e32 v14, s9, v4
	v_lshl_add_u64 v[0:1], s[0:1], 0, v[160:161]
	v_mul_hi_i32_i24_e32 v15, s8, v14
	v_mul_i32_i24_e32 v14, s8, v14
	s_waitcnt lgkmcnt(0)
	v_cvt_pk_bf16_f32 v13, v16, v17
	v_lshl_add_u64 v[14:15], v[14:15], 1, v[0:1]
	global_store_dwordx4 v[14:15], v[10:13], off
	ds_read_b32 v10, v5 offset:32
	ds_read_b32 v11, v5 offset:164
	ds_read_b32 v12, v5 offset:296
	ds_read_b32 v13, v5 offset:428
	ds_read_b32 v14, v5 offset:560
	ds_read_b32 v15, v5 offset:692
	ds_read_b32 v16, v5 offset:824
	ds_read_b32 v17, v5 offset:956
	s_waitcnt lgkmcnt(0)
	v_cvt_pk_bf16_f32 v10, v10, v11
	v_cvt_pk_bf16_f32 v11, v12, v13
	v_cvt_pk_bf16_f32 v12, v14, v15
	v_or_b32_e32 v14, s9, v6
	v_mul_hi_i32_i24_e32 v15, s8, v14
	v_mul_i32_i24_e32 v14, s8, v14
	v_cvt_pk_bf16_f32 v13, v16, v17
	v_lshl_add_u64 v[14:15], v[14:15], 1, v[0:1]
	global_store_dwordx4 v[14:15], v[10:13], off
	ds_read_b32 v10, v5 offset:64
	ds_read_b32 v11, v5 offset:196
	ds_read_b32 v12, v5 offset:328
	ds_read_b32 v13, v5 offset:460
	ds_read_b32 v14, v5 offset:592
	ds_read_b32 v15, v5 offset:724
	ds_read_b32 v16, v5 offset:856
	ds_read_b32 v17, v5 offset:988
	s_waitcnt lgkmcnt(0)
	v_cvt_pk_bf16_f32 v10, v10, v11
	v_cvt_pk_bf16_f32 v11, v12, v13
	v_cvt_pk_bf16_f32 v12, v14, v15
	v_or_b32_e32 v14, s9, v7
	v_mul_hi_i32_i24_e32 v15, s8, v14
	v_mul_i32_i24_e32 v14, s8, v14
	v_cvt_pk_bf16_f32 v13, v16, v17
	v_lshl_add_u64 v[14:15], v[14:15], 1, v[0:1]
	global_store_dwordx4 v[14:15], v[10:13], off
	ds_read_b32 v10, v5 offset:96
	ds_read_b32 v11, v5 offset:228
	ds_read_b32 v12, v5 offset:360
	ds_read_b32 v13, v5 offset:492
	ds_read_b32 v14, v5 offset:624
	ds_read_b32 v15, v5 offset:756
	ds_read_b32 v16, v5 offset:888
	ds_read_b32 v17, v5 offset:1020
	s_waitcnt lgkmcnt(0)
	v_cvt_pk_bf16_f32 v10, v10, v11
	v_cvt_pk_bf16_f32 v11, v12, v13
	v_cvt_pk_bf16_f32 v12, v14, v15
	v_or_b32_e32 v14, s9, v8
	v_mul_hi_i32_i24_e32 v15, s8, v14
	v_mul_i32_i24_e32 v14, s8, v14
	s_add_i32 s19, s19, s12
	v_cvt_pk_bf16_f32 v13, v16, v17
	v_lshl_add_u64 v[0:1], v[14:15], 1, v[0:1]
	s_cmpk_gt_i32 s19, 0x4907
	global_store_dwordx4 v[0:1], v[10:13], off
	s_cbranch_scc0 .LBB0_585
	s_branch .LBB0_639
